# flat->global, ksplit loads hoisted, P5 epilogue: dead halo/conv sections + DPP zero-inits removed
# speedup vs baseline: 1.0206x; 1.0206x over previous
; __device__ __forceinline__ unsigned cvt_pk_bf16(float lo, float hi) { unsigned r; asm volatile("v_cvt_pk_bf16_f32 %0, %1, %2" : "=v"(r) : "v"(lo), "v"(hi)); return r; }
; __device__ __forceinline__ void small_proj(const Params& p, int l, int G, int bx) {
;     ...
;     for (int ts = G - 1 - bx; ts < INW / 32; ts += G) {
;         const int n0 = ts * 32; f32x4 acc[2] = {(f32x4){0.f, 0.f, 0.f, 0.f}, (f32x4){0.f, 0.f, 0.f, 0.f}};
;         const bf16_t* ap = XB + (size_t)id.row * DM + 8 * id.fq;
;         const bf16_t* const bp[2] = {Bt + (size_t)(n0 + id.fr) * DM + 8 * id.fq, Bt + (size_t)(n0 + 16 + id.fr) * DM + 8 * id.fq};
;         small_mma<2, 8>(acc, ap, bp, DM);
;         const float rs = __builtin_amdgcn_rsqf(ssq[id.row] * (1.0f / 1024.0f) + EPS);
; #pragma unroll
;         for (int nb = 0; nb < 2; ++nb) { const int col = n0 + 16 * nb + 4 * id.fq; float v[4];
; #pragma unroll
;             for (int j = 0; j < 4; ++j) { float x = acc[nb][j] * rs; if (n0 >= 1280) { x += gb[col - 1280 + j]; x = __builtin_amdgcn_rcpf(1.0f + __builtin_amdgcn_exp2f(-LOG2E * x)); } v[j] = x; }
;             u32x2 w; w.x = cvt_pk_bf16(v[0], v[1]); w.y = cvt_pk_bf16(v[2], v[3]); *(u32x2*)(PROJ + (size_t)id.row * INW + col) = w; }
.LBB0_146:
	s_add_i32 s7, s7, s92
	v_add_u32_e32 v14, s37, v14
	s_cmpk_lt_i32 s7, 0x68
	v_add_u32_e32 v16, s37, v16
	v_cvt_pk_bf16_f32 v0, v0, v1
	v_cvt_pk_bf16_f32 v1, v2, v3
	global_store_dwordx2 v[4:5], v[0:1], off offset:32
	s_cbranch_scc0 .LBB0_165

; template <int NB, int UN>
; __device__ __forceinline__ void small_mma(f32x4 (&acc)[NB], const bf16_t* ap, const bf16_t* const (&bp)[NB], int K) {
; #pragma unroll 1
;     for (int k0 = 0; k0 < K; k0 += 32 * UN) {
;         bf16x8 a[UN], b[NB][UN];
; #pragma unroll
;         for (int u = 0; u < UN; ++u) { a[u] = *(const bf16x8*)(ap + k0 + 32 * u);
; #pragma unroll
;             for (int nb = 0; nb < NB; ++nb) b[nb][u] = *(const bf16x8*)(bp[nb] + k0 + 32 * u); }
; #pragma unroll
;         for (int u = 0; u < UN; ++u)
; #pragma unroll
;             for (int nb = 0; nb < NB; ++nb) acc[nb] = __builtin_amdgcn_mfma_f32_16x16x32_bf16(b[nb][u], a[u], acc[nb], 0, 0, 0);
;     }
; __device__ __forceinline__ void small_proj(const Params& p, int l, int G, int bx) {
;     ...
;         const float rs = __builtin_amdgcn_rsqf(ssq[id.row] * (1.0f / 1024.0f) + EPS);
; #pragma unroll
;         for (int nb = 0; nb < 2; ++nb) { const int col = n0 + 16 * nb + 4 * id.fq; float v[4];
; #pragma unroll
;             for (int j = 0; j < 4; ++j) { float x = acc[nb][j] * rs; if (n0 >= 1280) { x += gb[col - 1280 + j]; x = __builtin_amdgcn_rcpf(1.0f + __builtin_amdgcn_exp2f(-LOG2E * x)); } v[j] = x; }
.LBB0_148:
	v_lshl_add_u64 v[26:27], v[22:23], 0, v[96:97]
	v_add_co_u32_e32 v54, vcc, 0x3800000, v26
	v_lshl_add_u64 v[28:29], v[20:21], 0, v[96:97]
	s_mov_b64 s[0:1], vcc
	v_add_co_u32_e32 v58, vcc, 0x100000, v28
	v_addc_co_u32_e64 v55, s[0:1], 0, v27, s[0:1]
	s_mov_b64 s[0:1], vcc
	s_nop 0
	v_addc_co_u32_e64 v59, s[0:1], 0, v29, s[0:1]
	global_load_dwordx4 v[26:29], v[54:55], off
	global_load_dwordx4 v[30:33], v[54:55], off offset:64
	global_load_dwordx4 v[34:37], v[58:59], off
	v_lshl_add_u64 v[38:39], v[18:19], 0, v[96:97]
	v_add_co_u32_e32 v60, vcc, 0x100000, v38
	s_addk_i32 s10, 0x100
	s_nop 0
	v_addc_co_u32_e32 v61, vcc, 0, v39, vcc
	global_load_dwordx4 v[38:41], v[58:59], off offset:64
	global_load_dwordx4 v[42:45], v[60:61], off
	v_lshl_add_u64 v[22:23], v[22:23], 0, s[38:39]
	v_lshl_add_u64 v[18:19], v[18:19], 0, s[38:39]
	s_cmpk_lt_u32 s10, 0x300
	v_lshl_add_u64 v[20:21], v[20:21], 0, s[38:39]
	s_waitcnt vmcnt(0) lgkmcnt(0)
	v_mfma_f32_16x16x32_bf16 v[4:7], v[34:37], v[26:29], v[4:7]
	global_load_dwordx4 v[34:37], v[60:61], off offset:64
	v_mfma_f32_16x16x32_bf16 v[0:3], v[42:45], v[26:29], v[0:3]
	global_load_dwordx4 v[26:29], v[54:55], off offset:128
	global_load_dwordx4 v[42:45], v[54:55], off offset:192
	global_load_dwordx4 v[46:49], v[54:55], off offset:256
	v_mfma_f32_16x16x32_bf16 v[4:7], v[38:41], v[30:33], v[4:7]
	global_load_dwordx4 v[38:41], v[58:59], off offset:128
	global_load_dwordx4 v[50:53], v[58:59], off offset:192
	s_waitcnt vmcnt(0) lgkmcnt(0)
	v_mfma_f32_16x16x32_bf16 v[4:7], v[38:41], v[26:29], v[4:7]
	v_mfma_f32_16x16x32_bf16 v[0:3], v[34:37], v[30:33], v[0:3]
	global_load_dwordx4 v[30:33], v[60:61], off offset:128
	global_load_dwordx4 v[34:37], v[60:61], off offset:192
	v_mfma_f32_16x16x32_bf16 v[4:7], v[50:53], v[42:45], v[4:7]
	s_waitcnt vmcnt(0) lgkmcnt(0)
	v_mfma_f32_16x16x32_bf16 v[0:3], v[30:33], v[26:29], v[0:3]
	global_load_dwordx4 v[26:29], v[54:55], off offset:320
	global_load_dwordx4 v[30:33], v[54:55], off offset:384
	global_load_dwordx4 v[38:41], v[54:55], off offset:448
	global_load_dwordx4 v[50:53], v[58:59], off offset:256
	s_nop 0
	global_load_dwordx4 v[54:57], v[58:59], off offset:320
	v_mfma_f32_16x16x32_bf16 v[0:3], v[34:37], v[42:45], v[0:3]
	global_load_dwordx4 v[34:37], v[60:61], off offset:256
	global_load_dwordx4 v[42:45], v[60:61], off offset:320
	s_waitcnt vmcnt(0) lgkmcnt(0)
	v_mfma_f32_16x16x32_bf16 v[4:7], v[50:53], v[46:49], v[4:7]
	v_mfma_f32_16x16x32_bf16 v[0:3], v[34:37], v[46:49], v[0:3]
	global_load_dwordx4 v[34:37], v[58:59], off offset:384
	global_load_dwordx4 v[46:49], v[60:61], off offset:384
	v_mfma_f32_16x16x32_bf16 v[4:7], v[54:57], v[26:29], v[4:7]
	v_mfma_f32_16x16x32_bf16 v[0:3], v[42:45], v[26:29], v[0:3]
	global_load_dwordx4 v[26:29], v[58:59], off offset:448
	s_waitcnt vmcnt(0) lgkmcnt(0)
	v_mfma_f32_16x16x32_bf16 v[4:7], v[34:37], v[30:33], v[4:7]
	global_load_dwordx4 v[34:37], v[60:61], off offset:448
	v_mfma_f32_16x16x32_bf16 v[0:3], v[46:49], v[30:33], v[0:3]
	v_mfma_f32_16x16x32_bf16 v[4:7], v[26:29], v[38:41], v[4:7]
	s_waitcnt vmcnt(0) lgkmcnt(0)
	v_mfma_f32_16x16x32_bf16 v[0:3], v[34:37], v[38:41], v[0:3]
	s_cbranch_scc1 .LBB0_148
	global_load_dword v15, v[8:9], off
	s_cmp_gt_i32 s7, 39
	v_lshl_or_b32 v18, s7, 5, v24
	s_cselect_b64 s[10:11], -1, 0
	s_cmp_lt_i32 s7, 40
	s_waitcnt vmcnt(0) lgkmcnt(0)
	v_fmamk_f32 v15, v15, 0x3a800000, v223
	v_rsq_f32_e32 v15, v15
	s_nop 0
	v_mul_f32_e32 v4, v4, v15
	s_cbranch_scc1 .LBB0_151
	v_mov_b32_e32 v19, v97
	v_lshl_add_u64 v[20:21], v[18:19], 2, s[2:3]
	v_add_co_u32_e32 v20, vcc, 0xfffff000, v20
	s_nop 1
	v_addc_co_u32_e32 v21, vcc, -1, v21, vcc
	global_load_dword v17, v[20:21], off offset:-1024
	s_waitcnt vmcnt(0)
	v_add_f32_e32 v4, v4, v17
	v_mul_f32_e32 v4, 0xbfb8aa3b, v4
	v_exp_f32_e32 v4, v4
	s_nop 0
	v_add_f32_e32 v4, 1.0, v4
	v_rcp_f32_e32 v4, v4

; __device__ __forceinline__ unsigned cvt_pk_bf16(float lo, float hi) { unsigned r; asm volatile("v_cvt_pk_bf16_f32 %0, %1, %2" : "=v"(r) : "v"(lo), "v"(hi)); return r; }
; __device__ __forceinline__ void small_proj(const Params& p, int l, int G, int bx) {
;     ...
;         for (int nb = 0; nb < 2; ++nb) { const int col = n0 + 16 * nb + 4 * id.fq; float v[4];
; #pragma unroll
;             for (int j = 0; j < 4; ++j) { float x = acc[nb][j] * rs; if (n0 >= 1280) { x += gb[col - 1280 + j]; x = __builtin_amdgcn_rcpf(1.0f + __builtin_amdgcn_exp2f(-LOG2E * x)); } v[j] = x; }
;             u32x2 w; w.x = cvt_pk_bf16(v[0], v[1]); w.y = cvt_pk_bf16(v[2], v[3]); *(u32x2*)(PROJ + (size_t)id.row * INW + col) = w; }
.LBB0_155:
	v_ashrrev_i32_e32 v19, 31, v18
	v_cvt_pk_bf16_f32 v20, v4, v5
	v_lshl_add_u64 v[4:5], v[18:19], 1, v[10:11]
	s_and_b64 vcc, exec, s[0:1]
	v_mul_f32_e32 v0, v0, v15
	v_cvt_pk_bf16_f32 v21, v6, v7
	global_store_dwordx2 v[4:5], v[20:21], off
	s_cbranch_vccnz .LBB0_161
	v_mov_b32_e32 v19, v97
	v_lshl_add_u64 v[6:7], v[18:19], 2, s[2:3]
	v_add_co_u32_e32 v6, vcc, 0xfffff000, v6
	s_nop 1
	v_addc_co_u32_e32 v7, vcc, -1, v7, vcc
	global_load_dword v6, v[6:7], off offset:-960
	s_waitcnt vmcnt(0)
	v_add_f32_e32 v0, v0, v6
	v_mul_f32_e32 v0, 0xbfb8aa3b, v0
	v_exp_f32_e32 v0, v0
	s_nop 0
	v_add_f32_e32 v0, 1.0, v0
	v_rcp_f32_e32 v0, v0
	s_and_b64 vcc, exec, s[0:1]
	v_mul_f32_e32 v1, v1, v15
	s_cbranch_vccz .LBB0_162

; __device__ __forceinline__ u32x4 pack8(const float* f) { u32x4 w; w.x = cvt_pk_bf16(f[0], f[1]); w.y = cvt_pk_bf16(f[2], f[3]); w.z = cvt_pk_bf16(f[4], f[5]); w.w = cvt_pk_bf16(f[6], f[7]); return w; }
;     __device__ __forceinline__ void operator()(AccT& acc, const Unit& u, int wr, int wc, int fr, int fq) const {
;         const bool gate = u.pn >= 5;
;         const int col0 = u.pn * 256 + wc * 32 + 8 * fq;
;         f32x4 gb[2][2];
; #pragma unroll
;         for (int bj = 0; bj < 2; ++bj)
; #pragma unroll
;             for (int n = 0; n < 2; ++n) gb[bj][n] = gate ? *(const f32x4*)(gbias + (col0 - 1280) + bj * 128 + 4 * n) : (f32x4){0.f, 0.f, 0.f, 0.f};
;         float rsv[2][4];
; #pragma unroll
;         for (int ai = 0; ai < 2; ++ai)
; #pragma unroll
;             for (int m = 0; m < 4; ++m) rsv[ai][m] = ssq[u.pm * 256 + ai * 128 + wr * 64 + m * 16 + fr];
; #pragma unroll
;         for (int ai = 0; ai < 2; ++ai)
; #pragma unroll
;             for (int m = 0; m < 4; ++m) {
;                 const int row = u.pm * 256 + ai * 128 + wr * 64 + m * 16 + fr;
;                 const float rs = __builtin_amdgcn_rsqf(rsv[ai][m] * (1.0f / 1024.0f) + EPS);
;                 bf16_t* rowp = P + (size_t)row * INW + col0;
; #pragma unroll
;                 for (int bj = 0; bj < 2; ++bj) {
;                     float v[8];
; #pragma unroll
;                     for (int n = 0; n < 2; ++n)
; #pragma unroll
;                         for (int j = 0; j < 4; ++j) {
;                             float x = acc[ai][bj][m][n][j] * rs;
;                             if (gate) { x += gb[bj][n][j]; x = __builtin_amdgcn_rcpf(1.0f + __builtin_amdgcn_exp2f(-LOG2E * x)); }
;                             v[n * 4 + j] = x;
;                         }
;                     *(u32x4*)(rowp + bj * 128) = pack8(v);
;                 }
;             }
.LBB0_185:
	s_lshl_b32 s0, s49, 8
	s_add_i32 s0, s0, s33
	v_add_u32_e32 v160, s0, v160
	v_ashrrev_i32_e32 v161, 31, v160
	v_lshl_add_u64 v[156:157], v[160:161], 2, s[46:47]
	global_load_dword v161, v[156:157], off
	global_load_dword v179, v[156:157], off offset:64
	global_load_dword v177, v[156:157], off offset:128
	global_load_dword v175, v[156:157], off offset:192
	global_load_dword v173, v[156:157], off offset:512
	global_load_dword v171, v[156:157], off offset:576
	global_load_dword v169, v[156:157], off offset:640
	global_load_dword v167, v[156:157], off offset:704
	v_add_u32_e32 v178, 16, v160
	v_add_u32_e32 v176, 32, v160
	v_add_u32_e32 v174, 48, v160
	v_add_u32_e32 v172, 0x80, v160
	v_add_u32_e32 v170, 0x90, v160
	v_add_u32_e32 v168, 0xa0, v160
	v_add_u32_e32 v166, 0xb0, v160
	v_lshlrev_b64 v[158:159], 1, v[158:159]
	s_andn2_b64 vcc, exec, s[40:41]
	s_waitcnt vmcnt(0) lgkmcnt(0)
	v_fmamk_f32 v156, v161, 0x3a800000, v223
	v_rsq_f32_e32 v180, v156
	v_mov_b64_e32 v[156:157], s[84:85]
	v_mad_i64_i32 v[160:161], s[0:1], v160, s89, v[156:157]
	v_mul_f32_e32 v181, v142, v180
	v_fma_f32 v142, v142, v180, v52
	v_mul_f32_e32 v142, 0xbfb8aa3b, v142
	v_exp_f32_e32 v142, v142
	v_lshl_add_u64 v[160:161], v[160:161], 0, v[158:159]
	v_add_f32_e32 v142, 1.0, v142
	v_rcp_f32_e32 v142, v142
	s_nop 0
	v_cndmask_b32_e64 v142, v181, v142, s[42:43]
	v_mul_f32_e32 v181, v143, v180
	v_fma_f32 v143, v143, v180, v53
	v_mul_f32_e32 v143, 0xbfb8aa3b, v143
	v_exp_f32_e32 v143, v143
	s_nop 0
	v_add_f32_e32 v143, 1.0, v143
	v_rcp_f32_e32 v143, v143
	s_nop 0
	v_cndmask_b32_e64 v143, v181, v143, s[42:43]
	v_mul_f32_e32 v181, v144, v180
	v_fma_f32 v144, v144, v180, v54
	v_mul_f32_e32 v144, 0xbfb8aa3b, v144
	v_exp_f32_e32 v144, v144
	s_nop 0
	v_add_f32_e32 v144, 1.0, v144
	v_rcp_f32_e32 v144, v144
	s_nop 0
	v_cndmask_b32_e64 v144, v181, v144, s[42:43]
	v_mul_f32_e32 v181, v145, v180
	v_fma_f32 v145, v145, v180, v55
	v_mul_f32_e32 v145, 0xbfb8aa3b, v145
	v_exp_f32_e32 v145, v145
	s_nop 0
	v_add_f32_e32 v145, 1.0, v145
	v_rcp_f32_e32 v145, v145
	s_nop 0
	v_cndmask_b32_e64 v145, v181, v145, s[42:43]
	v_mul_f32_e32 v181, v138, v180
	v_fma_f32 v138, v138, v180, v44
	v_mul_f32_e32 v138, 0xbfb8aa3b, v138
	v_exp_f32_e32 v138, v138
	s_nop 0
	v_add_f32_e32 v138, 1.0, v138
	v_rcp_f32_e32 v138, v138
	s_nop 0
	v_cndmask_b32_e64 v181, v181, v138, s[42:43]
	v_mul_f32_e32 v138, v139, v180
	v_fma_f32 v139, v139, v180, v45
	v_mul_f32_e32 v139, 0xbfb8aa3b, v139
	v_exp_f32_e32 v139, v139
	s_nop 0
	v_add_f32_e32 v139, 1.0, v139
	v_rcp_f32_e32 v139, v139
	s_nop 0
	v_cndmask_b32_e64 v182, v138, v139, s[42:43]
	v_fma_f32 v139, v140, v180, v46
	v_mul_f32_e32 v139, 0xbfb8aa3b, v139
	v_exp_f32_e32 v139, v139
	v_mul_f32_e32 v138, v140, v180
	v_add_f32_e32 v139, 1.0, v139
	v_rcp_f32_e32 v139, v139
	s_nop 0
	v_cndmask_b32_e64 v183, v138, v139, s[42:43]
	v_fma_f32 v139, v141, v180, v47
	v_mul_f32_e32 v139, 0xbfb8aa3b, v139
	v_exp_f32_e32 v139, v139
	v_mul_f32_e32 v138, v141, v180
	v_add_f32_e32 v139, 1.0, v139
	v_rcp_f32_e32 v139, v139
	s_nop 0
	v_cndmask_b32_e64 v141, v138, v139, s[42:43]
	v_cvt_pk_bf16_f32 v138, v142, v143
	v_cvt_pk_bf16_f32 v139, v144, v145
	v_cvt_pk_bf16_f32 v140, v181, v182
	v_cvt_pk_bf16_f32 v141, v183, v141
	global_store_dwordx4 v[160:161], v[138:141], off
	s_nop 1
	v_mul_f32_e32 v138, v134, v180
	v_fma_f32 v134, v134, v180, v40
	v_mul_f32_e32 v134, 0xbfb8aa3b, v134
	v_exp_f32_e32 v134, v134
	s_nop 0
	v_add_f32_e32 v134, 1.0, v134
	v_rcp_f32_e32 v134, v134
	s_nop 0
	v_cndmask_b32_e64 v134, v138, v134, s[42:43]
	v_mul_f32_e32 v138, v135, v180
	v_fma_f32 v135, v135, v180, v41
	v_mul_f32_e32 v135, 0xbfb8aa3b, v135
	v_exp_f32_e32 v135, v135
	s_nop 0
	v_add_f32_e32 v135, 1.0, v135
	v_rcp_f32_e32 v135, v135
	s_nop 0
	v_cndmask_b32_e64 v135, v138, v135, s[42:43]
	v_mul_f32_e32 v138, v136, v180
	v_fma_f32 v136, v136, v180, v42
	v_mul_f32_e32 v136, 0xbfb8aa3b, v136
	v_exp_f32_e32 v136, v136
	s_nop 0
	v_add_f32_e32 v136, 1.0, v136
	v_rcp_f32_e32 v136, v136
	s_nop 0
	v_cndmask_b32_e64 v136, v138, v136, s[42:43]
	v_mul_f32_e32 v138, v137, v180
	v_fma_f32 v137, v137, v180, v43
	v_mul_f32_e32 v137, 0xbfb8aa3b, v137
	v_exp_f32_e32 v137, v137
	s_nop 0
	v_add_f32_e32 v137, 1.0, v137
	v_rcp_f32_e32 v137, v137
	s_nop 0
	v_cndmask_b32_e64 v137, v138, v137, s[42:43]
	v_mul_f32_e32 v138, v130, v180
	v_fma_f32 v130, v130, v180, v32
	v_mul_f32_e32 v130, 0xbfb8aa3b, v130
	v_exp_f32_e32 v130, v130
	s_nop 0
	v_add_f32_e32 v130, 1.0, v130
	v_rcp_f32_e32 v130, v130
	s_nop 0
	v_cndmask_b32_e64 v138, v138, v130, s[42:43]
	v_mul_f32_e32 v130, v131, v180
	v_fma_f32 v131, v131, v180, v33
	v_mul_f32_e32 v131, 0xbfb8aa3b, v131
	v_exp_f32_e32 v131, v131
	s_nop 0
	v_add_f32_e32 v131, 1.0, v131
	v_rcp_f32_e32 v131, v131
	s_nop 0
	v_cndmask_b32_e64 v139, v130, v131, s[42:43]
	v_fma_f32 v131, v132, v180, v34
	v_mul_f32_e32 v131, 0xbfb8aa3b, v131
	v_exp_f32_e32 v131, v131
	v_mul_f32_e32 v130, v132, v180
	v_add_f32_e32 v131, 1.0, v131
	v_rcp_f32_e32 v131, v131
	s_nop 0
	v_cndmask_b32_e64 v140, v130, v131, s[42:43]
	v_fma_f32 v131, v133, v180, v35
	v_mul_f32_e32 v131, 0xbfb8aa3b, v131
	v_exp_f32_e32 v131, v131
	v_mul_f32_e32 v130, v133, v180
	v_add_f32_e32 v131, 1.0, v131
	v_rcp_f32_e32 v131, v131
	s_nop 0
	v_cndmask_b32_e64 v133, v130, v131, s[42:43]
	v_cvt_pk_bf16_f32 v130, v134, v135
	v_cvt_pk_bf16_f32 v131, v136, v137
	v_cvt_pk_bf16_f32 v132, v138, v139
	v_cvt_pk_bf16_f32 v133, v140, v133
	global_store_dwordx4 v[160:161], v[130:133], off offset:256
	s_nop 1
	v_fmamk_f32 v130, v179, 0x3a800000, v223
	v_rsq_f32_e32 v132, v130
	v_mad_i64_i32 v[130:131], s[0:1], v178, s89, v[156:157]
	v_lshl_add_u64 v[130:131], v[130:131], 0, v[158:159]
; __device__ __forceinline__ u32x4 pack8(const float* f) { u32x4 w; w.x = cvt_pk_bf16(f[0], f[1]); w.y = cvt_pk_bf16(f[2], f[3]); w.z = cvt_pk_bf16(f[4], f[5]); w.w = cvt_pk_bf16(f[6], f[7]); return w; }
;     __device__ __forceinline__ void operator()(AccT& acc, const Unit& u, int wr, int wc, int fr, int fq) const {
;     ...
;         for (int ai = 0; ai < 2; ++ai)
; #pragma unroll
;             for (int m = 0; m < 4; ++m) {
;                 const int row = u.pm * 256 + ai * 128 + wr * 64 + m * 16 + fr;
;                 const float rs = __builtin_amdgcn_rsqf(rsv[ai][m] * (1.0f / 1024.0f) + EPS);
;                 bf16_t* rowp = P + (size_t)row * INW + col0;
; #pragma unroll
;                 for (int bj = 0; bj < 2; ++bj) {
;                     float v[8];
; #pragma unroll
;                     for (int n = 0; n < 2; ++n)
; #pragma unroll
;                         for (int j = 0; j < 4; ++j) {
;                             float x = acc[ai][bj][m][n][j] * rs;
;                             if (gate) { x += gb[bj][n][j]; x = __builtin_amdgcn_rcpf(1.0f + __builtin_amdgcn_exp2f(-LOG2E * x)); }
;                             v[n * 4 + j] = x;
;                         }
;                     *(u32x4*)(rowp + bj * 128) = pack8(v);
;                 }
;             }
	v_mul_f32_e32 v133, v126, v132
	v_fma_f32 v126, v126, v132, v52
	v_mul_f32_e32 v126, 0xbfb8aa3b, v126
	v_exp_f32_e32 v126, v126
	s_nop 0
	v_add_f32_e32 v126, 1.0, v126
	v_rcp_f32_e32 v126, v126
	s_nop 0
	v_cndmask_b32_e64 v126, v133, v126, s[42:43]
	v_mul_f32_e32 v133, v127, v132
	v_fma_f32 v127, v127, v132, v53
	v_mul_f32_e32 v127, 0xbfb8aa3b, v127
	v_exp_f32_e32 v127, v127
	s_nop 0
	v_add_f32_e32 v127, 1.0, v127
	v_rcp_f32_e32 v127, v127
	s_nop 0
	v_cndmask_b32_e64 v127, v133, v127, s[42:43]
	v_mul_f32_e32 v133, v128, v132
	v_fma_f32 v128, v128, v132, v54
	v_mul_f32_e32 v128, 0xbfb8aa3b, v128
	v_exp_f32_e32 v128, v128
	s_nop 0
	v_add_f32_e32 v128, 1.0, v128
	v_rcp_f32_e32 v128, v128
	s_nop 0
	v_cndmask_b32_e64 v128, v133, v128, s[42:43]
	v_mul_f32_e32 v133, v129, v132
	v_fma_f32 v129, v129, v132, v55
	v_mul_f32_e32 v129, 0xbfb8aa3b, v129
	v_exp_f32_e32 v129, v129
	s_nop 0
	v_add_f32_e32 v129, 1.0, v129
	v_rcp_f32_e32 v129, v129
	s_nop 0
	v_cndmask_b32_e64 v129, v133, v129, s[42:43]
	v_mul_f32_e32 v133, v122, v132
	v_fma_f32 v122, v122, v132, v44
	v_mul_f32_e32 v122, 0xbfb8aa3b, v122
	v_exp_f32_e32 v122, v122
	s_nop 0
	v_add_f32_e32 v122, 1.0, v122
	v_rcp_f32_e32 v122, v122
	s_nop 0
	v_cndmask_b32_e64 v133, v133, v122, s[42:43]
	v_mul_f32_e32 v122, v123, v132
	v_fma_f32 v123, v123, v132, v45
	v_mul_f32_e32 v123, 0xbfb8aa3b, v123
	v_exp_f32_e32 v123, v123
	s_nop 0
	v_add_f32_e32 v123, 1.0, v123
	v_rcp_f32_e32 v123, v123
	s_nop 0
	v_cndmask_b32_e64 v134, v122, v123, s[42:43]
	v_fma_f32 v123, v124, v132, v46
	v_mul_f32_e32 v123, 0xbfb8aa3b, v123
	v_exp_f32_e32 v123, v123
	v_mul_f32_e32 v122, v124, v132
	v_add_f32_e32 v123, 1.0, v123
	v_rcp_f32_e32 v123, v123
	s_nop 0
	v_cndmask_b32_e64 v135, v122, v123, s[42:43]
	v_fma_f32 v123, v125, v132, v47
	v_mul_f32_e32 v123, 0xbfb8aa3b, v123
	v_exp_f32_e32 v123, v123
	v_mul_f32_e32 v122, v125, v132
	v_add_f32_e32 v123, 1.0, v123
	v_rcp_f32_e32 v123, v123
	s_nop 0
	v_cndmask_b32_e64 v125, v122, v123, s[42:43]
	v_cvt_pk_bf16_f32 v122, v126, v127
	v_cvt_pk_bf16_f32 v123, v128, v129
	v_cvt_pk_bf16_f32 v124, v133, v134
	v_cvt_pk_bf16_f32 v125, v135, v125
	global_store_dwordx4 v[130:131], v[122:125], off
	s_nop 1
	v_mul_f32_e32 v122, v118, v132
	v_fma_f32 v118, v118, v132, v40
	v_mul_f32_e32 v118, 0xbfb8aa3b, v118
	v_exp_f32_e32 v118, v118
	s_nop 0
	v_add_f32_e32 v118, 1.0, v118
	v_rcp_f32_e32 v118, v118
	s_nop 0
	v_cndmask_b32_e64 v118, v122, v118, s[42:43]
	v_mul_f32_e32 v122, v119, v132
	v_fma_f32 v119, v119, v132, v41
	v_mul_f32_e32 v119, 0xbfb8aa3b, v119
	v_exp_f32_e32 v119, v119
	s_nop 0
	v_add_f32_e32 v119, 1.0, v119
	v_rcp_f32_e32 v119, v119
	s_nop 0
	v_cndmask_b32_e64 v119, v122, v119, s[42:43]
	v_mul_f32_e32 v122, v120, v132
	v_fma_f32 v120, v120, v132, v42
	v_mul_f32_e32 v120, 0xbfb8aa3b, v120
	v_exp_f32_e32 v120, v120
	s_nop 0
	v_add_f32_e32 v120, 1.0, v120
	v_rcp_f32_e32 v120, v120
	s_nop 0
	v_cndmask_b32_e64 v120, v122, v120, s[42:43]
	v_mul_f32_e32 v122, v121, v132
	v_fma_f32 v121, v121, v132, v43
	v_mul_f32_e32 v121, 0xbfb8aa3b, v121
	v_exp_f32_e32 v121, v121
	s_nop 0
	v_add_f32_e32 v121, 1.0, v121
	v_rcp_f32_e32 v121, v121
	s_nop 0
	v_cndmask_b32_e64 v121, v122, v121, s[42:43]
	v_mul_f32_e32 v122, v114, v132
	v_fma_f32 v114, v114, v132, v32
	v_mul_f32_e32 v114, 0xbfb8aa3b, v114
	v_exp_f32_e32 v114, v114
	s_nop 0
	v_add_f32_e32 v114, 1.0, v114
	v_rcp_f32_e32 v114, v114
	s_nop 0
	v_cndmask_b32_e64 v122, v122, v114, s[42:43]
	v_mul_f32_e32 v114, v115, v132
	v_fma_f32 v115, v115, v132, v33
	v_mul_f32_e32 v115, 0xbfb8aa3b, v115
	v_exp_f32_e32 v115, v115
	s_nop 0
	v_add_f32_e32 v115, 1.0, v115
	v_rcp_f32_e32 v115, v115
	s_nop 0
	v_cndmask_b32_e64 v123, v114, v115, s[42:43]
	v_fma_f32 v115, v116, v132, v34
	v_mul_f32_e32 v115, 0xbfb8aa3b, v115
	v_exp_f32_e32 v115, v115
	v_mul_f32_e32 v114, v116, v132
	v_add_f32_e32 v115, 1.0, v115
	v_rcp_f32_e32 v115, v115
	s_nop 0
	v_cndmask_b32_e64 v124, v114, v115, s[42:43]
	v_fma_f32 v115, v117, v132, v35
	v_mul_f32_e32 v115, 0xbfb8aa3b, v115
	v_exp_f32_e32 v115, v115
	v_mul_f32_e32 v114, v117, v132
	v_add_f32_e32 v115, 1.0, v115
	v_rcp_f32_e32 v115, v115
	s_nop 0
	v_cndmask_b32_e64 v117, v114, v115, s[42:43]
	v_cvt_pk_bf16_f32 v114, v118, v119
	v_cvt_pk_bf16_f32 v115, v120, v121
	v_cvt_pk_bf16_f32 v116, v122, v123
	v_cvt_pk_bf16_f32 v117, v124, v117
	global_store_dwordx4 v[130:131], v[114:117], off offset:256
	s_nop 1
	v_fmamk_f32 v114, v177, 0x3a800000, v223
	v_rsq_f32_e32 v116, v114
	v_mad_i64_i32 v[114:115], s[0:1], v176, s89, v[156:157]
	v_lshl_add_u64 v[114:115], v[114:115], 0, v[158:159]
	v_mul_f32_e32 v117, v110, v116
	v_fma_f32 v110, v110, v116, v52
	v_mul_f32_e32 v110, 0xbfb8aa3b, v110
	v_exp_f32_e32 v110, v110
	s_nop 0
	v_add_f32_e32 v110, 1.0, v110
	v_rcp_f32_e32 v110, v110
	s_nop 0
	v_cndmask_b32_e64 v110, v117, v110, s[42:43]
	v_mul_f32_e32 v117, v111, v116
	v_fma_f32 v111, v111, v116, v53
	v_mul_f32_e32 v111, 0xbfb8aa3b, v111
	v_exp_f32_e32 v111, v111
	s_nop 0
	v_add_f32_e32 v111, 1.0, v111
	v_rcp_f32_e32 v111, v111
	s_nop 0
	v_cndmask_b32_e64 v111, v117, v111, s[42:43]
	v_mul_f32_e32 v117, v112, v116
	v_fma_f32 v112, v112, v116, v54
	v_mul_f32_e32 v112, 0xbfb8aa3b, v112
	v_exp_f32_e32 v112, v112
	s_nop 0
	v_add_f32_e32 v112, 1.0, v112
	v_rcp_f32_e32 v112, v112
	s_nop 0
	v_cndmask_b32_e64 v112, v117, v112, s[42:43]
	v_mul_f32_e32 v117, v113, v116
	v_fma_f32 v113, v113, v116, v55
	v_mul_f32_e32 v113, 0xbfb8aa3b, v113
	v_exp_f32_e32 v113, v113
	s_nop 0
	v_add_f32_e32 v113, 1.0, v113
	v_rcp_f32_e32 v113, v113
	s_nop 0
	v_cndmask_b32_e64 v113, v117, v113, s[42:43]
	v_mul_f32_e32 v117, v106, v116
	v_fma_f32 v106, v106, v116, v44
; __device__ __forceinline__ u32x4 pack8(const float* f) { u32x4 w; w.x = cvt_pk_bf16(f[0], f[1]); w.y = cvt_pk_bf16(f[2], f[3]); w.z = cvt_pk_bf16(f[4], f[5]); w.w = cvt_pk_bf16(f[6], f[7]); return w; }
;     __device__ __forceinline__ void operator()(AccT& acc, const Unit& u, int wr, int wc, int fr, int fq) const {
;     ...
;         for (int ai = 0; ai < 2; ++ai)
; #pragma unroll
;             for (int m = 0; m < 4; ++m) {
;                 const int row = u.pm * 256 + ai * 128 + wr * 64 + m * 16 + fr;
;                 const float rs = __builtin_amdgcn_rsqf(rsv[ai][m] * (1.0f / 1024.0f) + EPS);
;                 bf16_t* rowp = P + (size_t)row * INW + col0;
; #pragma unroll
;                 for (int bj = 0; bj < 2; ++bj) {
;                     float v[8];
; #pragma unroll
;                     for (int n = 0; n < 2; ++n)
; #pragma unroll
;                         for (int j = 0; j < 4; ++j) {
;                             float x = acc[ai][bj][m][n][j] * rs;
;                             if (gate) { x += gb[bj][n][j]; x = __builtin_amdgcn_rcpf(1.0f + __builtin_amdgcn_exp2f(-LOG2E * x)); }
;                             v[n * 4 + j] = x;
;                         }
;                     *(u32x4*)(rowp + bj * 128) = pack8(v);
;                 }
;             }
	v_mul_f32_e32 v106, 0xbfb8aa3b, v106
	v_exp_f32_e32 v106, v106
	s_nop 0
	v_add_f32_e32 v106, 1.0, v106
	v_rcp_f32_e32 v106, v106
	s_nop 0
	v_cndmask_b32_e64 v117, v117, v106, s[42:43]
	v_mul_f32_e32 v106, v107, v116
	v_fma_f32 v107, v107, v116, v45
	v_mul_f32_e32 v107, 0xbfb8aa3b, v107
	v_exp_f32_e32 v107, v107
	s_nop 0
	v_add_f32_e32 v107, 1.0, v107
	v_rcp_f32_e32 v107, v107
	s_nop 0
	v_cndmask_b32_e64 v118, v106, v107, s[42:43]
	v_fma_f32 v107, v108, v116, v46
	v_mul_f32_e32 v107, 0xbfb8aa3b, v107
	v_exp_f32_e32 v107, v107
	v_mul_f32_e32 v106, v108, v116
	v_add_f32_e32 v107, 1.0, v107
	v_rcp_f32_e32 v107, v107
	s_nop 0
	v_cndmask_b32_e64 v119, v106, v107, s[42:43]
	v_fma_f32 v107, v109, v116, v47
	v_mul_f32_e32 v107, 0xbfb8aa3b, v107
	v_exp_f32_e32 v107, v107
	v_mul_f32_e32 v106, v109, v116
	v_add_f32_e32 v107, 1.0, v107
	v_rcp_f32_e32 v107, v107
	s_nop 0
	v_cndmask_b32_e64 v109, v106, v107, s[42:43]
	v_cvt_pk_bf16_f32 v106, v110, v111
	v_cvt_pk_bf16_f32 v107, v112, v113
	v_cvt_pk_bf16_f32 v108, v117, v118
	v_cvt_pk_bf16_f32 v109, v119, v109
	global_store_dwordx4 v[114:115], v[106:109], off
	s_nop 1
	v_mul_f32_e32 v106, v102, v116
	v_fma_f32 v102, v102, v116, v40
	v_mul_f32_e32 v102, 0xbfb8aa3b, v102
	v_exp_f32_e32 v102, v102
	s_nop 0
	v_add_f32_e32 v102, 1.0, v102
	v_rcp_f32_e32 v102, v102
	s_nop 0
	v_cndmask_b32_e64 v102, v106, v102, s[42:43]
	v_mul_f32_e32 v106, v103, v116
	v_fma_f32 v103, v103, v116, v41
	v_mul_f32_e32 v103, 0xbfb8aa3b, v103
	v_exp_f32_e32 v103, v103
	s_nop 0
	v_add_f32_e32 v103, 1.0, v103
	v_rcp_f32_e32 v103, v103
	s_nop 0
	v_cndmask_b32_e64 v103, v106, v103, s[42:43]
	v_mul_f32_e32 v106, v104, v116
	v_fma_f32 v104, v104, v116, v42
	v_mul_f32_e32 v104, 0xbfb8aa3b, v104
	v_exp_f32_e32 v104, v104
	s_nop 0
	v_add_f32_e32 v104, 1.0, v104
	v_rcp_f32_e32 v104, v104
	s_nop 0
	v_cndmask_b32_e64 v104, v106, v104, s[42:43]
	v_mul_f32_e32 v106, v105, v116
	v_fma_f32 v105, v105, v116, v43
	v_mul_f32_e32 v105, 0xbfb8aa3b, v105
	v_exp_f32_e32 v105, v105
	s_nop 0
	v_add_f32_e32 v105, 1.0, v105
	v_rcp_f32_e32 v105, v105
	s_nop 0
	v_cndmask_b32_e64 v105, v106, v105, s[42:43]
	v_mul_f32_e32 v106, v98, v116
	v_fma_f32 v98, v98, v116, v32
	v_mul_f32_e32 v98, 0xbfb8aa3b, v98
	v_exp_f32_e32 v98, v98
	s_nop 0
	v_add_f32_e32 v98, 1.0, v98
	v_rcp_f32_e32 v98, v98
	s_nop 0
	v_cndmask_b32_e64 v106, v106, v98, s[42:43]
	v_mul_f32_e32 v98, v99, v116
	v_fma_f32 v99, v99, v116, v33
	v_mul_f32_e32 v99, 0xbfb8aa3b, v99
	v_exp_f32_e32 v99, v99
	s_nop 0
	v_add_f32_e32 v99, 1.0, v99
	v_rcp_f32_e32 v99, v99
	s_nop 0
	v_cndmask_b32_e64 v107, v98, v99, s[42:43]
	v_fma_f32 v99, v100, v116, v34
	v_mul_f32_e32 v99, 0xbfb8aa3b, v99
	v_exp_f32_e32 v99, v99
	v_mul_f32_e32 v98, v100, v116
	v_add_f32_e32 v99, 1.0, v99
	v_rcp_f32_e32 v99, v99
	s_nop 0
	v_cndmask_b32_e64 v108, v98, v99, s[42:43]
	v_fma_f32 v99, v101, v116, v35
	v_mul_f32_e32 v99, 0xbfb8aa3b, v99
	v_exp_f32_e32 v99, v99
	v_mul_f32_e32 v98, v101, v116
	v_add_f32_e32 v99, 1.0, v99
	v_rcp_f32_e32 v99, v99
	s_nop 0
	v_cndmask_b32_e64 v101, v98, v99, s[42:43]
	v_cvt_pk_bf16_f32 v98, v102, v103
	v_cvt_pk_bf16_f32 v99, v104, v105
	v_cvt_pk_bf16_f32 v100, v106, v107
	v_cvt_pk_bf16_f32 v101, v108, v101
	global_store_dwordx4 v[114:115], v[98:101], off offset:256
	s_nop 1
	v_fmamk_f32 v98, v175, 0x3a800000, v223
	v_rsq_f32_e32 v100, v98
	v_mad_i64_i32 v[98:99], s[0:1], v174, s89, v[156:157]
	v_lshl_add_u64 v[98:99], v[98:99], 0, v[158:159]
	v_mul_f32_e32 v101, v92, v100
	v_fma_f32 v92, v92, v100, v52
	v_mul_f32_e32 v92, 0xbfb8aa3b, v92
	v_exp_f32_e32 v92, v92
	s_nop 0
	v_add_f32_e32 v92, 1.0, v92
	v_rcp_f32_e32 v92, v92
	s_nop 0
	v_cndmask_b32_e64 v92, v101, v92, s[42:43]
	v_mul_f32_e32 v101, v93, v100
	v_fma_f32 v93, v93, v100, v53
	v_mul_f32_e32 v93, 0xbfb8aa3b, v93
	v_exp_f32_e32 v93, v93
	s_nop 0
	v_add_f32_e32 v93, 1.0, v93
	v_rcp_f32_e32 v93, v93
	s_nop 0
	v_cndmask_b32_e64 v93, v101, v93, s[42:43]
	v_mul_f32_e32 v101, v94, v100
	v_fma_f32 v94, v94, v100, v54
	v_mul_f32_e32 v94, 0xbfb8aa3b, v94
	v_exp_f32_e32 v94, v94
	s_nop 0
	v_add_f32_e32 v94, 1.0, v94
	v_rcp_f32_e32 v94, v94
	s_nop 0
	v_cndmask_b32_e64 v94, v101, v94, s[42:43]
	v_mul_f32_e32 v101, v95, v100
	v_fma_f32 v95, v95, v100, v55
	v_mul_f32_e32 v95, 0xbfb8aa3b, v95
	v_exp_f32_e32 v95, v95
	s_nop 0
	v_add_f32_e32 v95, 1.0, v95
	v_rcp_f32_e32 v95, v95
	s_nop 0
	v_cndmask_b32_e64 v95, v101, v95, s[42:43]
	v_mul_f32_e32 v101, v88, v100
	v_fma_f32 v88, v88, v100, v44
	v_mul_f32_e32 v88, 0xbfb8aa3b, v88
	v_exp_f32_e32 v88, v88
	s_nop 0
	v_add_f32_e32 v88, 1.0, v88
	v_rcp_f32_e32 v88, v88
	s_nop 0
	v_cndmask_b32_e64 v101, v101, v88, s[42:43]
	v_mul_f32_e32 v88, v89, v100
	v_fma_f32 v89, v89, v100, v45
	v_mul_f32_e32 v89, 0xbfb8aa3b, v89
	v_exp_f32_e32 v89, v89
	s_nop 0
	v_add_f32_e32 v89, 1.0, v89
	v_rcp_f32_e32 v89, v89
	s_nop 0
	v_cndmask_b32_e64 v102, v88, v89, s[42:43]
	v_fma_f32 v89, v90, v100, v46
	v_mul_f32_e32 v89, 0xbfb8aa3b, v89
	v_exp_f32_e32 v89, v89
	v_mul_f32_e32 v88, v90, v100
	v_add_f32_e32 v89, 1.0, v89
	v_rcp_f32_e32 v89, v89
	s_nop 0
	v_cndmask_b32_e64 v103, v88, v89, s[42:43]
	v_fma_f32 v89, v91, v100, v47
	v_mul_f32_e32 v89, 0xbfb8aa3b, v89
	v_exp_f32_e32 v89, v89
	v_mul_f32_e32 v88, v91, v100
	v_add_f32_e32 v89, 1.0, v89
	v_rcp_f32_e32 v89, v89
	s_nop 0
	v_cndmask_b32_e64 v91, v88, v89, s[42:43]
	v_cvt_pk_bf16_f32 v88, v92, v93
	v_cvt_pk_bf16_f32 v89, v94, v95
	v_cvt_pk_bf16_f32 v90, v101, v102
	v_cvt_pk_bf16_f32 v91, v103, v91
	global_store_dwordx4 v[98:99], v[88:91], off
	s_nop 1
	v_mul_f32_e32 v88, v84, v100
	v_fma_f32 v84, v84, v100, v40
	v_mul_f32_e32 v84, 0xbfb8aa3b, v84
	v_exp_f32_e32 v84, v84
	s_nop 0
; __device__ __forceinline__ u32x4 pack8(const float* f) { u32x4 w; w.x = cvt_pk_bf16(f[0], f[1]); w.y = cvt_pk_bf16(f[2], f[3]); w.z = cvt_pk_bf16(f[4], f[5]); w.w = cvt_pk_bf16(f[6], f[7]); return w; }
;     __device__ __forceinline__ void operator()(AccT& acc, const Unit& u, int wr, int wc, int fr, int fq) const {
;     ...
;         for (int ai = 0; ai < 2; ++ai)
; #pragma unroll
;             for (int m = 0; m < 4; ++m) {
;                 const int row = u.pm * 256 + ai * 128 + wr * 64 + m * 16 + fr;
;                 const float rs = __builtin_amdgcn_rsqf(rsv[ai][m] * (1.0f / 1024.0f) + EPS);
;                 bf16_t* rowp = P + (size_t)row * INW + col0;
; #pragma unroll
;                 for (int bj = 0; bj < 2; ++bj) {
;                     float v[8];
; #pragma unroll
;                     for (int n = 0; n < 2; ++n)
; #pragma unroll
;                         for (int j = 0; j < 4; ++j) {
;                             float x = acc[ai][bj][m][n][j] * rs;
;                             if (gate) { x += gb[bj][n][j]; x = __builtin_amdgcn_rcpf(1.0f + __builtin_amdgcn_exp2f(-LOG2E * x)); }
;                             v[n * 4 + j] = x;
;                         }
;                     *(u32x4*)(rowp + bj * 128) = pack8(v);
;                 }
;             }
	v_add_f32_e32 v84, 1.0, v84
	v_rcp_f32_e32 v84, v84
	s_nop 0
	v_cndmask_b32_e64 v84, v88, v84, s[42:43]
	v_mul_f32_e32 v88, v85, v100
	v_fma_f32 v85, v85, v100, v41
	v_mul_f32_e32 v85, 0xbfb8aa3b, v85
	v_exp_f32_e32 v85, v85
	s_nop 0
	v_add_f32_e32 v85, 1.0, v85
	v_rcp_f32_e32 v85, v85
	s_nop 0
	v_cndmask_b32_e64 v85, v88, v85, s[42:43]
	v_mul_f32_e32 v88, v86, v100
	v_fma_f32 v86, v86, v100, v42
	v_mul_f32_e32 v86, 0xbfb8aa3b, v86
	v_exp_f32_e32 v86, v86
	s_nop 0
	v_add_f32_e32 v86, 1.0, v86
	v_rcp_f32_e32 v86, v86
	s_nop 0
	v_cndmask_b32_e64 v86, v88, v86, s[42:43]
	v_mul_f32_e32 v88, v87, v100
	v_fma_f32 v87, v87, v100, v43
	v_mul_f32_e32 v87, 0xbfb8aa3b, v87
	v_exp_f32_e32 v87, v87
	s_nop 0
	v_add_f32_e32 v87, 1.0, v87
	v_rcp_f32_e32 v87, v87
	s_nop 0
	v_cndmask_b32_e64 v87, v88, v87, s[42:43]
	v_mul_f32_e32 v88, v80, v100
	v_fma_f32 v80, v80, v100, v32
	v_mul_f32_e32 v80, 0xbfb8aa3b, v80
	v_exp_f32_e32 v80, v80
	s_nop 0
	v_add_f32_e32 v80, 1.0, v80
	v_rcp_f32_e32 v80, v80
	s_nop 0
	v_cndmask_b32_e64 v88, v88, v80, s[42:43]
	v_mul_f32_e32 v80, v81, v100
	v_fma_f32 v81, v81, v100, v33
	v_mul_f32_e32 v81, 0xbfb8aa3b, v81
	v_exp_f32_e32 v81, v81
	s_nop 0
	v_add_f32_e32 v81, 1.0, v81
	v_rcp_f32_e32 v81, v81
	s_nop 0
	v_cndmask_b32_e64 v89, v80, v81, s[42:43]
	v_fma_f32 v81, v82, v100, v34
	v_mul_f32_e32 v81, 0xbfb8aa3b, v81
	v_exp_f32_e32 v81, v81
	v_mul_f32_e32 v80, v82, v100
	v_add_f32_e32 v81, 1.0, v81
	v_rcp_f32_e32 v81, v81
	s_nop 0
	v_cndmask_b32_e64 v90, v80, v81, s[42:43]
	v_fma_f32 v81, v83, v100, v35
	v_mul_f32_e32 v81, 0xbfb8aa3b, v81
	v_exp_f32_e32 v81, v81
	v_mul_f32_e32 v80, v83, v100
	v_add_f32_e32 v81, 1.0, v81
	v_rcp_f32_e32 v81, v81
	s_nop 0
	v_cndmask_b32_e64 v83, v80, v81, s[42:43]
	v_cvt_pk_bf16_f32 v80, v84, v85
	v_cvt_pk_bf16_f32 v81, v86, v87
	v_cvt_pk_bf16_f32 v82, v88, v89
	v_cvt_pk_bf16_f32 v83, v90, v83
	global_store_dwordx4 v[98:99], v[80:83], off offset:256
	s_nop 1
	v_fmamk_f32 v80, v173, 0x3a800000, v223
	v_rsq_f32_e32 v82, v80
	v_mad_i64_i32 v[80:81], s[0:1], v172, s89, v[156:157]
	v_lshl_add_u64 v[80:81], v[80:81], 0, v[158:159]
	v_mul_f32_e32 v83, v76, v82
	v_fma_f32 v76, v76, v82, v52
	v_mul_f32_e32 v76, 0xbfb8aa3b, v76
	v_exp_f32_e32 v76, v76
	s_nop 0
	v_add_f32_e32 v76, 1.0, v76
	v_rcp_f32_e32 v76, v76
	s_nop 0
	v_cndmask_b32_e64 v76, v83, v76, s[42:43]
	v_mul_f32_e32 v83, v77, v82
	v_fma_f32 v77, v77, v82, v53
	v_mul_f32_e32 v77, 0xbfb8aa3b, v77
	v_exp_f32_e32 v77, v77
	s_nop 0
	v_add_f32_e32 v77, 1.0, v77
	v_rcp_f32_e32 v77, v77
	s_nop 0
	v_cndmask_b32_e64 v77, v83, v77, s[42:43]
	v_mul_f32_e32 v83, v78, v82
	v_fma_f32 v78, v78, v82, v54
	v_mul_f32_e32 v78, 0xbfb8aa3b, v78
	v_exp_f32_e32 v78, v78
	s_nop 0
	v_add_f32_e32 v78, 1.0, v78
	v_rcp_f32_e32 v78, v78
	s_nop 0
	v_cndmask_b32_e64 v78, v83, v78, s[42:43]
	v_mul_f32_e32 v83, v79, v82
	v_fma_f32 v79, v79, v82, v55
	v_mul_f32_e32 v79, 0xbfb8aa3b, v79
	v_exp_f32_e32 v79, v79
	s_nop 0
	v_add_f32_e32 v79, 1.0, v79
	v_rcp_f32_e32 v79, v79
	s_nop 0
	v_cndmask_b32_e64 v79, v83, v79, s[42:43]
	v_mul_f32_e32 v83, v72, v82
	v_fma_f32 v72, v72, v82, v44
	v_mul_f32_e32 v72, 0xbfb8aa3b, v72
	v_exp_f32_e32 v72, v72
	s_nop 0
	v_add_f32_e32 v72, 1.0, v72
	v_rcp_f32_e32 v72, v72
	s_nop 0
	v_cndmask_b32_e64 v83, v83, v72, s[42:43]
	v_mul_f32_e32 v72, v73, v82
	v_fma_f32 v73, v73, v82, v45
	v_mul_f32_e32 v73, 0xbfb8aa3b, v73
	v_exp_f32_e32 v73, v73
	s_nop 0
	v_add_f32_e32 v73, 1.0, v73
	v_rcp_f32_e32 v73, v73
	s_nop 0
	v_cndmask_b32_e64 v84, v72, v73, s[42:43]
	v_fma_f32 v73, v74, v82, v46
	v_mul_f32_e32 v73, 0xbfb8aa3b, v73
	v_exp_f32_e32 v73, v73
	v_mul_f32_e32 v72, v74, v82
	v_add_f32_e32 v73, 1.0, v73
	v_rcp_f32_e32 v73, v73
	s_nop 0
	v_cndmask_b32_e64 v85, v72, v73, s[42:43]
	v_fma_f32 v73, v75, v82, v47
	v_mul_f32_e32 v73, 0xbfb8aa3b, v73
	v_exp_f32_e32 v73, v73
	v_mul_f32_e32 v72, v75, v82
	v_add_f32_e32 v73, 1.0, v73
	v_rcp_f32_e32 v73, v73
	s_nop 0
	v_cndmask_b32_e64 v75, v72, v73, s[42:43]
	v_cvt_pk_bf16_f32 v72, v76, v77
	v_cvt_pk_bf16_f32 v73, v78, v79
	v_cvt_pk_bf16_f32 v74, v83, v84
	v_cvt_pk_bf16_f32 v75, v85, v75
	global_store_dwordx4 v[80:81], v[72:75], off
	s_nop 1
	v_mul_f32_e32 v72, v68, v82
	v_fma_f32 v68, v68, v82, v40
	v_mul_f32_e32 v68, 0xbfb8aa3b, v68
	v_exp_f32_e32 v68, v68
	s_nop 0
	v_add_f32_e32 v68, 1.0, v68
	v_rcp_f32_e32 v68, v68
	s_nop 0
	v_cndmask_b32_e64 v68, v72, v68, s[42:43]
	v_mul_f32_e32 v72, v69, v82
	v_fma_f32 v69, v69, v82, v41
	v_mul_f32_e32 v69, 0xbfb8aa3b, v69
	v_exp_f32_e32 v69, v69
	s_nop 0
	v_add_f32_e32 v69, 1.0, v69
	v_rcp_f32_e32 v69, v69
	s_nop 0
	v_cndmask_b32_e64 v69, v72, v69, s[42:43]
	v_mul_f32_e32 v72, v70, v82
	v_fma_f32 v70, v70, v82, v42
	v_mul_f32_e32 v70, 0xbfb8aa3b, v70
	v_exp_f32_e32 v70, v70
	s_nop 0
	v_add_f32_e32 v70, 1.0, v70
	v_rcp_f32_e32 v70, v70
	s_nop 0
	v_cndmask_b32_e64 v70, v72, v70, s[42:43]
	v_mul_f32_e32 v72, v71, v82
	v_fma_f32 v71, v71, v82, v43
	v_mul_f32_e32 v71, 0xbfb8aa3b, v71
	v_exp_f32_e32 v71, v71
	s_nop 0
	v_add_f32_e32 v71, 1.0, v71
	v_rcp_f32_e32 v71, v71
	s_nop 0
	v_cndmask_b32_e64 v71, v72, v71, s[42:43]
	v_mul_f32_e32 v72, v64, v82
	v_fma_f32 v64, v64, v82, v32
	v_mul_f32_e32 v64, 0xbfb8aa3b, v64
	v_exp_f32_e32 v64, v64
	s_nop 0
	v_add_f32_e32 v64, 1.0, v64
	v_rcp_f32_e32 v64, v64
	s_nop 0
	v_cndmask_b32_e64 v72, v72, v64, s[42:43]
	v_mul_f32_e32 v64, v65, v82
	v_fma_f32 v65, v65, v82, v33
	v_mul_f32_e32 v65, 0xbfb8aa3b, v65
	v_exp_f32_e32 v65, v65
	s_nop 0
	v_add_f32_e32 v65, 1.0, v65
	v_rcp_f32_e32 v65, v65
	s_nop 0
	v_cndmask_b32_e64 v73, v64, v65, s[42:43]
	v_fma_f32 v65, v66, v82, v34
	v_mul_f32_e32 v65, 0xbfb8aa3b, v65
	v_exp_f32_e32 v65, v65
	v_mul_f32_e32 v64, v66, v82
; __device__ __forceinline__ u32x4 pack8(const float* f) { u32x4 w; w.x = cvt_pk_bf16(f[0], f[1]); w.y = cvt_pk_bf16(f[2], f[3]); w.z = cvt_pk_bf16(f[4], f[5]); w.w = cvt_pk_bf16(f[6], f[7]); return w; }
;     __device__ __forceinline__ void operator()(AccT& acc, const Unit& u, int wr, int wc, int fr, int fq) const {
;     ...
;         for (int ai = 0; ai < 2; ++ai)
; #pragma unroll
;             for (int m = 0; m < 4; ++m) {
;                 const int row = u.pm * 256 + ai * 128 + wr * 64 + m * 16 + fr;
;                 const float rs = __builtin_amdgcn_rsqf(rsv[ai][m] * (1.0f / 1024.0f) + EPS);
;                 bf16_t* rowp = P + (size_t)row * INW + col0;
; #pragma unroll
;                 for (int bj = 0; bj < 2; ++bj) {
;                     float v[8];
; #pragma unroll
;                     for (int n = 0; n < 2; ++n)
; #pragma unroll
;                         for (int j = 0; j < 4; ++j) {
;                             float x = acc[ai][bj][m][n][j] * rs;
;                             if (gate) { x += gb[bj][n][j]; x = __builtin_amdgcn_rcpf(1.0f + __builtin_amdgcn_exp2f(-LOG2E * x)); }
;                             v[n * 4 + j] = x;
;                         }
;                     *(u32x4*)(rowp + bj * 128) = pack8(v);
;                 }
;             }
	v_add_f32_e32 v65, 1.0, v65
	v_rcp_f32_e32 v65, v65
	s_nop 0
	v_cndmask_b32_e64 v74, v64, v65, s[42:43]
	v_fma_f32 v65, v67, v82, v35
	v_mul_f32_e32 v65, 0xbfb8aa3b, v65
	v_exp_f32_e32 v65, v65
	v_mul_f32_e32 v64, v67, v82
	v_add_f32_e32 v65, 1.0, v65
	v_rcp_f32_e32 v65, v65
	s_nop 0
	v_cndmask_b32_e64 v67, v64, v65, s[42:43]
	v_cvt_pk_bf16_f32 v64, v68, v69
	v_cvt_pk_bf16_f32 v65, v70, v71
	v_cvt_pk_bf16_f32 v66, v72, v73
	v_cvt_pk_bf16_f32 v67, v74, v67
	global_store_dwordx4 v[80:81], v[64:67], off offset:256
	s_nop 1
	v_fmamk_f32 v64, v171, 0x3a800000, v223
	v_rsq_f32_e32 v66, v64
	v_mad_i64_i32 v[64:65], s[0:1], v170, s89, v[156:157]
	v_lshl_add_u64 v[64:65], v[64:65], 0, v[158:159]
	v_mul_f32_e32 v67, v60, v66
	v_fma_f32 v60, v60, v66, v52
	v_mul_f32_e32 v60, 0xbfb8aa3b, v60
	v_exp_f32_e32 v60, v60
	s_nop 0
	v_add_f32_e32 v60, 1.0, v60
	v_rcp_f32_e32 v60, v60
	s_nop 0
	v_cndmask_b32_e64 v60, v67, v60, s[42:43]
	v_mul_f32_e32 v67, v61, v66
	v_fma_f32 v61, v61, v66, v53
	v_mul_f32_e32 v61, 0xbfb8aa3b, v61
	v_exp_f32_e32 v61, v61
	s_nop 0
	v_add_f32_e32 v61, 1.0, v61
	v_rcp_f32_e32 v61, v61
	s_nop 0
	v_cndmask_b32_e64 v61, v67, v61, s[42:43]
	v_mul_f32_e32 v67, v62, v66
	v_fma_f32 v62, v62, v66, v54
	v_mul_f32_e32 v62, 0xbfb8aa3b, v62
	v_exp_f32_e32 v62, v62
	s_nop 0
	v_add_f32_e32 v62, 1.0, v62
	v_rcp_f32_e32 v62, v62
	s_nop 0
	v_cndmask_b32_e64 v62, v67, v62, s[42:43]
	v_mul_f32_e32 v67, v63, v66
	v_fma_f32 v63, v63, v66, v55
	v_mul_f32_e32 v63, 0xbfb8aa3b, v63
	v_exp_f32_e32 v63, v63
	s_nop 0
	v_add_f32_e32 v63, 1.0, v63
	v_rcp_f32_e32 v63, v63
	s_nop 0
	v_cndmask_b32_e64 v63, v67, v63, s[42:43]
	v_mul_f32_e32 v67, v56, v66
	v_fma_f32 v56, v56, v66, v44
	v_mul_f32_e32 v56, 0xbfb8aa3b, v56
	v_exp_f32_e32 v56, v56
	s_nop 0
	v_add_f32_e32 v56, 1.0, v56
	v_rcp_f32_e32 v56, v56
	s_nop 0
	v_cndmask_b32_e64 v67, v67, v56, s[42:43]
	v_mul_f32_e32 v56, v57, v66
	v_fma_f32 v57, v57, v66, v45
	v_mul_f32_e32 v57, 0xbfb8aa3b, v57
	v_exp_f32_e32 v57, v57
	s_nop 0
	v_add_f32_e32 v57, 1.0, v57
	v_rcp_f32_e32 v57, v57
	s_nop 0
	v_cndmask_b32_e64 v68, v56, v57, s[42:43]
	v_fma_f32 v57, v58, v66, v46
	v_mul_f32_e32 v57, 0xbfb8aa3b, v57
	v_exp_f32_e32 v57, v57
	v_mul_f32_e32 v56, v58, v66
	v_add_f32_e32 v57, 1.0, v57
	v_rcp_f32_e32 v57, v57
	s_nop 0
	v_cndmask_b32_e64 v69, v56, v57, s[42:43]
	v_fma_f32 v57, v59, v66, v47
	v_mul_f32_e32 v57, 0xbfb8aa3b, v57
	v_exp_f32_e32 v57, v57
	v_mul_f32_e32 v56, v59, v66
	v_add_f32_e32 v57, 1.0, v57
	v_rcp_f32_e32 v57, v57
	s_nop 0
	v_cndmask_b32_e64 v59, v56, v57, s[42:43]
	v_cvt_pk_bf16_f32 v56, v60, v61
	v_cvt_pk_bf16_f32 v57, v62, v63
	v_cvt_pk_bf16_f32 v58, v67, v68
	v_cvt_pk_bf16_f32 v59, v69, v59
	global_store_dwordx4 v[64:65], v[56:59], off
	s_nop 1
	v_mul_f32_e32 v56, v48, v66
	v_fma_f32 v48, v48, v66, v40
	v_mul_f32_e32 v48, 0xbfb8aa3b, v48
	v_exp_f32_e32 v48, v48
	s_nop 0
	v_add_f32_e32 v48, 1.0, v48
	v_rcp_f32_e32 v48, v48
	s_nop 0
	v_cndmask_b32_e64 v48, v56, v48, s[42:43]
	v_mul_f32_e32 v56, v49, v66
	v_fma_f32 v49, v49, v66, v41
	v_mul_f32_e32 v49, 0xbfb8aa3b, v49
	v_exp_f32_e32 v49, v49
	s_nop 0
	v_add_f32_e32 v49, 1.0, v49
	v_rcp_f32_e32 v49, v49
	s_nop 0
	v_cndmask_b32_e64 v49, v56, v49, s[42:43]
	v_mul_f32_e32 v56, v50, v66
	v_fma_f32 v50, v50, v66, v42
	v_mul_f32_e32 v50, 0xbfb8aa3b, v50
	v_exp_f32_e32 v50, v50
	s_nop 0
	v_add_f32_e32 v50, 1.0, v50
	v_rcp_f32_e32 v50, v50
	s_nop 0
	v_cndmask_b32_e64 v50, v56, v50, s[42:43]
	v_mul_f32_e32 v56, v51, v66
	v_fma_f32 v51, v51, v66, v43
	v_mul_f32_e32 v51, 0xbfb8aa3b, v51
	v_exp_f32_e32 v51, v51
	s_nop 0
	v_add_f32_e32 v51, 1.0, v51
	v_rcp_f32_e32 v51, v51
	s_nop 0
	v_cndmask_b32_e64 v51, v56, v51, s[42:43]
	v_mul_f32_e32 v56, v36, v66
	v_fma_f32 v36, v36, v66, v32
	v_mul_f32_e32 v36, 0xbfb8aa3b, v36
	v_exp_f32_e32 v36, v36
	s_nop 0
	v_add_f32_e32 v36, 1.0, v36
	v_rcp_f32_e32 v36, v36
	s_nop 0
	v_cndmask_b32_e64 v56, v56, v36, s[42:43]
	v_mul_f32_e32 v36, v37, v66
	v_fma_f32 v37, v37, v66, v33
	v_mul_f32_e32 v37, 0xbfb8aa3b, v37
	v_exp_f32_e32 v37, v37
	s_nop 0
	v_add_f32_e32 v37, 1.0, v37
	v_rcp_f32_e32 v37, v37
	s_nop 0
	v_cndmask_b32_e64 v57, v36, v37, s[42:43]
	v_fma_f32 v37, v38, v66, v34
	v_mul_f32_e32 v37, 0xbfb8aa3b, v37
	v_exp_f32_e32 v37, v37
	v_mul_f32_e32 v36, v38, v66
	v_add_f32_e32 v37, 1.0, v37
	v_rcp_f32_e32 v37, v37
	s_nop 0
	v_cndmask_b32_e64 v58, v36, v37, s[42:43]
	v_fma_f32 v37, v39, v66, v35
	v_mul_f32_e32 v37, 0xbfb8aa3b, v37
	v_exp_f32_e32 v37, v37
	v_mul_f32_e32 v36, v39, v66
	v_add_f32_e32 v37, 1.0, v37
	v_rcp_f32_e32 v37, v37
	s_nop 0
	v_cndmask_b32_e64 v39, v36, v37, s[42:43]
	v_cvt_pk_bf16_f32 v36, v48, v49
	v_cvt_pk_bf16_f32 v37, v50, v51
	v_cvt_pk_bf16_f32 v38, v56, v57
	v_cvt_pk_bf16_f32 v39, v58, v39
	global_store_dwordx4 v[64:65], v[36:39], off offset:256
	s_nop 1
	v_fmamk_f32 v36, v169, 0x3a800000, v223
	v_rsq_f32_e32 v38, v36
	v_mad_i64_i32 v[36:37], s[0:1], v168, s89, v[156:157]
	v_lshl_add_u64 v[36:37], v[36:37], 0, v[158:159]
	v_mul_f32_e32 v39, v28, v38
	v_fma_f32 v28, v28, v38, v52
	v_mul_f32_e32 v28, 0xbfb8aa3b, v28
	v_exp_f32_e32 v28, v28
	s_nop 0
	v_add_f32_e32 v28, 1.0, v28
	v_rcp_f32_e32 v28, v28
	s_nop 0
	v_cndmask_b32_e64 v28, v39, v28, s[42:43]
	v_mul_f32_e32 v39, v29, v38
	v_fma_f32 v29, v29, v38, v53
	v_mul_f32_e32 v29, 0xbfb8aa3b, v29
	v_exp_f32_e32 v29, v29
	s_nop 0
	v_add_f32_e32 v29, 1.0, v29
	v_rcp_f32_e32 v29, v29
	s_nop 0
	v_cndmask_b32_e64 v29, v39, v29, s[42:43]
	v_mul_f32_e32 v39, v30, v38
	v_fma_f32 v30, v30, v38, v54
	v_mul_f32_e32 v30, 0xbfb8aa3b, v30
	v_exp_f32_e32 v30, v30
	s_nop 0
	v_add_f32_e32 v30, 1.0, v30
	v_rcp_f32_e32 v30, v30
	s_nop 0
	v_cndmask_b32_e64 v30, v39, v30, s[42:43]
; __device__ __forceinline__ u32x4 pack8(const float* f) { u32x4 w; w.x = cvt_pk_bf16(f[0], f[1]); w.y = cvt_pk_bf16(f[2], f[3]); w.z = cvt_pk_bf16(f[4], f[5]); w.w = cvt_pk_bf16(f[6], f[7]); return w; }
;     __device__ __forceinline__ void operator()(AccT& acc, const Unit& u, int wr, int wc, int fr, int fq) const {
;     ...
;         for (int ai = 0; ai < 2; ++ai)
; #pragma unroll
;             for (int m = 0; m < 4; ++m) {
;                 const int row = u.pm * 256 + ai * 128 + wr * 64 + m * 16 + fr;
;                 const float rs = __builtin_amdgcn_rsqf(rsv[ai][m] * (1.0f / 1024.0f) + EPS);
;                 bf16_t* rowp = P + (size_t)row * INW + col0;
; #pragma unroll
;                 for (int bj = 0; bj < 2; ++bj) {
;                     float v[8];
; #pragma unroll
;                     for (int n = 0; n < 2; ++n)
; #pragma unroll
;                         for (int j = 0; j < 4; ++j) {
;                             float x = acc[ai][bj][m][n][j] * rs;
;                             if (gate) { x += gb[bj][n][j]; x = __builtin_amdgcn_rcpf(1.0f + __builtin_amdgcn_exp2f(-LOG2E * x)); }
;                             v[n * 4 + j] = x;
;                         }
;                     *(u32x4*)(rowp + bj * 128) = pack8(v);
;                 }
;             }
	v_mul_f32_e32 v39, v31, v38
	v_fma_f32 v31, v31, v38, v55
	v_mul_f32_e32 v31, 0xbfb8aa3b, v31
	v_exp_f32_e32 v31, v31
	s_nop 0
	v_add_f32_e32 v31, 1.0, v31
	v_rcp_f32_e32 v31, v31
	s_nop 0
	v_cndmask_b32_e64 v31, v39, v31, s[42:43]
	v_mul_f32_e32 v39, v24, v38
	v_fma_f32 v24, v24, v38, v44
	v_mul_f32_e32 v24, 0xbfb8aa3b, v24
	v_exp_f32_e32 v24, v24
	s_nop 0
	v_add_f32_e32 v24, 1.0, v24
	v_rcp_f32_e32 v24, v24
	s_nop 0
	v_cndmask_b32_e64 v39, v39, v24, s[42:43]
	v_mul_f32_e32 v24, v25, v38
	v_fma_f32 v25, v25, v38, v45
	v_mul_f32_e32 v25, 0xbfb8aa3b, v25
	v_exp_f32_e32 v25, v25
	s_nop 0
	v_add_f32_e32 v25, 1.0, v25
	v_rcp_f32_e32 v25, v25
	s_nop 0
	v_cndmask_b32_e64 v48, v24, v25, s[42:43]
	v_fma_f32 v25, v26, v38, v46
	v_mul_f32_e32 v25, 0xbfb8aa3b, v25
	v_exp_f32_e32 v25, v25
	v_mul_f32_e32 v24, v26, v38
	v_add_f32_e32 v25, 1.0, v25
	v_rcp_f32_e32 v25, v25
	s_nop 0
	v_cndmask_b32_e64 v49, v24, v25, s[42:43]
	v_fma_f32 v25, v27, v38, v47
	v_mul_f32_e32 v25, 0xbfb8aa3b, v25
	v_exp_f32_e32 v25, v25
	v_mul_f32_e32 v24, v27, v38
	v_add_f32_e32 v25, 1.0, v25
	v_rcp_f32_e32 v25, v25
	s_nop 0
	v_cndmask_b32_e64 v27, v24, v25, s[42:43]
	v_cvt_pk_bf16_f32 v24, v28, v29
	v_cvt_pk_bf16_f32 v25, v30, v31
	v_cvt_pk_bf16_f32 v26, v39, v48
	v_cvt_pk_bf16_f32 v27, v49, v27
	global_store_dwordx4 v[36:37], v[24:27], off
	s_nop 1
	v_mul_f32_e32 v24, v20, v38
	v_fma_f32 v20, v20, v38, v40
	v_mul_f32_e32 v20, 0xbfb8aa3b, v20
	v_exp_f32_e32 v20, v20
	s_nop 0
	v_add_f32_e32 v20, 1.0, v20
	v_rcp_f32_e32 v20, v20
	s_nop 0
	v_cndmask_b32_e64 v20, v24, v20, s[42:43]
	v_mul_f32_e32 v24, v21, v38
	v_fma_f32 v21, v21, v38, v41
	v_mul_f32_e32 v21, 0xbfb8aa3b, v21
	v_exp_f32_e32 v21, v21
	s_nop 0
	v_add_f32_e32 v21, 1.0, v21
	v_rcp_f32_e32 v21, v21
	s_nop 0
	v_cndmask_b32_e64 v21, v24, v21, s[42:43]
	v_mul_f32_e32 v24, v22, v38
	v_fma_f32 v22, v22, v38, v42
	v_mul_f32_e32 v22, 0xbfb8aa3b, v22
	v_exp_f32_e32 v22, v22
	s_nop 0
	v_add_f32_e32 v22, 1.0, v22
	v_rcp_f32_e32 v22, v22
	s_nop 0
	v_cndmask_b32_e64 v22, v24, v22, s[42:43]
	v_mul_f32_e32 v24, v23, v38
	v_fma_f32 v23, v23, v38, v43
	v_mul_f32_e32 v23, 0xbfb8aa3b, v23
	v_exp_f32_e32 v23, v23
	s_nop 0
	v_add_f32_e32 v23, 1.0, v23
	v_rcp_f32_e32 v23, v23
	s_nop 0
	v_cndmask_b32_e64 v23, v24, v23, s[42:43]
	v_mul_f32_e32 v24, v16, v38
	v_fma_f32 v16, v16, v38, v32
	v_mul_f32_e32 v16, 0xbfb8aa3b, v16
	v_exp_f32_e32 v16, v16
	s_nop 0
	v_add_f32_e32 v16, 1.0, v16
	v_rcp_f32_e32 v16, v16
	s_nop 0
	v_cndmask_b32_e64 v24, v24, v16, s[42:43]
	v_mul_f32_e32 v16, v17, v38
	v_fma_f32 v17, v17, v38, v33
	v_mul_f32_e32 v17, 0xbfb8aa3b, v17
	v_exp_f32_e32 v17, v17
	s_nop 0
	v_add_f32_e32 v17, 1.0, v17
	v_rcp_f32_e32 v17, v17
	s_nop 0
	v_cndmask_b32_e64 v25, v16, v17, s[42:43]
	v_fma_f32 v17, v18, v38, v34
	v_mul_f32_e32 v17, 0xbfb8aa3b, v17
	v_exp_f32_e32 v17, v17
	v_mul_f32_e32 v16, v18, v38
	v_add_f32_e32 v17, 1.0, v17
	v_rcp_f32_e32 v17, v17
	s_nop 0
	v_cndmask_b32_e64 v26, v16, v17, s[42:43]
	v_fma_f32 v17, v19, v38, v35
	v_mul_f32_e32 v17, 0xbfb8aa3b, v17
	v_exp_f32_e32 v17, v17
	v_mul_f32_e32 v16, v19, v38
	v_add_f32_e32 v17, 1.0, v17
	v_rcp_f32_e32 v17, v17
	s_nop 0
	v_cndmask_b32_e64 v19, v16, v17, s[42:43]
	v_cvt_pk_bf16_f32 v16, v20, v21
	v_cvt_pk_bf16_f32 v17, v22, v23
	v_cvt_pk_bf16_f32 v18, v24, v25
	v_cvt_pk_bf16_f32 v19, v26, v19
	global_store_dwordx4 v[36:37], v[16:19], off offset:256
	s_nop 1
	v_fmamk_f32 v16, v167, 0x3a800000, v223
	v_rsq_f32_e32 v18, v16
	v_mad_i64_i32 v[16:17], s[0:1], v166, s89, v[156:157]
	v_lshl_add_u64 v[16:17], v[16:17], 0, v[158:159]
	v_fmac_f32_e32 v52, v12, v18
	v_mul_f32_e32 v19, v12, v18
	v_mul_f32_e32 v12, 0xbfb8aa3b, v52
	v_exp_f32_e32 v12, v12
	v_fmac_f32_e32 v53, v13, v18
	v_fmac_f32_e32 v54, v14, v18
	v_fmac_f32_e32 v55, v15, v18
; __device__ __forceinline__ u32x4 pack8(const float* f) { u32x4 w; w.x = cvt_pk_bf16(f[0], f[1]); w.y = cvt_pk_bf16(f[2], f[3]); w.z = cvt_pk_bf16(f[4], f[5]); w.w = cvt_pk_bf16(f[6], f[7]); return w; }
; #define PG8_BAR __builtin_amdgcn_s_barrier()
; template <class Epi, class Sched>
; __device__ __forceinline__ void gemm_phase(LAS unsigned char* lds, const Gemm g, const Sched& S, const Epi& E) {
;     ...
;         if (wr == 1) PG8_BAR;
;     __device__ __forceinline__ void operator()(AccT& acc, const Unit& u, int wr, int wc, int fr, int fq) const {
;     ...
;         for (int ai = 0; ai < 2; ++ai)
; #pragma unroll
;             for (int m = 0; m < 4; ++m) {
;                 const int row = u.pm * 256 + ai * 128 + wr * 64 + m * 16 + fr;
;                 const float rs = __builtin_amdgcn_rsqf(rsv[ai][m] * (1.0f / 1024.0f) + EPS);
;                 bf16_t* rowp = P + (size_t)row * INW + col0;
; #pragma unroll
;                 for (int bj = 0; bj < 2; ++bj) {
;                     float v[8];
; #pragma unroll
;                     for (int n = 0; n < 2; ++n)
; #pragma unroll
;                         for (int j = 0; j < 4; ++j) {
;                             float x = acc[ai][bj][m][n][j] * rs;
;                             if (gate) { x += gb[bj][n][j]; x = __builtin_amdgcn_rcpf(1.0f + __builtin_amdgcn_exp2f(-LOG2E * x)); }
;                             v[n * 4 + j] = x;
;                         }
;                     *(u32x4*)(rowp + bj * 128) = pack8(v);
;                 }
;             }
	v_add_f32_e32 v12, 1.0, v12
	v_rcp_f32_e32 v12, v12
	v_fmac_f32_e32 v44, v8, v18
	v_fmac_f32_e32 v45, v9, v18
	v_fmac_f32_e32 v46, v10, v18
	v_cndmask_b32_e64 v12, v19, v12, s[42:43]
	v_mul_f32_e32 v19, v13, v18
	v_mul_f32_e32 v13, 0xbfb8aa3b, v53
	v_exp_f32_e32 v13, v13
	v_fmac_f32_e32 v47, v11, v18
	v_fmac_f32_e32 v40, v4, v18
	v_fmac_f32_e32 v41, v5, v18
	v_add_f32_e32 v13, 1.0, v13
	v_rcp_f32_e32 v13, v13
	v_fmac_f32_e32 v42, v6, v18
	v_fmac_f32_e32 v43, v7, v18
	v_fmac_f32_e32 v32, v0, v18
	v_cndmask_b32_e64 v13, v19, v13, s[42:43]
	v_mul_f32_e32 v19, v14, v18
	v_mul_f32_e32 v14, 0xbfb8aa3b, v54
	v_exp_f32_e32 v14, v14
	v_fmac_f32_e32 v33, v1, v18
	v_fmac_f32_e32 v34, v2, v18
	v_fmac_f32_e32 v35, v3, v18
	v_add_f32_e32 v14, 1.0, v14
	v_rcp_f32_e32 v14, v14
	s_mov_b64 s[0:1], -1
	v_cndmask_b32_e64 v14, v19, v14, s[42:43]
	v_mul_f32_e32 v19, v15, v18
	v_mul_f32_e32 v15, 0xbfb8aa3b, v55
	v_exp_f32_e32 v15, v15
	s_nop 0
	v_add_f32_e32 v15, 1.0, v15
	v_rcp_f32_e32 v15, v15
	s_nop 0
	v_cndmask_b32_e64 v15, v19, v15, s[42:43]
	v_mul_f32_e32 v19, v8, v18
	v_mul_f32_e32 v8, 0xbfb8aa3b, v44
	v_exp_f32_e32 v8, v8
	s_nop 0
	v_add_f32_e32 v8, 1.0, v8
	v_rcp_f32_e32 v8, v8
	s_nop 0
	v_cndmask_b32_e64 v19, v19, v8, s[42:43]
	v_mul_f32_e32 v8, v9, v18
	v_mul_f32_e32 v9, 0xbfb8aa3b, v45
	v_exp_f32_e32 v9, v9
	s_nop 0
	v_add_f32_e32 v9, 1.0, v9
	v_rcp_f32_e32 v9, v9
	s_nop 0
	v_cndmask_b32_e64 v20, v8, v9, s[42:43]
	v_mul_f32_e32 v9, 0xbfb8aa3b, v46
	v_exp_f32_e32 v9, v9
	v_mul_f32_e32 v8, v10, v18
	v_add_f32_e32 v9, 1.0, v9
	v_rcp_f32_e32 v9, v9
	s_nop 0
	v_cndmask_b32_e64 v21, v8, v9, s[42:43]
	v_mul_f32_e32 v9, 0xbfb8aa3b, v47
	v_exp_f32_e32 v9, v9
	v_mul_f32_e32 v8, v11, v18
	v_add_f32_e32 v9, 1.0, v9
	v_rcp_f32_e32 v9, v9
	s_nop 0
	v_cndmask_b32_e64 v11, v8, v9, s[42:43]
	v_cvt_pk_bf16_f32 v8, v12, v13
	v_cvt_pk_bf16_f32 v9, v14, v15
	v_cvt_pk_bf16_f32 v10, v19, v20
	v_cvt_pk_bf16_f32 v11, v21, v11
	global_store_dwordx4 v[16:17], v[8:11], off
	s_nop 1
	v_mul_f32_e32 v8, v4, v18
	v_mul_f32_e32 v4, 0xbfb8aa3b, v40
	v_exp_f32_e32 v4, v4
	s_nop 0
	v_add_f32_e32 v4, 1.0, v4
	v_rcp_f32_e32 v4, v4
	s_nop 0
	v_cndmask_b32_e64 v4, v8, v4, s[42:43]
	v_mul_f32_e32 v8, v5, v18
	v_mul_f32_e32 v5, 0xbfb8aa3b, v41
	v_exp_f32_e32 v5, v5
	s_nop 0
	v_add_f32_e32 v5, 1.0, v5
	v_rcp_f32_e32 v5, v5
	s_nop 0
	v_cndmask_b32_e64 v5, v8, v5, s[42:43]
	v_mul_f32_e32 v8, v6, v18
	v_mul_f32_e32 v6, 0xbfb8aa3b, v42
	v_exp_f32_e32 v6, v6
	s_nop 0
	v_add_f32_e32 v6, 1.0, v6
	v_rcp_f32_e32 v6, v6
	s_nop 0
	v_cndmask_b32_e64 v6, v8, v6, s[42:43]
	v_mul_f32_e32 v8, v7, v18
	v_mul_f32_e32 v7, 0xbfb8aa3b, v43
	v_exp_f32_e32 v7, v7
	s_nop 0
	v_add_f32_e32 v7, 1.0, v7
	v_rcp_f32_e32 v7, v7
	s_nop 0
	v_cndmask_b32_e64 v7, v8, v7, s[42:43]
	v_mul_f32_e32 v8, v0, v18
	v_mul_f32_e32 v0, 0xbfb8aa3b, v32
	v_exp_f32_e32 v0, v0
	s_nop 0
	v_add_f32_e32 v0, 1.0, v0
	v_rcp_f32_e32 v0, v0
	s_nop 0
	v_cndmask_b32_e64 v8, v8, v0, s[42:43]
	v_mul_f32_e32 v0, v1, v18
	v_mul_f32_e32 v1, 0xbfb8aa3b, v33
	v_exp_f32_e32 v1, v1
	s_nop 0
	v_add_f32_e32 v1, 1.0, v1
	v_rcp_f32_e32 v1, v1
	s_nop 0
	v_cndmask_b32_e64 v9, v0, v1, s[42:43]
	v_mul_f32_e32 v1, 0xbfb8aa3b, v34
	v_exp_f32_e32 v1, v1
	v_mul_f32_e32 v0, v2, v18
	v_add_f32_e32 v1, 1.0, v1
	v_rcp_f32_e32 v1, v1
	s_nop 0
	v_cndmask_b32_e64 v10, v0, v1, s[42:43]
	v_mul_f32_e32 v1, 0xbfb8aa3b, v35
	v_exp_f32_e32 v1, v1
	v_mul_f32_e32 v0, v3, v18
	v_add_f32_e32 v1, 1.0, v1
	v_rcp_f32_e32 v1, v1
	s_nop 0
	v_cndmask_b32_e64 v3, v0, v1, s[42:43]
	v_cvt_pk_bf16_f32 v0, v4, v5
	v_cvt_pk_bf16_f32 v1, v6, v7
	v_cvt_pk_bf16_f32 v2, v8, v9
	v_cvt_pk_bf16_f32 v3, v10, v3
	global_store_dwordx4 v[16:17], v[0:3], off offset:256
	s_cbranch_vccnz .LBB0_170
	s_andn2_b64 vcc, exec, s[8:9]
	s_cbranch_vccnz .LBB0_169
	s_barrier
	s_branch .LBB0_169

; #define LAS __attribute__((address_space(3)))
; __device__ __forceinline__ unsigned cvt_pk_bf16(float lo, float hi) { unsigned r; asm volatile("v_cvt_pk_bf16_f32 %0, %1, %2" : "=v"(r) : "v"(lo), "v"(hi)); return r; }
; __device__ __forceinline__ void transpose_item(const float* W, int N, const float* ks, bf16_t* WT, int ldo, int orow0, int k0, int n0, LAS float* scr, int lane) {
;     ...
;     for (int i = 0; i < 8; ++i) { const int kk = i * 4 + (lane >> 4); const float sc = ks ? ks[k0 + kk] : 1.0f; LAS float* d = scr + kk * 65 + 4 * (lane & 15);
;         d[0] = v[i][0] * sc; d[1] = v[i][1] * sc; d[2] = v[i][2] * sc; d[3] = v[i][3] * sc; }
;     asm volatile("s_waitcnt lgkmcnt(0)" ::: "memory");
;     const int kc = lane & 3;
; #pragma unroll
;     for (int j = 0; j < 4; ++j) { const int n = (lane >> 2) + 16 * j; const LAS float* s = scr + (8 * kc) * 65 + n;
;         u32x4 o; o.x = cvt_pk_bf16(s[0 * 65], s[1 * 65]); o.y = cvt_pk_bf16(s[2 * 65], s[3 * 65]); o.z = cvt_pk_bf16(s[4 * 65], s[5 * 65]); o.w = cvt_pk_bf16(s[6 * 65], s[7 * 65]);
;         *(u32x4*)(WT + (size_t)(orow0 + n) * ldo + k0 + 8 * kc) = o; }
;     asm volatile("s_waitcnt lgkmcnt(0)" ::: "memory");
.LBB0_194:
	v_add_u32_e32 v9, 0x1450, v24
	ds_write2_b32 v9, v4, v5 offset1:1
	v_add_u32_e32 v4, 0x1458, v24
	ds_write2_b32 v4, v6, v7 offset1:1
	v_pk_mul_f32 v[0:1], v[0:1], v[8:9] op_sel_hi:[1,0]
	v_add_u32_e32 v4, 0x1860, v24
	ds_write2_b32 v4, v0, v1 offset1:1
	v_pk_mul_f32 v[0:1], v[2:3], v[8:9] op_sel_hi:[1,0]
	v_add_u32_e32 v2, 0x1868, v24
	ds_write2_b32 v2, v0, v1 offset1:1
	s_waitcnt lgkmcnt(0)
	ds_read2_b32 v[0:1], v43 offset1:65
	s_waitcnt lgkmcnt(0)
	v_cvt_pk_bf16_f32 v0, v0, v1
	ds_read2_b32 v[2:3], v43 offset0:130 offset1:195
	v_add_u32_e32 v8, 0x400, v43
	s_waitcnt lgkmcnt(0)
	v_cvt_pk_bf16_f32 v1, v2, v3
	ds_read2_b32 v[2:3], v8 offset0:4 offset1:69
	s_lshl_b64 s[2:3], s[2:3], 1
	s_waitcnt lgkmcnt(0)
	v_cvt_pk_bf16_f32 v2, v2, v3
	ds_read2_b32 v[6:7], v8 offset0:134 offset1:199
	s_add_u32 s2, s14, s2
	s_waitcnt lgkmcnt(0)
	v_cvt_pk_bf16_f32 v3, v6, v7
	v_or_b32_e32 v6, s0, v39
	s_addc_u32 s3, s15, s3
	v_lshlrev_b32_e32 v96, 1, v36
	v_ashrrev_i32_e32 v7, 31, v6
	v_lshl_add_u64 v[4:5], s[2:3], 0, v[96:97]
	v_lshlrev_b64 v[6:7], 11, v[6:7]
	v_lshl_add_u64 v[6:7], v[4:5], 0, v[6:7]
	global_store_dwordx4 v[6:7], v[0:3], off
	ds_read2_b32 v[0:1], v43 offset0:16 offset1:81
	s_waitcnt lgkmcnt(0)
	v_cvt_pk_bf16_f32 v0, v0, v1
	ds_read2_b32 v[2:3], v43 offset0:146 offset1:211
	s_waitcnt lgkmcnt(0)
	v_cvt_pk_bf16_f32 v1, v2, v3
	ds_read2_b32 v[2:3], v8 offset0:20 offset1:85
	s_waitcnt lgkmcnt(0)
	v_cvt_pk_bf16_f32 v2, v2, v3
	ds_read2_b32 v[6:7], v8 offset0:150 offset1:215
	s_waitcnt lgkmcnt(0)
	v_cvt_pk_bf16_f32 v3, v6, v7
	v_or_b32_e32 v6, s0, v44
	v_ashrrev_i32_e32 v7, 31, v6
	v_lshlrev_b64 v[6:7], 11, v[6:7]
	v_lshl_add_u64 v[6:7], v[4:5], 0, v[6:7]
	global_store_dwordx4 v[6:7], v[0:3], off
	ds_read2_b32 v[0:1], v43 offset0:32 offset1:97
	s_waitcnt lgkmcnt(0)
	v_cvt_pk_bf16_f32 v0, v0, v1
	ds_read2_b32 v[2:3], v43 offset0:162 offset1:227
	s_waitcnt lgkmcnt(0)
	v_cvt_pk_bf16_f32 v1, v2, v3
	ds_read2_b32 v[2:3], v8 offset0:36 offset1:101
	s_waitcnt lgkmcnt(0)
	v_cvt_pk_bf16_f32 v2, v2, v3
	ds_read2_b32 v[6:7], v8 offset0:166 offset1:231
	s_waitcnt lgkmcnt(0)
	v_cvt_pk_bf16_f32 v3, v6, v7
	v_or_b32_e32 v6, s0, v45
	v_ashrrev_i32_e32 v7, 31, v6
	v_lshlrev_b64 v[6:7], 11, v[6:7]
	v_lshl_add_u64 v[6:7], v[4:5], 0, v[6:7]
	global_store_dwordx4 v[6:7], v[0:3], off
	ds_read2_b32 v[0:1], v43 offset0:48 offset1:113
	s_waitcnt lgkmcnt(0)
	v_cvt_pk_bf16_f32 v0, v0, v1
	ds_read2_b32 v[2:3], v43 offset0:178 offset1:243
	s_waitcnt lgkmcnt(0)
	v_cvt_pk_bf16_f32 v1, v2, v3
	ds_read2_b32 v[2:3], v8 offset0:52 offset1:117
	s_waitcnt lgkmcnt(0)
	v_cvt_pk_bf16_f32 v2, v2, v3
	ds_read2_b32 v[6:7], v8 offset0:182 offset1:247
	s_waitcnt lgkmcnt(0)
	v_cvt_pk_bf16_f32 v3, v6, v7
	v_or_b32_e32 v6, s0, v46
	v_ashrrev_i32_e32 v7, 31, v6
	v_lshlrev_b64 v[6:7], 11, v[6:7]
	v_lshl_add_u64 v[4:5], v[4:5], 0, v[6:7]
	global_store_dwordx4 v[4:5], v[0:3], off
	s_waitcnt lgkmcnt(0)

; #define LAS __attribute__((address_space(3)))
; __device__ __forceinline__ void transpose_item(const float* W, int N, const float* ks, bf16_t* WT, int ldo, int orow0, int k0, int n0, LAS float* scr, int lane) {
;     f32x4 v[8];
; #pragma unroll
;     for (int i = 0; i < 8; ++i) v[i] = *(const f32x4*)(W + (size_t)(k0 + i * 4 + (lane >> 4)) * N + n0 + 4 * (lane & 15));
; #pragma unroll
;     for (int i = 0; i < 8; ++i) { const int kk = i * 4 + (lane >> 4); const float sc = ks ? ks[k0 + kk] : 1.0f; LAS float* d = scr + kk * 65 + 4 * (lane & 15);
;         d[0] = v[i][0] * sc; d[1] = v[i][1] * sc; d[2] = v[i][2] * sc; d[3] = v[i][3] * sc; }
;     asm volatile("s_waitcnt lgkmcnt(0)" ::: "memory");
;     const int kc = lane & 3;
; #pragma unroll
;     for (int j = 0; j < 4; ++j) { const int n = (lane >> 2) + 16 * j; const LAS float* s = scr + (8 * kc) * 65 + n;
; __device__ __forceinline__ void convert_weights(const Params& p, LAS unsigned char* lds, int first, int last, int worker, int nworkers) {
;     ...
;     for (int it = first + worker; it < last; it += nworkers) {
;         const int l = it / WI_L; int r = it % WI_L;
;         unsigned char* wb = p.ws + WS_W + (size_t)l * W_LAYER;
;         if (r < WI_IN) { const int kb = r / 52, nb = r % 52; transpose_item(p.w_in + (size_t)l * DM * INW, INW, p.norm_mix + l * DM, (bf16_t*)(wb + WO_IN), DM, nb * 64, kb * 32, nb * 64, scr, lane); continue; } r -= WI_IN;
;         if (r < WI_BA) { const int kb = r / 16, nb = r % 16; transpose_item(p.w_br_attn + (size_t)l * 512 * DM, DM, nullptr, (bf16_t*)(wb + WO_MIX), 512, nb * 64, kb * 32, nb * 64, scr, lane); continue; } r -= WI_BA;
;         if (r < WI_OUT) { const int kb = r / 16, nb = r % 16; transpose_item(p.w_out + (size_t)l * DM * DM, DM, nullptr, (bf16_t*)(wb + WO_OUT), DM, nb * 64, kb * 32, nb * 64, scr, lane); continue; } r -= WI_OUT;
;         if (r < WI_UP) { const int kb = r / 88, nb = r % 88; const int n0 = nb * 64; const int nn = n0 < FF ? n0 : n0 - FF; const int orow = (nn >> 7) * 256 + (n0 < FF ? 0 : 128) + (nn & 127);
;             transpose_item(p.w_up + (size_t)l * DM * FF2, FF2, p.norm_ffn + l * DM, (bf16_t*)(wb + WO_UP), DM, orow, kb * 32, n0, scr, lane); continue; } r -= WI_UP;
;         { const int kb = r / 16, nb = r % 16; transpose_item(p.w_down + (size_t)l * FF * DM, DM, nullptr, (bf16_t*)(wb + WO_DOWN), FF, nb * 64, kb * 32, nb * 64, scr, lane); }
.LBB0_196:
	s_mul_hi_i32 s0, s7, 0x4ec4ec4f
	s_lshr_b32 s1, s0, 31
	s_ashr_i32 s0, s0, 11
	s_add_i32 s2, s0, s1
	s_mul_i32 s0, s2, 0xffffe600
	s_add_i32 s16, s7, s0
	s_ashr_i32 s3, s2, 31
	s_mul_i32 s1, s2, 0x1b00000
	s_mul_hi_i32 s0, s2, 0x1b00000
	s_add_u32 s14, s80, s1
	s_addc_u32 s15, s82, s0
	s_cmpk_gt_i32 s16, 0x67f
	s_mov_b64 s[0:1], -1
	s_cbranch_scc0 .LBB0_218
	s_cmpk_gt_u32 s16, 0x77f
	s_cbranch_scc0 .LBB0_215
	s_cmpk_gt_u32 s16, 0x97f
	s_cbranch_scc0 .LBB0_212
	s_cmpk_gt_u32 s16, 0x147f
	s_cbranch_scc0 .LBB0_201
	v_readlane_b32 s40, v248, 54
	s_mul_i32 s1, s2, 0xb00000
	v_readlane_b32 s50, v247, 0
	s_mul_hi_i32 s0, s2, 0xb00000
	v_readlane_b32 s51, v247, 1
	s_add_u32 s1, s50, s1
	s_mul_i32 s8, s2, 0xffffcc00
	s_addc_u32 s9, s51, s0
	s_add_i32 s8, s10, s8
	s_and_b32 s0, s12, 0x3c0
	s_and_b32 s8, s8, 0x7fffffe0
	s_add_i32 s96, s8, 0xffffd700
	s_lshl_b32 s8, s0, 2
	s_add_u32 s8, s1, s8
	v_or_b32_e32 v28, s96, v32
	s_addc_u32 s9, s9, 0
	v_lshlrev_b32_e32 v96, 2, v34
	v_mov_b32_e32 v29, v97
	v_lshl_add_u64 v[30:31], s[8:9], 0, v[96:97]
	v_lshlrev_b64 v[0:1], 12, v[28:29]
	v_or_b32_e32 v96, 4, v28
	v_lshl_add_u64 v[0:1], v[30:31], 0, v[0:1]
	v_lshlrev_b64 v[4:5], 12, v[96:97]
	global_load_dwordx4 v[0:3], v[0:1], off
	v_lshl_add_u64 v[4:5], v[30:31], 0, v[4:5]
	v_or_b32_e32 v96, 8, v28
	global_load_dwordx4 v[4:7], v[4:5], off
	v_lshlrev_b64 v[8:9], 12, v[96:97]
	v_lshl_add_u64 v[8:9], v[30:31], 0, v[8:9]
	v_or_b32_e32 v96, 12, v28
	global_load_dwordx4 v[8:11], v[8:9], off
	v_lshlrev_b64 v[12:13], 12, v[96:97]
	v_lshl_add_u64 v[12:13], v[30:31], 0, v[12:13]
	v_or_b32_e32 v96, 16, v28
	global_load_dwordx4 v[12:15], v[12:13], off
	v_lshlrev_b64 v[16:17], 12, v[96:97]
	v_lshl_add_u64 v[16:17], v[30:31], 0, v[16:17]
	v_or_b32_e32 v96, 20, v28
	global_load_dwordx4 v[16:19], v[16:17], off
	v_lshlrev_b64 v[20:21], 12, v[96:97]
	v_lshl_add_u64 v[20:21], v[30:31], 0, v[20:21]
	v_or_b32_e32 v96, 24, v28
	global_load_dwordx4 v[20:23], v[20:21], off
	v_lshlrev_b64 v[24:25], 12, v[96:97]
	v_lshl_add_u64 v[24:25], v[30:31], 0, v[24:25]
	v_or_b32_e32 v96, 28, v28
	global_load_dwordx4 v[24:27], v[24:25], off
	v_lshlrev_b64 v[28:29], 12, v[96:97]
	v_lshl_add_u64 v[28:29], v[30:31], 0, v[28:29]
	global_load_dwordx4 v[28:31], v[28:29], off
	v_add_u32_e32 v38, v35, v37
	s_lshl_b64 s[8:9], s[96:97], 1
	s_add_u32 s8, s14, s8
	s_addc_u32 s9, s15, s9
	v_lshlrev_b32_e32 v96, 1, v36
	v_readlane_b32 s41, v248, 55
	v_readlane_b32 s42, v248, 56
	v_readlane_b32 s43, v248, 57
	v_readlane_b32 s44, v248, 58
	v_readlane_b32 s45, v248, 59
	v_readlane_b32 s46, v248, 60
	v_readlane_b32 s47, v248, 61
	v_readlane_b32 s48, v248, 62
	v_readlane_b32 s49, v248, 63
	v_readlane_b32 s52, v247, 2
	v_readlane_b32 s53, v247, 3
	v_readlane_b32 s54, v247, 4
	v_readlane_b32 s55, v247, 5
	s_waitcnt vmcnt(0)
	ds_write2_b32 v38, v0, v1 offset1:1
	ds_write2_b32 v38, v2, v3 offset0:2 offset1:3
	v_add_u32_e32 v0, 0x410, v38
	ds_write2_b32 v0, v4, v5 offset1:1
	v_add_u32_e32 v0, 0x418, v38
	ds_write2_b32 v0, v6, v7 offset1:1
	v_add_u32_e32 v0, 0x820, v38
	ds_write2_b32 v0, v8, v9 offset1:1
	v_add_u32_e32 v0, 0x828, v38
	ds_write2_b32 v0, v10, v11 offset1:1
	v_add_u32_e32 v0, 0xc30, v38
	ds_write2_b32 v0, v12, v13 offset1:1
	v_add_u32_e32 v0, 0xc38, v38
	ds_write2_b32 v0, v14, v15 offset1:1
	v_add_u32_e32 v0, 0x1040, v38
	ds_write2_b32 v0, v16, v17 offset1:1
	v_add_u32_e32 v0, 0x1048, v38
	ds_write2_b32 v0, v18, v19 offset1:1
	v_add_u32_e32 v0, 0x1450, v38
	ds_write2_b32 v0, v20, v21 offset1:1
	v_add_u32_e32 v0, 0x1458, v38
	ds_write2_b32 v0, v22, v23 offset1:1
	v_add_u32_e32 v0, 0x1860, v38
	ds_write2_b32 v0, v24, v25 offset1:1
	v_add_u32_e32 v0, 0x1868, v38
	ds_write2_b32 v0, v26, v27 offset1:1
	v_add_u32_e32 v0, 0x1c70, v38
	ds_write2_b32 v0, v28, v29 offset1:1
	v_add_u32_e32 v0, 0x1c78, v38
	ds_write2_b32 v0, v30, v31 offset1:1
	s_waitcnt lgkmcnt(0)
	v_lshl_add_u64 v[0:1], s[8:9], 0, v[96:97]
	s_mov_b64 s[8:9], 0x1580000
	v_lshl_add_u64 v[4:5], v[0:1], 0, s[8:9]
	ds_read2_b32 v[0:1], v43 offset1:65
	s_waitcnt lgkmcnt(0)
	v_cvt_pk_bf16_f32 v0, v0, v1
	ds_read2_b32 v[2:3], v43 offset0:130 offset1:195
	v_add_u32_e32 v8, 0x400, v43
	s_waitcnt lgkmcnt(0)
	v_cvt_pk_bf16_f32 v1, v2, v3
	ds_read2_b32 v[2:3], v8 offset0:4 offset1:69
	s_waitcnt lgkmcnt(0)
	v_cvt_pk_bf16_f32 v2, v2, v3
	ds_read2_b32 v[6:7], v8 offset0:134 offset1:199
	s_waitcnt lgkmcnt(0)
	v_cvt_pk_bf16_f32 v3, v6, v7
	v_or_b32_e32 v6, s0, v39
	v_mul_u32_u24_e32 v6, 0xb00, v6
	v_lshlrev_b32_e32 v96, 1, v6
	v_lshl_add_u64 v[6:7], v[4:5], 0, v[96:97]
	global_store_dwordx4 v[6:7], v[0:3], off
	ds_read2_b32 v[0:1], v43 offset0:16 offset1:81
	s_waitcnt lgkmcnt(0)
	v_cvt_pk_bf16_f32 v0, v0, v1
	ds_read2_b32 v[2:3], v43 offset0:146 offset1:211
	s_waitcnt lgkmcnt(0)
	v_cvt_pk_bf16_f32 v1, v2, v3
	ds_read2_b32 v[2:3], v8 offset0:20 offset1:85
	s_waitcnt lgkmcnt(0)
	v_cvt_pk_bf16_f32 v2, v2, v3
	ds_read2_b32 v[6:7], v8 offset0:150 offset1:215
	s_waitcnt lgkmcnt(0)
	v_cvt_pk_bf16_f32 v3, v6, v7
	v_or_b32_e32 v6, s0, v44
	v_mul_u32_u24_e32 v6, 0xb00, v6
	v_lshlrev_b32_e32 v96, 1, v6
	v_lshl_add_u64 v[6:7], v[4:5], 0, v[96:97]
	global_store_dwordx4 v[6:7], v[0:3], off
	ds_read2_b32 v[0:1], v43 offset0:32 offset1:97
	s_waitcnt lgkmcnt(0)
	v_cvt_pk_bf16_f32 v0, v0, v1
	ds_read2_b32 v[2:3], v43 offset0:162 offset1:227
	s_waitcnt lgkmcnt(0)
	v_cvt_pk_bf16_f32 v1, v2, v3
	ds_read2_b32 v[2:3], v8 offset0:36 offset1:101
	s_waitcnt lgkmcnt(0)
	v_cvt_pk_bf16_f32 v2, v2, v3
	ds_read2_b32 v[6:7], v8 offset0:166 offset1:231
	s_waitcnt lgkmcnt(0)
	v_cvt_pk_bf16_f32 v3, v6, v7
	v_or_b32_e32 v6, s0, v45
	v_mul_u32_u24_e32 v6, 0xb00, v6
	v_lshlrev_b32_e32 v96, 1, v6
	v_lshl_add_u64 v[6:7], v[4:5], 0, v[96:97]
	global_store_dwordx4 v[6:7], v[0:3], off
	ds_read2_b32 v[0:1], v43 offset0:48 offset1:113
	s_waitcnt lgkmcnt(0)
	v_cvt_pk_bf16_f32 v0, v0, v1
	ds_read2_b32 v[2:3], v43 offset0:178 offset1:243
	s_waitcnt lgkmcnt(0)
	v_cvt_pk_bf16_f32 v1, v2, v3
	ds_read2_b32 v[2:3], v8 offset0:52 offset1:117
	s_waitcnt lgkmcnt(0)
	v_cvt_pk_bf16_f32 v2, v2, v3
	ds_read2_b32 v[6:7], v8 offset0:182 offset1:247
	s_waitcnt lgkmcnt(0)
	v_cvt_pk_bf16_f32 v3, v6, v7
	v_or_b32_e32 v6, s0, v46
	v_mul_u32_u24_e32 v6, 0xb00, v6
	v_lshlrev_b32_e32 v96, 1, v6
	v_lshl_add_u64 v[4:5], v[4:5], 0, v[96:97]
	global_store_dwordx4 v[4:5], v[0:3], off
	s_waitcnt lgkmcnt(0)
	s_mov_b64 s[0:1], 0

; #define LAS __attribute__((address_space(3)))
; __device__ __forceinline__ unsigned cvt_pk_bf16(float lo, float hi) { unsigned r; asm volatile("v_cvt_pk_bf16_f32 %0, %1, %2" : "=v"(r) : "v"(lo), "v"(hi)); return r; }
; __device__ __forceinline__ void transpose_item(const float* W, int N, const float* ks, bf16_t* WT, int ldo, int orow0, int k0, int n0, LAS float* scr, int lane) {
;     ...
;     for (int i = 0; i < 8; ++i) { const int kk = i * 4 + (lane >> 4); const float sc = ks ? ks[k0 + kk] : 1.0f; LAS float* d = scr + kk * 65 + 4 * (lane & 15);
;         d[0] = v[i][0] * sc; d[1] = v[i][1] * sc; d[2] = v[i][2] * sc; d[3] = v[i][3] * sc; }
;     asm volatile("s_waitcnt lgkmcnt(0)" ::: "memory");
;     const int kc = lane & 3;
; #pragma unroll
;     for (int j = 0; j < 4; ++j) { const int n = (lane >> 2) + 16 * j; const LAS float* s = scr + (8 * kc) * 65 + n;
;         u32x4 o; o.x = cvt_pk_bf16(s[0 * 65], s[1 * 65]); o.y = cvt_pk_bf16(s[2 * 65], s[3 * 65]); o.z = cvt_pk_bf16(s[4 * 65], s[5 * 65]); o.w = cvt_pk_bf16(s[6 * 65], s[7 * 65]);
;         *(u32x4*)(WT + (size_t)(orow0 + n) * ldo + k0 + 8 * kc) = o; }
;     asm volatile("s_waitcnt lgkmcnt(0)" ::: "memory");
; __device__ __forceinline__ void convert_weights(const Params& p, LAS unsigned char* lds, int first, int last, int worker, int nworkers) {
;     ...
;         if (r < WI_UP) { const int kb = r / 88, nb = r % 88; const int n0 = nb * 64; const int nn = n0 < FF ? n0 : n0 - FF; const int orow = (nn >> 7) * 256 + (n0 < FF ? 0 : 128) + (nn & 127);
;             transpose_item(p.w_up + (size_t)l * DM * FF2, FF2, p.norm_ffn + l * DM, (bf16_t*)(wb + WO_UP), DM, orow, kb * 32, n0, scr, lane); continue; } r -= WI_UP;
.LBB0_210:
	s_lshl_b32 s0, s18, 6
	s_and_b32 s0, 0xffff, s0
	s_and_b32 s1, 0xffff, s18
	s_add_i32 s8, s0, 0xfffff500
	s_cmp_lt_u32 s1, 44
	s_cselect_b32 s0, s0, s8
	s_cselect_b32 s1, 0, 0x80
	s_lshl_b32 s8, s0, 1
	s_and_b32 s0, s0, 64
	v_add_u32_e32 v8, 0x1450, v24
	s_and_b32 s8, s8, 0xffffff00
	s_or_b32 s0, s0, s1
	ds_write2_b32 v8, v4, v5 offset1:1
	v_add_u32_e32 v4, 0x1458, v24
	s_or_b32 s0, s0, s8
	ds_write2_b32 v4, v6, v7 offset1:1
	v_pk_mul_f32 v[0:1], v[0:1], v[16:17] op_sel_hi:[1,0]
	v_add_u32_e32 v4, 0x1860, v24
	s_lshl_b32 s1, s17, 1
	ds_write2_b32 v4, v0, v1 offset1:1
	v_pk_mul_f32 v[0:1], v[2:3], v[16:17] op_sel_hi:[1,0]
	v_add_u32_e32 v2, 0x1868, v24
	s_add_u32 s8, s14, s1
	ds_write2_b32 v2, v0, v1 offset1:1
	s_addc_u32 s9, s15, 0
	v_lshlrev_b32_e32 v96, 1, v36
	s_waitcnt lgkmcnt(0)
	v_lshl_add_u64 v[0:1], s[8:9], 0, v[96:97]
	s_mov_b64 s[8:9], 0xa80000
	v_lshl_add_u64 v[4:5], v[0:1], 0, s[8:9]
	ds_read2_b32 v[0:1], v43 offset1:65
	s_waitcnt lgkmcnt(0)
	v_cvt_pk_bf16_f32 v0, v0, v1
	ds_read2_b32 v[2:3], v43 offset0:130 offset1:195
	v_add_u32_e32 v8, 0x400, v43
	s_waitcnt lgkmcnt(0)
	v_cvt_pk_bf16_f32 v1, v2, v3
	ds_read2_b32 v[2:3], v8 offset0:4 offset1:69
	s_waitcnt lgkmcnt(0)
	v_cvt_pk_bf16_f32 v2, v2, v3
	ds_read2_b32 v[6:7], v8 offset0:134 offset1:199
	s_waitcnt lgkmcnt(0)
	v_cvt_pk_bf16_f32 v3, v6, v7
	v_or_b32_e32 v6, s0, v39
	v_ashrrev_i32_e32 v7, 31, v6
	v_lshlrev_b64 v[6:7], 11, v[6:7]
	v_lshl_add_u64 v[6:7], v[4:5], 0, v[6:7]
	global_store_dwordx4 v[6:7], v[0:3], off
	ds_read2_b32 v[0:1], v43 offset0:16 offset1:81
	s_waitcnt lgkmcnt(0)
	v_cvt_pk_bf16_f32 v0, v0, v1
	ds_read2_b32 v[2:3], v43 offset0:146 offset1:211
	s_waitcnt lgkmcnt(0)
	v_cvt_pk_bf16_f32 v1, v2, v3
	ds_read2_b32 v[2:3], v8 offset0:20 offset1:85
	s_waitcnt lgkmcnt(0)
	v_cvt_pk_bf16_f32 v2, v2, v3
	ds_read2_b32 v[6:7], v8 offset0:150 offset1:215
	s_waitcnt lgkmcnt(0)
	v_cvt_pk_bf16_f32 v3, v6, v7
	v_or_b32_e32 v6, s0, v44
	v_ashrrev_i32_e32 v7, 31, v6
	v_lshlrev_b64 v[6:7], 11, v[6:7]
	v_lshl_add_u64 v[6:7], v[4:5], 0, v[6:7]
	global_store_dwordx4 v[6:7], v[0:3], off
	ds_read2_b32 v[0:1], v43 offset0:32 offset1:97
	s_waitcnt lgkmcnt(0)
	v_cvt_pk_bf16_f32 v0, v0, v1
	ds_read2_b32 v[2:3], v43 offset0:162 offset1:227
	s_waitcnt lgkmcnt(0)
	v_cvt_pk_bf16_f32 v1, v2, v3
	ds_read2_b32 v[2:3], v8 offset0:36 offset1:101
	s_waitcnt lgkmcnt(0)
	v_cvt_pk_bf16_f32 v2, v2, v3
	ds_read2_b32 v[6:7], v8 offset0:166 offset1:231
	s_waitcnt lgkmcnt(0)
	v_cvt_pk_bf16_f32 v3, v6, v7
	v_or_b32_e32 v6, s0, v45
	v_ashrrev_i32_e32 v7, 31, v6
	v_lshlrev_b64 v[6:7], 11, v[6:7]
	v_lshl_add_u64 v[6:7], v[4:5], 0, v[6:7]
	global_store_dwordx4 v[6:7], v[0:3], off
	ds_read2_b32 v[0:1], v43 offset0:48 offset1:113
	s_waitcnt lgkmcnt(0)
	v_cvt_pk_bf16_f32 v0, v0, v1
	ds_read2_b32 v[2:3], v43 offset0:178 offset1:243
	s_waitcnt lgkmcnt(0)
	v_cvt_pk_bf16_f32 v1, v2, v3
	ds_read2_b32 v[2:3], v8 offset0:52 offset1:117
	s_waitcnt lgkmcnt(0)
	v_cvt_pk_bf16_f32 v2, v2, v3
	ds_read2_b32 v[6:7], v8 offset0:182 offset1:247
	s_waitcnt lgkmcnt(0)
	v_cvt_pk_bf16_f32 v3, v6, v7
	v_or_b32_e32 v6, s0, v46
	v_ashrrev_i32_e32 v7, 31, v6
	v_lshlrev_b64 v[6:7], 11, v[6:7]
	v_lshl_add_u64 v[4:5], v[4:5], 0, v[6:7]
	global_store_dwordx4 v[4:5], v[0:3], off
	s_waitcnt lgkmcnt(0)

; #define LAS __attribute__((address_space(3)))
; __device__ __forceinline__ unsigned cvt_pk_bf16(float lo, float hi) { unsigned r; asm volatile("v_cvt_pk_bf16_f32 %0, %1, %2" : "=v"(r) : "v"(lo), "v"(hi)); return r; }
; __device__ __forceinline__ void transpose_item(const float* W, int N, const float* ks, bf16_t* WT, int ldo, int orow0, int k0, int n0, LAS float* scr, int lane) {
;     f32x4 v[8];
; #pragma unroll
;     for (int i = 0; i < 8; ++i) v[i] = *(const f32x4*)(W + (size_t)(k0 + i * 4 + (lane >> 4)) * N + n0 + 4 * (lane & 15));
; #pragma unroll
;     for (int i = 0; i < 8; ++i) { const int kk = i * 4 + (lane >> 4); const float sc = ks ? ks[k0 + kk] : 1.0f; LAS float* d = scr + kk * 65 + 4 * (lane & 15);
;         d[0] = v[i][0] * sc; d[1] = v[i][1] * sc; d[2] = v[i][2] * sc; d[3] = v[i][3] * sc; }
;     asm volatile("s_waitcnt lgkmcnt(0)" ::: "memory");
;     const int kc = lane & 3;
; #pragma unroll
;     for (int j = 0; j < 4; ++j) { const int n = (lane >> 2) + 16 * j; const LAS float* s = scr + (8 * kc) * 65 + n;
;         u32x4 o; o.x = cvt_pk_bf16(s[0 * 65], s[1 * 65]); o.y = cvt_pk_bf16(s[2 * 65], s[3 * 65]); o.z = cvt_pk_bf16(s[4 * 65], s[5 * 65]); o.w = cvt_pk_bf16(s[6 * 65], s[7 * 65]);
;         *(u32x4*)(WT + (size_t)(orow0 + n) * ldo + k0 + 8 * kc) = o; }
;     asm volatile("s_waitcnt lgkmcnt(0)" ::: "memory");
; }
; __device__ __forceinline__ void convert_weights(const Params& p, LAS unsigned char* lds, int first, int last, int worker, int nworkers) {
;     ...
;         if (r < WI_OUT) { const int kb = r / 16, nb = r % 16; transpose_item(p.w_out + (size_t)l * DM * DM, DM, nullptr, (bf16_t*)(wb + WO_OUT), DM, nb * 64, kb * 32, nb * 64, scr, lane); continue; } r -= WI_OUT;
.LBB0_212:
	s_andn2_b64 vcc, exec, s[0:1]
	s_cbranch_vccnz .LBB0_214
	s_lshl_b64 s[0:1], s[2:3], 22
	v_readlane_b32 s40, v248, 54
	v_readlane_b32 s41, v248, 55
	s_add_u32 s8, s40, s0
	s_mul_i32 s9, s2, 0xffffcc00
	s_addc_u32 s1, s41, s1
	s_add_i32 s9, s10, s9
	s_and_b32 s0, s12, 0x3c0
	s_and_b32 s9, s9, 0x1fe0
	s_add_i32 s96, s9, 0xfffff100
	s_lshl_b32 s9, s0, 2
	s_add_u32 s8, s8, s9
	v_or_b32_e32 v28, s96, v32
	s_addc_u32 s9, s1, 0
	v_lshlrev_b32_e32 v96, 2, v34
	v_mov_b32_e32 v29, v97
	v_lshl_add_u64 v[30:31], s[8:9], 0, v[96:97]
	v_lshlrev_b64 v[0:1], 12, v[28:29]
	v_or_b32_e32 v96, 4, v28
	v_lshl_add_u64 v[0:1], v[30:31], 0, v[0:1]
	v_lshlrev_b64 v[4:5], 12, v[96:97]
	global_load_dwordx4 v[0:3], v[0:1], off
	v_lshl_add_u64 v[4:5], v[30:31], 0, v[4:5]
	v_or_b32_e32 v96, 8, v28
	global_load_dwordx4 v[4:7], v[4:5], off
	v_lshlrev_b64 v[8:9], 12, v[96:97]
	v_lshl_add_u64 v[8:9], v[30:31], 0, v[8:9]
	v_or_b32_e32 v96, 12, v28
	global_load_dwordx4 v[8:11], v[8:9], off
	v_lshlrev_b64 v[12:13], 12, v[96:97]
	v_lshl_add_u64 v[12:13], v[30:31], 0, v[12:13]
	v_or_b32_e32 v96, 16, v28
	global_load_dwordx4 v[12:15], v[12:13], off
	v_lshlrev_b64 v[16:17], 12, v[96:97]
	v_lshl_add_u64 v[16:17], v[30:31], 0, v[16:17]
	v_or_b32_e32 v96, 20, v28
	global_load_dwordx4 v[16:19], v[16:17], off
	v_lshlrev_b64 v[20:21], 12, v[96:97]
	v_lshl_add_u64 v[20:21], v[30:31], 0, v[20:21]
	v_or_b32_e32 v96, 24, v28
	global_load_dwordx4 v[20:23], v[20:21], off
	v_lshlrev_b64 v[24:25], 12, v[96:97]
	v_lshl_add_u64 v[24:25], v[30:31], 0, v[24:25]
	v_or_b32_e32 v96, 28, v28
	global_load_dwordx4 v[24:27], v[24:25], off
	v_lshlrev_b64 v[28:29], 12, v[96:97]
	v_lshl_add_u64 v[28:29], v[30:31], 0, v[28:29]
	global_load_dwordx4 v[28:31], v[28:29], off
	v_add_u32_e32 v38, v35, v37
	s_lshl_b64 s[8:9], s[96:97], 1
	s_add_u32 s8, s14, s8
	s_addc_u32 s9, s15, s9
	v_lshlrev_b32_e32 v96, 1, v36
	v_readlane_b32 s42, v248, 56
	v_readlane_b32 s43, v248, 57
	v_readlane_b32 s44, v248, 58
	v_readlane_b32 s45, v248, 59
	v_readlane_b32 s46, v248, 60
	v_readlane_b32 s47, v248, 61
	v_readlane_b32 s48, v248, 62
	v_readlane_b32 s49, v248, 63
	v_readlane_b32 s50, v247, 0
	v_readlane_b32 s51, v247, 1
	v_readlane_b32 s52, v247, 2
	v_readlane_b32 s53, v247, 3
	v_readlane_b32 s54, v247, 4
	v_readlane_b32 s55, v247, 5
	s_waitcnt vmcnt(0)
	ds_write2_b32 v38, v0, v1 offset1:1
	ds_write2_b32 v38, v2, v3 offset0:2 offset1:3
	v_add_u32_e32 v0, 0x410, v38
	ds_write2_b32 v0, v4, v5 offset1:1
	v_add_u32_e32 v0, 0x418, v38
	ds_write2_b32 v0, v6, v7 offset1:1
	v_add_u32_e32 v0, 0x820, v38
	ds_write2_b32 v0, v8, v9 offset1:1
	v_add_u32_e32 v0, 0x828, v38
	ds_write2_b32 v0, v10, v11 offset1:1
	v_add_u32_e32 v0, 0xc30, v38
	ds_write2_b32 v0, v12, v13 offset1:1
	v_add_u32_e32 v0, 0xc38, v38
	ds_write2_b32 v0, v14, v15 offset1:1
	v_add_u32_e32 v0, 0x1040, v38
	ds_write2_b32 v0, v16, v17 offset1:1
	v_add_u32_e32 v0, 0x1048, v38
	ds_write2_b32 v0, v18, v19 offset1:1
	v_add_u32_e32 v0, 0x1450, v38
	ds_write2_b32 v0, v20, v21 offset1:1
	v_add_u32_e32 v0, 0x1458, v38
	ds_write2_b32 v0, v22, v23 offset1:1
	v_add_u32_e32 v0, 0x1860, v38
	ds_write2_b32 v0, v24, v25 offset1:1
	v_add_u32_e32 v0, 0x1868, v38
	ds_write2_b32 v0, v26, v27 offset1:1
	v_add_u32_e32 v0, 0x1c70, v38
	ds_write2_b32 v0, v28, v29 offset1:1
	v_add_u32_e32 v0, 0x1c78, v38
	ds_write2_b32 v0, v30, v31 offset1:1
	s_waitcnt lgkmcnt(0)
	v_lshl_add_u64 v[0:1], s[8:9], 0, v[96:97]
	s_mov_b64 s[8:9], 0x880000
	v_lshl_add_u64 v[4:5], v[0:1], 0, s[8:9]
	ds_read2_b32 v[0:1], v43 offset1:65
	s_waitcnt lgkmcnt(0)
	v_cvt_pk_bf16_f32 v0, v0, v1
	ds_read2_b32 v[2:3], v43 offset0:130 offset1:195
	v_add_u32_e32 v8, 0x400, v43
	s_waitcnt lgkmcnt(0)
	v_cvt_pk_bf16_f32 v1, v2, v3
	ds_read2_b32 v[2:3], v8 offset0:4 offset1:69
	s_waitcnt lgkmcnt(0)
	v_cvt_pk_bf16_f32 v2, v2, v3
	ds_read2_b32 v[6:7], v8 offset0:134 offset1:199
	s_waitcnt lgkmcnt(0)
	v_cvt_pk_bf16_f32 v3, v6, v7
	v_or_b32_e32 v6, s0, v39
	v_lshlrev_b32_e32 v96, 11, v6
	v_lshl_add_u64 v[6:7], v[4:5], 0, v[96:97]
	global_store_dwordx4 v[6:7], v[0:3], off
	ds_read2_b32 v[0:1], v43 offset0:16 offset1:81
	s_waitcnt lgkmcnt(0)
	v_cvt_pk_bf16_f32 v0, v0, v1
	ds_read2_b32 v[2:3], v43 offset0:146 offset1:211
	s_waitcnt lgkmcnt(0)
	v_cvt_pk_bf16_f32 v1, v2, v3
	ds_read2_b32 v[2:3], v8 offset0:20 offset1:85
	s_waitcnt lgkmcnt(0)
	v_cvt_pk_bf16_f32 v2, v2, v3
	ds_read2_b32 v[6:7], v8 offset0:150 offset1:215
	s_waitcnt lgkmcnt(0)
	v_cvt_pk_bf16_f32 v3, v6, v7
	v_or_b32_e32 v6, s0, v44
	v_lshlrev_b32_e32 v96, 11, v6
	v_lshl_add_u64 v[6:7], v[4:5], 0, v[96:97]
	global_store_dwordx4 v[6:7], v[0:3], off
	ds_read2_b32 v[0:1], v43 offset0:32 offset1:97
	s_waitcnt lgkmcnt(0)
	v_cvt_pk_bf16_f32 v0, v0, v1
	ds_read2_b32 v[2:3], v43 offset0:162 offset1:227
	s_waitcnt lgkmcnt(0)
	v_cvt_pk_bf16_f32 v1, v2, v3
	ds_read2_b32 v[2:3], v8 offset0:36 offset1:101
	s_waitcnt lgkmcnt(0)
	v_cvt_pk_bf16_f32 v2, v2, v3
	ds_read2_b32 v[6:7], v8 offset0:166 offset1:231
	s_waitcnt lgkmcnt(0)
	v_cvt_pk_bf16_f32 v3, v6, v7
	v_or_b32_e32 v6, s0, v45
	v_lshlrev_b32_e32 v96, 11, v6
	v_lshl_add_u64 v[6:7], v[4:5], 0, v[96:97]
	global_store_dwordx4 v[6:7], v[0:3], off
	ds_read2_b32 v[0:1], v43 offset0:48 offset1:113
	s_waitcnt lgkmcnt(0)
	v_cvt_pk_bf16_f32 v0, v0, v1
	ds_read2_b32 v[2:3], v43 offset0:178 offset1:243
	s_waitcnt lgkmcnt(0)
	v_cvt_pk_bf16_f32 v1, v2, v3
	ds_read2_b32 v[2:3], v8 offset0:52 offset1:117
	s_waitcnt lgkmcnt(0)
	v_cvt_pk_bf16_f32 v2, v2, v3
	ds_read2_b32 v[6:7], v8 offset0:182 offset1:247
	s_waitcnt lgkmcnt(0)
	v_cvt_pk_bf16_f32 v3, v6, v7
	v_or_b32_e32 v6, s0, v46
	v_lshlrev_b32_e32 v96, 11, v6
	v_lshl_add_u64 v[4:5], v[4:5], 0, v[96:97]
	global_store_dwordx4 v[4:5], v[0:3], off
	s_waitcnt lgkmcnt(0)

; #define LAS __attribute__((address_space(3)))
; __device__ __forceinline__ unsigned cvt_pk_bf16(float lo, float hi) { unsigned r; asm volatile("v_cvt_pk_bf16_f32 %0, %1, %2" : "=v"(r) : "v"(lo), "v"(hi)); return r; }
; __device__ __forceinline__ void transpose_item(const float* W, int N, const float* ks, bf16_t* WT, int ldo, int orow0, int k0, int n0, LAS float* scr, int lane) {
;     f32x4 v[8];
; #pragma unroll
;     for (int i = 0; i < 8; ++i) v[i] = *(const f32x4*)(W + (size_t)(k0 + i * 4 + (lane >> 4)) * N + n0 + 4 * (lane & 15));
; #pragma unroll
;     for (int i = 0; i < 8; ++i) { const int kk = i * 4 + (lane >> 4); const float sc = ks ? ks[k0 + kk] : 1.0f; LAS float* d = scr + kk * 65 + 4 * (lane & 15);
;         d[0] = v[i][0] * sc; d[1] = v[i][1] * sc; d[2] = v[i][2] * sc; d[3] = v[i][3] * sc; }
;     asm volatile("s_waitcnt lgkmcnt(0)" ::: "memory");
;     const int kc = lane & 3;
; #pragma unroll
;     for (int j = 0; j < 4; ++j) { const int n = (lane >> 2) + 16 * j; const LAS float* s = scr + (8 * kc) * 65 + n;
;         u32x4 o; o.x = cvt_pk_bf16(s[0 * 65], s[1 * 65]); o.y = cvt_pk_bf16(s[2 * 65], s[3 * 65]); o.z = cvt_pk_bf16(s[4 * 65], s[5 * 65]); o.w = cvt_pk_bf16(s[6 * 65], s[7 * 65]);
;         *(u32x4*)(WT + (size_t)(orow0 + n) * ldo + k0 + 8 * kc) = o; }
;     asm volatile("s_waitcnt lgkmcnt(0)" ::: "memory");
; }
; __device__ __forceinline__ void convert_weights(const Params& p, LAS unsigned char* lds, int first, int last, int worker, int nworkers) {
;     ...
;         if (r < WI_BA) { const int kb = r / 16, nb = r % 16; transpose_item(p.w_br_attn + (size_t)l * 512 * DM, DM, nullptr, (bf16_t*)(wb + WO_MIX), 512, nb * 64, kb * 32, nb * 64, scr, lane); continue; } r -= WI_BA;
.LBB0_215:
	s_andn2_b64 vcc, exec, s[0:1]
	s_cbranch_vccnz .LBB0_217
	v_readlane_b32 s40, v249, 20
	s_lshl_b64 s[0:1], s[2:3], 21
	v_readlane_b32 s50, v249, 30
	v_readlane_b32 s51, v249, 31
	s_add_u32 s3, s50, s0
	s_addc_u32 s1, s51, s1
	s_lshl_b32 s8, s2, 10
	s_sub_i32 s8, s10, s8
	s_and_b32 s0, s12, 0x3c0
	s_and_b32 s8, s8, 0xfe0
	s_add_i32 s96, s8, 0xfffff300
	s_lshl_b32 s8, s0, 2
	s_add_u32 s8, s3, s8
	v_or_b32_e32 v28, s96, v32
	s_addc_u32 s9, s1, 0
	v_lshlrev_b32_e32 v96, 2, v34
	v_mov_b32_e32 v29, v97
	v_lshl_add_u64 v[30:31], s[8:9], 0, v[96:97]
	v_lshlrev_b64 v[0:1], 12, v[28:29]
	v_or_b32_e32 v96, 4, v28
	v_lshl_add_u64 v[0:1], v[30:31], 0, v[0:1]
	v_lshlrev_b64 v[4:5], 12, v[96:97]
	global_load_dwordx4 v[0:3], v[0:1], off
	v_lshl_add_u64 v[4:5], v[30:31], 0, v[4:5]
	v_or_b32_e32 v96, 8, v28
	global_load_dwordx4 v[4:7], v[4:5], off
	v_lshlrev_b64 v[8:9], 12, v[96:97]
	v_lshl_add_u64 v[8:9], v[30:31], 0, v[8:9]
	v_or_b32_e32 v96, 12, v28
	global_load_dwordx4 v[8:11], v[8:9], off
	v_lshlrev_b64 v[12:13], 12, v[96:97]
	v_lshl_add_u64 v[12:13], v[30:31], 0, v[12:13]
	v_or_b32_e32 v96, 16, v28
	global_load_dwordx4 v[12:15], v[12:13], off
	v_lshlrev_b64 v[16:17], 12, v[96:97]
	v_lshl_add_u64 v[16:17], v[30:31], 0, v[16:17]
	v_or_b32_e32 v96, 20, v28
	global_load_dwordx4 v[16:19], v[16:17], off
	v_lshlrev_b64 v[20:21], 12, v[96:97]
	v_lshl_add_u64 v[20:21], v[30:31], 0, v[20:21]
	v_or_b32_e32 v96, 24, v28
	global_load_dwordx4 v[20:23], v[20:21], off
	v_lshlrev_b64 v[24:25], 12, v[96:97]
	v_lshl_add_u64 v[24:25], v[30:31], 0, v[24:25]
	v_or_b32_e32 v96, 28, v28
	global_load_dwordx4 v[24:27], v[24:25], off
	v_lshlrev_b64 v[28:29], 12, v[96:97]
	v_lshl_add_u64 v[28:29], v[30:31], 0, v[28:29]
	global_load_dwordx4 v[28:31], v[28:29], off
	v_add_u32_e32 v38, v35, v37
	s_lshl_b64 s[8:9], s[96:97], 1
	s_add_u32 s8, s14, s8
	s_addc_u32 s9, s15, s9
	v_lshlrev_b32_e32 v96, 1, v36
	v_readlane_b32 s41, v249, 21
	v_readlane_b32 s42, v249, 22
	v_readlane_b32 s43, v249, 23
	v_readlane_b32 s44, v249, 24
	v_readlane_b32 s45, v249, 25
	v_readlane_b32 s46, v249, 26
	v_readlane_b32 s47, v249, 27
	v_readlane_b32 s48, v249, 28
	v_readlane_b32 s49, v249, 29
	v_readlane_b32 s52, v249, 32
	v_readlane_b32 s53, v249, 33
	v_readlane_b32 s54, v249, 34
	v_readlane_b32 s55, v249, 35
	s_waitcnt vmcnt(0)
	ds_write2_b32 v38, v0, v1 offset1:1
	ds_write2_b32 v38, v2, v3 offset0:2 offset1:3
	v_add_u32_e32 v0, 0x410, v38
	ds_write2_b32 v0, v4, v5 offset1:1
	v_add_u32_e32 v0, 0x418, v38
	ds_write2_b32 v0, v6, v7 offset1:1
	v_add_u32_e32 v0, 0x820, v38
	ds_write2_b32 v0, v8, v9 offset1:1
	v_add_u32_e32 v0, 0x828, v38
	ds_write2_b32 v0, v10, v11 offset1:1
	v_add_u32_e32 v0, 0xc30, v38
	ds_write2_b32 v0, v12, v13 offset1:1
	v_add_u32_e32 v0, 0xc38, v38
	ds_write2_b32 v0, v14, v15 offset1:1
	v_add_u32_e32 v0, 0x1040, v38
	ds_write2_b32 v0, v16, v17 offset1:1
	v_add_u32_e32 v0, 0x1048, v38
	ds_write2_b32 v0, v18, v19 offset1:1
	v_add_u32_e32 v0, 0x1450, v38
	ds_write2_b32 v0, v20, v21 offset1:1
	v_add_u32_e32 v0, 0x1458, v38
	ds_write2_b32 v0, v22, v23 offset1:1
	v_add_u32_e32 v0, 0x1860, v38
	ds_write2_b32 v0, v24, v25 offset1:1
	v_add_u32_e32 v0, 0x1868, v38
	ds_write2_b32 v0, v26, v27 offset1:1
	v_add_u32_e32 v0, 0x1c70, v38
	ds_write2_b32 v0, v28, v29 offset1:1
	v_add_u32_e32 v0, 0x1c78, v38
	ds_write2_b32 v0, v30, v31 offset1:1
	s_waitcnt lgkmcnt(0)
	v_lshl_add_u64 v[0:1], s[8:9], 0, v[96:97]
	s_mov_b64 s[8:9], 0x680000
	v_lshl_add_u64 v[4:5], v[0:1], 0, s[8:9]
	ds_read2_b32 v[0:1], v43 offset1:65
	s_waitcnt lgkmcnt(0)
	v_cvt_pk_bf16_f32 v0, v0, v1
	ds_read2_b32 v[2:3], v43 offset0:130 offset1:195
	v_add_u32_e32 v8, 0x400, v43
	s_waitcnt lgkmcnt(0)
	v_cvt_pk_bf16_f32 v1, v2, v3
	ds_read2_b32 v[2:3], v8 offset0:4 offset1:69
	s_waitcnt lgkmcnt(0)
	v_cvt_pk_bf16_f32 v2, v2, v3
	ds_read2_b32 v[6:7], v8 offset0:134 offset1:199
	s_waitcnt lgkmcnt(0)
	v_cvt_pk_bf16_f32 v3, v6, v7
	v_or_b32_e32 v6, s0, v39
	v_lshlrev_b32_e32 v96, 10, v6
	v_lshl_add_u64 v[6:7], v[4:5], 0, v[96:97]
	global_store_dwordx4 v[6:7], v[0:3], off
	ds_read2_b32 v[0:1], v43 offset0:16 offset1:81
	s_waitcnt lgkmcnt(0)
	v_cvt_pk_bf16_f32 v0, v0, v1
	ds_read2_b32 v[2:3], v43 offset0:146 offset1:211
	s_waitcnt lgkmcnt(0)
	v_cvt_pk_bf16_f32 v1, v2, v3
	ds_read2_b32 v[2:3], v8 offset0:20 offset1:85
	s_waitcnt lgkmcnt(0)
	v_cvt_pk_bf16_f32 v2, v2, v3
	ds_read2_b32 v[6:7], v8 offset0:150 offset1:215
	s_waitcnt lgkmcnt(0)
	v_cvt_pk_bf16_f32 v3, v6, v7
	v_or_b32_e32 v6, s0, v44
	v_lshlrev_b32_e32 v96, 10, v6
	v_lshl_add_u64 v[6:7], v[4:5], 0, v[96:97]
	global_store_dwordx4 v[6:7], v[0:3], off
	ds_read2_b32 v[0:1], v43 offset0:32 offset1:97
	s_waitcnt lgkmcnt(0)
	v_cvt_pk_bf16_f32 v0, v0, v1
	ds_read2_b32 v[2:3], v43 offset0:162 offset1:227
	s_waitcnt lgkmcnt(0)
	v_cvt_pk_bf16_f32 v1, v2, v3
	ds_read2_b32 v[2:3], v8 offset0:36 offset1:101
	s_waitcnt lgkmcnt(0)
	v_cvt_pk_bf16_f32 v2, v2, v3
	ds_read2_b32 v[6:7], v8 offset0:166 offset1:231
	s_waitcnt lgkmcnt(0)
	v_cvt_pk_bf16_f32 v3, v6, v7
	v_or_b32_e32 v6, s0, v45
	v_lshlrev_b32_e32 v96, 10, v6
	v_lshl_add_u64 v[6:7], v[4:5], 0, v[96:97]
	global_store_dwordx4 v[6:7], v[0:3], off
	ds_read2_b32 v[0:1], v43 offset0:48 offset1:113
	s_waitcnt lgkmcnt(0)
	v_cvt_pk_bf16_f32 v0, v0, v1
	ds_read2_b32 v[2:3], v43 offset0:178 offset1:243
	s_waitcnt lgkmcnt(0)
	v_cvt_pk_bf16_f32 v1, v2, v3
	ds_read2_b32 v[2:3], v8 offset0:52 offset1:117
	s_waitcnt lgkmcnt(0)
	v_cvt_pk_bf16_f32 v2, v2, v3
	ds_read2_b32 v[6:7], v8 offset0:182 offset1:247
	s_waitcnt lgkmcnt(0)
	v_cvt_pk_bf16_f32 v3, v6, v7
	v_or_b32_e32 v6, s0, v46
	v_lshlrev_b32_e32 v96, 10, v6
	v_lshl_add_u64 v[4:5], v[4:5], 0, v[96:97]
	global_store_dwordx4 v[4:5], v[0:3], off
	s_waitcnt lgkmcnt(0)

; __device__ __forceinline__ void attn_macro(const Params& p, int l, LAS unsigned char* lds, int b, int cg, int kvh) {
;     ...
;     const int gq = wid >> 1, half = wid & 1, h = kvh * 4 + gq, tq = half * 32 + q32;
;     u32x4 qraw[4];
; #pragma unroll
;     for (int i = 0; i < 4; ++i) qraw[i] = *(const u32x4*)(P + (size_t)(rowb + c0 * 64 + half * 32 + i * 8 + (lane >> 3)) * INW + h * 64 + (lane & 7) * 8);
;     u32x4 kraw[6], vraw[6];
; #pragma unroll
;     for (int it = 0; it < 6; ++it) {
;         const int idx = it * 512 + tid, j = idx >> 3, ch = idx & 7, tk = c0 * 64 - 128 + j;
;         kraw[it] = (u32x4){0u, 0u, 0u, 0u}; vraw[it] = kraw[it];
;         if (tk >= 0) { const size_t o = (size_t)(rowb + tk) * INW + kvh * 64 + ch * 8; kraw[it] = *(const u32x4*)(P + o + 512); vraw[it] = *(const u32x4*)(P + o + 640); }
;     }
; __global__ void __launch_bounds__(512) mk_fwd(Params p0) {
;     ...
;             for (int idx = vcu; idx < 16 + 256; idx += G) {
;                 if (idx < 16) attn_unit(p, l, lds, true, idx >> 1, 0, idx & 1);
;                 else { const int q = idx - 16; attn_macro(p, l, lds, q >> 7, q & 63, (q >> 6) & 1); }
.LBB0_287:
	s_cmp_gt_i32 s23, 15
	s_mov_b64 s[0:1], -1
	s_cbranch_scc0 .LBB0_413
	s_add_i32 s10, s23, -16
	v_mov_b32_e32 v136, v222
	s_bfe_u32 s12, s10, 0x10006
	s_lshr_b32 s7, s10, 7
	v_readfirstlane_b32 s0, v136
	s_and_b32 s11, s10, 63
	s_ashr_i32 s13, s0, 6
	s_ashr_i32 s14, s0, 7
	s_lshl_b32 s0, s12, 2
	s_lshl_b32 s15, s7, 14
	s_add_i32 s14, s14, s0
	s_lshl_b32 s0, s13, 5
	s_lshl_b32 s17, s11, 8
	s_and_b32 s16, s0, 32
	s_or_b32 s0, s17, s15
	s_or_b32 s96, s0, s16
	s_lshl_b32 s0, s14, 6
	v_and_b32_e32 v137, 63, v136
	s_ashr_i32 s1, s0, 31
	s_lshl_b64 s[2:3], s[0:1], 1
	v_lshlrev_b32_e32 v0, 3, v137
	v_ashrrev_i32_e32 v126, 3, v137
	s_add_u32 s0, s84, s2
	v_and_b32_e32 v0, 56, v0
	v_ashrrev_i32_e32 v127, 31, v126
	s_addc_u32 s1, s85, s3
	v_lshlrev_b32_e32 v56, 1, v0
	v_mov_b32_e32 v57, v97
	v_lshl_add_u64 v[0:1], s[0:1], 0, v[56:57]
	v_lshl_add_u64 v[2:3], s[96:97], 0, v[126:127]
	v_mad_u64_u32 v[4:5], s[8:9], v2, s89, v[0:1]
	s_or_b32 s8, s96, 8
	s_mov_b32 s9, s97
	v_mad_i32_i24 v5, v3, s89, v5
	v_lshl_add_u64 v[2:3], s[8:9], 0, v[126:127]
	v_mad_u64_u32 v[6:7], s[8:9], v2, s89, v[0:1]
	s_or_b32 s8, s96, 16
	s_mov_b32 s9, s97
	v_mad_i32_i24 v7, v3, s89, v7
	v_lshl_add_u64 v[2:3], s[8:9], 0, v[126:127]
	global_load_dwordx4 v[98:101], v[4:5], off
	global_load_dwordx4 v[102:105], v[6:7], off
	v_mad_u64_u32 v[4:5], s[8:9], v2, s89, v[0:1]
	s_or_b32 s96, s96, 24
	v_mad_i32_i24 v5, v3, s89, v5
	v_lshl_add_u64 v[2:3], s[96:97], 0, v[126:127]
	v_mad_u64_u32 v[0:1], s[8:9], v2, s89, v[0:1]
	v_mad_i32_i24 v1, v3, s89, v1
	global_load_dwordx4 v[106:109], v[4:5], off
	global_load_dwordx4 v[110:113], v[0:1], off
	s_addk_i32 s17, 0xff80
	v_lshlrev_b32_e32 v138, 3, v136
	s_lshl_b32 s8, s12, 7
	v_and_b32_e32 v57, 56, v138
	s_add_u32 s8, s84, s8
	v_ashrrev_i32_e32 v73, 3, v136
	s_addc_u32 s9, s85, 0
	v_lshlrev_b32_e32 v96, 1, v57
	v_add_u32_e32 v0, s17, v73
	v_lshl_add_u64 v[48:49], s[8:9], 0, v[96:97]
	v_cmp_lt_i32_e32 vcc, -1, v0
	v_mov_b32_e32 v32, 0
	v_mov_b32_e32 v44, 0
	v_mov_b32_e32 v45, 0
	v_mov_b32_e32 v46, 0
	v_mov_b32_e32 v47, 0
	v_mov_b32_e32 v40, 0
	v_mov_b32_e32 v41, 0
	v_mov_b32_e32 v42, 0
	v_mov_b32_e32 v43, 0
	s_and_saveexec_b64 s[8:9], vcc
	s_cbranch_execz .LBB0_290
	v_add_u32_e32 v0, s15, v0
	v_mad_u64_u32 v[0:1], s[40:41], v0, s89, v[48:49]
	global_load_dwordx4 v[40:43], v[0:1], off offset:1024
	global_load_dwordx4 v[44:47], v[0:1], off offset:1280
.LBB0_290:
	s_or_b64 exec, exec, s[8:9]
	v_add_u32_e32 v0, 0x200, v136
	v_ashrrev_i32_e32 v72, 3, v0
	v_add_u32_e32 v0, s17, v72
	v_cmp_lt_i32_e32 vcc, -1, v0
	v_mov_b32_e32 v33, 0
	v_mov_b32_e32 v34, 0
	v_mov_b32_e32 v35, 0
	v_mov_b32_e32 v36, 0
	v_mov_b32_e32 v37, 0
	v_mov_b32_e32 v38, 0
	v_mov_b32_e32 v39, 0
	s_and_saveexec_b64 s[8:9], vcc
	s_cbranch_execz .LBB0_292
	v_add_u32_e32 v0, s15, v0
	v_mad_u64_u32 v[0:1], s[40:41], v0, s89, v[48:49]
	global_load_dwordx4 v[36:39], v[0:1], off offset:1024
	global_load_dwordx4 v[32:35], v[0:1], off offset:1280
.LBB0_292:
	s_or_b64 exec, exec, s[8:9]
	v_add_u32_e32 v0, 0x400, v136
	v_ashrrev_i32_e32 v71, 3, v0
	v_add_u32_e32 v0, s17, v71
	v_cmp_lt_i32_e32 vcc, -1, v0
	v_mov_b32_e32 v16, 0
	v_mov_b32_e32 v24, 0
	v_mov_b32_e32 v25, 0
	v_mov_b32_e32 v26, 0
	v_mov_b32_e32 v27, 0
	v_mov_b32_e32 v28, 0
	v_mov_b32_e32 v29, 0
	v_mov_b32_e32 v30, 0
	v_mov_b32_e32 v31, 0
	s_and_saveexec_b64 s[8:9], vcc
	s_cbranch_execz .LBB0_294
	v_add_u32_e32 v0, s15, v0
	v_mad_u64_u32 v[0:1], s[40:41], v0, s89, v[48:49]
	global_load_dwordx4 v[28:31], v[0:1], off offset:1024
	global_load_dwordx4 v[24:27], v[0:1], off offset:1280
.LBB0_294:
	s_or_b64 exec, exec, s[8:9]
	v_add_u32_e32 v0, 0x600, v136
	v_ashrrev_i32_e32 v65, 3, v0
	v_add_u32_e32 v0, s17, v65
	v_cmp_lt_i32_e32 vcc, -1, v0
	v_mov_b32_e32 v17, 0
	v_mov_b32_e32 v18, 0
	v_mov_b32_e32 v19, 0
	v_mov_b32_e32 v20, 0
	v_mov_b32_e32 v21, 0
	v_mov_b32_e32 v22, 0
	v_mov_b32_e32 v23, 0
	s_and_saveexec_b64 s[8:9], vcc
	s_cbranch_execz .LBB0_296
	v_add_u32_e32 v0, s15, v0
	v_mad_u64_u32 v[0:1], s[40:41], v0, s89, v[48:49]
	global_load_dwordx4 v[20:23], v[0:1], off offset:1024
	global_load_dwordx4 v[16:19], v[0:1], off offset:1280
.LBB0_296:
	s_or_b64 exec, exec, s[8:9]
	v_add_u32_e32 v0, 0x800, v136
	v_ashrrev_i32_e32 v61, 3, v0
	v_add_u32_e32 v1, s17, v61
	v_cmp_lt_i32_e32 vcc, -1, v1
	v_mov_b32_e32 v0, 0
	v_mov_b32_e32 v8, 0
	v_mov_b32_e32 v9, 0
	v_mov_b32_e32 v10, 0
	v_mov_b32_e32 v11, 0
	v_mov_b32_e32 v12, 0
	v_mov_b32_e32 v13, 0
	v_mov_b32_e32 v14, 0
	v_mov_b32_e32 v15, 0
	s_and_saveexec_b64 s[8:9], vcc
	s_cbranch_execz .LBB0_298
	v_add_u32_e32 v1, s15, v1
	v_mad_u64_u32 v[2:3], s[40:41], v1, s89, v[48:49]
	global_load_dwordx4 v[12:15], v[2:3], off offset:1024
	global_load_dwordx4 v[8:11], v[2:3], off offset:1280
.LBB0_298:
	s_or_b64 exec, exec, s[8:9]
	v_add_u32_e32 v1, 0xa00, v136
	v_ashrrev_i32_e32 v59, 3, v1
	v_add_u32_e32 v50, s17, v59
	v_cmp_lt_i32_e32 vcc, -1, v50
	v_mov_b32_e32 v1, 0
	v_mov_b32_e32 v2, 0
	v_mov_b32_e32 v3, 0
	v_mov_b32_e32 v4, 0
	v_mov_b32_e32 v5, 0
	v_mov_b32_e32 v6, 0
	v_mov_b32_e32 v7, 0
	s_and_saveexec_b64 s[8:9], vcc
	s_cbranch_execz .LBB0_300
	v_add_u32_e32 v0, s15, v50
	v_mad_u64_u32 v[0:1], s[40:41], v0, s89, v[48:49]
	global_load_dwordx4 v[4:7], v[0:1], off offset:1024
	s_nop 0
	global_load_dwordx4 v[0:3], v[0:1], off offset:1280
; #define LAS __attribute__((address_space(3)))
; __device__ __forceinline__ unsigned cvt_pk_bf16(float lo, float hi) { unsigned r; asm volatile("v_cvt_pk_bf16_f32 %0, %1, %2" : "=v"(r) : "v"(lo), "v"(hi)); return r; }
; __device__ __forceinline__ void unpack8(const u32x4 w, float* f) { f[0] = bf_lo(w.x); f[1] = bf_hi(w.x); f[2] = bf_lo(w.y); f[3] = bf_hi(w.y); f[4] = bf_lo(w.z); f[5] = bf_hi(w.z); f[6] = bf_lo(w.w); f[7] = bf_hi(w.w); }
; __device__ __forceinline__ u32x4 pack8(const float* f) { u32x4 w; w.x = cvt_pk_bf16(f[0], f[1]); w.y = cvt_pk_bf16(f[2], f[3]); w.z = cvt_pk_bf16(f[4], f[5]); w.w = cvt_pk_bf16(f[6], f[7]); return w; }
; __device__ __forceinline__ void attn_macro(const Params& p, int l, LAS unsigned char* lds, int b, int cg, int kvh) {
;     ...
; #pragma unroll
;     for (int it = 0; it < 6; ++it) {
;         const int idx = it * 512 + tid, j = idx >> 3, ch = idx & 7;
;         float kf[8], vf[8]; unpack8(kraw[it], kf); unpack8(vraw[it], vf);
;         float ss = 0.f;
; #pragma unroll
;         for (int i = 0; i < 8; ++i) ss += kf[i] * kf[i];
;         ss += __shfl_xor(ss, 1); ss += __shfl_xor(ss, 2); ss += __shfl_xor(ss, 4);
;         const float sc = __builtin_amdgcn_rsqf(ss * (1.0f / 64.0f) + EPS);
; #pragma unroll
;         for (int i = 0; i < 8; ++i) kf[i] = kf[i] * sc * knorm[ch * 8 + i];
;         *(LAS u32x4*)(Ks + j * MK_LD + ch * 8) = pack8(kf);
;         const int js = j ^ (ch << 3);
; #pragma unroll
;         for (int i = 0; i < 8; i += 2) { const unsigned w = cvt_pk_bf16(vf[i], vf[i + 1]); Vt[(ch * 8 + i) * MV_LD + js] = (bf16_t)(w & 0xffffu); Vt[(ch * 8 + i + 1) * MV_LD + js] = (bf16_t)(w >> 16); }
;         if (cg == 63 && j >= 256) {
;             const size_t o = ((((size_t)l * 2 + b) * 128 + (j - 256)) * 2 + kvh) * 64 + ch * 8; float* kd = p.out + O_KP + o; float* vd = p.out + O_VP + o;
;             *(f32x4*)kd = (f32x4){kf[0], kf[1], kf[2], kf[3]}; *(f32x4*)(kd + 4) = (f32x4){kf[4], kf[5], kf[6], kf[7]};
;             *(f32x4*)vd = (f32x4){vf[0], vf[1], vf[2], vf[3]}; *(f32x4*)(vd + 4) = (f32x4){vf[4], vf[5], vf[6], vf[7]};
;         }
;     }
.LBB0_300:
	s_or_b64 exec, exec, s[8:9]
	v_lshlrev_b32_e32 v96, 2, v57
	global_load_dwordx4 v[52:55], v96, s[50:51]
	global_load_dwordx4 v[74:77], v96, s[50:51] offset:16
	v_and_b32_e32 v60, 64, v225
	v_xor_b32_e32 v63, 1, v225
	s_waitcnt vmcnt(0) lgkmcnt(0)
	v_lshlrev_b32_e32 v78, 16, v40
	v_and_b32_e32 v79, 0xffff0000, v40
	v_add_u32_e32 v60, 64, v60
	v_lshlrev_b32_e32 v40, 16, v41
	v_and_b32_e32 v41, 0xffff0000, v41
	v_pk_mul_f32 v[66:67], v[78:79], v[78:79]
	v_cmp_lt_i32_e32 vcc, v63, v60
	v_pk_mul_f32 v[68:69], v[40:41], v[40:41]
	v_add_f32_e32 v66, v66, v67
	v_cndmask_b32_e32 v63, v225, v63, vcc
	v_lshlrev_b32_e32 v80, 16, v42
	v_and_b32_e32 v81, 0xffff0000, v42
	v_lshlrev_b32_e32 v64, 2, v63
	v_add_f32_e32 v63, v68, v66
	v_pk_mul_f32 v[82:83], v[80:81], v[80:81]
	v_add_f32_e32 v63, v69, v63
	v_lshlrev_b32_e32 v42, 16, v43
	v_and_b32_e32 v43, 0xffff0000, v43
	v_add_f32_e32 v63, v82, v63
	v_pk_mul_f32 v[84:85], v[42:43], v[42:43]
	v_add_f32_e32 v63, v83, v63
	v_add_f32_e32 v63, v84, v63
	v_add_f32_e32 v63, v85, v63
	ds_bpermute_b32 v67, v64, v63
	v_xor_b32_e32 v70, 2, v225
	v_cmp_lt_i32_e32 vcc, v70, v60
	v_xor_b32_e32 v86, 4, v225
	s_lshl_b32 s8, s12, 6
	v_cndmask_b32_e32 v66, v225, v70, vcc
	v_lshlrev_b32_e32 v66, 2, v66
	s_waitcnt lgkmcnt(0)
	v_add_f32_e32 v67, v63, v67
	ds_bpermute_b32 v69, v66, v67
	v_cmp_lt_i32_e32 vcc, v86, v60
	v_lshl_add_u32 v58, v57, 1, 0
	v_or_b32_e32 v62, s8, v57
	v_cndmask_b32_e32 v68, v225, v86, vcc
	v_lshlrev_b32_e32 v68, 2, v68
	s_waitcnt lgkmcnt(0)
	v_add_f32_e32 v67, v67, v69
	ds_bpermute_b32 v69, v68, v67
	v_mad_u64_u32 v[82:83], s[8:9], v73, s83, v[58:59]
	v_xor_b32_e32 v87, v57, v73
	s_movk_i32 s8, 0x30e
	s_waitcnt lgkmcnt(0)
	v_add_f32_e32 v67, v67, v69
	v_fmamk_f32 v67, v67, 0x3c800000, v223
	v_rsq_f32_e32 v70, v67
	v_mad_u32_u24 v63, v57, s8, v58
	v_lshlrev_b32_e32 v83, 1, v87
	v_lshlrev_b32_e32 v48, 16, v44
	v_pk_mul_f32 v[78:79], v[70:71], v[78:79] op_sel_hi:[0,1]
	v_pk_mul_f32 v[40:41], v[70:71], v[40:41] op_sel_hi:[0,1]
	v_pk_mul_f32 v[80:81], v[70:71], v[80:81] op_sel_hi:[0,1]
	v_pk_mul_f32 v[42:43], v[70:71], v[42:43] op_sel_hi:[0,1]
	v_and_b32_e32 v49, 0xffff0000, v44
	v_add_u32_e32 v84, v63, v83
	v_add_u32_e32 v67, 0x620, v63
	v_lshlrev_b32_e32 v50, 16, v45
	v_and_b32_e32 v51, 0xffff0000, v45
	v_add_u32_e32 v69, v67, v83
	s_cmp_eq_u32 s11, 63
	v_lshlrev_b32_e32 v44, 16, v46
	v_and_b32_e32 v45, 0xffff0000, v46
	s_cselect_b64 s[8:9], -1, 0
	s_and_b32 s15, s10, 0xffffff80
	s_movk_i32 s10, 0xff
	v_cmp_lt_i32_e32 vcc, s10, v73
	v_lshlrev_b32_e32 v46, 16, v47
	v_and_b32_e32 v47, 0xffff0000, v47
	s_add_i32 s15, s15, s18
	s_and_b64 s[40:41], s[8:9], vcc
	v_pk_mul_f32 v[52:53], v[52:53], v[78:79]
	v_pk_mul_f32 v[54:55], v[54:55], v[40:41]
	v_pk_mul_f32 v[40:41], v[74:75], v[80:81]
	v_pk_mul_f32 v[42:43], v[42:43], v[76:77]
	v_cvt_pk_bf16_f32 v74, v52, v53
	v_cvt_pk_bf16_f32 v75, v54, v55
	v_cvt_pk_bf16_f32 v76, v40, v41
	s_nop 0
	v_cvt_pk_bf16_f32 v77, v42, v43
	ds_write_b128 v82, v[74:77]
	v_cvt_pk_bf16_f32 v70, v48, v49
	ds_write_b16 v84, v70 offset:55296
	ds_write_b16_d16_hi v84, v70 offset:56080
	v_cvt_pk_bf16_f32 v70, v50, v51
	ds_write_b16 v69, v70 offset:55296
	ds_write_b16_d16_hi v69, v70 offset:56080
	v_add_u32_e32 v69, 0xc40, v63
	v_cvt_pk_bf16_f32 v70, v44, v45
	v_add_u32_e32 v74, v69, v83
	ds_write_b16 v74, v70 offset:55296
	ds_write_b16_d16_hi v74, v70 offset:56080
	v_add_u32_e32 v70, 0x1260, v63
	v_cvt_pk_bf16_f32 v74, v46, v47
	v_add_u32_e32 v75, v70, v83
	ds_write_b16 v75, v74 offset:55296
	ds_write_b16_d16_hi v75, v74 offset:56080
	s_and_saveexec_b64 s[10:11], s[40:41]
	s_cbranch_execz .LBB0_302
	v_add_u32_e32 v73, s15, v73
	v_add_u32_e32 v74, 0xffffff00, v73
	v_mov_b32_e32 v75, v97
	v_lshlrev_b64 v[74:75], 9, v[74:75]
	v_lshl_or_b32 v74, v62, 2, v74
	v_lshl_add_u64 v[76:77], s[54:55], 0, v[74:75]
	v_lshl_add_u64 v[74:75], s[56:57], 0, v[74:75]
	global_store_dwordx4 v[76:77], v[52:55], off
	global_store_dwordx4 v[76:77], v[40:43], off offset:16
	global_store_dwordx4 v[74:75], v[48:51], off
	global_store_dwordx4 v[74:75], v[44:47], off offset:16
.LBB0_302:
	s_or_b64 exec, exec, s[10:11]
	v_lshl_add_u64 v[48:49], s[50:51], 0, v[96:97]
	global_load_dwordx4 v[44:47], v[48:49], off
	global_load_dwordx4 v[50:53], v[48:49], off offset:16
	v_lshlrev_b32_e32 v54, 16, v36
	v_and_b32_e32 v55, 0xffff0000, v36
	v_lshlrev_b32_e32 v36, 16, v37
	v_and_b32_e32 v37, 0xffff0000, v37
	v_pk_mul_f32 v[42:43], v[54:55], v[54:55]
	v_lshlrev_b32_e32 v40, 16, v32
	v_and_b32_e32 v41, 0xffff0000, v32
	v_pk_mul_f32 v[76:77], v[36:37], v[36:37]
	v_add_f32_e32 v32, v42, v43
	v_lshlrev_b32_e32 v74, 16, v38
	v_and_b32_e32 v75, 0xffff0000, v38
	v_add_f32_e32 v32, v76, v32
	v_pk_mul_f32 v[78:79], v[74:75], v[74:75]
	v_add_f32_e32 v32, v77, v32
	v_lshlrev_b32_e32 v38, 16, v39
	v_and_b32_e32 v39, 0xffff0000, v39
	v_add_f32_e32 v32, v78, v32
	v_pk_mul_f32 v[80:81], v[38:39], v[38:39]
	v_add_f32_e32 v32, v79, v32
	v_add_f32_e32 v32, v80, v32
	v_add_f32_e32 v73, v81, v32
	ds_bpermute_b32 v76, v64, v73
	v_lshlrev_b32_e32 v42, 16, v33
	v_and_b32_e32 v43, 0xffff0000, v33
	v_lshlrev_b32_e32 v32, 16, v34
	v_and_b32_e32 v33, 0xffff0000, v34
	s_waitcnt lgkmcnt(0)
	v_add_f32_e32 v73, v73, v76
	ds_bpermute_b32 v78, v66, v73
	v_mad_u64_u32 v[76:77], s[10:11], v72, s83, v[58:59]
	s_movk_i32 s10, 0xff
	s_nop 0
	v_cmp_lt_i32_e32 vcc, s10, v72
	s_waitcnt lgkmcnt(0)
	v_add_f32_e32 v73, v73, v78
	ds_bpermute_b32 v77, v68, v73
	v_xor_b32_e32 v78, v72, v57
	v_lshlrev_b32_e32 v79, 1, v78
	v_add_u32_e32 v80, v63, v79
	v_lshlrev_b32_e32 v34, 16, v35
	s_waitcnt lgkmcnt(0)
	v_add_f32_e32 v73, v73, v77
	v_fmamk_f32 v73, v73, 0x3c800000, v223
	v_rsq_f32_e32 v78, v73
	v_add_u32_e32 v73, v67, v79
	v_add_u32_e32 v77, v69, v79
	v_add_u32_e32 v79, v70, v79
	v_pk_mul_f32 v[54:55], v[78:79], v[54:55] op_sel_hi:[0,1]
	v_pk_mul_f32 v[36:37], v[78:79], v[36:37] op_sel_hi:[0,1]
	v_pk_mul_f32 v[74:75], v[78:79], v[74:75] op_sel_hi:[0,1]
	v_pk_mul_f32 v[38:39], v[78:79], v[38:39] op_sel_hi:[0,1]
	v_and_b32_e32 v35, 0xffff0000, v35
	s_and_b64 s[40:41], s[8:9], vcc
	s_waitcnt vmcnt(0)
	v_pk_mul_f32 v[44:45], v[44:45], v[54:55]
	v_pk_mul_f32 v[46:47], v[46:47], v[36:37]
	v_pk_mul_f32 v[36:37], v[50:51], v[74:75]
	v_cvt_pk_bf16_f32 v50, v44, v45
	v_pk_mul_f32 v[38:39], v[38:39], v[52:53]
	v_cvt_pk_bf16_f32 v51, v46, v47
	v_cvt_pk_bf16_f32 v52, v36, v37
	s_nop 0
	v_cvt_pk_bf16_f32 v53, v38, v39
	ds_write_b128 v76, v[50:53]
	v_cvt_pk_bf16_f32 v50, v40, v41
	ds_write_b16 v80, v50 offset:55296
	ds_write_b16_d16_hi v80, v50 offset:56080
	v_cvt_pk_bf16_f32 v50, v42, v43
	ds_write_b16 v73, v50 offset:55296
	ds_write_b16_d16_hi v73, v50 offset:56080
	v_cvt_pk_bf16_f32 v50, v32, v33
	ds_write_b16 v77, v50 offset:55296
	ds_write_b16_d16_hi v77, v50 offset:56080
	v_cvt_pk_bf16_f32 v50, v34, v35
	ds_write_b16 v79, v50 offset:55296
	ds_write_b16_d16_hi v79, v50 offset:56080
	s_and_saveexec_b64 s[10:11], s[40:41]
	s_cbranch_execz .LBB0_304
; #define LAS __attribute__((address_space(3)))
; __device__ __forceinline__ unsigned cvt_pk_bf16(float lo, float hi) { unsigned r; asm volatile("v_cvt_pk_bf16_f32 %0, %1, %2" : "=v"(r) : "v"(lo), "v"(hi)); return r; }
; __device__ __forceinline__ void unpack8(const u32x4 w, float* f) { f[0] = bf_lo(w.x); f[1] = bf_hi(w.x); f[2] = bf_lo(w.y); f[3] = bf_hi(w.y); f[4] = bf_lo(w.z); f[5] = bf_hi(w.z); f[6] = bf_lo(w.w); f[7] = bf_hi(w.w); }
; __device__ __forceinline__ u32x4 pack8(const float* f) { u32x4 w; w.x = cvt_pk_bf16(f[0], f[1]); w.y = cvt_pk_bf16(f[2], f[3]); w.z = cvt_pk_bf16(f[4], f[5]); w.w = cvt_pk_bf16(f[6], f[7]); return w; }
; __device__ __forceinline__ void attn_macro(const Params& p, int l, LAS unsigned char* lds, int b, int cg, int kvh) {
;     ...
; #pragma unroll
;     for (int it = 0; it < 6; ++it) {
;         const int idx = it * 512 + tid, j = idx >> 3, ch = idx & 7;
;         float kf[8], vf[8]; unpack8(kraw[it], kf); unpack8(vraw[it], vf);
;         float ss = 0.f;
; #pragma unroll
;         for (int i = 0; i < 8; ++i) ss += kf[i] * kf[i];
;         ss += __shfl_xor(ss, 1); ss += __shfl_xor(ss, 2); ss += __shfl_xor(ss, 4);
;         const float sc = __builtin_amdgcn_rsqf(ss * (1.0f / 64.0f) + EPS);
; #pragma unroll
;         for (int i = 0; i < 8; ++i) kf[i] = kf[i] * sc * knorm[ch * 8 + i];
;         *(LAS u32x4*)(Ks + j * MK_LD + ch * 8) = pack8(kf);
;         const int js = j ^ (ch << 3);
; #pragma unroll
;         for (int i = 0; i < 8; i += 2) { const unsigned w = cvt_pk_bf16(vf[i], vf[i + 1]); Vt[(ch * 8 + i) * MV_LD + js] = (bf16_t)(w & 0xffffu); Vt[(ch * 8 + i + 1) * MV_LD + js] = (bf16_t)(w >> 16); }
;         if (cg == 63 && j >= 256) {
;             const size_t o = ((((size_t)l * 2 + b) * 128 + (j - 256)) * 2 + kvh) * 64 + ch * 8; float* kd = p.out + O_KP + o; float* vd = p.out + O_VP + o;
;             *(f32x4*)kd = (f32x4){kf[0], kf[1], kf[2], kf[3]}; *(f32x4*)(kd + 4) = (f32x4){kf[4], kf[5], kf[6], kf[7]};
;             *(f32x4*)vd = (f32x4){vf[0], vf[1], vf[2], vf[3]}; *(f32x4*)(vd + 4) = (f32x4){vf[4], vf[5], vf[6], vf[7]};
;         }
;     }
	v_add_u32_e32 v50, s15, v72
	v_add_u32_e32 v96, 0xffffff00, v50
	v_lshlrev_b64 v[50:51], 9, v[96:97]
	v_lshl_or_b32 v50, v62, 2, v50
	v_lshl_add_u64 v[52:53], s[54:55], 0, v[50:51]
	v_lshl_add_u64 v[50:51], s[56:57], 0, v[50:51]
	global_store_dwordx4 v[52:53], v[44:47], off
	global_store_dwordx4 v[52:53], v[36:39], off offset:16
	global_store_dwordx4 v[50:51], v[40:43], off
	global_store_dwordx4 v[50:51], v[32:35], off offset:16
.LBB0_304:
	s_or_b64 exec, exec, s[10:11]
	global_load_dwordx4 v[36:39], v[48:49], off
	global_load_dwordx4 v[40:43], v[48:49], off offset:16
	v_lshlrev_b32_e32 v44, 16, v28
	v_and_b32_e32 v45, 0xffff0000, v28
	v_lshlrev_b32_e32 v28, 16, v29
	v_and_b32_e32 v29, 0xffff0000, v29
	v_pk_mul_f32 v[34:35], v[44:45], v[44:45]
	v_lshlrev_b32_e32 v32, 16, v24
	v_and_b32_e32 v33, 0xffff0000, v24
	v_pk_mul_f32 v[50:51], v[28:29], v[28:29]
	v_add_f32_e32 v24, v34, v35
	v_lshlrev_b32_e32 v46, 16, v30
	v_and_b32_e32 v47, 0xffff0000, v30
	v_add_f32_e32 v24, v50, v24
	v_pk_mul_f32 v[52:53], v[46:47], v[46:47]
	v_add_f32_e32 v24, v51, v24
	v_lshlrev_b32_e32 v30, 16, v31
	v_and_b32_e32 v31, 0xffff0000, v31
	v_add_f32_e32 v24, v52, v24
	v_pk_mul_f32 v[54:55], v[30:31], v[30:31]
	v_add_f32_e32 v24, v53, v24
	v_add_f32_e32 v24, v54, v24
	v_add_f32_e32 v50, v55, v24
	ds_bpermute_b32 v51, v64, v50
	v_lshlrev_b32_e32 v34, 16, v25
	v_and_b32_e32 v35, 0xffff0000, v25
	v_lshlrev_b32_e32 v24, 16, v26
	v_and_b32_e32 v25, 0xffff0000, v26
	s_waitcnt lgkmcnt(0)
	v_add_f32_e32 v52, v50, v51
	ds_bpermute_b32 v53, v66, v52
	v_mad_u64_u32 v[50:51], s[10:11], v71, s83, v[58:59]
	s_movk_i32 s10, 0xff
	s_nop 0
	v_cmp_lt_i32_e32 vcc, s10, v71
	s_waitcnt lgkmcnt(0)
	v_add_f32_e32 v51, v52, v53
	ds_bpermute_b32 v52, v68, v51
	v_xor_b32_e32 v53, v71, v57
	v_lshlrev_b32_e32 v53, 1, v53
	v_add_u32_e32 v54, v63, v53
	v_add_u32_e32 v55, v69, v53
	s_waitcnt lgkmcnt(0)
	v_add_f32_e32 v51, v51, v52
	v_fmamk_f32 v51, v51, 0x3c800000, v223
	v_rsq_f32_e32 v52, v51
	v_add_u32_e32 v51, v67, v53
	v_add_u32_e32 v53, v70, v53
	v_lshlrev_b32_e32 v26, 16, v27
	v_pk_mul_f32 v[44:45], v[52:53], v[44:45] op_sel_hi:[0,1]
	v_pk_mul_f32 v[28:29], v[52:53], v[28:29] op_sel_hi:[0,1]
	v_pk_mul_f32 v[46:47], v[52:53], v[46:47] op_sel_hi:[0,1]
	v_pk_mul_f32 v[30:31], v[52:53], v[30:31] op_sel_hi:[0,1]
	v_and_b32_e32 v27, 0xffff0000, v27
	s_and_b64 s[40:41], s[8:9], vcc
	s_waitcnt vmcnt(0)
	v_pk_mul_f32 v[36:37], v[36:37], v[44:45]
	v_pk_mul_f32 v[38:39], v[38:39], v[28:29]
	v_pk_mul_f32 v[28:29], v[40:41], v[46:47]
	v_cvt_pk_bf16_f32 v40, v36, v37
	v_pk_mul_f32 v[30:31], v[30:31], v[42:43]
	v_cvt_pk_bf16_f32 v41, v38, v39
	v_cvt_pk_bf16_f32 v42, v28, v29
	s_nop 0
	v_cvt_pk_bf16_f32 v43, v30, v31
	ds_write_b128 v50, v[40:43]
	v_cvt_pk_bf16_f32 v40, v32, v33
	ds_write_b16 v54, v40 offset:55296
	ds_write_b16_d16_hi v54, v40 offset:56080
	v_cvt_pk_bf16_f32 v40, v34, v35
	ds_write_b16 v51, v40 offset:55296
	ds_write_b16_d16_hi v51, v40 offset:56080
	v_cvt_pk_bf16_f32 v40, v24, v25
	ds_write_b16 v55, v40 offset:55296
	ds_write_b16_d16_hi v55, v40 offset:56080
	v_cvt_pk_bf16_f32 v40, v26, v27
	ds_write_b16 v53, v40 offset:55296
	ds_write_b16_d16_hi v53, v40 offset:56080
	s_and_saveexec_b64 s[10:11], s[40:41]
	s_cbranch_execz .LBB0_306
	v_add_u32_e32 v40, s15, v71
	v_add_u32_e32 v96, 0xffffff00, v40
	v_lshlrev_b64 v[40:41], 9, v[96:97]
	v_lshl_or_b32 v40, v62, 2, v40
	v_lshl_add_u64 v[42:43], s[54:55], 0, v[40:41]
	v_lshl_add_u64 v[40:41], s[56:57], 0, v[40:41]
	global_store_dwordx4 v[42:43], v[36:39], off
	global_store_dwordx4 v[42:43], v[28:31], off offset:16
	global_store_dwordx4 v[40:41], v[32:35], off
	global_store_dwordx4 v[40:41], v[24:27], off offset:16
.LBB0_306:
	s_or_b64 exec, exec, s[10:11]
	global_load_dwordx4 v[28:31], v[48:49], off
	global_load_dwordx4 v[32:35], v[48:49], off offset:16
	v_lshlrev_b32_e32 v36, 16, v20
	v_and_b32_e32 v37, 0xffff0000, v20
	v_lshlrev_b32_e32 v20, 16, v21
	v_and_b32_e32 v21, 0xffff0000, v21
	v_pk_mul_f32 v[26:27], v[36:37], v[36:37]
	v_lshlrev_b32_e32 v24, 16, v16
	v_and_b32_e32 v25, 0xffff0000, v16
	v_pk_mul_f32 v[40:41], v[20:21], v[20:21]
	v_add_f32_e32 v16, v26, v27
	v_lshlrev_b32_e32 v38, 16, v22
	v_and_b32_e32 v39, 0xffff0000, v22
	v_add_f32_e32 v16, v40, v16
	v_pk_mul_f32 v[42:43], v[38:39], v[38:39]
	v_add_f32_e32 v16, v41, v16
	v_lshlrev_b32_e32 v22, 16, v23
	v_and_b32_e32 v23, 0xffff0000, v23
	v_add_f32_e32 v16, v42, v16
	v_pk_mul_f32 v[44:45], v[22:23], v[22:23]
	v_add_f32_e32 v16, v43, v16
	v_add_f32_e32 v16, v44, v16
	v_add_f32_e32 v40, v45, v16
	ds_bpermute_b32 v41, v64, v40
	v_lshlrev_b32_e32 v26, 16, v17
	v_and_b32_e32 v27, 0xffff0000, v17
	v_lshlrev_b32_e32 v16, 16, v18
	v_and_b32_e32 v17, 0xffff0000, v18
	s_waitcnt lgkmcnt(0)
	v_add_f32_e32 v42, v40, v41
	ds_bpermute_b32 v43, v66, v42
	v_mad_u64_u32 v[40:41], s[10:11], v65, s83, v[58:59]
	s_movk_i32 s10, 0xff
	s_nop 0
	v_cmp_lt_i32_e32 vcc, s10, v65
	s_waitcnt lgkmcnt(0)
	v_add_f32_e32 v41, v42, v43
	ds_bpermute_b32 v42, v68, v41
	v_xor_b32_e32 v43, v65, v57
	v_lshlrev_b32_e32 v43, 1, v43
	v_add_u32_e32 v44, v63, v43
	v_add_u32_e32 v45, v69, v43
	s_waitcnt lgkmcnt(0)
	v_add_f32_e32 v41, v41, v42
	v_fmamk_f32 v41, v41, 0x3c800000, v223
	v_rsq_f32_e32 v42, v41
	v_add_u32_e32 v41, v67, v43
	v_add_u32_e32 v43, v70, v43
	v_lshlrev_b32_e32 v18, 16, v19
	v_pk_mul_f32 v[36:37], v[42:43], v[36:37] op_sel_hi:[0,1]
	v_pk_mul_f32 v[20:21], v[42:43], v[20:21] op_sel_hi:[0,1]
	v_pk_mul_f32 v[38:39], v[42:43], v[38:39] op_sel_hi:[0,1]
	v_pk_mul_f32 v[22:23], v[42:43], v[22:23] op_sel_hi:[0,1]
	v_and_b32_e32 v19, 0xffff0000, v19
	s_and_b64 s[40:41], s[8:9], vcc
	s_waitcnt vmcnt(0)
	v_pk_mul_f32 v[28:29], v[28:29], v[36:37]
	v_pk_mul_f32 v[30:31], v[30:31], v[20:21]
	v_pk_mul_f32 v[20:21], v[32:33], v[38:39]
	v_cvt_pk_bf16_f32 v32, v28, v29
	v_pk_mul_f32 v[22:23], v[22:23], v[34:35]
	v_cvt_pk_bf16_f32 v33, v30, v31
	v_cvt_pk_bf16_f32 v34, v20, v21
	s_nop 0
	v_cvt_pk_bf16_f32 v35, v22, v23
	ds_write_b128 v40, v[32:35]
	v_cvt_pk_bf16_f32 v32, v24, v25
	ds_write_b16 v44, v32 offset:55296
	ds_write_b16_d16_hi v44, v32 offset:56080
	v_cvt_pk_bf16_f32 v32, v26, v27
	ds_write_b16 v41, v32 offset:55296
	ds_write_b16_d16_hi v41, v32 offset:56080
	v_cvt_pk_bf16_f32 v32, v16, v17
	ds_write_b16 v45, v32 offset:55296
	ds_write_b16_d16_hi v45, v32 offset:56080
	v_cvt_pk_bf16_f32 v32, v18, v19
	ds_write_b16 v43, v32 offset:55296
	ds_write_b16_d16_hi v43, v32 offset:56080
	s_and_saveexec_b64 s[10:11], s[40:41]
	s_cbranch_execz .LBB0_308
	v_add_u32_e32 v32, s15, v65
	v_add_u32_e32 v96, 0xffffff00, v32
	v_lshlrev_b64 v[32:33], 9, v[96:97]
	v_lshl_or_b32 v32, v62, 2, v32
	v_lshl_add_u64 v[34:35], s[54:55], 0, v[32:33]
	v_lshl_add_u64 v[32:33], s[56:57], 0, v[32:33]
	global_store_dwordx4 v[34:35], v[28:31], off
	global_store_dwordx4 v[34:35], v[20:23], off offset:16
	global_store_dwordx4 v[32:33], v[24:27], off
	global_store_dwordx4 v[32:33], v[16:19], off offset:16
; #define LAS __attribute__((address_space(3)))
; __device__ __forceinline__ unsigned cvt_pk_bf16(float lo, float hi) { unsigned r; asm volatile("v_cvt_pk_bf16_f32 %0, %1, %2" : "=v"(r) : "v"(lo), "v"(hi)); return r; }
; __device__ __forceinline__ void unpack8(const u32x4 w, float* f) { f[0] = bf_lo(w.x); f[1] = bf_hi(w.x); f[2] = bf_lo(w.y); f[3] = bf_hi(w.y); f[4] = bf_lo(w.z); f[5] = bf_hi(w.z); f[6] = bf_lo(w.w); f[7] = bf_hi(w.w); }
; __device__ __forceinline__ u32x4 pack8(const float* f) { u32x4 w; w.x = cvt_pk_bf16(f[0], f[1]); w.y = cvt_pk_bf16(f[2], f[3]); w.z = cvt_pk_bf16(f[4], f[5]); w.w = cvt_pk_bf16(f[6], f[7]); return w; }
; __device__ __forceinline__ void attn_macro(const Params& p, int l, LAS unsigned char* lds, int b, int cg, int kvh) {
;     ...
; #pragma unroll
;     for (int it = 0; it < 6; ++it) {
;         const int idx = it * 512 + tid, j = idx >> 3, ch = idx & 7;
;         float kf[8], vf[8]; unpack8(kraw[it], kf); unpack8(vraw[it], vf);
;         float ss = 0.f;
; #pragma unroll
;         for (int i = 0; i < 8; ++i) ss += kf[i] * kf[i];
;         ss += __shfl_xor(ss, 1); ss += __shfl_xor(ss, 2); ss += __shfl_xor(ss, 4);
;         const float sc = __builtin_amdgcn_rsqf(ss * (1.0f / 64.0f) + EPS);
; #pragma unroll
;         for (int i = 0; i < 8; ++i) kf[i] = kf[i] * sc * knorm[ch * 8 + i];
;         *(LAS u32x4*)(Ks + j * MK_LD + ch * 8) = pack8(kf);
;         const int js = j ^ (ch << 3);
; #pragma unroll
;         for (int i = 0; i < 8; i += 2) { const unsigned w = cvt_pk_bf16(vf[i], vf[i + 1]); Vt[(ch * 8 + i) * MV_LD + js] = (bf16_t)(w & 0xffffu); Vt[(ch * 8 + i + 1) * MV_LD + js] = (bf16_t)(w >> 16); }
;         if (cg == 63 && j >= 256) {
;             const size_t o = ((((size_t)l * 2 + b) * 128 + (j - 256)) * 2 + kvh) * 64 + ch * 8; float* kd = p.out + O_KP + o; float* vd = p.out + O_VP + o;
;             *(f32x4*)kd = (f32x4){kf[0], kf[1], kf[2], kf[3]}; *(f32x4*)(kd + 4) = (f32x4){kf[4], kf[5], kf[6], kf[7]};
;             *(f32x4*)vd = (f32x4){vf[0], vf[1], vf[2], vf[3]}; *(f32x4*)(vd + 4) = (f32x4){vf[4], vf[5], vf[6], vf[7]};
;         }
;     }
.LBB0_308:
	s_or_b64 exec, exec, s[10:11]
	global_load_dwordx4 v[20:23], v[48:49], off
	global_load_dwordx4 v[24:27], v[48:49], off offset:16
	v_lshlrev_b32_e32 v28, 16, v12
	v_and_b32_e32 v29, 0xffff0000, v12
	v_lshlrev_b32_e32 v12, 16, v13
	v_and_b32_e32 v13, 0xffff0000, v13
	v_pk_mul_f32 v[18:19], v[28:29], v[28:29]
	v_lshlrev_b32_e32 v16, 16, v8
	v_and_b32_e32 v17, 0xffff0000, v8
	v_pk_mul_f32 v[32:33], v[12:13], v[12:13]
	v_add_f32_e32 v8, v18, v19
	v_lshlrev_b32_e32 v30, 16, v14
	v_and_b32_e32 v31, 0xffff0000, v14
	v_add_f32_e32 v8, v32, v8
	v_pk_mul_f32 v[34:35], v[30:31], v[30:31]
	v_add_f32_e32 v8, v33, v8
	v_lshlrev_b32_e32 v14, 16, v15
	v_and_b32_e32 v15, 0xffff0000, v15
	v_add_f32_e32 v8, v34, v8
	v_pk_mul_f32 v[36:37], v[14:15], v[14:15]
	v_add_f32_e32 v8, v35, v8
	v_add_f32_e32 v8, v36, v8
	v_add_f32_e32 v32, v37, v8
	ds_bpermute_b32 v33, v64, v32
	v_lshlrev_b32_e32 v18, 16, v9
	v_and_b32_e32 v19, 0xffff0000, v9
	v_lshlrev_b32_e32 v8, 16, v10
	v_and_b32_e32 v9, 0xffff0000, v10
	s_waitcnt lgkmcnt(0)
	v_add_f32_e32 v34, v32, v33
	ds_bpermute_b32 v35, v66, v34
	v_mad_u64_u32 v[32:33], s[10:11], v61, s83, v[58:59]
	s_movk_i32 s10, 0xff
	s_nop 0
	v_cmp_lt_i32_e32 vcc, s10, v61
	s_waitcnt lgkmcnt(0)
	v_add_f32_e32 v33, v34, v35
	ds_bpermute_b32 v34, v68, v33
	v_xor_b32_e32 v35, v61, v57
	v_lshlrev_b32_e32 v35, 1, v35
	v_add_u32_e32 v36, v63, v35
	v_add_u32_e32 v37, v69, v35
	s_waitcnt lgkmcnt(0)
	v_add_f32_e32 v33, v33, v34
	v_fmamk_f32 v33, v33, 0x3c800000, v223
	v_rsq_f32_e32 v34, v33
	v_add_u32_e32 v33, v67, v35
	v_add_u32_e32 v35, v70, v35
	v_lshlrev_b32_e32 v10, 16, v11
	v_pk_mul_f32 v[28:29], v[34:35], v[28:29] op_sel_hi:[0,1]
	v_pk_mul_f32 v[12:13], v[34:35], v[12:13] op_sel_hi:[0,1]
	v_pk_mul_f32 v[30:31], v[34:35], v[30:31] op_sel_hi:[0,1]
	v_pk_mul_f32 v[14:15], v[34:35], v[14:15] op_sel_hi:[0,1]
	v_and_b32_e32 v11, 0xffff0000, v11
	s_and_b64 s[40:41], s[8:9], vcc
	s_waitcnt vmcnt(0)
	v_pk_mul_f32 v[20:21], v[20:21], v[28:29]
	v_pk_mul_f32 v[22:23], v[22:23], v[12:13]
	v_pk_mul_f32 v[12:13], v[24:25], v[30:31]
	v_cvt_pk_bf16_f32 v24, v20, v21
	v_pk_mul_f32 v[14:15], v[14:15], v[26:27]
	v_cvt_pk_bf16_f32 v25, v22, v23
	v_cvt_pk_bf16_f32 v26, v12, v13
	s_nop 0
	v_cvt_pk_bf16_f32 v27, v14, v15
	ds_write_b128 v32, v[24:27]
	v_cvt_pk_bf16_f32 v24, v16, v17
	ds_write_b16 v36, v24 offset:55296
	ds_write_b16_d16_hi v36, v24 offset:56080
	v_cvt_pk_bf16_f32 v24, v18, v19
	ds_write_b16 v33, v24 offset:55296
	ds_write_b16_d16_hi v33, v24 offset:56080
	v_cvt_pk_bf16_f32 v24, v8, v9
	ds_write_b16 v37, v24 offset:55296
	ds_write_b16_d16_hi v37, v24 offset:56080
	v_cvt_pk_bf16_f32 v24, v10, v11
	ds_write_b16 v35, v24 offset:55296
	ds_write_b16_d16_hi v35, v24 offset:56080
	s_and_saveexec_b64 s[10:11], s[40:41]
	s_cbranch_execz .LBB0_310
	v_add_u32_e32 v24, s15, v61
	v_add_u32_e32 v96, 0xffffff00, v24
	v_lshlrev_b64 v[24:25], 9, v[96:97]
	v_lshl_or_b32 v24, v62, 2, v24
	v_lshl_add_u64 v[26:27], s[54:55], 0, v[24:25]
	v_lshl_add_u64 v[24:25], s[56:57], 0, v[24:25]
	global_store_dwordx4 v[26:27], v[20:23], off
	global_store_dwordx4 v[26:27], v[12:15], off offset:16
	global_store_dwordx4 v[24:25], v[16:19], off
	global_store_dwordx4 v[24:25], v[8:11], off offset:16
.LBB0_310:
	s_or_b64 exec, exec, s[10:11]
	global_load_dwordx4 v[12:15], v[48:49], off
	global_load_dwordx4 v[16:19], v[48:49], off offset:16
	v_lshlrev_b32_e32 v20, 16, v4
	v_and_b32_e32 v21, 0xffff0000, v4
	v_lshlrev_b32_e32 v4, 16, v5
	v_and_b32_e32 v5, 0xffff0000, v5
	v_pk_mul_f32 v[10:11], v[20:21], v[20:21]
	v_lshlrev_b32_e32 v8, 16, v0
	v_and_b32_e32 v9, 0xffff0000, v0
	v_pk_mul_f32 v[24:25], v[4:5], v[4:5]
	v_add_f32_e32 v0, v10, v11
	v_lshlrev_b32_e32 v22, 16, v6
	v_and_b32_e32 v23, 0xffff0000, v6
	v_add_f32_e32 v0, v24, v0
	v_pk_mul_f32 v[26:27], v[22:23], v[22:23]
	v_add_f32_e32 v0, v25, v0
	v_lshlrev_b32_e32 v6, 16, v7
	v_and_b32_e32 v7, 0xffff0000, v7
	v_add_f32_e32 v0, v26, v0
	v_pk_mul_f32 v[28:29], v[6:7], v[6:7]
	v_add_f32_e32 v0, v27, v0
	v_add_f32_e32 v0, v28, v0
	v_add_f32_e32 v24, v29, v0
	ds_bpermute_b32 v25, v64, v24
	v_lshlrev_b32_e32 v10, 16, v1
	v_and_b32_e32 v11, 0xffff0000, v1
	v_lshlrev_b32_e32 v0, 16, v2
	v_and_b32_e32 v1, 0xffff0000, v2
	s_waitcnt lgkmcnt(0)
	v_add_f32_e32 v26, v24, v25
	ds_bpermute_b32 v27, v66, v26
	v_mad_u64_u32 v[24:25], s[10:11], v59, s83, v[58:59]
	s_movk_i32 s10, 0xff
	s_nop 0
	v_cmp_lt_i32_e32 vcc, s10, v59
	s_waitcnt lgkmcnt(0)
	v_add_f32_e32 v25, v26, v27
	ds_bpermute_b32 v26, v68, v25
	v_xor_b32_e32 v27, v59, v57
	v_lshlrev_b32_e32 v27, 1, v27
	v_add_u32_e32 v28, v63, v27
	v_add_u32_e32 v29, v69, v27
	s_waitcnt lgkmcnt(0)
	v_add_f32_e32 v25, v25, v26
	v_fmamk_f32 v25, v25, 0x3c800000, v223
	v_rsq_f32_e32 v26, v25
	v_add_u32_e32 v25, v67, v27
	v_add_u32_e32 v27, v70, v27
	v_lshlrev_b32_e32 v2, 16, v3
	v_pk_mul_f32 v[20:21], v[26:27], v[20:21] op_sel_hi:[0,1]
	v_pk_mul_f32 v[4:5], v[26:27], v[4:5] op_sel_hi:[0,1]
	v_pk_mul_f32 v[22:23], v[26:27], v[22:23] op_sel_hi:[0,1]
	v_pk_mul_f32 v[6:7], v[26:27], v[6:7] op_sel_hi:[0,1]
	v_and_b32_e32 v3, 0xffff0000, v3
	s_and_b64 s[10:11], s[8:9], vcc
	s_waitcnt vmcnt(0)
	v_pk_mul_f32 v[12:13], v[12:13], v[20:21]
	v_pk_mul_f32 v[14:15], v[14:15], v[4:5]
	v_pk_mul_f32 v[4:5], v[16:17], v[22:23]
	v_cvt_pk_bf16_f32 v16, v12, v13
	v_pk_mul_f32 v[6:7], v[6:7], v[18:19]
	v_cvt_pk_bf16_f32 v17, v14, v15
	v_cvt_pk_bf16_f32 v18, v4, v5
	s_nop 0
	v_cvt_pk_bf16_f32 v19, v6, v7
	ds_write_b128 v24, v[16:19]
	v_cvt_pk_bf16_f32 v16, v8, v9
	ds_write_b16 v28, v16 offset:55296
	ds_write_b16_d16_hi v28, v16 offset:56080
	v_cvt_pk_bf16_f32 v16, v10, v11
	ds_write_b16 v25, v16 offset:55296
	ds_write_b16_d16_hi v25, v16 offset:56080
	v_cvt_pk_bf16_f32 v16, v0, v1
	ds_write_b16 v29, v16 offset:55296
	ds_write_b16_d16_hi v29, v16 offset:56080
	v_cvt_pk_bf16_f32 v16, v2, v3
	ds_write_b16 v27, v16 offset:55296
	ds_write_b16_d16_hi v27, v16 offset:56080
	s_and_saveexec_b64 s[8:9], s[10:11]
	s_cbranch_execz .LBB0_312
	v_add_u32_e32 v16, s15, v59
	v_add_u32_e32 v96, 0xffffff00, v16
	v_lshlrev_b64 v[16:17], 9, v[96:97]
	v_lshl_or_b32 v16, v62, 2, v16
	v_lshl_add_u64 v[18:19], s[54:55], 0, v[16:17]
	v_lshl_add_u64 v[16:17], s[56:57], 0, v[16:17]
	global_store_dwordx4 v[18:19], v[12:15], off
	global_store_dwordx4 v[18:19], v[4:7], off offset:16
	global_store_dwordx4 v[16:17], v[8:11], off
	global_store_dwordx4 v[16:17], v[0:3], off offset:16

; #define LAS __attribute__((address_space(3)))
; __device__ __forceinline__ unsigned cvt_pk_bf16(float lo, float hi) { unsigned r; asm volatile("v_cvt_pk_bf16_f32 %0, %1, %2" : "=v"(r) : "v"(lo), "v"(hi)); return r; }
; __device__ __forceinline__ void attn_macro(const Params& p, int l, LAS unsigned char* lds, int b, int cg, int kvh) {
;     ...
;         f32x16 o[2]; o[0] = (f32x16){}; o[1] = (f32x16){};
; #pragma unroll
;         for (int kt = 0; kt < 6; ++kt)
; #pragma unroll
;             for (int jj = 0; jj < 2; ++jj) {
;                 u32x4 pw;
;                 pw.x = cvt_pk_bf16(s[kt][8 * jj + 0], s[kt][8 * jj + 1]); pw.y = cvt_pk_bf16(s[kt][8 * jj + 2], s[kt][8 * jj + 3]);
;                 pw.z = cvt_pk_bf16(s[kt][8 * jj + 4], s[kt][8 * jj + 5]); pw.w = cvt_pk_bf16(s[kt][8 * jj + 6], s[kt][8 * jj + 7]);
;                 const bf16x8 pa = __builtin_bit_cast(bf16x8, pw);
;                 const int e0 = 32 * kt + 16 * jj + 4 * hi;
; #pragma unroll
;                 for (int db = 0; db < 2; ++db) {
;                     const int sw = (((db * 32 + q32) >> 3) & 7) << 3;
;                     const LAS bf16_t* vrow = Vt + (db * 32 + q32) * MV_LD + ci * 64;
;                     const u32x2 lo = *(const LAS u32x2*)(vrow + (e0 ^ sw)), hi2 = *(const LAS u32x2*)(vrow + ((e0 + 8) ^ sw));
;                     const bf16x8 vb = __builtin_bit_cast(bf16x8, (u32x4){lo.x, lo.y, hi2.x, hi2.y});
;                     o[db] = __builtin_amdgcn_mfma_f32_32x32x16_bf16(pa, vb, o[db], 0, 0, 0);
;                 }
;                 __builtin_amdgcn_sched_barrier(0);
;             }
.LBB0_313:
	s_or_b64 exec, exec, s[2:3]
	v_or_b32_e32 v183, 32, v144
	v_bitop3_b32 v4, v183, v96, 56 bitop3:0x6c
	v_mul_u32_u24_e32 v182, 0x310, v144
	v_cvt_pk_bf16_f32 v16, v0, v1
	v_cvt_pk_bf16_f32 v17, v2, v3
	v_cvt_pk_bf16_f32 v18, v5, v6
	v_bitop3_b32 v0, v96, v145, 24 bitop3:0x78
	s_add_i32 s2, s25, 0
	v_bitop3_b32 v1, v83, v145, 24 bitop3:0x78
	v_lshlrev_b32_e32 v4, 1, v4
	v_bitop3_b32 v5, v183, v83, 56 bitop3:0x6c
	v_lshlrev_b32_e32 v0, 1, v0
	v_lshlrev_b32_e32 v1, 1, v1
	v_add3_u32 v4, v182, v4, s2
	v_lshlrev_b32_e32 v5, 1, v5
	v_add3_u32 v0, v182, v0, s2
	v_add3_u32 v2, v182, v1, s2
	v_add_u32_e32 v4, 0x13a00, v4
	v_add3_u32 v5, v182, v5, s2
	v_cvt_pk_bf16_f32 v19, v7, v12
	ds_read_b64 v[0:1], v0 offset:55296
	ds_read_b64 v[2:3], v2 offset:55296
	v_add_u32_e32 v5, 0x13a00, v5
	ds_read_b64 v[20:21], v4
	ds_read_b64 v[22:23], v5
	s_waitcnt lgkmcnt(0)
	v_mfma_f32_32x32x16_bf16 v[0:15], v[16:19], v[0:3], 0
	v_mfma_f32_32x32x16_bf16 v[16:31], v[16:19], v[20:23], 0
	v_cvt_pk_bf16_f32 v184, v42, v43
	v_bitop3_b32 v42, v81, v145, 24 bitop3:0x78
	v_lshlrev_b32_e32 v42, 1, v42
	v_add3_u32 v42, v182, v42, s2
	v_cvt_pk_bf16_f32 v185, v45, v53
	v_cvt_pk_bf16_f32 v186, v61, v70
	v_cvt_pk_bf16_f32 v187, v74, v86
	ds_read_b64 v[188:189], v42 offset:55296
	v_bitop3_b32 v42, v84, v145, 24 bitop3:0x78
	v_lshlrev_b32_e32 v42, 1, v42
	v_add3_u32 v42, v182, v42, s2
	ds_read_b64 v[190:191], v42 offset:55296
	v_bitop3_b32 v42, v183, v81, 56 bitop3:0x6c
	v_lshlrev_b32_e32 v42, 1, v42
	v_add3_u32 v42, v182, v42, s2
	v_add_u32_e32 v42, 0x13a00, v42
	s_waitcnt lgkmcnt(0)
	v_mfma_f32_32x32x16_bf16 v[0:15], v[184:187], v[188:191], v[0:15]
	ds_read_b64 v[188:189], v42
	v_bitop3_b32 v42, v183, v84, 56 bitop3:0x6c
	v_lshlrev_b32_e32 v42, 1, v42
	v_add3_u32 v42, v182, v42, s2
	v_add_u32_e32 v42, 0x13a00, v42
	ds_read_b64 v[190:191], v42
	s_waitcnt lgkmcnt(0)
	v_mfma_f32_32x32x16_bf16 v[16:31], v[184:187], v[188:191], v[16:31]
	v_cvt_pk_bf16_f32 v42, v44, v46
	v_bitop3_b32 v46, v82, v145, 24 bitop3:0x78
	v_lshlrev_b32_e32 v46, 1, v46
	v_add3_u32 v46, v182, v46, s2
	v_cvt_pk_bf16_f32 v43, v54, v57
	v_cvt_pk_bf16_f32 v44, v71, v77
	v_cvt_pk_bf16_f32 v45, v87, v94
	ds_read_b64 v[184:185], v46 offset:55296
	v_bitop3_b32 v46, v67, v145, 24 bitop3:0x78
	v_lshlrev_b32_e32 v46, 1, v46
	v_add3_u32 v46, v182, v46, s2
	ds_read_b64 v[186:187], v46 offset:55296
	v_bitop3_b32 v46, v183, v82, 56 bitop3:0x6c
	v_lshlrev_b32_e32 v46, 1, v46
	v_add3_u32 v46, v182, v46, s2
	v_add_u32_e32 v46, 0x13a00, v46
	s_waitcnt lgkmcnt(0)
	v_mfma_f32_32x32x16_bf16 v[0:15], v[42:45], v[184:187], v[0:15]
	ds_read_b64 v[184:185], v46
	v_bitop3_b32 v46, v183, v67, 56 bitop3:0x6c
	v_lshlrev_b32_e32 v46, 1, v46
	v_add3_u32 v46, v182, v46, s2
	v_add_u32_e32 v46, 0x13a00, v46
	ds_read_b64 v[186:187], v46
	s_waitcnt lgkmcnt(0)
	v_mfma_f32_32x32x16_bf16 v[16:31], v[42:45], v[184:187], v[16:31]
	v_bitop3_b32 v46, v65, v145, 24 bitop3:0x78
	v_lshlrev_b32_e32 v46, 1, v46
	v_add3_u32 v46, v182, v46, s2
	v_cvt_pk_bf16_f32 v42, v47, v55
	v_cvt_pk_bf16_f32 v43, v58, v62
	v_cvt_pk_bf16_f32 v44, v78, v90
	v_cvt_pk_bf16_f32 v45, v95, v120
	ds_read_b64 v[184:185], v46 offset:55296
	v_bitop3_b32 v46, v66, v145, 24 bitop3:0x78
	v_lshlrev_b32_e32 v46, 1, v46
	v_add3_u32 v46, v182, v46, s2
	ds_read_b64 v[186:187], v46 offset:55296
	v_bitop3_b32 v46, v183, v65, 56 bitop3:0x6c
	v_lshlrev_b32_e32 v46, 1, v46
	v_add3_u32 v46, v182, v46, s2
	v_add_u32_e32 v46, 0x13a00, v46
	s_waitcnt lgkmcnt(0)
	v_mfma_f32_32x32x16_bf16 v[0:15], v[42:45], v[184:187], v[0:15]
	ds_read_b64 v[184:185], v46
	v_bitop3_b32 v46, v183, v66, 56 bitop3:0x6c
	v_lshlrev_b32_e32 v46, 1, v46
	v_add3_u32 v46, v182, v46, s2
	v_add_u32_e32 v46, 0x13a00, v46
	ds_read_b64 v[186:187], v46
	s_waitcnt lgkmcnt(0)
	v_mfma_f32_32x32x16_bf16 v[16:31], v[42:45], v[184:187], v[16:31]
	v_bitop3_b32 v46, v64, v145, 24 bitop3:0x78
	v_lshlrev_b32_e32 v46, 1, v46
	v_add3_u32 v46, v182, v46, s2
	v_cvt_pk_bf16_f32 v42, v56, v59
	v_cvt_pk_bf16_f32 v43, v63, v72
	v_cvt_pk_bf16_f32 v44, v91, v116
	v_cvt_pk_bf16_f32 v45, v121, v148
	ds_read_b64 v[54:55], v46 offset:55296
	v_bitop3_b32 v46, v52, v145, 24 bitop3:0x78
	v_lshlrev_b32_e32 v46, 1, v46
	v_add3_u32 v46, v182, v46, s2
	ds_read_b64 v[56:57], v46 offset:55296
	v_bitop3_b32 v46, v183, v64, 56 bitop3:0x6c
	v_lshlrev_b32_e32 v46, 1, v46
	v_add3_u32 v46, v182, v46, s2
	v_add_u32_e32 v46, 0x13a00, v46
	s_waitcnt lgkmcnt(0)
	v_mfma_f32_32x32x16_bf16 v[0:15], v[42:45], v[54:57], v[0:15]
	ds_read_b64 v[54:55], v46
	v_bitop3_b32 v46, v183, v52, 56 bitop3:0x6c
	v_lshlrev_b32_e32 v46, 1, v46
	v_add3_u32 v46, v182, v46, s2
	v_add_u32_e32 v46, 0x13a00, v46
	ds_read_b64 v[56:57], v46
	s_waitcnt lgkmcnt(0)
	v_mfma_f32_32x32x16_bf16 v[16:31], v[42:45], v[54:57], v[16:31]
	v_bitop3_b32 v46, v49, v145, 24 bitop3:0x78
	v_lshlrev_b32_e32 v46, 1, v46
	v_add3_u32 v46, v182, v46, s2
	v_cvt_pk_bf16_f32 v42, v60, v68
	v_cvt_pk_bf16_f32 v43, v73, v79
	v_cvt_pk_bf16_f32 v44, v117, v124
	v_cvt_pk_bf16_f32 v45, v149, v156
	ds_read_b64 v[52:53], v46 offset:55296
	v_bitop3_b32 v46, v51, v145, 24 bitop3:0x78
	v_lshlrev_b32_e32 v46, 1, v46
	v_add3_u32 v46, v182, v46, s2
	ds_read_b64 v[54:55], v46 offset:55296
	v_bitop3_b32 v46, v183, v49, 56 bitop3:0x6c
	v_lshlrev_b32_e32 v46, 1, v46
	v_add3_u32 v46, v182, v46, s2
	v_add_u32_e32 v46, 0x13a00, v46
	s_waitcnt lgkmcnt(0)
	v_mfma_f32_32x32x16_bf16 v[0:15], v[42:45], v[52:55], v[0:15]
	ds_read_b64 v[52:53], v46
	v_bitop3_b32 v46, v183, v51, 56 bitop3:0x6c
	v_lshlrev_b32_e32 v46, 1, v46
	v_add3_u32 v46, v182, v46, s2
	v_add_u32_e32 v46, 0x13a00, v46
	ds_read_b64 v[54:55], v46
	s_waitcnt lgkmcnt(0)
; #define LAS __attribute__((address_space(3)))
; __device__ __forceinline__ unsigned cvt_pk_bf16(float lo, float hi) { unsigned r; asm volatile("v_cvt_pk_bf16_f32 %0, %1, %2" : "=v"(r) : "v"(lo), "v"(hi)); return r; }
; __device__ __forceinline__ void attn_macro(const Params& p, int l, LAS unsigned char* lds, int b, int cg, int kvh) {
;     ...
;         f32x16 o[2]; o[0] = (f32x16){}; o[1] = (f32x16){};
; #pragma unroll
;         for (int kt = 0; kt < 6; ++kt)
; #pragma unroll
;             for (int jj = 0; jj < 2; ++jj) {
;                 u32x4 pw;
;                 pw.x = cvt_pk_bf16(s[kt][8 * jj + 0], s[kt][8 * jj + 1]); pw.y = cvt_pk_bf16(s[kt][8 * jj + 2], s[kt][8 * jj + 3]);
;                 pw.z = cvt_pk_bf16(s[kt][8 * jj + 4], s[kt][8 * jj + 5]); pw.w = cvt_pk_bf16(s[kt][8 * jj + 6], s[kt][8 * jj + 7]);
;                 const bf16x8 pa = __builtin_bit_cast(bf16x8, pw);
;                 const int e0 = 32 * kt + 16 * jj + 4 * hi;
; #pragma unroll
;                 for (int db = 0; db < 2; ++db) {
;                     const int sw = (((db * 32 + q32) >> 3) & 7) << 3;
;                     const LAS bf16_t* vrow = Vt + (db * 32 + q32) * MV_LD + ci * 64;
;                     const u32x2 lo = *(const LAS u32x2*)(vrow + (e0 ^ sw)), hi2 = *(const LAS u32x2*)(vrow + ((e0 + 8) ^ sw));
;                     const bf16x8 vb = __builtin_bit_cast(bf16x8, (u32x4){lo.x, lo.y, hi2.x, hi2.y});
;                     o[db] = __builtin_amdgcn_mfma_f32_32x32x16_bf16(pa, vb, o[db], 0, 0, 0);
;                 }
;                 __builtin_amdgcn_sched_barrier(0);
;             }
	v_mfma_f32_32x32x16_bf16 v[16:31], v[42:45], v[52:55], v[16:31]
	v_bitop3_b32 v46, v48, v145, 24 bitop3:0x78
	v_lshlrev_b32_e32 v46, 1, v46
	v_add3_u32 v46, v182, v46, s2
	v_cvt_pk_bf16_f32 v42, v69, v75
	v_cvt_pk_bf16_f32 v43, v85, v92
	v_cvt_pk_bf16_f32 v44, v125, v152
	v_cvt_pk_bf16_f32 v45, v157, v163
	ds_read_b64 v[52:53], v46 offset:55296
	v_bitop3_b32 v46, v50, v145, 24 bitop3:0x78
	v_lshlrev_b32_e32 v46, 1, v46
	v_add3_u32 v46, v182, v46, s2
	ds_read_b64 v[54:55], v46 offset:55296
	v_bitop3_b32 v46, v183, v48, 56 bitop3:0x6c
	v_bitop3_b32 v48, v183, v50, 56 bitop3:0x6c
	v_lshlrev_b32_e32 v46, 1, v46
	v_lshlrev_b32_e32 v48, 1, v48
	v_add3_u32 v46, v182, v46, s2
	v_add3_u32 v48, v182, v48, s2
	v_add_u32_e32 v46, 0x13a00, v46
	v_add_u32_e32 v48, 0x13a00, v48
	ds_read_b64 v[46:47], v46
	ds_read_b64 v[48:49], v48
	s_waitcnt lgkmcnt(0)
	v_mfma_f32_32x32x16_bf16 v[0:15], v[42:45], v[52:55], v[0:15]
	v_mfma_f32_32x32x16_bf16 v[16:31], v[42:45], v[46:49], v[16:31]
	v_bitop3_b32 v46, v39, v145, 24 bitop3:0x78
	v_bitop3_b32 v48, v41, v145, 24 bitop3:0x78
	v_lshlrev_b32_e32 v46, 1, v46
	v_lshlrev_b32_e32 v48, 1, v48
	v_add3_u32 v46, v182, v46, s2
	v_add3_u32 v48, v182, v48, s2
	v_cvt_pk_bf16_f32 v42, v76, v88
	v_cvt_pk_bf16_f32 v43, v93, v118
	v_cvt_pk_bf16_f32 v44, v153, v159
	v_cvt_pk_bf16_f32 v45, v164, v168
	ds_read_b64 v[46:47], v46 offset:55296
	ds_read_b64 v[48:49], v48 offset:55296
	v_bitop3_b32 v39, v183, v39, 56 bitop3:0x6c
	v_lshlrev_b32_e32 v39, 1, v39
	v_add3_u32 v39, v182, v39, s2
	v_add_u32_e32 v39, 0x13a00, v39
	s_waitcnt lgkmcnt(0)
	v_mfma_f32_32x32x16_bf16 v[0:15], v[42:45], v[46:49], v[0:15]
	ds_read_b64 v[46:47], v39
	v_bitop3_b32 v39, v183, v41, 56 bitop3:0x6c
	v_lshlrev_b32_e32 v39, 1, v39
	v_add3_u32 v39, v182, v39, s2
	v_add_u32_e32 v39, 0x13a00, v39
	ds_read_b64 v[48:49], v39
	s_waitcnt lgkmcnt(0)
	v_mfma_f32_32x32x16_bf16 v[16:31], v[42:45], v[46:49], v[16:31]
	v_bitop3_b32 v39, v37, v145, 24 bitop3:0x78
	v_lshlrev_b32_e32 v39, 1, v39
	v_add3_u32 v39, v182, v39, s2
	v_cvt_pk_bf16_f32 v42, v89, v114
	v_cvt_pk_bf16_f32 v43, v119, v146
	v_cvt_pk_bf16_f32 v44, v160, v165
	v_cvt_pk_bf16_f32 v45, v169, v172
	ds_read_b64 v[46:47], v39 offset:55296
	v_bitop3_b32 v39, v40, v145, 24 bitop3:0x78
	v_lshlrev_b32_e32 v39, 1, v39
	v_add3_u32 v39, v182, v39, s2
	ds_read_b64 v[48:49], v39 offset:55296
	v_bitop3_b32 v37, v183, v37, 56 bitop3:0x6c
	v_lshlrev_b32_e32 v37, 1, v37
	v_add3_u32 v37, v182, v37, s2
	v_add_u32_e32 v37, 0x13a00, v37
	s_waitcnt lgkmcnt(0)
	v_mfma_f32_32x32x16_bf16 v[0:15], v[42:45], v[46:49], v[0:15]
	ds_read_b64 v[46:47], v37
	v_bitop3_b32 v37, v183, v40, 56 bitop3:0x6c
	v_lshlrev_b32_e32 v37, 1, v37
	v_add3_u32 v37, v182, v37, s2
	v_add_u32_e32 v37, 0x13a00, v37
	ds_read_b64 v[48:49], v37
	s_waitcnt lgkmcnt(0)
	v_mfma_f32_32x32x16_bf16 v[16:31], v[42:45], v[46:49], v[16:31]
	v_bitop3_b32 v37, v35, v145, 24 bitop3:0x78
	v_lshlrev_b32_e32 v37, 1, v37
	v_add3_u32 v37, v182, v37, s2
	v_cvt_pk_bf16_f32 v40, v115, v122
	v_cvt_pk_bf16_f32 v41, v147, v154
	v_cvt_pk_bf16_f32 v42, v166, v170
	v_cvt_pk_bf16_f32 v43, v173, v176
	ds_read_b64 v[44:45], v37 offset:55296
	v_bitop3_b32 v37, v38, v145, 24 bitop3:0x78
	v_lshlrev_b32_e32 v37, 1, v37
	v_add3_u32 v37, v182, v37, s2
	ds_read_b64 v[46:47], v37 offset:55296
	v_bitop3_b32 v35, v183, v35, 56 bitop3:0x6c
	v_lshlrev_b32_e32 v35, 1, v35
	v_add3_u32 v35, v182, v35, s2
	v_add_u32_e32 v35, 0x13a00, v35
	s_waitcnt lgkmcnt(0)
	v_mfma_f32_32x32x16_bf16 v[0:15], v[40:43], v[44:47], v[0:15]
	ds_read_b64 v[44:45], v35
	v_bitop3_b32 v35, v183, v38, 56 bitop3:0x6c
	v_lshlrev_b32_e32 v35, 1, v35
	v_add3_u32 v35, v182, v35, s2
	v_add_u32_e32 v35, 0x13a00, v35
	ds_read_b64 v[46:47], v35
	s_waitcnt lgkmcnt(0)
	v_mfma_f32_32x32x16_bf16 v[16:31], v[40:43], v[44:47], v[16:31]
	v_bitop3_b32 v35, v33, v145, 24 bitop3:0x78
	v_lshlrev_b32_e32 v35, 1, v35
	v_add3_u32 v35, v182, v35, s2
	v_cvt_pk_bf16_f32 v38, v123, v150
	v_cvt_pk_bf16_f32 v39, v155, v161
	v_cvt_pk_bf16_f32 v40, v171, v174
	v_cvt_pk_bf16_f32 v41, v177, v179
	ds_read_b64 v[42:43], v35 offset:55296
	v_bitop3_b32 v35, v36, v145, 24 bitop3:0x78
	v_lshlrev_b32_e32 v35, 1, v35
	v_add3_u32 v35, v182, v35, s2
	ds_read_b64 v[44:45], v35 offset:55296
	v_bitop3_b32 v33, v183, v33, 56 bitop3:0x6c
	v_lshlrev_b32_e32 v33, 1, v33
	v_add3_u32 v33, v182, v33, s2
	v_add_u32_e32 v33, 0x13a00, v33
	s_waitcnt lgkmcnt(0)
	v_mfma_f32_32x32x16_bf16 v[0:15], v[38:41], v[42:45], v[0:15]
	ds_read_b64 v[42:43], v33
	v_bitop3_b32 v33, v183, v36, 56 bitop3:0x6c
	v_lshlrev_b32_e32 v33, 1, v33
	v_add3_u32 v33, v182, v33, s2
	v_add_u32_e32 v33, 0x13a00, v33
	ds_read_b64 v[44:45], v33
	s_waitcnt lgkmcnt(0)
	v_mfma_f32_32x32x16_bf16 v[16:31], v[38:41], v[42:45], v[16:31]
	v_bitop3_b32 v33, v32, v145, 24 bitop3:0x78
	v_lshlrev_b32_e32 v33, 1, v33
	v_add3_u32 v33, v182, v33, s2
	v_cvt_pk_bf16_f32 v36, v151, v158
	v_cvt_pk_bf16_f32 v37, v162, v167
	v_cvt_pk_bf16_f32 v38, v175, v178
	v_cvt_pk_bf16_f32 v39, v180, v181
	ds_read_b64 v[40:41], v33 offset:55296
	v_bitop3_b32 v33, v34, v145, 24 bitop3:0x78
	v_bitop3_b32 v32, v183, v32, 56 bitop3:0x6c
	v_bitop3_b32 v34, v183, v34, 56 bitop3:0x6c
	v_lshlrev_b32_e32 v32, 1, v32
	v_lshlrev_b32_e32 v34, 1, v34
	v_lshlrev_b32_e32 v33, 1, v33
	v_add3_u32 v32, v182, v32, s2
	v_add3_u32 v34, v182, v34, s2
	v_add3_u32 v33, v182, v33, s2
	v_add_u32_e32 v32, 0x13a00, v32
	v_add_u32_e32 v34, 0x13a00, v34
	ds_read_b64 v[42:43], v33 offset:55296
	ds_read_b64 v[32:33], v32
	ds_read_b64 v[34:35], v34
	s_waitcnt lgkmcnt(0)
	v_mfma_f32_32x32x16_bf16 v[0:15], v[36:39], v[40:43], v[0:15]
	v_mfma_f32_32x32x16_bf16 v[16:31], v[36:39], v[32:35], v[16:31]
	s_waitcnt lgkmcnt(0)
; #define LAS __attribute__((address_space(3)))
; __device__ __forceinline__ unsigned cvt_pk_bf16(float lo, float hi) { unsigned r; asm volatile("v_cvt_pk_bf16_f32 %0, %1, %2" : "=v"(r) : "v"(lo), "v"(hi)); return r; }
; __device__ __forceinline__ int crow(int r, int hi) { return (r & 3) + 8 * (r >> 2) + 4 * hi; }
; __device__ __forceinline__ void attn_macro(const Params& p, int l, LAS unsigned char* lds, int b, int cg, int kvh) {
;     ...
;         asm volatile("s_waitcnt lgkmcnt(0)" ::: "memory");
;         LAS bf16_t* ost = (LAS bf16_t*)(lds + M_OST) + wid * (32 * 72);
; #pragma unroll
;         for (int r = 0; r < 16; ++r) {
;             const int qq = crow(r, hi);
;             const float inv = wsc[qq];
; #pragma unroll
;             for (int db = 0; db < 2; ++db) ost[qq * 72 + db * 32 + q32] = (bf16_t)(cvt_pk_bf16(o[db][r] * inv, 0.f) & 0xffffu);
;         }
;         asm volatile("s_waitcnt lgkmcnt(0)" ::: "memory");
; #pragma unroll
;         for (int i = 0; i < 4; ++i) {
;             const int row = i * 8 + (lane >> 3), chn = lane & 7;
;             const u32x4 v = *(const LAS u32x4*)(ost + row * 72 + chn * 8);
;             *(u32x4*)(AD + (size_t)(row0 + half * 32 + row) * DM + h * 64 + chn * 8) = v;
;         }
	v_lshl_add_u32 v36, v96, 2, s9
	ds_read_b32 v33, v36
	v_lshl_add_u32 v32, v144, 1, s11
	s_movk_i32 s2, 0x240
	s_movk_i32 s27, 0x90
	s_add_i32 s96, s16, s17
	s_waitcnt lgkmcnt(0)
	s_nop 3
	v_mul_f32_e32 v0, v0, v33
	v_mad_u64_u32 v[34:35], s[2:3], v143, s2, v[32:33]
	v_cvt_pk_bf16_f32 v0, v0, v97
	ds_write_b16 v34, v0
	v_mul_f32_e32 v0, v16, v33
	v_cvt_pk_bf16_f32 v0, v0, v97
	ds_read_b32 v16, v36 offset:4
	ds_write_b16 v34, v0 offset:64
	v_mad_u64_u32 v[32:33], s[2:3], v80, s27, v[32:33]
	s_addk_i32 s25, 0x80
	s_waitcnt lgkmcnt(0)
	v_mul_f32_e32 v0, v1, v16
	v_cvt_pk_bf16_f32 v0, v0, v97
	ds_write_b16 v32, v0
	v_mul_f32_e32 v0, v17, v16
	v_cvt_pk_bf16_f32 v0, v0, v97
	ds_read_b32 v1, v36 offset:8
	ds_write_b16 v32, v0 offset:64
	s_add_i32 s17, s17, 64
	s_sub_i32 s13, s13, 64
	s_add_i32 s10, s10, 1
	s_waitcnt lgkmcnt(0)
	v_mul_f32_e32 v0, v2, v1
	v_cvt_pk_bf16_f32 v0, v0, v97
	ds_write_b16 v32, v0 offset:144
	v_mul_f32_e32 v0, v18, v1
	v_cvt_pk_bf16_f32 v0, v0, v97
	ds_read_b32 v1, v36 offset:12
	ds_write_b16 v32, v0 offset:208
	s_cmpk_eq_i32 s25, 0x200
	s_waitcnt lgkmcnt(0)
	v_mul_f32_e32 v0, v3, v1
	v_cvt_pk_bf16_f32 v0, v0, v97
	ds_write_b16 v32, v0 offset:288
	v_mul_f32_e32 v0, v19, v1
	v_cvt_pk_bf16_f32 v0, v0, v97
	ds_read_b32 v1, v36 offset:32
	ds_write_b16 v32, v0 offset:352
	s_waitcnt lgkmcnt(0)
	v_mul_f32_e32 v0, v4, v1
	v_cvt_pk_bf16_f32 v0, v0, v97
	ds_write_b16 v32, v0 offset:1008
	v_mul_f32_e32 v0, v20, v1
	v_cvt_pk_bf16_f32 v0, v0, v97
	ds_read_b32 v1, v36 offset:36
	ds_write_b16 v32, v0 offset:1072
	s_waitcnt lgkmcnt(0)
	v_mul_f32_e32 v0, v5, v1
	v_cvt_pk_bf16_f32 v0, v0, v97
	ds_write_b16 v32, v0 offset:1152
	v_mul_f32_e32 v0, v21, v1
	v_cvt_pk_bf16_f32 v0, v0, v97
	ds_read_b32 v1, v36 offset:40
	ds_write_b16 v32, v0 offset:1216
	v_lshl_add_u64 v[4:5], s[96:97], 0, v[126:127]
	v_lshlrev_b64 v[4:5], 11, v[4:5]
	v_lshl_add_u64 v[4:5], v[128:129], 0, v[4:5]
	s_waitcnt lgkmcnt(0)
	v_mul_f32_e32 v0, v6, v1
	v_cvt_pk_bf16_f32 v0, v0, v97
	ds_write_b16 v32, v0 offset:1296
	v_mul_f32_e32 v0, v22, v1
	v_cvt_pk_bf16_f32 v0, v0, v97
	ds_read_b32 v1, v36 offset:44
	ds_write_b16 v32, v0 offset:1360
	s_waitcnt lgkmcnt(0)
	v_mul_f32_e32 v0, v7, v1
	v_cvt_pk_bf16_f32 v0, v0, v97
	ds_write_b16 v32, v0 offset:1440
	v_mul_f32_e32 v0, v23, v1
	v_cvt_pk_bf16_f32 v0, v0, v97
	ds_read_b32 v1, v36 offset:64
	ds_write_b16 v32, v0 offset:1504
	s_waitcnt lgkmcnt(0)
	v_mul_f32_e32 v0, v8, v1
	v_cvt_pk_bf16_f32 v0, v0, v97
	ds_write_b16 v32, v0 offset:2160
	v_mul_f32_e32 v0, v24, v1
	v_cvt_pk_bf16_f32 v0, v0, v97
	ds_read_b32 v1, v36 offset:68
	ds_write_b16 v32, v0 offset:2224
	s_waitcnt lgkmcnt(0)
	v_mul_f32_e32 v0, v9, v1
	v_cvt_pk_bf16_f32 v0, v0, v97
	ds_write_b16 v32, v0 offset:2304
	v_mul_f32_e32 v0, v25, v1
	v_cvt_pk_bf16_f32 v0, v0, v97
	ds_read_b32 v1, v36 offset:72
	ds_write_b16 v32, v0 offset:2368
	s_waitcnt lgkmcnt(0)
	v_mul_f32_e32 v0, v10, v1
	v_cvt_pk_bf16_f32 v0, v0, v97
	ds_write_b16 v32, v0 offset:2448
	v_mul_f32_e32 v0, v26, v1
	v_cvt_pk_bf16_f32 v0, v0, v97
	ds_read_b32 v1, v36 offset:76
	ds_write_b16 v32, v0 offset:2512
	s_waitcnt lgkmcnt(0)
	v_mul_f32_e32 v0, v11, v1
	v_cvt_pk_bf16_f32 v0, v0, v97
	ds_write_b16 v32, v0 offset:2592
	v_mul_f32_e32 v0, v27, v1
	v_cvt_pk_bf16_f32 v0, v0, v97
	ds_read_b32 v1, v36 offset:96
	ds_write_b16 v32, v0 offset:2656
	s_waitcnt lgkmcnt(0)
	v_mul_f32_e32 v0, v12, v1
	v_cvt_pk_bf16_f32 v0, v0, v97
	ds_write_b16 v32, v0 offset:3312
	v_mul_f32_e32 v0, v28, v1
	v_cvt_pk_bf16_f32 v0, v0, v97
	ds_read_b32 v1, v36 offset:100
	ds_write_b16 v32, v0 offset:3376
	s_waitcnt lgkmcnt(0)
	v_mul_f32_e32 v0, v13, v1
	v_cvt_pk_bf16_f32 v0, v0, v97
	ds_write_b16 v32, v0 offset:3456
	v_mul_f32_e32 v0, v29, v1
	v_cvt_pk_bf16_f32 v0, v0, v97
	ds_read_b32 v1, v36 offset:104
	ds_write_b16 v32, v0 offset:3520
	s_waitcnt lgkmcnt(0)
	v_mul_f32_e32 v0, v14, v1
	v_cvt_pk_bf16_f32 v0, v0, v97
	ds_write_b16 v32, v0 offset:3600
	v_mul_f32_e32 v0, v30, v1
	v_cvt_pk_bf16_f32 v0, v0, v97
	ds_read_b32 v1, v36 offset:108
	ds_write_b16 v32, v0 offset:3664
	s_waitcnt lgkmcnt(0)
	v_mul_f32_e32 v0, v15, v1
	v_cvt_pk_bf16_f32 v0, v0, v97
	ds_write_b16 v32, v0 offset:3744
	v_mul_f32_e32 v0, v31, v1
	v_cvt_pk_bf16_f32 v0, v0, v97
	ds_write_b16 v32, v0 offset:3808
	s_waitcnt lgkmcnt(0)
	ds_read_b128 v[0:3], v142
	s_waitcnt lgkmcnt(0)
	global_store_dwordx4 v[4:5], v[0:3], off
	ds_read_b128 v[0:3], v142 offset:1152
	v_lshl_add_u64 v[4:5], s[96:97], 0, v[130:131]
	v_lshlrev_b64 v[4:5], 11, v[4:5]
	v_lshl_add_u64 v[4:5], v[128:129], 0, v[4:5]
	s_waitcnt lgkmcnt(0)
	global_store_dwordx4 v[4:5], v[0:3], off
	ds_read_b128 v[0:3], v142 offset:2304
	v_lshl_add_u64 v[4:5], s[96:97], 0, v[132:133]
	v_lshlrev_b64 v[4:5], 11, v[4:5]
	v_lshl_add_u64 v[4:5], v[128:129], 0, v[4:5]
	s_waitcnt lgkmcnt(0)
	global_store_dwordx4 v[4:5], v[0:3], off
	ds_read_b128 v[0:3], v142 offset:3456
	v_lshl_add_u64 v[4:5], s[96:97], 0, v[134:135]
	v_lshlrev_b64 v[4:5], 11, v[4:5]
	v_lshl_add_u64 v[4:5], v[128:129], 0, v[4:5]
	s_waitcnt lgkmcnt(0)
	global_store_dwordx4 v[4:5], v[0:3], off
	s_waitcnt lgkmcnt(0)
	s_cbranch_scc1 .LBB0_318
; #define LAS __attribute__((address_space(3)))
; __device__ __forceinline__ void unpack8(const u32x4 w, float* f) { f[0] = bf_lo(w.x); f[1] = bf_hi(w.x); f[2] = bf_lo(w.y); f[3] = bf_hi(w.y); f[4] = bf_lo(w.z); f[5] = bf_hi(w.z); f[6] = bf_lo(w.w); f[7] = bf_hi(w.w); }
; __device__ __forceinline__ u32x4 pack8(const float* f) { u32x4 w; w.x = cvt_pk_bf16(f[0], f[1]); w.y = cvt_pk_bf16(f[2], f[3]); w.z = cvt_pk_bf16(f[4], f[5]); w.w = cvt_pk_bf16(f[6], f[7]); return w; }
; __device__ __forceinline__ void attn_macro(const Params& p, int l, LAS unsigned char* lds, int b, int cg, int kvh) {
;     ...
;         int lane_ = lane; asm volatile("" : "+v"(lane_));
;         const int q32 = lane_ & 31, hi = lane_ >> 5, tq = half * 32 + q32;
;         const float relb = (float)(128 + tq - 4 * hi);
;         bf16x8 qf[4];
;         {
;             LAS bf16_t* qst = (LAS bf16_t*)(lds + M_OST) + wid * (32 * 72);
; #pragma unroll
;             for (int i = 0; i < 4; ++i) *(LAS u32x4*)(qst + (i * 8 + (lane_ >> 3)) * 72 + (lane_ & 7) * 8) = qraw[i];
;             asm volatile("s_waitcnt lgkmcnt(0)" ::: "memory");
;             float qv[4][8]; float ss = 0.f;
; #pragma unroll
;             for (int d0 = 0; d0 < 4; ++d0) { unpack8(*(const LAS u32x4*)(qst + q32 * 72 + d0 * 16 + hi * 8), qv[d0]);
; #pragma unroll
;                 for (int i = 0; i < 8; ++i) ss += qv[d0][i] * qv[d0][i]; }
;             asm volatile("s_waitcnt lgkmcnt(0)" ::: "memory");
;             ss += __shfl_xor(ss, 32);
;             const float sc = __builtin_amdgcn_rsqf(ss * (1.0f / 64.0f) + EPS) * (0.125f * LOG2E);
; #pragma unroll
;             for (int d0 = 0; d0 < 4; ++d0) { float t8[8];
; #pragma unroll
;                 for (int i = 0; i < 8; ++i) t8[i] = qv[d0][i] * sc * qn[d0 * 16 + hi * 8 + i];
;                 qf[d0] = __builtin_bit_cast(bf16x8, pack8(t8)); }
;         }
;         if (ci < 3) {
; #pragma unroll
;             for (int i = 0; i < 4; ++i) qraw[i] = *(const u32x4*)(P + (size_t)(row0 + 64 + half * 32 + i * 8 + (lane_ >> 3)) * INW + h * 64 + (lane_ & 7) * 8);
;         }
.LBB0_314:
	v_mov_b32_e32 v145, v137
	s_movk_i32 s40, 0x90
	v_lshlrev_b32_e32 v0, 3, v145
	v_ashrrev_i32_e32 v8, 3, v145
	v_and_b32_e32 v0, 56, v0
	v_lshlrev_b32_e32 v96, 1, v0
	v_mul_lo_u32 v0, v8, s27
	v_and_b32_e32 v144, 31, v145
	v_ashrrev_i32_e32 v143, 5, v145
	v_add3_u32 v0, s11, v96, v0
	s_waitcnt vmcnt(0)
	ds_write_b128 v0, v[98:101]
	ds_write_b128 v0, v[102:105] offset:1152
	ds_write_b128 v0, v[106:109] offset:2304
	ds_write_b128 v0, v[110:113] offset:3456
	v_mul_u32_u24_e32 v0, 0x90, v144
	v_lshlrev_b32_e32 v16, 4, v143
	s_waitcnt lgkmcnt(0)
	v_add3_u32 v10, s11, v0, v16
	ds_read_b128 v[0:3], v10
	ds_read_b128 v[4:7], v10 offset:32
	s_cmpk_eq_i32 s25, 0x180
	s_waitcnt lgkmcnt(0)
	v_and_b32_e32 v30, 0xffff0000, v0
	v_lshlrev_b32_e32 v14, 16, v0
	v_mul_f32_e32 v12, v30, v30
	v_lshlrev_b32_e32 v29, 16, v1
	v_fmac_f32_e32 v12, v14, v14
	v_and_b32_e32 v28, 0xffff0000, v1
	v_fmac_f32_e32 v12, v29, v29
	v_lshlrev_b32_e32 v26, 16, v2
	v_fmac_f32_e32 v12, v28, v28
	v_and_b32_e32 v25, 0xffff0000, v2
	v_fmac_f32_e32 v12, v26, v26
	v_lshlrev_b32_e32 v24, 16, v3
	v_fmac_f32_e32 v12, v25, v25
	v_and_b32_e32 v23, 0xffff0000, v3
	v_fmac_f32_e32 v12, v24, v24
	v_fmac_f32_e32 v12, v23, v23
	s_waitcnt lgkmcnt(0)
	v_lshlrev_b32_e32 v27, 16, v4
	v_and_b32_e32 v22, 0xffff0000, v4
	v_fmac_f32_e32 v12, v27, v27
	v_lshlrev_b32_e32 v21, 16, v5
	v_fmac_f32_e32 v12, v22, v22
	v_and_b32_e32 v20, 0xffff0000, v5
	v_fmac_f32_e32 v12, v21, v21
	ds_read_b128 v[0:3], v10 offset:64
	v_lshlrev_b32_e32 v19, 16, v6
	v_fmac_f32_e32 v12, v20, v20
	v_and_b32_e32 v18, 0xffff0000, v6
	v_fmac_f32_e32 v12, v19, v19
	v_lshlrev_b32_e32 v17, 16, v7
	v_fmac_f32_e32 v12, v18, v18
	v_and_b32_e32 v9, 0xffff0000, v7
	v_fmac_f32_e32 v12, v17, v17
	v_fmac_f32_e32 v12, v9, v9
	s_waitcnt lgkmcnt(0)
	v_lshlrev_b32_e32 v42, 16, v0
	v_and_b32_e32 v37, 0xffff0000, v0
	v_fmac_f32_e32 v12, v42, v42
	v_lshlrev_b32_e32 v36, 16, v1
	v_fmac_f32_e32 v12, v37, v37
	v_and_b32_e32 v35, 0xffff0000, v1
	v_lshlrev_b32_e32 v34, 16, v2
	v_and_b32_e32 v33, 0xffff0000, v2
	v_lshlrev_b32_e32 v32, 16, v3
	v_and_b32_e32 v31, 0xffff0000, v3
	v_fmac_f32_e32 v12, v36, v36
	ds_read_b128 v[0:3], v10 offset:96
	v_fmac_f32_e32 v12, v35, v35
	v_fmac_f32_e32 v12, v34, v34
	v_fmac_f32_e32 v12, v33, v33
	v_fmac_f32_e32 v12, v32, v32
	v_fmac_f32_e32 v12, v31, v31
	s_waitcnt lgkmcnt(0)
	v_lshlrev_b32_e32 v41, 16, v0
	v_and_b32_e32 v40, 0xffff0000, v0
	v_fmac_f32_e32 v12, v41, v41
	v_lshlrev_b32_e32 v39, 16, v1
	v_fmac_f32_e32 v12, v40, v40
	v_and_b32_e32 v38, 0xffff0000, v1
	v_fmac_f32_e32 v12, v39, v39
	v_and_b32_e32 v10, 0xffff0000, v2
	v_lshlrev_b32_e32 v11, 16, v2
	v_fmac_f32_e32 v12, v38, v38
	v_pk_mul_f32 v[0:1], v[10:11], v[10:11]
	v_lshlrev_b32_e32 v13, 16, v3
	v_add_f32_e32 v1, v1, v12
	v_and_b32_e32 v12, 0xffff0000, v3
	v_add_f32_e32 v2, v0, v1
	v_pk_mul_f32 v[0:1], v[12:13], v[12:13]
	s_waitcnt lgkmcnt(0)
	s_nop 0
	v_add_f32_e32 v1, v1, v2
	v_add_f32_e32 v0, v0, v1
	ds_bpermute_b32 v1, v141, v0
	s_waitcnt lgkmcnt(0)
	v_add_f32_e32 v0, v0, v1
	v_fmamk_f32 v0, v0, 0x3c800000, v223
	v_rsq_f32_e32 v0, v0
	s_nop 0
	v_mul_f32_e32 v43, 0x3e38aa3b, v0
	v_lshlrev_b32_e32 v0, 3, v143
	v_ashrrev_i32_e32 v1, 31, v0
	v_mul_f32_e32 v44, v43, v14
	v_lshl_add_u64 v[14:15], v[0:1], 2, s[58:59]
	global_load_dwordx4 v[0:3], v[14:15], off offset:16
	global_load_dwordx4 v[4:7], v[14:15], off
	v_mul_f32_e32 v26, v43, v26
	v_mul_f32_e32 v30, v43, v30
	v_mul_f32_e32 v29, v43, v29
	v_mul_f32_e32 v28, v43, v28
	v_mul_f32_e32 v21, v43, v21
	v_mul_f32_e32 v20, v43, v20
	v_mul_f32_e32 v19, v43, v19
	v_mul_f32_e32 v18, v43, v18
	v_mul_f32_e32 v17, v43, v17
	v_mul_f32_e32 v9, v43, v9
	v_mul_f32_e32 v22, v43, v22
	v_mul_f32_e32 v10, v43, v10
	v_mul_f32_e32 v11, v43, v11
	s_waitcnt vmcnt(1)
	v_mul_f32_e32 v26, v0, v26
	v_mul_f32_e32 v0, v43, v25
	v_mul_f32_e32 v25, v1, v0
	v_mul_f32_e32 v0, v43, v24
	v_mul_f32_e32 v24, v2, v0
	v_mul_f32_e32 v0, v43, v23
	s_waitcnt vmcnt(0)
	v_mul_f32_e32 v4, v4, v44
	v_mul_f32_e32 v5, v5, v30
	v_mul_f32_e32 v6, v6, v29
	v_mul_f32_e32 v7, v7, v28
	v_mul_f32_e32 v3, v3, v0
	v_cvt_pk_bf16_f32 v0, v4, v5
	v_cvt_pk_bf16_f32 v1, v6, v7
	v_cvt_pk_bf16_f32 v2, v26, v25
	v_cvt_pk_bf16_f32 v3, v24, v3
	v_mul_f32_e32 v23, v43, v27
	global_load_dwordx4 v[4:7], v[14:15], off offset:80
	global_load_dwordx4 v[24:27], v[14:15], off offset:64
	s_waitcnt vmcnt(1)
	v_mul_f32_e32 v4, v4, v19
	s_waitcnt vmcnt(0)
	v_mul_f32_e32 v21, v26, v21
	v_mul_f32_e32 v20, v27, v20
	v_mul_f32_e32 v5, v5, v18
	v_mul_f32_e32 v6, v6, v17
	v_mul_f32_e32 v7, v7, v9
	v_mul_f32_e32 v23, v24, v23
	v_mul_f32_e32 v22, v25, v22
	v_cvt_pk_bf16_f32 v114, v23, v22
	v_cvt_pk_bf16_f32 v115, v21, v20
	v_cvt_pk_bf16_f32 v116, v4, v5
	v_cvt_pk_bf16_f32 v117, v6, v7
	global_load_dwordx4 v[4:7], v[14:15], off offset:144
	global_load_dwordx4 v[18:21], v[14:15], off offset:128
	v_mul_f32_e32 v9, v43, v42
	v_mul_f32_e32 v17, v43, v37
	s_waitcnt vmcnt(0)
	v_mul_f32_e32 v9, v18, v9
	v_mul_f32_e32 v18, v43, v36
	v_mul_f32_e32 v18, v20, v18
	v_mul_f32_e32 v20, v43, v34
	v_mul_f32_e32 v4, v4, v20
	v_mul_f32_e32 v20, v43, v33
	v_mul_f32_e32 v5, v5, v20
	v_mul_f32_e32 v20, v43, v32
	v_mul_f32_e32 v17, v19, v17
	v_mul_f32_e32 v19, v43, v35
	v_mul_f32_e32 v6, v6, v20
	v_mul_f32_e32 v20, v43, v31
	v_mul_f32_e32 v19, v21, v19
	v_mul_f32_e32 v7, v7, v20
	v_cvt_pk_bf16_f32 v118, v9, v17
	v_cvt_pk_bf16_f32 v119, v18, v19
	v_cvt_pk_bf16_f32 v120, v4, v5
	v_cvt_pk_bf16_f32 v121, v6, v7
	global_load_dwordx4 v[4:7], v[14:15], off offset:208
	global_load_dwordx4 v[18:21], v[14:15], off offset:192
	v_mul_f32_e32 v9, v43, v41
	v_mul_f32_e32 v14, v43, v40
	v_mul_f32_e32 v15, v43, v39
	v_mul_f32_e32 v17, v43, v38
	s_waitcnt vmcnt(1)
	v_mul_f32_e32 v5, v10, v5
	v_mul_f32_e32 v10, v43, v13
	v_mul_f32_e32 v6, v10, v6
	v_mul_f32_e32 v10, v43, v12
	s_waitcnt vmcnt(0)
	v_mul_f32_e32 v9, v9, v18
	v_mul_f32_e32 v14, v14, v19
	v_mul_f32_e32 v15, v15, v20
	v_mul_f32_e32 v17, v17, v21
	v_mul_f32_e32 v4, v11, v4
	v_mul_f32_e32 v7, v10, v7
	v_cvt_pk_bf16_f32 v122, v9, v14
	v_cvt_pk_bf16_f32 v123, v15, v17
	v_cvt_pk_bf16_f32 v124, v4, v5
	v_cvt_pk_bf16_f32 v125, v6, v7
	s_cbranch_scc1 .LBB0_316
	s_add_i32 s27, s16, s17
	s_add_i32 s96, s27, 64
	v_ashrrev_i32_e32 v9, 31, v8
	v_lshl_add_u64 v[4:5], s[0:1], 0, v[96:97]
	v_lshl_add_u64 v[6:7], s[96:97], 0, v[8:9]
	v_mad_u64_u32 v[10:11], s[2:3], v6, s89, v[4:5]
	s_add_i32 s96, s27, 0x48
	v_mad_i32_i24 v11, v7, s89, v11
	v_lshl_add_u64 v[6:7], s[96:97], 0, v[8:9]
	v_mad_u64_u32 v[12:13], s[2:3], v6, s89, v[4:5]
	s_add_i32 s96, s27, 0x50
	v_mad_i32_i24 v13, v7, s89, v13
	v_lshl_add_u64 v[6:7], s[96:97], 0, v[8:9]
	global_load_dwordx4 v[98:101], v[10:11], off
	global_load_dwordx4 v[102:105], v[12:13], off
	v_mad_u64_u32 v[10:11], s[2:3], v6, s89, v[4:5]
	s_add_i32 s96, s27, 0x58
	v_mad_i32_i24 v11, v7, s89, v11
	v_lshl_add_u64 v[6:7], s[96:97], 0, v[8:9]
	v_mad_u64_u32 v[4:5], s[2:3], v6, s89, v[4:5]
	v_mad_i32_i24 v5, v7, s89, v5
	global_load_dwordx4 v[106:109], v[10:11], off
	global_load_dwordx4 v[110:113], v[4:5], off

; template <int W>
; __device__ __forceinline__ void pool_task_prompt(const Params& p, int l, int b, int c, int g, int rg, int ch, long row0) {
;     ...
;     u32x4 raw[W + 3];
; #pragma unroll
;     for (int i = 0; i < W + 3; ++i) { const int tt = t0 - (W - 1) + i; raw[i] = (u32x4){0u, 0u, 0u, 0u};
;         if (tt >= 0) raw[i] = *(const u32x4*)(P + (size_t)((long)b * SEQ + tt) * INW + 768 + col); }
; __device__ __forceinline__ void attn_macro(const Params& p, int l, LAS unsigned char* lds, int b, int cg, int kvh) {
;     ...
;         const int gl = tid >> 8, g = kvh * 2 + gl, rg = (tid >> 4) & 15, ch = tid & 15;
; #pragma unroll 1
;         for (int ci = 0; ci < 4; ++ci) {
;             const int c = c0 + ci; const long row0 = rowb + (long)c * 64;
;             if (g == 0) pool_task_prompt<2>(p, l, b, c, g, rg, ch, row0);
;             else if (g == 1) pool_task_prompt<4>(p, l, b, c, g, rg, ch, row0);
;             else if (g == 2) pool_task_prompt<8>(p, l, b, c, g, rg, ch, row0);
;             else pool_task_prompt<16>(p, l, b, c, g, rg, ch, row0);
.LBB0_320:
	v_add_u32_e32 v101, s25, v99
	v_cmp_lt_i32_e32 vcc, 0, v98
	s_mov_b64 s[2:3], 0
	s_mov_b64 s[0:1], 0
	s_mov_b64 s[8:9], 0
	s_and_saveexec_b64 s[10:11], vcc
	s_xor_b64 s[10:11], exec, s[10:11]
	s_cbranch_execz .LBB0_399
	v_cmp_lt_i32_e32 vcc, 1, v98
	s_mov_b64 s[12:13], 0
	s_mov_b64 s[14:15], 0
	s_and_saveexec_b64 s[0:1], vcc
	s_xor_b64 s[8:9], exec, s[0:1]
	s_cbranch_execz .LBB0_345
	v_cmp_eq_u32_e32 vcc, 2, v98
	s_mov_b64 s[0:1], -1
	s_and_saveexec_b64 s[12:13], vcc
	s_cbranch_execz .LBB0_344
	v_cmp_lt_u32_e32 vcc, 6, v101
	v_mov_b32_e32 v4, 0
	v_lshlrev_b32_e32 v40, 1, v78
	v_mov_b32_e32 v12, 0
	v_mov_b32_e32 v13, 0
	v_mov_b32_e32 v14, 0
	v_mov_b32_e32 v15, 0
	s_and_saveexec_b64 s[0:1], vcc
	s_cbranch_execz .LBB0_325
	v_add3_u32 v2, v100, s25, -7
	v_mov_b64_e32 v[0:1], s[86:87]
	v_mad_u64_u32 v[0:1], s[14:15], v2, s89, v[0:1]
	v_mov_b32_e32 v41, v97
	v_lshl_add_u64 v[0:1], v[0:1], 0, v[40:41]
	v_add_co_u32_e32 v0, vcc, 0xfb00000, v0
	s_nop 1
	v_addc_co_u32_e32 v1, vcc, 0, v1, vcc
	global_load_dwordx4 v[12:15], v[0:1], off offset:1536
.LBB0_325:
	s_or_b64 exec, exec, s[0:1]
	v_cmp_lt_u32_e32 vcc, 5, v101
	v_mov_b32_e32 v5, 0
	v_mov_b32_e32 v6, 0
	v_mov_b32_e32 v7, 0
	s_and_saveexec_b64 s[0:1], vcc
	s_cbranch_execz .LBB0_327
	v_add3_u32 v2, v100, s25, -6
	v_mov_b64_e32 v[0:1], s[86:87]
	v_mad_u64_u32 v[0:1], s[14:15], v2, s89, v[0:1]
	v_mov_b32_e32 v41, v97
	v_lshl_add_u64 v[0:1], v[0:1], 0, v[40:41]
	v_add_co_u32_e32 v0, vcc, 0xfb00000, v0
	s_nop 1
	v_addc_co_u32_e32 v1, vcc, 0, v1, vcc
	global_load_dwordx4 v[4:7], v[0:1], off offset:1536
.LBB0_327:
	s_or_b64 exec, exec, s[0:1]
	v_cmp_lt_u32_e32 vcc, 4, v101
	v_mov_b32_e32 v16, 0
	v_mov_b32_e32 v20, 0
	v_mov_b32_e32 v21, 0
	v_mov_b32_e32 v22, 0
	v_mov_b32_e32 v23, 0
	s_and_saveexec_b64 s[0:1], vcc
	s_cbranch_execz .LBB0_329
	v_add3_u32 v2, v100, s25, -5
	v_mov_b64_e32 v[0:1], s[86:87]
	v_mad_u64_u32 v[0:1], s[14:15], v2, s89, v[0:1]
	v_mov_b32_e32 v41, v97
	v_lshl_add_u64 v[0:1], v[0:1], 0, v[40:41]
	v_add_co_u32_e32 v0, vcc, 0xfb00000, v0
	s_nop 1
	v_addc_co_u32_e32 v1, vcc, 0, v1, vcc
	global_load_dwordx4 v[20:23], v[0:1], off offset:1536
.LBB0_329:
	s_or_b64 exec, exec, s[0:1]
	v_cmp_ne_u32_e64 s[0:1], 0, v101
	v_mov_b32_e32 v17, 0
	v_mov_b32_e32 v18, 0
	v_mov_b32_e32 v19, 0
	s_and_saveexec_b64 s[14:15], s[0:1]
	s_cbranch_execz .LBB0_331
	v_add3_u32 v2, v100, s25, -4
	v_mov_b64_e32 v[0:1], s[86:87]
	v_mad_u64_u32 v[0:1], s[16:17], v2, s89, v[0:1]
	v_mov_b32_e32 v41, v97
	v_lshl_add_u64 v[0:1], v[0:1], 0, v[40:41]
	v_add_co_u32_e32 v0, vcc, 0xfb00000, v0
	s_nop 1
	v_addc_co_u32_e32 v1, vcc, 0, v1, vcc
	global_load_dwordx4 v[16:19], v[0:1], off offset:1536
.LBB0_331:
	s_or_b64 exec, exec, s[14:15]
	v_mov_b32_e32 v28, 0
	v_mov_b32_e32 v32, 0
	v_mov_b32_e32 v33, 0
	v_mov_b32_e32 v34, 0
	v_mov_b32_e32 v35, 0
	s_and_saveexec_b64 s[14:15], s[0:1]
	s_cbranch_execz .LBB0_333
	v_add3_u32 v2, v100, s25, -3
	v_mov_b64_e32 v[0:1], s[86:87]
	v_mad_u64_u32 v[0:1], s[16:17], v2, s89, v[0:1]
	v_mov_b32_e32 v41, v97
	v_lshl_add_u64 v[0:1], v[0:1], 0, v[40:41]
	v_add_co_u32_e32 v0, vcc, 0xfb00000, v0
	s_nop 1
	v_addc_co_u32_e32 v1, vcc, 0, v1, vcc
	global_load_dwordx4 v[32:35], v[0:1], off offset:1536
.LBB0_333:
	s_or_b64 exec, exec, s[14:15]
	v_mov_b32_e32 v29, 0
	v_mov_b32_e32 v30, 0
	v_mov_b32_e32 v31, 0
	s_and_saveexec_b64 s[14:15], s[0:1]
	s_cbranch_execz .LBB0_335
	v_add3_u32 v2, v100, s25, -2
	v_mov_b64_e32 v[0:1], s[86:87]
	v_mad_u64_u32 v[0:1], s[16:17], v2, s89, v[0:1]
	v_mov_b32_e32 v41, v97
	v_lshl_add_u64 v[0:1], v[0:1], 0, v[40:41]
	v_add_co_u32_e32 v0, vcc, 0xfb00000, v0
	s_nop 1
	v_addc_co_u32_e32 v1, vcc, 0, v1, vcc
	global_load_dwordx4 v[28:31], v[0:1], off offset:1536
.LBB0_335:
	s_or_b64 exec, exec, s[14:15]
	v_mov_b32_e32 v36, 0
	v_mov_b32_e32 v37, 0
	v_mov_b32_e32 v38, 0
	v_mov_b32_e32 v39, 0
	s_and_saveexec_b64 s[14:15], s[0:1]
	s_cbranch_execz .LBB0_337
	v_add3_u32 v2, v100, s25, -1
	v_mov_b64_e32 v[0:1], s[86:87]
	v_mad_u64_u32 v[0:1], s[0:1], v2, s89, v[0:1]
	v_mov_b32_e32 v41, v97
	v_lshl_add_u64 v[0:1], v[0:1], 0, v[40:41]
	v_add_co_u32_e32 v0, vcc, 0xfb00000, v0
	s_nop 1
	v_addc_co_u32_e32 v1, vcc, 0, v1, vcc
	global_load_dwordx4 v[36:39], v[0:1], off offset:1536
.LBB0_337:
	s_or_b64 exec, exec, s[14:15]
	v_lshl_add_u64 v[0:1], s[86:87], 0, v[96:97]
	v_mov_b32_e32 v41, v97
	v_lshl_add_u64 v[0:1], v[0:1], 0, v[40:41]
	v_add_co_u32_e32 v2, vcc, 0xfb00000, v0
	s_waitcnt vmcnt(0) lgkmcnt(0)
; __device__ __forceinline__ void unpack8(const u32x4 w, float* f) { f[0] = bf_lo(w.x); f[1] = bf_hi(w.x); f[2] = bf_lo(w.y); f[3] = bf_hi(w.y); f[4] = bf_lo(w.z); f[5] = bf_hi(w.z); f[6] = bf_lo(w.w); f[7] = bf_hi(w.w); }
; __device__ __forceinline__ u32x4 pack8(const float* f) { u32x4 w; w.x = cvt_pk_bf16(f[0], f[1]); w.y = cvt_pk_bf16(f[2], f[3]); w.z = cvt_pk_bf16(f[4], f[5]); w.w = cvt_pk_bf16(f[6], f[7]); return w; }
; template <int W>
; __device__ __forceinline__ void pool_task_prompt(const Params& p, int l, int b, int c, int g, int rg, int ch, long row0) {
;     ...
;     for (int i = 0; i < W + 3; ++i) { const int tt = t0 - (W - 1) + i; raw[i] = (u32x4){0u, 0u, 0u, 0u};
;         if (tt >= 0) raw[i] = *(const u32x4*)(P + (size_t)((long)b * SEQ + tt) * INW + 768 + col); }
;     float a[4][8], cur[4][8];
; #pragma unroll
;     for (int k = 0; k < 8; ++k) a[0][k] = 0.f;
; #pragma unroll
;     for (int i = 0; i < W; ++i) { float x[8]; unpack8(raw[i], x);
; #pragma unroll
;         for (int k = 0; k < 8; ++k) { a[0][k] += x[k]; if (i == W - 1) cur[0][k] = x[k]; } }
; #pragma unroll
;     for (int r = 1; r < 4; ++r) { float xin[8], xout[8]; unpack8(raw[W - 1 + r], xin); unpack8(raw[r - 1], xout);
; #pragma unroll
;         for (int k = 0; k < 8; ++k) { a[r][k] = a[r - 1][k] + (xin[k] - xout[k]); cur[r][k] = xin[k]; } }
; #pragma unroll
;     for (int r = 0; r < 4; ++r) {
;         const int t = t0 + r;
;         const float inv = 1.0f / (float)((t + 1) < W ? (t + 1) : W);
;         float d[8];
; #pragma unroll
;         for (int k = 0; k < 8; ++k) d[k] = a[r][k] * inv - cur[r][k];
;         *(u32x4*)(AD + (size_t)(row0 + tl0 + r) * DM + 512 + col) = pack8(d);
;         if (t >= SEQ - 15) { float* pd = p.out + O_PP + (((size_t)l * 2 + b) * 15 + (t - (SEQ - 15))) * 512 + col;
;             *(f32x4*)pd = (f32x4){cur[r][0], cur[r][1], cur[r][2], cur[r][3]}; *(f32x4*)(pd + 4) = (f32x4){cur[r][4], cur[r][5], cur[r][6], cur[r][7]}; }
	v_lshlrev_b32_e32 v61, 16, v12
	v_addc_co_u32_e32 v3, vcc, 0, v1, vcc
	v_add_co_u32_e32 v8, vcc, 0xfb02000, v0
	v_and_b32_e32 v62, 0xffff0000, v12
	s_nop 0
	v_addc_co_u32_e32 v9, vcc, 0, v1, vcc
	global_load_dwordx4 v[64:67], v[2:3], off offset:1536
	global_load_dwordx4 v[24:27], v[8:9], off
	v_add_co_u32_e32 v2, vcc, 0xfb03000, v0
	v_lshlrev_b32_e32 v60, 16, v13
	s_nop 0
	v_addc_co_u32_e32 v3, vcc, 0, v1, vcc
	v_add_co_u32_e32 v0, vcc, 0xfb05000, v0
	v_and_b32_e32 v59, 0xffff0000, v13
	s_nop 0
	v_addc_co_u32_e32 v1, vcc, 0, v1, vcc
	global_load_dwordx4 v[8:11], v[2:3], off offset:2560
	s_nop 0
	global_load_dwordx4 v[0:3], v[0:1], off offset:1024
	v_lshlrev_b32_e32 v58, 16, v14
	v_and_b32_e32 v57, 0xffff0000, v14
	v_lshlrev_b32_e32 v56, 16, v15
	v_and_b32_e32 v55, 0xffff0000, v15
	v_add_f32_e32 v13, 0, v61
	v_add_f32_e32 v12, 0, v62
	v_lshlrev_b32_e32 v53, 16, v4
	v_and_b32_e32 v54, 0xffff0000, v4
	v_add_f32_e32 v14, 0, v60
	v_add_f32_e32 v15, 0, v59
	v_add_f32_e32 v42, 0, v58
	v_add_f32_e32 v43, 0, v57
	v_add_f32_e32 v44, 0, v56
	v_add_f32_e32 v45, 0, v55
	v_lshlrev_b32_e32 v52, 16, v5
	v_and_b32_e32 v51, 0xffff0000, v5
	v_lshlrev_b32_e32 v50, 16, v6
	v_and_b32_e32 v49, 0xffff0000, v6
	v_lshlrev_b32_e32 v48, 16, v7
	v_and_b32_e32 v47, 0xffff0000, v7
	v_add_f32_e32 v5, v13, v53
	v_add_f32_e32 v4, v12, v54
	v_lshlrev_b32_e32 v46, 16, v20
	v_and_b32_e32 v20, 0xffff0000, v20
	v_add_f32_e32 v6, v14, v52
	v_add_f32_e32 v7, v15, v51
	v_add_f32_e32 v12, v42, v50
	v_add_f32_e32 v13, v43, v49
	v_add_f32_e32 v14, v44, v48
	v_add_f32_e32 v15, v45, v47
	v_lshlrev_b32_e32 v45, 16, v21
	v_and_b32_e32 v44, 0xffff0000, v21
	v_lshlrev_b32_e32 v43, 16, v22
	v_and_b32_e32 v42, 0xffff0000, v22
	v_lshlrev_b32_e32 v22, 16, v23
	v_and_b32_e32 v21, 0xffff0000, v23
	v_add_f32_e32 v5, v5, v46
	v_add_f32_e32 v4, v4, v20
	v_lshlrev_b32_e32 v23, 16, v16
	v_and_b32_e32 v16, 0xffff0000, v16
	v_add_f32_e32 v5, v5, v23
	v_add_f32_e32 v4, v4, v16
	v_lshlrev_b32_e32 v16, 16, v32
	v_add_f32_e32 v12, v12, v43
	v_add_f32_e32 v15, v15, v21
	v_lshlrev_b32_e32 v68, 16, v18
	v_lshlrev_b32_e32 v69, 16, v19
	v_and_b32_e32 v19, 0xffff0000, v19
	v_add_f32_e32 v5, v5, v16
	v_and_b32_e32 v16, 0xffff0000, v32
	v_add_f32_e32 v12, v12, v68
	v_add_f32_e32 v15, v15, v19
	v_lshlrev_b32_e32 v19, 16, v34
	v_add_f32_e32 v4, v4, v16
	v_lshlrev_b32_e32 v16, 16, v28
	v_add_f32_e32 v12, v12, v19
	v_lshlrev_b32_e32 v19, 16, v30
	v_add_f32_e32 v5, v5, v16
	v_and_b32_e32 v16, 0xffff0000, v28
	v_add_f32_e32 v4, v4, v16
	v_add_f32_e32 v12, v12, v19
	v_lshlrev_b32_e32 v16, 16, v36
	v_lshlrev_b32_e32 v19, 16, v38
	v_add_f32_e32 v16, v5, v16
	v_add_f32_e32 v19, v12, v19
	v_add_f32_e32 v6, v6, v45
	v_add_f32_e32 v7, v7, v44
	s_waitcnt vmcnt(0) lgkmcnt(0)
	v_lshlrev_b32_e32 v12, 16, v64
	v_add_f32_e32 v32, v16, v12
	v_min_i32_e32 v16, 7, v101
	v_add_f32_e32 v13, v13, v42
	v_add_f32_e32 v14, v14, v22
	v_lshlrev_b32_e32 v63, 16, v17
	v_and_b32_e32 v17, 0xffff0000, v17
	v_and_b32_e32 v18, 0xffff0000, v18
	v_add_u32_e32 v16, 1, v16
	v_add_f32_e32 v6, v6, v63
	v_add_f32_e32 v7, v7, v17
	v_add_f32_e32 v13, v13, v18
	v_add_f32_e32 v14, v14, v69
	v_lshlrev_b32_e32 v17, 16, v33
	v_and_b32_e32 v18, 0xffff0000, v33
	v_lshlrev_b32_e32 v33, 16, v35
	v_cvt_f32_u32_e32 v16, v16
	v_and_b32_e32 v23, 0xffff0000, v34
	v_and_b32_e32 v34, 0xffff0000, v35
	v_add_f32_e32 v6, v6, v17
	v_add_f32_e32 v7, v7, v18
	v_add_f32_e32 v14, v14, v33
	v_lshlrev_b32_e32 v17, 16, v29
	v_and_b32_e32 v18, 0xffff0000, v29
	v_lshlrev_b32_e32 v29, 16, v31
	v_add_f32_e32 v13, v13, v23
	v_add_f32_e32 v15, v15, v34
	v_and_b32_e32 v23, 0xffff0000, v30
	v_and_b32_e32 v30, 0xffff0000, v31
	v_add_f32_e32 v6, v6, v17
	v_add_f32_e32 v14, v14, v29
	v_lshlrev_b32_e32 v17, 16, v37
	v_lshlrev_b32_e32 v28, 16, v39
	v_add_f32_e32 v7, v7, v18
	v_add_f32_e32 v15, v15, v30
	v_and_b32_e32 v18, 0xffff0000, v37
	v_and_b32_e32 v29, 0xffff0000, v39
	v_add_f32_e32 v17, v6, v17
	v_add_f32_e32 v28, v14, v28
	v_lshlrev_b32_e32 v14, 16, v65
	v_add_f32_e32 v18, v7, v18
	v_add_f32_e32 v35, v15, v29
	v_and_b32_e32 v15, 0xffff0000, v65
	v_add_f32_e32 v29, v17, v14
	v_div_scale_f32 v17, s[0:1], v16, v16, 1.0
	v_add_f32_e32 v34, v18, v15
	v_rcp_f32_e32 v18, v17
	v_and_b32_e32 v5, 0xffff0000, v36
	v_add_f32_e32 v30, v4, v5
	v_lshlrev_b32_e32 v4, 16, v66
	v_add_f32_e32 v13, v13, v23
	v_and_b32_e32 v23, 0xffff0000, v38
	v_add_f32_e32 v33, v19, v4
	v_fma_f32 v19, -v17, v18, 1.0
	v_add_f32_e32 v23, v13, v23
	v_and_b32_e32 v13, 0xffff0000, v64
	v_and_b32_e32 v5, 0xffff0000, v66
	v_and_b32_e32 v7, 0xffff0000, v67
	v_fmac_f32_e32 v18, v19, v18
	v_div_scale_f32 v19, vcc, 1.0, v16, 1.0
	v_add_f32_e32 v31, v30, v13
	v_add_f32_e32 v30, v23, v5
	v_add_f32_e32 v23, v35, v7
	v_mul_f32_e32 v35, v19, v18
	v_fma_f32 v36, -v17, v35, v19
	v_fmac_f32_e32 v35, v36, v18
	v_fma_f32 v17, -v17, v35, v19
	v_lshlrev_b32_e32 v6, 16, v67
	v_div_fmas_f32 v17, v17, v18, v35
	v_add_f32_e32 v28, v28, v6
	v_div_fixup_f32 v16, v17, v16, 1.0
	v_fma_f32 v17, v16, v32, -v12
	v_fma_f32 v18, v16, v31, -v13
	v_fma_f32 v19, v16, v29, -v14
	v_fma_f32 v35, v16, v34, -v15
	v_fma_f32 v38, v16, v33, -v4
	v_fma_f32 v39, v16, v30, -v5
	v_fma_f32 v63, v16, v28, -v6
	v_fma_f32 v16, v16, v23, -v7
	v_mov_b32_e32 v93, v97
	v_cvt_pk_bf16_f32 v36, v17, v18
	v_cvt_pk_bf16_f32 v37, v19, v35
	v_cvt_pk_bf16_f32 v38, v38, v39
	v_cvt_pk_bf16_f32 v39, v63, v16
	v_lshl_add_u64 v[16:17], s[86:87], 0, v[92:93]
	v_lshl_add_u64 v[18:19], v[16:17], 0, v[40:41]
	v_add_co_u32_e32 v64, vcc, 0x7900000, v18
	s_movk_i32 s0, 0x3ff0
	s_nop 0
	v_addc_co_u32_e32 v65, vcc, 0, v19, vcc
	v_cmp_lt_u32_e32 vcc, s0, v101
	global_store_dwordx4 v[64:65], v[36:39], off offset:1024
	s_and_saveexec_b64 s[0:1], vcc
	s_cbranch_execz .LBB0_339
	v_add_u32_e32 v35, s7, v101
	v_add_u32_e32 v36, 0xffffc00f, v35
	v_mov_b32_e32 v37, v97
	v_lshlrev_b64 v[36:37], 11, v[36:37]
	v_lshl_add_u64 v[36:37], v[88:89], 0, v[36:37]
	global_store_dwordx4 v[36:37], v[12:15], off
	global_store_dwordx4 v[36:37], v[4:7], off offset:16
; __device__ __forceinline__ void unpack8(const u32x4 w, float* f) { f[0] = bf_lo(w.x); f[1] = bf_hi(w.x); f[2] = bf_lo(w.y); f[3] = bf_hi(w.y); f[4] = bf_lo(w.z); f[5] = bf_hi(w.z); f[6] = bf_lo(w.w); f[7] = bf_hi(w.w); }
; __device__ __forceinline__ u32x4 pack8(const float* f) { u32x4 w; w.x = cvt_pk_bf16(f[0], f[1]); w.y = cvt_pk_bf16(f[2], f[3]); w.z = cvt_pk_bf16(f[4], f[5]); w.w = cvt_pk_bf16(f[6], f[7]); return w; }
; template <int W>
; __device__ __forceinline__ void pool_task_prompt(const Params& p, int l, int b, int c, int g, int rg, int ch, long row0) {
;     ...
;     for (int r = 1; r < 4; ++r) { float xin[8], xout[8]; unpack8(raw[W - 1 + r], xin); unpack8(raw[r - 1], xout);
; #pragma unroll
;         for (int k = 0; k < 8; ++k) { a[r][k] = a[r - 1][k] + (xin[k] - xout[k]); cur[r][k] = xin[k]; } }
; #pragma unroll
;     for (int r = 0; r < 4; ++r) {
;         const int t = t0 + r;
;         const float inv = 1.0f / (float)((t + 1) < W ? (t + 1) : W);
;         float d[8];
; #pragma unroll
;         for (int k = 0; k < 8; ++k) d[k] = a[r][k] * inv - cur[r][k];
;         *(u32x4*)(AD + (size_t)(row0 + tl0 + r) * DM + 512 + col) = pack8(d);
;         if (t >= SEQ - 15) { float* pd = p.out + O_PP + (((size_t)l * 2 + b) * 15 + (t - (SEQ - 15))) * 512 + col;
;             *(f32x4*)pd = (f32x4){cur[r][0], cur[r][1], cur[r][2], cur[r][3]}; *(f32x4*)(pd + 4) = (f32x4){cur[r][4], cur[r][5], cur[r][6], cur[r][7]}; }
.LBB0_339:
	s_or_b64 exec, exec, s[0:1]
	v_lshlrev_b32_e32 v12, 16, v24
	v_and_b32_e32 v13, 0xffff0000, v24
	v_sub_f32_e32 v24, v12, v61
	v_add_f32_e32 v24, v32, v24
	v_add_u32_e32 v32, 1, v101
	v_min_i32_e32 v32, 7, v32
	v_add_u32_e32 v32, 1, v32
	v_cvt_f32_u32_e32 v32, v32
	v_lshlrev_b32_e32 v14, 16, v25
	v_lshlrev_b32_e32 v4, 16, v26
	v_and_b32_e32 v5, 0xffff0000, v26
	v_sub_f32_e32 v26, v14, v60
	v_and_b32_e32 v15, 0xffff0000, v25
	v_add_f32_e32 v26, v29, v26
	v_sub_f32_e32 v29, v4, v58
	v_lshlrev_b32_e32 v6, 16, v27
	v_and_b32_e32 v7, 0xffff0000, v27
	v_sub_f32_e32 v27, v15, v59
	v_add_f32_e32 v29, v33, v29
	v_div_scale_f32 v33, s[0:1], v32, v32, 1.0
	v_sub_f32_e32 v25, v13, v62
	v_add_f32_e32 v27, v34, v27
	v_rcp_f32_e32 v34, v33
	v_add_f32_e32 v25, v31, v25
	v_sub_f32_e32 v31, v5, v57
	v_add_f32_e32 v30, v30, v31
	v_sub_f32_e32 v31, v6, v56
	v_add_f32_e32 v28, v28, v31
	v_sub_f32_e32 v31, v7, v55
	v_add_f32_e32 v23, v23, v31
	v_fma_f32 v31, -v33, v34, 1.0
	v_fmac_f32_e32 v34, v31, v34
	v_div_scale_f32 v31, vcc, 1.0, v32, 1.0
	v_mul_f32_e32 v35, v31, v34
	v_fma_f32 v36, -v33, v35, v31
	v_fmac_f32_e32 v35, v36, v34
	v_fma_f32 v31, -v33, v35, v31
	v_div_fmas_f32 v31, v31, v34, v35
	v_div_fixup_f32 v31, v31, v32, 1.0
	v_add_co_u32_e32 v18, vcc, 0x7900000, v18
	s_movk_i32 s0, 0x3fef
	v_fma_f32 v32, v31, v24, -v12
	v_fma_f32 v33, v31, v25, -v13
	v_fma_f32 v34, v31, v26, -v14
	v_fma_f32 v35, v31, v27, -v15
	v_addc_co_u32_e32 v19, vcc, 0, v19, vcc
	v_cmp_lt_u32_e64 s[0:1], s0, v101
	v_fma_f32 v36, v31, v29, -v4
	v_fma_f32 v37, v31, v30, -v5
	v_fma_f32 v38, v31, v28, -v6
	v_fma_f32 v31, v31, v23, -v7
	v_cvt_pk_bf16_f32 v32, v32, v33
	v_cvt_pk_bf16_f32 v33, v34, v35
	v_cvt_pk_bf16_f32 v34, v36, v37
	v_cvt_pk_bf16_f32 v35, v38, v31
	global_store_dwordx4 v[18:19], v[32:35], off offset:3072
	s_and_saveexec_b64 s[14:15], s[0:1]
	s_cbranch_execz .LBB0_341
	v_add_u32_e32 v18, s7, v101
	v_add_u32_e32 v18, 0xffffc010, v18
	v_mov_b32_e32 v19, v97
	v_lshlrev_b64 v[18:19], 11, v[18:19]
	v_lshl_add_u64 v[18:19], v[88:89], 0, v[18:19]
	global_store_dwordx4 v[18:19], v[12:15], off
	global_store_dwordx4 v[18:19], v[4:7], off offset:16
.LBB0_341:
	s_or_b64 exec, exec, s[14:15]
	v_lshlrev_b32_e32 v14, 16, v9
	v_and_b32_e32 v15, 0xffff0000, v9
	v_add_u32_e32 v9, 2, v101
	v_min_i32_e32 v9, 7, v9
	v_lshlrev_b32_e32 v12, 16, v8
	v_add_u32_e32 v9, 1, v9
	v_and_b32_e32 v13, 0xffff0000, v8
	v_sub_f32_e32 v8, v12, v53
	v_cvt_f32_u32_e32 v9, v9
	v_lshlrev_b32_e32 v4, 16, v10
	v_and_b32_e32 v5, 0xffff0000, v10
	v_add_f32_e32 v10, v8, v24
	v_sub_f32_e32 v8, v13, v54
	v_lshlrev_b32_e32 v6, 16, v11
	v_and_b32_e32 v7, 0xffff0000, v11
	v_add_f32_e32 v11, v8, v25
	v_sub_f32_e32 v8, v14, v52
	v_add_f32_e32 v18, v8, v26
	v_sub_f32_e32 v8, v15, v51
	v_add_f32_e32 v19, v8, v27
	v_sub_f32_e32 v8, v4, v50
	v_div_scale_f32 v27, s[14:15], v9, v9, 1.0
	v_add_f32_e32 v24, v8, v29
	v_rcp_f32_e32 v29, v27
	v_sub_f32_e32 v8, v5, v49
	v_add_f32_e32 v25, v8, v30
	v_sub_f32_e32 v8, v6, v48
	v_add_f32_e32 v26, v8, v28
	v_sub_f32_e32 v8, v7, v47
	v_add_f32_e32 v23, v8, v23
	v_fma_f32 v8, -v27, v29, 1.0
	v_fmac_f32_e32 v29, v8, v29
	v_div_scale_f32 v8, vcc, 1.0, v9, 1.0
	v_mul_f32_e32 v28, v8, v29
	v_fma_f32 v30, -v27, v28, v8
	v_fmac_f32_e32 v28, v30, v29
	v_fma_f32 v8, -v27, v28, v8
	v_div_fmas_f32 v8, v8, v29, v28
	v_div_fixup_f32 v8, v8, v9, 1.0
	v_fma_f32 v9, v8, v10, -v12
	v_fma_f32 v27, v8, v11, -v13
	v_fma_f32 v29, v8, v18, -v14
	v_fma_f32 v30, v8, v19, -v15
	v_fma_f32 v31, v8, v24, -v4
	v_fma_f32 v32, v8, v25, -v5
	v_fma_f32 v33, v8, v26, -v6
	v_fma_f32 v8, v8, v23, -v7
	v_mov_b32_e32 v41, v97
	v_cvt_pk_bf16_f32 v28, v9, v27
	v_cvt_pk_bf16_f32 v29, v29, v30
	v_cvt_pk_bf16_f32 v30, v31, v32
	v_cvt_pk_bf16_f32 v31, v33, v8
	v_lshl_add_u64 v[8:9], v[16:17], 0, v[40:41]
	v_add_co_u32_e32 v16, vcc, 0x7901000, v8
	s_nop 1
	v_addc_co_u32_e32 v17, vcc, 0, v9, vcc
	global_store_dwordx4 v[16:17], v[28:31], off offset:1024
	s_and_saveexec_b64 s[14:15], s[0:1]
	s_cbranch_execz .LBB0_343
	v_add_u32_e32 v16, s7, v101
	v_add_u32_e32 v16, 0xffffc011, v16
	v_mov_b32_e32 v17, v97
	v_lshlrev_b64 v[16:17], 11, v[16:17]
	v_lshl_add_u64 v[16:17], v[88:89], 0, v[16:17]
	global_store_dwordx4 v[16:17], v[12:15], off
	global_store_dwordx4 v[16:17], v[4:7], off offset:16
.LBB0_343:
	s_or_b64 exec, exec, s[14:15]
	v_add_u32_e32 v16, 3, v101
	v_min_i32_e32 v17, 7, v16
	v_add_u32_e32 v17, 1, v17
	v_cvt_f32_u32_e32 v17, v17
	v_and_b32_e32 v7, 0xffff0000, v1
	v_lshlrev_b32_e32 v4, 16, v0
	v_sub_f32_e32 v13, v7, v44
	v_and_b32_e32 v5, 0xffff0000, v0
	v_sub_f32_e32 v12, v4, v46
	v_add_f32_e32 v13, v13, v19
	v_div_scale_f32 v19, s[0:1], v17, v17, 1.0
	v_add_f32_e32 v10, v12, v10
	v_sub_f32_e32 v12, v5, v20
	v_rcp_f32_e32 v20, v19
	v_lshlrev_b32_e32 v6, 16, v1
	v_lshlrev_b32_e32 v0, 16, v2
	v_and_b32_e32 v1, 0xffff0000, v2
	v_lshlrev_b32_e32 v2, 16, v3
	v_add_f32_e32 v11, v12, v11
	v_sub_f32_e32 v12, v6, v45
	v_and_b32_e32 v3, 0xffff0000, v3
	v_add_f32_e32 v12, v12, v18
	v_sub_f32_e32 v18, v2, v22
	v_fma_f32 v22, -v19, v20, 1.0
	v_sub_f32_e32 v21, v3, v21
	v_fmac_f32_e32 v20, v22, v20
	v_div_scale_f32 v22, vcc, 1.0, v17, 1.0
	v_sub_f32_e32 v14, v0, v43
	v_add_f32_e32 v21, v21, v23
	v_mul_f32_e32 v23, v22, v20
	v_add_f32_e32 v14, v14, v24
	v_fma_f32 v24, -v19, v23, v22
	v_fmac_f32_e32 v23, v24, v20
	v_fma_f32 v19, -v19, v23, v22
	v_div_fmas_f32 v19, v19, v20, v23
	v_add_co_u32_e32 v8, vcc, 0x7901000, v8
	s_movk_i32 s0, 0x3ff0
	s_nop 0
	v_addc_co_u32_e32 v9, vcc, 0, v9, vcc
	v_sub_f32_e32 v15, v1, v42
	v_div_fixup_f32 v17, v19, v17, 1.0
	v_cmp_lt_u32_e32 vcc, s0, v16
	v_add_f32_e32 v15, v15, v25
	v_add_f32_e32 v18, v18, v26
	v_fma_f32 v10, v17, v10, -v4
	v_fma_f32 v11, v17, v11, -v5
	v_fma_f32 v12, v17, v12, -v6
	v_fma_f32 v13, v17, v13, -v7
	s_and_b64 s[14:15], vcc, exec
	s_xor_b64 s[0:1], exec, -1
	v_fma_f32 v14, v17, v14, -v0
	v_fma_f32 v15, v17, v15, -v1
	v_fma_f32 v18, v17, v18, -v2
	v_fma_f32 v17, v17, v21, -v3
	v_cvt_pk_bf16_f32 v10, v10, v11
	v_cvt_pk_bf16_f32 v11, v12, v13
	v_cvt_pk_bf16_f32 v12, v14, v15
	v_cvt_pk_bf16_f32 v13, v18, v17
	global_store_dwordx4 v[8:9], v[10:13], off offset:3072

; __device__ __forceinline__ void unpack8(const u32x4 w, float* f) { f[0] = bf_lo(w.x); f[1] = bf_hi(w.x); f[2] = bf_lo(w.y); f[3] = bf_hi(w.y); f[4] = bf_lo(w.z); f[5] = bf_hi(w.z); f[6] = bf_lo(w.w); f[7] = bf_hi(w.w); }
; __device__ __forceinline__ u32x4 pack8(const float* f) { u32x4 w; w.x = cvt_pk_bf16(f[0], f[1]); w.y = cvt_pk_bf16(f[2], f[3]); w.z = cvt_pk_bf16(f[4], f[5]); w.w = cvt_pk_bf16(f[6], f[7]); return w; }
; template <int W>
; __device__ __forceinline__ void pool_task_prompt(const Params& p, int l, int b, int c, int g, int rg, int ch, long row0) {
;     ...
;     u32x4 raw[W + 3];
; #pragma unroll
;     for (int i = 0; i < W + 3; ++i) { const int tt = t0 - (W - 1) + i; raw[i] = (u32x4){0u, 0u, 0u, 0u};
;         if (tt >= 0) raw[i] = *(const u32x4*)(P + (size_t)((long)b * SEQ + tt) * INW + 768 + col); }
;     float a[4][8], cur[4][8];
; #pragma unroll
;     for (int k = 0; k < 8; ++k) a[0][k] = 0.f;
; #pragma unroll
;     for (int i = 0; i < W; ++i) { float x[8]; unpack8(raw[i], x);
; #pragma unroll
;         for (int k = 0; k < 8; ++k) { a[0][k] += x[k]; if (i == W - 1) cur[0][k] = x[k]; } }
; #pragma unroll
;     for (int r = 1; r < 4; ++r) { float xin[8], xout[8]; unpack8(raw[W - 1 + r], xin); unpack8(raw[r - 1], xout);
; #pragma unroll
;         for (int k = 0; k < 8; ++k) { a[r][k] = a[r - 1][k] + (xin[k] - xout[k]); cur[r][k] = xin[k]; } }
; #pragma unroll
;     for (int r = 0; r < 4; ++r) {
;         const int t = t0 + r;
;         const float inv = 1.0f / (float)((t + 1) < W ? (t + 1) : W);
;         float d[8];
; #pragma unroll
;         for (int k = 0; k < 8; ++k) d[k] = a[r][k] * inv - cur[r][k];
;         *(u32x4*)(AD + (size_t)(row0 + tl0 + r) * DM + 512 + col) = pack8(d);
;         if (t >= SEQ - 15) { float* pd = p.out + O_PP + (((size_t)l * 2 + b) * 15 + (t - (SEQ - 15))) * 512 + col;
;             *(f32x4*)pd = (f32x4){cur[r][0], cur[r][1], cur[r][2], cur[r][3]}; *(f32x4*)(pd + 4) = (f32x4){cur[r][4], cur[r][5], cur[r][6], cur[r][7]}; }
.LBB0_345:
	s_or_saveexec_b64 s[8:9], s[8:9]
	v_mov_b64_e32 v[8:9], v[78:79]
	s_xor_b64 exec, exec, s[8:9]
	s_cbranch_execz .LBB0_359
	v_mov_b32_e32 v0, 0
	v_cmp_ne_u32_e64 s[0:1], 0, v101
	v_lshlrev_b32_e32 v20, 1, v80
	v_mov_b32_e32 v4, 0
	v_mov_b32_e32 v5, 0
	v_mov_b32_e32 v6, 0
	v_mov_b32_e32 v7, 0
	s_and_saveexec_b64 s[16:17], s[0:1]
	s_cbranch_execz .LBB0_348
	v_add3_u32 v1, v100, s25, -3
	v_mov_b64_e32 v[2:3], s[86:87]
	v_mad_u64_u32 v[2:3], s[40:41], v1, s89, v[2:3]
	v_mov_b32_e32 v21, v97
	v_lshl_add_u64 v[2:3], v[2:3], 0, v[20:21]
	v_add_co_u32_e32 v2, vcc, 0xfb00000, v2
	s_nop 1
	v_addc_co_u32_e32 v3, vcc, 0, v3, vcc
	global_load_dwordx4 v[4:7], v[2:3], off offset:1536
.LBB0_348:
	s_or_b64 exec, exec, s[16:17]
	v_mov_b32_e32 v1, 0
	v_mov_b32_e32 v2, 0
	v_mov_b32_e32 v3, 0
	s_and_saveexec_b64 s[16:17], s[0:1]
	s_cbranch_execz .LBB0_350
	v_add3_u32 v2, v100, s25, -2
	v_mov_b64_e32 v[0:1], s[86:87]
	v_mad_u64_u32 v[0:1], s[40:41], v2, s89, v[0:1]
	v_mov_b32_e32 v21, v97
	v_lshl_add_u64 v[0:1], v[0:1], 0, v[20:21]
	v_add_co_u32_e32 v0, vcc, 0xfb00000, v0
	s_nop 1
	v_addc_co_u32_e32 v1, vcc, 0, v1, vcc
	global_load_dwordx4 v[0:3], v[0:1], off offset:1536
.LBB0_350:
	s_or_b64 exec, exec, s[16:17]
	v_mov_b32_e32 v8, 0
	v_mov_b32_e32 v9, 0
	v_mov_b32_e32 v10, 0
	v_mov_b32_e32 v11, 0
	s_and_saveexec_b64 s[16:17], s[0:1]
	s_cbranch_execz .LBB0_352
	v_add3_u32 v10, v100, s25, -1
	v_mov_b64_e32 v[8:9], s[86:87]
	v_mad_u64_u32 v[8:9], s[0:1], v10, s89, v[8:9]
	v_mov_b32_e32 v21, v97
	v_lshl_add_u64 v[8:9], v[8:9], 0, v[20:21]
	v_add_co_u32_e32 v8, vcc, 0xfb00000, v8
	s_nop 1
	v_addc_co_u32_e32 v9, vcc, 0, v9, vcc
	global_load_dwordx4 v[8:11], v[8:9], off offset:1536
.LBB0_352:
	s_or_b64 exec, exec, s[16:17]
	v_lshl_add_u64 v[12:13], s[86:87], 0, v[96:97]
	v_mov_b32_e32 v21, v97
	v_lshl_add_u64 v[16:17], v[12:13], 0, v[20:21]
	v_add_co_u32_e32 v12, vcc, 0xfb00000, v16
	s_waitcnt vmcnt(0) lgkmcnt(0)
	v_lshlrev_b32_e32 v40, 16, v0
	v_addc_co_u32_e32 v13, vcc, 0, v17, vcc
	global_load_dwordx4 v[12:15], v[12:13], off offset:1536
	v_and_b32_e32 v41, 0xffff0000, v0
	v_add_co_u32_e32 v0, vcc, 0xfb02000, v16
	v_lshlrev_b32_e32 v39, 16, v1
	v_and_b32_e32 v38, 0xffff0000, v1
	v_addc_co_u32_e32 v1, vcc, 0, v17, vcc
	v_lshlrev_b32_e32 v37, 16, v2
	v_and_b32_e32 v36, 0xffff0000, v2
	v_add_co_u32_e32 v2, vcc, 0xfb03000, v16
	v_lshlrev_b32_e32 v35, 16, v3
	v_and_b32_e32 v34, 0xffff0000, v3
	v_addc_co_u32_e32 v3, vcc, 0, v17, vcc
	v_lshlrev_b32_e32 v32, 16, v8
	v_lshlrev_b32_e32 v31, 16, v9
	v_and_b32_e32 v30, 0xffff0000, v9
	v_lshlrev_b32_e32 v29, 16, v10
	v_and_b32_e32 v28, 0xffff0000, v10
	v_lshlrev_b32_e32 v27, 16, v11
	v_and_b32_e32 v26, 0xffff0000, v11
	v_and_b32_e32 v33, 0xffff0000, v8
	global_load_dwordx4 v[8:11], v[0:1], off
	v_add_co_u32_e32 v0, vcc, 0xfb05000, v16
	v_lshlrev_b32_e32 v48, 16, v4
	s_nop 0
	v_addc_co_u32_e32 v1, vcc, 0, v17, vcc
	v_lshlrev_b32_e32 v47, 16, v5
	v_and_b32_e32 v46, 0xffff0000, v5
	v_lshlrev_b32_e32 v45, 16, v6
	v_and_b32_e32 v44, 0xffff0000, v6
	v_lshlrev_b32_e32 v43, 16, v7
	v_and_b32_e32 v42, 0xffff0000, v7
	v_and_b32_e32 v49, 0xffff0000, v4
	global_load_dwordx4 v[4:7], v[2:3], off offset:2560
	s_nop 0
	global_load_dwordx4 v[0:3], v[0:1], off offset:1024
	v_add_f32_e32 v16, 0, v48
	v_add_f32_e32 v18, 0, v47
	v_add_f32_e32 v16, v16, v40
	v_add_f32_e32 v18, v18, v39
	v_add_f32_e32 v50, v16, v32
	v_add_f32_e32 v53, v18, v31
	v_add_f32_e32 v17, 0, v49
	v_add_f32_e32 v22, 0, v45
	v_add_f32_e32 v17, v17, v41
	v_add_f32_e32 v22, v22, v37
	v_add_f32_e32 v51, v17, v33
	v_add_f32_e32 v22, v22, v29
	v_add_f32_e32 v19, 0, v46
	v_add_f32_e32 v23, 0, v44
	v_add_f32_e32 v19, v19, v38
	v_add_f32_e32 v23, v23, v36
	v_add_f32_e32 v24, 0, v43
	v_add_f32_e32 v54, v19, v30
	v_add_f32_e32 v23, v23, v28
	v_add_f32_e32 v25, 0, v42
	v_add_f32_e32 v24, v24, v35
	v_add_f32_e32 v25, v25, v34
	v_add_f32_e32 v24, v24, v27
	v_add_f32_e32 v25, v25, v26
	v_mov_b32_e32 v93, v97
	s_waitcnt vmcnt(0) lgkmcnt(0)
	v_lshlrev_b32_e32 v16, 16, v12
	v_lshlrev_b32_e32 v18, 16, v13
	v_add_f32_e32 v52, v50, v16
	v_add_f32_e32 v50, v53, v18
	v_min_i32_e32 v53, 3, v101
	v_add_u32_e32 v53, 1, v53
	v_cvt_f32_u32_e32 v58, v53
	v_and_b32_e32 v17, 0xffff0000, v12
	v_lshlrev_b32_e32 v12, 16, v14
	v_add_f32_e32 v56, v22, v12
	v_div_scale_f32 v22, s[0:1], v58, v58, 1.0
	v_rcp_f32_e32 v59, v22
	v_and_b32_e32 v19, 0xffff0000, v13
	v_and_b32_e32 v13, 0xffff0000, v14
	v_add_f32_e32 v55, v23, v13
	v_fma_f32 v23, -v22, v59, 1.0
	v_lshlrev_b32_e32 v14, 16, v15
	v_fmac_f32_e32 v59, v23, v59
	v_div_scale_f32 v23, vcc, 1.0, v58, 1.0
	v_and_b32_e32 v15, 0xffff0000, v15
	v_add_f32_e32 v57, v54, v19
	v_add_f32_e32 v54, v24, v14
	v_mul_f32_e32 v24, v23, v59
	v_add_f32_e32 v53, v25, v15
	v_fma_f32 v25, -v22, v24, v23
	v_fmac_f32_e32 v24, v25, v59
	v_fma_f32 v22, -v22, v24, v23
	v_div_fmas_f32 v22, v22, v59, v24
	v_add_f32_e32 v51, v51, v17
	v_div_fixup_f32 v22, v22, v58, 1.0
	v_fma_f32 v23, v22, v52, -v16
	v_fma_f32 v24, v22, v51, -v17
	v_fma_f32 v25, v22, v50, -v18
	v_fma_f32 v59, v22, v57, -v19
	v_fma_f32 v60, v22, v56, -v12
	v_fma_f32 v61, v22, v55, -v13
	v_fma_f32 v62, v22, v54, -v14
	v_fma_f32 v22, v22, v53, -v15
	v_cvt_pk_bf16_f32 v58, v23, v24
	v_cvt_pk_bf16_f32 v59, v25, v59
	v_cvt_pk_bf16_f32 v60, v60, v61
	v_cvt_pk_bf16_f32 v61, v62, v22
	v_lshl_add_u64 v[22:23], s[86:87], 0, v[92:93]
	v_lshl_add_u64 v[24:25], v[22:23], 0, v[20:21]
	v_add_co_u32_e32 v62, vcc, 0x7900000, v24
	s_movk_i32 s0, 0x3ff0
	s_nop 0
	v_addc_co_u32_e32 v63, vcc, 0, v25, vcc
	v_cmp_lt_u32_e32 vcc, s0, v101
	global_store_dwordx4 v[62:63], v[58:61], off offset:1024
	s_and_saveexec_b64 s[0:1], vcc
	s_cbranch_execz .LBB0_354
	v_add_u32_e32 v21, s7, v101
	v_add_u32_e32 v58, 0xffffc00f, v21
	v_mov_b32_e32 v59, v97
	v_lshlrev_b64 v[58:59], 11, v[58:59]
	v_lshl_add_u64 v[58:59], v[90:91], 0, v[58:59]
	global_store_dwordx4 v[58:59], v[16:19], off
	global_store_dwordx4 v[58:59], v[12:15], off offset:16
; __device__ __forceinline__ void unpack8(const u32x4 w, float* f) { f[0] = bf_lo(w.x); f[1] = bf_hi(w.x); f[2] = bf_lo(w.y); f[3] = bf_hi(w.y); f[4] = bf_lo(w.z); f[5] = bf_hi(w.z); f[6] = bf_lo(w.w); f[7] = bf_hi(w.w); }
; __device__ __forceinline__ u32x4 pack8(const float* f) { u32x4 w; w.x = cvt_pk_bf16(f[0], f[1]); w.y = cvt_pk_bf16(f[2], f[3]); w.z = cvt_pk_bf16(f[4], f[5]); w.w = cvt_pk_bf16(f[6], f[7]); return w; }
; template <int W>
; __device__ __forceinline__ void pool_task_prompt(const Params& p, int l, int b, int c, int g, int rg, int ch, long row0) {
;     ...
;     for (int r = 1; r < 4; ++r) { float xin[8], xout[8]; unpack8(raw[W - 1 + r], xin); unpack8(raw[r - 1], xout);
; #pragma unroll
;         for (int k = 0; k < 8; ++k) { a[r][k] = a[r - 1][k] + (xin[k] - xout[k]); cur[r][k] = xin[k]; } }
; #pragma unroll
;     for (int r = 0; r < 4; ++r) {
;         const int t = t0 + r;
;         const float inv = 1.0f / (float)((t + 1) < W ? (t + 1) : W);
;         float d[8];
; #pragma unroll
;         for (int k = 0; k < 8; ++k) d[k] = a[r][k] * inv - cur[r][k];
;         *(u32x4*)(AD + (size_t)(row0 + tl0 + r) * DM + 512 + col) = pack8(d);
;         if (t >= SEQ - 15) { float* pd = p.out + O_PP + (((size_t)l * 2 + b) * 15 + (t - (SEQ - 15))) * 512 + col;
;             *(f32x4*)pd = (f32x4){cur[r][0], cur[r][1], cur[r][2], cur[r][3]}; *(f32x4*)(pd + 4) = (f32x4){cur[r][4], cur[r][5], cur[r][6], cur[r][7]}; }
.LBB0_354:
	s_or_b64 exec, exec, s[0:1]
	s_nop 0
	v_lshlrev_b32_e32 v12, 16, v8
	v_and_b32_e32 v13, 0xffff0000, v8
	v_lshlrev_b32_e32 v8, 16, v10
	v_sub_f32_e32 v21, v8, v45
	v_add_u32_e32 v45, 1, v101
	v_min_i32_e32 v45, 3, v45
	v_add_u32_e32 v45, 1, v45
	v_cvt_f32_u32_e32 v45, v45
	v_and_b32_e32 v15, 0xffff0000, v9
	v_lshlrev_b32_e32 v14, 16, v9
	v_sub_f32_e32 v19, v15, v46
	v_div_scale_f32 v46, s[0:1], v45, v45, 1.0
	v_sub_f32_e32 v18, v14, v47
	v_rcp_f32_e32 v47, v46
	v_sub_f32_e32 v16, v12, v48
	v_sub_f32_e32 v17, v13, v49
	v_add_f32_e32 v18, v50, v18
	v_fma_f32 v48, -v46, v47, 1.0
	v_fmac_f32_e32 v47, v48, v47
	v_div_scale_f32 v48, vcc, 1.0, v45, 1.0
	v_mul_f32_e32 v49, v48, v47
	v_fma_f32 v50, -v46, v49, v48
	v_fmac_f32_e32 v49, v50, v47
	v_fma_f32 v46, -v46, v49, v48
	v_and_b32_e32 v9, 0xffff0000, v10
	v_lshlrev_b32_e32 v10, 16, v11
	v_and_b32_e32 v11, 0xffff0000, v11
	v_div_fmas_f32 v46, v46, v47, v49
	v_add_f32_e32 v16, v52, v16
	v_add_f32_e32 v17, v51, v17
	v_add_f32_e32 v19, v57, v19
	v_sub_f32_e32 v44, v9, v44
	v_sub_f32_e32 v43, v10, v43
	v_sub_f32_e32 v42, v11, v42
	v_div_fixup_f32 v45, v46, v45, 1.0
	v_add_co_u32_e32 v24, vcc, 0x7900000, v24
	s_movk_i32 s0, 0x3fef
	v_add_f32_e32 v21, v56, v21
	v_add_f32_e32 v44, v55, v44
	v_add_f32_e32 v43, v54, v43
	v_add_f32_e32 v42, v53, v42
	v_fma_f32 v46, v45, v16, -v12
	v_fma_f32 v47, v45, v17, -v13
	v_fma_f32 v48, v45, v18, -v14
	v_fma_f32 v49, v45, v19, -v15
	v_addc_co_u32_e32 v25, vcc, 0, v25, vcc
	v_cmp_lt_u32_e64 s[0:1], s0, v101
	v_fma_f32 v50, v45, v21, -v8
	v_fma_f32 v51, v45, v44, -v9
	v_fma_f32 v52, v45, v43, -v10
	v_fma_f32 v45, v45, v42, -v11
	v_cvt_pk_bf16_f32 v46, v46, v47
	v_cvt_pk_bf16_f32 v47, v48, v49
	v_cvt_pk_bf16_f32 v48, v50, v51
	v_cvt_pk_bf16_f32 v49, v52, v45
	global_store_dwordx4 v[24:25], v[46:49], off offset:3072
	s_and_saveexec_b64 s[16:17], s[0:1]
	s_cbranch_execz .LBB0_356
	v_add_u32_e32 v24, s7, v101
	v_add_u32_e32 v24, 0xffffc010, v24
	v_mov_b32_e32 v25, v97
	v_lshlrev_b64 v[24:25], 11, v[24:25]
	v_lshl_add_u64 v[24:25], v[90:91], 0, v[24:25]
	global_store_dwordx4 v[24:25], v[12:15], off
	global_store_dwordx4 v[24:25], v[8:11], off offset:16
.LBB0_356:
	s_or_b64 exec, exec, s[16:17]
	v_add_u32_e32 v13, 2, v101
	v_lshlrev_b32_e32 v8, 16, v4
	v_min_i32_e32 v13, 3, v13
	v_and_b32_e32 v9, 0xffff0000, v4
	v_sub_f32_e32 v12, v8, v40
	v_add_u32_e32 v13, 1, v13
	v_lshlrev_b32_e32 v10, 16, v5
	v_add_f32_e32 v14, v12, v16
	v_sub_f32_e32 v12, v9, v41
	v_cvt_f32_u32_e32 v13, v13
	v_and_b32_e32 v11, 0xffff0000, v5
	v_add_f32_e32 v15, v12, v17
	v_sub_f32_e32 v12, v10, v39
	v_lshlrev_b32_e32 v4, 16, v6
	v_add_f32_e32 v16, v12, v18
	v_sub_f32_e32 v12, v11, v38
	v_and_b32_e32 v5, 0xffff0000, v6
	v_add_f32_e32 v17, v12, v19
	v_sub_f32_e32 v12, v4, v37
	v_lshlrev_b32_e32 v6, 16, v7
	v_add_f32_e32 v18, v12, v21
	v_sub_f32_e32 v12, v5, v36
	v_div_scale_f32 v21, s[16:17], v13, v13, 1.0
	v_add_f32_e32 v19, v12, v44
	v_sub_f32_e32 v12, v6, v35
	v_rcp_f32_e32 v35, v21
	v_and_b32_e32 v7, 0xffff0000, v7
	v_add_f32_e32 v24, v12, v43
	v_sub_f32_e32 v12, v7, v34
	v_add_f32_e32 v25, v12, v42
	v_fma_f32 v12, -v21, v35, 1.0
	v_fmac_f32_e32 v35, v12, v35
	v_div_scale_f32 v12, vcc, 1.0, v13, 1.0
	v_mul_f32_e32 v34, v12, v35
	v_fma_f32 v36, -v21, v34, v12
	v_fmac_f32_e32 v34, v36, v35
	v_fma_f32 v12, -v21, v34, v12
	v_div_fmas_f32 v12, v12, v35, v34
	v_div_fixup_f32 v12, v12, v13, 1.0
	v_fma_f32 v21, v12, v15, -v9
	v_fma_f32 v13, v12, v14, -v8
	v_fma_f32 v35, v12, v16, -v10
	v_fma_f32 v36, v12, v17, -v11
	v_fma_f32 v37, v12, v18, -v4
	v_fma_f32 v38, v12, v19, -v5
	v_fma_f32 v39, v12, v24, -v6
	v_fma_f32 v12, v12, v25, -v7
	v_cvt_pk_bf16_f32 v34, v13, v21
	v_mov_b32_e32 v21, v97
	v_cvt_pk_bf16_f32 v35, v35, v36
	v_cvt_pk_bf16_f32 v36, v37, v38
	v_cvt_pk_bf16_f32 v37, v39, v12
	v_lshl_add_u64 v[12:13], v[22:23], 0, v[20:21]
	v_add_co_u32_e32 v20, vcc, 0x7901000, v12
	s_nop 1
	v_addc_co_u32_e32 v21, vcc, 0, v13, vcc
	global_store_dwordx4 v[20:21], v[34:37], off offset:1024
	s_and_saveexec_b64 s[16:17], s[0:1]
	s_cbranch_execz .LBB0_358
	v_add_u32_e32 v20, s7, v101
	v_add_u32_e32 v20, 0xffffc011, v20
	v_mov_b32_e32 v21, v97
	v_lshlrev_b64 v[20:21], 11, v[20:21]
	v_lshl_add_u64 v[20:21], v[90:91], 0, v[20:21]
	global_store_dwordx4 v[20:21], v[8:11], off
	global_store_dwordx4 v[20:21], v[4:7], off offset:16
.LBB0_358:
	s_or_b64 exec, exec, s[16:17]
	s_nop 0
	v_lshlrev_b32_e32 v4, 16, v0
	v_and_b32_e32 v5, 0xffff0000, v0
	v_lshlrev_b32_e32 v6, 16, v1
	v_and_b32_e32 v7, 0xffff0000, v1
	v_lshlrev_b32_e32 v0, 16, v2
	v_and_b32_e32 v1, 0xffff0000, v2
	v_lshlrev_b32_e32 v2, 16, v3
	v_and_b32_e32 v3, 0xffff0000, v3
	v_sub_f32_e32 v8, v4, v32
	v_sub_f32_e32 v9, v5, v33
	v_sub_f32_e32 v10, v6, v31
	v_sub_f32_e32 v11, v7, v30
	v_add_f32_e32 v8, v8, v14
	v_add_f32_e32 v9, v9, v15
	v_add_f32_e32 v10, v10, v16
	v_add_f32_e32 v11, v11, v17
	v_sub_f32_e32 v14, v0, v29
	v_sub_f32_e32 v15, v1, v28
	v_sub_f32_e32 v16, v2, v27
	v_sub_f32_e32 v17, v3, v26
	v_add_f32_e32 v14, v14, v18
	v_add_f32_e32 v15, v15, v19
	v_add_f32_e32 v16, v16, v24
	v_add_f32_e32 v17, v17, v25
	s_mov_b32 s0, 0x3e800000
	v_add_co_u32_e32 v12, vcc, 0x7901000, v12
	v_add_u32_e32 v18, 3, v101
	v_fma_f32 v8, v8, s0, -v4
	v_fma_f32 v9, v9, s0, -v5
	v_fma_f32 v10, v10, s0, -v6
	v_fma_f32 v11, v11, s0, -v7
	v_fma_f32 v14, v14, s0, -v0
	v_fma_f32 v15, v15, s0, -v1
	v_fma_f32 v16, v16, s0, -v2
	v_fma_f32 v17, v17, s0, -v3
	v_addc_co_u32_e32 v13, vcc, 0, v13, vcc
	s_movk_i32 s0, 0x3ff0
	v_cmp_lt_u32_e32 vcc, s0, v18
	v_cvt_pk_bf16_f32 v8, v8, v9
	v_cvt_pk_bf16_f32 v9, v10, v11
	s_andn2_b64 s[0:1], s[14:15], exec
	s_and_b64 s[14:15], vcc, exec
	v_cvt_pk_bf16_f32 v10, v14, v15
	v_cvt_pk_bf16_f32 v11, v16, v17
	global_store_dwordx4 v[12:13], v[8:11], off offset:3072
	s_or_b64 s[14:15], s[0:1], s[14:15]
	s_nop 0
	v_mov_b64_e32 v[8:9], v[80:81]

; template <int W>
; __device__ __forceinline__ void pool_task_prompt(const Params& p, int l, int b, int c, int g, int rg, int ch, long row0) {
;     ...
;     u32x4 raw[W + 3];
; #pragma unroll
;     for (int i = 0; i < W + 3; ++i) { const int tt = t0 - (W - 1) + i; raw[i] = (u32x4){0u, 0u, 0u, 0u};
;         if (tt >= 0) raw[i] = *(const u32x4*)(P + (size_t)((long)b * SEQ + tt) * INW + 768 + col); }
.LBB0_361:
	v_cmp_lt_u32_e32 vcc, 14, v101
	v_mov_b32_e32 v0, 0
	v_mov_b32_e32 v4, 0
	v_mov_b32_e32 v5, 0
	v_mov_b32_e32 v6, 0
	v_mov_b32_e32 v7, 0
	s_and_saveexec_b64 s[0:1], vcc
	s_cbranch_execz .LBB0_363
	v_add3_u32 v1, v100, s25, -15
	v_mov_b64_e32 v[2:3], s[86:87]
	v_mad_u64_u32 v[2:3], s[12:13], v1, s89, v[2:3]
	v_lshl_add_u64 v[2:3], v[82:83], 1, v[2:3]
	v_add_co_u32_e32 v2, vcc, 0xfb00000, v2
	s_nop 1
	v_addc_co_u32_e32 v3, vcc, 0, v3, vcc
	global_load_dwordx4 v[4:7], v[2:3], off offset:1536
.LBB0_363:
	s_or_b64 exec, exec, s[0:1]
	v_cmp_lt_u32_e32 vcc, 13, v101
	v_mov_b32_e32 v1, 0
	v_mov_b32_e32 v2, 0
	v_mov_b32_e32 v3, 0
	s_and_saveexec_b64 s[0:1], vcc
	s_cbranch_execz .LBB0_365
	v_add3_u32 v2, v100, s25, -14
	v_mov_b64_e32 v[0:1], s[86:87]
	v_mad_u64_u32 v[0:1], s[12:13], v2, s89, v[0:1]
	v_lshl_add_u64 v[0:1], v[82:83], 1, v[0:1]
	v_add_co_u32_e32 v0, vcc, 0xfb00000, v0
	s_nop 1
	v_addc_co_u32_e32 v1, vcc, 0, v1, vcc
	global_load_dwordx4 v[0:3], v[0:1], off offset:1536
.LBB0_365:
	s_or_b64 exec, exec, s[0:1]
	v_cmp_lt_u32_e32 vcc, 12, v101
	v_mov_b32_e32 v8, 0
	v_mov_b32_e32 v12, 0
	v_mov_b32_e32 v13, 0
	v_mov_b32_e32 v14, 0
	v_mov_b32_e32 v15, 0
	s_and_saveexec_b64 s[0:1], vcc
	s_cbranch_execz .LBB0_367
	v_add3_u32 v9, v100, s25, -13
	v_mov_b64_e32 v[10:11], s[86:87]
	v_mad_u64_u32 v[10:11], s[12:13], v9, s89, v[10:11]
	v_lshl_add_u64 v[10:11], v[82:83], 1, v[10:11]
	v_add_co_u32_e32 v10, vcc, 0xfb00000, v10
	s_nop 1
	v_addc_co_u32_e32 v11, vcc, 0, v11, vcc
	global_load_dwordx4 v[12:15], v[10:11], off offset:1536
.LBB0_367:
	s_or_b64 exec, exec, s[0:1]
	v_cmp_lt_u32_e32 vcc, 11, v101
	v_mov_b32_e32 v9, 0
	v_mov_b32_e32 v10, 0
	v_mov_b32_e32 v11, 0
	s_and_saveexec_b64 s[0:1], vcc
	s_cbranch_execz .LBB0_369
	v_add3_u32 v10, v100, s25, -12
	v_mov_b64_e32 v[8:9], s[86:87]
	v_mad_u64_u32 v[8:9], s[12:13], v10, s89, v[8:9]
	v_lshl_add_u64 v[8:9], v[82:83], 1, v[8:9]
	v_add_co_u32_e32 v8, vcc, 0xfb00000, v8
	s_nop 1
	v_addc_co_u32_e32 v9, vcc, 0, v9, vcc
	global_load_dwordx4 v[8:11], v[8:9], off offset:1536
.LBB0_369:
	s_or_b64 exec, exec, s[0:1]
	v_cmp_lt_u32_e32 vcc, 10, v101
	v_mov_b32_e32 v20, 0
	v_mov_b32_e32 v24, 0
	v_mov_b32_e32 v25, 0
	v_mov_b32_e32 v26, 0
	v_mov_b32_e32 v27, 0
	s_and_saveexec_b64 s[0:1], vcc
	s_cbranch_execz .LBB0_371
	v_add3_u32 v18, v100, s25, -11
	v_mov_b64_e32 v[16:17], s[86:87]
	v_mad_u64_u32 v[16:17], s[12:13], v18, s89, v[16:17]
	v_lshl_add_u64 v[16:17], v[82:83], 1, v[16:17]
	v_add_co_u32_e32 v16, vcc, 0xfb00000, v16
	s_nop 1
	v_addc_co_u32_e32 v17, vcc, 0, v17, vcc
	global_load_dwordx4 v[24:27], v[16:17], off offset:1536
.LBB0_371:
	s_or_b64 exec, exec, s[0:1]
	v_cmp_lt_u32_e32 vcc, 9, v101
	v_mov_b32_e32 v21, 0
	v_mov_b32_e32 v22, 0
	v_mov_b32_e32 v23, 0
	s_and_saveexec_b64 s[0:1], vcc
	s_cbranch_execz .LBB0_373
	v_add3_u32 v18, v100, s25, -10
	v_mov_b64_e32 v[16:17], s[86:87]
	v_mad_u64_u32 v[16:17], s[12:13], v18, s89, v[16:17]
	v_lshl_add_u64 v[16:17], v[82:83], 1, v[16:17]
	v_add_co_u32_e32 v16, vcc, 0xfb00000, v16
	s_nop 1
	v_addc_co_u32_e32 v17, vcc, 0, v17, vcc
	global_load_dwordx4 v[20:23], v[16:17], off offset:1536
.LBB0_373:
	s_or_b64 exec, exec, s[0:1]
	v_cmp_lt_u32_e32 vcc, 8, v101
	v_mov_b32_e32 v28, 0
	v_mov_b32_e32 v32, 0
	v_mov_b32_e32 v33, 0
	v_mov_b32_e32 v34, 0
	v_mov_b32_e32 v35, 0
	s_and_saveexec_b64 s[0:1], vcc
	s_cbranch_execz .LBB0_375
	v_add3_u32 v18, v100, s25, -9
	v_mov_b64_e32 v[16:17], s[86:87]
	v_mad_u64_u32 v[16:17], s[12:13], v18, s89, v[16:17]
	v_lshl_add_u64 v[16:17], v[82:83], 1, v[16:17]
	v_add_co_u32_e32 v16, vcc, 0xfb00000, v16
	s_nop 1
	v_addc_co_u32_e32 v17, vcc, 0, v17, vcc
	global_load_dwordx4 v[32:35], v[16:17], off offset:1536
.LBB0_375:
	s_or_b64 exec, exec, s[0:1]
	v_cmp_lt_u32_e32 vcc, 7, v101
	v_mov_b32_e32 v29, 0
	v_mov_b32_e32 v30, 0
	v_mov_b32_e32 v31, 0
	s_and_saveexec_b64 s[0:1], vcc
	s_cbranch_execz .LBB0_377
	v_add3_u32 v18, v100, s25, -8
	v_mov_b64_e32 v[16:17], s[86:87]
	v_mad_u64_u32 v[16:17], s[12:13], v18, s89, v[16:17]
	v_lshl_add_u64 v[16:17], v[82:83], 1, v[16:17]
	v_add_co_u32_e32 v16, vcc, 0xfb00000, v16
	s_nop 1
	v_addc_co_u32_e32 v17, vcc, 0, v17, vcc
	global_load_dwordx4 v[28:31], v[16:17], off offset:1536
.LBB0_377:
	s_or_b64 exec, exec, s[0:1]
	v_cmp_lt_u32_e32 vcc, 6, v101
	v_mov_b32_e32 v40, 0
	v_mov_b32_e32 v44, 0
	v_mov_b32_e32 v45, 0
	v_mov_b32_e32 v46, 0
	v_mov_b32_e32 v47, 0
	s_and_saveexec_b64 s[0:1], vcc
	s_cbranch_execz .LBB0_379
	v_add3_u32 v18, v100, s25, -7
	v_mov_b64_e32 v[16:17], s[86:87]
	v_mad_u64_u32 v[16:17], s[12:13], v18, s89, v[16:17]
	v_lshl_add_u64 v[16:17], v[82:83], 1, v[16:17]
	v_add_co_u32_e32 v16, vcc, 0xfb00000, v16
	s_nop 1
	v_addc_co_u32_e32 v17, vcc, 0, v17, vcc
	global_load_dwordx4 v[44:47], v[16:17], off offset:1536
.LBB0_379:
	s_or_b64 exec, exec, s[0:1]
	v_cmp_lt_u32_e32 vcc, 5, v101
	v_mov_b32_e32 v41, 0
	v_mov_b32_e32 v42, 0
	v_mov_b32_e32 v43, 0
	s_and_saveexec_b64 s[0:1], vcc
	s_cbranch_execz .LBB0_381
	v_add3_u32 v18, v100, s25, -6
	v_mov_b64_e32 v[16:17], s[86:87]
	v_mad_u64_u32 v[16:17], s[12:13], v18, s89, v[16:17]
	v_lshl_add_u64 v[16:17], v[82:83], 1, v[16:17]
	v_add_co_u32_e32 v16, vcc, 0xfb00000, v16
	s_nop 1
	v_addc_co_u32_e32 v17, vcc, 0, v17, vcc
	global_load_dwordx4 v[40:43], v[16:17], off offset:1536
.LBB0_381:
	s_or_b64 exec, exec, s[0:1]
	v_cmp_lt_u32_e32 vcc, 4, v101
	v_mov_b32_e32 v48, 0
	v_mov_b32_e32 v52, 0
	v_mov_b32_e32 v53, 0
	v_mov_b32_e32 v54, 0
	v_mov_b32_e32 v55, 0
	s_and_saveexec_b64 s[0:1], vcc
	s_cbranch_execz .LBB0_383
	v_add3_u32 v18, v100, s25, -5
	v_mov_b64_e32 v[16:17], s[86:87]
	v_mad_u64_u32 v[16:17], s[12:13], v18, s89, v[16:17]
	v_lshl_add_u64 v[16:17], v[82:83], 1, v[16:17]
	v_add_co_u32_e32 v16, vcc, 0xfb00000, v16
	s_nop 1
	v_addc_co_u32_e32 v17, vcc, 0, v17, vcc
	global_load_dwordx4 v[52:55], v[16:17], off offset:1536
; __device__ __forceinline__ void unpack8(const u32x4 w, float* f) { f[0] = bf_lo(w.x); f[1] = bf_hi(w.x); f[2] = bf_lo(w.y); f[3] = bf_hi(w.y); f[4] = bf_lo(w.z); f[5] = bf_hi(w.z); f[6] = bf_lo(w.w); f[7] = bf_hi(w.w); }
; template <int W>
; __device__ __forceinline__ void pool_task_prompt(const Params& p, int l, int b, int c, int g, int rg, int ch, long row0) {
;     ...
;     for (int i = 0; i < W + 3; ++i) { const int tt = t0 - (W - 1) + i; raw[i] = (u32x4){0u, 0u, 0u, 0u};
;         if (tt >= 0) raw[i] = *(const u32x4*)(P + (size_t)((long)b * SEQ + tt) * INW + 768 + col); }
;     float a[4][8], cur[4][8];
; #pragma unroll
;     for (int k = 0; k < 8; ++k) a[0][k] = 0.f;
; #pragma unroll
;     for (int i = 0; i < W; ++i) { float x[8]; unpack8(raw[i], x);
; #pragma unroll
;         for (int k = 0; k < 8; ++k) { a[0][k] += x[k]; if (i == W - 1) cur[0][k] = x[k]; } }
; #pragma unroll
;     for (int r = 1; r < 4; ++r) { float xin[8], xout[8]; unpack8(raw[W - 1 + r], xin); unpack8(raw[r - 1], xout);
; #pragma unroll
;         for (int k = 0; k < 8; ++k) { a[r][k] = a[r - 1][k] + (xin[k] - xout[k]); cur[r][k] = xin[k]; } }
.LBB0_383:
	s_or_b64 exec, exec, s[0:1]
	v_cmp_ne_u32_e64 s[0:1], 0, v101
	v_mov_b32_e32 v49, 0
	v_mov_b32_e32 v50, 0
	v_mov_b32_e32 v51, 0
	s_and_saveexec_b64 s[12:13], s[0:1]
	s_cbranch_execz .LBB0_385
	v_add3_u32 v18, v100, s25, -4
	v_mov_b64_e32 v[16:17], s[86:87]
	v_mad_u64_u32 v[16:17], s[14:15], v18, s89, v[16:17]
	v_lshl_add_u64 v[16:17], v[82:83], 1, v[16:17]
	v_add_co_u32_e32 v16, vcc, 0xfb00000, v16
	s_nop 1
	v_addc_co_u32_e32 v17, vcc, 0, v17, vcc
	global_load_dwordx4 v[48:51], v[16:17], off offset:1536
.LBB0_385:
	s_or_b64 exec, exec, s[12:13]
	v_mov_b32_e32 v60, 0
	v_mov_b32_e32 v64, 0
	v_mov_b32_e32 v65, 0
	v_mov_b32_e32 v66, 0
	v_mov_b32_e32 v67, 0
	s_and_saveexec_b64 s[12:13], s[0:1]
	s_cbranch_execz .LBB0_387
	v_add3_u32 v18, v100, s25, -3
	v_mov_b64_e32 v[16:17], s[86:87]
	v_mad_u64_u32 v[16:17], s[14:15], v18, s89, v[16:17]
	v_lshl_add_u64 v[16:17], v[82:83], 1, v[16:17]
	v_add_co_u32_e32 v16, vcc, 0xfb00000, v16
	s_nop 1
	v_addc_co_u32_e32 v17, vcc, 0, v17, vcc
	global_load_dwordx4 v[64:67], v[16:17], off offset:1536
.LBB0_387:
	s_or_b64 exec, exec, s[12:13]
	v_mov_b32_e32 v61, 0
	v_mov_b32_e32 v62, 0
	v_mov_b32_e32 v63, 0
	s_and_saveexec_b64 s[12:13], s[0:1]
	s_cbranch_execz .LBB0_389
	v_add3_u32 v18, v100, s25, -2
	v_mov_b64_e32 v[16:17], s[86:87]
	v_mad_u64_u32 v[16:17], s[14:15], v18, s89, v[16:17]
	v_lshl_add_u64 v[16:17], v[82:83], 1, v[16:17]
	v_add_co_u32_e32 v16, vcc, 0xfb00000, v16
	s_nop 1
	v_addc_co_u32_e32 v17, vcc, 0, v17, vcc
	global_load_dwordx4 v[60:63], v[16:17], off offset:1536
.LBB0_389:
	s_or_b64 exec, exec, s[12:13]
	v_mov_b32_e32 v68, 0
	v_mov_b32_e32 v69, 0
	v_mov_b32_e32 v70, 0
	v_mov_b32_e32 v71, 0
	s_and_saveexec_b64 s[12:13], s[0:1]
	s_cbranch_execz .LBB0_391
	v_add3_u32 v18, v100, s25, -1
	v_mov_b64_e32 v[16:17], s[86:87]
	v_mad_u64_u32 v[16:17], s[0:1], v18, s89, v[16:17]
	v_lshl_add_u64 v[16:17], v[82:83], 1, v[16:17]
	v_add_co_u32_e32 v16, vcc, 0xfb00000, v16
	s_nop 1
	v_addc_co_u32_e32 v17, vcc, 0, v17, vcc
	global_load_dwordx4 v[68:71], v[16:17], off offset:1536
.LBB0_391:
	s_or_b64 exec, exec, s[12:13]
	v_lshl_add_u64 v[16:17], s[86:87], 0, v[96:97]
	v_lshlrev_b64 v[94:95], 1, v[82:83]
	v_lshl_add_u64 v[16:17], v[16:17], 0, v[94:95]
	v_add_co_u32_e32 v18, vcc, 0xfb00000, v16
	s_waitcnt vmcnt(0) lgkmcnt(0)
	v_lshlrev_b32_e32 v121, 16, v4
	v_addc_co_u32_e32 v19, vcc, 0, v17, vcc
	v_add_co_u32_e32 v36, vcc, 0xfb02000, v16
	v_and_b32_e32 v122, 0xffff0000, v4
	s_nop 0
	v_addc_co_u32_e32 v37, vcc, 0, v17, vcc
	global_load_dwordx4 v[72:75], v[18:19], off offset:1536
	global_load_dwordx4 v[56:59], v[36:37], off
	v_add_co_u32_e32 v18, vcc, 0xfb03000, v16
	v_lshlrev_b32_e32 v120, 16, v5
	s_nop 0
	v_addc_co_u32_e32 v19, vcc, 0, v17, vcc
	v_add_co_u32_e32 v16, vcc, 0xfb05000, v16
	v_and_b32_e32 v119, 0xffff0000, v5
	s_nop 0
	v_addc_co_u32_e32 v17, vcc, 0, v17, vcc
	global_load_dwordx4 v[36:39], v[18:19], off offset:2560
	s_nop 0
	global_load_dwordx4 v[16:19], v[16:17], off offset:1024
	v_and_b32_e32 v117, 0xffff0000, v6
	v_lshlrev_b32_e32 v116, 16, v7
	v_and_b32_e32 v115, 0xffff0000, v7
	v_add_f32_e32 v5, 0, v121
	v_add_f32_e32 v4, 0, v122
	v_lshlrev_b32_e32 v113, 16, v0
	v_and_b32_e32 v114, 0xffff0000, v0
	v_lshlrev_b32_e32 v118, 16, v6
	v_add_f32_e32 v6, 0, v120
	v_add_f32_e32 v7, 0, v119
	v_add_f32_e32 v102, 0, v117
	v_add_f32_e32 v103, 0, v116
	v_add_f32_e32 v104, 0, v115
	v_lshlrev_b32_e32 v112, 16, v1
	v_and_b32_e32 v111, 0xffff0000, v1
	v_and_b32_e32 v109, 0xffff0000, v2
	v_lshlrev_b32_e32 v108, 16, v3
	v_and_b32_e32 v107, 0xffff0000, v3
	v_add_f32_e32 v1, v5, v113
	v_add_f32_e32 v0, v4, v114
	v_lshlrev_b32_e32 v106, 16, v12
	v_and_b32_e32 v12, 0xffff0000, v12
	v_lshlrev_b32_e32 v110, 16, v2
	v_add_f32_e32 v2, v6, v112
	v_add_f32_e32 v3, v7, v111
	v_add_f32_e32 v5, v102, v109
	v_add_f32_e32 v6, v103, v108
	v_add_f32_e32 v7, v104, v107
	v_lshlrev_b32_e32 v105, 16, v13
	v_and_b32_e32 v104, 0xffff0000, v13
	v_lshlrev_b32_e32 v103, 16, v14
	v_and_b32_e32 v102, 0xffff0000, v14
	v_lshlrev_b32_e32 v14, 16, v15
	v_and_b32_e32 v13, 0xffff0000, v15
	v_add_f32_e32 v1, v1, v106
	v_add_f32_e32 v0, v0, v12
	v_lshlrev_b32_e32 v15, 16, v8
	v_and_b32_e32 v8, 0xffff0000, v8
	v_add_f32_e32 v1, v1, v15
	v_add_f32_e32 v0, v0, v8
	v_lshlrev_b32_e32 v8, 16, v24
	v_add_f32_e32 v1, v1, v8
	v_and_b32_e32 v8, 0xffff0000, v24
	v_add_f32_e32 v0, v0, v8
	v_lshlrev_b32_e32 v8, 16, v20
	v_add_f32_e32 v1, v1, v8
	v_and_b32_e32 v8, 0xffff0000, v20
	v_add_f32_e32 v0, v0, v8
	v_lshlrev_b32_e32 v8, 16, v32
	v_add_f32_e32 v1, v1, v8
	v_and_b32_e32 v8, 0xffff0000, v32
	v_add_f32_e32 v0, v0, v8
	v_lshlrev_b32_e32 v8, 16, v28
	v_add_f32_e32 v93, 0, v118
	v_add_f32_e32 v1, v1, v8
	v_and_b32_e32 v8, 0xffff0000, v28
	v_add_f32_e32 v4, v93, v110
	v_add_f32_e32 v0, v0, v8
	v_lshlrev_b32_e32 v8, 16, v44
	v_add_f32_e32 v4, v4, v103
	v_add_f32_e32 v7, v7, v13
	v_lshlrev_b32_e32 v123, 16, v10
	v_lshlrev_b32_e32 v124, 16, v11
	v_and_b32_e32 v11, 0xffff0000, v11
	v_add_f32_e32 v1, v1, v8
	v_and_b32_e32 v8, 0xffff0000, v44
	v_add_f32_e32 v5, v5, v102
	v_and_b32_e32 v10, 0xffff0000, v10
	v_add_f32_e32 v4, v4, v123
	v_add_f32_e32 v7, v7, v11
	v_lshlrev_b32_e32 v11, 16, v26
	v_add_f32_e32 v0, v0, v8
	v_lshlrev_b32_e32 v8, 16, v40
	v_add_f32_e32 v5, v5, v10
	v_and_b32_e32 v15, 0xffff0000, v26
	v_add_f32_e32 v4, v4, v11
	v_lshlrev_b32_e32 v11, 16, v22
	v_add_f32_e32 v1, v1, v8
	v_and_b32_e32 v8, 0xffff0000, v40
	v_add_f32_e32 v5, v5, v15
	v_and_b32_e32 v15, 0xffff0000, v22
	v_add_f32_e32 v4, v4, v11
	v_lshlrev_b32_e32 v11, 16, v34
	v_add_f32_e32 v0, v0, v8
	v_lshlrev_b32_e32 v8, 16, v52
	v_add_f32_e32 v5, v5, v15
	v_and_b32_e32 v15, 0xffff0000, v34
; __device__ __forceinline__ void unpack8(const u32x4 w, float* f) { f[0] = bf_lo(w.x); f[1] = bf_hi(w.x); f[2] = bf_lo(w.y); f[3] = bf_hi(w.y); f[4] = bf_lo(w.z); f[5] = bf_hi(w.z); f[6] = bf_lo(w.w); f[7] = bf_hi(w.w); }
; __device__ __forceinline__ u32x4 pack8(const float* f) { u32x4 w; w.x = cvt_pk_bf16(f[0], f[1]); w.y = cvt_pk_bf16(f[2], f[3]); w.z = cvt_pk_bf16(f[4], f[5]); w.w = cvt_pk_bf16(f[6], f[7]); return w; }
; template <int W>
; __device__ __forceinline__ void pool_task_prompt(const Params& p, int l, int b, int c, int g, int rg, int ch, long row0) {
;     ...
;     for (int i = 0; i < W; ++i) { float x[8]; unpack8(raw[i], x);
; #pragma unroll
;         for (int k = 0; k < 8; ++k) { a[0][k] += x[k]; if (i == W - 1) cur[0][k] = x[k]; } }
; #pragma unroll
;     for (int r = 1; r < 4; ++r) { float xin[8], xout[8]; unpack8(raw[W - 1 + r], xin); unpack8(raw[r - 1], xout);
; #pragma unroll
;         for (int k = 0; k < 8; ++k) { a[r][k] = a[r - 1][k] + (xin[k] - xout[k]); cur[r][k] = xin[k]; } }
; #pragma unroll
;     for (int r = 0; r < 4; ++r) {
;         const int t = t0 + r;
;         const float inv = 1.0f / (float)((t + 1) < W ? (t + 1) : W);
;         float d[8];
; #pragma unroll
;         for (int k = 0; k < 8; ++k) d[k] = a[r][k] * inv - cur[r][k];
;         *(u32x4*)(AD + (size_t)(row0 + tl0 + r) * DM + 512 + col) = pack8(d);
;         if (t >= SEQ - 15) { float* pd = p.out + O_PP + (((size_t)l * 2 + b) * 15 + (t - (SEQ - 15))) * 512 + col;
;             *(f32x4*)pd = (f32x4){cur[r][0], cur[r][1], cur[r][2], cur[r][3]}; *(f32x4*)(pd + 4) = (f32x4){cur[r][4], cur[r][5], cur[r][6], cur[r][7]}; }
	v_add_f32_e32 v4, v4, v11
	v_lshlrev_b32_e32 v11, 16, v30
	v_add_f32_e32 v1, v1, v8
	v_and_b32_e32 v8, 0xffff0000, v52
	v_add_f32_e32 v5, v5, v15
	v_and_b32_e32 v15, 0xffff0000, v30
	v_add_f32_e32 v4, v4, v11
	v_lshlrev_b32_e32 v11, 16, v46
	v_add_f32_e32 v0, v0, v8
	v_lshlrev_b32_e32 v8, 16, v48
	v_add_f32_e32 v2, v2, v105
	v_add_f32_e32 v3, v3, v104
	v_add_f32_e32 v6, v6, v14
	v_lshlrev_b32_e32 v93, 16, v9
	v_and_b32_e32 v9, 0xffff0000, v9
	v_add_f32_e32 v5, v5, v15
	v_and_b32_e32 v15, 0xffff0000, v46
	v_add_f32_e32 v4, v4, v11
	v_lshlrev_b32_e32 v11, 16, v42
	v_add_f32_e32 v1, v1, v8
	v_and_b32_e32 v8, 0xffff0000, v48
	v_add_f32_e32 v2, v2, v93
	v_add_f32_e32 v3, v3, v9
	v_add_f32_e32 v6, v6, v124
	v_lshlrev_b32_e32 v9, 16, v25
	v_and_b32_e32 v10, 0xffff0000, v25
	v_lshlrev_b32_e32 v25, 16, v27
	v_add_f32_e32 v5, v5, v15
	v_and_b32_e32 v15, 0xffff0000, v42
	v_add_f32_e32 v4, v4, v11
	v_lshlrev_b32_e32 v11, 16, v54
	v_add_f32_e32 v0, v0, v8
	v_lshlrev_b32_e32 v8, 16, v64
	v_and_b32_e32 v26, 0xffff0000, v27
	v_add_f32_e32 v2, v2, v9
	v_add_f32_e32 v3, v3, v10
	v_add_f32_e32 v6, v6, v25
	v_lshlrev_b32_e32 v9, 16, v21
	v_and_b32_e32 v10, 0xffff0000, v21
	v_lshlrev_b32_e32 v21, 16, v23
	v_add_f32_e32 v5, v5, v15
	v_and_b32_e32 v15, 0xffff0000, v54
	v_add_f32_e32 v4, v4, v11
	v_lshlrev_b32_e32 v11, 16, v50
	v_add_f32_e32 v1, v1, v8
	v_and_b32_e32 v8, 0xffff0000, v64
	v_add_f32_e32 v7, v7, v26
	v_and_b32_e32 v22, 0xffff0000, v23
	v_add_f32_e32 v2, v2, v9
	v_add_f32_e32 v6, v6, v21
	v_lshlrev_b32_e32 v9, 16, v33
	v_lshlrev_b32_e32 v20, 16, v35
	v_add_f32_e32 v5, v5, v15
	v_and_b32_e32 v15, 0xffff0000, v50
	v_add_f32_e32 v4, v4, v11
	v_lshlrev_b32_e32 v11, 16, v66
	v_add_f32_e32 v0, v0, v8
	v_lshlrev_b32_e32 v8, 16, v60
	v_add_f32_e32 v7, v7, v22
	v_and_b32_e32 v21, 0xffff0000, v35
	v_add_f32_e32 v2, v2, v9
	v_add_f32_e32 v6, v6, v20
	v_lshlrev_b32_e32 v9, 16, v29
	v_lshlrev_b32_e32 v20, 16, v31
	v_add_f32_e32 v5, v5, v15
	v_and_b32_e32 v15, 0xffff0000, v66
	v_add_f32_e32 v4, v4, v11
	v_lshlrev_b32_e32 v11, 16, v62
	v_add_f32_e32 v1, v1, v8
	v_and_b32_e32 v8, 0xffff0000, v60
	v_add_f32_e32 v7, v7, v21
	v_and_b32_e32 v21, 0xffff0000, v31
	v_add_f32_e32 v2, v2, v9
	v_add_f32_e32 v6, v6, v20
	v_lshlrev_b32_e32 v9, 16, v45
	v_lshlrev_b32_e32 v20, 16, v47
	v_add_f32_e32 v5, v5, v15
	v_and_b32_e32 v15, 0xffff0000, v62
	v_add_f32_e32 v0, v0, v8
	v_add_f32_e32 v4, v4, v11
	v_lshlrev_b32_e32 v8, 16, v68
	v_lshlrev_b32_e32 v11, 16, v70
	v_add_f32_e32 v7, v7, v21
	v_and_b32_e32 v21, 0xffff0000, v47
	v_add_f32_e32 v2, v2, v9
	v_add_f32_e32 v6, v6, v20
	v_lshlrev_b32_e32 v9, 16, v41
	v_lshlrev_b32_e32 v20, 16, v43
	v_add_f32_e32 v5, v5, v15
	v_and_b32_e32 v15, 0xffff0000, v70
	v_add_f32_e32 v8, v1, v8
	v_add_f32_e32 v11, v4, v11
	s_waitcnt vmcnt(0) lgkmcnt(0)
	v_lshlrev_b32_e32 v4, 16, v72
	v_add_f32_e32 v7, v7, v21
	v_and_b32_e32 v21, 0xffff0000, v43
	v_add_f32_e32 v2, v2, v9
	v_add_f32_e32 v6, v6, v20
	v_lshlrev_b32_e32 v9, 16, v53
	v_lshlrev_b32_e32 v20, 16, v55
	v_add_f32_e32 v24, v5, v15
	v_add_f32_e32 v15, v8, v4
	v_min_i32_e32 v8, 15, v101
	v_add_f32_e32 v7, v7, v21
	v_and_b32_e32 v21, 0xffff0000, v55
	v_add_f32_e32 v2, v2, v9
	v_add_f32_e32 v6, v6, v20
	v_lshlrev_b32_e32 v9, 16, v49
	v_lshlrev_b32_e32 v20, 16, v51
	v_add_u32_e32 v8, 1, v8
	v_add_f32_e32 v7, v7, v21
	v_and_b32_e32 v21, 0xffff0000, v51
	v_add_f32_e32 v2, v2, v9
	v_add_f32_e32 v6, v6, v20
	v_lshlrev_b32_e32 v9, 16, v65
	v_lshlrev_b32_e32 v20, 16, v67
	v_cvt_f32_u32_e32 v8, v8
	v_add_f32_e32 v3, v3, v10
	v_and_b32_e32 v10, 0xffff0000, v33
	v_add_f32_e32 v7, v7, v21
	v_and_b32_e32 v21, 0xffff0000, v67
	v_add_f32_e32 v2, v2, v9
	v_add_f32_e32 v6, v6, v20
	v_lshlrev_b32_e32 v9, 16, v61
	v_lshlrev_b32_e32 v20, 16, v63
	v_add_f32_e32 v3, v3, v10
	v_and_b32_e32 v10, 0xffff0000, v29
	v_add_f32_e32 v7, v7, v21
	v_and_b32_e32 v21, 0xffff0000, v63
	v_add_f32_e32 v2, v2, v9
	v_add_f32_e32 v6, v6, v20
	v_lshlrev_b32_e32 v9, 16, v69
	v_lshlrev_b32_e32 v20, 16, v71
	v_add_f32_e32 v3, v3, v10
	v_and_b32_e32 v10, 0xffff0000, v45
	v_add_f32_e32 v7, v7, v21
	v_and_b32_e32 v21, 0xffff0000, v71
	v_add_f32_e32 v9, v2, v9
	v_add_f32_e32 v25, v6, v20
	v_lshlrev_b32_e32 v6, 16, v73
	v_add_f32_e32 v3, v3, v10
	v_and_b32_e32 v10, 0xffff0000, v41
	v_add_f32_e32 v26, v7, v21
	v_add_f32_e32 v21, v9, v6
	v_div_scale_f32 v9, s[0:1], v8, v8, 1.0
	v_add_f32_e32 v3, v3, v10
	v_and_b32_e32 v10, 0xffff0000, v53
	v_rcp_f32_e32 v27, v9
	v_add_f32_e32 v3, v3, v10
	v_and_b32_e32 v10, 0xffff0000, v49
	v_add_f32_e32 v3, v3, v10
	v_and_b32_e32 v10, 0xffff0000, v65
	v_and_b32_e32 v1, 0xffff0000, v68
	v_add_f32_e32 v3, v3, v10
	v_and_b32_e32 v10, 0xffff0000, v61
	v_add_f32_e32 v22, v0, v1
	v_lshlrev_b32_e32 v0, 16, v74
	v_lshlrev_b32_e32 v2, 16, v75
	v_add_f32_e32 v3, v3, v10
	v_and_b32_e32 v10, 0xffff0000, v69
	v_add_f32_e32 v23, v11, v0
	v_add_f32_e32 v11, v25, v2
	v_fma_f32 v25, -v9, v27, 1.0
	v_add_f32_e32 v10, v3, v10
	v_and_b32_e32 v5, 0xffff0000, v72
	v_and_b32_e32 v7, 0xffff0000, v73
	v_and_b32_e32 v3, 0xffff0000, v75
	v_fmac_f32_e32 v27, v25, v27
	v_div_scale_f32 v25, vcc, 1.0, v8, 1.0
	v_add_f32_e32 v20, v22, v5
	v_add_f32_e32 v22, v10, v7
	v_add_f32_e32 v10, v26, v3
	v_mul_f32_e32 v26, v25, v27
	v_fma_f32 v28, -v9, v26, v25
	v_fmac_f32_e32 v26, v28, v27
	v_fma_f32 v9, -v9, v26, v25
	v_and_b32_e32 v1, 0xffff0000, v74
	v_div_fmas_f32 v9, v9, v27, v26
	v_add_f32_e32 v24, v24, v1
	v_div_fixup_f32 v8, v9, v8, 1.0
	v_fma_f32 v9, v8, v15, -v4
	v_fma_f32 v25, v8, v20, -v5
	v_fma_f32 v27, v8, v21, -v6
	v_fma_f32 v28, v8, v22, -v7
	v_fma_f32 v29, v8, v23, -v0
	v_fma_f32 v30, v8, v24, -v1
	v_fma_f32 v31, v8, v11, -v2
	v_fma_f32 v8, v8, v10, -v3
	v_mov_b32_e32 v93, v97
	v_cvt_pk_bf16_f32 v26, v9, v25
	v_cvt_pk_bf16_f32 v27, v27, v28
	v_cvt_pk_bf16_f32 v28, v29, v30
	v_cvt_pk_bf16_f32 v29, v31, v8
	v_lshl_add_u64 v[8:9], s[86:87], 0, v[92:93]
	v_lshl_add_u64 v[30:31], v[8:9], 0, v[94:95]
	v_add_co_u32_e32 v30, vcc, 0x7900000, v30
	s_movk_i32 s0, 0x3ff0
	s_nop 0
	v_addc_co_u32_e32 v31, vcc, 0, v31, vcc
	v_cmp_lt_u32_e32 vcc, s0, v101
	global_store_dwordx4 v[30:31], v[26:29], off offset:1024
	s_and_saveexec_b64 s[0:1], vcc
	s_cbranch_execz .LBB0_393
	v_add_u32_e32 v25, s7, v101
	v_add_u32_e32 v26, 0xffffc00f, v25
	v_mov_b32_e32 v27, v97
	v_lshlrev_b64 v[26:27], 11, v[26:27]
	v_lshl_add_u64 v[26:27], v[86:87], 0, v[26:27]
	global_store_dwordx4 v[26:27], v[4:7], off
	global_store_dwordx4 v[26:27], v[0:3], off offset:16
; __device__ __forceinline__ void unpack8(const u32x4 w, float* f) { f[0] = bf_lo(w.x); f[1] = bf_hi(w.x); f[2] = bf_lo(w.y); f[3] = bf_hi(w.y); f[4] = bf_lo(w.z); f[5] = bf_hi(w.z); f[6] = bf_lo(w.w); f[7] = bf_hi(w.w); }
; __device__ __forceinline__ u32x4 pack8(const float* f) { u32x4 w; w.x = cvt_pk_bf16(f[0], f[1]); w.y = cvt_pk_bf16(f[2], f[3]); w.z = cvt_pk_bf16(f[4], f[5]); w.w = cvt_pk_bf16(f[6], f[7]); return w; }
; template <int W>
; __device__ __forceinline__ void pool_task_prompt(const Params& p, int l, int b, int c, int g, int rg, int ch, long row0) {
;     ...
;     for (int r = 1; r < 4; ++r) { float xin[8], xout[8]; unpack8(raw[W - 1 + r], xin); unpack8(raw[r - 1], xout);
; #pragma unroll
;         for (int k = 0; k < 8; ++k) { a[r][k] = a[r - 1][k] + (xin[k] - xout[k]); cur[r][k] = xin[k]; } }
; #pragma unroll
;     for (int r = 0; r < 4; ++r) {
;         const int t = t0 + r;
;         const float inv = 1.0f / (float)((t + 1) < W ? (t + 1) : W);
;         float d[8];
; #pragma unroll
;         for (int k = 0; k < 8; ++k) d[k] = a[r][k] * inv - cur[r][k];
;         *(u32x4*)(AD + (size_t)(row0 + tl0 + r) * DM + 512 + col) = pack8(d);
;         if (t >= SEQ - 15) { float* pd = p.out + O_PP + (((size_t)l * 2 + b) * 15 + (t - (SEQ - 15))) * 512 + col;
;             *(f32x4*)pd = (f32x4){cur[r][0], cur[r][1], cur[r][2], cur[r][3]}; *(f32x4*)(pd + 4) = (f32x4){cur[r][4], cur[r][5], cur[r][6], cur[r][7]}; }
.LBB0_393:
	s_or_b64 exec, exec, s[0:1]
	v_add_u32_e32 v26, 1, v101
	v_min_i32_e32 v26, 15, v26
	v_add_u32_e32 v26, 1, v26
	v_lshlrev_b32_e32 v4, 16, v56
	v_cvt_f32_u32_e32 v26, v26
	v_and_b32_e32 v5, 0xffff0000, v56
	v_sub_f32_e32 v25, v4, v121
	v_lshlrev_b32_e32 v6, 16, v57
	v_add_f32_e32 v15, v15, v25
	v_sub_f32_e32 v25, v5, v122
	v_and_b32_e32 v7, 0xffff0000, v57
	v_add_f32_e32 v20, v20, v25
	v_sub_f32_e32 v25, v6, v120
	v_lshlrev_b32_e32 v0, 16, v58
	v_add_f32_e32 v21, v21, v25
	v_sub_f32_e32 v25, v7, v119
	v_div_scale_f32 v27, s[0:1], v26, v26, 1.0
	v_and_b32_e32 v1, 0xffff0000, v58
	v_add_f32_e32 v22, v22, v25
	v_sub_f32_e32 v25, v0, v118
	v_rcp_f32_e32 v28, v27
	v_lshlrev_b32_e32 v2, 16, v59
	v_add_f32_e32 v23, v23, v25
	v_sub_f32_e32 v25, v1, v117
	v_and_b32_e32 v3, 0xffff0000, v59
	v_add_f32_e32 v24, v24, v25
	v_sub_f32_e32 v25, v2, v116
	v_add_f32_e32 v11, v11, v25
	v_sub_f32_e32 v25, v3, v115
	v_add_f32_e32 v10, v10, v25
	v_fma_f32 v25, -v27, v28, 1.0
	v_fmac_f32_e32 v28, v25, v28
	v_div_scale_f32 v25, vcc, 1.0, v26, 1.0
	v_mul_f32_e32 v29, v25, v28
	v_fma_f32 v30, -v27, v29, v25
	v_fmac_f32_e32 v29, v30, v28
	v_fma_f32 v25, -v27, v29, v25
	v_div_fmas_f32 v25, v25, v28, v29
	v_div_fixup_f32 v25, v25, v26, 1.0
	v_fma_f32 v26, v25, v15, -v4
	v_fma_f32 v27, v25, v20, -v5
	v_fma_f32 v28, v25, v21, -v6
	v_fma_f32 v30, v25, v23, -v0
	v_lshl_add_u64 v[8:9], v[82:83], 1, v[8:9]
	v_fma_f32 v29, v25, v22, -v7
	v_fma_f32 v31, v25, v24, -v1
	v_cvt_pk_bf16_f32 v26, v26, v27
	v_cvt_pk_bf16_f32 v27, v28, v29
	v_cvt_pk_bf16_f32 v28, v30, v31
	v_add_co_u32_e32 v30, vcc, 0x7900000, v8
	s_movk_i32 s0, 0x3fef
	s_nop 0
	v_addc_co_u32_e32 v31, vcc, 0, v9, vcc
	v_cmp_lt_u32_e64 s[0:1], s0, v101
	v_fma_f32 v32, v25, v11, -v2
	v_fma_f32 v25, v25, v10, -v3
	v_cvt_pk_bf16_f32 v29, v32, v25
	global_store_dwordx4 v[30:31], v[26:29], off offset:3072
	s_and_saveexec_b64 s[12:13], s[0:1]
	s_cbranch_execz .LBB0_395
	v_add_u32_e32 v25, s7, v101
	v_add_u32_e32 v26, 0xffffc010, v25
	v_mov_b32_e32 v27, v97
	v_lshlrev_b64 v[26:27], 11, v[26:27]
	v_lshl_add_u64 v[26:27], v[86:87], 0, v[26:27]
	global_store_dwordx4 v[26:27], v[4:7], off
	global_store_dwordx4 v[26:27], v[0:3], off offset:16
.LBB0_395:
	s_or_b64 exec, exec, s[12:13]
	v_add_u32_e32 v26, 2, v101
	v_min_i32_e32 v26, 15, v26
	v_add_u32_e32 v26, 1, v26
	v_lshlrev_b32_e32 v4, 16, v36
	v_cvt_f32_u32_e32 v26, v26
	v_and_b32_e32 v5, 0xffff0000, v36
	v_sub_f32_e32 v25, v4, v113
	v_lshlrev_b32_e32 v6, 16, v37
	v_add_f32_e32 v15, v25, v15
	v_sub_f32_e32 v25, v5, v114
	v_and_b32_e32 v7, 0xffff0000, v37
	v_add_f32_e32 v20, v25, v20
	v_sub_f32_e32 v25, v6, v112
	v_lshlrev_b32_e32 v0, 16, v38
	v_add_f32_e32 v21, v25, v21
	v_sub_f32_e32 v25, v7, v111
	v_div_scale_f32 v27, s[12:13], v26, v26, 1.0
	v_and_b32_e32 v1, 0xffff0000, v38
	v_add_f32_e32 v22, v25, v22
	v_sub_f32_e32 v25, v0, v110
	v_rcp_f32_e32 v28, v27
	v_lshlrev_b32_e32 v2, 16, v39
	v_add_f32_e32 v23, v25, v23
	v_sub_f32_e32 v25, v1, v109
	v_and_b32_e32 v3, 0xffff0000, v39
	v_add_f32_e32 v24, v25, v24
	v_sub_f32_e32 v25, v2, v108
	v_add_f32_e32 v11, v25, v11
	v_sub_f32_e32 v25, v3, v107
	v_add_f32_e32 v10, v25, v10
	v_fma_f32 v25, -v27, v28, 1.0
	v_fmac_f32_e32 v28, v25, v28
	v_div_scale_f32 v25, vcc, 1.0, v26, 1.0
	v_mul_f32_e32 v29, v25, v28
	v_fma_f32 v30, -v27, v29, v25
	v_fmac_f32_e32 v29, v30, v28
	v_fma_f32 v25, -v27, v29, v25
	v_div_fmas_f32 v25, v25, v28, v29
	v_div_fixup_f32 v25, v25, v26, 1.0
	v_fma_f32 v26, v25, v15, -v4
	v_fma_f32 v27, v25, v20, -v5
	v_fma_f32 v28, v25, v21, -v6
	v_fma_f32 v30, v25, v23, -v0
	v_fma_f32 v29, v25, v22, -v7
	v_fma_f32 v31, v25, v24, -v1
	v_cvt_pk_bf16_f32 v26, v26, v27
	v_cvt_pk_bf16_f32 v27, v28, v29
	v_cvt_pk_bf16_f32 v28, v30, v31
	v_add_co_u32_e32 v30, vcc, 0x7901000, v8
	v_fma_f32 v32, v25, v11, -v2
	s_nop 0
	v_addc_co_u32_e32 v31, vcc, 0, v9, vcc
	v_fma_f32 v25, v25, v10, -v3
	v_cvt_pk_bf16_f32 v29, v32, v25
	global_store_dwordx4 v[30:31], v[26:29], off offset:1024
	s_and_saveexec_b64 s[12:13], s[0:1]
	s_cbranch_execz .LBB0_397
	v_add_u32_e32 v25, s7, v101
	v_add_u32_e32 v26, 0xffffc011, v25
	v_mov_b32_e32 v27, v97
	v_lshlrev_b64 v[26:27], 11, v[26:27]
	v_lshl_add_u64 v[26:27], v[86:87], 0, v[26:27]
	global_store_dwordx4 v[26:27], v[4:7], off
	global_store_dwordx4 v[26:27], v[0:3], off offset:16
.LBB0_397:
	s_or_b64 exec, exec, s[12:13]
	v_lshlrev_b32_e32 v4, 16, v16
	v_and_b32_e32 v5, 0xffff0000, v16
	v_lshlrev_b32_e32 v6, 16, v17
	v_sub_f32_e32 v16, v4, v106
	v_sub_f32_e32 v12, v5, v12
	v_add_f32_e32 v15, v16, v15
	v_add_f32_e32 v12, v12, v20
	v_sub_f32_e32 v16, v6, v105
	v_add_u32_e32 v20, 3, v101
	v_add_f32_e32 v16, v16, v21
	v_min_i32_e32 v21, 15, v20
	v_add_u32_e32 v21, 1, v21
	v_cvt_f32_u32_e32 v21, v21
	v_and_b32_e32 v7, 0xffff0000, v17
	v_lshlrev_b32_e32 v0, 16, v18
	v_sub_f32_e32 v17, v7, v104
	v_and_b32_e32 v1, 0xffff0000, v18
	v_add_f32_e32 v17, v17, v22
	v_sub_f32_e32 v18, v0, v103
	v_div_scale_f32 v22, s[0:1], v21, v21, 1.0
	v_add_f32_e32 v18, v18, v23
	v_rcp_f32_e32 v23, v22
	v_and_b32_e32 v3, 0xffff0000, v19
	v_sub_f32_e32 v13, v3, v13
	v_lshlrev_b32_e32 v2, 16, v19
	v_add_f32_e32 v10, v13, v10
	v_fma_f32 v13, -v22, v23, 1.0
	v_sub_f32_e32 v14, v2, v14
	v_fmac_f32_e32 v23, v13, v23
	v_div_scale_f32 v13, vcc, 1.0, v21, 1.0
	v_sub_f32_e32 v19, v1, v102
	v_add_f32_e32 v11, v14, v11
	v_mul_f32_e32 v14, v13, v23
	v_add_f32_e32 v19, v19, v24
	v_fma_f32 v24, -v22, v14, v13
	v_fmac_f32_e32 v14, v24, v23
	v_fma_f32 v13, -v22, v14, v13
	v_div_fmas_f32 v13, v13, v23, v14
	v_add_co_u32_e32 v8, vcc, 0x7901000, v8
	s_movk_i32 s0, 0x3ff0
	s_nop 0
	v_addc_co_u32_e32 v9, vcc, 0, v9, vcc
	v_div_fixup_f32 v13, v13, v21, 1.0
	v_cmp_lt_u32_e32 vcc, s0, v20
	v_fma_f32 v14, v13, v15, -v4
	v_fma_f32 v12, v13, v12, -v5
	v_fma_f32 v15, v13, v16, -v6
	v_fma_f32 v16, v13, v17, -v7
	v_fma_f32 v17, v13, v18, -v0
	v_fma_f32 v18, v13, v19, -v1
	v_fma_f32 v19, v13, v11, -v2
	v_fma_f32 v13, v13, v10, -v3
	s_andn2_b64 s[0:1], s[8:9], exec
	s_and_b64 s[8:9], vcc, exec
	v_cvt_pk_bf16_f32 v10, v14, v12
	v_cvt_pk_bf16_f32 v11, v15, v16
	v_cvt_pk_bf16_f32 v12, v17, v18
	v_cvt_pk_bf16_f32 v13, v19, v13
	global_store_dwordx4 v[8:9], v[10:13], off offset:3072
	s_or_b64 s[8:9], s[0:1], s[8:9]
	s_andn2_b64 s[2:3], s[2:3], exec
	v_mov_b64_e32 v[8:9], v[82:83]
	s_or_b64 exec, exec, s[10:11]
	s_and_saveexec_b64 s[0:1], s[2:3]
	s_xor_b64 s[2:3], exec, s[0:1]
	s_cbranch_execnz .LBB0_402

; __device__ __forceinline__ void unpack8(const u32x4 w, float* f) { f[0] = bf_lo(w.x); f[1] = bf_hi(w.x); f[2] = bf_lo(w.y); f[3] = bf_hi(w.y); f[4] = bf_lo(w.z); f[5] = bf_hi(w.z); f[6] = bf_lo(w.w); f[7] = bf_hi(w.w); }
; __device__ __forceinline__ u32x4 pack8(const float* f) { u32x4 w; w.x = cvt_pk_bf16(f[0], f[1]); w.y = cvt_pk_bf16(f[2], f[3]); w.z = cvt_pk_bf16(f[4], f[5]); w.w = cvt_pk_bf16(f[6], f[7]); return w; }
; template <int W>
; __device__ __forceinline__ void pool_task_prompt(const Params& p, int l, int b, int c, int g, int rg, int ch, long row0) {
;     ...
;     u32x4 raw[W + 3];
; #pragma unroll
;     for (int i = 0; i < W + 3; ++i) { const int tt = t0 - (W - 1) + i; raw[i] = (u32x4){0u, 0u, 0u, 0u};
;         if (tt >= 0) raw[i] = *(const u32x4*)(P + (size_t)((long)b * SEQ + tt) * INW + 768 + col); }
;     float a[4][8], cur[4][8];
; #pragma unroll
;     for (int k = 0; k < 8; ++k) a[0][k] = 0.f;
; #pragma unroll
;     for (int i = 0; i < W; ++i) { float x[8]; unpack8(raw[i], x);
; #pragma unroll
;         for (int k = 0; k < 8; ++k) { a[0][k] += x[k]; if (i == W - 1) cur[0][k] = x[k]; } }
; #pragma unroll
;     for (int r = 1; r < 4; ++r) { float xin[8], xout[8]; unpack8(raw[W - 1 + r], xin); unpack8(raw[r - 1], xout);
; #pragma unroll
;         for (int k = 0; k < 8; ++k) { a[r][k] = a[r - 1][k] + (xin[k] - xout[k]); cur[r][k] = xin[k]; } }
; #pragma unroll
;     for (int r = 0; r < 4; ++r) {
;         const int t = t0 + r;
;         const float inv = 1.0f / (float)((t + 1) < W ? (t + 1) : W);
;         float d[8];
; #pragma unroll
;         for (int k = 0; k < 8; ++k) d[k] = a[r][k] * inv - cur[r][k];
;         *(u32x4*)(AD + (size_t)(row0 + tl0 + r) * DM + 512 + col) = pack8(d);
;         if (t >= SEQ - 15) { float* pd = p.out + O_PP + (((size_t)l * 2 + b) * 15 + (t - (SEQ - 15))) * 512 + col;
;             *(f32x4*)pd = (f32x4){cur[r][0], cur[r][1], cur[r][2], cur[r][3]}; *(f32x4*)(pd + 4) = (f32x4){cur[r][4], cur[r][5], cur[r][6], cur[r][7]}; }
.LBB0_402:
	v_mov_b32_e32 v8, 0
	v_cmp_ne_u32_e32 vcc, 0, v101
	v_lshlrev_b32_e32 v28, 1, v76
	v_mov_b32_e32 v9, 0
	v_mov_b32_e32 v10, 0
	v_mov_b32_e32 v11, 0
	s_and_saveexec_b64 s[0:1], vcc
	s_cbranch_execz .LBB0_404
	v_add3_u32 v2, v100, s25, -1
	v_mov_b64_e32 v[0:1], s[86:87]
	v_mad_u64_u32 v[0:1], s[10:11], v2, s89, v[0:1]
	v_mov_b32_e32 v29, v97
	v_lshl_add_u64 v[0:1], v[0:1], 0, v[28:29]
	v_add_co_u32_e32 v0, vcc, 0xfb00000, v0
	s_nop 1
	v_addc_co_u32_e32 v1, vcc, 0, v1, vcc
	global_load_dwordx4 v[8:11], v[0:1], off offset:1536
.LBB0_404:
	s_or_b64 exec, exec, s[0:1]
	v_lshl_add_u64 v[0:1], s[86:87], 0, v[96:97]
	v_mov_b32_e32 v29, v97
	v_lshl_add_u64 v[0:1], v[0:1], 0, v[28:29]
	v_add_co_u32_e32 v2, vcc, 0xfb00000, v0
	s_waitcnt vmcnt(0) lgkmcnt(0)
	v_lshlrev_b32_e32 v36, 16, v8
	v_addc_co_u32_e32 v3, vcc, 0, v1, vcc
	global_load_dwordx4 v[20:23], v[2:3], off offset:1536
	v_add_co_u32_e32 v2, vcc, 0xfb02000, v0
	v_and_b32_e32 v37, 0xffff0000, v8
	s_nop 0
	v_addc_co_u32_e32 v3, vcc, 0, v1, vcc
	v_add_co_u32_e32 v4, vcc, 0xfb03000, v0
	global_load_dwordx4 v[16:19], v[2:3], off
	s_nop 0
	v_addc_co_u32_e32 v5, vcc, 0, v1, vcc
	v_add_co_u32_e32 v0, vcc, 0xfb05000, v0
	v_min_i32_e32 v8, 1, v101
	s_nop 0
	v_addc_co_u32_e32 v1, vcc, 0, v1, vcc
	global_load_dwordx4 v[4:7], v[4:5], off offset:2560
	s_nop 0
	global_load_dwordx4 v[0:3], v[0:1], off offset:1024
	v_add_u32_e32 v8, 1, v8
	v_cvt_f32_u32_e32 v8, v8
	v_lshlrev_b32_e32 v35, 16, v9
	v_and_b32_e32 v34, 0xffff0000, v9
	v_lshlrev_b32_e32 v33, 16, v10
	v_div_scale_f32 v9, s[0:1], v8, v8, 1.0
	v_and_b32_e32 v32, 0xffff0000, v10
	v_rcp_f32_e32 v10, v9
	v_lshlrev_b32_e32 v27, 16, v11
	v_and_b32_e32 v26, 0xffff0000, v11
	v_div_scale_f32 v11, vcc, 1.0, v8, 1.0
	v_fma_f32 v12, -v9, v10, 1.0
	v_fmac_f32_e32 v10, v12, v10
	v_mul_f32_e32 v12, v11, v10
	v_fma_f32 v13, -v9, v12, v11
	v_fmac_f32_e32 v12, v13, v10
	v_fma_f32 v9, -v9, v12, v11
	v_div_fmas_f32 v9, v9, v10, v12
	v_add_f32_e32 v24, 0, v36
	v_add_f32_e32 v25, 0, v37
	v_add_f32_e32 v30, 0, v35
	v_add_f32_e32 v31, 0, v34
	v_add_f32_e32 v38, 0, v33
	v_add_f32_e32 v39, 0, v32
	v_add_f32_e32 v46, 0, v27
	v_add_f32_e32 v47, 0, v26
	v_div_fixup_f32 v48, v9, v8, 1.0
	v_mov_b32_e32 v93, v97
	s_movk_i32 s0, 0x3ff0
	s_waitcnt vmcnt(0) lgkmcnt(0)
	v_lshlrev_b32_e32 v12, 16, v20
	v_and_b32_e32 v13, 0xffff0000, v20
	v_lshlrev_b32_e32 v14, 16, v21
	v_and_b32_e32 v15, 0xffff0000, v21
	v_lshlrev_b32_e32 v8, 16, v22
	v_and_b32_e32 v9, 0xffff0000, v22
	v_lshlrev_b32_e32 v10, 16, v23
	v_and_b32_e32 v11, 0xffff0000, v23
	v_add_f32_e32 v45, v24, v12
	v_add_f32_e32 v44, v25, v13
	v_add_f32_e32 v43, v30, v14
	v_add_f32_e32 v42, v31, v15
	v_add_f32_e32 v41, v38, v8
	v_add_f32_e32 v40, v39, v9
	v_add_f32_e32 v39, v46, v10
	v_add_f32_e32 v38, v47, v11
	v_fma_f32 v20, v48, v45, -v12
	v_fma_f32 v21, v48, v44, -v13
	v_fma_f32 v22, v48, v43, -v14
	v_fma_f32 v23, v48, v42, -v15
	v_fma_f32 v30, v48, v39, -v10
	v_fma_f32 v31, v48, v38, -v11
	v_fma_f32 v24, v48, v41, -v8
	v_fma_f32 v25, v48, v40, -v9
	v_cvt_pk_bf16_f32 v20, v20, v21
	v_cvt_pk_bf16_f32 v21, v22, v23
	v_cvt_pk_bf16_f32 v22, v24, v25
	v_cvt_pk_bf16_f32 v23, v30, v31
	v_lshl_add_u64 v[30:31], s[86:87], 0, v[92:93]
	v_lshl_add_u64 v[24:25], v[30:31], 0, v[28:29]
	v_add_co_u32_e32 v46, vcc, 0x7900000, v24
	s_nop 1
	v_addc_co_u32_e32 v47, vcc, 0, v25, vcc
	v_cmp_lt_u32_e32 vcc, s0, v101
	global_store_dwordx4 v[46:47], v[20:23], off offset:1024
	s_and_saveexec_b64 s[0:1], vcc
	s_cbranch_execz .LBB0_406
	v_add_u32_e32 v20, s7, v101
	v_add_u32_e32 v20, 0xffffc00f, v20
	v_mov_b32_e32 v21, v97
	v_lshlrev_b64 v[20:21], 11, v[20:21]
	v_lshl_add_u64 v[20:21], v[84:85], 0, v[20:21]
	global_store_dwordx4 v[20:21], v[12:15], off
	global_store_dwordx4 v[20:21], v[8:11], off offset:16
; __device__ __forceinline__ void unpack8(const u32x4 w, float* f) { f[0] = bf_lo(w.x); f[1] = bf_hi(w.x); f[2] = bf_lo(w.y); f[3] = bf_hi(w.y); f[4] = bf_lo(w.z); f[5] = bf_hi(w.z); f[6] = bf_lo(w.w); f[7] = bf_hi(w.w); }
; __device__ __forceinline__ u32x4 pack8(const float* f) { u32x4 w; w.x = cvt_pk_bf16(f[0], f[1]); w.y = cvt_pk_bf16(f[2], f[3]); w.z = cvt_pk_bf16(f[4], f[5]); w.w = cvt_pk_bf16(f[6], f[7]); return w; }
; template <int W>
; __device__ __forceinline__ void pool_task_prompt(const Params& p, int l, int b, int c, int g, int rg, int ch, long row0) {
;     ...
;     for (int r = 1; r < 4; ++r) { float xin[8], xout[8]; unpack8(raw[W - 1 + r], xin); unpack8(raw[r - 1], xout);
; #pragma unroll
;         for (int k = 0; k < 8; ++k) { a[r][k] = a[r - 1][k] + (xin[k] - xout[k]); cur[r][k] = xin[k]; } }
; #pragma unroll
;     for (int r = 0; r < 4; ++r) {
;         const int t = t0 + r;
;         const float inv = 1.0f / (float)((t + 1) < W ? (t + 1) : W);
;         float d[8];
; #pragma unroll
;         for (int k = 0; k < 8; ++k) d[k] = a[r][k] * inv - cur[r][k];
;         *(u32x4*)(AD + (size_t)(row0 + tl0 + r) * DM + 512 + col) = pack8(d);
;         if (t >= SEQ - 15) { float* pd = p.out + O_PP + (((size_t)l * 2 + b) * 15 + (t - (SEQ - 15))) * 512 + col;
;             *(f32x4*)pd = (f32x4){cur[r][0], cur[r][1], cur[r][2], cur[r][3]}; *(f32x4*)(pd + 4) = (f32x4){cur[r][4], cur[r][5], cur[r][6], cur[r][7]}; }
;     }
; __device__ __forceinline__ void attn_macro(const Params& p, int l, LAS unsigned char* lds, int b, int cg, int kvh) {
;     ...
;         for (int ci = 0; ci < 4; ++ci) {
;             const int c = c0 + ci; const long row0 = rowb + (long)c * 64;
;             if (g == 0) pool_task_prompt<2>(p, l, b, c, g, rg, ch, row0);
;             else if (g == 1) pool_task_prompt<4>(p, l, b, c, g, rg, ch, row0);
;             else if (g == 2) pool_task_prompt<8>(p, l, b, c, g, rg, ch, row0);
;             else pool_task_prompt<16>(p, l, b, c, g, rg, ch, row0);
;         }
.LBB0_406:
	s_or_b64 exec, exec, s[0:1]
	v_lshlrev_b32_e32 v20, 16, v16
	v_and_b32_e32 v21, 0xffff0000, v16
	v_lshlrev_b32_e32 v22, 16, v17
	v_and_b32_e32 v23, 0xffff0000, v17
	v_lshlrev_b32_e32 v16, 16, v18
	v_and_b32_e32 v17, 0xffff0000, v18
	v_lshlrev_b32_e32 v18, 16, v19
	v_and_b32_e32 v19, 0xffff0000, v19
	v_sub_f32_e32 v34, v23, v34
	v_sub_f32_e32 v33, v16, v33
	v_sub_f32_e32 v32, v17, v32
	v_sub_f32_e32 v29, v20, v36
	v_sub_f32_e32 v36, v21, v37
	v_sub_f32_e32 v35, v22, v35
	v_add_f32_e32 v34, v42, v34
	v_add_f32_e32 v33, v41, v33
	v_add_f32_e32 v32, v40, v32
	v_sub_f32_e32 v27, v18, v27
	v_sub_f32_e32 v26, v19, v26
	v_add_co_u32_e32 v24, vcc, 0x7900000, v24
	s_movk_i32 s0, 0x3fef
	v_add_f32_e32 v29, v45, v29
	v_add_f32_e32 v36, v44, v36
	v_add_f32_e32 v35, v43, v35
	v_add_f32_e32 v37, v39, v27
	v_add_f32_e32 v38, v38, v26
	v_fma_f32 v41, v34, 0.5, -v23
	v_fma_f32 v42, v33, 0.5, -v16
	v_fma_f32 v43, v32, 0.5, -v17
	v_addc_co_u32_e32 v25, vcc, 0, v25, vcc
	v_cmp_lt_u32_e64 s[0:1], s0, v101
	v_fma_f32 v26, v29, 0.5, -v20
	v_fma_f32 v27, v36, 0.5, -v21
	v_fma_f32 v39, v35, 0.5, -v22
	v_fma_f32 v44, v37, 0.5, -v18
	v_fma_f32 v45, v38, 0.5, -v19
	v_cvt_pk_bf16_f32 v40, v26, v27
	v_cvt_pk_bf16_f32 v41, v39, v41
	v_cvt_pk_bf16_f32 v42, v42, v43
	v_cvt_pk_bf16_f32 v43, v44, v45
	global_store_dwordx4 v[24:25], v[40:43], off offset:3072
	s_and_saveexec_b64 s[10:11], s[0:1]
	s_cbranch_execz .LBB0_408
	v_add_u32_e32 v24, s7, v101
	v_add_u32_e32 v24, 0xffffc010, v24
	v_mov_b32_e32 v25, v97
	v_lshlrev_b64 v[24:25], 11, v[24:25]
	v_lshl_add_u64 v[24:25], v[84:85], 0, v[24:25]
	global_store_dwordx4 v[24:25], v[20:23], off
	global_store_dwordx4 v[24:25], v[16:19], off offset:16
.LBB0_408:
	s_or_b64 exec, exec, s[10:11]
	v_lshlrev_b32_e32 v24, 16, v4
	v_and_b32_e32 v25, 0xffff0000, v4
	v_lshlrev_b32_e32 v4, 16, v6
	v_lshlrev_b32_e32 v26, 16, v5
	v_and_b32_e32 v27, 0xffff0000, v5
	v_and_b32_e32 v5, 0xffff0000, v6
	v_sub_f32_e32 v8, v4, v8
	v_lshlrev_b32_e32 v6, 16, v7
	v_sub_f32_e32 v14, v26, v14
	v_sub_f32_e32 v15, v27, v15
	v_add_f32_e32 v33, v8, v33
	v_sub_f32_e32 v8, v5, v9
	v_and_b32_e32 v7, 0xffff0000, v7
	v_sub_f32_e32 v12, v24, v12
	v_sub_f32_e32 v13, v25, v13
	v_add_f32_e32 v14, v14, v35
	v_add_f32_e32 v15, v15, v34
	v_add_f32_e32 v32, v8, v32
	v_sub_f32_e32 v8, v6, v10
	v_add_f32_e32 v12, v12, v29
	v_add_f32_e32 v13, v13, v36
	v_add_f32_e32 v10, v8, v37
	v_sub_f32_e32 v8, v7, v11
	v_fma_f32 v29, v14, 0.5, -v26
	v_fma_f32 v35, v15, 0.5, -v27
	v_add_f32_e32 v11, v8, v38
	v_fma_f32 v8, v12, 0.5, -v24
	v_fma_f32 v9, v13, 0.5, -v25
	v_cvt_pk_bf16_f32 v34, v8, v9
	v_cvt_pk_bf16_f32 v35, v29, v35
	v_mov_b32_e32 v29, v97
	v_lshl_add_u64 v[8:9], v[30:31], 0, v[28:29]
	v_add_co_u32_e32 v28, vcc, 0x7901000, v8
	v_fma_f32 v36, v33, 0.5, -v4
	v_fma_f32 v37, v32, 0.5, -v5
	v_addc_co_u32_e32 v29, vcc, 0, v9, vcc
	v_fma_f32 v38, v10, 0.5, -v6
	v_fma_f32 v39, v11, 0.5, -v7
	v_cvt_pk_bf16_f32 v36, v36, v37
	v_cvt_pk_bf16_f32 v37, v38, v39
	global_store_dwordx4 v[28:29], v[34:37], off offset:1024
	s_and_saveexec_b64 s[10:11], s[0:1]
	s_cbranch_execz .LBB0_410
	v_add_u32_e32 v28, s7, v101
	v_add_u32_e32 v28, 0xffffc011, v28
	v_mov_b32_e32 v29, v97
	v_lshlrev_b64 v[28:29], 11, v[28:29]
	v_lshl_add_u64 v[28:29], v[84:85], 0, v[28:29]
	global_store_dwordx4 v[28:29], v[24:27], off
	global_store_dwordx4 v[28:29], v[4:7], off offset:16
.LBB0_410:
	s_or_b64 exec, exec, s[10:11]
	s_nop 0
	v_lshlrev_b32_e32 v4, 16, v0
	v_and_b32_e32 v5, 0xffff0000, v0
	v_lshlrev_b32_e32 v6, 16, v1
	v_and_b32_e32 v7, 0xffff0000, v1
	v_lshlrev_b32_e32 v0, 16, v2
	v_and_b32_e32 v1, 0xffff0000, v2
	v_lshlrev_b32_e32 v2, 16, v3
	v_and_b32_e32 v3, 0xffff0000, v3
	v_sub_f32_e32 v20, v4, v20
	v_sub_f32_e32 v18, v2, v18
	v_add_f32_e32 v12, v20, v12
	v_sub_f32_e32 v20, v5, v21
	v_add_f32_e32 v10, v18, v10
	v_sub_f32_e32 v18, v3, v19
	v_add_co_u32_e32 v8, vcc, 0x7901000, v8
	v_add_f32_e32 v13, v20, v13
	v_sub_f32_e32 v20, v6, v22
	v_add_f32_e32 v11, v18, v11
	v_add_u32_e32 v18, 3, v101
	v_addc_co_u32_e32 v9, vcc, 0, v9, vcc
	s_movk_i32 s0, 0x3ff0
	v_add_f32_e32 v14, v20, v14
	v_sub_f32_e32 v20, v7, v23
	v_sub_f32_e32 v16, v0, v16
	v_sub_f32_e32 v17, v1, v17
	v_cmp_lt_u32_e32 vcc, s0, v18
	v_add_f32_e32 v15, v20, v15
	v_add_f32_e32 v16, v16, v33
	v_add_f32_e32 v17, v17, v32
	v_fma_f32 v12, v12, 0.5, -v4
	v_fma_f32 v13, v13, 0.5, -v5
	s_andn2_b64 s[0:1], s[8:9], exec
	s_and_b64 s[8:9], vcc, exec
	v_fma_f32 v14, v14, 0.5, -v6
	v_fma_f32 v15, v15, 0.5, -v7
	v_fma_f32 v16, v16, 0.5, -v0
	v_fma_f32 v17, v17, 0.5, -v1
	v_fma_f32 v19, v10, 0.5, -v2
	v_fma_f32 v20, v11, 0.5, -v3
	v_cvt_pk_bf16_f32 v10, v12, v13
	v_cvt_pk_bf16_f32 v11, v14, v15
	v_cvt_pk_bf16_f32 v12, v16, v17
	v_cvt_pk_bf16_f32 v13, v19, v20
	global_store_dwordx4 v[8:9], v[10:13], off offset:3072
	s_or_b64 s[8:9], s[0:1], s[8:9]
	v_mov_b64_e32 v[8:9], v[76:77]
	s_or_b64 exec, exec, s[2:3]
	s_and_saveexec_b64 s[0:1], s[8:9]
	s_cbranch_execz .LBB0_319
.LBB0_411:
	v_add_u32_e32 v10, s7, v101
	v_add_u32_e32 v10, 0xffffc012, v10
	v_mov_b32_e32 v11, v97
	v_lshlrev_b64 v[10:11], 11, v[10:11]
	v_lshl_add_u64 v[10:11], s[60:61], 0, v[10:11]
	v_lshl_add_u64 v[8:9], v[8:9], 2, v[10:11]
	global_store_dwordx4 v[8:9], v[4:7], off
	global_store_dwordx4 v[8:9], v[0:3], off offset:16
	s_branch .LBB0_319

; template <int W>
; __device__ __forceinline__ void pool_items(const Params& p, int l, bool sample, int b, int c, int g, long row0, int tid) {
;     ...
;         const int tl = it >> 4, ch = it & 15, col = g * 128 + ch * 8;
;         const long prow = row0 + tl; const int t = sample ? tl : c * 64 + tl;
;         u32x4 raw[W]; f32x4 h0[W], h1[W];
; #pragma unroll
;         for (int i = 0; i < W; ++i) {
;             const int tt = t - i;
;             raw[i] = (u32x4){0u, 0u, 0u, 0u}; h0[i] = (f32x4){0.f, 0.f, 0.f, 0.f}; h1[i] = h0[i];
;             if (tt >= 0) raw[i] = *(const u32x4*)(P + (size_t)(prow - i) * INW + 768 + col);
;             else if (sample) { const float* sp = p.state_pool + (((size_t)l * 8 + b) * 15 + (15 + tt)) * 512 + col; h0[i] = *(const f32x4*)sp; h1[i] = *(const f32x4*)(sp + 4); }
.LBB0_418:
	v_ashrrev_i32_e32 v68, 4, v101
	v_and_b32_e32 v8, 0x78, v100
	v_or_b32_e32 v1, 0x100, v8
	v_ashrrev_i32_e32 v69, 31, v68
	v_lshl_add_u64 v[72:73], s[40:41], 0, v[68:69]
	v_cmp_lt_i32_e32 vcc, -1, v68
	v_mov_b32_e32 v0, 0
	v_lshlrev_b32_e32 v70, 1, v1
	v_mov_b32_e32 v1, 0
	v_mov_b32_e32 v2, 0
	v_mov_b32_e32 v3, 0
	s_and_saveexec_b64 s[14:15], vcc
	s_cbranch_execz .LBB0_420
	v_mov_b64_e32 v[0:1], s[86:87]
	v_mad_u64_u32 v[0:1], s[16:17], v72, s89, v[0:1]
	v_mad_i32_i24 v1, v73, s89, v1
	v_mov_b32_e32 v71, v97
	v_lshl_add_u64 v[0:1], v[0:1], 0, v[70:71]
	v_add_co_u32_e32 v0, vcc, 0xfb00000, v0
	s_nop 1
	v_addc_co_u32_e32 v1, vcc, 0, v1, vcc
	global_load_dwordx4 v[0:3], v[0:1], off offset:1536
.LBB0_420:
	s_or_b64 exec, exec, s[14:15]
	v_cmp_lt_i32_e64 s[44:45], 0, v68
	s_and_saveexec_b64 s[14:15], s[44:45]
	s_xor_b64 s[14:15], exec, s[14:15]
	s_cbranch_execz .LBB0_422
	v_mov_b64_e32 v[4:5], s[86:87]
	v_mad_u64_u32 v[4:5], s[16:17], v72, s89, v[4:5]
	v_mad_i32_i24 v5, v73, s89, v5
	v_mov_b32_e32 v71, v97
	v_lshl_add_u64 v[4:5], v[4:5], 0, v[70:71]
	v_add_co_u32_e32 v4, vcc, 0xfafe000, v4
	s_nop 1
	v_addc_co_u32_e32 v5, vcc, 0, v5, vcc
	global_load_dwordx4 v[4:7], v[4:5], off offset:3072

; template <int W>
; __device__ __forceinline__ void pool_items(const Params& p, int l, bool sample, int b, int c, int g, long row0, int tid) {
;     ...
;         for (int i = 0; i < W; ++i) {
;             const int tt = t - i;
;             raw[i] = (u32x4){0u, 0u, 0u, 0u}; h0[i] = (f32x4){0.f, 0.f, 0.f, 0.f}; h1[i] = h0[i];
;             if (tt >= 0) raw[i] = *(const u32x4*)(P + (size_t)(prow - i) * INW + 768 + col);
;             else if (sample) { const float* sp = p.state_pool + (((size_t)l * 8 + b) * 15 + (15 + tt)) * 512 + col; h0[i] = *(const f32x4*)sp; h1[i] = *(const f32x4*)(sp + 4); }
.LBB0_426:
	s_or_saveexec_b64 s[14:15], s[14:15]
	v_mov_b32_e32 v24, 0
	v_mov_b32_e32 v25, 0
	v_mov_b32_e32 v26, 0
	v_mov_b32_e32 v27, 0
	s_xor_b64 exec, exec, s[14:15]
	s_cbranch_execz .LBB0_428
	v_mov_b64_e32 v[16:17], s[86:87]
	v_mad_u64_u32 v[16:17], s[16:17], v72, s89, v[16:17]
	v_mad_i32_i24 v17, v73, s89, v17
	v_mov_b32_e32 v71, v97
	v_lshl_add_u64 v[16:17], v[16:17], 0, v[70:71]
	v_add_co_u32_e32 v16, vcc, 0xfafd000, v16
	v_mov_b32_e32 v20, 0
	s_nop 0
	v_addc_co_u32_e32 v17, vcc, 0, v17, vcc
	global_load_dwordx4 v[24:27], v[16:17], off offset:512
	v_mov_b32_e32 v80, 0
	v_mov_b32_e32 v22, v20
	v_mov_b32_e32 v76, v20
	v_mov_b32_e32 v16, v20
	v_mov_b32_e32 v78, v20
	v_mov_b32_e32 v18, v20
	v_mov_b32_e32 v74, v20

; template <int W>
; __device__ __forceinline__ void pool_items(const Params& p, int l, bool sample, int b, int c, int g, long row0, int tid) {
;     ...
;         for (int i = 0; i < W; ++i) {
;             const int tt = t - i;
;             raw[i] = (u32x4){0u, 0u, 0u, 0u}; h0[i] = (f32x4){0.f, 0.f, 0.f, 0.f}; h1[i] = h0[i];
;             if (tt >= 0) raw[i] = *(const u32x4*)(P + (size_t)(prow - i) * INW + 768 + col);
;             else if (sample) { const float* sp = p.state_pool + (((size_t)l * 8 + b) * 15 + (15 + tt)) * 512 + col; h0[i] = *(const f32x4*)sp; h1[i] = *(const f32x4*)(sp + 4); }
.LBB0_430:
	s_or_saveexec_b64 s[14:15], s[14:15]
	v_mov_b32_e32 v28, 0
	v_mov_b32_e32 v29, 0
	v_mov_b32_e32 v30, 0
	v_mov_b32_e32 v31, 0
	s_xor_b64 exec, exec, s[14:15]
	s_cbranch_execz .LBB0_432
	v_mov_b64_e32 v[28:29], s[86:87]
	v_mad_u64_u32 v[28:29], s[16:17], v72, s89, v[28:29]
	v_mad_i32_i24 v29, v73, s89, v29
	v_mov_b32_e32 v71, v97
	v_lshl_add_u64 v[28:29], v[28:29], 0, v[70:71]
	v_add_co_u32_e32 v28, vcc, 0xfafb000, v28
	v_mov_b32_e32 v21, 0
	s_nop 0
	v_addc_co_u32_e32 v29, vcc, 0, v29, vcc
	global_load_dwordx4 v[28:31], v[28:29], off offset:2048
	v_mov_b32_e32 v81, v21
	v_mov_b32_e32 v23, v21
	v_mov_b32_e32 v77, v21
	v_mov_b32_e32 v17, v21
	v_mov_b32_e32 v79, v21
	v_mov_b32_e32 v19, v21
	v_mov_b32_e32 v75, v21

; template <int W>
; __device__ __forceinline__ void pool_items(const Params& p, int l, bool sample, int b, int c, int g, long row0, int tid) {
;     ...
;         for (int i = 0; i < W; ++i) {
;             const int tt = t - i;
;             raw[i] = (u32x4){0u, 0u, 0u, 0u}; h0[i] = (f32x4){0.f, 0.f, 0.f, 0.f}; h1[i] = h0[i];
;             if (tt >= 0) raw[i] = *(const u32x4*)(P + (size_t)(prow - i) * INW + 768 + col);
;             else if (sample) { const float* sp = p.state_pool + (((size_t)l * 8 + b) * 15 + (15 + tt)) * 512 + col; h0[i] = *(const f32x4*)sp; h1[i] = *(const f32x4*)(sp + 4); }
.LBB0_434:
	s_or_saveexec_b64 s[14:15], s[14:15]
	v_mov_b32_e32 v40, 0
	v_mov_b32_e32 v41, 0
	v_mov_b32_e32 v42, 0
	v_mov_b32_e32 v43, 0
	s_xor_b64 exec, exec, s[14:15]
	s_cbranch_execz .LBB0_436
	v_mov_b64_e32 v[32:33], s[86:87]
	v_mad_u64_u32 v[32:33], s[16:17], v72, s89, v[32:33]
	v_mad_i32_i24 v33, v73, s89, v33
	v_mov_b32_e32 v71, v97
	v_lshl_add_u64 v[32:33], v[32:33], 0, v[70:71]
	v_add_co_u32_e32 v32, vcc, 0xfaf9000, v32
	v_mov_b32_e32 v36, 0
	s_nop 0
	v_addc_co_u32_e32 v33, vcc, 0, v33, vcc
	global_load_dwordx4 v[40:43], v[32:33], off offset:3584
	v_mov_b32_e32 v88, 0
	v_mov_b32_e32 v38, v36
	v_mov_b32_e32 v84, v36
	v_mov_b32_e32 v32, v36
	v_mov_b32_e32 v86, v36
	v_mov_b32_e32 v34, v36
	v_mov_b32_e32 v82, v36

; template <int W>
; __device__ __forceinline__ void pool_items(const Params& p, int l, bool sample, int b, int c, int g, long row0, int tid) {
;     ...
;         for (int i = 0; i < W; ++i) {
;             const int tt = t - i;
;             raw[i] = (u32x4){0u, 0u, 0u, 0u}; h0[i] = (f32x4){0.f, 0.f, 0.f, 0.f}; h1[i] = h0[i];
;             if (tt >= 0) raw[i] = *(const u32x4*)(P + (size_t)(prow - i) * INW + 768 + col);
;             else if (sample) { const float* sp = p.state_pool + (((size_t)l * 8 + b) * 15 + (15 + tt)) * 512 + col; h0[i] = *(const f32x4*)sp; h1[i] = *(const f32x4*)(sp + 4); }
.LBB0_438:
	s_or_saveexec_b64 s[14:15], s[14:15]
	v_mov_b32_e32 v44, 0
	v_mov_b32_e32 v45, 0
	v_mov_b32_e32 v46, 0
	v_mov_b32_e32 v47, 0
	s_xor_b64 exec, exec, s[14:15]
	s_cbranch_execz .LBB0_440
	v_mov_b64_e32 v[44:45], s[86:87]
	v_mad_u64_u32 v[44:45], s[16:17], v72, s89, v[44:45]
	v_mad_i32_i24 v45, v73, s89, v45
	v_mov_b32_e32 v71, v97
	v_lshl_add_u64 v[44:45], v[44:45], 0, v[70:71]
	v_add_co_u32_e32 v44, vcc, 0xfaf8000, v44
	v_mov_b32_e32 v37, 0
	s_nop 0
	v_addc_co_u32_e32 v45, vcc, 0, v45, vcc
	global_load_dwordx4 v[44:47], v[44:45], off offset:1024
	v_mov_b32_e32 v89, v37
	v_mov_b32_e32 v39, v37
	v_mov_b32_e32 v85, v37
	v_mov_b32_e32 v33, v37
	v_mov_b32_e32 v87, v37
	v_mov_b32_e32 v35, v37
	v_mov_b32_e32 v83, v37

; template <int W>
; __device__ __forceinline__ void pool_items(const Params& p, int l, bool sample, int b, int c, int g, long row0, int tid) {
;     ...
;         for (int i = 0; i < W; ++i) {
;             const int tt = t - i;
;             raw[i] = (u32x4){0u, 0u, 0u, 0u}; h0[i] = (f32x4){0.f, 0.f, 0.f, 0.f}; h1[i] = h0[i];
;             if (tt >= 0) raw[i] = *(const u32x4*)(P + (size_t)(prow - i) * INW + 768 + col);
;             else if (sample) { const float* sp = p.state_pool + (((size_t)l * 8 + b) * 15 + (15 + tt)) * 512 + col; h0[i] = *(const f32x4*)sp; h1[i] = *(const f32x4*)(sp + 4); }
.LBB0_442:
	s_or_saveexec_b64 s[14:15], s[14:15]
	v_mov_b32_e32 v56, 0
	v_mov_b32_e32 v57, 0
	v_mov_b32_e32 v58, 0
	v_mov_b32_e32 v59, 0
	s_xor_b64 exec, exec, s[14:15]
	s_cbranch_execz .LBB0_444
	v_mov_b64_e32 v[48:49], s[86:87]
	v_mad_u64_u32 v[48:49], s[16:17], v72, s89, v[48:49]
	v_mad_i32_i24 v49, v73, s89, v49
	v_mov_b32_e32 v71, v97
	v_lshl_add_u64 v[48:49], v[48:49], 0, v[70:71]
	v_add_co_u32_e32 v48, vcc, 0xfaf6000, v48
	v_mov_b32_e32 v52, 0
	s_nop 0
	v_addc_co_u32_e32 v49, vcc, 0, v49, vcc
	global_load_dwordx4 v[56:59], v[48:49], off offset:2560
	v_mov_b32_e32 v98, 0
	v_mov_b32_e32 v54, v52
	v_mov_b32_e32 v92, v52
	v_mov_b32_e32 v48, v52
	v_mov_b32_e32 v94, v52
	v_mov_b32_e32 v50, v52
	v_mov_b32_e32 v90, v52

; __device__ __forceinline__ void unpack8(const u32x4 w, float* f) { f[0] = bf_lo(w.x); f[1] = bf_hi(w.x); f[2] = bf_lo(w.y); f[3] = bf_hi(w.y); f[4] = bf_lo(w.z); f[5] = bf_hi(w.z); f[6] = bf_lo(w.w); f[7] = bf_hi(w.w); }
; __device__ __forceinline__ u32x4 pack8(const float* f) { u32x4 w; w.x = cvt_pk_bf16(f[0], f[1]); w.y = cvt_pk_bf16(f[2], f[3]); w.z = cvt_pk_bf16(f[4], f[5]); w.w = cvt_pk_bf16(f[6], f[7]); return w; }
; template <int W>
; __device__ __forceinline__ void pool_items(const Params& p, int l, bool sample, int b, int c, int g, long row0, int tid) {
;     ...
;             if (tt >= 0) raw[i] = *(const u32x4*)(P + (size_t)(prow - i) * INW + 768 + col);
;             else if (sample) { const float* sp = p.state_pool + (((size_t)l * 8 + b) * 15 + (15 + tt)) * 512 + col; h0[i] = *(const f32x4*)sp; h1[i] = *(const f32x4*)(sp + 4); }
;         }
;         float cur[8], a[8];
;         unpack8(raw[0], cur);
; #pragma unroll
;         for (int k = 0; k < 8; ++k) a[k] = cur[k];
; #pragma unroll
;         for (int i = 1; i < W; ++i) { float x[8]; unpack8(raw[i], x);
; #pragma unroll
;             for (int k = 0; k < 4; ++k) { a[k] += x[k] + h0[i][k]; a[4 + k] += x[4 + k] + h1[i][k]; } }
;         const float cnt = sample ? (float)W : (float)((t + 1) < W ? (t + 1) : W);
;         const float inv = 1.0f / cnt;
;         float d[8];
; #pragma unroll
;         for (int k = 0; k < 8; ++k) d[k] = a[k] * inv - cur[k];
;         *(u32x4*)(AD + (size_t)prow * DM + 512 + col) = pack8(d);
;         float* pd = nullptr;
;         if (!sample) { if (t >= SEQ - 15) pd = p.out + O_PP + (((size_t)l * 2 + b) * 15 + (t - (SEQ - 15))) * 512 + col; }
;         else if (tl >= 1) pd = p.out + O_PS + (((size_t)l * 8 + b) * 15 + (tl - 1)) * 512 + col;
;         if (pd) { *(f32x4*)pd = (f32x4){cur[0], cur[1], cur[2], cur[3]}; *(f32x4*)(pd + 4) = (f32x4){cur[4], cur[5], cur[6], cur[7]}; }
.LBB0_446:
	s_or_saveexec_b64 s[14:15], s[14:15]
	v_mov_b32_e32 v64, 0
	v_mov_b32_e32 v65, 0
	v_mov_b32_e32 v66, 0
	v_mov_b32_e32 v67, 0
	s_xor_b64 exec, exec, s[14:15]
	s_cbranch_execz .LBB0_448
	v_mov_b64_e32 v[60:61], s[86:87]
	v_mad_u64_u32 v[60:61], s[16:17], v72, s89, v[60:61]
	v_mad_i32_i24 v61, v73, s89, v61
	v_mov_b32_e32 v71, v97
	v_lshl_add_u64 v[60:61], v[60:61], 0, v[70:71]
	v_add_co_u32_e32 v60, vcc, 0xfaf5000, v60
	v_mov_b32_e32 v53, 0
	s_nop 0
	v_addc_co_u32_e32 v61, vcc, 0, v61, vcc
	global_load_dwordx4 v[64:67], v[60:61], off
	v_mov_b32_e32 v99, v53
	v_mov_b32_e32 v55, v53
	v_mov_b32_e32 v93, v53
	v_mov_b32_e32 v49, v53
	v_mov_b32_e32 v95, v53
	v_mov_b32_e32 v51, v53
	v_mov_b32_e32 v91, v53
.LBB0_448:
	s_or_b64 exec, exec, s[14:15]
	s_waitcnt vmcnt(0) lgkmcnt(0)
	v_lshlrev_b32_e32 v69, 16, v4
	v_and_b32_e32 v4, 0xffff0000, v4
	v_and_b32_e32 v61, 0xffff0000, v0
	v_lshlrev_b32_e32 v102, 16, v6
	v_and_b32_e32 v6, 0xffff0000, v6
	v_add_f32_e32 v4, v9, v4
	v_lshlrev_b32_e32 v62, 16, v1
	v_and_b32_e32 v63, 0xffff0000, v1
	v_and_b32_e32 v1, 0xffff0000, v2
	v_lshlrev_b32_e32 v71, 16, v5
	v_add_f32_e32 v9, v4, v61
	v_add_f32_e32 v4, v13, v6
	v_lshlrev_b32_e32 v103, 16, v7
	v_add_f32_e32 v6, v4, v1
	v_add_f32_e32 v4, v10, v71
	v_lshlrev_b32_e32 v60, 16, v0
	v_lshlrev_b32_e32 v0, 16, v2
	v_lshlrev_b32_e32 v2, 16, v3
	v_and_b32_e32 v5, 0xffff0000, v5
	v_add_f32_e32 v10, v4, v62
	v_add_f32_e32 v4, v14, v103
	v_and_b32_e32 v7, 0xffff0000, v7
	v_add_f32_e32 v13, v4, v2
	v_add_f32_e32 v4, v11, v5
	v_and_b32_e32 v3, 0xffff0000, v3
	v_add_f32_e32 v11, v4, v63
	v_add_f32_e32 v4, v15, v7
	v_add_f32_e32 v8, v8, v69
	v_add_f32_e32 v7, v4, v3
	v_lshlrev_b32_e32 v5, 16, v28
	v_lshlrev_b32_e32 v4, 16, v24
	v_add_f32_e32 v8, v8, v60
	v_pk_add_f32 v[4:5], v[20:21], v[4:5]
	v_add_f32_e32 v12, v12, v102
	v_add_f32_e32 v4, v8, v4
	v_add_f32_e32 v8, v4, v5
	v_lshlrev_b32_e32 v5, 16, v30
	v_lshlrev_b32_e32 v4, 16, v26
	v_add_f32_e32 v12, v12, v0
	v_pk_add_f32 v[4:5], v[16:17], v[4:5]
	s_mov_b32 s7, 0x3e000000
	v_add_f32_e32 v4, v12, v4
	v_add_f32_e32 v12, v4, v5
	v_and_b32_e32 v5, 0xffff0000, v28
	v_and_b32_e32 v4, 0xffff0000, v24
	v_pk_add_f32 v[4:5], v[80:81], v[4:5]
	v_mov_b32_e32 v71, v97
	v_add_f32_e32 v4, v9, v4
	v_add_f32_e32 v9, v4, v5
	v_and_b32_e32 v5, 0xffff0000, v30
	v_and_b32_e32 v4, 0xffff0000, v26
	v_pk_add_f32 v[4:5], v[78:79], v[4:5]
	s_nop 0
	v_add_f32_e32 v4, v6, v4
	v_add_f32_e32 v6, v4, v5
	v_lshlrev_b32_e32 v4, 16, v25
	v_lshlrev_b32_e32 v5, 16, v29
	v_pk_add_f32 v[4:5], v[22:23], v[4:5]
	s_nop 0
	v_add_f32_e32 v4, v10, v4
	v_add_f32_e32 v10, v4, v5
	v_lshlrev_b32_e32 v4, 16, v27
	v_lshlrev_b32_e32 v5, 16, v31
	v_pk_add_f32 v[4:5], v[18:19], v[4:5]
	s_nop 0
	v_add_f32_e32 v4, v13, v4
	v_add_f32_e32 v13, v4, v5
	v_and_b32_e32 v5, 0xffff0000, v29
	v_and_b32_e32 v4, 0xffff0000, v25
	v_pk_add_f32 v[4:5], v[76:77], v[4:5]
	s_nop 0
	v_add_f32_e32 v4, v11, v4
	v_add_f32_e32 v11, v4, v5
	v_and_b32_e32 v5, 0xffff0000, v31
	v_and_b32_e32 v4, 0xffff0000, v27
	v_pk_add_f32 v[4:5], v[74:75], v[4:5]
	s_nop 0
	v_add_f32_e32 v4, v7, v4
	v_add_f32_e32 v7, v4, v5
	v_lshlrev_b32_e32 v5, 16, v44
	v_lshlrev_b32_e32 v4, 16, v40
	v_pk_add_f32 v[4:5], v[36:37], v[4:5]
	s_nop 0
	v_add_f32_e32 v4, v8, v4
	v_add_f32_e32 v8, v4, v5
	v_lshlrev_b32_e32 v5, 16, v46
	v_lshlrev_b32_e32 v4, 16, v42
	v_pk_add_f32 v[4:5], v[32:33], v[4:5]
	s_nop 0
	v_add_f32_e32 v4, v12, v4
	v_add_f32_e32 v12, v4, v5
	v_and_b32_e32 v5, 0xffff0000, v44
	v_and_b32_e32 v4, 0xffff0000, v40
	v_pk_add_f32 v[4:5], v[88:89], v[4:5]
	s_nop 0
	v_add_f32_e32 v4, v9, v4
	v_add_f32_e32 v9, v4, v5
	v_and_b32_e32 v5, 0xffff0000, v46
	v_and_b32_e32 v4, 0xffff0000, v42
	v_pk_add_f32 v[4:5], v[86:87], v[4:5]
	s_nop 0
	v_add_f32_e32 v4, v6, v4
	v_add_f32_e32 v6, v4, v5
	v_lshlrev_b32_e32 v4, 16, v41
	v_lshlrev_b32_e32 v5, 16, v45
	v_pk_add_f32 v[4:5], v[38:39], v[4:5]
	s_nop 0
	v_add_f32_e32 v4, v10, v4
	v_add_f32_e32 v10, v4, v5
	v_lshlrev_b32_e32 v4, 16, v43
	v_lshlrev_b32_e32 v5, 16, v47
	v_pk_add_f32 v[4:5], v[34:35], v[4:5]
	s_nop 0
	v_add_f32_e32 v4, v13, v4
	v_add_f32_e32 v13, v4, v5
	v_and_b32_e32 v5, 0xffff0000, v45
	v_and_b32_e32 v4, 0xffff0000, v41
	v_pk_add_f32 v[4:5], v[84:85], v[4:5]
	s_nop 0
	v_add_f32_e32 v4, v11, v4
	v_add_f32_e32 v11, v4, v5
	v_and_b32_e32 v5, 0xffff0000, v47
	v_and_b32_e32 v4, 0xffff0000, v43
	v_pk_add_f32 v[4:5], v[82:83], v[4:5]
	s_nop 0
	v_add_f32_e32 v4, v7, v4
	v_add_f32_e32 v7, v4, v5
	v_lshlrev_b32_e32 v5, 16, v64
	v_lshlrev_b32_e32 v4, 16, v56
	v_pk_add_f32 v[4:5], v[52:53], v[4:5]
	s_nop 0
	v_add_f32_e32 v4, v8, v4
	v_add_f32_e32 v8, v4, v5
	v_lshlrev_b32_e32 v5, 16, v66
	v_lshlrev_b32_e32 v4, 16, v58
	v_pk_add_f32 v[4:5], v[48:49], v[4:5]
	s_nop 0
	v_add_f32_e32 v4, v12, v4
	v_add_f32_e32 v12, v4, v5
	v_and_b32_e32 v5, 0xffff0000, v64
	v_and_b32_e32 v4, 0xffff0000, v56
	v_pk_add_f32 v[4:5], v[98:99], v[4:5]
	s_nop 0
	v_add_f32_e32 v4, v9, v4
	v_add_f32_e32 v9, v4, v5
	v_and_b32_e32 v5, 0xffff0000, v66
	v_and_b32_e32 v4, 0xffff0000, v58
	v_pk_add_f32 v[4:5], v[94:95], v[4:5]
	s_nop 0
	v_add_f32_e32 v4, v6, v4
	v_add_f32_e32 v6, v4, v5
	v_lshlrev_b32_e32 v4, 16, v57
	v_lshlrev_b32_e32 v5, 16, v65
	v_pk_add_f32 v[4:5], v[54:55], v[4:5]
	v_fma_f32 v6, v6, s7, -v1
	v_add_f32_e32 v4, v10, v4
	v_add_f32_e32 v10, v4, v5
	v_lshlrev_b32_e32 v4, 16, v59
	v_lshlrev_b32_e32 v5, 16, v67
	v_pk_add_f32 v[4:5], v[50:51], v[4:5]
	s_nop 0
	v_add_f32_e32 v4, v13, v4
	v_add_f32_e32 v13, v4, v5
	v_and_b32_e32 v5, 0xffff0000, v65
	v_and_b32_e32 v4, 0xffff0000, v57
	v_pk_add_f32 v[4:5], v[92:93], v[4:5]
	s_nop 0
	v_add_f32_e32 v4, v11, v4
	v_add_f32_e32 v11, v4, v5
	v_and_b32_e32 v5, 0xffff0000, v67
	v_and_b32_e32 v4, 0xffff0000, v59
	v_pk_add_f32 v[4:5], v[90:91], v[4:5]
	s_nop 0
	v_add_f32_e32 v4, v7, v4
	v_add_f32_e32 v4, v4, v5
	v_fma_f32 v5, v8, s7, -v60
	v_fma_f32 v7, v9, s7, -v61
	v_fma_f32 v8, v10, s7, -v62
	v_fma_f32 v9, v11, s7, -v63
	v_fma_f32 v10, v12, s7, -v0
	v_fma_f32 v12, v4, s7, -v3
	v_cvt_pk_bf16_f32 v4, v5, v7
	v_cvt_pk_bf16_f32 v5, v8, v9
	v_lshlrev_b64 v[8:9], 11, v[72:73]
	v_lshl_add_u64 v[8:9], s[86:87], 0, v[8:9]
	v_lshl_add_u64 v[8:9], v[8:9], 0, v[70:71]
	v_add_co_u32_e32 v8, vcc, 0x7900000, v8
	v_fma_f32 v11, v13, s7, -v2
	s_nop 0
	v_addc_co_u32_e32 v9, vcc, 0, v9, vcc
	v_cvt_pk_bf16_f32 v6, v10, v6
	v_cvt_pk_bf16_f32 v7, v11, v12
	global_store_dwordx4 v[8:9], v[4:7], off offset:1024
	s_and_saveexec_b64 s[14:15], s[44:45]
	s_cbranch_execz .LBB0_417
	v_add_u32_e32 v4, -1, v68
	v_mov_b32_e32 v5, v97
	v_lshl_add_u64 v[4:5], s[2:3], 0, v[4:5]
	v_lshlrev_b64 v[4:5], 11, v[4:5]
	v_lshl_add_u64 v[4:5], s[62:63], 0, v[4:5]
	v_lshl_add_u64 v[4:5], v[4:5], 0, v[96:97]
	global_store_dwordx4 v[4:5], v[60:63], off offset:1024
	global_store_dwordx4 v[4:5], v[0:3], off offset:1040
	s_branch .LBB0_417

; template <int W>
; __device__ __forceinline__ void pool_items(const Params& p, int l, bool sample, int b, int c, int g, long row0, int tid) {
;     ...
;         const int tl = it >> 4, ch = it & 15, col = g * 128 + ch * 8;
;         const long prow = row0 + tl; const int t = sample ? tl : c * 64 + tl;
;         u32x4 raw[W]; f32x4 h0[W], h1[W];
; #pragma unroll
;         for (int i = 0; i < W; ++i) {
;             const int tt = t - i;
;             raw[i] = (u32x4){0u, 0u, 0u, 0u}; h0[i] = (f32x4){0.f, 0.f, 0.f, 0.f}; h1[i] = h0[i];
;             if (tt >= 0) raw[i] = *(const u32x4*)(P + (size_t)(prow - i) * INW + 768 + col);
;             else if (sample) { const float* sp = p.state_pool + (((size_t)l * 8 + b) * 15 + (15 + tt)) * 512 + col; h0[i] = *(const f32x4*)sp; h1[i] = *(const f32x4*)(sp + 4); }
.LBB0_454:
	v_ashrrev_i32_e32 v20, 4, v27
	v_and_b32_e32 v9, 0x78, v26
	v_ashrrev_i32_e32 v21, 31, v20
	v_lshl_add_u64 v[22:23], s[40:41], 0, v[20:21]
	v_cmp_lt_i32_e32 vcc, -1, v20
	v_mov_b32_e32 v0, 0
	v_lshlrev_b32_e32 v96, 1, v9
	v_mov_b32_e32 v1, 0
	v_mov_b32_e32 v2, 0
	v_mov_b32_e32 v3, 0
	s_and_saveexec_b64 s[0:1], vcc
	s_cbranch_execz .LBB0_456
	v_mov_b64_e32 v[0:1], s[86:87]
	v_mad_u64_u32 v[0:1], s[16:17], v22, s89, v[0:1]
	v_mad_i32_i24 v1, v23, s89, v1
	v_lshl_add_u64 v[0:1], v[0:1], 0, v[96:97]
	v_add_co_u32_e32 v0, vcc, 0xfb00000, v0
	s_nop 1
	v_addc_co_u32_e32 v1, vcc, 0, v1, vcc
	global_load_dwordx4 v[0:3], v[0:1], off offset:1536
.LBB0_456:
	s_or_b64 exec, exec, s[0:1]
	v_cmp_lt_i32_e64 s[0:1], 0, v20
	s_and_saveexec_b64 s[16:17], s[0:1]
	s_xor_b64 s[16:17], exec, s[16:17]
	s_cbranch_execz .LBB0_458
	v_mov_b64_e32 v[4:5], s[86:87]
	v_mad_u64_u32 v[4:5], s[44:45], v22, s89, v[4:5]
	v_mad_i32_i24 v5, v23, s89, v5
	v_lshl_add_u64 v[4:5], v[4:5], 0, v[96:97]
	v_add_co_u32_e32 v4, vcc, 0xfafe000, v4
	s_nop 1
	v_addc_co_u32_e32 v5, vcc, 0, v5, vcc
	global_load_dwordx4 v[4:7], v[4:5], off offset:3072

; __device__ __forceinline__ void unpack8(const u32x4 w, float* f) { f[0] = bf_lo(w.x); f[1] = bf_hi(w.x); f[2] = bf_lo(w.y); f[3] = bf_hi(w.y); f[4] = bf_lo(w.z); f[5] = bf_hi(w.z); f[6] = bf_lo(w.w); f[7] = bf_hi(w.w); }
; __device__ __forceinline__ u32x4 pack8(const float* f) { u32x4 w; w.x = cvt_pk_bf16(f[0], f[1]); w.y = cvt_pk_bf16(f[2], f[3]); w.z = cvt_pk_bf16(f[4], f[5]); w.w = cvt_pk_bf16(f[6], f[7]); return w; }
; template <int W>
; __device__ __forceinline__ void pool_items(const Params& p, int l, bool sample, int b, int c, int g, long row0, int tid) {
;     ...
;         float cur[8], a[8];
;         unpack8(raw[0], cur);
; #pragma unroll
;         for (int k = 0; k < 8; ++k) a[k] = cur[k];
; #pragma unroll
;         for (int i = 1; i < W; ++i) { float x[8]; unpack8(raw[i], x);
; #pragma unroll
;             for (int k = 0; k < 4; ++k) { a[k] += x[k] + h0[i][k]; a[4 + k] += x[4 + k] + h1[i][k]; } }
;         const float cnt = sample ? (float)W : (float)((t + 1) < W ? (t + 1) : W);
;         const float inv = 1.0f / cnt;
;         float d[8];
; #pragma unroll
;         for (int k = 0; k < 8; ++k) d[k] = a[k] * inv - cur[k];
;         *(u32x4*)(AD + (size_t)prow * DM + 512 + col) = pack8(d);
;         float* pd = nullptr;
;         if (!sample) { if (t >= SEQ - 15) pd = p.out + O_PP + (((size_t)l * 2 + b) * 15 + (t - (SEQ - 15))) * 512 + col; }
;         else if (tl >= 1) pd = p.out + O_PS + (((size_t)l * 8 + b) * 15 + (tl - 1)) * 512 + col;
;         if (pd) { *(f32x4*)pd = (f32x4){cur[0], cur[1], cur[2], cur[3]}; *(f32x4*)(pd + 4) = (f32x4){cur[4], cur[5], cur[6], cur[7]}; }
.LBB0_460:
	s_or_b64 exec, exec, s[16:17]
	s_waitcnt vmcnt(0) lgkmcnt(0)
	v_lshlrev_b32_e32 v21, 16, v4
	v_and_b32_e32 v4, 0xffff0000, v4
	v_lshlrev_b32_e32 v25, 16, v5
	v_and_b32_e32 v5, 0xffff0000, v5
	v_lshlrev_b32_e32 v12, 16, v0
	v_and_b32_e32 v13, 0xffff0000, v0
	v_lshlrev_b32_e32 v14, 16, v1
	v_and_b32_e32 v15, 0xffff0000, v1
	v_add_f32_e32 v8, v8, v21
	v_add_f32_e32 v4, v9, v4
	v_add_f32_e32 v9, v10, v25
	v_add_f32_e32 v5, v11, v5
	v_add_f32_e32 v8, v8, v12
	v_add_f32_e32 v4, v4, v13
	v_add_f32_e32 v9, v9, v14
	v_add_f32_e32 v5, v5, v15
	v_fma_f32 v8, v8, 0.5, -v12
	v_fma_f32 v4, v4, 0.5, -v13
	v_fma_f32 v9, v9, 0.5, -v14
	v_fma_f32 v5, v5, 0.5, -v15
	v_cvt_pk_bf16_f32 v4, v8, v4
	v_cvt_pk_bf16_f32 v5, v9, v5
	v_lshlrev_b64 v[8:9], 11, v[22:23]
	v_lshlrev_b32_e32 v28, 16, v6
	v_and_b32_e32 v6, 0xffff0000, v6
	v_lshlrev_b32_e32 v29, 16, v7
	v_and_b32_e32 v7, 0xffff0000, v7
	v_lshl_add_u64 v[8:9], s[86:87], 0, v[8:9]
	v_lshlrev_b32_e32 v0, 16, v2
	v_and_b32_e32 v1, 0xffff0000, v2
	v_lshlrev_b32_e32 v2, 16, v3
	v_and_b32_e32 v3, 0xffff0000, v3
	v_add_f32_e32 v6, v17, v6
	v_add_f32_e32 v7, v19, v7
	v_lshl_add_u64 v[8:9], v[8:9], 0, v[96:97]
	v_add_f32_e32 v16, v16, v28
	v_add_f32_e32 v6, v6, v1
	v_add_f32_e32 v10, v18, v29
	v_add_f32_e32 v7, v7, v3
	v_add_co_u32_e32 v8, vcc, 0x7900000, v8
	v_add_f32_e32 v16, v16, v0
	v_add_f32_e32 v10, v10, v2
	v_fma_f32 v6, v6, 0.5, -v1
	v_fma_f32 v7, v7, 0.5, -v3
	v_addc_co_u32_e32 v9, vcc, 0, v9, vcc
	v_fma_f32 v11, v16, 0.5, -v0
	v_fma_f32 v10, v10, 0.5, -v2
	v_cvt_pk_bf16_f32 v6, v11, v6
	v_cvt_pk_bf16_f32 v7, v10, v7
	global_store_dwordx4 v[8:9], v[4:7], off offset:1024
	s_and_saveexec_b64 s[16:17], s[0:1]
	s_cbranch_execz .LBB0_453
	v_add_u32_e32 v96, -1, v20
	v_lshl_add_u64 v[4:5], s[2:3], 0, v[96:97]
	v_lshlrev_b64 v[4:5], 11, v[4:5]
	v_lshl_add_u64 v[4:5], s[62:63], 0, v[4:5]
	v_mov_b32_e32 v25, v97
	v_lshl_add_u64 v[4:5], v[4:5], 0, v[24:25]
	global_store_dwordx4 v[4:5], v[12:15], off
	global_store_dwordx4 v[4:5], v[0:3], off offset:16
	s_branch .LBB0_453

; template <int W>
; __device__ __forceinline__ void pool_items(const Params& p, int l, bool sample, int b, int c, int g, long row0, int tid) {
;     ...
;         const int tl = it >> 4, ch = it & 15, col = g * 128 + ch * 8;
;         const long prow = row0 + tl; const int t = sample ? tl : c * 64 + tl;
;         u32x4 raw[W]; f32x4 h0[W], h1[W];
; #pragma unroll
;         for (int i = 0; i < W; ++i) {
;             const int tt = t - i;
;             raw[i] = (u32x4){0u, 0u, 0u, 0u}; h0[i] = (f32x4){0.f, 0.f, 0.f, 0.f}; h1[i] = h0[i];
;             if (tt >= 0) raw[i] = *(const u32x4*)(P + (size_t)(prow - i) * INW + 768 + col);
;             else if (sample) { const float* sp = p.state_pool + (((size_t)l * 8 + b) * 15 + (15 + tt)) * 512 + col; h0[i] = *(const f32x4*)sp; h1[i] = *(const f32x4*)(sp + 4); }
.LBB0_467:
	v_ashrrev_i32_e32 v158, 4, v211
	v_and_b32_e32 v8, 0x78, v210
	v_or_b32_e32 v1, 0x180, v8
	v_ashrrev_i32_e32 v159, 31, v158
	v_lshl_add_u64 v[162:163], s[40:41], 0, v[158:159]
	v_cmp_lt_i32_e32 vcc, -1, v158
	v_mov_b32_e32 v0, 0
	v_lshlrev_b32_e32 v160, 1, v1
	v_mov_b32_e32 v1, 0
	v_mov_b32_e32 v2, 0
	v_mov_b32_e32 v3, 0
	s_and_saveexec_b64 s[12:13], vcc
	s_cbranch_execz .LBB0_469
	v_mov_b64_e32 v[0:1], s[86:87]
	v_mad_u64_u32 v[0:1], s[14:15], v162, s89, v[0:1]
	v_mad_i32_i24 v1, v163, s89, v1
	v_mov_b32_e32 v161, v97
	v_lshl_add_u64 v[0:1], v[0:1], 0, v[160:161]
	v_add_co_u32_e32 v0, vcc, 0xfb00000, v0
	s_nop 1
	v_addc_co_u32_e32 v1, vcc, 0, v1, vcc
	global_load_dwordx4 v[0:3], v[0:1], off offset:1536
.LBB0_469:
	s_or_b64 exec, exec, s[12:13]
	v_cmp_lt_i32_e64 s[44:45], 0, v158
	s_and_saveexec_b64 s[12:13], s[44:45]
	s_xor_b64 s[12:13], exec, s[12:13]
	s_cbranch_execz .LBB0_471
	v_mov_b64_e32 v[4:5], s[86:87]
	v_mad_u64_u32 v[4:5], s[14:15], v162, s89, v[4:5]
	v_mad_i32_i24 v5, v163, s89, v5
	v_mov_b32_e32 v161, v97
	v_lshl_add_u64 v[4:5], v[4:5], 0, v[160:161]
	v_add_co_u32_e32 v4, vcc, 0xfafe000, v4
	s_nop 1
	v_addc_co_u32_e32 v5, vcc, 0, v5, vcc
	global_load_dwordx4 v[4:7], v[4:5], off offset:3072

; template <int W>
; __device__ __forceinline__ void pool_items(const Params& p, int l, bool sample, int b, int c, int g, long row0, int tid) {
;     ...
;         for (int i = 0; i < W; ++i) {
;             const int tt = t - i;
;             raw[i] = (u32x4){0u, 0u, 0u, 0u}; h0[i] = (f32x4){0.f, 0.f, 0.f, 0.f}; h1[i] = h0[i];
;             if (tt >= 0) raw[i] = *(const u32x4*)(P + (size_t)(prow - i) * INW + 768 + col);
;             else if (sample) { const float* sp = p.state_pool + (((size_t)l * 8 + b) * 15 + (15 + tt)) * 512 + col; h0[i] = *(const f32x4*)sp; h1[i] = *(const f32x4*)(sp + 4); }
.LBB0_475:
	s_or_saveexec_b64 s[12:13], s[12:13]
	v_mov_b32_e32 v24, 0
	v_mov_b32_e32 v25, 0
	v_mov_b32_e32 v26, 0
	v_mov_b32_e32 v27, 0
	s_xor_b64 exec, exec, s[12:13]
	s_cbranch_execz .LBB0_477
	s_waitcnt vmcnt(0)
	v_mov_b64_e32 v[16:17], s[86:87]
	v_mad_u64_u32 v[16:17], s[14:15], v162, s89, v[16:17]
	v_mad_i32_i24 v17, v163, s89, v17
	v_mov_b32_e32 v161, v97
	v_lshl_add_u64 v[16:17], v[16:17], 0, v[160:161]
	v_add_co_u32_e32 v16, vcc, 0xfafd000, v16
	s_nop 1
	v_addc_co_u32_e32 v17, vcc, 0, v17, vcc
	global_load_dwordx4 v[24:27], v[16:17], off offset:512
	v_mov_b32_e32 v16, 0
	v_mov_b32_e32 v17, v16
	v_mov_b32_e32 v18, v16
	v_mov_b32_e32 v19, v16
	v_mov_b32_e32 v20, v16
	v_mov_b32_e32 v21, v16
	v_mov_b32_e32 v22, v16
	v_mov_b32_e32 v23, v16

; template <int W>
; __device__ __forceinline__ void pool_items(const Params& p, int l, bool sample, int b, int c, int g, long row0, int tid) {
;     ...
;         for (int i = 0; i < W; ++i) {
;             const int tt = t - i;
;             raw[i] = (u32x4){0u, 0u, 0u, 0u}; h0[i] = (f32x4){0.f, 0.f, 0.f, 0.f}; h1[i] = h0[i];
;             if (tt >= 0) raw[i] = *(const u32x4*)(P + (size_t)(prow - i) * INW + 768 + col);
;             else if (sample) { const float* sp = p.state_pool + (((size_t)l * 8 + b) * 15 + (15 + tt)) * 512 + col; h0[i] = *(const f32x4*)sp; h1[i] = *(const f32x4*)(sp + 4); }
.LBB0_479:
	s_or_saveexec_b64 s[12:13], s[12:13]
	v_mov_b32_e32 v36, 0
	v_mov_b32_e32 v37, 0
	v_mov_b32_e32 v38, 0
	v_mov_b32_e32 v39, 0
	s_xor_b64 exec, exec, s[12:13]
	s_cbranch_execz .LBB0_481
	s_waitcnt vmcnt(0)
	v_mov_b64_e32 v[28:29], s[86:87]
	v_mad_u64_u32 v[28:29], s[14:15], v162, s89, v[28:29]
	v_mad_i32_i24 v29, v163, s89, v29
	v_mov_b32_e32 v161, v97
	v_lshl_add_u64 v[28:29], v[28:29], 0, v[160:161]
	v_add_co_u32_e32 v28, vcc, 0xfafb000, v28
	s_nop 1
	v_addc_co_u32_e32 v29, vcc, 0, v29, vcc
	global_load_dwordx4 v[36:39], v[28:29], off offset:2048
	v_mov_b32_e32 v28, 0
	v_mov_b32_e32 v29, v28
	v_mov_b32_e32 v30, v28
	v_mov_b32_e32 v31, v28
	v_mov_b32_e32 v32, v28
	v_mov_b32_e32 v33, v28
	v_mov_b32_e32 v34, v28
	v_mov_b32_e32 v35, v28

; template <int W>
; __device__ __forceinline__ void pool_items(const Params& p, int l, bool sample, int b, int c, int g, long row0, int tid) {
;     ...
;         for (int i = 0; i < W; ++i) {
;             const int tt = t - i;
;             raw[i] = (u32x4){0u, 0u, 0u, 0u}; h0[i] = (f32x4){0.f, 0.f, 0.f, 0.f}; h1[i] = h0[i];
;             if (tt >= 0) raw[i] = *(const u32x4*)(P + (size_t)(prow - i) * INW + 768 + col);
;             else if (sample) { const float* sp = p.state_pool + (((size_t)l * 8 + b) * 15 + (15 + tt)) * 512 + col; h0[i] = *(const f32x4*)sp; h1[i] = *(const f32x4*)(sp + 4); }
.LBB0_483:
	s_or_saveexec_b64 s[12:13], s[12:13]
	v_mov_b32_e32 v48, 0
	v_mov_b32_e32 v49, 0
	v_mov_b32_e32 v50, 0
	v_mov_b32_e32 v51, 0
	s_xor_b64 exec, exec, s[12:13]
	s_cbranch_execz .LBB0_485
	s_waitcnt vmcnt(0)
	v_mov_b64_e32 v[40:41], s[86:87]
	v_mad_u64_u32 v[40:41], s[14:15], v162, s89, v[40:41]
	v_mad_i32_i24 v41, v163, s89, v41
	v_mov_b32_e32 v161, v97
	v_lshl_add_u64 v[40:41], v[40:41], 0, v[160:161]
	v_add_co_u32_e32 v40, vcc, 0xfaf9000, v40
	s_nop 1
	v_addc_co_u32_e32 v41, vcc, 0, v41, vcc
	global_load_dwordx4 v[48:51], v[40:41], off offset:3584
	v_mov_b32_e32 v40, 0
	v_mov_b32_e32 v41, v40
	v_mov_b32_e32 v42, v40
	v_mov_b32_e32 v43, v40
	v_mov_b32_e32 v44, v40
	v_mov_b32_e32 v45, v40
	v_mov_b32_e32 v46, v40
	v_mov_b32_e32 v47, v40

; template <int W>
; __device__ __forceinline__ void pool_items(const Params& p, int l, bool sample, int b, int c, int g, long row0, int tid) {
;     ...
;         for (int i = 0; i < W; ++i) {
;             const int tt = t - i;
;             raw[i] = (u32x4){0u, 0u, 0u, 0u}; h0[i] = (f32x4){0.f, 0.f, 0.f, 0.f}; h1[i] = h0[i];
;             if (tt >= 0) raw[i] = *(const u32x4*)(P + (size_t)(prow - i) * INW + 768 + col);
;             else if (sample) { const float* sp = p.state_pool + (((size_t)l * 8 + b) * 15 + (15 + tt)) * 512 + col; h0[i] = *(const f32x4*)sp; h1[i] = *(const f32x4*)(sp + 4); }
.LBB0_487:
	s_or_saveexec_b64 s[12:13], s[12:13]
	v_mov_b32_e32 v60, 0
	v_mov_b32_e32 v61, 0
	v_mov_b32_e32 v62, 0
	v_mov_b32_e32 v63, 0
	s_xor_b64 exec, exec, s[12:13]
	s_cbranch_execz .LBB0_489
	s_waitcnt vmcnt(0)
	v_mov_b64_e32 v[52:53], s[86:87]
	v_mad_u64_u32 v[52:53], s[14:15], v162, s89, v[52:53]
	v_mad_i32_i24 v53, v163, s89, v53
	v_mov_b32_e32 v161, v97
	v_lshl_add_u64 v[52:53], v[52:53], 0, v[160:161]
	v_add_co_u32_e32 v52, vcc, 0xfaf8000, v52
	s_nop 1
	v_addc_co_u32_e32 v53, vcc, 0, v53, vcc
	global_load_dwordx4 v[60:63], v[52:53], off offset:1024
	v_mov_b32_e32 v52, 0
	v_mov_b32_e32 v53, v52
	v_mov_b32_e32 v54, v52
	v_mov_b32_e32 v55, v52
	v_mov_b32_e32 v56, v52
	v_mov_b32_e32 v57, v52
	v_mov_b32_e32 v58, v52
	v_mov_b32_e32 v59, v52

; template <int W>
; __device__ __forceinline__ void pool_items(const Params& p, int l, bool sample, int b, int c, int g, long row0, int tid) {
;     ...
;         for (int i = 0; i < W; ++i) {
;             const int tt = t - i;
;             raw[i] = (u32x4){0u, 0u, 0u, 0u}; h0[i] = (f32x4){0.f, 0.f, 0.f, 0.f}; h1[i] = h0[i];
;             if (tt >= 0) raw[i] = *(const u32x4*)(P + (size_t)(prow - i) * INW + 768 + col);
;             else if (sample) { const float* sp = p.state_pool + (((size_t)l * 8 + b) * 15 + (15 + tt)) * 512 + col; h0[i] = *(const f32x4*)sp; h1[i] = *(const f32x4*)(sp + 4); }
.LBB0_491:
	s_or_saveexec_b64 s[12:13], s[12:13]
	v_mov_b32_e32 v72, 0
	v_mov_b32_e32 v73, 0
	v_mov_b32_e32 v74, 0
	v_mov_b32_e32 v75, 0
	s_xor_b64 exec, exec, s[12:13]
	s_cbranch_execz .LBB0_493
	s_waitcnt vmcnt(0)
	v_mov_b64_e32 v[64:65], s[86:87]
	v_mad_u64_u32 v[64:65], s[14:15], v162, s89, v[64:65]
	v_mad_i32_i24 v65, v163, s89, v65
	v_mov_b32_e32 v161, v97
	v_lshl_add_u64 v[64:65], v[64:65], 0, v[160:161]
	v_add_co_u32_e32 v64, vcc, 0xfaf6000, v64
	s_nop 1
	v_addc_co_u32_e32 v65, vcc, 0, v65, vcc
	global_load_dwordx4 v[72:75], v[64:65], off offset:2560
	v_mov_b32_e32 v64, 0
	v_mov_b32_e32 v65, v64
	v_mov_b32_e32 v66, v64
	v_mov_b32_e32 v67, v64
	v_mov_b32_e32 v68, v64
	v_mov_b32_e32 v69, v64
	v_mov_b32_e32 v70, v64
	v_mov_b32_e32 v71, v64

; template <int W>
; __device__ __forceinline__ void pool_items(const Params& p, int l, bool sample, int b, int c, int g, long row0, int tid) {
;     ...
;         for (int i = 0; i < W; ++i) {
;             const int tt = t - i;
;             raw[i] = (u32x4){0u, 0u, 0u, 0u}; h0[i] = (f32x4){0.f, 0.f, 0.f, 0.f}; h1[i] = h0[i];
;             if (tt >= 0) raw[i] = *(const u32x4*)(P + (size_t)(prow - i) * INW + 768 + col);
;             else if (sample) { const float* sp = p.state_pool + (((size_t)l * 8 + b) * 15 + (15 + tt)) * 512 + col; h0[i] = *(const f32x4*)sp; h1[i] = *(const f32x4*)(sp + 4); }
.LBB0_495:
	s_or_saveexec_b64 s[12:13], s[12:13]
	v_mov_b32_e32 v84, 0
	v_mov_b32_e32 v85, 0
	v_mov_b32_e32 v86, 0
	v_mov_b32_e32 v87, 0
	s_xor_b64 exec, exec, s[12:13]
	s_cbranch_execz .LBB0_497
	s_waitcnt vmcnt(0)
	v_mov_b64_e32 v[76:77], s[86:87]
	v_mad_u64_u32 v[76:77], s[14:15], v162, s89, v[76:77]
	v_mad_i32_i24 v77, v163, s89, v77
	v_mov_b32_e32 v161, v97
	v_lshl_add_u64 v[76:77], v[76:77], 0, v[160:161]
	v_add_co_u32_e32 v76, vcc, 0xfaf5000, v76
	s_nop 1
	v_addc_co_u32_e32 v77, vcc, 0, v77, vcc
	global_load_dwordx4 v[84:87], v[76:77], off
	v_mov_b32_e32 v76, 0
	v_mov_b32_e32 v77, v76
	v_mov_b32_e32 v78, v76
	v_mov_b32_e32 v79, v76
	v_mov_b32_e32 v80, v76
	v_mov_b32_e32 v81, v76
	v_mov_b32_e32 v82, v76
	v_mov_b32_e32 v83, v76

; template <int W>
; __device__ __forceinline__ void pool_items(const Params& p, int l, bool sample, int b, int c, int g, long row0, int tid) {
;     ...
;         for (int i = 0; i < W; ++i) {
;             const int tt = t - i;
;             raw[i] = (u32x4){0u, 0u, 0u, 0u}; h0[i] = (f32x4){0.f, 0.f, 0.f, 0.f}; h1[i] = h0[i];
;             if (tt >= 0) raw[i] = *(const u32x4*)(P + (size_t)(prow - i) * INW + 768 + col);
;             else if (sample) { const float* sp = p.state_pool + (((size_t)l * 8 + b) * 15 + (15 + tt)) * 512 + col; h0[i] = *(const f32x4*)sp; h1[i] = *(const f32x4*)(sp + 4); }
.LBB0_499:
	s_or_saveexec_b64 s[12:13], s[12:13]
	v_mov_b32_e32 v98, 0
	v_mov_b32_e32 v99, 0
	v_mov_b32_e32 v100, 0
	v_mov_b32_e32 v101, 0
	s_xor_b64 exec, exec, s[12:13]
	s_cbranch_execz .LBB0_501
	v_mov_b64_e32 v[88:89], s[86:87]
	v_mad_u64_u32 v[88:89], s[14:15], v162, s89, v[88:89]
	v_mad_i32_i24 v89, v163, s89, v89
	v_mov_b32_e32 v161, v97
	v_lshl_add_u64 v[88:89], v[88:89], 0, v[160:161]
	v_add_co_u32_e32 v88, vcc, 0xfaf3000, v88
	v_mov_b32_e32 v92, 0
	s_nop 0
	v_addc_co_u32_e32 v89, vcc, 0, v89, vcc
	global_load_dwordx4 v[98:101], v[88:89], off offset:1536
	v_mov_b32_e32 v170, 0
	v_mov_b32_e32 v94, v92
	v_mov_b32_e32 v166, v92
	v_mov_b32_e32 v88, v92
	v_mov_b32_e32 v168, v92
	v_mov_b32_e32 v90, v92
	v_mov_b32_e32 v164, v92

; template <int W>
; __device__ __forceinline__ void pool_items(const Params& p, int l, bool sample, int b, int c, int g, long row0, int tid) {
;     ...
;         for (int i = 0; i < W; ++i) {
;             const int tt = t - i;
;             raw[i] = (u32x4){0u, 0u, 0u, 0u}; h0[i] = (f32x4){0.f, 0.f, 0.f, 0.f}; h1[i] = h0[i];
;             if (tt >= 0) raw[i] = *(const u32x4*)(P + (size_t)(prow - i) * INW + 768 + col);
;             else if (sample) { const float* sp = p.state_pool + (((size_t)l * 8 + b) * 15 + (15 + tt)) * 512 + col; h0[i] = *(const f32x4*)sp; h1[i] = *(const f32x4*)(sp + 4); }
.LBB0_503:
	s_or_saveexec_b64 s[12:13], s[12:13]
	v_mov_b32_e32 v102, 0
	v_mov_b32_e32 v103, 0
	v_mov_b32_e32 v104, 0
	v_mov_b32_e32 v105, 0
	s_xor_b64 exec, exec, s[12:13]
	s_cbranch_execz .LBB0_505
	v_mov_b64_e32 v[102:103], s[86:87]
	v_mad_u64_u32 v[102:103], s[14:15], v162, s89, v[102:103]
	v_mad_i32_i24 v103, v163, s89, v103
	v_mov_b32_e32 v161, v97
	v_lshl_add_u64 v[102:103], v[102:103], 0, v[160:161]
	v_add_co_u32_e32 v102, vcc, 0xfaf1000, v102
	v_mov_b32_e32 v93, 0
	s_nop 0
	v_addc_co_u32_e32 v103, vcc, 0, v103, vcc
	global_load_dwordx4 v[102:105], v[102:103], off offset:3072
	v_mov_b32_e32 v171, v93
	v_mov_b32_e32 v95, v93
	v_mov_b32_e32 v167, v93
	v_mov_b32_e32 v89, v93
	v_mov_b32_e32 v169, v93
	v_mov_b32_e32 v91, v93
	v_mov_b32_e32 v165, v93

; template <int W>
; __device__ __forceinline__ void pool_items(const Params& p, int l, bool sample, int b, int c, int g, long row0, int tid) {
;     ...
;         for (int i = 0; i < W; ++i) {
;             const int tt = t - i;
;             raw[i] = (u32x4){0u, 0u, 0u, 0u}; h0[i] = (f32x4){0.f, 0.f, 0.f, 0.f}; h1[i] = h0[i];
;             if (tt >= 0) raw[i] = *(const u32x4*)(P + (size_t)(prow - i) * INW + 768 + col);
;             else if (sample) { const float* sp = p.state_pool + (((size_t)l * 8 + b) * 15 + (15 + tt)) * 512 + col; h0[i] = *(const f32x4*)sp; h1[i] = *(const f32x4*)(sp + 4); }
.LBB0_507:
	s_or_saveexec_b64 s[12:13], s[12:13]
	v_mov_b32_e32 v114, 0
	v_mov_b32_e32 v115, 0
	v_mov_b32_e32 v116, 0
	v_mov_b32_e32 v117, 0
	s_xor_b64 exec, exec, s[12:13]
	s_cbranch_execz .LBB0_509
	v_mov_b64_e32 v[106:107], s[86:87]
	v_mad_u64_u32 v[106:107], s[14:15], v162, s89, v[106:107]
	v_mad_i32_i24 v107, v163, s89, v107
	v_mov_b32_e32 v161, v97
	v_lshl_add_u64 v[106:107], v[106:107], 0, v[160:161]
	v_add_co_u32_e32 v106, vcc, 0xfaf0000, v106
	v_mov_b32_e32 v110, 0
	s_nop 0
	v_addc_co_u32_e32 v107, vcc, 0, v107, vcc
	global_load_dwordx4 v[114:117], v[106:107], off offset:512
	v_mov_b32_e32 v178, 0
	v_mov_b32_e32 v112, v110
	v_mov_b32_e32 v174, v110
	v_mov_b32_e32 v106, v110
	v_mov_b32_e32 v176, v110
	v_mov_b32_e32 v108, v110
	v_mov_b32_e32 v172, v110

; template <int W>
; __device__ __forceinline__ void pool_items(const Params& p, int l, bool sample, int b, int c, int g, long row0, int tid) {
;     ...
;         for (int i = 0; i < W; ++i) {
;             const int tt = t - i;
;             raw[i] = (u32x4){0u, 0u, 0u, 0u}; h0[i] = (f32x4){0.f, 0.f, 0.f, 0.f}; h1[i] = h0[i];
;             if (tt >= 0) raw[i] = *(const u32x4*)(P + (size_t)(prow - i) * INW + 768 + col);
;             else if (sample) { const float* sp = p.state_pool + (((size_t)l * 8 + b) * 15 + (15 + tt)) * 512 + col; h0[i] = *(const f32x4*)sp; h1[i] = *(const f32x4*)(sp + 4); }
.LBB0_511:
	s_or_saveexec_b64 s[12:13], s[12:13]
	v_mov_b32_e32 v118, 0
	v_mov_b32_e32 v119, 0
	v_mov_b32_e32 v120, 0
	v_mov_b32_e32 v121, 0
	s_xor_b64 exec, exec, s[12:13]
	s_cbranch_execz .LBB0_513
	v_mov_b64_e32 v[118:119], s[86:87]
	v_mad_u64_u32 v[118:119], s[14:15], v162, s89, v[118:119]
	v_mad_i32_i24 v119, v163, s89, v119
	v_mov_b32_e32 v161, v97
	v_lshl_add_u64 v[118:119], v[118:119], 0, v[160:161]
	v_add_co_u32_e32 v118, vcc, 0xfaee000, v118
	v_mov_b32_e32 v111, 0
	s_nop 0
	v_addc_co_u32_e32 v119, vcc, 0, v119, vcc
	global_load_dwordx4 v[118:121], v[118:119], off offset:2048
	v_mov_b32_e32 v179, v111
	v_mov_b32_e32 v113, v111
	v_mov_b32_e32 v175, v111
	v_mov_b32_e32 v107, v111
	v_mov_b32_e32 v177, v111
	v_mov_b32_e32 v109, v111
	v_mov_b32_e32 v173, v111

; template <int W>
; __device__ __forceinline__ void pool_items(const Params& p, int l, bool sample, int b, int c, int g, long row0, int tid) {
;     ...
;         for (int i = 0; i < W; ++i) {
;             const int tt = t - i;
;             raw[i] = (u32x4){0u, 0u, 0u, 0u}; h0[i] = (f32x4){0.f, 0.f, 0.f, 0.f}; h1[i] = h0[i];
;             if (tt >= 0) raw[i] = *(const u32x4*)(P + (size_t)(prow - i) * INW + 768 + col);
;             else if (sample) { const float* sp = p.state_pool + (((size_t)l * 8 + b) * 15 + (15 + tt)) * 512 + col; h0[i] = *(const f32x4*)sp; h1[i] = *(const f32x4*)(sp + 4); }
.LBB0_515:
	s_or_saveexec_b64 s[12:13], s[12:13]
	v_mov_b32_e32 v130, 0
	v_mov_b32_e32 v131, 0
	v_mov_b32_e32 v132, 0
	v_mov_b32_e32 v133, 0
	s_xor_b64 exec, exec, s[12:13]
	s_cbranch_execz .LBB0_517
	v_mov_b64_e32 v[122:123], s[86:87]
	v_mad_u64_u32 v[122:123], s[14:15], v162, s89, v[122:123]
	v_mad_i32_i24 v123, v163, s89, v123
	v_mov_b32_e32 v161, v97
	v_lshl_add_u64 v[122:123], v[122:123], 0, v[160:161]
	v_add_co_u32_e32 v122, vcc, 0xfaec000, v122
	v_mov_b32_e32 v126, 0
	s_nop 0
	v_addc_co_u32_e32 v123, vcc, 0, v123, vcc
	global_load_dwordx4 v[130:133], v[122:123], off offset:3584
	v_mov_b32_e32 v186, 0
	v_mov_b32_e32 v128, v126
	v_mov_b32_e32 v182, v126
	v_mov_b32_e32 v122, v126
	v_mov_b32_e32 v184, v126
	v_mov_b32_e32 v124, v126
	v_mov_b32_e32 v180, v126

; template <int W>
; __device__ __forceinline__ void pool_items(const Params& p, int l, bool sample, int b, int c, int g, long row0, int tid) {
;     ...
;         for (int i = 0; i < W; ++i) {
;             const int tt = t - i;
;             raw[i] = (u32x4){0u, 0u, 0u, 0u}; h0[i] = (f32x4){0.f, 0.f, 0.f, 0.f}; h1[i] = h0[i];
;             if (tt >= 0) raw[i] = *(const u32x4*)(P + (size_t)(prow - i) * INW + 768 + col);
;             else if (sample) { const float* sp = p.state_pool + (((size_t)l * 8 + b) * 15 + (15 + tt)) * 512 + col; h0[i] = *(const f32x4*)sp; h1[i] = *(const f32x4*)(sp + 4); }
.LBB0_519:
	s_or_saveexec_b64 s[12:13], s[12:13]
	v_mov_b32_e32 v134, 0
	v_mov_b32_e32 v135, 0
	v_mov_b32_e32 v136, 0
	v_mov_b32_e32 v137, 0
	s_xor_b64 exec, exec, s[12:13]
	s_cbranch_execz .LBB0_521
	v_mov_b64_e32 v[134:135], s[86:87]
	v_mad_u64_u32 v[134:135], s[14:15], v162, s89, v[134:135]
	v_mad_i32_i24 v135, v163, s89, v135
	v_mov_b32_e32 v161, v97
	v_lshl_add_u64 v[134:135], v[134:135], 0, v[160:161]
	v_add_co_u32_e32 v134, vcc, 0xfaeb000, v134
	v_mov_b32_e32 v127, 0
	s_nop 0
	v_addc_co_u32_e32 v135, vcc, 0, v135, vcc
	global_load_dwordx4 v[134:137], v[134:135], off offset:1024
	v_mov_b32_e32 v187, v127
	v_mov_b32_e32 v129, v127
	v_mov_b32_e32 v183, v127
	v_mov_b32_e32 v123, v127
	v_mov_b32_e32 v185, v127
	v_mov_b32_e32 v125, v127
	v_mov_b32_e32 v181, v127

; template <int W>
; __device__ __forceinline__ void pool_items(const Params& p, int l, bool sample, int b, int c, int g, long row0, int tid) {
;     ...
;         for (int i = 0; i < W; ++i) {
;             const int tt = t - i;
;             raw[i] = (u32x4){0u, 0u, 0u, 0u}; h0[i] = (f32x4){0.f, 0.f, 0.f, 0.f}; h1[i] = h0[i];
;             if (tt >= 0) raw[i] = *(const u32x4*)(P + (size_t)(prow - i) * INW + 768 + col);
;             else if (sample) { const float* sp = p.state_pool + (((size_t)l * 8 + b) * 15 + (15 + tt)) * 512 + col; h0[i] = *(const f32x4*)sp; h1[i] = *(const f32x4*)(sp + 4); }
.LBB0_523:
	s_or_saveexec_b64 s[12:13], s[12:13]
	v_mov_b32_e32 v146, 0
	v_mov_b32_e32 v147, 0
	v_mov_b32_e32 v148, 0
	v_mov_b32_e32 v149, 0
	s_xor_b64 exec, exec, s[12:13]
	s_cbranch_execz .LBB0_525
	v_mov_b64_e32 v[138:139], s[86:87]
	v_mad_u64_u32 v[138:139], s[14:15], v162, s89, v[138:139]
	v_mad_i32_i24 v139, v163, s89, v139
	v_mov_b32_e32 v161, v97
	v_lshl_add_u64 v[138:139], v[138:139], 0, v[160:161]
	v_add_co_u32_e32 v138, vcc, 0xfae9000, v138
	v_mov_b32_e32 v142, 0
	s_nop 0
	v_addc_co_u32_e32 v139, vcc, 0, v139, vcc
	global_load_dwordx4 v[146:149], v[138:139], off offset:2560
	v_mov_b32_e32 v206, 0
	v_mov_b32_e32 v144, v142
	v_mov_b32_e32 v190, v142
	v_mov_b32_e32 v138, v142
	v_mov_b32_e32 v192, v142
	v_mov_b32_e32 v140, v142
	v_mov_b32_e32 v188, v142

; __device__ __forceinline__ void unpack8(const u32x4 w, float* f) { f[0] = bf_lo(w.x); f[1] = bf_hi(w.x); f[2] = bf_lo(w.y); f[3] = bf_hi(w.y); f[4] = bf_lo(w.z); f[5] = bf_hi(w.z); f[6] = bf_lo(w.w); f[7] = bf_hi(w.w); }
; template <int W>
; __device__ __forceinline__ void pool_items(const Params& p, int l, bool sample, int b, int c, int g, long row0, int tid) {
;     ...
;             if (tt >= 0) raw[i] = *(const u32x4*)(P + (size_t)(prow - i) * INW + 768 + col);
;             else if (sample) { const float* sp = p.state_pool + (((size_t)l * 8 + b) * 15 + (15 + tt)) * 512 + col; h0[i] = *(const f32x4*)sp; h1[i] = *(const f32x4*)(sp + 4); }
;         }
;         float cur[8], a[8];
;         unpack8(raw[0], cur);
; #pragma unroll
;         for (int k = 0; k < 8; ++k) a[k] = cur[k];
; #pragma unroll
;         for (int i = 1; i < W; ++i) { float x[8]; unpack8(raw[i], x);
; #pragma unroll
;             for (int k = 0; k < 4; ++k) { a[k] += x[k] + h0[i][k]; a[4 + k] += x[4 + k] + h1[i][k]; } }
.LBB0_527:
	s_or_saveexec_b64 s[12:13], s[12:13]
	v_mov_b32_e32 v154, 0
	v_mov_b32_e32 v155, 0
	v_mov_b32_e32 v156, 0
	v_mov_b32_e32 v157, 0
	s_xor_b64 exec, exec, s[12:13]
	s_cbranch_execz .LBB0_529
	v_mov_b64_e32 v[150:151], s[86:87]
	v_mad_u64_u32 v[150:151], s[14:15], v162, s89, v[150:151]
	v_mad_i32_i24 v151, v163, s89, v151
	v_mov_b32_e32 v161, v97
	v_lshl_add_u64 v[150:151], v[150:151], 0, v[160:161]
	v_add_co_u32_e32 v150, vcc, 0xfae8000, v150
	v_mov_b32_e32 v143, 0
	s_nop 0
	v_addc_co_u32_e32 v151, vcc, 0, v151, vcc
	global_load_dwordx4 v[154:157], v[150:151], off
	v_mov_b32_e32 v207, v143
	v_mov_b32_e32 v145, v143
	v_mov_b32_e32 v191, v143
	v_mov_b32_e32 v139, v143
	v_mov_b32_e32 v193, v143
	v_mov_b32_e32 v141, v143
	v_mov_b32_e32 v189, v143
.LBB0_529:
	s_or_b64 exec, exec, s[12:13]
	s_waitcnt vmcnt(0) lgkmcnt(0)
	v_lshlrev_b32_e32 v159, 16, v4
	v_lshlrev_b32_e32 v161, 16, v5
	v_and_b32_e32 v5, 0xffff0000, v5
	v_lshlrev_b32_e32 v150, 16, v0
	v_lshlrev_b32_e32 v212, 16, v6
	v_and_b32_e32 v6, 0xffff0000, v6
	v_add_f32_e32 v8, v8, v159
	v_add_f32_e32 v5, v11, v5
	v_lshlrev_b32_e32 v11, 16, v24
	v_and_b32_e32 v151, 0xffff0000, v0
	v_lshlrev_b32_e32 v0, 16, v2
	v_and_b32_e32 v4, 0xffff0000, v4
	v_add_f32_e32 v8, v8, v150
	v_add_f32_e32 v12, v12, v212
	v_add_f32_e32 v6, v13, v6
	v_and_b32_e32 v13, 0xffff0000, v24
	v_lshlrev_b32_e32 v24, 16, v26
	v_add_f32_e32 v11, v16, v11
	v_lshlrev_b32_e32 v213, 16, v7
	v_and_b32_e32 v7, 0xffff0000, v7
	v_add_f32_e32 v12, v12, v0
	v_add_f32_e32 v4, v9, v4
	v_add_f32_e32 v8, v8, v11
	v_add_f32_e32 v11, v20, v24
	v_lshlrev_b32_e32 v152, 16, v1
	v_and_b32_e32 v153, 0xffff0000, v1
	v_and_b32_e32 v1, 0xffff0000, v2
	v_add_f32_e32 v4, v4, v151
	v_add_f32_e32 v9, v10, v161
	v_add_f32_e32 v10, v14, v213
	v_add_f32_e32 v7, v15, v7
	v_lshlrev_b32_e32 v14, 16, v25
	v_and_b32_e32 v15, 0xffff0000, v25
	v_and_b32_e32 v25, 0xffff0000, v26
	v_add_f32_e32 v11, v12, v11
	v_add_f32_e32 v12, v17, v13
	v_add_f32_e32 v6, v6, v1
	v_add_f32_e32 v4, v4, v12
	v_add_f32_e32 v12, v21, v25
	v_lshlrev_b32_e32 v2, 16, v3
	v_add_f32_e32 v9, v9, v152
	v_lshlrev_b32_e32 v26, 16, v27
	v_add_f32_e32 v6, v6, v12
	v_add_f32_e32 v12, v18, v14
	v_add_f32_e32 v10, v10, v2
	v_add_f32_e32 v9, v9, v12
	v_add_f32_e32 v12, v22, v26
	v_and_b32_e32 v3, 0xffff0000, v3
	v_add_f32_e32 v5, v5, v153
	v_and_b32_e32 v27, 0xffff0000, v27
	v_add_f32_e32 v10, v10, v12
	v_add_f32_e32 v12, v19, v15
	v_add_f32_e32 v7, v7, v3
	v_add_f32_e32 v5, v5, v12
	v_add_f32_e32 v12, v23, v27
	v_add_f32_e32 v7, v7, v12
	v_lshlrev_b32_e32 v12, 16, v36
	v_lshlrev_b32_e32 v16, 16, v38
	v_add_f32_e32 v12, v28, v12
	v_and_b32_e32 v13, 0xffff0000, v36
	v_add_f32_e32 v8, v8, v12
	v_add_f32_e32 v12, v32, v16
	v_and_b32_e32 v17, 0xffff0000, v38
	v_add_f32_e32 v11, v11, v12
	v_add_f32_e32 v12, v29, v13
	v_lshlrev_b32_e32 v14, 16, v37
	v_add_f32_e32 v4, v4, v12
	v_add_f32_e32 v12, v33, v17
	v_lshlrev_b32_e32 v18, 16, v39
	v_add_f32_e32 v6, v6, v12
	v_add_f32_e32 v12, v30, v14
	v_and_b32_e32 v15, 0xffff0000, v37
	v_add_f32_e32 v9, v9, v12
	v_add_f32_e32 v12, v34, v18
	v_and_b32_e32 v19, 0xffff0000, v39
	v_add_f32_e32 v10, v10, v12
	v_add_f32_e32 v12, v31, v15
	v_add_f32_e32 v5, v5, v12
	v_add_f32_e32 v12, v35, v19
	v_add_f32_e32 v7, v7, v12
	v_lshlrev_b32_e32 v12, 16, v48
	v_lshlrev_b32_e32 v16, 16, v50
	v_add_f32_e32 v12, v40, v12
	v_and_b32_e32 v13, 0xffff0000, v48
	v_add_f32_e32 v8, v8, v12
	v_add_f32_e32 v12, v44, v16
	v_and_b32_e32 v17, 0xffff0000, v50
	v_add_f32_e32 v11, v11, v12
	v_add_f32_e32 v12, v41, v13
	v_lshlrev_b32_e32 v14, 16, v49
	v_add_f32_e32 v4, v4, v12
	v_add_f32_e32 v12, v45, v17
	v_lshlrev_b32_e32 v18, 16, v51
	v_add_f32_e32 v6, v6, v12
	v_add_f32_e32 v12, v42, v14
	v_and_b32_e32 v15, 0xffff0000, v49
	v_add_f32_e32 v9, v9, v12
	v_add_f32_e32 v12, v46, v18
	v_and_b32_e32 v19, 0xffff0000, v51
	v_add_f32_e32 v10, v10, v12
	v_add_f32_e32 v12, v43, v15
	v_add_f32_e32 v5, v5, v12
	v_add_f32_e32 v12, v47, v19
	v_add_f32_e32 v7, v7, v12
	v_lshlrev_b32_e32 v12, 16, v60
	v_lshlrev_b32_e32 v16, 16, v62
	v_add_f32_e32 v12, v52, v12
	v_and_b32_e32 v13, 0xffff0000, v60
	v_add_f32_e32 v8, v8, v12
	v_add_f32_e32 v12, v56, v16
	v_and_b32_e32 v17, 0xffff0000, v62
	v_add_f32_e32 v11, v11, v12
	v_add_f32_e32 v12, v53, v13
	v_lshlrev_b32_e32 v14, 16, v61
	v_add_f32_e32 v4, v4, v12
	v_add_f32_e32 v12, v57, v17
	v_lshlrev_b32_e32 v18, 16, v63
	v_add_f32_e32 v6, v6, v12
	v_add_f32_e32 v12, v54, v14
	v_and_b32_e32 v15, 0xffff0000, v61
	v_add_f32_e32 v9, v9, v12
	v_add_f32_e32 v12, v58, v18
	v_and_b32_e32 v19, 0xffff0000, v63
	v_add_f32_e32 v10, v10, v12
	v_add_f32_e32 v12, v55, v15
	v_add_f32_e32 v5, v5, v12
	v_add_f32_e32 v12, v59, v19
	v_add_f32_e32 v7, v7, v12
	v_lshlrev_b32_e32 v12, 16, v72
	v_lshlrev_b32_e32 v16, 16, v74
	v_add_f32_e32 v12, v64, v12
	v_and_b32_e32 v13, 0xffff0000, v72
	v_add_f32_e32 v8, v8, v12
	v_add_f32_e32 v12, v68, v16
	v_and_b32_e32 v17, 0xffff0000, v74
	v_add_f32_e32 v11, v11, v12
	v_add_f32_e32 v12, v65, v13
	v_lshlrev_b32_e32 v14, 16, v73
	v_add_f32_e32 v4, v4, v12
	v_add_f32_e32 v12, v69, v17
	v_lshlrev_b32_e32 v18, 16, v75
	v_add_f32_e32 v6, v6, v12
	v_add_f32_e32 v12, v66, v14
	v_and_b32_e32 v15, 0xffff0000, v73
	v_add_f32_e32 v9, v9, v12
	v_add_f32_e32 v12, v70, v18
	v_and_b32_e32 v19, 0xffff0000, v75
	v_add_f32_e32 v10, v10, v12
	v_add_f32_e32 v12, v67, v15
	v_add_f32_e32 v5, v5, v12
	v_add_f32_e32 v12, v71, v19
	v_add_f32_e32 v7, v7, v12
	v_lshlrev_b32_e32 v12, 16, v84
	v_lshlrev_b32_e32 v16, 16, v86
	v_add_f32_e32 v12, v76, v12
	v_and_b32_e32 v13, 0xffff0000, v84
	v_add_f32_e32 v8, v8, v12
	v_add_f32_e32 v12, v80, v16
	v_and_b32_e32 v17, 0xffff0000, v86
; __device__ __forceinline__ void unpack8(const u32x4 w, float* f) { f[0] = bf_lo(w.x); f[1] = bf_hi(w.x); f[2] = bf_lo(w.y); f[3] = bf_hi(w.y); f[4] = bf_lo(w.z); f[5] = bf_hi(w.z); f[6] = bf_lo(w.w); f[7] = bf_hi(w.w); }
; __device__ __forceinline__ u32x4 pack8(const float* f) { u32x4 w; w.x = cvt_pk_bf16(f[0], f[1]); w.y = cvt_pk_bf16(f[2], f[3]); w.z = cvt_pk_bf16(f[4], f[5]); w.w = cvt_pk_bf16(f[6], f[7]); return w; }
; template <int W>
; __device__ __forceinline__ void pool_items(const Params& p, int l, bool sample, int b, int c, int g, long row0, int tid) {
;     ...
;         for (int i = 1; i < W; ++i) { float x[8]; unpack8(raw[i], x);
; #pragma unroll
;             for (int k = 0; k < 4; ++k) { a[k] += x[k] + h0[i][k]; a[4 + k] += x[4 + k] + h1[i][k]; } }
;         const float cnt = sample ? (float)W : (float)((t + 1) < W ? (t + 1) : W);
;         const float inv = 1.0f / cnt;
;         float d[8];
; #pragma unroll
;         for (int k = 0; k < 8; ++k) d[k] = a[k] * inv - cur[k];
;         *(u32x4*)(AD + (size_t)prow * DM + 512 + col) = pack8(d);
;         float* pd = nullptr;
;         if (!sample) { if (t >= SEQ - 15) pd = p.out + O_PP + (((size_t)l * 2 + b) * 15 + (t - (SEQ - 15))) * 512 + col; }
;         else if (tl >= 1) pd = p.out + O_PS + (((size_t)l * 8 + b) * 15 + (tl - 1)) * 512 + col;
;         if (pd) { *(f32x4*)pd = (f32x4){cur[0], cur[1], cur[2], cur[3]}; *(f32x4*)(pd + 4) = (f32x4){cur[4], cur[5], cur[6], cur[7]}; }
	v_add_f32_e32 v11, v11, v12
	v_add_f32_e32 v12, v77, v13
	v_lshlrev_b32_e32 v14, 16, v85
	v_add_f32_e32 v12, v4, v12
	v_add_f32_e32 v4, v81, v17
	v_lshlrev_b32_e32 v18, 16, v87
	v_add_f32_e32 v6, v6, v4
	v_add_f32_e32 v4, v78, v14
	v_and_b32_e32 v15, 0xffff0000, v85
	v_add_f32_e32 v9, v9, v4
	v_add_f32_e32 v4, v82, v18
	v_and_b32_e32 v19, 0xffff0000, v87
	v_add_f32_e32 v10, v10, v4
	v_add_f32_e32 v4, v79, v15
	v_add_f32_e32 v13, v5, v4
	v_add_f32_e32 v4, v83, v19
	v_add_f32_e32 v7, v7, v4
	v_lshlrev_b32_e32 v5, 16, v102
	v_lshlrev_b32_e32 v4, 16, v98
	v_pk_add_f32 v[4:5], v[92:93], v[4:5]
	s_mov_b32 s7, 0x3d800000
	v_add_f32_e32 v4, v8, v4
	v_add_f32_e32 v8, v4, v5
	v_lshlrev_b32_e32 v5, 16, v104
	v_lshlrev_b32_e32 v4, 16, v100
	v_pk_add_f32 v[4:5], v[88:89], v[4:5]
	v_mov_b32_e32 v161, v97
	v_add_f32_e32 v4, v11, v4
	v_add_f32_e32 v11, v4, v5
	v_and_b32_e32 v5, 0xffff0000, v102
	v_and_b32_e32 v4, 0xffff0000, v98
	v_pk_add_f32 v[4:5], v[170:171], v[4:5]
	s_nop 0
	v_add_f32_e32 v4, v12, v4
	v_add_f32_e32 v12, v4, v5
	v_and_b32_e32 v5, 0xffff0000, v104
	v_and_b32_e32 v4, 0xffff0000, v100
	v_pk_add_f32 v[4:5], v[168:169], v[4:5]
	s_nop 0
	v_add_f32_e32 v4, v6, v4
	v_add_f32_e32 v6, v4, v5
	v_lshlrev_b32_e32 v4, 16, v99
	v_lshlrev_b32_e32 v5, 16, v103
	v_pk_add_f32 v[4:5], v[94:95], v[4:5]
	s_nop 0
	v_add_f32_e32 v4, v9, v4
	v_add_f32_e32 v9, v4, v5
	v_lshlrev_b32_e32 v4, 16, v101
	v_lshlrev_b32_e32 v5, 16, v105
	v_pk_add_f32 v[4:5], v[90:91], v[4:5]
	s_nop 0
	v_add_f32_e32 v4, v10, v4
	v_add_f32_e32 v10, v4, v5
	v_and_b32_e32 v5, 0xffff0000, v103
	v_and_b32_e32 v4, 0xffff0000, v99
	v_pk_add_f32 v[4:5], v[166:167], v[4:5]
	s_nop 0
	v_add_f32_e32 v4, v13, v4
	v_add_f32_e32 v13, v4, v5
	v_and_b32_e32 v5, 0xffff0000, v105
	v_and_b32_e32 v4, 0xffff0000, v101
	v_pk_add_f32 v[4:5], v[164:165], v[4:5]
	s_nop 0
	v_add_f32_e32 v4, v7, v4
	v_add_f32_e32 v7, v4, v5
	v_lshlrev_b32_e32 v5, 16, v118
	v_lshlrev_b32_e32 v4, 16, v114
	v_pk_add_f32 v[4:5], v[110:111], v[4:5]
	s_nop 0
	v_add_f32_e32 v4, v8, v4
	v_add_f32_e32 v8, v4, v5
	v_lshlrev_b32_e32 v5, 16, v120
	v_lshlrev_b32_e32 v4, 16, v116
	v_pk_add_f32 v[4:5], v[106:107], v[4:5]
	s_nop 0
	v_add_f32_e32 v4, v11, v4
	v_add_f32_e32 v11, v4, v5
	v_and_b32_e32 v5, 0xffff0000, v118
	v_and_b32_e32 v4, 0xffff0000, v114
	v_pk_add_f32 v[4:5], v[178:179], v[4:5]
	s_nop 0
	v_add_f32_e32 v4, v12, v4
	v_add_f32_e32 v12, v4, v5
	v_and_b32_e32 v5, 0xffff0000, v120
	v_and_b32_e32 v4, 0xffff0000, v116
	v_pk_add_f32 v[4:5], v[176:177], v[4:5]
	s_nop 0
	v_add_f32_e32 v4, v6, v4
	v_add_f32_e32 v6, v4, v5
	v_lshlrev_b32_e32 v4, 16, v115
	v_lshlrev_b32_e32 v5, 16, v119
	v_pk_add_f32 v[4:5], v[112:113], v[4:5]
	s_nop 0
	v_add_f32_e32 v4, v9, v4
	v_add_f32_e32 v9, v4, v5
	v_lshlrev_b32_e32 v4, 16, v117
	v_lshlrev_b32_e32 v5, 16, v121
	v_pk_add_f32 v[4:5], v[108:109], v[4:5]
	s_nop 0
	v_add_f32_e32 v4, v10, v4
	v_add_f32_e32 v10, v4, v5
	v_and_b32_e32 v5, 0xffff0000, v119
	v_and_b32_e32 v4, 0xffff0000, v115
	v_pk_add_f32 v[4:5], v[174:175], v[4:5]
	s_nop 0
	v_add_f32_e32 v4, v13, v4
	v_add_f32_e32 v13, v4, v5
	v_and_b32_e32 v5, 0xffff0000, v121
	v_and_b32_e32 v4, 0xffff0000, v117
	v_pk_add_f32 v[4:5], v[172:173], v[4:5]
	s_nop 0
	v_add_f32_e32 v4, v7, v4
	v_add_f32_e32 v7, v4, v5
	v_lshlrev_b32_e32 v5, 16, v134
	v_lshlrev_b32_e32 v4, 16, v130
	v_pk_add_f32 v[4:5], v[126:127], v[4:5]
	s_nop 0
	v_add_f32_e32 v4, v8, v4
	v_add_f32_e32 v8, v4, v5
	v_lshlrev_b32_e32 v5, 16, v136
	v_lshlrev_b32_e32 v4, 16, v132
	v_pk_add_f32 v[4:5], v[122:123], v[4:5]
	s_nop 0
	v_add_f32_e32 v4, v11, v4
	v_add_f32_e32 v11, v4, v5
	v_and_b32_e32 v5, 0xffff0000, v134
	v_and_b32_e32 v4, 0xffff0000, v130
	v_pk_add_f32 v[4:5], v[186:187], v[4:5]
	s_nop 0
	v_add_f32_e32 v4, v12, v4
	v_add_f32_e32 v12, v4, v5
	v_and_b32_e32 v5, 0xffff0000, v136
	v_and_b32_e32 v4, 0xffff0000, v132
	v_pk_add_f32 v[4:5], v[184:185], v[4:5]
	s_nop 0
	v_add_f32_e32 v4, v6, v4
	v_add_f32_e32 v6, v4, v5
	v_lshlrev_b32_e32 v4, 16, v131
	v_lshlrev_b32_e32 v5, 16, v135
	v_pk_add_f32 v[4:5], v[128:129], v[4:5]
	s_nop 0
	v_add_f32_e32 v4, v9, v4
	v_add_f32_e32 v9, v4, v5
	v_lshlrev_b32_e32 v4, 16, v133
	v_lshlrev_b32_e32 v5, 16, v137
	v_pk_add_f32 v[4:5], v[124:125], v[4:5]
	s_nop 0
	v_add_f32_e32 v4, v10, v4
	v_add_f32_e32 v10, v4, v5
	v_and_b32_e32 v5, 0xffff0000, v135
	v_and_b32_e32 v4, 0xffff0000, v131
	v_pk_add_f32 v[4:5], v[182:183], v[4:5]
	s_nop 0
	v_add_f32_e32 v4, v13, v4
	v_add_f32_e32 v13, v4, v5
	v_and_b32_e32 v5, 0xffff0000, v137
	v_and_b32_e32 v4, 0xffff0000, v133
	v_pk_add_f32 v[4:5], v[180:181], v[4:5]
	s_nop 0
	v_add_f32_e32 v4, v7, v4
	v_add_f32_e32 v7, v4, v5
	v_lshlrev_b32_e32 v5, 16, v154
	v_lshlrev_b32_e32 v4, 16, v146
	v_pk_add_f32 v[4:5], v[142:143], v[4:5]
	s_nop 0
	v_add_f32_e32 v4, v8, v4
	v_add_f32_e32 v8, v4, v5
	v_lshlrev_b32_e32 v5, 16, v156
	v_lshlrev_b32_e32 v4, 16, v148
	v_pk_add_f32 v[4:5], v[138:139], v[4:5]
	s_nop 0
	v_add_f32_e32 v4, v11, v4
	v_add_f32_e32 v11, v4, v5
	v_and_b32_e32 v5, 0xffff0000, v154
	v_and_b32_e32 v4, 0xffff0000, v146
	v_pk_add_f32 v[4:5], v[206:207], v[4:5]
	v_fma_f32 v11, v11, s7, -v0
	v_add_f32_e32 v4, v12, v4
	v_add_f32_e32 v12, v4, v5
	v_and_b32_e32 v5, 0xffff0000, v156
	v_and_b32_e32 v4, 0xffff0000, v148
	v_pk_add_f32 v[4:5], v[192:193], v[4:5]
	s_nop 0
	v_add_f32_e32 v4, v6, v4
	v_add_f32_e32 v6, v4, v5
	v_lshlrev_b32_e32 v4, 16, v147
	v_lshlrev_b32_e32 v5, 16, v155
	v_pk_add_f32 v[4:5], v[144:145], v[4:5]
	v_fma_f32 v6, v6, s7, -v1
	v_add_f32_e32 v4, v9, v4
	v_add_f32_e32 v9, v4, v5
	v_lshlrev_b32_e32 v4, 16, v149
	v_lshlrev_b32_e32 v5, 16, v157
	v_pk_add_f32 v[4:5], v[140:141], v[4:5]
	s_nop 0
	v_add_f32_e32 v4, v10, v4
	v_add_f32_e32 v10, v4, v5
	v_and_b32_e32 v5, 0xffff0000, v155
	v_and_b32_e32 v4, 0xffff0000, v147
	v_pk_add_f32 v[4:5], v[190:191], v[4:5]
	v_fma_f32 v10, v10, s7, -v2
	v_add_f32_e32 v4, v13, v4
	v_add_f32_e32 v13, v4, v5
	v_and_b32_e32 v5, 0xffff0000, v157
	v_and_b32_e32 v4, 0xffff0000, v149
	v_pk_add_f32 v[4:5], v[188:189], v[4:5]
	s_nop 0
	v_add_f32_e32 v4, v7, v4
	v_add_f32_e32 v4, v4, v5
	v_fma_f32 v5, v8, s7, -v150
	v_fma_f32 v8, v9, s7, -v152
	v_fma_f32 v9, v13, s7, -v153
	v_fma_f32 v7, v12, s7, -v151
	v_fma_f32 v12, v4, s7, -v3
	v_cvt_pk_bf16_f32 v4, v5, v7
	v_cvt_pk_bf16_f32 v5, v8, v9
	v_lshlrev_b64 v[8:9], 11, v[162:163]
	v_lshl_add_u64 v[8:9], s[86:87], 0, v[8:9]
	v_lshl_add_u64 v[8:9], v[8:9], 0, v[160:161]
	v_add_co_u32_e32 v8, vcc, 0x7900000, v8
	v_cvt_pk_bf16_f32 v6, v11, v6
	v_cvt_pk_bf16_f32 v7, v10, v12
	s_nop 1
	v_addc_co_u32_e32 v9, vcc, 0, v9, vcc
	global_store_dwordx4 v[8:9], v[4:7], off offset:1024
	s_and_saveexec_b64 s[12:13], s[44:45]
	s_cbranch_execz .LBB0_466
	v_add_u32_e32 v4, -1, v158
	v_mov_b32_e32 v5, v97
	v_lshl_add_u64 v[4:5], s[2:3], 0, v[4:5]
	v_lshlrev_b64 v[4:5], 11, v[4:5]
	v_lshl_add_u64 v[4:5], s[62:63], 0, v[4:5]
	v_lshl_add_u64 v[4:5], v[4:5], 0, v[96:97]
	global_store_dwordx4 v[4:5], v[150:153], off offset:1536
	global_store_dwordx4 v[4:5], v[0:3], off offset:1552
	s_branch .LBB0_466

; template <int W>
; __device__ __forceinline__ void pool_items(const Params& p, int l, bool sample, int b, int c, int g, long row0, int tid) {
;     ...
;         const int tl = it >> 4, ch = it & 15, col = g * 128 + ch * 8;
;         const long prow = row0 + tl; const int t = sample ? tl : c * 64 + tl;
;         u32x4 raw[W]; f32x4 h0[W], h1[W];
; #pragma unroll
;         for (int i = 0; i < W; ++i) {
;             const int tt = t - i;
;             raw[i] = (u32x4){0u, 0u, 0u, 0u}; h0[i] = (f32x4){0.f, 0.f, 0.f, 0.f}; h1[i] = h0[i];
;             if (tt >= 0) raw[i] = *(const u32x4*)(P + (size_t)(prow - i) * INW + 768 + col);
;             else if (sample) { const float* sp = p.state_pool + (((size_t)l * 8 + b) * 15 + (15 + tt)) * 512 + col; h0[i] = *(const f32x4*)sp; h1[i] = *(const f32x4*)(sp + 4); }
.LBB0_537:
	v_ashrrev_i32_e32 v36, 4, v51
	v_and_b32_e32 v8, 0x78, v50
	v_or_b32_e32 v1, 0x80, v8
	v_ashrrev_i32_e32 v37, 31, v36
	v_lshl_add_u64 v[40:41], s[40:41], 0, v[36:37]
	v_cmp_lt_i32_e32 vcc, -1, v36
	v_mov_b32_e32 v0, 0
	v_lshlrev_b32_e32 v38, 1, v1
	v_mov_b32_e32 v1, 0
	v_mov_b32_e32 v2, 0
	v_mov_b32_e32 v3, 0
	s_and_saveexec_b64 s[0:1], vcc
	s_cbranch_execz .LBB0_539
	v_mov_b64_e32 v[0:1], s[86:87]
	v_mad_u64_u32 v[0:1], s[14:15], v40, s89, v[0:1]
	v_mad_i32_i24 v1, v41, s89, v1
	v_mov_b32_e32 v39, v97
	v_lshl_add_u64 v[0:1], v[0:1], 0, v[38:39]
	v_add_co_u32_e32 v0, vcc, 0xfb00000, v0
	s_nop 1
	v_addc_co_u32_e32 v1, vcc, 0, v1, vcc
	global_load_dwordx4 v[0:3], v[0:1], off offset:1536
.LBB0_539:
	s_or_b64 exec, exec, s[0:1]
	v_cmp_lt_i32_e64 s[0:1], 0, v36
	s_and_saveexec_b64 s[14:15], s[0:1]
	s_xor_b64 s[14:15], exec, s[14:15]
	s_cbranch_execz .LBB0_541
	v_mov_b64_e32 v[4:5], s[86:87]
	v_mad_u64_u32 v[4:5], s[16:17], v40, s89, v[4:5]
	v_mad_i32_i24 v5, v41, s89, v5
	v_mov_b32_e32 v39, v97
	v_lshl_add_u64 v[4:5], v[4:5], 0, v[38:39]
	v_add_co_u32_e32 v4, vcc, 0xfafe000, v4
	s_nop 1
	v_addc_co_u32_e32 v5, vcc, 0, v5, vcc
	global_load_dwordx4 v[4:7], v[4:5], off offset:3072

; template <int W>
; __device__ __forceinline__ void pool_items(const Params& p, int l, bool sample, int b, int c, int g, long row0, int tid) {
;     ...
;         for (int i = 0; i < W; ++i) {
;             const int tt = t - i;
;             raw[i] = (u32x4){0u, 0u, 0u, 0u}; h0[i] = (f32x4){0.f, 0.f, 0.f, 0.f}; h1[i] = h0[i];
;             if (tt >= 0) raw[i] = *(const u32x4*)(P + (size_t)(prow - i) * INW + 768 + col);
;             else if (sample) { const float* sp = p.state_pool + (((size_t)l * 8 + b) * 15 + (15 + tt)) * 512 + col; h0[i] = *(const f32x4*)sp; h1[i] = *(const f32x4*)(sp + 4); }
.LBB0_545:
	s_or_saveexec_b64 s[14:15], s[14:15]
	v_mov_b32_e32 v24, 0
	v_mov_b32_e32 v25, 0
	v_mov_b32_e32 v26, 0
	v_mov_b32_e32 v27, 0
	s_xor_b64 exec, exec, s[14:15]
	s_cbranch_execz .LBB0_547
	v_mov_b64_e32 v[16:17], s[86:87]
	v_mad_u64_u32 v[16:17], s[16:17], v40, s89, v[16:17]
	v_mad_i32_i24 v17, v41, s89, v17
	v_mov_b32_e32 v39, v97
	v_lshl_add_u64 v[16:17], v[16:17], 0, v[38:39]
	v_add_co_u32_e32 v16, vcc, 0xfafd000, v16
	v_mov_b32_e32 v20, 0
	s_nop 0
	v_addc_co_u32_e32 v17, vcc, 0, v17, vcc
	global_load_dwordx4 v[24:27], v[16:17], off offset:512
	v_mov_b32_e32 v48, 0
	v_mov_b32_e32 v22, v20
	v_mov_b32_e32 v44, v20
	v_mov_b32_e32 v16, v20
	v_mov_b32_e32 v46, v20
	v_mov_b32_e32 v18, v20
	v_mov_b32_e32 v42, v20

; __device__ __forceinline__ void unpack8(const u32x4 w, float* f) { f[0] = bf_lo(w.x); f[1] = bf_hi(w.x); f[2] = bf_lo(w.y); f[3] = bf_hi(w.y); f[4] = bf_lo(w.z); f[5] = bf_hi(w.z); f[6] = bf_lo(w.w); f[7] = bf_hi(w.w); }
; __device__ __forceinline__ u32x4 pack8(const float* f) { u32x4 w; w.x = cvt_pk_bf16(f[0], f[1]); w.y = cvt_pk_bf16(f[2], f[3]); w.z = cvt_pk_bf16(f[4], f[5]); w.w = cvt_pk_bf16(f[6], f[7]); return w; }
; template <int W>
; __device__ __forceinline__ void pool_items(const Params& p, int l, bool sample, int b, int c, int g, long row0, int tid) {
;     ...
;             if (tt >= 0) raw[i] = *(const u32x4*)(P + (size_t)(prow - i) * INW + 768 + col);
;             else if (sample) { const float* sp = p.state_pool + (((size_t)l * 8 + b) * 15 + (15 + tt)) * 512 + col; h0[i] = *(const f32x4*)sp; h1[i] = *(const f32x4*)(sp + 4); }
;         }
;         float cur[8], a[8];
;         unpack8(raw[0], cur);
; #pragma unroll
;         for (int k = 0; k < 8; ++k) a[k] = cur[k];
; #pragma unroll
;         for (int i = 1; i < W; ++i) { float x[8]; unpack8(raw[i], x);
; #pragma unroll
;             for (int k = 0; k < 4; ++k) { a[k] += x[k] + h0[i][k]; a[4 + k] += x[4 + k] + h1[i][k]; } }
;         const float cnt = sample ? (float)W : (float)((t + 1) < W ? (t + 1) : W);
;         const float inv = 1.0f / cnt;
;         float d[8];
; #pragma unroll
;         for (int k = 0; k < 8; ++k) d[k] = a[k] * inv - cur[k];
;         *(u32x4*)(AD + (size_t)prow * DM + 512 + col) = pack8(d);
;         float* pd = nullptr;
;         if (!sample) { if (t >= SEQ - 15) pd = p.out + O_PP + (((size_t)l * 2 + b) * 15 + (t - (SEQ - 15))) * 512 + col; }
;         else if (tl >= 1) pd = p.out + O_PS + (((size_t)l * 8 + b) * 15 + (tl - 1)) * 512 + col;
;         if (pd) { *(f32x4*)pd = (f32x4){cur[0], cur[1], cur[2], cur[3]}; *(f32x4*)(pd + 4) = (f32x4){cur[4], cur[5], cur[6], cur[7]}; }
.LBB0_549:
	s_or_saveexec_b64 s[14:15], s[14:15]
	v_mov_b32_e32 v32, 0
	v_mov_b32_e32 v33, 0
	v_mov_b32_e32 v34, 0
	v_mov_b32_e32 v35, 0
	s_xor_b64 exec, exec, s[14:15]
	s_cbranch_execz .LBB0_551
	v_mov_b64_e32 v[28:29], s[86:87]
	v_mad_u64_u32 v[28:29], s[16:17], v40, s89, v[28:29]
	v_mad_i32_i24 v29, v41, s89, v29
	v_mov_b32_e32 v39, v97
	v_lshl_add_u64 v[28:29], v[28:29], 0, v[38:39]
	v_add_co_u32_e32 v28, vcc, 0xfafb000, v28
	v_mov_b32_e32 v21, 0
	s_nop 0
	v_addc_co_u32_e32 v29, vcc, 0, v29, vcc
	global_load_dwordx4 v[32:35], v[28:29], off offset:2048
	v_mov_b32_e32 v49, v21
	v_mov_b32_e32 v23, v21
	v_mov_b32_e32 v45, v21
	v_mov_b32_e32 v17, v21
	v_mov_b32_e32 v47, v21
	v_mov_b32_e32 v19, v21
	v_mov_b32_e32 v43, v21
.LBB0_551:
	s_or_b64 exec, exec, s[14:15]
	s_waitcnt vmcnt(0) lgkmcnt(0)
	v_lshlrev_b32_e32 v37, 16, v4
	v_and_b32_e32 v4, 0xffff0000, v4
	v_and_b32_e32 v29, 0xffff0000, v0
	v_lshlrev_b32_e32 v52, 16, v6
	v_and_b32_e32 v6, 0xffff0000, v6
	v_add_f32_e32 v4, v9, v4
	v_lshlrev_b32_e32 v30, 16, v1
	v_and_b32_e32 v31, 0xffff0000, v1
	v_and_b32_e32 v1, 0xffff0000, v2
	v_lshlrev_b32_e32 v39, 16, v5
	v_add_f32_e32 v9, v4, v29
	v_add_f32_e32 v4, v13, v6
	v_lshlrev_b32_e32 v53, 16, v7
	v_add_f32_e32 v6, v4, v1
	v_add_f32_e32 v4, v10, v39
	v_lshlrev_b32_e32 v28, 16, v0
	v_lshlrev_b32_e32 v0, 16, v2
	v_lshlrev_b32_e32 v2, 16, v3
	v_and_b32_e32 v5, 0xffff0000, v5
	v_add_f32_e32 v10, v4, v30
	v_add_f32_e32 v4, v14, v53
	v_and_b32_e32 v7, 0xffff0000, v7
	v_add_f32_e32 v13, v4, v2
	v_add_f32_e32 v4, v11, v5
	v_and_b32_e32 v3, 0xffff0000, v3
	v_add_f32_e32 v11, v4, v31
	v_add_f32_e32 v4, v15, v7
	v_add_f32_e32 v8, v8, v37
	v_add_f32_e32 v7, v4, v3
	v_lshlrev_b32_e32 v5, 16, v32
	v_lshlrev_b32_e32 v4, 16, v24
	v_add_f32_e32 v8, v8, v28
	v_pk_add_f32 v[4:5], v[20:21], v[4:5]
	v_add_f32_e32 v12, v12, v52
	v_add_f32_e32 v4, v8, v4
	v_add_f32_e32 v8, v4, v5
	v_lshlrev_b32_e32 v5, 16, v34
	v_lshlrev_b32_e32 v4, 16, v26
	v_add_f32_e32 v12, v12, v0
	v_pk_add_f32 v[4:5], v[16:17], v[4:5]
	s_mov_b32 s7, 0x3e800000
	v_add_f32_e32 v4, v12, v4
	v_add_f32_e32 v12, v4, v5
	v_and_b32_e32 v5, 0xffff0000, v32
	v_and_b32_e32 v4, 0xffff0000, v24
	v_pk_add_f32 v[4:5], v[48:49], v[4:5]
	v_mov_b32_e32 v39, v97
	v_add_f32_e32 v4, v9, v4
	v_add_f32_e32 v9, v4, v5
	v_and_b32_e32 v5, 0xffff0000, v34
	v_and_b32_e32 v4, 0xffff0000, v26
	v_pk_add_f32 v[4:5], v[46:47], v[4:5]
	s_nop 0
	v_add_f32_e32 v4, v6, v4
	v_add_f32_e32 v6, v4, v5
	v_lshlrev_b32_e32 v4, 16, v25
	v_lshlrev_b32_e32 v5, 16, v33
	v_pk_add_f32 v[4:5], v[22:23], v[4:5]
	v_fma_f32 v6, v6, s7, -v1
	v_add_f32_e32 v4, v10, v4
	v_add_f32_e32 v10, v4, v5
	v_lshlrev_b32_e32 v4, 16, v27
	v_lshlrev_b32_e32 v5, 16, v35
	v_pk_add_f32 v[4:5], v[18:19], v[4:5]
	s_nop 0
	v_add_f32_e32 v4, v13, v4
	v_add_f32_e32 v13, v4, v5
	v_and_b32_e32 v5, 0xffff0000, v33
	v_and_b32_e32 v4, 0xffff0000, v25
	v_pk_add_f32 v[4:5], v[44:45], v[4:5]
	s_nop 0
	v_add_f32_e32 v4, v11, v4
	v_add_f32_e32 v11, v4, v5
	v_and_b32_e32 v5, 0xffff0000, v35
	v_and_b32_e32 v4, 0xffff0000, v27
	v_pk_add_f32 v[4:5], v[42:43], v[4:5]
	s_nop 0
	v_add_f32_e32 v4, v7, v4
	v_add_f32_e32 v4, v4, v5
	v_fma_f32 v5, v8, s7, -v28
	v_fma_f32 v7, v9, s7, -v29
	v_fma_f32 v8, v10, s7, -v30
	v_fma_f32 v9, v11, s7, -v31
	v_fma_f32 v10, v12, s7, -v0
	v_fma_f32 v12, v4, s7, -v3
	v_cvt_pk_bf16_f32 v4, v5, v7
	v_cvt_pk_bf16_f32 v5, v8, v9
	v_lshlrev_b64 v[8:9], 11, v[40:41]
	v_lshl_add_u64 v[8:9], s[86:87], 0, v[8:9]
	v_lshl_add_u64 v[8:9], v[8:9], 0, v[38:39]
	v_add_co_u32_e32 v8, vcc, 0x7900000, v8
	v_fma_f32 v11, v13, s7, -v2
	s_nop 0
	v_addc_co_u32_e32 v9, vcc, 0, v9, vcc
	v_cvt_pk_bf16_f32 v6, v10, v6
	v_cvt_pk_bf16_f32 v7, v11, v12
	global_store_dwordx4 v[8:9], v[4:7], off offset:1024
	s_and_saveexec_b64 s[14:15], s[0:1]
	s_cbranch_execz .LBB0_536
	v_add_u32_e32 v4, -1, v36
	v_mov_b32_e32 v5, v97
	v_lshl_add_u64 v[4:5], s[2:3], 0, v[4:5]
	v_lshlrev_b64 v[4:5], 11, v[4:5]
	v_lshl_add_u64 v[4:5], s[62:63], 0, v[4:5]
	v_lshl_add_u64 v[4:5], v[4:5], 0, v[96:97]
	global_store_dwordx4 v[4:5], v[28:31], off offset:512
	global_store_dwordx4 v[4:5], v[0:3], off offset:528
	s_branch .LBB0_536

; __device__ __forceinline__ void attn_unit(const Params& p, int l, LAS unsigned char* lds, bool sample, int b, int c, int kvh) {
;     ...
;     u32x4 qraw[4];
; #pragma unroll
;     for (int d0 = 0; d0 < 4; ++d0) qraw[d0] = *(const u32x4*)(P + (size_t)qrow * INW + h * 64 + d0 * 16 + hi * 8);
;     u32x4 kraw[3], vraw[3]; f32x4 kc0[3], kc1[3], vc0[3], vc1[3];
; #pragma unroll
;     for (int it = 0; it < 3; ++it) {
;         const int idx = it * 512 + tid, j = idx >> 3, ch = idx & 7;
;         kraw[it] = (u32x4){0u, 0u, 0u, 0u}; vraw[it] = kraw[it];
;         kc0[it] = (f32x4){0.f, 0.f, 0.f, 0.f}; kc1[it] = kc0[it]; vc0[it] = kc0[it]; vc1[it] = kc0[it];
;         if (!sample) { const int tk = c * 64 - 128 + j;
;             if (tk >= 0) { const size_t o = (size_t)((long)b * SEQ + tk) * INW + kvh * 64 + ch * 8; kraw[it] = *(const u32x4*)(P + o + 512); vraw[it] = *(const u32x4*)(P + o + 640); } }
;         else if (j < 128) { const size_t ci = ((((size_t)l * 8 + b) * 128 + j) * 2 + kvh) * 64 + ch * 8;
;             kc0[it] = *(const f32x4*)(p.cache_k + ci); kc1[it] = *(const f32x4*)(p.cache_k + ci + 4); vc0[it] = *(const f32x4*)(p.cache_v + ci); vc1[it] = *(const f32x4*)(p.cache_v + ci + 4); }
;         else if (j < 144) { const size_t o = (size_t)((long)MP + b * 16 + (j - 128)) * INW + kvh * 64 + ch * 8; kraw[it] = *(const u32x4*)(P + o + 512); vraw[it] = *(const u32x4*)(P + o + 640); }
.LBB0_554:
	s_and_b32 s12, s23, 1
	v_ashrrev_i32_e32 v110, 5, v208
	s_ashr_i32 s7, s25, 7
	s_lshl_b32 s0, s12, 2
	s_add_i32 s7, s7, s0
	v_and_or_b32 v2, v208, 15, s40
	v_mov_b64_e32 v[0:1], s[84:85]
	v_mad_u64_u32 v[0:1], s[0:1], v2, s89, v[0:1]
	s_lshl_b32 s2, s7, 6
	v_mad_i32_i24 v1, s41, v227, v1
	s_ashr_i32 s3, s2, 31
	v_lshlrev_b32_e32 v88, 3, v110
	v_lshl_add_u64 v[0:1], s[2:3], 1, v[0:1]
	v_ashrrev_i32_e32 v89, 31, v88
	v_lshl_add_u64 v[0:1], v[88:89], 1, v[0:1]
	global_load_dwordx4 v[12:15], v[0:1], off
	global_load_dwordx4 v[8:11], v[0:1], off offset:32
	global_load_dwordx4 v[4:7], v[0:1], off offset:64
	s_nop 0
	global_load_dwordx4 v[0:3], v[0:1], off offset:96
	v_lshlrev_b32_e32 v16, 3, v209
	s_lshl_b32 s0, s12, 7
	v_and_b32_e32 v98, 56, v16
	s_add_u32 s0, s84, s0
	s_addc_u32 s1, s85, 0
	v_lshlrev_b32_e32 v96, 1, v98
	v_lshl_add_u64 v[16:17], s[0:1], 0, v[96:97]
	v_ashrrev_i32_e32 v94, 3, v209
	s_movk_i32 s0, 0x7f
	v_cmp_lt_i32_e32 vcc, s0, v94
	s_and_saveexec_b64 s[0:1], vcc
	s_xor_b64 s[0:1], exec, s[0:1]
	s_cbranch_execz .LBB0_558
	v_cmp_gt_u32_e32 vcc, s83, v94
	v_mov_b32_e32 v87, 0
	v_mov_b32_e32 v86, 0
	v_mov_b32_e32 v85, 0
	v_mov_b32_e32 v84, 0
	v_mov_b32_e32 v83, 0
	v_mov_b32_e32 v82, 0
	v_mov_b32_e32 v81, 0
	v_mov_b32_e32 v80, 0
	s_and_saveexec_b64 s[10:11], vcc
	s_cbranch_execz .LBB0_557
	v_add_u32_e32 v96, 0xffffff80, v94
	v_lshl_add_u64 v[18:19], s[40:41], 0, v[96:97]
	v_mad_u64_u32 v[20:21], s[14:15], v18, s89, v[16:17]
	v_mad_i32_i24 v21, v19, s89, v21
	global_load_dwordx4 v[84:87], v[20:21], off offset:1024
	global_load_dwordx4 v[80:83], v[20:21], off offset:1280

; __device__ __forceinline__ void attn_unit(const Params& p, int l, LAS unsigned char* lds, bool sample, int b, int c, int kvh) {
;     ...
;     for (int it = 0; it < 3; ++it) {
;         const int idx = it * 512 + tid, j = idx >> 3, ch = idx & 7;
;         kraw[it] = (u32x4){0u, 0u, 0u, 0u}; vraw[it] = kraw[it];
;         kc0[it] = (f32x4){0.f, 0.f, 0.f, 0.f}; kc1[it] = kc0[it]; vc0[it] = kc0[it]; vc1[it] = kc0[it];
;         if (!sample) { const int tk = c * 64 - 128 + j;
;             if (tk >= 0) { const size_t o = (size_t)((long)b * SEQ + tk) * INW + kvh * 64 + ch * 8; kraw[it] = *(const u32x4*)(P + o + 512); vraw[it] = *(const u32x4*)(P + o + 640); } }
;         else if (j < 128) { const size_t ci = ((((size_t)l * 8 + b) * 128 + j) * 2 + kvh) * 64 + ch * 8;
;             kc0[it] = *(const f32x4*)(p.cache_k + ci); kc1[it] = *(const f32x4*)(p.cache_k + ci + 4); vc0[it] = *(const f32x4*)(p.cache_v + ci); vc1[it] = *(const f32x4*)(p.cache_v + ci + 4); }
;         else if (j < 144) { const size_t o = (size_t)((long)MP + b * 16 + (j - 128)) * INW + kvh * 64 + ch * 8; kraw[it] = *(const u32x4*)(P + o + 512); vraw[it] = *(const u32x4*)(P + o + 640); }
.LBB0_560:
	s_or_b64 exec, exec, s[0:1]
	v_add_u32_e32 v18, 0x200, v209
	v_ashrrev_i32_e32 v92, 3, v18
	s_movk_i32 s0, 0x7f
	v_cmp_lt_i32_e32 vcc, s0, v92
	s_and_saveexec_b64 s[0:1], vcc
	s_xor_b64 s[0:1], exec, s[0:1]
	s_cbranch_execz .LBB0_564
	v_cmp_gt_u32_e32 vcc, s83, v92
	v_mov_b32_e32 v79, 0
	v_mov_b32_e32 v78, 0
	v_mov_b32_e32 v77, 0
	v_mov_b32_e32 v76, 0
	v_mov_b32_e32 v75, 0
	v_mov_b32_e32 v74, 0
	v_mov_b32_e32 v73, 0
	v_mov_b32_e32 v72, 0
	s_and_saveexec_b64 s[10:11], vcc
	s_cbranch_execz .LBB0_563
	v_add_u32_e32 v96, 0xffffff80, v92
	v_lshl_add_u64 v[18:19], s[40:41], 0, v[96:97]
	v_mad_u64_u32 v[20:21], s[14:15], v18, s89, v[16:17]
	v_mad_i32_i24 v21, v19, s89, v21
	global_load_dwordx4 v[76:79], v[20:21], off offset:1024
	global_load_dwordx4 v[72:75], v[20:21], off offset:1280

; __device__ __forceinline__ void attn_unit(const Params& p, int l, LAS unsigned char* lds, bool sample, int b, int c, int kvh) {
;     ...
;     for (int it = 0; it < 3; ++it) {
;         const int idx = it * 512 + tid, j = idx >> 3, ch = idx & 7;
;         kraw[it] = (u32x4){0u, 0u, 0u, 0u}; vraw[it] = kraw[it];
;         kc0[it] = (f32x4){0.f, 0.f, 0.f, 0.f}; kc1[it] = kc0[it]; vc0[it] = kc0[it]; vc1[it] = kc0[it];
;         if (!sample) { const int tk = c * 64 - 128 + j;
;             if (tk >= 0) { const size_t o = (size_t)((long)b * SEQ + tk) * INW + kvh * 64 + ch * 8; kraw[it] = *(const u32x4*)(P + o + 512); vraw[it] = *(const u32x4*)(P + o + 640); } }
;         else if (j < 128) { const size_t ci = ((((size_t)l * 8 + b) * 128 + j) * 2 + kvh) * 64 + ch * 8;
;             kc0[it] = *(const f32x4*)(p.cache_k + ci); kc1[it] = *(const f32x4*)(p.cache_k + ci + 4); vc0[it] = *(const f32x4*)(p.cache_v + ci); vc1[it] = *(const f32x4*)(p.cache_v + ci + 4); }
;         else if (j < 144) { const size_t o = (size_t)((long)MP + b * 16 + (j - 128)) * INW + kvh * 64 + ch * 8; kraw[it] = *(const u32x4*)(P + o + 512); vraw[it] = *(const u32x4*)(P + o + 640); }
.LBB0_566:
	s_or_b64 exec, exec, s[0:1]
	v_add_u32_e32 v18, 0x400, v209
	v_ashrrev_i32_e32 v90, 3, v18
	s_movk_i32 s0, 0x7f
	v_cmp_lt_i32_e32 vcc, s0, v90
	s_and_saveexec_b64 s[0:1], vcc
	s_xor_b64 s[0:1], exec, s[0:1]
	s_cbranch_execz .LBB0_570
	v_cmp_gt_u32_e32 vcc, s83, v90
	v_mov_b32_e32 v55, 0
	v_mov_b32_e32 v54, 0
	v_mov_b32_e32 v53, 0
	v_mov_b32_e32 v52, 0
	v_mov_b32_e32 v51, 0
	v_mov_b32_e32 v50, 0
	v_mov_b32_e32 v49, 0
	v_mov_b32_e32 v48, 0
	s_and_saveexec_b64 s[10:11], vcc
	s_cbranch_execz .LBB0_569
	v_add_u32_e32 v96, 0xffffff80, v90
	v_lshl_add_u64 v[18:19], s[40:41], 0, v[96:97]
	v_mad_u64_u32 v[16:17], s[14:15], v18, s89, v[16:17]
	v_mad_i32_i24 v17, v19, s89, v17
	global_load_dwordx4 v[52:55], v[16:17], off offset:1024
	global_load_dwordx4 v[48:51], v[16:17], off offset:1280

; #define LAS __attribute__((address_space(3)))
; __device__ __forceinline__ unsigned cvt_pk_bf16(float lo, float hi) { unsigned r; asm volatile("v_cvt_pk_bf16_f32 %0, %1, %2" : "=v"(r) : "v"(lo), "v"(hi)); return r; }
; __device__ __forceinline__ u32x4 pack8(const float* f) { u32x4 w; w.x = cvt_pk_bf16(f[0], f[1]); w.y = cvt_pk_bf16(f[2], f[3]); w.z = cvt_pk_bf16(f[4], f[5]); w.w = cvt_pk_bf16(f[6], f[7]); return w; }
; __device__ __forceinline__ void attn_unit(const Params& p, int l, LAS unsigned char* lds, bool sample, int b, int c, int kvh) {
;     ...
;         *(LAS u32x4*)(Ks + j * KS_LD + ch * 8) = pack8(kf);
; #pragma unroll
;         for (int i = 0; i < 8; i += 2) { const unsigned w = cvt_pk_bf16(vf[i], vf[i + 1]); const int js = j ^ (ch << 3);
;             Vt[(ch * 8 + i) * VT_LD + js] = (bf16_t)(w & 0xffffu); Vt[(ch * 8 + i + 1) * VT_LD + js] = (bf16_t)(w >> 16); }
;         float* kd = nullptr; float* vd = nullptr;
;         if (!sample) { if (c >= 254 && j >= 128) { const size_t o = ((((size_t)l * 2 + b) * 128 + (c - 254) * 64 + (j - 128)) * 2 + kvh) * 64 + ch * 8; kd = p.out + O_KP + o; vd = p.out + O_VP + o; } }
;         else if (j >= 16 && j < 144) { const size_t o = ((((size_t)l * 8 + b) * 128 + (j - 16)) * 2 + kvh) * 64 + ch * 8; kd = p.out + O_KS + o; vd = p.out + O_VS + o; }
;         if (kd) { *(f32x4*)kd = (f32x4){kf[0], kf[1], kf[2], kf[3]}; *(f32x4*)(kd + 4) = (f32x4){kf[4], kf[5], kf[6], kf[7]};
;                   *(f32x4*)vd = (f32x4){vf[0], vf[1], vf[2], vf[3]}; *(f32x4*)(vd + 4) = (f32x4){vf[4], vf[5], vf[6], vf[7]}; }
.LBB0_580:
	s_or_b64 exec, exec, s[0:1]
	v_lshl_add_u32 v84, v98, 1, 0
	v_mad_u64_u32 v[86:87], s[0:1], v94, s83, v[84:85]
	v_cvt_pk_bf16_f32 v100, v64, v65
	v_xor_b32_e32 v81, v98, v94
	s_movk_i32 s0, 0x18e
	v_cvt_pk_bf16_f32 v101, v66, v67
	v_cvt_pk_bf16_f32 v102, v56, v57
	v_cvt_pk_bf16_f32 v103, v58, v59
	ds_write_b128 v86, v[100:103]
	v_mad_u32_u24 v100, v98, s0, v84
	v_lshlrev_b32_e32 v81, 1, v81
	s_movk_i32 s0, 0x190
	s_waitcnt lgkmcnt(1)
	v_cvt_pk_bf16_f32 v83, v68, v69
	v_add_u32_e32 v86, v100, v81
	v_mad_i32_i24 v101, v96, s0, 0
	ds_write_b16 v86, v83 offset:27648
	ds_write_b16_d16_hi v86, v83 offset:28048
	v_cvt_pk_bf16_f32 v83, v70, v71
	v_add_u32_e32 v86, v101, v81
	v_mad_i32_i24 v102, v82, s0, 0
	ds_write_b16 v86, v83 offset:27648
	ds_write_b16_d16_hi v86, v83 offset:28048
	v_cvt_pk_bf16_f32 v83, v60, v61
	v_add_u32_e32 v86, v102, v81
	v_mad_i32_i24 v103, v80, s0, 0
	ds_write_b16 v86, v83 offset:27648
	ds_write_b16_d16_hi v86, v83 offset:28048
	v_cvt_pk_bf16_f32 v83, v62, v63
	v_add_u32_e32 v81, v103, v81
	s_lshl_b64 s[8:9], s[8:9], 8
	ds_write_b16 v81, v83 offset:27648
	ds_write_b16_d16_hi v81, v83 offset:28048
	v_add_u32_e32 v81, -16, v94
	s_or_b32 s8, s8, s12
	s_movk_i32 s14, 0x190
	v_cmp_gt_u32_e32 vcc, s31, v81
	v_mov_b64_e32 v[86:87], 0
	v_mov_b64_e32 v[94:95], 0
	s_and_saveexec_b64 s[0:1], vcc
	v_lshl_or_b32 v86, v81, 1, s8
	v_mov_b32_e32 v87, s9
	v_lshlrev_b64 v[86:87], 8, v[86:87]
	v_lshl_or_b32 v86, v98, 2, v86
	v_lshl_add_u64 v[94:95], s[46:47], 0, v[86:87]
	v_lshl_add_u64 v[86:87], s[52:53], 0, v[86:87]
	s_or_b64 exec, exec, s[0:1]
	v_cmp_ne_u64_e32 vcc, 0, v[94:95]
	s_and_saveexec_b64 s[0:1], vcc
	s_cbranch_execz .LBB0_584
	global_store_dwordx4 v[94:95], v[64:67], off
	global_store_dwordx4 v[94:95], v[56:59], off offset:16
	global_store_dwordx4 v[86:87], v[68:71], off
	global_store_dwordx4 v[86:87], v[60:63], off offset:16

; #define LAS __attribute__((address_space(3)))
; __device__ __forceinline__ unsigned cvt_pk_bf16(float lo, float hi) { unsigned r; asm volatile("v_cvt_pk_bf16_f32 %0, %1, %2" : "=v"(r) : "v"(lo), "v"(hi)); return r; }
; __device__ __forceinline__ u32x4 pack8(const float* f) { u32x4 w; w.x = cvt_pk_bf16(f[0], f[1]); w.y = cvt_pk_bf16(f[2], f[3]); w.z = cvt_pk_bf16(f[4], f[5]); w.w = cvt_pk_bf16(f[6], f[7]); return w; }
; __device__ __forceinline__ void attn_unit(const Params& p, int l, LAS unsigned char* lds, bool sample, int b, int c, int kvh) {
;     ...
;         *(LAS u32x4*)(Ks + j * KS_LD + ch * 8) = pack8(kf);
; #pragma unroll
;         for (int i = 0; i < 8; i += 2) { const unsigned w = cvt_pk_bf16(vf[i], vf[i + 1]); const int js = j ^ (ch << 3);
;             Vt[(ch * 8 + i) * VT_LD + js] = (bf16_t)(w & 0xffffu); Vt[(ch * 8 + i + 1) * VT_LD + js] = (bf16_t)(w >> 16); }
;         float* kd = nullptr; float* vd = nullptr;
;         if (!sample) { if (c >= 254 && j >= 128) { const size_t o = ((((size_t)l * 2 + b) * 128 + (c - 254) * 64 + (j - 128)) * 2 + kvh) * 64 + ch * 8; kd = p.out + O_KP + o; vd = p.out + O_VP + o; } }
;         else if (j >= 16 && j < 144) { const size_t o = ((((size_t)l * 8 + b) * 128 + (j - 16)) * 2 + kvh) * 64 + ch * 8; kd = p.out + O_KS + o; vd = p.out + O_VS + o; }
;         if (kd) { *(f32x4*)kd = (f32x4){kf[0], kf[1], kf[2], kf[3]}; *(f32x4*)(kd + 4) = (f32x4){kf[4], kf[5], kf[6], kf[7]};
;                   *(f32x4*)vd = (f32x4){vf[0], vf[1], vf[2], vf[3]}; *(f32x4*)(vd + 4) = (f32x4){vf[4], vf[5], vf[6], vf[7]}; }
.LBB0_590:
	s_or_b64 exec, exec, s[0:1]
	v_cvt_pk_bf16_f32 v56, v36, v37
	v_mad_u64_u32 v[60:61], s[0:1], v92, s83, v[84:85]
	s_waitcnt lgkmcnt(0)
	v_cvt_pk_bf16_f32 v57, v38, v39
	v_cvt_pk_bf16_f32 v58, v32, v33
	v_cvt_pk_bf16_f32 v59, v34, v35
	ds_write_b128 v60, v[56:59]
	v_xor_b32_e32 v56, v92, v98
	v_lshlrev_b32_e32 v56, 1, v56
	v_cvt_pk_bf16_f32 v57, v44, v45
	v_add_u32_e32 v58, v100, v56
	ds_write_b16 v58, v57 offset:27648
	ds_write_b16_d16_hi v58, v57 offset:28048
	v_cvt_pk_bf16_f32 v57, v46, v47
	v_add_u32_e32 v58, v101, v56
	ds_write_b16 v58, v57 offset:27648
	ds_write_b16_d16_hi v58, v57 offset:28048
	v_cvt_pk_bf16_f32 v57, v40, v41
	v_add_u32_e32 v58, v102, v56
	ds_write_b16 v58, v57 offset:27648
	ds_write_b16_d16_hi v58, v57 offset:28048
	v_cvt_pk_bf16_f32 v57, v42, v43
	v_add_u32_e32 v56, v103, v56
	v_add_u32_e32 v60, -16, v92
	ds_write_b16 v56, v57 offset:27648
	ds_write_b16_d16_hi v56, v57 offset:28048
	v_cmp_gt_u32_e32 vcc, s31, v60
	v_mov_b64_e32 v[56:57], 0
	v_mov_b64_e32 v[58:59], 0
	s_and_saveexec_b64 s[0:1], vcc
	v_lshl_or_b32 v56, v60, 1, s8
	v_mov_b32_e32 v57, s9
	v_lshlrev_b64 v[56:57], 8, v[56:57]
	v_lshl_or_b32 v56, v98, 2, v56
	v_lshl_add_u64 v[58:59], s[46:47], 0, v[56:57]
	v_lshl_add_u64 v[56:57], s[52:53], 0, v[56:57]
	s_or_b64 exec, exec, s[0:1]
	v_cmp_ne_u64_e32 vcc, 0, v[58:59]
	s_and_saveexec_b64 s[0:1], vcc
	s_cbranch_execz .LBB0_594
	global_store_dwordx4 v[58:59], v[36:39], off
	global_store_dwordx4 v[58:59], v[32:35], off offset:16
	global_store_dwordx4 v[56:57], v[44:47], off
	global_store_dwordx4 v[56:57], v[40:43], off offset:16

; #define LAS __attribute__((address_space(3)))
; __device__ __forceinline__ unsigned cvt_pk_bf16(float lo, float hi) { unsigned r; asm volatile("v_cvt_pk_bf16_f32 %0, %1, %2" : "=v"(r) : "v"(lo), "v"(hi)); return r; }
; __device__ __forceinline__ u32x4 pack8(const float* f) { u32x4 w; w.x = cvt_pk_bf16(f[0], f[1]); w.y = cvt_pk_bf16(f[2], f[3]); w.z = cvt_pk_bf16(f[4], f[5]); w.w = cvt_pk_bf16(f[6], f[7]); return w; }
; __device__ __forceinline__ void attn_unit(const Params& p, int l, LAS unsigned char* lds, bool sample, int b, int c, int kvh) {
;     ...
;         *(LAS u32x4*)(Ks + j * KS_LD + ch * 8) = pack8(kf);
; #pragma unroll
;         for (int i = 0; i < 8; i += 2) { const unsigned w = cvt_pk_bf16(vf[i], vf[i + 1]); const int js = j ^ (ch << 3);
;             Vt[(ch * 8 + i) * VT_LD + js] = (bf16_t)(w & 0xffffu); Vt[(ch * 8 + i + 1) * VT_LD + js] = (bf16_t)(w >> 16); }
;         float* kd = nullptr; float* vd = nullptr;
;         if (!sample) { if (c >= 254 && j >= 128) { const size_t o = ((((size_t)l * 2 + b) * 128 + (c - 254) * 64 + (j - 128)) * 2 + kvh) * 64 + ch * 8; kd = p.out + O_KP + o; vd = p.out + O_VP + o; } }
;         else if (j >= 16 && j < 144) { const size_t o = ((((size_t)l * 8 + b) * 128 + (j - 16)) * 2 + kvh) * 64 + ch * 8; kd = p.out + O_KS + o; vd = p.out + O_VS + o; }
;         if (kd) { *(f32x4*)kd = (f32x4){kf[0], kf[1], kf[2], kf[3]}; *(f32x4*)(kd + 4) = (f32x4){kf[4], kf[5], kf[6], kf[7]};
;                   *(f32x4*)vd = (f32x4){vf[0], vf[1], vf[2], vf[3]}; *(f32x4*)(vd + 4) = (f32x4){vf[4], vf[5], vf[6], vf[7]}; }
.LBB0_600:
	s_or_b64 exec, exec, s[0:1]
	v_cvt_pk_bf16_f32 v32, v20, v21
	v_mad_u64_u32 v[36:37], s[0:1], v90, s83, v[84:85]
	s_waitcnt lgkmcnt(0)
	v_cvt_pk_bf16_f32 v33, v22, v23
	v_cvt_pk_bf16_f32 v34, v16, v17
	v_cvt_pk_bf16_f32 v35, v18, v19
	ds_write_b128 v36, v[32:35]
	v_xor_b32_e32 v32, v90, v98
	v_lshlrev_b32_e32 v32, 1, v32
	v_cvt_pk_bf16_f32 v33, v28, v29
	v_add_u32_e32 v34, v100, v32
	ds_write_b16 v34, v33 offset:27648
	ds_write_b16_d16_hi v34, v33 offset:28048
	v_cvt_pk_bf16_f32 v33, v30, v31
	v_add_u32_e32 v34, v101, v32
	ds_write_b16 v34, v33 offset:27648
	ds_write_b16_d16_hi v34, v33 offset:28048
	v_cvt_pk_bf16_f32 v33, v24, v25
	v_add_u32_e32 v34, v102, v32
	ds_write_b16 v34, v33 offset:27648
	ds_write_b16_d16_hi v34, v33 offset:28048
	v_cvt_pk_bf16_f32 v33, v26, v27
	v_add_u32_e32 v32, v103, v32
	v_add_u32_e32 v36, -16, v90
	ds_write_b16 v32, v33 offset:27648
	ds_write_b16_d16_hi v32, v33 offset:28048
	v_cmp_gt_u32_e32 vcc, s31, v36
	v_mov_b64_e32 v[32:33], 0
	v_mov_b64_e32 v[34:35], 0
	s_and_saveexec_b64 s[0:1], vcc
	v_lshl_or_b32 v32, v36, 1, s8
	v_mov_b32_e32 v33, s9
	v_lshlrev_b64 v[32:33], 8, v[32:33]
	v_lshl_or_b32 v32, v98, 2, v32
	v_lshl_add_u64 v[34:35], s[46:47], 0, v[32:33]
	v_lshl_add_u64 v[32:33], s[52:53], 0, v[32:33]
	s_or_b64 exec, exec, s[0:1]
	v_cmp_ne_u64_e32 vcc, 0, v[34:35]
	s_and_saveexec_b64 s[0:1], vcc
	s_cbranch_execz .LBB0_604
	global_store_dwordx4 v[34:35], v[20:23], off
	global_store_dwordx4 v[34:35], v[16:19], off offset:16
	global_store_dwordx4 v[32:33], v[28:31], off
	global_store_dwordx4 v[32:33], v[24:27], off offset:16

; #define LAS __attribute__((address_space(3)))
; __device__ __forceinline__ unsigned cvt_pk_bf16(float lo, float hi) { unsigned r; asm volatile("v_cvt_pk_bf16_f32 %0, %1, %2" : "=v"(r) : "v"(lo), "v"(hi)); return r; }
; __device__ __forceinline__ void attn_unit(const Params& p, int l, LAS unsigned char* lds, bool sample, int b, int c, int kvh) {
;     ...
;         f32x16 o[2]; o[0] = (f32x16){}; o[1] = (f32x16){};
; #pragma unroll
;         for (int kt = 0; kt < 6; ++kt)
; #pragma unroll
;             for (int jj = 0; jj < 2; ++jj) {
;                 u32x4 pw;
;                 pw.x = cvt_pk_bf16(s[kt][8 * jj + 0], s[kt][8 * jj + 1]); pw.y = cvt_pk_bf16(s[kt][8 * jj + 2], s[kt][8 * jj + 3]);
;                 pw.z = cvt_pk_bf16(s[kt][8 * jj + 4], s[kt][8 * jj + 5]); pw.w = cvt_pk_bf16(s[kt][8 * jj + 6], s[kt][8 * jj + 7]);
;                 const bf16x8 pa = __builtin_bit_cast(bf16x8, pw);
;                 const int e0 = 32 * kt + 16 * jj + 4 * hi;
; #pragma unroll
;                 for (int db = 0; db < 2; ++db) {
;                     const int sw = (((db * 32 + q32) >> 3) & 7) << 3;
;                     const u32x2 lo = *(const LAS u32x2*)(Vt + (db * 32 + q32) * VT_LD + (e0 ^ sw)), hi2 = *(const LAS u32x2*)(Vt + (db * 32 + q32) * VT_LD + ((e0 + 8) ^ sw));
;                     const bf16x8 vb = __builtin_bit_cast(bf16x8, (u32x4){lo.x, lo.y, hi2.x, hi2.y});
;                     o[db] = __builtin_amdgcn_mfma_f32_32x32x16_bf16(pa, vb, o[db], 0, 0, 0);
;                 }
;                 __builtin_amdgcn_sched_barrier(0);
;             }
.LBB0_607:
	s_or_b64 exec, exec, s[0:1]
	v_mad_u32_u24 v148, v111, s14, 0
	v_bitop3_b32 v0, v98, v208, 24 bitop3:0x78
	s_waitcnt lgkmcnt(0)
	v_bitop3_b32 v1, v83, v208, 24 bitop3:0x78
	v_lshl_add_u32 v0, v0, 1, v148
	v_lshl_add_u32 v2, v1, 1, v148
	v_cvt_pk_bf16_f32 v16, v8, v9
	v_cvt_pk_bf16_f32 v17, v10, v11
	v_cvt_pk_bf16_f32 v18, v14, v15
	v_cvt_pk_bf16_f32 v19, v28, v29
	ds_read_b64 v[0:1], v0 offset:27648
	ds_read_b64 v[2:3], v2 offset:27648
	v_or_b32_e32 v96, 32, v111
	v_add_u32_e32 v149, 0x3200, v148
	v_bitop3_b32 v4, v96, v98, 56 bitop3:0x6c
	v_bitop3_b32 v5, v96, v83, 56 bitop3:0x6c
	v_lshl_add_u32 v4, v4, 1, v149
	v_lshl_add_u32 v5, v5, 1, v149
	ds_read_b64 v[20:21], v4 offset:27648
	ds_read_b64 v[22:23], v5 offset:27648
	s_waitcnt lgkmcnt(2)
	v_mfma_f32_32x32x16_bf16 v[0:15], v[16:19], v[0:3], 0
	s_waitcnt lgkmcnt(0)
	v_mfma_f32_32x32x16_bf16 v[16:31], v[16:19], v[20:23], 0
	v_bitop3_b32 v83, v81, v208, 24 bitop3:0x78
	v_lshl_add_u32 v83, v83, 1, v148
	v_cvt_pk_bf16_f32 v150, v126, v127
	v_cvt_pk_bf16_f32 v151, v124, v125
	v_cvt_pk_bf16_f32 v152, v123, v121
	v_cvt_pk_bf16_f32 v153, v122, v120
	ds_read_b64 v[120:121], v83 offset:27648
	v_bitop3_b32 v83, v82, v208, 24 bitop3:0x78
	v_lshl_add_u32 v83, v83, 1, v148
	ds_read_b64 v[122:123], v83 offset:27648
	v_bitop3_b32 v81, v96, v81, 56 bitop3:0x6c
	s_waitcnt lgkmcnt(0)
	v_mfma_f32_32x32x16_bf16 v[0:15], v[150:153], v[120:123], v[0:15]
	v_lshl_add_u32 v81, v81, 1, v149
	ds_read_b64 v[120:121], v81 offset:27648
	v_bitop3_b32 v81, v96, v82, 56 bitop3:0x6c
	v_lshl_add_u32 v81, v81, 1, v149
	ds_read_b64 v[122:123], v81 offset:27648
	s_waitcnt lgkmcnt(0)
	v_mfma_f32_32x32x16_bf16 v[16:31], v[150:153], v[120:123], v[16:31]
	v_bitop3_b32 v81, v80, v208, 24 bitop3:0x78
	v_lshl_add_u32 v81, v81, 1, v148
	v_cvt_pk_bf16_f32 v120, v119, v117
	v_cvt_pk_bf16_f32 v121, v118, v116
	v_cvt_pk_bf16_f32 v122, v115, v114
	v_cvt_pk_bf16_f32 v123, v113, v112
	ds_read_b64 v[112:113], v81 offset:27648
	v_bitop3_b32 v81, v67, v208, 24 bitop3:0x78
	v_lshl_add_u32 v81, v81, 1, v148
	ds_read_b64 v[114:115], v81 offset:27648
	s_waitcnt lgkmcnt(0)
	v_mfma_f32_32x32x16_bf16 v[0:15], v[120:123], v[112:115], v[0:15]
	v_bitop3_b32 v80, v96, v80, 56 bitop3:0x6c
	v_bitop3_b32 v67, v96, v67, 56 bitop3:0x6c
	v_lshl_add_u32 v80, v80, 1, v149
	v_lshl_add_u32 v67, v67, 1, v149
	ds_read_b64 v[80:81], v80 offset:27648
	ds_read_b64 v[82:83], v67 offset:27648
	s_waitcnt lgkmcnt(0)
	v_mfma_f32_32x32x16_bf16 v[16:31], v[120:123], v[80:83], v[16:31]
	v_bitop3_b32 v67, v65, v208, 24 bitop3:0x78
	v_lshl_add_u32 v67, v67, 1, v148
	v_cvt_pk_bf16_f32 v80, v108, v109
	v_cvt_pk_bf16_f32 v81, v106, v107
	v_cvt_pk_bf16_f32 v82, v105, v103
	v_cvt_pk_bf16_f32 v83, v104, v102
	ds_read_b64 v[102:103], v67 offset:27648
	v_bitop3_b32 v67, v66, v208, 24 bitop3:0x78
	v_lshl_add_u32 v67, v67, 1, v148
	ds_read_b64 v[104:105], v67 offset:27648
	v_bitop3_b32 v65, v96, v65, 56 bitop3:0x6c
	s_waitcnt lgkmcnt(0)
	v_mfma_f32_32x32x16_bf16 v[0:15], v[80:83], v[102:105], v[0:15]
	v_lshl_add_u32 v65, v65, 1, v149
	ds_read_b64 v[102:103], v65 offset:27648
	v_bitop3_b32 v65, v96, v66, 56 bitop3:0x6c
	v_lshl_add_u32 v65, v65, 1, v149
	ds_read_b64 v[104:105], v65 offset:27648
	s_waitcnt lgkmcnt(0)
	v_mfma_f32_32x32x16_bf16 v[16:31], v[80:83], v[102:105], v[16:31]
	v_bitop3_b32 v65, v64, v208, 24 bitop3:0x78
	v_lshl_add_u32 v65, v65, 1, v148
	v_cvt_pk_bf16_f32 v80, v101, v100
	v_cvt_pk_bf16_f32 v81, v99, v95
	v_cvt_pk_bf16_f32 v82, v94, v93
	v_cvt_pk_bf16_f32 v83, v92, v91
	ds_read_b64 v[92:93], v65 offset:27648
	v_bitop3_b32 v65, v52, v208, 24 bitop3:0x78
	v_lshl_add_u32 v65, v65, 1, v148
	ds_read_b64 v[94:95], v65 offset:27648
	s_waitcnt lgkmcnt(0)
	v_mfma_f32_32x32x16_bf16 v[0:15], v[80:83], v[92:95], v[0:15]
	v_bitop3_b32 v64, v96, v64, 56 bitop3:0x6c
	v_bitop3_b32 v52, v96, v52, 56 bitop3:0x6c
	v_lshl_add_u32 v64, v64, 1, v149
	v_lshl_add_u32 v52, v52, 1, v149
	ds_read_b64 v[64:65], v64 offset:27648
	ds_read_b64 v[66:67], v52 offset:27648
	s_waitcnt lgkmcnt(0)
	v_mfma_f32_32x32x16_bf16 v[16:31], v[80:83], v[64:67], v[16:31]
	v_bitop3_b32 v52, v50, v208, 24 bitop3:0x78
	v_lshl_add_u32 v52, v52, 1, v148
	v_cvt_pk_bf16_f32 v64, v90, v89
	v_cvt_pk_bf16_f32 v65, v88, v87
	v_cvt_pk_bf16_f32 v66, v86, v85
	v_cvt_pk_bf16_f32 v67, v84, v79
	ds_read_b64 v[80:81], v52 offset:27648
	v_bitop3_b32 v52, v51, v208, 24 bitop3:0x78
	v_lshl_add_u32 v52, v52, 1, v148
	ds_read_b64 v[82:83], v52 offset:27648
	v_bitop3_b32 v50, v96, v50, 56 bitop3:0x6c
	s_waitcnt lgkmcnt(0)
	v_mfma_f32_32x32x16_bf16 v[0:15], v[64:67], v[80:83], v[0:15]
	v_lshl_add_u32 v50, v50, 1, v149
	ds_read_b64 v[80:81], v50 offset:27648
	v_bitop3_b32 v50, v96, v51, 56 bitop3:0x6c
	v_lshl_add_u32 v50, v50, 1, v149
	ds_read_b64 v[82:83], v50 offset:27648
	s_waitcnt lgkmcnt(0)
	v_mfma_f32_32x32x16_bf16 v[16:31], v[64:67], v[80:83], v[16:31]
	v_bitop3_b32 v50, v48, v208, 24 bitop3:0x78
	v_lshl_add_u32 v50, v50, 1, v148
	v_cvt_pk_bf16_f32 v64, v78, v77
	v_cvt_pk_bf16_f32 v65, v76, v75
	v_cvt_pk_bf16_f32 v66, v74, v73
	v_cvt_pk_bf16_f32 v67, v72, v71
	ds_read_b64 v[72:73], v50 offset:27648
	v_bitop3_b32 v50, v49, v208, 24 bitop3:0x78
	v_lshl_add_u32 v50, v50, 1, v148
	ds_read_b64 v[74:75], v50 offset:27648
	v_bitop3_b32 v48, v96, v48, 56 bitop3:0x6c
	s_waitcnt lgkmcnt(0)
	v_mfma_f32_32x32x16_bf16 v[0:15], v[64:67], v[72:75], v[0:15]
	v_lshl_add_u32 v48, v48, 1, v149
	ds_read_b64 v[72:73], v48 offset:27648
	v_bitop3_b32 v48, v96, v49, 56 bitop3:0x6c
	v_lshl_add_u32 v48, v48, 1, v149
	ds_read_b64 v[74:75], v48 offset:27648
	s_waitcnt lgkmcnt(0)
; #define LAS __attribute__((address_space(3)))
; __device__ __forceinline__ unsigned cvt_pk_bf16(float lo, float hi) { unsigned r; asm volatile("v_cvt_pk_bf16_f32 %0, %1, %2" : "=v"(r) : "v"(lo), "v"(hi)); return r; }
; __device__ __forceinline__ int crow(int r, int hi) { return (r & 3) + 8 * (r >> 2) + 4 * hi; }
; __device__ __forceinline__ void attn_unit(const Params& p, int l, LAS unsigned char* lds, bool sample, int b, int c, int kvh) {
;     ...
; #pragma unroll
;         for (int kt = 0; kt < 6; ++kt)
; #pragma unroll
;             for (int jj = 0; jj < 2; ++jj) {
;                 u32x4 pw;
;                 pw.x = cvt_pk_bf16(s[kt][8 * jj + 0], s[kt][8 * jj + 1]); pw.y = cvt_pk_bf16(s[kt][8 * jj + 2], s[kt][8 * jj + 3]);
;                 pw.z = cvt_pk_bf16(s[kt][8 * jj + 4], s[kt][8 * jj + 5]); pw.w = cvt_pk_bf16(s[kt][8 * jj + 6], s[kt][8 * jj + 7]);
;                 const bf16x8 pa = __builtin_bit_cast(bf16x8, pw);
;                 const int e0 = 32 * kt + 16 * jj + 4 * hi;
; #pragma unroll
;                 for (int db = 0; db < 2; ++db) {
;                     const int sw = (((db * 32 + q32) >> 3) & 7) << 3;
;                     const u32x2 lo = *(const LAS u32x2*)(Vt + (db * 32 + q32) * VT_LD + (e0 ^ sw)), hi2 = *(const LAS u32x2*)(Vt + (db * 32 + q32) * VT_LD + ((e0 + 8) ^ sw));
;                     const bf16x8 vb = __builtin_bit_cast(bf16x8, (u32x4){lo.x, lo.y, hi2.x, hi2.y});
;                     o[db] = __builtin_amdgcn_mfma_f32_32x32x16_bf16(pa, vb, o[db], 0, 0, 0);
;                 }
;                 __builtin_amdgcn_sched_barrier(0);
;             }
;         asm volatile("s_waitcnt lgkmcnt(0)" ::: "memory");
;         LAS bf16_t* ost = (LAS bf16_t*)(lds + LDS_OST) + wid * (32 * 72);
; #pragma unroll
;         for (int r = 0; r < 16; ++r) {
;             const int qq = crow(r, hi);
;             const float inv = wsc[qq];
; #pragma unroll
;             for (int db = 0; db < 2; ++db) ost[qq * 72 + db * 32 + q32] = (bf16_t)(cvt_pk_bf16(o[db][r] * inv, 0.f) & 0xffffu);
	v_mfma_f32_32x32x16_bf16 v[16:31], v[64:67], v[72:75], v[16:31]
	v_bitop3_b32 v52, v40, v208, 24 bitop3:0x78
	v_lshl_add_u32 v52, v52, 1, v148
	v_cvt_pk_bf16_f32 v48, v70, v69
	v_cvt_pk_bf16_f32 v49, v68, v63
	v_cvt_pk_bf16_f32 v50, v62, v61
	v_cvt_pk_bf16_f32 v51, v60, v59
	ds_read_b64 v[60:61], v52 offset:27648
	v_bitop3_b32 v52, v41, v208, 24 bitop3:0x78
	v_lshl_add_u32 v52, v52, 1, v148
	ds_read_b64 v[62:63], v52 offset:27648
	v_bitop3_b32 v40, v96, v40, 56 bitop3:0x6c
	s_waitcnt lgkmcnt(0)
	v_mfma_f32_32x32x16_bf16 v[0:15], v[48:51], v[60:63], v[0:15]
	v_lshl_add_u32 v40, v40, 1, v149
	ds_read_b64 v[60:61], v40 offset:27648
	v_bitop3_b32 v40, v96, v41, 56 bitop3:0x6c
	v_lshl_add_u32 v40, v40, 1, v149
	ds_read_b64 v[62:63], v40 offset:27648
	s_waitcnt lgkmcnt(0)
	v_mfma_f32_32x32x16_bf16 v[16:31], v[48:51], v[60:63], v[16:31]
	v_bitop3_b32 v40, v38, v208, 24 bitop3:0x78
	v_lshl_add_u32 v40, v40, 1, v148
	v_cvt_pk_bf16_f32 v48, v58, v57
	v_cvt_pk_bf16_f32 v49, v56, v55
	v_cvt_pk_bf16_f32 v50, v54, v53
	v_cvt_pk_bf16_f32 v51, v130, v134
	ds_read_b64 v[52:53], v40 offset:27648
	v_bitop3_b32 v40, v39, v208, 24 bitop3:0x78
	v_lshl_add_u32 v40, v40, 1, v148
	ds_read_b64 v[54:55], v40 offset:27648
	v_bitop3_b32 v38, v96, v38, 56 bitop3:0x6c
	s_waitcnt lgkmcnt(0)
	v_mfma_f32_32x32x16_bf16 v[0:15], v[48:51], v[52:55], v[0:15]
	v_lshl_add_u32 v38, v38, 1, v149
	ds_read_b64 v[52:53], v38 offset:27648
	v_bitop3_b32 v38, v96, v39, 56 bitop3:0x6c
	v_lshl_add_u32 v38, v38, 1, v149
	ds_read_b64 v[54:55], v38 offset:27648
	s_waitcnt lgkmcnt(0)
	v_mfma_f32_32x32x16_bf16 v[16:31], v[48:51], v[52:55], v[16:31]
	v_cvt_pk_bf16_f32 v38, v45, v44
	v_cvt_pk_bf16_f32 v39, v43, v46
	v_bitop3_b32 v43, v36, v208, 24 bitop3:0x78
	v_lshl_add_u32 v43, v43, 1, v148
	v_cvt_pk_bf16_f32 v40, v131, v135
	v_cvt_pk_bf16_f32 v41, v137, v140
	ds_read_b64 v[48:49], v43 offset:27648
	v_bitop3_b32 v43, v37, v208, 24 bitop3:0x78
	v_lshl_add_u32 v43, v43, 1, v148
	ds_read_b64 v[50:51], v43 offset:27648
	v_bitop3_b32 v36, v96, v36, 56 bitop3:0x6c
	s_waitcnt lgkmcnt(0)
	v_mfma_f32_32x32x16_bf16 v[0:15], v[38:41], v[48:51], v[0:15]
	v_lshl_add_u32 v36, v36, 1, v149
	ds_read_b64 v[48:49], v36 offset:27648
	v_bitop3_b32 v36, v96, v37, 56 bitop3:0x6c
	v_lshl_add_u32 v36, v36, 1, v149
	ds_read_b64 v[50:51], v36 offset:27648
	s_waitcnt lgkmcnt(0)
	v_mfma_f32_32x32x16_bf16 v[16:31], v[38:41], v[48:51], v[16:31]
	v_cvt_pk_bf16_f32 v36, v42, v47
	v_bitop3_b32 v40, v34, v208, 24 bitop3:0x78
	v_bitop3_b32 v42, v35, v208, 24 bitop3:0x78
	v_lshl_add_u32 v40, v40, 1, v148
	v_lshl_add_u32 v42, v42, 1, v148
	v_cvt_pk_bf16_f32 v37, v128, v132
	v_cvt_pk_bf16_f32 v38, v138, v141
	v_cvt_pk_bf16_f32 v39, v142, v144
	ds_read_b64 v[40:41], v40 offset:27648
	ds_read_b64 v[42:43], v42 offset:27648
	v_bitop3_b32 v34, v96, v34, 56 bitop3:0x6c
	s_waitcnt lgkmcnt(0)
	v_mfma_f32_32x32x16_bf16 v[0:15], v[36:39], v[40:43], v[0:15]
	v_lshl_add_u32 v34, v34, 1, v149
	ds_read_b64 v[40:41], v34 offset:27648
	v_bitop3_b32 v34, v96, v35, 56 bitop3:0x6c
	v_lshl_add_u32 v34, v34, 1, v149
	ds_read_b64 v[42:43], v34 offset:27648
	s_waitcnt lgkmcnt(0)
	v_mfma_f32_32x32x16_bf16 v[16:31], v[36:39], v[40:43], v[16:31]
	v_bitop3_b32 v38, v32, v208, 24 bitop3:0x78
	v_bitop3_b32 v40, v33, v208, 24 bitop3:0x78
	v_lshl_add_u32 v38, v38, 1, v148
	v_lshl_add_u32 v40, v40, 1, v148
	v_cvt_pk_bf16_f32 v34, v129, v133
	v_cvt_pk_bf16_f32 v35, v136, v139
	v_cvt_pk_bf16_f32 v36, v143, v145
	v_cvt_pk_bf16_f32 v37, v146, v147
	ds_read_b64 v[38:39], v38 offset:27648
	ds_read_b64 v[40:41], v40 offset:27648
	v_bitop3_b32 v32, v96, v32, 56 bitop3:0x6c
	s_waitcnt lgkmcnt(0)
	v_mfma_f32_32x32x16_bf16 v[0:15], v[34:37], v[38:41], v[0:15]
	v_lshl_add_u32 v32, v32, 1, v149
	ds_read_b64 v[38:39], v32 offset:27648
	v_bitop3_b32 v32, v96, v33, 56 bitop3:0x6c
	v_lshl_add_u32 v32, v32, 1, v149
	ds_read_b64 v[40:41], v32 offset:27648
	s_waitcnt lgkmcnt(0)
	v_mfma_f32_32x32x16_bf16 v[16:31], v[34:37], v[38:41], v[16:31]
	s_waitcnt lgkmcnt(0)
	v_lshl_add_u32 v36, v98, 2, s8
	ds_read_b32 v33, v36 offset:53248
	s_mulk_i32 s9, 0x1200
	s_add_i32 s7, s9, 0
	v_lshl_add_u32 v32, v111, 1, s7
	s_movk_i32 s0, 0x240
	s_waitcnt lgkmcnt(0)
	v_mul_f32_e32 v0, v0, v33
	v_mad_u64_u32 v[34:35], s[0:1], v110, s0, v[32:33]
	v_cvt_pk_bf16_f32 v0, v0, v97
	ds_write_b16 v34, v0 offset:54272
	s_nop 1
	v_mul_f32_e32 v0, v16, v33
	v_cvt_pk_bf16_f32 v0, v0, v97
	ds_read_b32 v16, v36 offset:53252
	ds_write_b16 v34, v0 offset:54336
	v_or_b32_e32 v0, 1, v98
	v_mad_u64_u32 v[32:33], s[0:1], v0, s83, v[32:33]
	s_waitcnt lgkmcnt(1)
; #define LAS __attribute__((address_space(3)))
; __device__ __forceinline__ unsigned cvt_pk_bf16(float lo, float hi) { unsigned r; asm volatile("v_cvt_pk_bf16_f32 %0, %1, %2" : "=v"(r) : "v"(lo), "v"(hi)); return r; }
; __device__ __forceinline__ int crow(int r, int hi) { return (r & 3) + 8 * (r >> 2) + 4 * hi; }
; __device__ __forceinline__ void attn_unit(const Params& p, int l, LAS unsigned char* lds, bool sample, int b, int c, int kvh) {
;     ...
; #pragma unroll
;         for (int r = 0; r < 16; ++r) {
;             const int qq = crow(r, hi);
;             const float inv = wsc[qq];
; #pragma unroll
;             for (int db = 0; db < 2; ++db) ost[qq * 72 + db * 32 + q32] = (bf16_t)(cvt_pk_bf16(o[db][r] * inv, 0.f) & 0xffffu);
;         }
;         asm volatile("s_waitcnt lgkmcnt(0)" ::: "memory");
; #pragma unroll
;         for (int i = 0; i < 4; ++i) {
;             const int row = i * 8 + (lane >> 3), chn = lane & 7;
;             const u32x4 v = *(const LAS u32x4*)(ost + row * 72 + chn * 8);
;             if (!sample || row < 16) { const long orow = sample ? row0 + row : row0 + half * 32 + row; *(u32x4*)(AD + (size_t)orow * DM + h * 64 + chn * 8) = v; }
;         }
	v_mul_f32_e32 v0, v1, v16
	v_cvt_pk_bf16_f32 v0, v0, v97
	ds_write_b16 v32, v0 offset:54272
	v_mul_f32_e32 v0, v17, v16
	v_cvt_pk_bf16_f32 v0, v0, v97
	ds_read_b32 v1, v36 offset:53256
	ds_write_b16 v32, v0 offset:54336
	s_lshl_b64 s[0:1], s[2:3], 1
	s_add_u32 s0, s48, s0
	s_addc_u32 s1, s49, s1
	s_waitcnt lgkmcnt(1)
	v_mul_f32_e32 v0, v2, v1
	v_cvt_pk_bf16_f32 v0, v0, v97
	ds_write_b16 v32, v0 offset:54416
	v_mul_f32_e32 v0, v18, v1
	v_cvt_pk_bf16_f32 v0, v0, v97
	ds_read_b32 v1, v36 offset:53260
	ds_write_b16 v32, v0 offset:54480
	s_waitcnt lgkmcnt(1)
	v_mul_f32_e32 v0, v3, v1
	v_cvt_pk_bf16_f32 v0, v0, v97
	ds_write_b16 v32, v0 offset:54560
	v_mul_f32_e32 v0, v19, v1
	v_cvt_pk_bf16_f32 v0, v0, v97
	ds_read_b32 v1, v36 offset:53280
	ds_write_b16 v32, v0 offset:54624
	s_waitcnt lgkmcnt(1)
	v_mul_f32_e32 v0, v4, v1
	v_cvt_pk_bf16_f32 v0, v0, v97
	ds_write_b16 v32, v0 offset:55280
	v_mul_f32_e32 v0, v20, v1
	v_cvt_pk_bf16_f32 v0, v0, v97
	ds_read_b32 v1, v36 offset:53284
	ds_write_b16 v32, v0 offset:55344
	s_waitcnt lgkmcnt(1)
	v_mul_f32_e32 v0, v5, v1
	v_cvt_pk_bf16_f32 v0, v0, v97
	ds_write_b16 v32, v0 offset:55424
	v_mul_f32_e32 v0, v21, v1
	v_cvt_pk_bf16_f32 v0, v0, v97
	ds_read_b32 v1, v36 offset:53288
	ds_write_b16 v32, v0 offset:55488
	s_waitcnt lgkmcnt(1)
	v_mul_f32_e32 v0, v6, v1
	v_cvt_pk_bf16_f32 v0, v0, v97
	ds_write_b16 v32, v0 offset:55568
	v_mul_f32_e32 v0, v22, v1
	v_cvt_pk_bf16_f32 v0, v0, v97
	ds_read_b32 v1, v36 offset:53292
	ds_write_b16 v32, v0 offset:55632
	s_waitcnt lgkmcnt(1)
	v_mul_f32_e32 v0, v7, v1
	v_cvt_pk_bf16_f32 v0, v0, v97
	ds_write_b16 v32, v0 offset:55712
	v_mul_f32_e32 v0, v23, v1
	v_cvt_pk_bf16_f32 v0, v0, v97
	ds_read_b32 v1, v36 offset:53312
	ds_write_b16 v32, v0 offset:55776
	s_waitcnt lgkmcnt(1)
	v_mul_f32_e32 v0, v8, v1
	v_cvt_pk_bf16_f32 v0, v0, v97
	ds_write_b16 v32, v0 offset:56432
	v_mul_f32_e32 v0, v24, v1
	v_cvt_pk_bf16_f32 v0, v0, v97
	ds_read_b32 v1, v36 offset:53316
	ds_write_b16 v32, v0 offset:56496
	s_waitcnt lgkmcnt(1)
	v_mul_f32_e32 v0, v9, v1
	v_cvt_pk_bf16_f32 v0, v0, v97
	ds_write_b16 v32, v0 offset:56576
	v_mul_f32_e32 v0, v25, v1
	v_cvt_pk_bf16_f32 v0, v0, v97
	ds_read_b32 v1, v36 offset:53320
	ds_write_b16 v32, v0 offset:56640
	s_waitcnt lgkmcnt(1)
	v_mul_f32_e32 v0, v10, v1
	v_cvt_pk_bf16_f32 v0, v0, v97
	ds_write_b16 v32, v0 offset:56720
	v_mul_f32_e32 v0, v26, v1
	v_cvt_pk_bf16_f32 v0, v0, v97
	ds_read_b32 v1, v36 offset:53324
	ds_write_b16 v32, v0 offset:56784
	s_waitcnt lgkmcnt(1)
	v_mul_f32_e32 v0, v11, v1
	v_cvt_pk_bf16_f32 v0, v0, v97
	ds_write_b16 v32, v0 offset:56864
	v_mul_f32_e32 v0, v27, v1
	v_cvt_pk_bf16_f32 v0, v0, v97
	ds_read_b32 v1, v36 offset:53344
	ds_write_b16 v32, v0 offset:56928
	s_waitcnt lgkmcnt(1)
	v_mul_f32_e32 v0, v12, v1
	v_cvt_pk_bf16_f32 v0, v0, v97
	ds_write_b16 v32, v0 offset:57584
	v_mul_f32_e32 v0, v28, v1
	v_cvt_pk_bf16_f32 v0, v0, v97
	ds_read_b32 v1, v36 offset:53348
	ds_write_b16 v32, v0 offset:57648
	s_waitcnt lgkmcnt(1)
	v_mul_f32_e32 v0, v13, v1
	v_cvt_pk_bf16_f32 v0, v0, v97
	ds_write_b16 v32, v0 offset:57728
	v_mul_f32_e32 v0, v29, v1
	v_cvt_pk_bf16_f32 v0, v0, v97
	ds_read_b32 v1, v36 offset:53352
	ds_write_b16 v32, v0 offset:57792
	s_waitcnt lgkmcnt(1)
	v_mul_f32_e32 v0, v14, v1
	v_cvt_pk_bf16_f32 v0, v0, v97
	ds_write_b16 v32, v0 offset:57872
	v_mul_f32_e32 v0, v30, v1
	v_cvt_pk_bf16_f32 v0, v0, v97
	ds_read_b32 v1, v36 offset:53356
	ds_write_b16 v32, v0 offset:57936
	s_waitcnt lgkmcnt(1)
	v_mul_f32_e32 v0, v15, v1
	v_cvt_pk_bf16_f32 v0, v0, v97
	ds_write_b16 v32, v0 offset:58016
	v_mul_f32_e32 v0, v31, v1
	v_cvt_pk_bf16_f32 v0, v0, v97
	ds_write_b16 v32, v0 offset:58080
	s_waitcnt lgkmcnt(0)
	v_lshlrev_b32_e32 v1, 4, v208
	v_ashrrev_i32_e32 v0, 3, v208
	v_and_b32_e32 v96, 0x70, v1
	v_add_u32_e32 v2, s7, v96
	v_lshl_add_u64 v[4:5], s[0:1], 0, v[96:97]
	v_cmp_gt_i32_e32 vcc, 16, v0
	s_and_saveexec_b64 s[0:1], vcc
	s_cbranch_execz .LBB0_611
	v_mad_u64_u32 v[6:7], s[2:3], v0, s83, v[2:3]
	ds_read_b128 v[6:9], v6 offset:54272
	v_ashrrev_i32_e32 v1, 31, v0
	v_lshl_add_u64 v[10:11], s[40:41], 0, v[0:1]
	v_lshlrev_b64 v[10:11], 11, v[10:11]
	v_lshl_add_u64 v[10:11], v[4:5], 0, v[10:11]
	s_waitcnt lgkmcnt(0)
	global_store_dwordx4 v[10:11], v[6:9], off
	s_or_b64 exec, exec, s[0:1]
	v_cmp_gt_i32_e32 vcc, 8, v0
	s_and_saveexec_b64 s[0:1], vcc
	s_cbranch_execnz .LBB0_612

; #define LAS __attribute__((address_space(3)))
; __device__ __forceinline__ void attn_unit(const Params& p, int l, LAS unsigned char* lds, bool sample, int b, int c, int kvh) {
;     ...
; #pragma unroll
;         for (int i = 0; i < 4; ++i) {
;             const int row = i * 8 + (lane >> 3), chn = lane & 7;
;             const u32x4 v = *(const LAS u32x4*)(ost + row * 72 + chn * 8);
;             if (!sample || row < 16) { const long orow = sample ? row0 + row : row0 + half * 32 + row; *(u32x4*)(AD + (size_t)orow * DM + h * 64 + chn * 8) = v; }
;         }
.LBB0_610:
	v_mad_u64_u32 v[6:7], s[2:3], v0, s83, v[2:3]
	v_add_u32_e32 v10, 16, v0
	ds_read_b128 v[6:9], v6 offset:56576
	v_ashrrev_i32_e32 v11, 31, v10
	v_lshl_add_u64 v[10:11], s[40:41], 0, v[10:11]
	v_lshlrev_b64 v[10:11], 11, v[10:11]
	v_lshl_add_u64 v[10:11], v[4:5], 0, v[10:11]
	s_waitcnt lgkmcnt(0)
	global_store_dwordx4 v[10:11], v[6:9], off
	s_or_b64 exec, exec, s[0:1]
	v_cmp_gt_i32_e32 vcc, -8, v0
	s_and_saveexec_b64 s[0:1], vcc
	s_cbranch_execz .LBB0_284
	s_branch .LBB0_614

; #define LAS __attribute__((address_space(3)))
; __device__ __forceinline__ void attn_unit(const Params& p, int l, LAS unsigned char* lds, bool sample, int b, int c, int kvh) {
;     ...
; #pragma unroll
;         for (int i = 0; i < 4; ++i) {
;             const int row = i * 8 + (lane >> 3), chn = lane & 7;
;             const u32x4 v = *(const LAS u32x4*)(ost + row * 72 + chn * 8);
;             if (!sample || row < 16) { const long orow = sample ? row0 + row : row0 + half * 32 + row; *(u32x4*)(AD + (size_t)orow * DM + h * 64 + chn * 8) = v; }
;         }
.LBB0_612:
	v_mad_u64_u32 v[6:7], s[2:3], v0, s83, v[2:3]
	v_add_u32_e32 v10, 8, v0
	ds_read_b128 v[6:9], v6 offset:55424
	v_ashrrev_i32_e32 v11, 31, v10
	v_lshl_add_u64 v[10:11], s[40:41], 0, v[10:11]
	v_lshlrev_b64 v[10:11], 11, v[10:11]
	v_lshl_add_u64 v[10:11], v[4:5], 0, v[10:11]
	s_waitcnt lgkmcnt(0)
	global_store_dwordx4 v[10:11], v[6:9], off
	s_or_b64 exec, exec, s[0:1]
	v_cmp_gt_i32_e32 vcc, 0, v0
	s_and_saveexec_b64 s[0:1], vcc
	s_cbranch_execnz .LBB0_610

; #define LAS __attribute__((address_space(3)))
; __device__ __forceinline__ void attn_unit(const Params& p, int l, LAS unsigned char* lds, bool sample, int b, int c, int kvh) {
;     ...
; #pragma unroll
;         for (int i = 0; i < 4; ++i) {
;             const int row = i * 8 + (lane >> 3), chn = lane & 7;
;             const u32x4 v = *(const LAS u32x4*)(ost + row * 72 + chn * 8);
;             if (!sample || row < 16) { const long orow = sample ? row0 + row : row0 + half * 32 + row; *(u32x4*)(AD + (size_t)orow * DM + h * 64 + chn * 8) = v; }
;         }
.LBB0_614:
	v_add_u32_e32 v6, 24, v0
	v_mad_u64_u32 v[0:1], s[2:3], v0, s83, v[2:3]
	ds_read_b128 v[0:3], v0 offset:57728
	v_ashrrev_i32_e32 v7, 31, v6
	v_lshl_add_u64 v[6:7], s[40:41], 0, v[6:7]
	v_lshlrev_b64 v[6:7], 11, v[6:7]
	v_lshl_add_u64 v[4:5], v[4:5], 0, v[6:7]
	s_waitcnt lgkmcnt(0)
	global_store_dwordx4 v[4:5], v[0:3], off
	s_branch .LBB0_284

; #define LAS __attribute__((address_space(3)))
; __device__ __forceinline__ unsigned cvt_pk_bf16(float lo, float hi) { unsigned r; asm volatile("v_cvt_pk_bf16_f32 %0, %1, %2" : "=v"(r) : "v"(lo), "v"(hi)); return r; }
; __device__ __forceinline__ void transpose_item(const float* W, int N, const float* ks, bf16_t* WT, int ldo, int orow0, int k0, int n0, LAS float* scr, int lane) {
;     f32x4 v[8];
; #pragma unroll
;     for (int i = 0; i < 8; ++i) v[i] = *(const f32x4*)(W + (size_t)(k0 + i * 4 + (lane >> 4)) * N + n0 + 4 * (lane & 15));
; #pragma unroll
;     for (int i = 0; i < 8; ++i) { const int kk = i * 4 + (lane >> 4); const float sc = ks ? ks[k0 + kk] : 1.0f; LAS float* d = scr + kk * 65 + 4 * (lane & 15);
;         d[0] = v[i][0] * sc; d[1] = v[i][1] * sc; d[2] = v[i][2] * sc; d[3] = v[i][3] * sc; }
;     asm volatile("s_waitcnt lgkmcnt(0)" ::: "memory");
;     const int kc = lane & 3;
; #pragma unroll
;     for (int j = 0; j < 4; ++j) { const int n = (lane >> 2) + 16 * j; const LAS float* s = scr + (8 * kc) * 65 + n;
;         u32x4 o; o.x = cvt_pk_bf16(s[0 * 65], s[1 * 65]); o.y = cvt_pk_bf16(s[2 * 65], s[3 * 65]); o.z = cvt_pk_bf16(s[4 * 65], s[5 * 65]); o.w = cvt_pk_bf16(s[6 * 65], s[7 * 65]);
;         *(u32x4*)(WT + (size_t)(orow0 + n) * ldo + k0 + 8 * kc) = o; }
;     asm volatile("s_waitcnt lgkmcnt(0)" ::: "memory");
; }
; __device__ __forceinline__ void convert_weights(const Params& p, LAS unsigned char* lds, int first, int last, int worker, int nworkers) {
;     ...
;         { const int kb = r / 16, nb = r % 16; transpose_item(p.w_down + (size_t)l * FF * DM, DM, nullptr, (bf16_t*)(wb + WO_DOWN), FF, nb * 64, kb * 32, nb * 64, scr, lane); }
.LBB0_621:
	s_mul_hi_i32 s0, s7, 0x4ec4ec4f
	s_lshr_b32 s1, s0, 31
	s_ashr_i32 s0, s0, 11
	s_add_i32 s2, s0, s1
	s_mul_i32 s0, s2, 0xffffe600
	s_add_i32 s16, s7, s0
	s_ashr_i32 s3, s2, 31
	s_mul_i32 s1, s2, 0x1b00000
	s_mul_hi_i32 s0, s2, 0x1b00000
	s_add_u32 s14, s80, s1
	s_addc_u32 s15, s82, s0
	s_cmpk_gt_i32 s16, 0x67f
	s_mov_b64 s[0:1], -1
	s_cbranch_scc0 .LBB0_643
	s_cmpk_gt_u32 s16, 0x77f
	s_cbranch_scc0 .LBB0_640
	s_cmpk_gt_u32 s16, 0x97f
	s_cbranch_scc0 .LBB0_637
	s_cmpk_gt_u32 s16, 0x147f
	s_cbranch_scc0 .LBB0_626
	v_readlane_b32 s52, v248, 54
	s_mul_i32 s1, s2, 0xb00000
	v_readlane_b32 s62, v247, 0
	s_mul_hi_i32 s0, s2, 0xb00000
	v_readlane_b32 s63, v247, 1
	s_add_u32 s1, s62, s1
	s_mul_i32 s8, s2, 0xffffcc00
	s_addc_u32 s9, s63, s0
	s_add_i32 s8, s10, s8
	s_and_b32 s0, s12, 0x3c0
	s_and_b32 s8, s8, 0x7fffffe0
	s_add_i32 s96, s8, 0xffffd700
	s_lshl_b32 s8, s0, 2
	s_add_u32 s8, s1, s8
	v_or_b32_e32 v28, s96, v32
	s_addc_u32 s9, s9, 0
	v_lshlrev_b32_e32 v96, 2, v34
	v_mov_b32_e32 v29, v97
	v_lshl_add_u64 v[30:31], s[8:9], 0, v[96:97]
	v_lshlrev_b64 v[0:1], 12, v[28:29]
	v_or_b32_e32 v96, 4, v28
	v_lshl_add_u64 v[0:1], v[30:31], 0, v[0:1]
	v_lshlrev_b64 v[4:5], 12, v[96:97]
	global_load_dwordx4 v[0:3], v[0:1], off
	v_lshl_add_u64 v[4:5], v[30:31], 0, v[4:5]
	v_or_b32_e32 v96, 8, v28
	global_load_dwordx4 v[4:7], v[4:5], off
	v_lshlrev_b64 v[8:9], 12, v[96:97]
	v_lshl_add_u64 v[8:9], v[30:31], 0, v[8:9]
	v_or_b32_e32 v96, 12, v28
	global_load_dwordx4 v[8:11], v[8:9], off
	v_lshlrev_b64 v[12:13], 12, v[96:97]
	v_lshl_add_u64 v[12:13], v[30:31], 0, v[12:13]
	v_or_b32_e32 v96, 16, v28
	global_load_dwordx4 v[12:15], v[12:13], off
	v_lshlrev_b64 v[16:17], 12, v[96:97]
	v_lshl_add_u64 v[16:17], v[30:31], 0, v[16:17]
	v_or_b32_e32 v96, 20, v28
	global_load_dwordx4 v[16:19], v[16:17], off
	v_lshlrev_b64 v[20:21], 12, v[96:97]
	v_lshl_add_u64 v[20:21], v[30:31], 0, v[20:21]
	v_or_b32_e32 v96, 24, v28
	global_load_dwordx4 v[20:23], v[20:21], off
	v_lshlrev_b64 v[24:25], 12, v[96:97]
	v_lshl_add_u64 v[24:25], v[30:31], 0, v[24:25]
	v_or_b32_e32 v96, 28, v28
	global_load_dwordx4 v[24:27], v[24:25], off
	v_lshlrev_b64 v[28:29], 12, v[96:97]
	v_lshl_add_u64 v[28:29], v[30:31], 0, v[28:29]
	global_load_dwordx4 v[28:31], v[28:29], off
	v_add_u32_e32 v38, v35, v37
	s_lshl_b64 s[8:9], s[96:97], 1
	s_add_u32 s8, s14, s8
	s_addc_u32 s9, s15, s9
	v_lshlrev_b32_e32 v96, 1, v36
	v_readlane_b32 s53, v248, 55
	v_readlane_b32 s54, v248, 56
	v_readlane_b32 s55, v248, 57
	v_readlane_b32 s56, v248, 58
	v_readlane_b32 s57, v248, 59
	v_readlane_b32 s58, v248, 60
	v_readlane_b32 s59, v248, 61
	v_readlane_b32 s60, v248, 62
	v_readlane_b32 s61, v248, 63
	v_readlane_b32 s64, v247, 2
	v_readlane_b32 s65, v247, 3
	v_readlane_b32 s66, v247, 4
	v_readlane_b32 s67, v247, 5
	s_waitcnt vmcnt(0)
	ds_write2_b32 v38, v0, v1 offset1:1
	ds_write2_b32 v38, v2, v3 offset0:2 offset1:3
	v_add_u32_e32 v0, 0x410, v38
	ds_write2_b32 v0, v4, v5 offset1:1
	v_add_u32_e32 v0, 0x418, v38
	ds_write2_b32 v0, v6, v7 offset1:1
	v_add_u32_e32 v0, 0x820, v38
	ds_write2_b32 v0, v8, v9 offset1:1
	v_add_u32_e32 v0, 0x828, v38
	ds_write2_b32 v0, v10, v11 offset1:1
	v_add_u32_e32 v0, 0xc30, v38
	ds_write2_b32 v0, v12, v13 offset1:1
	v_add_u32_e32 v0, 0xc38, v38
	ds_write2_b32 v0, v14, v15 offset1:1
	v_add_u32_e32 v0, 0x1040, v38
	ds_write2_b32 v0, v16, v17 offset1:1
	v_add_u32_e32 v0, 0x1048, v38
	ds_write2_b32 v0, v18, v19 offset1:1
	v_add_u32_e32 v0, 0x1450, v38
	ds_write2_b32 v0, v20, v21 offset1:1
	v_add_u32_e32 v0, 0x1458, v38
	ds_write2_b32 v0, v22, v23 offset1:1
	v_add_u32_e32 v0, 0x1860, v38
	ds_write2_b32 v0, v24, v25 offset1:1
	v_add_u32_e32 v0, 0x1868, v38
	ds_write2_b32 v0, v26, v27 offset1:1
	v_add_u32_e32 v0, 0x1c70, v38
	ds_write2_b32 v0, v28, v29 offset1:1
	v_add_u32_e32 v0, 0x1c78, v38
	ds_write2_b32 v0, v30, v31 offset1:1
	s_waitcnt lgkmcnt(0)
	v_lshl_add_u64 v[0:1], s[8:9], 0, v[96:97]
	s_mov_b64 s[8:9], 0x1580000
	v_lshl_add_u64 v[4:5], v[0:1], 0, s[8:9]
	ds_read2_b32 v[0:1], v43 offset1:65
	s_waitcnt lgkmcnt(0)
	v_cvt_pk_bf16_f32 v0, v0, v1
	ds_read2_b32 v[2:3], v43 offset0:130 offset1:195
	v_add_u32_e32 v8, 0x400, v43
	s_waitcnt lgkmcnt(0)
	v_cvt_pk_bf16_f32 v1, v2, v3
	ds_read2_b32 v[2:3], v8 offset0:4 offset1:69
	s_waitcnt lgkmcnt(0)
	v_cvt_pk_bf16_f32 v2, v2, v3
	ds_read2_b32 v[6:7], v8 offset0:134 offset1:199
	s_waitcnt lgkmcnt(0)
	v_cvt_pk_bf16_f32 v3, v6, v7
	v_or_b32_e32 v6, s0, v39
	v_mul_u32_u24_e32 v6, 0xb00, v6
	v_lshlrev_b32_e32 v96, 1, v6
	v_lshl_add_u64 v[6:7], v[4:5], 0, v[96:97]
	global_store_dwordx4 v[6:7], v[0:3], off
	ds_read2_b32 v[0:1], v43 offset0:16 offset1:81
	s_waitcnt lgkmcnt(0)
	v_cvt_pk_bf16_f32 v0, v0, v1
	ds_read2_b32 v[2:3], v43 offset0:146 offset1:211
	s_waitcnt lgkmcnt(0)
	v_cvt_pk_bf16_f32 v1, v2, v3
	ds_read2_b32 v[2:3], v8 offset0:20 offset1:85
	s_waitcnt lgkmcnt(0)
	v_cvt_pk_bf16_f32 v2, v2, v3
	ds_read2_b32 v[6:7], v8 offset0:150 offset1:215
	s_waitcnt lgkmcnt(0)
	v_cvt_pk_bf16_f32 v3, v6, v7
	v_or_b32_e32 v6, s0, v44
	v_mul_u32_u24_e32 v6, 0xb00, v6
	v_lshlrev_b32_e32 v96, 1, v6
	v_lshl_add_u64 v[6:7], v[4:5], 0, v[96:97]
	global_store_dwordx4 v[6:7], v[0:3], off
	ds_read2_b32 v[0:1], v43 offset0:32 offset1:97
	s_waitcnt lgkmcnt(0)
	v_cvt_pk_bf16_f32 v0, v0, v1
	ds_read2_b32 v[2:3], v43 offset0:162 offset1:227
	s_waitcnt lgkmcnt(0)
	v_cvt_pk_bf16_f32 v1, v2, v3
	ds_read2_b32 v[2:3], v8 offset0:36 offset1:101
	s_waitcnt lgkmcnt(0)
	v_cvt_pk_bf16_f32 v2, v2, v3
	ds_read2_b32 v[6:7], v8 offset0:166 offset1:231
	s_waitcnt lgkmcnt(0)
	v_cvt_pk_bf16_f32 v3, v6, v7
	v_or_b32_e32 v6, s0, v45
	v_mul_u32_u24_e32 v6, 0xb00, v6
	v_lshlrev_b32_e32 v96, 1, v6
	v_lshl_add_u64 v[6:7], v[4:5], 0, v[96:97]
	global_store_dwordx4 v[6:7], v[0:3], off
	ds_read2_b32 v[0:1], v43 offset0:48 offset1:113
	s_waitcnt lgkmcnt(0)
	v_cvt_pk_bf16_f32 v0, v0, v1
	ds_read2_b32 v[2:3], v43 offset0:178 offset1:243
	s_waitcnt lgkmcnt(0)
	v_cvt_pk_bf16_f32 v1, v2, v3
	ds_read2_b32 v[2:3], v8 offset0:52 offset1:117
	s_waitcnt lgkmcnt(0)
	v_cvt_pk_bf16_f32 v2, v2, v3
	ds_read2_b32 v[6:7], v8 offset0:182 offset1:247
	s_waitcnt lgkmcnt(0)
	v_cvt_pk_bf16_f32 v3, v6, v7
	v_or_b32_e32 v6, s0, v46
	v_mul_u32_u24_e32 v6, 0xb00, v6
	v_lshlrev_b32_e32 v96, 1, v6
	v_lshl_add_u64 v[4:5], v[4:5], 0, v[96:97]
	global_store_dwordx4 v[4:5], v[0:3], off
	s_waitcnt lgkmcnt(0)
	s_mov_b64 s[0:1], 0

; #define LAS __attribute__((address_space(3)))
; __device__ __forceinline__ unsigned cvt_pk_bf16(float lo, float hi) { unsigned r; asm volatile("v_cvt_pk_bf16_f32 %0, %1, %2" : "=v"(r) : "v"(lo), "v"(hi)); return r; }
; __device__ __forceinline__ void transpose_item(const float* W, int N, const float* ks, bf16_t* WT, int ldo, int orow0, int k0, int n0, LAS float* scr, int lane) {
;     f32x4 v[8];
; #pragma unroll
;     for (int i = 0; i < 8; ++i) v[i] = *(const f32x4*)(W + (size_t)(k0 + i * 4 + (lane >> 4)) * N + n0 + 4 * (lane & 15));
; #pragma unroll
;     for (int i = 0; i < 8; ++i) { const int kk = i * 4 + (lane >> 4); const float sc = ks ? ks[k0 + kk] : 1.0f; LAS float* d = scr + kk * 65 + 4 * (lane & 15);
;         d[0] = v[i][0] * sc; d[1] = v[i][1] * sc; d[2] = v[i][2] * sc; d[3] = v[i][3] * sc; }
;     asm volatile("s_waitcnt lgkmcnt(0)" ::: "memory");
;     const int kc = lane & 3;
; #pragma unroll
;     for (int j = 0; j < 4; ++j) { const int n = (lane >> 2) + 16 * j; const LAS float* s = scr + (8 * kc) * 65 + n;
;         u32x4 o; o.x = cvt_pk_bf16(s[0 * 65], s[1 * 65]); o.y = cvt_pk_bf16(s[2 * 65], s[3 * 65]); o.z = cvt_pk_bf16(s[4 * 65], s[5 * 65]); o.w = cvt_pk_bf16(s[6 * 65], s[7 * 65]);
;         *(u32x4*)(WT + (size_t)(orow0 + n) * ldo + k0 + 8 * kc) = o; }
;     asm volatile("s_waitcnt lgkmcnt(0)" ::: "memory");
; }
; __device__ __forceinline__ void convert_weights(const Params& p, LAS unsigned char* lds, int first, int last, int worker, int nworkers) {
;     ...
;         if (r < WI_OUT) { const int kb = r / 16, nb = r % 16; transpose_item(p.w_out + (size_t)l * DM * DM, DM, nullptr, (bf16_t*)(wb + WO_OUT), DM, nb * 64, kb * 32, nb * 64, scr, lane); continue; } r -= WI_OUT;
.LBB0_637:
	s_andn2_b64 vcc, exec, s[0:1]
	s_cbranch_vccnz .LBB0_639
	s_lshl_b64 s[0:1], s[2:3], 22
	v_readlane_b32 s52, v248, 54
	v_readlane_b32 s53, v248, 55
	s_add_u32 s8, s52, s0
	s_mul_i32 s9, s2, 0xffffcc00
	s_addc_u32 s1, s53, s1
	s_add_i32 s9, s10, s9
	s_and_b32 s0, s12, 0x3c0
	s_and_b32 s9, s9, 0x1fe0
	s_add_i32 s96, s9, 0xfffff100
	s_lshl_b32 s9, s0, 2
	s_add_u32 s8, s8, s9
	v_or_b32_e32 v28, s96, v32
	s_addc_u32 s9, s1, 0
	v_lshlrev_b32_e32 v96, 2, v34
	v_mov_b32_e32 v29, v97
	v_lshl_add_u64 v[30:31], s[8:9], 0, v[96:97]
	v_lshlrev_b64 v[0:1], 12, v[28:29]
	v_or_b32_e32 v96, 4, v28
	v_lshl_add_u64 v[0:1], v[30:31], 0, v[0:1]
	v_lshlrev_b64 v[4:5], 12, v[96:97]
	global_load_dwordx4 v[0:3], v[0:1], off
	v_lshl_add_u64 v[4:5], v[30:31], 0, v[4:5]
	v_or_b32_e32 v96, 8, v28
	global_load_dwordx4 v[4:7], v[4:5], off
	v_lshlrev_b64 v[8:9], 12, v[96:97]
	v_lshl_add_u64 v[8:9], v[30:31], 0, v[8:9]
	v_or_b32_e32 v96, 12, v28
	global_load_dwordx4 v[8:11], v[8:9], off
	v_lshlrev_b64 v[12:13], 12, v[96:97]
	v_lshl_add_u64 v[12:13], v[30:31], 0, v[12:13]
	v_or_b32_e32 v96, 16, v28
	global_load_dwordx4 v[12:15], v[12:13], off
	v_lshlrev_b64 v[16:17], 12, v[96:97]
	v_lshl_add_u64 v[16:17], v[30:31], 0, v[16:17]
	v_or_b32_e32 v96, 20, v28
	global_load_dwordx4 v[16:19], v[16:17], off
	v_lshlrev_b64 v[20:21], 12, v[96:97]
	v_lshl_add_u64 v[20:21], v[30:31], 0, v[20:21]
	v_or_b32_e32 v96, 24, v28
	global_load_dwordx4 v[20:23], v[20:21], off
	v_lshlrev_b64 v[24:25], 12, v[96:97]
	v_lshl_add_u64 v[24:25], v[30:31], 0, v[24:25]
	v_or_b32_e32 v96, 28, v28
	global_load_dwordx4 v[24:27], v[24:25], off
	v_lshlrev_b64 v[28:29], 12, v[96:97]
	v_lshl_add_u64 v[28:29], v[30:31], 0, v[28:29]
	global_load_dwordx4 v[28:31], v[28:29], off
	v_add_u32_e32 v38, v35, v37
	s_lshl_b64 s[8:9], s[96:97], 1
	s_add_u32 s8, s14, s8
	s_addc_u32 s9, s15, s9
	v_lshlrev_b32_e32 v96, 1, v36
	v_readlane_b32 s54, v248, 56
	v_readlane_b32 s55, v248, 57
	v_readlane_b32 s56, v248, 58
	v_readlane_b32 s57, v248, 59
	v_readlane_b32 s58, v248, 60
	v_readlane_b32 s59, v248, 61
	v_readlane_b32 s60, v248, 62
	v_readlane_b32 s61, v248, 63
	v_readlane_b32 s62, v247, 0
	v_readlane_b32 s63, v247, 1
	v_readlane_b32 s64, v247, 2
	v_readlane_b32 s65, v247, 3
	v_readlane_b32 s66, v247, 4
	v_readlane_b32 s67, v247, 5
	s_waitcnt vmcnt(0)
	ds_write2_b32 v38, v0, v1 offset1:1
	ds_write2_b32 v38, v2, v3 offset0:2 offset1:3
	v_add_u32_e32 v0, 0x410, v38
	ds_write2_b32 v0, v4, v5 offset1:1
	v_add_u32_e32 v0, 0x418, v38
	ds_write2_b32 v0, v6, v7 offset1:1
	v_add_u32_e32 v0, 0x820, v38
	ds_write2_b32 v0, v8, v9 offset1:1
	v_add_u32_e32 v0, 0x828, v38
	ds_write2_b32 v0, v10, v11 offset1:1
	v_add_u32_e32 v0, 0xc30, v38
	ds_write2_b32 v0, v12, v13 offset1:1
	v_add_u32_e32 v0, 0xc38, v38
	ds_write2_b32 v0, v14, v15 offset1:1
	v_add_u32_e32 v0, 0x1040, v38
	ds_write2_b32 v0, v16, v17 offset1:1
	v_add_u32_e32 v0, 0x1048, v38
	ds_write2_b32 v0, v18, v19 offset1:1
	v_add_u32_e32 v0, 0x1450, v38
	ds_write2_b32 v0, v20, v21 offset1:1
	v_add_u32_e32 v0, 0x1458, v38
	ds_write2_b32 v0, v22, v23 offset1:1
	v_add_u32_e32 v0, 0x1860, v38
	ds_write2_b32 v0, v24, v25 offset1:1
	v_add_u32_e32 v0, 0x1868, v38
	ds_write2_b32 v0, v26, v27 offset1:1
	v_add_u32_e32 v0, 0x1c70, v38
	ds_write2_b32 v0, v28, v29 offset1:1
	v_add_u32_e32 v0, 0x1c78, v38
	ds_write2_b32 v0, v30, v31 offset1:1
	s_waitcnt lgkmcnt(0)
	v_lshl_add_u64 v[0:1], s[8:9], 0, v[96:97]
	s_mov_b64 s[8:9], 0x880000
	v_lshl_add_u64 v[4:5], v[0:1], 0, s[8:9]
	ds_read2_b32 v[0:1], v43 offset1:65
	s_waitcnt lgkmcnt(0)
	v_cvt_pk_bf16_f32 v0, v0, v1
	ds_read2_b32 v[2:3], v43 offset0:130 offset1:195
	v_add_u32_e32 v8, 0x400, v43
	s_waitcnt lgkmcnt(0)
	v_cvt_pk_bf16_f32 v1, v2, v3
	ds_read2_b32 v[2:3], v8 offset0:4 offset1:69
	s_waitcnt lgkmcnt(0)
	v_cvt_pk_bf16_f32 v2, v2, v3
	ds_read2_b32 v[6:7], v8 offset0:134 offset1:199
	s_waitcnt lgkmcnt(0)
	v_cvt_pk_bf16_f32 v3, v6, v7
	v_or_b32_e32 v6, s0, v39
	v_lshlrev_b32_e32 v96, 11, v6
	v_lshl_add_u64 v[6:7], v[4:5], 0, v[96:97]
	global_store_dwordx4 v[6:7], v[0:3], off
	ds_read2_b32 v[0:1], v43 offset0:16 offset1:81
	s_waitcnt lgkmcnt(0)
	v_cvt_pk_bf16_f32 v0, v0, v1
	ds_read2_b32 v[2:3], v43 offset0:146 offset1:211
	s_waitcnt lgkmcnt(0)
	v_cvt_pk_bf16_f32 v1, v2, v3
	ds_read2_b32 v[2:3], v8 offset0:20 offset1:85
	s_waitcnt lgkmcnt(0)
	v_cvt_pk_bf16_f32 v2, v2, v3
	ds_read2_b32 v[6:7], v8 offset0:150 offset1:215
	s_waitcnt lgkmcnt(0)
	v_cvt_pk_bf16_f32 v3, v6, v7
	v_or_b32_e32 v6, s0, v44
	v_lshlrev_b32_e32 v96, 11, v6
	v_lshl_add_u64 v[6:7], v[4:5], 0, v[96:97]
	global_store_dwordx4 v[6:7], v[0:3], off
	ds_read2_b32 v[0:1], v43 offset0:32 offset1:97
	s_waitcnt lgkmcnt(0)
	v_cvt_pk_bf16_f32 v0, v0, v1
	ds_read2_b32 v[2:3], v43 offset0:162 offset1:227
	s_waitcnt lgkmcnt(0)
	v_cvt_pk_bf16_f32 v1, v2, v3
	ds_read2_b32 v[2:3], v8 offset0:36 offset1:101
	s_waitcnt lgkmcnt(0)
	v_cvt_pk_bf16_f32 v2, v2, v3
	ds_read2_b32 v[6:7], v8 offset0:166 offset1:231
	s_waitcnt lgkmcnt(0)
	v_cvt_pk_bf16_f32 v3, v6, v7
	v_or_b32_e32 v6, s0, v45
	v_lshlrev_b32_e32 v96, 11, v6
	v_lshl_add_u64 v[6:7], v[4:5], 0, v[96:97]
	global_store_dwordx4 v[6:7], v[0:3], off
	ds_read2_b32 v[0:1], v43 offset0:48 offset1:113
	s_waitcnt lgkmcnt(0)
	v_cvt_pk_bf16_f32 v0, v0, v1
	ds_read2_b32 v[2:3], v43 offset0:178 offset1:243
	s_waitcnt lgkmcnt(0)
	v_cvt_pk_bf16_f32 v1, v2, v3
	ds_read2_b32 v[2:3], v8 offset0:52 offset1:117
	s_waitcnt lgkmcnt(0)
	v_cvt_pk_bf16_f32 v2, v2, v3
	ds_read2_b32 v[6:7], v8 offset0:182 offset1:247
	s_waitcnt lgkmcnt(0)
	v_cvt_pk_bf16_f32 v3, v6, v7
	v_or_b32_e32 v6, s0, v46
	v_lshlrev_b32_e32 v96, 11, v6
	v_lshl_add_u64 v[4:5], v[4:5], 0, v[96:97]
	global_store_dwordx4 v[4:5], v[0:3], off
	s_waitcnt lgkmcnt(0)

; #define LAS __attribute__((address_space(3)))
; __device__ __forceinline__ unsigned cvt_pk_bf16(float lo, float hi) { unsigned r; asm volatile("v_cvt_pk_bf16_f32 %0, %1, %2" : "=v"(r) : "v"(lo), "v"(hi)); return r; }
; __device__ __forceinline__ void transpose_item(const float* W, int N, const float* ks, bf16_t* WT, int ldo, int orow0, int k0, int n0, LAS float* scr, int lane) {
;     f32x4 v[8];
; #pragma unroll
;     for (int i = 0; i < 8; ++i) v[i] = *(const f32x4*)(W + (size_t)(k0 + i * 4 + (lane >> 4)) * N + n0 + 4 * (lane & 15));
; #pragma unroll
;     for (int i = 0; i < 8; ++i) { const int kk = i * 4 + (lane >> 4); const float sc = ks ? ks[k0 + kk] : 1.0f; LAS float* d = scr + kk * 65 + 4 * (lane & 15);
;         d[0] = v[i][0] * sc; d[1] = v[i][1] * sc; d[2] = v[i][2] * sc; d[3] = v[i][3] * sc; }
;     asm volatile("s_waitcnt lgkmcnt(0)" ::: "memory");
;     const int kc = lane & 3;
; #pragma unroll
;     for (int j = 0; j < 4; ++j) { const int n = (lane >> 2) + 16 * j; const LAS float* s = scr + (8 * kc) * 65 + n;
;         u32x4 o; o.x = cvt_pk_bf16(s[0 * 65], s[1 * 65]); o.y = cvt_pk_bf16(s[2 * 65], s[3 * 65]); o.z = cvt_pk_bf16(s[4 * 65], s[5 * 65]); o.w = cvt_pk_bf16(s[6 * 65], s[7 * 65]);
;         *(u32x4*)(WT + (size_t)(orow0 + n) * ldo + k0 + 8 * kc) = o; }
;     asm volatile("s_waitcnt lgkmcnt(0)" ::: "memory");
; }
; __device__ __forceinline__ void convert_weights(const Params& p, LAS unsigned char* lds, int first, int last, int worker, int nworkers) {
;     ...
;         if (r < WI_BA) { const int kb = r / 16, nb = r % 16; transpose_item(p.w_br_attn + (size_t)l * 512 * DM, DM, nullptr, (bf16_t*)(wb + WO_MIX), 512, nb * 64, kb * 32, nb * 64, scr, lane); continue; } r -= WI_BA;
.LBB0_640:
	s_andn2_b64 vcc, exec, s[0:1]
	s_cbranch_vccnz .LBB0_642
	v_readlane_b32 s52, v249, 20
	v_readlane_b32 s62, v249, 30
	v_readlane_b32 s63, v249, 31
	s_lshl_b64 s[0:1], s[2:3], 21
	s_mov_b64 s[50:51], s[62:63]
	s_add_u32 s3, s50, s0
	s_addc_u32 s1, s51, s1
	s_lshl_b32 s8, s2, 10
	s_sub_i32 s8, s10, s8
	s_and_b32 s0, s12, 0x3c0
	s_and_b32 s8, s8, 0xfe0
	s_add_i32 s96, s8, 0xfffff300
	s_lshl_b32 s8, s0, 2
	s_add_u32 s8, s3, s8
	v_or_b32_e32 v28, s96, v32
	s_addc_u32 s9, s1, 0
	v_lshlrev_b32_e32 v96, 2, v34
	v_mov_b32_e32 v29, v97
	v_lshl_add_u64 v[30:31], s[8:9], 0, v[96:97]
	v_lshlrev_b64 v[0:1], 12, v[28:29]
	v_or_b32_e32 v96, 4, v28
	v_lshl_add_u64 v[0:1], v[30:31], 0, v[0:1]
	v_lshlrev_b64 v[4:5], 12, v[96:97]
	global_load_dwordx4 v[0:3], v[0:1], off
	v_lshl_add_u64 v[4:5], v[30:31], 0, v[4:5]
	v_or_b32_e32 v96, 8, v28
	global_load_dwordx4 v[4:7], v[4:5], off
	v_lshlrev_b64 v[8:9], 12, v[96:97]
	v_lshl_add_u64 v[8:9], v[30:31], 0, v[8:9]
	v_or_b32_e32 v96, 12, v28
	global_load_dwordx4 v[8:11], v[8:9], off
	v_lshlrev_b64 v[12:13], 12, v[96:97]
	v_lshl_add_u64 v[12:13], v[30:31], 0, v[12:13]
	v_or_b32_e32 v96, 16, v28
	global_load_dwordx4 v[12:15], v[12:13], off
	v_lshlrev_b64 v[16:17], 12, v[96:97]
	v_lshl_add_u64 v[16:17], v[30:31], 0, v[16:17]
	v_or_b32_e32 v96, 20, v28
	global_load_dwordx4 v[16:19], v[16:17], off
	v_lshlrev_b64 v[20:21], 12, v[96:97]
	v_lshl_add_u64 v[20:21], v[30:31], 0, v[20:21]
	v_or_b32_e32 v96, 24, v28
	global_load_dwordx4 v[20:23], v[20:21], off
	v_lshlrev_b64 v[24:25], 12, v[96:97]
	v_lshl_add_u64 v[24:25], v[30:31], 0, v[24:25]
	v_or_b32_e32 v96, 28, v28
	global_load_dwordx4 v[24:27], v[24:25], off
	v_lshlrev_b64 v[28:29], 12, v[96:97]
	v_lshl_add_u64 v[28:29], v[30:31], 0, v[28:29]
	global_load_dwordx4 v[28:31], v[28:29], off
	v_add_u32_e32 v38, v35, v37
	s_lshl_b64 s[8:9], s[96:97], 1
	s_add_u32 s8, s14, s8
	s_addc_u32 s9, s15, s9
	v_lshlrev_b32_e32 v96, 1, v36
	v_readlane_b32 s53, v249, 21
	v_readlane_b32 s54, v249, 22
	v_readlane_b32 s55, v249, 23
	v_readlane_b32 s56, v249, 24
	v_readlane_b32 s57, v249, 25
	v_readlane_b32 s58, v249, 26
	v_readlane_b32 s59, v249, 27
	v_readlane_b32 s60, v249, 28
	v_readlane_b32 s61, v249, 29
	v_readlane_b32 s64, v249, 32
	v_readlane_b32 s65, v249, 33
	v_readlane_b32 s66, v249, 34
	v_readlane_b32 s67, v249, 35
	s_waitcnt vmcnt(0)
	ds_write2_b32 v38, v0, v1 offset1:1
	ds_write2_b32 v38, v2, v3 offset0:2 offset1:3
	v_add_u32_e32 v0, 0x410, v38
	ds_write2_b32 v0, v4, v5 offset1:1
	v_add_u32_e32 v0, 0x418, v38
	ds_write2_b32 v0, v6, v7 offset1:1
	v_add_u32_e32 v0, 0x820, v38
	ds_write2_b32 v0, v8, v9 offset1:1
	v_add_u32_e32 v0, 0x828, v38
	ds_write2_b32 v0, v10, v11 offset1:1
	v_add_u32_e32 v0, 0xc30, v38
	ds_write2_b32 v0, v12, v13 offset1:1
	v_add_u32_e32 v0, 0xc38, v38
	ds_write2_b32 v0, v14, v15 offset1:1
	v_add_u32_e32 v0, 0x1040, v38
	ds_write2_b32 v0, v16, v17 offset1:1
	v_add_u32_e32 v0, 0x1048, v38
	ds_write2_b32 v0, v18, v19 offset1:1
	v_add_u32_e32 v0, 0x1450, v38
	ds_write2_b32 v0, v20, v21 offset1:1
	v_add_u32_e32 v0, 0x1458, v38
	ds_write2_b32 v0, v22, v23 offset1:1
	v_add_u32_e32 v0, 0x1860, v38
	ds_write2_b32 v0, v24, v25 offset1:1
	v_add_u32_e32 v0, 0x1868, v38
	ds_write2_b32 v0, v26, v27 offset1:1
	v_add_u32_e32 v0, 0x1c70, v38
	ds_write2_b32 v0, v28, v29 offset1:1
	v_add_u32_e32 v0, 0x1c78, v38
	ds_write2_b32 v0, v30, v31 offset1:1
	s_waitcnt lgkmcnt(0)
	v_lshl_add_u64 v[0:1], s[8:9], 0, v[96:97]
	s_mov_b64 s[8:9], 0x680000
	v_lshl_add_u64 v[4:5], v[0:1], 0, s[8:9]
	ds_read2_b32 v[0:1], v43 offset1:65
	s_waitcnt lgkmcnt(0)
	v_cvt_pk_bf16_f32 v0, v0, v1
	ds_read2_b32 v[2:3], v43 offset0:130 offset1:195
	v_add_u32_e32 v8, 0x400, v43
	s_waitcnt lgkmcnt(0)
	v_cvt_pk_bf16_f32 v1, v2, v3
	ds_read2_b32 v[2:3], v8 offset0:4 offset1:69
	s_waitcnt lgkmcnt(0)
	v_cvt_pk_bf16_f32 v2, v2, v3
	ds_read2_b32 v[6:7], v8 offset0:134 offset1:199
	s_waitcnt lgkmcnt(0)
	v_cvt_pk_bf16_f32 v3, v6, v7
	v_or_b32_e32 v6, s0, v39
	v_lshlrev_b32_e32 v96, 10, v6
	v_lshl_add_u64 v[6:7], v[4:5], 0, v[96:97]
	global_store_dwordx4 v[6:7], v[0:3], off
	ds_read2_b32 v[0:1], v43 offset0:16 offset1:81
	s_waitcnt lgkmcnt(0)
	v_cvt_pk_bf16_f32 v0, v0, v1
	ds_read2_b32 v[2:3], v43 offset0:146 offset1:211
	s_waitcnt lgkmcnt(0)
	v_cvt_pk_bf16_f32 v1, v2, v3
	ds_read2_b32 v[2:3], v8 offset0:20 offset1:85
	s_waitcnt lgkmcnt(0)
	v_cvt_pk_bf16_f32 v2, v2, v3
	ds_read2_b32 v[6:7], v8 offset0:150 offset1:215
	s_waitcnt lgkmcnt(0)
	v_cvt_pk_bf16_f32 v3, v6, v7
	v_or_b32_e32 v6, s0, v44
	v_lshlrev_b32_e32 v96, 10, v6
	v_lshl_add_u64 v[6:7], v[4:5], 0, v[96:97]
	global_store_dwordx4 v[6:7], v[0:3], off
	ds_read2_b32 v[0:1], v43 offset0:32 offset1:97
	s_waitcnt lgkmcnt(0)
	v_cvt_pk_bf16_f32 v0, v0, v1
	ds_read2_b32 v[2:3], v43 offset0:162 offset1:227
	s_waitcnt lgkmcnt(0)
	v_cvt_pk_bf16_f32 v1, v2, v3
	ds_read2_b32 v[2:3], v8 offset0:36 offset1:101
	s_waitcnt lgkmcnt(0)
	v_cvt_pk_bf16_f32 v2, v2, v3
	ds_read2_b32 v[6:7], v8 offset0:166 offset1:231
	s_waitcnt lgkmcnt(0)
	v_cvt_pk_bf16_f32 v3, v6, v7
	v_or_b32_e32 v6, s0, v45
	v_lshlrev_b32_e32 v96, 10, v6
	v_lshl_add_u64 v[6:7], v[4:5], 0, v[96:97]
	global_store_dwordx4 v[6:7], v[0:3], off
	ds_read2_b32 v[0:1], v43 offset0:48 offset1:113
	s_waitcnt lgkmcnt(0)
	v_cvt_pk_bf16_f32 v0, v0, v1
	ds_read2_b32 v[2:3], v43 offset0:178 offset1:243
	s_waitcnt lgkmcnt(0)
	v_cvt_pk_bf16_f32 v1, v2, v3
	ds_read2_b32 v[2:3], v8 offset0:52 offset1:117
	s_waitcnt lgkmcnt(0)
	v_cvt_pk_bf16_f32 v2, v2, v3
	ds_read2_b32 v[6:7], v8 offset0:182 offset1:247
	s_waitcnt lgkmcnt(0)
	v_cvt_pk_bf16_f32 v3, v6, v7
	v_or_b32_e32 v6, s0, v46
	v_lshlrev_b32_e32 v96, 10, v6
	v_lshl_add_u64 v[4:5], v[4:5], 0, v[96:97]
	global_store_dwordx4 v[4:5], v[0:3], off
	s_waitcnt lgkmcnt(0)

; #define LAS __attribute__((address_space(3)))
; template <int KSTEPS  >
; __device__ __forceinline__ void small_mma_ksplit(f32x4 (&acc)[2], const bf16_t* A, int lda, const bf16_t* Bt, int ldb, int n0, LAS unsigned char* lds, const SmallId& id) {
;     ...
;     for (int ks = 0; ks < KSTEPS; ++ks) {
;         bf16x8 a[8], b[2];
; #pragma unroll
;         for (int rb = 0; rb < 8; ++rb) a[rb] = *(const bf16x8*)(ap + (size_t)(16 * rb) * lda + 32 * ks);
;         b[0] = *(const bf16x8*)(bp + 32 * ks); b[1] = *(const bf16x8*)(bp + (size_t)16 * ldb + 32 * ks);
; #pragma unroll
;         for (int rb = 0; rb < 8; ++rb) { part[rb][0] = __builtin_amdgcn_mfma_f32_16x16x32_bf16(b[0], a[rb], part[rb][0], 0, 0, 0); part[rb][1] = __builtin_amdgcn_mfma_f32_16x16x32_bf16(b[1], a[rb], part[rb][1], 0, 0, 0); }
;     }
;     LAS f32x4* red = (LAS f32x4*)lds;
; #pragma unroll
;     for (int rb = 0; rb < 8; ++rb) { red[((id.w * 8 + rb) * 2 + 0) * 64 + lane] = part[rb][0]; red[((id.w * 8 + rb) * 2 + 1) * 64 + lane] = part[rb][1]; }
;     asm volatile("s_waitcnt lgkmcnt(0)" ::: "memory"); __syncthreads();
;     acc[0] = (f32x4){0.f, 0.f, 0.f, 0.f}; acc[1] = acc[0];
; #pragma unroll
;     for (int w2 = 0; w2 < 8; ++w2) { acc[0] += red[((w2 * 8 + id.w) * 2 + 0) * 64 + lane]; acc[1] += red[((w2 * 8 + id.w) * 2 + 1) * 64 + lane]; }
.LBB0_710:
	s_lshl_b64 s[2:3], s[2:3], 1
	v_lshl_add_u64 v[68:69], v[64:65], 0, s[2:3]
	v_lshl_add_u64 v[76:77], v[66:67], 0, s[2:3]
	v_lshl_add_u64 v[80:81], v[130:131], 0, s[2:3]
	global_load_dwordx4 v[68:71], v[68:69], off
	global_load_dwordx4 v[72:75], v[80:81], off
	global_load_dwordx4 v[76:79], v[76:77], off
	v_add_co_u32_e32 v82, vcc, s9, v80
	s_mov_b64 s[2:3], 32
	s_nop 1
	v_addc_co_u32_e32 v83, vcc, 0, v81, vcc
	global_load_dwordx4 v[180:183], v[82:83], off
	v_add_co_u32_e32 v82, vcc, s10, v80
	s_nop 1
	v_addc_co_u32_e32 v83, vcc, 0, v81, vcc
	global_load_dwordx4 v[184:187], v[82:83], off
	v_add_co_u32_e32 v82, vcc, s11, v80
	s_nop 1
	v_addc_co_u32_e32 v83, vcc, 0, v81, vcc
	global_load_dwordx4 v[188:191], v[82:83], off
	v_add_co_u32_e32 v82, vcc, s12, v80
	s_nop 1
	v_addc_co_u32_e32 v83, vcc, 0, v81, vcc
	global_load_dwordx4 v[206:209], v[82:83], off
	v_add_co_u32_e32 v82, vcc, s13, v80
	s_nop 1
	v_addc_co_u32_e32 v83, vcc, 0, v81, vcc
	global_load_dwordx4 v[210:213], v[82:83], off
	v_add_co_u32_e32 v82, vcc, s14, v80
	s_nop 1
	v_addc_co_u32_e32 v83, vcc, 0, v81, vcc
	v_add_co_u32_e32 v80, vcc, s15, v80
	global_load_dwordx4 v[214:217], v[82:83], off
	s_nop 1
	v_addc_co_u32_e32 v81, vcc, 0, v81, vcc
	s_and_b64 vcc, exec, s[0:1]
	s_mov_b64 s[0:1], 0
	global_load_dwordx4 v[218:221], v[80:81], off
	s_waitcnt vmcnt(0) lgkmcnt(0)
	v_mfma_f32_16x16x32_bf16 v[36:39], v[68:71], v[72:75], v[36:39]
	v_mfma_f32_16x16x32_bf16 v[24:27], v[76:79], v[72:75], v[24:27]
	v_mfma_f32_16x16x32_bf16 v[20:23], v[68:71], v[180:183], v[20:23]
	v_mfma_f32_16x16x32_bf16 v[16:19], v[76:79], v[180:183], v[16:19]
	v_mfma_f32_16x16x32_bf16 v[12:15], v[68:71], v[184:187], v[12:15]
	v_mfma_f32_16x16x32_bf16 v[8:11], v[76:79], v[184:187], v[8:11]
	v_mfma_f32_16x16x32_bf16 v[4:7], v[68:71], v[188:191], v[4:7]
	v_mfma_f32_16x16x32_bf16 v[0:3], v[76:79], v[188:191], v[0:3]
	v_mfma_f32_16x16x32_bf16 v[28:31], v[68:71], v[206:209], v[28:31]
	v_mfma_f32_16x16x32_bf16 v[32:35], v[76:79], v[206:209], v[32:35]
	v_mfma_f32_16x16x32_bf16 v[40:43], v[68:71], v[210:213], v[40:43]
	v_mfma_f32_16x16x32_bf16 v[44:47], v[76:79], v[210:213], v[44:47]
	v_mfma_f32_16x16x32_bf16 v[48:51], v[68:71], v[214:217], v[48:51]
	v_mfma_f32_16x16x32_bf16 v[52:55], v[76:79], v[214:217], v[52:55]
	v_mfma_f32_16x16x32_bf16 v[56:59], v[68:71], v[218:221], v[56:59]
	v_mfma_f32_16x16x32_bf16 v[60:63], v[76:79], v[218:221], v[60:63]
	s_cbranch_vccnz .LBB0_710
	ds_write_b128 v149, v[36:39]
	ds_write_b128 v149, v[24:27] offset:1024
	ds_write_b128 v149, v[20:23] offset:2048
	ds_write_b128 v149, v[16:19] offset:3072
	ds_write_b128 v149, v[12:15] offset:4096
	ds_write_b128 v149, v[8:11] offset:5120
	ds_write_b128 v149, v[4:7] offset:6144
	ds_write_b128 v149, v[0:3] offset:7168
	ds_write_b128 v149, v[28:31] offset:8192
	ds_write_b128 v149, v[32:35] offset:9216
	ds_write_b128 v149, v[40:43] offset:10240
	ds_write_b128 v149, v[44:47] offset:11264
	ds_write_b128 v149, v[48:51] offset:12288
	ds_write_b128 v149, v[52:55] offset:13312
	ds_write_b128 v149, v[56:59] offset:14336
	ds_write_b128 v149, v[60:63] offset:15360
	s_waitcnt lgkmcnt(0)
	s_waitcnt lgkmcnt(0)
	s_barrier
	ds_read_b128 v[126:129], v150
	ds_read_b128 v[122:125], v150 offset:1024
	ds_read_b128 v[118:121], v150 offset:16384
	ds_read_b128 v[114:117], v150 offset:17408
	ds_read_b128 v[110:113], v150 offset:32768
	ds_read_b128 v[106:109], v150 offset:33792
	ds_read_b128 v[102:105], v150 offset:49152
	ds_read_b128 v[98:101], v150 offset:50176
	ds_read_b128 v[92:95], v151
	ds_read_b128 v[88:91], v152
	ds_read_b128 v[84:87], v153
	ds_read_b128 v[80:83], v154
	ds_read_b128 v[76:79], v155
	ds_read_b128 v[72:75], v156
	ds_read_b128 v[68:71], v157
	ds_read_b128 v[64:67], v158
	s_waitcnt lgkmcnt(0)
	v_lshl_add_u64 v[144:145], v[136:137], 0, v[144:145]
	s_mov_b64 s[0:1], 0x4000
	v_mov_b32_e32 v0, 0
	v_lshl_add_u64 v[146:147], v[144:145], 0, s[0:1]
	s_mov_b64 s[2:3], 0
	s_mov_b64 s[0:1], -1
	v_mov_b32_e32 v1, v0
	v_mov_b32_e32 v2, v0
	v_mov_b32_e32 v3, v0
	v_mov_b32_e32 v4, v0
	v_mov_b32_e32 v5, v0
	v_mov_b32_e32 v6, v0
	v_mov_b32_e32 v7, v0
	v_mov_b32_e32 v8, v0
	v_mov_b32_e32 v9, v0
	v_mov_b32_e32 v10, v0
	v_mov_b32_e32 v11, v0
	v_mov_b32_e32 v12, v0
	v_mov_b32_e32 v13, v0
	v_mov_b32_e32 v14, v0
	v_mov_b32_e32 v15, v0
	v_mov_b32_e32 v16, v0
	v_mov_b32_e32 v17, v0
	v_mov_b32_e32 v18, v0
	v_mov_b32_e32 v19, v0
	v_mov_b32_e32 v20, v0
	v_mov_b32_e32 v21, v0
	v_mov_b32_e32 v22, v0
	v_mov_b32_e32 v23, v0
	v_mov_b32_e32 v24, v0
	v_mov_b32_e32 v25, v0
	v_mov_b32_e32 v26, v0
	v_mov_b32_e32 v27, v0
	v_mov_b32_e32 v36, v0
	v_mov_b32_e32 v37, v0
	v_mov_b32_e32 v38, v0
	v_mov_b32_e32 v39, v0
	v_mov_b32_e32 v28, v0
	v_mov_b32_e32 v29, v0
	v_mov_b32_e32 v30, v0
	v_mov_b32_e32 v31, v0
	v_mov_b32_e32 v32, v0
	v_mov_b32_e32 v33, v0
	v_mov_b32_e32 v34, v0
	v_mov_b32_e32 v35, v0
	v_mov_b32_e32 v40, v0
	v_mov_b32_e32 v41, v0
	v_mov_b32_e32 v42, v0
	v_mov_b32_e32 v43, v0
	v_mov_b32_e32 v44, v0
	v_mov_b32_e32 v45, v0
	v_mov_b32_e32 v46, v0
	v_mov_b32_e32 v47, v0
	v_mov_b32_e32 v48, v0
	v_mov_b32_e32 v49, v0
	v_mov_b32_e32 v50, v0
	v_mov_b32_e32 v51, v0
	v_mov_b32_e32 v52, v0
	v_mov_b32_e32 v53, v0
	v_mov_b32_e32 v54, v0
	v_mov_b32_e32 v55, v0
	v_mov_b32_e32 v56, v0
	v_mov_b32_e32 v57, v0
	v_mov_b32_e32 v58, v0
	v_mov_b32_e32 v59, v0
	v_mov_b32_e32 v60, v0
	v_mov_b32_e32 v61, v0
	v_mov_b32_e32 v62, v0
	v_mov_b32_e32 v63, v0
	s_waitcnt lgkmcnt(0)
	s_barrier
; #define LAS __attribute__((address_space(3)))
; template <int KSTEPS  >
; __device__ __forceinline__ void small_mma_ksplit(f32x4 (&acc)[2], const bf16_t* A, int lda, const bf16_t* Bt, int ldb, int n0, LAS unsigned char* lds, const SmallId& id) {
;     ...
;     for (int ks = 0; ks < KSTEPS; ++ks) {
;         bf16x8 a[8], b[2];
; #pragma unroll
;         for (int rb = 0; rb < 8; ++rb) a[rb] = *(const bf16x8*)(ap + (size_t)(16 * rb) * lda + 32 * ks);
;         b[0] = *(const bf16x8*)(bp + 32 * ks); b[1] = *(const bf16x8*)(bp + (size_t)16 * ldb + 32 * ks);
; #pragma unroll
;         for (int rb = 0; rb < 8; ++rb) { part[rb][0] = __builtin_amdgcn_mfma_f32_16x16x32_bf16(b[0], a[rb], part[rb][0], 0, 0, 0); part[rb][1] = __builtin_amdgcn_mfma_f32_16x16x32_bf16(b[1], a[rb], part[rb][1], 0, 0, 0); }
;     }
;     LAS f32x4* red = (LAS f32x4*)lds;
; #pragma unroll
;     for (int rb = 0; rb < 8; ++rb) { red[((id.w * 8 + rb) * 2 + 0) * 64 + lane] = part[rb][0]; red[((id.w * 8 + rb) * 2 + 1) * 64 + lane] = part[rb][1]; }
;     asm volatile("s_waitcnt lgkmcnt(0)" ::: "memory"); __syncthreads();
.LBB0_712:
	s_lshl_b64 s[2:3], s[2:3], 1
	v_lshl_add_u64 v[160:161], v[144:145], 0, s[2:3]
	v_lshl_add_u64 v[168:169], v[146:147], 0, s[2:3]
	v_lshl_add_u64 v[172:173], v[134:135], 0, s[2:3]
	global_load_dwordx4 v[160:163], v[160:161], off
	global_load_dwordx4 v[164:167], v[172:173], off
	global_load_dwordx4 v[168:171], v[168:169], off
	v_add_co_u32_e32 v174, vcc, s9, v172
	s_mov_b64 s[2:3], 32
	s_nop 1
	v_addc_co_u32_e32 v175, vcc, 0, v173, vcc
	global_load_dwordx4 v[180:183], v[174:175], off
	v_add_co_u32_e32 v174, vcc, s10, v172
	s_nop 1
	v_addc_co_u32_e32 v175, vcc, 0, v173, vcc
	global_load_dwordx4 v[184:187], v[174:175], off
	v_add_co_u32_e32 v174, vcc, s11, v172
	s_nop 1
	v_addc_co_u32_e32 v175, vcc, 0, v173, vcc
	global_load_dwordx4 v[188:191], v[174:175], off
	v_add_co_u32_e32 v174, vcc, s12, v172
	s_nop 1
	v_addc_co_u32_e32 v175, vcc, 0, v173, vcc
	global_load_dwordx4 v[206:209], v[174:175], off
	v_add_co_u32_e32 v174, vcc, s13, v172
	s_nop 1
	v_addc_co_u32_e32 v175, vcc, 0, v173, vcc
	global_load_dwordx4 v[210:213], v[174:175], off
	v_add_co_u32_e32 v174, vcc, s14, v172
	s_nop 1
	v_addc_co_u32_e32 v175, vcc, 0, v173, vcc
	v_add_co_u32_e32 v172, vcc, s15, v172
	global_load_dwordx4 v[214:217], v[174:175], off
	s_nop 1
	v_addc_co_u32_e32 v173, vcc, 0, v173, vcc
	s_and_b64 vcc, exec, s[0:1]
	s_mov_b64 s[0:1], 0
	global_load_dwordx4 v[218:221], v[172:173], off
	s_waitcnt vmcnt(0) lgkmcnt(0)
	v_mfma_f32_16x16x32_bf16 v[36:39], v[160:163], v[164:167], v[36:39]
	v_mfma_f32_16x16x32_bf16 v[24:27], v[168:171], v[164:167], v[24:27]
	v_mfma_f32_16x16x32_bf16 v[20:23], v[160:163], v[180:183], v[20:23]
	v_mfma_f32_16x16x32_bf16 v[16:19], v[168:171], v[180:183], v[16:19]
	v_mfma_f32_16x16x32_bf16 v[12:15], v[160:163], v[184:187], v[12:15]
	v_mfma_f32_16x16x32_bf16 v[8:11], v[168:171], v[184:187], v[8:11]
	v_mfma_f32_16x16x32_bf16 v[4:7], v[160:163], v[188:191], v[4:7]
	v_mfma_f32_16x16x32_bf16 v[0:3], v[168:171], v[188:191], v[0:3]
	v_mfma_f32_16x16x32_bf16 v[28:31], v[160:163], v[206:209], v[28:31]
	v_mfma_f32_16x16x32_bf16 v[32:35], v[168:171], v[206:209], v[32:35]
	v_mfma_f32_16x16x32_bf16 v[40:43], v[160:163], v[210:213], v[40:43]
	v_mfma_f32_16x16x32_bf16 v[44:47], v[168:171], v[210:213], v[44:47]
	v_mfma_f32_16x16x32_bf16 v[48:51], v[160:163], v[214:217], v[48:51]
	v_mfma_f32_16x16x32_bf16 v[52:55], v[168:171], v[214:217], v[52:55]
	v_mfma_f32_16x16x32_bf16 v[56:59], v[160:163], v[218:221], v[56:59]
	v_mfma_f32_16x16x32_bf16 v[60:63], v[168:171], v[218:221], v[60:63]
	s_cbranch_vccnz .LBB0_712
	ds_write_b128 v149, v[36:39]
	ds_write_b128 v149, v[24:27] offset:1024
	ds_write_b128 v149, v[20:23] offset:2048
	ds_write_b128 v149, v[16:19] offset:3072
	ds_write_b128 v149, v[12:15] offset:4096
	ds_write_b128 v149, v[8:11] offset:5120
	ds_write_b128 v149, v[4:7] offset:6144
	ds_write_b128 v149, v[0:3] offset:7168
	ds_write_b128 v149, v[28:31] offset:8192
	ds_write_b128 v149, v[32:35] offset:9216
	ds_write_b128 v149, v[40:43] offset:10240
	ds_write_b128 v149, v[44:47] offset:11264
	ds_write_b128 v149, v[48:51] offset:12288
	ds_write_b128 v149, v[52:55] offset:13312
	ds_write_b128 v149, v[56:59] offset:14336
	ds_write_b128 v149, v[60:63] offset:15360
	s_waitcnt lgkmcnt(0)
	s_waitcnt lgkmcnt(0)
	s_barrier
; __device__ __forceinline__ unsigned cvt_pk_bf16(float lo, float hi) { unsigned r; asm volatile("v_cvt_pk_bf16_f32 %0, %1, %2" : "=v"(r) : "v"(lo), "v"(hi)); return r; }
; template <int KSTEPS  >
; __device__ __forceinline__ void small_mma_ksplit(f32x4 (&acc)[2], const bf16_t* A, int lda, const bf16_t* Bt, int ldb, int n0, LAS unsigned char* lds, const SmallId& id) {
;     ...
;     for (int w2 = 0; w2 < 8; ++w2) { acc[0] += red[((w2 * 8 + id.w) * 2 + 0) * 64 + lane]; acc[1] += red[((w2 * 8 + id.w) * 2 + 1) * 64 + lane]; }
;     asm volatile("s_waitcnt lgkmcnt(0)" ::: "memory"); __syncthreads();
; __device__ __forceinline__ void small_mix(const Params& p, int l, LAS unsigned char* lds, int G, int bx) {
;     ...
;         for (int nb = 0; nb < 2; ++nb) { const int col = n0 + 16 * nb + 4 * id.fq;
;             const u32x2 g0 = *(const u32x2*)(PROJ + (size_t)id.row * INW + 1280 + col), g1 = *(const u32x2*)(PROJ + (size_t)id.row * INW + 2304 + col);
;             const float v0 = bf_lo(g0.x) * ya[nb][0] + bf_lo(g1.x) * yb[nb][0], v1 = bf_hi(g0.x) * ya[nb][1] + bf_hi(g1.x) * yb[nb][1];
;             const float v2 = bf_lo(g0.y) * ya[nb][2] + bf_lo(g1.y) * yb[nb][2], v3 = bf_hi(g0.y) * ya[nb][3] + bf_hi(g1.y) * yb[nb][3];
;             u32x2 w; w.x = cvt_pk_bf16(v0, v1); w.y = cvt_pk_bf16(v2, v3); *(u32x2*)(MIX + (size_t)id.row * DM + col) = w; }
	ds_read_b128 v[0:3], v150
	v_pk_add_f32 v[126:127], v[126:127], 0 op_sel_hi:[1,0]
	v_pk_add_f32 v[128:129], v[128:129], 0 op_sel_hi:[1,0]
	v_pk_add_f32 v[118:119], v[126:127], v[118:119]
	v_pk_add_f32 v[120:121], v[128:129], v[120:121]
	s_waitcnt lgkmcnt(0)
	v_pk_add_f32 v[4:5], v[2:3], 0 op_sel_hi:[1,0]
	v_pk_add_f32 v[6:7], v[0:1], 0 op_sel_hi:[1,0]
	ds_read_b128 v[0:3], v150 offset:1024
	v_pk_add_f32 v[110:111], v[118:119], v[110:111]
	v_pk_add_f32 v[112:113], v[120:121], v[112:113]
	v_pk_add_f32 v[102:103], v[110:111], v[102:103]
	v_pk_add_f32 v[104:105], v[112:113], v[104:105]
	s_waitcnt lgkmcnt(0)
	v_pk_add_f32 v[8:9], v[2:3], 0 op_sel_hi:[1,0]
	v_pk_add_f32 v[10:11], v[0:1], 0 op_sel_hi:[1,0]
	ds_read_b128 v[0:3], v150 offset:16384
	v_pk_add_f32 v[92:93], v[102:103], v[92:93]
	v_pk_add_f32 v[94:95], v[104:105], v[94:95]
	v_pk_add_f32 v[84:85], v[92:93], v[84:85]
	v_pk_add_f32 v[86:87], v[94:95], v[86:87]
	s_waitcnt lgkmcnt(0)
	v_pk_add_f32 v[4:5], v[4:5], v[2:3]
	v_pk_add_f32 v[6:7], v[6:7], v[0:1]
	ds_read_b128 v[0:3], v150 offset:17408
	v_pk_add_f32 v[76:77], v[84:85], v[76:77]
	v_pk_add_f32 v[78:79], v[86:87], v[78:79]
	v_pk_add_f32 v[68:69], v[76:77], v[68:69]
	v_pk_add_f32 v[70:71], v[78:79], v[70:71]
	s_waitcnt lgkmcnt(0)
	v_pk_add_f32 v[8:9], v[8:9], v[2:3]
	v_pk_add_f32 v[10:11], v[10:11], v[0:1]
	ds_read_b128 v[0:3], v150 offset:32768
	v_mov_b32_e32 v20, v68
	v_pk_add_f32 v[122:123], v[122:123], 0 op_sel_hi:[1,0]
	v_pk_add_f32 v[124:125], v[124:125], 0 op_sel_hi:[1,0]
	v_pk_add_f32 v[114:115], v[122:123], v[114:115]
	s_waitcnt lgkmcnt(0)
	v_pk_add_f32 v[4:5], v[4:5], v[2:3]
	v_pk_add_f32 v[6:7], v[6:7], v[0:1]
	ds_read_b128 v[0:3], v150 offset:33792
	v_pk_add_f32 v[106:107], v[114:115], v[106:107]
	v_pk_add_f32 v[116:117], v[124:125], v[116:117]
	v_pk_add_f32 v[98:99], v[106:107], v[98:99]
	v_pk_add_f32 v[108:109], v[116:117], v[108:109]
	s_waitcnt lgkmcnt(0)
	v_pk_add_f32 v[8:9], v[8:9], v[2:3]
	v_pk_add_f32 v[10:11], v[10:11], v[0:1]
	ds_read_b128 v[0:3], v150 offset:49152
	v_pk_add_f32 v[88:89], v[98:99], v[88:89]
	v_pk_add_f32 v[100:101], v[108:109], v[100:101]
	v_pk_add_f32 v[80:81], v[88:89], v[80:81]
	v_pk_add_f32 v[90:91], v[100:101], v[90:91]
	s_waitcnt lgkmcnt(0)
	v_pk_add_f32 v[4:5], v[4:5], v[2:3]
	v_pk_add_f32 v[6:7], v[6:7], v[0:1]
	ds_read_b128 v[0:3], v150 offset:50176
	v_pk_add_f32 v[72:73], v[80:81], v[72:73]
	v_pk_add_f32 v[82:83], v[90:91], v[82:83]
	v_pk_add_f32 v[64:65], v[72:73], v[64:65]
	v_pk_add_f32 v[74:75], v[82:83], v[74:75]
	s_waitcnt lgkmcnt(0)
	v_pk_add_f32 v[8:9], v[8:9], v[2:3]
	v_pk_add_f32 v[10:11], v[10:11], v[0:1]
	ds_read_b128 v[0:3], v151
	v_pk_add_f32 v[66:67], v[74:75], v[66:67]
	s_add_i32 s7, s7, s92
	s_cmp_lt_i32 s7, 32
	s_waitcnt lgkmcnt(0)
	v_pk_add_f32 v[4:5], v[4:5], v[2:3]
	v_pk_add_f32 v[6:7], v[6:7], v[0:1]
	ds_read_b128 v[0:3], v152
	s_waitcnt lgkmcnt(0)
	v_pk_add_f32 v[8:9], v[8:9], v[2:3]
	v_pk_add_f32 v[10:11], v[10:11], v[0:1]
	ds_read_b128 v[0:3], v153
	s_waitcnt lgkmcnt(0)
	v_pk_add_f32 v[4:5], v[4:5], v[2:3]
	v_pk_add_f32 v[6:7], v[6:7], v[0:1]
	ds_read_b128 v[0:3], v154
	s_waitcnt lgkmcnt(0)
	v_pk_add_f32 v[8:9], v[8:9], v[2:3]
	v_pk_add_f32 v[10:11], v[10:11], v[0:1]
	ds_read_b128 v[0:3], v155
	s_waitcnt lgkmcnt(0)
	v_pk_add_f32 v[4:5], v[4:5], v[2:3]
	v_pk_add_f32 v[6:7], v[6:7], v[0:1]
	ds_read_b128 v[0:3], v156
	s_waitcnt lgkmcnt(0)
	v_pk_add_f32 v[8:9], v[8:9], v[2:3]
	v_pk_add_f32 v[10:11], v[10:11], v[0:1]
	ds_read_b128 v[0:3], v157
	s_waitcnt lgkmcnt(0)
	v_pk_add_f32 v[12:13], v[4:5], v[2:3]
	ds_read_b128 v[2:5], v158
	v_pk_add_f32 v[6:7], v[6:7], v[0:1]
	s_waitcnt lgkmcnt(0)
	s_waitcnt lgkmcnt(0)
	s_barrier
	v_pk_add_f32 v[0:1], v[8:9], v[4:5]
	v_or_b32_e32 v4, s8, v96
	v_ashrrev_i32_e32 v5, 31, v4
	v_lshlrev_b64 v[8:9], 1, v[4:5]
	v_pk_add_f32 v[2:3], v[10:11], v[2:3]
	v_lshl_add_u64 v[10:11], v[138:139], 0, v[8:9]
	v_lshl_add_u64 v[16:17], v[140:141], 0, v[8:9]
	global_load_dwordx2 v[14:15], v[10:11], off offset:2560
	v_mov_b32_e32 v21, v6
	global_load_dwordx2 v[16:17], v[16:17], off
	v_mov_b32_e32 v6, v69
	v_or_b32_e32 v4, 16, v4
	v_lshl_add_u64 v[8:9], v[142:143], 0, v[8:9]
	s_waitcnt vmcnt(0) lgkmcnt(0)
	v_lshlrev_b32_e32 v18, 16, v14
	v_lshlrev_b32_e32 v19, 16, v16
	v_pk_mul_f32 v[18:19], v[20:21], v[18:19]
	s_nop 0
	v_add_f32_e32 v5, v18, v19
	v_and_b32_e32 v19, 0xffff0000, v16
	v_and_b32_e32 v18, 0xffff0000, v14
	v_pk_mul_f32 v[6:7], v[6:7], v[18:19]
	v_mov_b32_e32 v18, v70
	v_add_f32_e32 v14, v6, v7
	v_lshlrev_b32_e32 v7, 16, v17
	v_lshlrev_b32_e32 v6, 16, v15
	v_mov_b32_e32 v19, v12
	v_pk_mul_f32 v[6:7], v[18:19], v[6:7]
	v_mov_b32_e32 v12, v71
	v_add_f32_e32 v16, v6, v7
	v_and_b32_e32 v7, 0xffff0000, v17
	v_and_b32_e32 v6, 0xffff0000, v15
	v_pk_mul_f32 v[6:7], v[12:13], v[6:7]
	v_mov_b32_e32 v12, v64
	v_add_f32_e32 v7, v6, v7
	v_cvt_pk_bf16_f32 v6, v5, v14
	v_ashrrev_i32_e32 v5, 31, v4
	v_cvt_pk_bf16_f32 v7, v16, v7
	v_lshl_add_u64 v[4:5], v[4:5], 1, v[140:141]
	global_store_dwordx2 v[8:9], v[6:7], off
	global_load_dwordx2 v[6:7], v[10:11], off offset:2592
	v_mov_b32_e32 v13, v2
	global_load_dwordx2 v[4:5], v[4:5], off
	v_mov_b32_e32 v2, v65
	s_waitcnt vmcnt(0) lgkmcnt(0)
	v_lshlrev_b32_e32 v10, 16, v6
	v_lshlrev_b32_e32 v11, 16, v4
	v_pk_mul_f32 v[10:11], v[12:13], v[10:11]
	s_nop 0
	v_add_f32_e32 v12, v10, v11
	v_and_b32_e32 v11, 0xffff0000, v4
	v_and_b32_e32 v10, 0xffff0000, v6
	v_pk_mul_f32 v[2:3], v[2:3], v[10:11]
	v_mov_b32_e32 v10, v66
	v_add_f32_e32 v4, v2, v3
	v_lshlrev_b32_e32 v3, 16, v5
	v_lshlrev_b32_e32 v2, 16, v7
	v_mov_b32_e32 v11, v0
	v_pk_mul_f32 v[2:3], v[10:11], v[2:3]
	v_mov_b32_e32 v0, v67
	v_add_f32_e32 v6, v2, v3
	v_and_b32_e32 v3, 0xffff0000, v5
	v_and_b32_e32 v2, 0xffff0000, v7
	v_pk_mul_f32 v[0:1], v[0:1], v[2:3]
	s_nop 0
	v_add_f32_e32 v1, v0, v1
	v_cvt_pk_bf16_f32 v0, v12, v4
	v_cvt_pk_bf16_f32 v1, v6, v1
	global_store_dwordx2 v[8:9], v[0:1], off offset:32
	s_cbranch_scc1 .LBB0_709

; __device__ __forceinline__ void unpack8(const u32x4 w, float* f) { f[0] = bf_lo(w.x); f[1] = bf_hi(w.x); f[2] = bf_lo(w.y); f[3] = bf_hi(w.y); f[4] = bf_lo(w.z); f[5] = bf_hi(w.z); f[6] = bf_lo(w.w); f[7] = bf_hi(w.w); }
;     __device__ __forceinline__ void operator()(AccT& acc, const Unit& u, int wr, int wc, int fr, int fq) const {
;     ...
;         if (u.z == 0) {
; #pragma unroll
;             for (int ai = 0; ai < 2; ++ai)
; #pragma unroll
;                 for (int m = 0; m < 4; ++m)
; #pragma unroll
;                     for (int bj = 0; bj < 2; ++bj) gw[ai][m][bj] = __builtin_nontemporal_load((const u32x4*)(Pb + (unsigned)(((u.pm * 256 + ai * 128 + wr * 64 + m * 16 + fr) * INW + col0 + bj * 128 + 1280) * 2)));
; #pragma unroll
;             for (int ai = 0; ai < 2; ++ai)
; #pragma unroll
;                 for (int m = 0; m < 4; ++m)
; #pragma unroll
;                     for (int bj = 0; bj < 2; ++bj) { float g0[8]; unpack8(gw[ai][m][bj], g0);
; #pragma unroll
;                         for (int n = 0; n < 2; ++n)
; #pragma unroll
;                             for (int j = 0; j < 4; ++j) acc[ai][bj][m][n][j] *= g0[n * 4 + j]; }
.LBB0_732:
	v_add_u32_e32 v96, 0xa00, v234
	v_lshl_add_u64 v[132:133], s[84:85], 0, v[96:97]
	global_load_dwordx4 v[236:239], v[132:133], off nt
	v_add_u32_e32 v96, 0xb00, v234
	v_lshl_add_u64 v[132:133], s[84:85], 0, v[96:97]
	global_load_dwordx4 v[188:191], v[132:133], off nt
	v_add_u32_e32 v96, 0x1aa00, v234
	v_lshl_add_u64 v[132:133], s[84:85], 0, v[96:97]
	global_load_dwordx4 v[184:187], v[132:133], off nt
	v_add_u32_e32 v96, 0x1ab00, v234
	v_lshl_add_u64 v[132:133], s[84:85], 0, v[96:97]
	global_load_dwordx4 v[180:183], v[132:133], off nt
	v_add_u32_e32 v96, 0x34a00, v234
	v_lshl_add_u64 v[132:133], s[84:85], 0, v[96:97]
	global_load_dwordx4 v[176:179], v[132:133], off nt
	v_add_u32_e32 v96, 0x34b00, v234
	v_lshl_add_u64 v[132:133], s[84:85], 0, v[96:97]
	global_load_dwordx4 v[172:175], v[132:133], off nt
	v_add_u32_e32 v96, 0x4ea00, v234
	v_lshl_add_u64 v[132:133], s[84:85], 0, v[96:97]
	global_load_dwordx4 v[168:171], v[132:133], off nt
	v_add_u32_e32 v96, 0x4eb00, v234
	v_lshl_add_u64 v[132:133], s[84:85], 0, v[96:97]
	global_load_dwordx4 v[164:167], v[132:133], off nt
	v_add_u32_e32 v96, 0xd0a00, v234
	v_lshl_add_u64 v[132:133], s[84:85], 0, v[96:97]
	global_load_dwordx4 v[160:163], v[132:133], off nt
	v_add_u32_e32 v96, 0xd0b00, v234
	v_lshl_add_u64 v[132:133], s[84:85], 0, v[96:97]
	global_load_dwordx4 v[156:159], v[132:133], off nt
	v_add_u32_e32 v96, 0xeaa00, v234
	v_lshl_add_u64 v[132:133], s[84:85], 0, v[96:97]
	global_load_dwordx4 v[152:155], v[132:133], off nt
	v_add_u32_e32 v96, 0xeab00, v234
	v_lshl_add_u64 v[132:133], s[84:85], 0, v[96:97]
	global_load_dwordx4 v[148:151], v[132:133], off nt
	v_add_u32_e32 v96, 0x104a00, v234
	v_lshl_add_u64 v[132:133], s[84:85], 0, v[96:97]
	global_load_dwordx4 v[144:147], v[132:133], off nt
	v_add_u32_e32 v96, 0x104b00, v234
	v_lshl_add_u64 v[132:133], s[84:85], 0, v[96:97]
	global_load_dwordx4 v[140:143], v[132:133], off nt
	v_add_u32_e32 v96, 0x11ea00, v234
	v_lshl_add_u64 v[132:133], s[84:85], 0, v[96:97]
	global_load_dwordx4 v[136:139], v[132:133], off nt
	v_add_u32_e32 v96, 0x11eb00, v234
	v_lshl_add_u64 v[132:133], s[84:85], 0, v[96:97]
	global_load_dwordx4 v[132:135], v[132:133], off nt
	s_waitcnt vmcnt(0) lgkmcnt(0)
	v_lshlrev_b32_e32 v240, 16, v236
	v_and_b32_e32 v241, 0xffff0000, v236
	v_lshlrev_b32_e32 v236, 16, v237
	v_and_b32_e32 v237, 0xffff0000, v237
	v_pk_mul_f32 v[130:131], v[130:131], v[236:237]
	v_lshlrev_b32_e32 v236, 16, v238
	v_and_b32_e32 v237, 0xffff0000, v238
	v_pk_mul_f32 v[124:125], v[124:125], v[236:237]
	v_lshlrev_b32_e32 v236, 16, v239
	v_and_b32_e32 v237, 0xffff0000, v239
	v_pk_mul_f32 v[126:127], v[126:127], v[236:237]
	v_lshlrev_b32_e32 v236, 16, v188
	v_and_b32_e32 v237, 0xffff0000, v188
	v_lshlrev_b32_e32 v188, 16, v189
	v_and_b32_e32 v189, 0xffff0000, v189
	v_pk_mul_f32 v[94:95], v[94:95], v[188:189]
	v_lshlrev_b32_e32 v188, 16, v190
	v_and_b32_e32 v189, 0xffff0000, v190
	v_pk_mul_f32 v[88:89], v[88:89], v[188:189]
	v_lshlrev_b32_e32 v188, 16, v191
	v_and_b32_e32 v189, 0xffff0000, v191
	v_pk_mul_f32 v[90:91], v[90:91], v[188:189]
	v_lshlrev_b32_e32 v188, 16, v184
	v_and_b32_e32 v189, 0xffff0000, v184
	v_lshlrev_b32_e32 v184, 16, v185
	v_and_b32_e32 v185, 0xffff0000, v185
	v_pk_mul_f32 v[122:123], v[122:123], v[184:185]
	v_lshlrev_b32_e32 v184, 16, v186
	v_and_b32_e32 v185, 0xffff0000, v186
	v_pk_mul_f32 v[116:117], v[116:117], v[184:185]
	v_lshlrev_b32_e32 v184, 16, v187
	v_and_b32_e32 v185, 0xffff0000, v187
	v_pk_mul_f32 v[118:119], v[118:119], v[184:185]
	v_lshlrev_b32_e32 v184, 16, v180
	v_and_b32_e32 v185, 0xffff0000, v180
	v_lshlrev_b32_e32 v180, 16, v181
	v_and_b32_e32 v181, 0xffff0000, v181
	v_pk_mul_f32 v[86:87], v[86:87], v[180:181]
	v_lshlrev_b32_e32 v180, 16, v182
	v_and_b32_e32 v181, 0xffff0000, v182
	v_pk_mul_f32 v[80:81], v[80:81], v[180:181]
	v_lshlrev_b32_e32 v180, 16, v183
	v_and_b32_e32 v181, 0xffff0000, v183
	v_pk_mul_f32 v[82:83], v[82:83], v[180:181]
	v_lshlrev_b32_e32 v180, 16, v176
	v_and_b32_e32 v181, 0xffff0000, v176
	v_lshlrev_b32_e32 v176, 16, v177
	v_and_b32_e32 v177, 0xffff0000, v177
	v_pk_mul_f32 v[114:115], v[114:115], v[176:177]
	v_lshlrev_b32_e32 v176, 16, v178
	v_and_b32_e32 v177, 0xffff0000, v178
	v_pk_mul_f32 v[108:109], v[108:109], v[176:177]
	v_lshlrev_b32_e32 v176, 16, v179
	v_and_b32_e32 v177, 0xffff0000, v179
	v_pk_mul_f32 v[110:111], v[110:111], v[176:177]
	v_lshlrev_b32_e32 v176, 16, v172
	v_and_b32_e32 v177, 0xffff0000, v172
	v_lshlrev_b32_e32 v172, 16, v173
	v_and_b32_e32 v173, 0xffff0000, v173
	v_pk_mul_f32 v[78:79], v[78:79], v[172:173]
	v_lshlrev_b32_e32 v172, 16, v174
	v_and_b32_e32 v173, 0xffff0000, v174
	v_pk_mul_f32 v[72:73], v[72:73], v[172:173]
	v_lshlrev_b32_e32 v172, 16, v175
	v_and_b32_e32 v173, 0xffff0000, v175
	v_pk_mul_f32 v[74:75], v[74:75], v[172:173]
	v_lshlrev_b32_e32 v172, 16, v168
	v_and_b32_e32 v173, 0xffff0000, v168
	v_lshlrev_b32_e32 v168, 16, v169
; __device__ __forceinline__ void unpack8(const u32x4 w, float* f) { f[0] = bf_lo(w.x); f[1] = bf_hi(w.x); f[2] = bf_lo(w.y); f[3] = bf_hi(w.y); f[4] = bf_lo(w.z); f[5] = bf_hi(w.z); f[6] = bf_lo(w.w); f[7] = bf_hi(w.w); }
;     __device__ __forceinline__ void operator()(AccT& acc, const Unit& u, int wr, int wc, int fr, int fq) const {
;     ...
;                     for (int bj = 0; bj < 2; ++bj) { float g0[8]; unpack8(gw[ai][m][bj], g0);
; #pragma unroll
;                         for (int n = 0; n < 2; ++n)
; #pragma unroll
;                             for (int j = 0; j < 4; ++j) acc[ai][bj][m][n][j] *= g0[n * 4 + j]; }
	v_and_b32_e32 v169, 0xffff0000, v169
	v_pk_mul_f32 v[106:107], v[106:107], v[168:169]
	v_lshlrev_b32_e32 v168, 16, v170
	v_and_b32_e32 v169, 0xffff0000, v170
	v_pk_mul_f32 v[100:101], v[100:101], v[168:169]
	v_lshlrev_b32_e32 v168, 16, v171
	v_and_b32_e32 v169, 0xffff0000, v171
	v_pk_mul_f32 v[102:103], v[102:103], v[168:169]
	v_lshlrev_b32_e32 v168, 16, v164
	v_and_b32_e32 v169, 0xffff0000, v164
	v_lshlrev_b32_e32 v164, 16, v165
	v_and_b32_e32 v165, 0xffff0000, v165
	v_pk_mul_f32 v[70:71], v[70:71], v[164:165]
	v_lshlrev_b32_e32 v164, 16, v166
	v_and_b32_e32 v165, 0xffff0000, v166
	v_pk_mul_f32 v[64:65], v[64:65], v[164:165]
	v_lshlrev_b32_e32 v164, 16, v167
	v_and_b32_e32 v165, 0xffff0000, v167
	v_pk_mul_f32 v[66:67], v[66:67], v[164:165]
	v_lshlrev_b32_e32 v164, 16, v160
	v_and_b32_e32 v165, 0xffff0000, v160
	v_lshlrev_b32_e32 v160, 16, v161
	v_and_b32_e32 v161, 0xffff0000, v161
	v_pk_mul_f32 v[62:63], v[62:63], v[160:161]
	v_lshlrev_b32_e32 v160, 16, v162
	v_and_b32_e32 v161, 0xffff0000, v162
	v_pk_mul_f32 v[56:57], v[56:57], v[160:161]
	v_lshlrev_b32_e32 v160, 16, v163
	v_and_b32_e32 v161, 0xffff0000, v163
	v_pk_mul_f32 v[58:59], v[58:59], v[160:161]
	v_lshlrev_b32_e32 v160, 16, v156
	v_and_b32_e32 v161, 0xffff0000, v156
	v_lshlrev_b32_e32 v156, 16, v157
	v_and_b32_e32 v157, 0xffff0000, v157
	v_pk_mul_f32 v[30:31], v[30:31], v[156:157]
	v_lshlrev_b32_e32 v156, 16, v158
	v_and_b32_e32 v157, 0xffff0000, v158
	v_pk_mul_f32 v[24:25], v[24:25], v[156:157]
	v_lshlrev_b32_e32 v156, 16, v159
	v_and_b32_e32 v157, 0xffff0000, v159
	v_pk_mul_f32 v[26:27], v[26:27], v[156:157]
	v_lshlrev_b32_e32 v156, 16, v152
	v_and_b32_e32 v157, 0xffff0000, v152
	v_lshlrev_b32_e32 v152, 16, v153
	v_and_b32_e32 v153, 0xffff0000, v153
	v_pk_mul_f32 v[54:55], v[54:55], v[152:153]
	v_lshlrev_b32_e32 v152, 16, v154
	v_and_b32_e32 v153, 0xffff0000, v154
	v_pk_mul_f32 v[48:49], v[48:49], v[152:153]
	v_lshlrev_b32_e32 v152, 16, v155
	v_and_b32_e32 v153, 0xffff0000, v155
	v_pk_mul_f32 v[50:51], v[50:51], v[152:153]
	v_lshlrev_b32_e32 v152, 16, v148
	v_and_b32_e32 v153, 0xffff0000, v148
	v_lshlrev_b32_e32 v148, 16, v149
	v_and_b32_e32 v149, 0xffff0000, v149
	v_pk_mul_f32 v[22:23], v[22:23], v[148:149]
	v_lshlrev_b32_e32 v148, 16, v150
	v_and_b32_e32 v149, 0xffff0000, v150
	v_pk_mul_f32 v[16:17], v[16:17], v[148:149]
	v_lshlrev_b32_e32 v148, 16, v151
	v_and_b32_e32 v149, 0xffff0000, v151
	v_pk_mul_f32 v[18:19], v[18:19], v[148:149]
	v_lshlrev_b32_e32 v148, 16, v144
	v_and_b32_e32 v149, 0xffff0000, v144
	v_lshlrev_b32_e32 v144, 16, v145
	v_and_b32_e32 v145, 0xffff0000, v145
	v_pk_mul_f32 v[46:47], v[46:47], v[144:145]
	v_lshlrev_b32_e32 v144, 16, v146
	v_and_b32_e32 v145, 0xffff0000, v146
	v_pk_mul_f32 v[40:41], v[40:41], v[144:145]
	v_lshlrev_b32_e32 v144, 16, v147
	v_and_b32_e32 v145, 0xffff0000, v147
	v_pk_mul_f32 v[42:43], v[42:43], v[144:145]
	v_lshlrev_b32_e32 v144, 16, v140
	v_and_b32_e32 v145, 0xffff0000, v140
	v_lshlrev_b32_e32 v140, 16, v141
	v_and_b32_e32 v141, 0xffff0000, v141
	v_pk_mul_f32 v[14:15], v[14:15], v[140:141]
	v_lshlrev_b32_e32 v140, 16, v142
	v_and_b32_e32 v141, 0xffff0000, v142
	v_pk_mul_f32 v[8:9], v[8:9], v[140:141]
	v_lshlrev_b32_e32 v140, 16, v143
	v_and_b32_e32 v141, 0xffff0000, v143
	v_pk_mul_f32 v[10:11], v[10:11], v[140:141]
	v_lshlrev_b32_e32 v140, 16, v136
	v_and_b32_e32 v141, 0xffff0000, v136
	v_lshlrev_b32_e32 v136, 16, v137
	v_and_b32_e32 v137, 0xffff0000, v137
	v_pk_mul_f32 v[38:39], v[38:39], v[136:137]
	v_lshlrev_b32_e32 v136, 16, v138
	v_and_b32_e32 v137, 0xffff0000, v138
	v_pk_mul_f32 v[32:33], v[32:33], v[136:137]
	v_lshlrev_b32_e32 v136, 16, v139
	v_and_b32_e32 v137, 0xffff0000, v139
	v_pk_mul_f32 v[34:35], v[34:35], v[136:137]
	v_lshlrev_b32_e32 v136, 16, v132
	v_and_b32_e32 v137, 0xffff0000, v132
	v_lshlrev_b32_e32 v132, 16, v133
	v_and_b32_e32 v133, 0xffff0000, v133
	v_pk_mul_f32 v[6:7], v[6:7], v[132:133]
	v_lshlrev_b32_e32 v132, 16, v134
	v_and_b32_e32 v133, 0xffff0000, v134
	v_pk_mul_f32 v[0:1], v[0:1], v[132:133]
	v_lshlrev_b32_e32 v132, 16, v135
	v_and_b32_e32 v133, 0xffff0000, v135
	v_pk_mul_f32 v[128:129], v[128:129], v[240:241]
	v_pk_mul_f32 v[92:93], v[92:93], v[236:237]
	v_pk_mul_f32 v[120:121], v[120:121], v[188:189]
	v_pk_mul_f32 v[84:85], v[84:85], v[184:185]
	v_pk_mul_f32 v[112:113], v[112:113], v[180:181]
	v_pk_mul_f32 v[76:77], v[76:77], v[176:177]
	v_pk_mul_f32 v[104:105], v[104:105], v[172:173]
	v_pk_mul_f32 v[68:69], v[68:69], v[168:169]
	v_pk_mul_f32 v[60:61], v[60:61], v[164:165]
	v_pk_mul_f32 v[28:29], v[28:29], v[160:161]
	v_pk_mul_f32 v[52:53], v[52:53], v[156:157]
	v_pk_mul_f32 v[20:21], v[20:21], v[152:153]
	v_pk_mul_f32 v[44:45], v[44:45], v[148:149]
	v_pk_mul_f32 v[12:13], v[12:13], v[144:145]
	v_pk_mul_f32 v[36:37], v[36:37], v[140:141]
	v_pk_mul_f32 v[4:5], v[4:5], v[136:137]
	v_pk_mul_f32 v[2:3], v[2:3], v[132:133]
	s_branch .LBB0_735

; __device__ __forceinline__ void unpack8(const u32x4 w, float* f) { f[0] = bf_lo(w.x); f[1] = bf_hi(w.x); f[2] = bf_lo(w.y); f[3] = bf_hi(w.y); f[4] = bf_lo(w.z); f[5] = bf_hi(w.z); f[6] = bf_lo(w.w); f[7] = bf_hi(w.w); }
; __device__ __forceinline__ u32x4 pack8(const float* f) { u32x4 w; w.x = cvt_pk_bf16(f[0], f[1]); w.y = cvt_pk_bf16(f[2], f[3]); w.z = cvt_pk_bf16(f[4], f[5]); w.w = cvt_pk_bf16(f[6], f[7]); return w; }
;     __device__ __forceinline__ void operator()(AccT& acc, const Unit& u, int wr, int wc, int fr, int fq) const {
;     ...
; #pragma unroll
;         for (int ai = 0; ai < 2; ++ai)
; #pragma unroll
;             for (int m = 0; m < 4; ++m)
; #pragma unroll
;                 for (int bj = 0; bj < 2; ++bj) gw[ai][m][bj] = __builtin_nontemporal_load((const u32x4*)(Pb + (unsigned)(((u.pm * 256 + ai * 128 + wr * 64 + m * 16 + fr) * INW + col0 + bj * 128 + 2304) * 2)));
; #pragma unroll
;         for (int ai = 0; ai < 2; ++ai)
; #pragma unroll
;             for (int m = 0; m < 4; ++m)
; #pragma unroll
;                 for (int bj = 0; bj < 2; ++bj) {
;                     const int row = u.pm * 256 + ai * 128 + wr * 64 + m * 16 + fr, col = col0 + bj * 128;
;                     float g1[8]; unpack8(gw[ai][m][bj], g1);
;                     if (u.z == 0) {
; #pragma unroll
;                         for (int n = 0; n < 2; ++n)
; #pragma unroll
;                             for (int j = 0; j < 4; ++j) acc[ai][bj][m][n][j] *= __builtin_amdgcn_rcpf(__builtin_fmaxf(g1[n * 4 + j], 1.0e-30f));
;                     } else {
;                         float v[8];
; #pragma unroll
;                         for (int n = 0; n < 2; ++n)
; #pragma unroll
;                             for (int j = 0; j < 4; ++j) v[n * 4 + j] = acc[ai][bj][m][n][j] * g1[n * 4 + j];
;                         *(u32x4*)((char*)MIX + (unsigned)((row * DM + col) * 2)) = pack8(v);
;                     }
.LBB0_735:
	v_add_u32_e32 v96, 0x1200, v234
	v_lshl_add_u64 v[132:133], s[84:85], 0, v[96:97]
	v_add_u32_e32 v96, 0x1300, v234
	v_lshl_add_u64 v[134:135], s[84:85], 0, v[96:97]
	v_add_u32_e32 v96, 0x1200, v233
	global_load_dwordx4 v[236:239], v[132:133], off nt
	global_load_dwordx4 v[188:191], v[134:135], off nt
	v_lshl_add_u64 v[132:133], s[84:85], 0, v[96:97]
	v_add_u32_e32 v96, 0x1300, v233
	v_lshl_add_u64 v[134:135], s[84:85], 0, v[96:97]
	v_add_u32_e32 v96, 0x1200, v232
	global_load_dwordx4 v[184:187], v[132:133], off nt
	global_load_dwordx4 v[180:183], v[134:135], off nt
	v_lshl_add_u64 v[132:133], s[84:85], 0, v[96:97]
	v_add_u32_e32 v96, 0x1300, v232
	v_lshl_add_u64 v[134:135], s[84:85], 0, v[96:97]
	v_add_u32_e32 v96, 0x1200, v231
	global_load_dwordx4 v[176:179], v[132:133], off nt
	global_load_dwordx4 v[172:175], v[134:135], off nt
	v_lshl_add_u64 v[132:133], s[84:85], 0, v[96:97]
	v_add_u32_e32 v96, 0x1300, v231
	v_lshl_add_u64 v[134:135], s[84:85], 0, v[96:97]
	v_add_u32_e32 v96, 0x1200, v230
	global_load_dwordx4 v[168:171], v[132:133], off nt
	global_load_dwordx4 v[164:167], v[134:135], off nt
	v_lshl_add_u64 v[132:133], s[84:85], 0, v[96:97]
	v_add_u32_e32 v96, 0x1300, v230
	v_lshl_add_u64 v[134:135], s[84:85], 0, v[96:97]
	v_add_u32_e32 v96, 0x1200, v229
	global_load_dwordx4 v[160:163], v[132:133], off nt
	global_load_dwordx4 v[156:159], v[134:135], off nt
	v_lshl_add_u64 v[132:133], s[84:85], 0, v[96:97]
	v_add_u32_e32 v96, 0x1300, v229
	v_lshl_add_u64 v[134:135], s[84:85], 0, v[96:97]
	v_add_u32_e32 v96, 0x1200, v221
	global_load_dwordx4 v[152:155], v[132:133], off nt
	global_load_dwordx4 v[148:151], v[134:135], off nt
	v_lshl_add_u64 v[132:133], s[84:85], 0, v[96:97]
	v_add_u32_e32 v96, 0x1300, v221
	v_lshl_add_u64 v[134:135], s[84:85], 0, v[96:97]
	v_add_u32_e32 v96, 0x1200, v220
	global_load_dwordx4 v[144:147], v[132:133], off nt
	global_load_dwordx4 v[140:143], v[134:135], off nt
	v_lshl_add_u64 v[132:133], s[84:85], 0, v[96:97]
	v_add_u32_e32 v96, 0x1300, v220
	v_lshl_add_u64 v[134:135], s[84:85], 0, v[96:97]
	global_load_dwordx4 v[136:139], v[132:133], off nt
	s_nop 0
	global_load_dwordx4 v[132:135], v[134:135], off nt
	v_cndmask_b32_e64 v96, 0, 1, s[16:17]
	v_lshlrev_b32_e32 v98, 1, v98
	v_cmp_ne_u32_e64 s[46:47], 1, v96
	s_andn2_b64 vcc, exec, s[16:17]
	v_lshlrev_b32_e32 v99, 11, v99
	s_waitcnt vmcnt(0) lgkmcnt(0)
	v_lshlrev_b32_e32 v234, 16, v236
	v_and_b32_e32 v233, 0xffff0000, v236
	v_lshlrev_b32_e32 v232, 16, v237
	v_and_b32_e32 v231, 0xffff0000, v237
	v_lshlrev_b32_e32 v230, 16, v238
	v_and_b32_e32 v229, 0xffff0000, v238
	v_lshlrev_b32_e32 v221, 16, v239
	v_and_b32_e32 v220, 0xffff0000, v239
	s_cbranch_vccnz .LBB0_788
	s_lshl_b32 s9, s71, 19
	v_mul_f32_e32 v96, v128, v234
	s_add_i32 s9, s9, s42
	v_mul_f32_e32 v235, v129, v233
	v_mul_f32_e32 v237, v130, v232
	v_mul_f32_e32 v238, v131, v231
	v_mul_f32_e32 v239, v124, v230
	v_mul_f32_e32 v240, v125, v229
	v_mul_f32_e32 v241, v126, v221
	v_cvt_pk_bf16_f32 v236, v96, v235
	v_add3_u32 v96, s9, v99, v98
	v_mul_f32_e32 v242, v127, v220
	v_cvt_pk_bf16_f32 v237, v237, v238
	v_cvt_pk_bf16_f32 v238, v239, v240
	v_cvt_pk_bf16_f32 v239, v241, v242
	v_lshl_add_u64 v[240:241], s[54:55], 0, v[96:97]
	global_store_dwordx4 v[240:241], v[236:239], off
	s_cbranch_execnz .LBB0_738

; __device__ __forceinline__ void unpack8(const u32x4 w, float* f) { f[0] = bf_lo(w.x); f[1] = bf_hi(w.x); f[2] = bf_lo(w.y); f[3] = bf_hi(w.y); f[4] = bf_lo(w.z); f[5] = bf_hi(w.z); f[6] = bf_lo(w.w); f[7] = bf_hi(w.w); }
; __device__ __forceinline__ u32x4 pack8(const float* f) { u32x4 w; w.x = cvt_pk_bf16(f[0], f[1]); w.y = cvt_pk_bf16(f[2], f[3]); w.z = cvt_pk_bf16(f[4], f[5]); w.w = cvt_pk_bf16(f[6], f[7]); return w; }
;     __device__ __forceinline__ void operator()(AccT& acc, const Unit& u, int wr, int wc, int fr, int fq) const {
;     ...
;                 for (int bj = 0; bj < 2; ++bj) {
;                     const int row = u.pm * 256 + ai * 128 + wr * 64 + m * 16 + fr, col = col0 + bj * 128;
;                     float g1[8]; unpack8(gw[ai][m][bj], g1);
;                     if (u.z == 0) {
; #pragma unroll
;                         for (int n = 0; n < 2; ++n)
; #pragma unroll
;                             for (int j = 0; j < 4; ++j) acc[ai][bj][m][n][j] *= __builtin_amdgcn_rcpf(__builtin_fmaxf(g1[n * 4 + j], 1.0e-30f));
;                     } else {
;                         float v[8];
; #pragma unroll
;                         for (int n = 0; n < 2; ++n)
; #pragma unroll
;                             for (int j = 0; j < 4; ++j) v[n * 4 + j] = acc[ai][bj][m][n][j] * g1[n * 4 + j];
;                         *(u32x4*)((char*)MIX + (unsigned)((row * DM + col) * 2)) = pack8(v);
;                     }
.LBB0_738:
	v_lshlrev_b32_e32 v231, 16, v188
	v_and_b32_e32 v230, 0xffff0000, v188
	v_lshlrev_b32_e32 v229, 16, v189
	v_and_b32_e32 v221, 0xffff0000, v189
	v_lshlrev_b32_e32 v220, 16, v190
	v_and_b32_e32 v190, 0xffff0000, v190
	v_lshlrev_b32_e32 v188, 16, v191
	s_and_b64 vcc, exec, s[46:47]
	v_and_b32_e32 v189, 0xffff0000, v191
	s_cbranch_vccnz .LBB0_789
	s_lshl_b32 s9, s71, 19
	v_mul_f32_e32 v96, v92, v231
	s_add_i32 s9, s43, s9
	v_mul_f32_e32 v191, v93, v230
	v_mul_f32_e32 v233, v94, v229
	v_mul_f32_e32 v234, v95, v221
	v_mul_f32_e32 v235, v88, v220
	v_mul_f32_e32 v236, v89, v190
	v_mul_f32_e32 v237, v90, v188
	v_cvt_pk_bf16_f32 v232, v96, v191
	v_add3_u32 v96, s9, v99, v98
	v_mul_f32_e32 v238, v91, v189
	v_cvt_pk_bf16_f32 v233, v233, v234
	v_cvt_pk_bf16_f32 v234, v235, v236
	v_cvt_pk_bf16_f32 v235, v237, v238
	v_lshl_add_u64 v[236:237], s[54:55], 0, v[96:97]
	global_store_dwordx4 v[236:237], v[232:235], off
	s_cbranch_execnz .LBB0_741

; __device__ __forceinline__ void unpack8(const u32x4 w, float* f) { f[0] = bf_lo(w.x); f[1] = bf_hi(w.x); f[2] = bf_lo(w.y); f[3] = bf_hi(w.y); f[4] = bf_lo(w.z); f[5] = bf_hi(w.z); f[6] = bf_lo(w.w); f[7] = bf_hi(w.w); }
; __device__ __forceinline__ u32x4 pack8(const float* f) { u32x4 w; w.x = cvt_pk_bf16(f[0], f[1]); w.y = cvt_pk_bf16(f[2], f[3]); w.z = cvt_pk_bf16(f[4], f[5]); w.w = cvt_pk_bf16(f[6], f[7]); return w; }
;     __device__ __forceinline__ void operator()(AccT& acc, const Unit& u, int wr, int wc, int fr, int fq) const {
;     ...
;                 for (int bj = 0; bj < 2; ++bj) {
;                     const int row = u.pm * 256 + ai * 128 + wr * 64 + m * 16 + fr, col = col0 + bj * 128;
;                     float g1[8]; unpack8(gw[ai][m][bj], g1);
;                     if (u.z == 0) {
; #pragma unroll
;                         for (int n = 0; n < 2; ++n)
; #pragma unroll
;                             for (int j = 0; j < 4; ++j) acc[ai][bj][m][n][j] *= __builtin_amdgcn_rcpf(__builtin_fmaxf(g1[n * 4 + j], 1.0e-30f));
;                     } else {
;                         float v[8];
; #pragma unroll
;                         for (int n = 0; n < 2; ++n)
; #pragma unroll
;                             for (int j = 0; j < 4; ++j) v[n * 4 + j] = acc[ai][bj][m][n][j] * g1[n * 4 + j];
;                         *(u32x4*)((char*)MIX + (unsigned)((row * DM + col) * 2)) = pack8(v);
;                     }
.LBB0_741:
	v_lshlrev_b32_e32 v220, 16, v184
	v_and_b32_e32 v191, 0xffff0000, v184
	v_lshlrev_b32_e32 v190, 16, v185
	v_and_b32_e32 v189, 0xffff0000, v185
	v_lshlrev_b32_e32 v188, 16, v186
	v_and_b32_e32 v186, 0xffff0000, v186
	v_lshlrev_b32_e32 v184, 16, v187
	s_and_b64 vcc, exec, s[46:47]
	v_and_b32_e32 v185, 0xffff0000, v187
	s_cbranch_vccnz .LBB0_790
	s_lshl_b32 s9, s71, 19
	v_mul_f32_e32 v96, v120, v220
	s_add_i32 s9, s50, s9
	v_mul_f32_e32 v187, v121, v191
	v_mul_f32_e32 v232, v116, v188
	v_mul_f32_e32 v233, v117, v186
	v_mul_f32_e32 v234, v118, v184
	v_mul_f32_e32 v235, v119, v185
	v_cvt_pk_bf16_f32 v230, v96, v187
	v_add3_u32 v96, s9, v99, v98
	v_mul_f32_e32 v221, v122, v190
	v_mul_f32_e32 v229, v123, v189
	v_cvt_pk_bf16_f32 v231, v221, v229
	v_cvt_pk_bf16_f32 v232, v232, v233
	v_cvt_pk_bf16_f32 v233, v234, v235
	v_lshl_add_u64 v[234:235], s[54:55], 0, v[96:97]
	global_store_dwordx4 v[234:235], v[230:233], off
	s_cbranch_execnz .LBB0_744

; __device__ __forceinline__ void unpack8(const u32x4 w, float* f) { f[0] = bf_lo(w.x); f[1] = bf_hi(w.x); f[2] = bf_lo(w.y); f[3] = bf_hi(w.y); f[4] = bf_lo(w.z); f[5] = bf_hi(w.z); f[6] = bf_lo(w.w); f[7] = bf_hi(w.w); }
; __device__ __forceinline__ u32x4 pack8(const float* f) { u32x4 w; w.x = cvt_pk_bf16(f[0], f[1]); w.y = cvt_pk_bf16(f[2], f[3]); w.z = cvt_pk_bf16(f[4], f[5]); w.w = cvt_pk_bf16(f[6], f[7]); return w; }
;     __device__ __forceinline__ void operator()(AccT& acc, const Unit& u, int wr, int wc, int fr, int fq) const {
;     ...
;                 for (int bj = 0; bj < 2; ++bj) {
;                     const int row = u.pm * 256 + ai * 128 + wr * 64 + m * 16 + fr, col = col0 + bj * 128;
;                     float g1[8]; unpack8(gw[ai][m][bj], g1);
;                     if (u.z == 0) {
; #pragma unroll
;                         for (int n = 0; n < 2; ++n)
; #pragma unroll
;                             for (int j = 0; j < 4; ++j) acc[ai][bj][m][n][j] *= __builtin_amdgcn_rcpf(__builtin_fmaxf(g1[n * 4 + j], 1.0e-30f));
;                     } else {
;                         float v[8];
; #pragma unroll
;                         for (int n = 0; n < 2; ++n)
; #pragma unroll
;                             for (int j = 0; j < 4; ++j) v[n * 4 + j] = acc[ai][bj][m][n][j] * g1[n * 4 + j];
;                         *(u32x4*)((char*)MIX + (unsigned)((row * DM + col) * 2)) = pack8(v);
;                     }
.LBB0_744:
	v_lshlrev_b32_e32 v188, 16, v180
	v_and_b32_e32 v187, 0xffff0000, v180
	v_lshlrev_b32_e32 v186, 16, v181
	v_and_b32_e32 v185, 0xffff0000, v181
	v_lshlrev_b32_e32 v184, 16, v182
	v_and_b32_e32 v182, 0xffff0000, v182
	v_lshlrev_b32_e32 v180, 16, v183
	s_and_b64 vcc, exec, s[46:47]
	v_and_b32_e32 v181, 0xffff0000, v183
	s_cbranch_vccnz .LBB0_791
	s_lshl_b32 s9, s71, 19
	v_mul_f32_e32 v96, v84, v188
	s_add_i32 s9, s51, s9
	v_mul_f32_e32 v183, v85, v187
	v_mul_f32_e32 v190, v87, v185
	v_mul_f32_e32 v191, v80, v184
	v_cvt_pk_bf16_f32 v230, v96, v183
	v_add3_u32 v96, s9, v99, v98
	v_mul_f32_e32 v189, v86, v186
	v_mul_f32_e32 v220, v81, v182
	v_cvt_pk_bf16_f32 v231, v189, v190
	v_cvt_pk_bf16_f32 v232, v191, v220
	v_lshl_add_u64 v[190:191], s[54:55], 0, v[96:97]
	v_mul_f32_e32 v221, v82, v180
	v_mul_f32_e32 v229, v83, v181
	v_cvt_pk_bf16_f32 v233, v221, v229
	global_store_dwordx4 v[190:191], v[230:233], off
	s_cbranch_execnz .LBB0_747

; __device__ __forceinline__ void unpack8(const u32x4 w, float* f) { f[0] = bf_lo(w.x); f[1] = bf_hi(w.x); f[2] = bf_lo(w.y); f[3] = bf_hi(w.y); f[4] = bf_lo(w.z); f[5] = bf_hi(w.z); f[6] = bf_lo(w.w); f[7] = bf_hi(w.w); }
; __device__ __forceinline__ u32x4 pack8(const float* f) { u32x4 w; w.x = cvt_pk_bf16(f[0], f[1]); w.y = cvt_pk_bf16(f[2], f[3]); w.z = cvt_pk_bf16(f[4], f[5]); w.w = cvt_pk_bf16(f[6], f[7]); return w; }
;     __device__ __forceinline__ void operator()(AccT& acc, const Unit& u, int wr, int wc, int fr, int fq) const {
;     ...
;                 for (int bj = 0; bj < 2; ++bj) {
;                     const int row = u.pm * 256 + ai * 128 + wr * 64 + m * 16 + fr, col = col0 + bj * 128;
;                     float g1[8]; unpack8(gw[ai][m][bj], g1);
;                     if (u.z == 0) {
; #pragma unroll
;                         for (int n = 0; n < 2; ++n)
; #pragma unroll
;                             for (int j = 0; j < 4; ++j) acc[ai][bj][m][n][j] *= __builtin_amdgcn_rcpf(__builtin_fmaxf(g1[n * 4 + j], 1.0e-30f));
;                     } else {
;                         float v[8];
; #pragma unroll
;                         for (int n = 0; n < 2; ++n)
; #pragma unroll
;                             for (int j = 0; j < 4; ++j) v[n * 4 + j] = acc[ai][bj][m][n][j] * g1[n * 4 + j];
;                         *(u32x4*)((char*)MIX + (unsigned)((row * DM + col) * 2)) = pack8(v);
;                     }
.LBB0_747:
	v_lshlrev_b32_e32 v184, 16, v176
	v_and_b32_e32 v183, 0xffff0000, v176
	v_lshlrev_b32_e32 v182, 16, v177
	v_and_b32_e32 v181, 0xffff0000, v177
	v_lshlrev_b32_e32 v180, 16, v178
	v_and_b32_e32 v178, 0xffff0000, v178
	v_lshlrev_b32_e32 v176, 16, v179
	s_and_b64 vcc, exec, s[46:47]
	v_and_b32_e32 v177, 0xffff0000, v179
	s_cbranch_vccnz .LBB0_792
	s_lshl_b32 s9, s71, 19
	v_mul_f32_e32 v96, v112, v184
	s_add_i32 s9, s56, s9
	v_mul_f32_e32 v179, v113, v183
	v_mul_f32_e32 v187, v115, v181
	v_mul_f32_e32 v188, v108, v180
	v_mul_f32_e32 v189, v109, v178
	v_mul_f32_e32 v190, v110, v176
	v_mul_f32_e32 v191, v111, v177
	v_cvt_pk_bf16_f32 v186, v96, v179
	v_add3_u32 v96, s9, v99, v98
	v_mul_f32_e32 v185, v114, v182
	v_cvt_pk_bf16_f32 v187, v185, v187
	v_cvt_pk_bf16_f32 v188, v188, v189
	v_cvt_pk_bf16_f32 v189, v190, v191
	v_lshl_add_u64 v[190:191], s[54:55], 0, v[96:97]
	global_store_dwordx4 v[190:191], v[186:189], off
	s_cbranch_execnz .LBB0_750

; __device__ __forceinline__ void unpack8(const u32x4 w, float* f) { f[0] = bf_lo(w.x); f[1] = bf_hi(w.x); f[2] = bf_lo(w.y); f[3] = bf_hi(w.y); f[4] = bf_lo(w.z); f[5] = bf_hi(w.z); f[6] = bf_lo(w.w); f[7] = bf_hi(w.w); }
; __device__ __forceinline__ u32x4 pack8(const float* f) { u32x4 w; w.x = cvt_pk_bf16(f[0], f[1]); w.y = cvt_pk_bf16(f[2], f[3]); w.z = cvt_pk_bf16(f[4], f[5]); w.w = cvt_pk_bf16(f[6], f[7]); return w; }
;     __device__ __forceinline__ void operator()(AccT& acc, const Unit& u, int wr, int wc, int fr, int fq) const {
;     ...
;                 for (int bj = 0; bj < 2; ++bj) {
;                     const int row = u.pm * 256 + ai * 128 + wr * 64 + m * 16 + fr, col = col0 + bj * 128;
;                     float g1[8]; unpack8(gw[ai][m][bj], g1);
;                     if (u.z == 0) {
; #pragma unroll
;                         for (int n = 0; n < 2; ++n)
; #pragma unroll
;                             for (int j = 0; j < 4; ++j) acc[ai][bj][m][n][j] *= __builtin_amdgcn_rcpf(__builtin_fmaxf(g1[n * 4 + j], 1.0e-30f));
;                     } else {
;                         float v[8];
; #pragma unroll
;                         for (int n = 0; n < 2; ++n)
; #pragma unroll
;                             for (int j = 0; j < 4; ++j) v[n * 4 + j] = acc[ai][bj][m][n][j] * g1[n * 4 + j];
;                         *(u32x4*)((char*)MIX + (unsigned)((row * DM + col) * 2)) = pack8(v);
;                     }
.LBB0_750:
	v_lshlrev_b32_e32 v180, 16, v172
	v_and_b32_e32 v179, 0xffff0000, v172
	v_lshlrev_b32_e32 v178, 16, v173
	v_and_b32_e32 v177, 0xffff0000, v173
	v_lshlrev_b32_e32 v176, 16, v174
	v_and_b32_e32 v174, 0xffff0000, v174
	v_lshlrev_b32_e32 v172, 16, v175
	s_and_b64 vcc, exec, s[46:47]
	v_and_b32_e32 v173, 0xffff0000, v175
	s_cbranch_vccnz .LBB0_793
	s_lshl_b32 s9, s71, 19
	v_mul_f32_e32 v96, v76, v180
	s_add_i32 s9, s57, s9
	v_mul_f32_e32 v175, v77, v179
	v_mul_f32_e32 v183, v79, v177
	v_mul_f32_e32 v184, v72, v176
	v_mul_f32_e32 v185, v73, v174
	v_mul_f32_e32 v186, v74, v172
	v_mul_f32_e32 v187, v75, v173
	v_cvt_pk_bf16_f32 v182, v96, v175
	v_add3_u32 v96, s9, v99, v98
	v_mul_f32_e32 v181, v78, v178
	v_cvt_pk_bf16_f32 v183, v181, v183
	v_cvt_pk_bf16_f32 v184, v184, v185
	v_cvt_pk_bf16_f32 v185, v186, v187
	v_lshl_add_u64 v[186:187], s[54:55], 0, v[96:97]
	global_store_dwordx4 v[186:187], v[182:185], off
	s_cbranch_execnz .LBB0_753

; __device__ __forceinline__ void unpack8(const u32x4 w, float* f) { f[0] = bf_lo(w.x); f[1] = bf_hi(w.x); f[2] = bf_lo(w.y); f[3] = bf_hi(w.y); f[4] = bf_lo(w.z); f[5] = bf_hi(w.z); f[6] = bf_lo(w.w); f[7] = bf_hi(w.w); }
; __device__ __forceinline__ u32x4 pack8(const float* f) { u32x4 w; w.x = cvt_pk_bf16(f[0], f[1]); w.y = cvt_pk_bf16(f[2], f[3]); w.z = cvt_pk_bf16(f[4], f[5]); w.w = cvt_pk_bf16(f[6], f[7]); return w; }
;     __device__ __forceinline__ void operator()(AccT& acc, const Unit& u, int wr, int wc, int fr, int fq) const {
;     ...
;                 for (int bj = 0; bj < 2; ++bj) {
;                     const int row = u.pm * 256 + ai * 128 + wr * 64 + m * 16 + fr, col = col0 + bj * 128;
;                     float g1[8]; unpack8(gw[ai][m][bj], g1);
;                     if (u.z == 0) {
; #pragma unroll
;                         for (int n = 0; n < 2; ++n)
; #pragma unroll
;                             for (int j = 0; j < 4; ++j) acc[ai][bj][m][n][j] *= __builtin_amdgcn_rcpf(__builtin_fmaxf(g1[n * 4 + j], 1.0e-30f));
;                     } else {
;                         float v[8];
; #pragma unroll
;                         for (int n = 0; n < 2; ++n)
; #pragma unroll
;                             for (int j = 0; j < 4; ++j) v[n * 4 + j] = acc[ai][bj][m][n][j] * g1[n * 4 + j];
;                         *(u32x4*)((char*)MIX + (unsigned)((row * DM + col) * 2)) = pack8(v);
;                     }
.LBB0_753:
	v_lshlrev_b32_e32 v176, 16, v168
	v_and_b32_e32 v175, 0xffff0000, v168
	v_lshlrev_b32_e32 v174, 16, v169
	v_and_b32_e32 v173, 0xffff0000, v169
	v_lshlrev_b32_e32 v172, 16, v170
	v_and_b32_e32 v170, 0xffff0000, v170
	v_lshlrev_b32_e32 v168, 16, v171
	s_and_b64 vcc, exec, s[46:47]
	v_and_b32_e32 v169, 0xffff0000, v171
	s_cbranch_vccnz .LBB0_794
	s_lshl_b32 s9, s71, 19
	v_mul_f32_e32 v96, v104, v176
	s_add_i32 s9, s58, s9
	v_mul_f32_e32 v171, v105, v175
	v_mul_f32_e32 v179, v107, v173
	v_mul_f32_e32 v180, v100, v172
	v_mul_f32_e32 v181, v101, v170
	v_mul_f32_e32 v182, v102, v168
	v_mul_f32_e32 v183, v103, v169
	v_cvt_pk_bf16_f32 v178, v96, v171
	v_add3_u32 v96, s9, v99, v98
	v_mul_f32_e32 v177, v106, v174
	v_cvt_pk_bf16_f32 v179, v177, v179
	v_cvt_pk_bf16_f32 v180, v180, v181
	v_cvt_pk_bf16_f32 v181, v182, v183
	v_lshl_add_u64 v[182:183], s[54:55], 0, v[96:97]
	global_store_dwordx4 v[182:183], v[178:181], off
	s_cbranch_execnz .LBB0_756

; __device__ __forceinline__ void unpack8(const u32x4 w, float* f) { f[0] = bf_lo(w.x); f[1] = bf_hi(w.x); f[2] = bf_lo(w.y); f[3] = bf_hi(w.y); f[4] = bf_lo(w.z); f[5] = bf_hi(w.z); f[6] = bf_lo(w.w); f[7] = bf_hi(w.w); }
; __device__ __forceinline__ u32x4 pack8(const float* f) { u32x4 w; w.x = cvt_pk_bf16(f[0], f[1]); w.y = cvt_pk_bf16(f[2], f[3]); w.z = cvt_pk_bf16(f[4], f[5]); w.w = cvt_pk_bf16(f[6], f[7]); return w; }
;     __device__ __forceinline__ void operator()(AccT& acc, const Unit& u, int wr, int wc, int fr, int fq) const {
;     ...
;                 for (int bj = 0; bj < 2; ++bj) {
;                     const int row = u.pm * 256 + ai * 128 + wr * 64 + m * 16 + fr, col = col0 + bj * 128;
;                     float g1[8]; unpack8(gw[ai][m][bj], g1);
;                     if (u.z == 0) {
; #pragma unroll
;                         for (int n = 0; n < 2; ++n)
; #pragma unroll
;                             for (int j = 0; j < 4; ++j) acc[ai][bj][m][n][j] *= __builtin_amdgcn_rcpf(__builtin_fmaxf(g1[n * 4 + j], 1.0e-30f));
;                     } else {
;                         float v[8];
; #pragma unroll
;                         for (int n = 0; n < 2; ++n)
; #pragma unroll
;                             for (int j = 0; j < 4; ++j) v[n * 4 + j] = acc[ai][bj][m][n][j] * g1[n * 4 + j];
;                         *(u32x4*)((char*)MIX + (unsigned)((row * DM + col) * 2)) = pack8(v);
;                     }
.LBB0_756:
	v_lshlrev_b32_e32 v172, 16, v164
	v_and_b32_e32 v171, 0xffff0000, v164
	v_lshlrev_b32_e32 v170, 16, v165
	v_and_b32_e32 v169, 0xffff0000, v165
	v_lshlrev_b32_e32 v168, 16, v166
	v_and_b32_e32 v166, 0xffff0000, v166
	v_lshlrev_b32_e32 v164, 16, v167
	s_and_b64 vcc, exec, s[46:47]
	v_and_b32_e32 v165, 0xffff0000, v167
	s_cbranch_vccnz .LBB0_795
	s_lshl_b32 s9, s71, 19
	v_mul_f32_e32 v96, v68, v172
	s_add_i32 s9, s59, s9
	v_mul_f32_e32 v167, v69, v171
	v_mul_f32_e32 v175, v71, v169
	v_mul_f32_e32 v176, v64, v168
	v_mul_f32_e32 v177, v65, v166
	v_mul_f32_e32 v178, v66, v164
	v_mul_f32_e32 v179, v67, v165
	v_cvt_pk_bf16_f32 v174, v96, v167
	v_add3_u32 v96, s9, v99, v98
	v_mul_f32_e32 v173, v70, v170
	v_cvt_pk_bf16_f32 v175, v173, v175
	v_cvt_pk_bf16_f32 v176, v176, v177
	v_cvt_pk_bf16_f32 v177, v178, v179
	v_lshl_add_u64 v[178:179], s[54:55], 0, v[96:97]
	global_store_dwordx4 v[178:179], v[174:177], off
	s_cbranch_execnz .LBB0_759

; __device__ __forceinline__ void unpack8(const u32x4 w, float* f) { f[0] = bf_lo(w.x); f[1] = bf_hi(w.x); f[2] = bf_lo(w.y); f[3] = bf_hi(w.y); f[4] = bf_lo(w.z); f[5] = bf_hi(w.z); f[6] = bf_lo(w.w); f[7] = bf_hi(w.w); }
; __device__ __forceinline__ u32x4 pack8(const float* f) { u32x4 w; w.x = cvt_pk_bf16(f[0], f[1]); w.y = cvt_pk_bf16(f[2], f[3]); w.z = cvt_pk_bf16(f[4], f[5]); w.w = cvt_pk_bf16(f[6], f[7]); return w; }
;     __device__ __forceinline__ void operator()(AccT& acc, const Unit& u, int wr, int wc, int fr, int fq) const {
;     ...
;                 for (int bj = 0; bj < 2; ++bj) {
;                     const int row = u.pm * 256 + ai * 128 + wr * 64 + m * 16 + fr, col = col0 + bj * 128;
;                     float g1[8]; unpack8(gw[ai][m][bj], g1);
;                     if (u.z == 0) {
; #pragma unroll
;                         for (int n = 0; n < 2; ++n)
; #pragma unroll
;                             for (int j = 0; j < 4; ++j) acc[ai][bj][m][n][j] *= __builtin_amdgcn_rcpf(__builtin_fmaxf(g1[n * 4 + j], 1.0e-30f));
;                     } else {
;                         float v[8];
; #pragma unroll
;                         for (int n = 0; n < 2; ++n)
; #pragma unroll
;                             for (int j = 0; j < 4; ++j) v[n * 4 + j] = acc[ai][bj][m][n][j] * g1[n * 4 + j];
;                         *(u32x4*)((char*)MIX + (unsigned)((row * DM + col) * 2)) = pack8(v);
;                     }
.LBB0_759:
	v_lshlrev_b32_e32 v168, 16, v160
	v_and_b32_e32 v167, 0xffff0000, v160
	v_lshlrev_b32_e32 v166, 16, v161
	v_and_b32_e32 v165, 0xffff0000, v161
	v_lshlrev_b32_e32 v164, 16, v162
	v_and_b32_e32 v162, 0xffff0000, v162
	v_lshlrev_b32_e32 v160, 16, v163
	s_and_b64 vcc, exec, s[46:47]
	v_and_b32_e32 v161, 0xffff0000, v163
	s_cbranch_vccnz .LBB0_796
	s_lshl_b32 s9, s71, 19
	v_mul_f32_e32 v96, v60, v168
	s_add_i32 s9, s60, s9
	v_mul_f32_e32 v163, v61, v167
	v_mul_f32_e32 v171, v63, v165
	v_mul_f32_e32 v172, v56, v164
	v_mul_f32_e32 v173, v57, v162
	v_mul_f32_e32 v174, v58, v160
	v_mul_f32_e32 v175, v59, v161
	v_cvt_pk_bf16_f32 v170, v96, v163
	v_add3_u32 v96, s9, v99, v98
	v_mul_f32_e32 v169, v62, v166
	v_cvt_pk_bf16_f32 v171, v169, v171
	v_cvt_pk_bf16_f32 v172, v172, v173
	v_cvt_pk_bf16_f32 v173, v174, v175
	v_lshl_add_u64 v[174:175], s[54:55], 0, v[96:97]
	global_store_dwordx4 v[174:175], v[170:173], off
	s_cbranch_execnz .LBB0_762

; __device__ __forceinline__ void unpack8(const u32x4 w, float* f) { f[0] = bf_lo(w.x); f[1] = bf_hi(w.x); f[2] = bf_lo(w.y); f[3] = bf_hi(w.y); f[4] = bf_lo(w.z); f[5] = bf_hi(w.z); f[6] = bf_lo(w.w); f[7] = bf_hi(w.w); }
; __device__ __forceinline__ u32x4 pack8(const float* f) { u32x4 w; w.x = cvt_pk_bf16(f[0], f[1]); w.y = cvt_pk_bf16(f[2], f[3]); w.z = cvt_pk_bf16(f[4], f[5]); w.w = cvt_pk_bf16(f[6], f[7]); return w; }
;     __device__ __forceinline__ void operator()(AccT& acc, const Unit& u, int wr, int wc, int fr, int fq) const {
;     ...
;                 for (int bj = 0; bj < 2; ++bj) {
;                     const int row = u.pm * 256 + ai * 128 + wr * 64 + m * 16 + fr, col = col0 + bj * 128;
;                     float g1[8]; unpack8(gw[ai][m][bj], g1);
;                     if (u.z == 0) {
; #pragma unroll
;                         for (int n = 0; n < 2; ++n)
; #pragma unroll
;                             for (int j = 0; j < 4; ++j) acc[ai][bj][m][n][j] *= __builtin_amdgcn_rcpf(__builtin_fmaxf(g1[n * 4 + j], 1.0e-30f));
;                     } else {
;                         float v[8];
; #pragma unroll
;                         for (int n = 0; n < 2; ++n)
; #pragma unroll
;                             for (int j = 0; j < 4; ++j) v[n * 4 + j] = acc[ai][bj][m][n][j] * g1[n * 4 + j];
;                         *(u32x4*)((char*)MIX + (unsigned)((row * DM + col) * 2)) = pack8(v);
;                     }
.LBB0_762:
	v_lshlrev_b32_e32 v164, 16, v156
	v_and_b32_e32 v163, 0xffff0000, v156
	v_lshlrev_b32_e32 v162, 16, v157
	v_and_b32_e32 v161, 0xffff0000, v157
	v_lshlrev_b32_e32 v160, 16, v158
	v_and_b32_e32 v158, 0xffff0000, v158
	v_lshlrev_b32_e32 v156, 16, v159
	s_and_b64 vcc, exec, s[46:47]
	v_and_b32_e32 v157, 0xffff0000, v159
	s_cbranch_vccnz .LBB0_797
	s_lshl_b32 s9, s71, 19
	v_mul_f32_e32 v96, v28, v164
	s_add_i32 s9, s61, s9
	v_mul_f32_e32 v159, v29, v163
	v_mul_f32_e32 v167, v31, v161
	v_mul_f32_e32 v168, v24, v160
	v_mul_f32_e32 v169, v25, v158
	v_mul_f32_e32 v170, v26, v156
	v_mul_f32_e32 v171, v27, v157
	v_cvt_pk_bf16_f32 v166, v96, v159
	v_add3_u32 v96, s9, v99, v98
	v_mul_f32_e32 v165, v30, v162
	v_cvt_pk_bf16_f32 v167, v165, v167
	v_cvt_pk_bf16_f32 v168, v168, v169
	v_cvt_pk_bf16_f32 v169, v170, v171
	v_lshl_add_u64 v[170:171], s[54:55], 0, v[96:97]
	global_store_dwordx4 v[170:171], v[166:169], off
	s_cbranch_execnz .LBB0_765

; __device__ __forceinline__ void unpack8(const u32x4 w, float* f) { f[0] = bf_lo(w.x); f[1] = bf_hi(w.x); f[2] = bf_lo(w.y); f[3] = bf_hi(w.y); f[4] = bf_lo(w.z); f[5] = bf_hi(w.z); f[6] = bf_lo(w.w); f[7] = bf_hi(w.w); }
; __device__ __forceinline__ u32x4 pack8(const float* f) { u32x4 w; w.x = cvt_pk_bf16(f[0], f[1]); w.y = cvt_pk_bf16(f[2], f[3]); w.z = cvt_pk_bf16(f[4], f[5]); w.w = cvt_pk_bf16(f[6], f[7]); return w; }
;     __device__ __forceinline__ void operator()(AccT& acc, const Unit& u, int wr, int wc, int fr, int fq) const {
;     ...
;                 for (int bj = 0; bj < 2; ++bj) {
;                     const int row = u.pm * 256 + ai * 128 + wr * 64 + m * 16 + fr, col = col0 + bj * 128;
;                     float g1[8]; unpack8(gw[ai][m][bj], g1);
;                     if (u.z == 0) {
; #pragma unroll
;                         for (int n = 0; n < 2; ++n)
; #pragma unroll
;                             for (int j = 0; j < 4; ++j) acc[ai][bj][m][n][j] *= __builtin_amdgcn_rcpf(__builtin_fmaxf(g1[n * 4 + j], 1.0e-30f));
;                     } else {
;                         float v[8];
; #pragma unroll
;                         for (int n = 0; n < 2; ++n)
; #pragma unroll
;                             for (int j = 0; j < 4; ++j) v[n * 4 + j] = acc[ai][bj][m][n][j] * g1[n * 4 + j];
;                         *(u32x4*)((char*)MIX + (unsigned)((row * DM + col) * 2)) = pack8(v);
;                     }
.LBB0_765:
	v_lshlrev_b32_e32 v160, 16, v152
	v_and_b32_e32 v159, 0xffff0000, v152
	v_lshlrev_b32_e32 v158, 16, v153
	v_and_b32_e32 v157, 0xffff0000, v153
	v_lshlrev_b32_e32 v156, 16, v154
	v_and_b32_e32 v154, 0xffff0000, v154
	v_lshlrev_b32_e32 v152, 16, v155
	s_and_b64 vcc, exec, s[46:47]
	v_and_b32_e32 v153, 0xffff0000, v155
	s_cbranch_vccnz .LBB0_798
	s_lshl_b32 s9, s71, 19
	v_mul_f32_e32 v96, v52, v160
	s_add_i32 s9, s62, s9
	v_mul_f32_e32 v155, v53, v159
	v_mul_f32_e32 v163, v55, v157
	v_mul_f32_e32 v164, v48, v156
	v_mul_f32_e32 v165, v49, v154
	v_mul_f32_e32 v166, v50, v152
	v_mul_f32_e32 v167, v51, v153
	v_cvt_pk_bf16_f32 v162, v96, v155
	v_add3_u32 v96, s9, v99, v98
	v_mul_f32_e32 v161, v54, v158
	v_cvt_pk_bf16_f32 v163, v161, v163
	v_cvt_pk_bf16_f32 v164, v164, v165
	v_cvt_pk_bf16_f32 v165, v166, v167
	v_lshl_add_u64 v[166:167], s[54:55], 0, v[96:97]
	global_store_dwordx4 v[166:167], v[162:165], off
	s_cbranch_execnz .LBB0_768

; __device__ __forceinline__ void unpack8(const u32x4 w, float* f) { f[0] = bf_lo(w.x); f[1] = bf_hi(w.x); f[2] = bf_lo(w.y); f[3] = bf_hi(w.y); f[4] = bf_lo(w.z); f[5] = bf_hi(w.z); f[6] = bf_lo(w.w); f[7] = bf_hi(w.w); }
; __device__ __forceinline__ u32x4 pack8(const float* f) { u32x4 w; w.x = cvt_pk_bf16(f[0], f[1]); w.y = cvt_pk_bf16(f[2], f[3]); w.z = cvt_pk_bf16(f[4], f[5]); w.w = cvt_pk_bf16(f[6], f[7]); return w; }
;     __device__ __forceinline__ void operator()(AccT& acc, const Unit& u, int wr, int wc, int fr, int fq) const {
;     ...
;                 for (int bj = 0; bj < 2; ++bj) {
;                     const int row = u.pm * 256 + ai * 128 + wr * 64 + m * 16 + fr, col = col0 + bj * 128;
;                     float g1[8]; unpack8(gw[ai][m][bj], g1);
;                     if (u.z == 0) {
; #pragma unroll
;                         for (int n = 0; n < 2; ++n)
; #pragma unroll
;                             for (int j = 0; j < 4; ++j) acc[ai][bj][m][n][j] *= __builtin_amdgcn_rcpf(__builtin_fmaxf(g1[n * 4 + j], 1.0e-30f));
;                     } else {
;                         float v[8];
; #pragma unroll
;                         for (int n = 0; n < 2; ++n)
; #pragma unroll
;                             for (int j = 0; j < 4; ++j) v[n * 4 + j] = acc[ai][bj][m][n][j] * g1[n * 4 + j];
;                         *(u32x4*)((char*)MIX + (unsigned)((row * DM + col) * 2)) = pack8(v);
;                     }
.LBB0_768:
	v_lshlrev_b32_e32 v156, 16, v148
	v_and_b32_e32 v155, 0xffff0000, v148
	v_lshlrev_b32_e32 v154, 16, v149
	v_and_b32_e32 v153, 0xffff0000, v149
	v_lshlrev_b32_e32 v152, 16, v150
	v_and_b32_e32 v150, 0xffff0000, v150
	v_lshlrev_b32_e32 v148, 16, v151
	s_and_b64 vcc, exec, s[46:47]
	v_and_b32_e32 v149, 0xffff0000, v151
	s_cbranch_vccnz .LBB0_799
	s_lshl_b32 s9, s71, 19
	v_mul_f32_e32 v96, v20, v156
	s_add_i32 s9, s63, s9
	v_mul_f32_e32 v151, v21, v155
	v_mul_f32_e32 v159, v23, v153
	v_mul_f32_e32 v160, v16, v152
	v_mul_f32_e32 v161, v17, v150
	v_mul_f32_e32 v162, v18, v148
	v_mul_f32_e32 v163, v19, v149
	v_cvt_pk_bf16_f32 v158, v96, v151
	v_add3_u32 v96, s9, v99, v98
	v_mul_f32_e32 v157, v22, v154
	v_cvt_pk_bf16_f32 v159, v157, v159
	v_cvt_pk_bf16_f32 v160, v160, v161
	v_cvt_pk_bf16_f32 v161, v162, v163
	v_lshl_add_u64 v[162:163], s[54:55], 0, v[96:97]
	global_store_dwordx4 v[162:163], v[158:161], off
	s_cbranch_execnz .LBB0_771

; __device__ __forceinline__ void unpack8(const u32x4 w, float* f) { f[0] = bf_lo(w.x); f[1] = bf_hi(w.x); f[2] = bf_lo(w.y); f[3] = bf_hi(w.y); f[4] = bf_lo(w.z); f[5] = bf_hi(w.z); f[6] = bf_lo(w.w); f[7] = bf_hi(w.w); }
; __device__ __forceinline__ u32x4 pack8(const float* f) { u32x4 w; w.x = cvt_pk_bf16(f[0], f[1]); w.y = cvt_pk_bf16(f[2], f[3]); w.z = cvt_pk_bf16(f[4], f[5]); w.w = cvt_pk_bf16(f[6], f[7]); return w; }
;     __device__ __forceinline__ void operator()(AccT& acc, const Unit& u, int wr, int wc, int fr, int fq) const {
;     ...
;                 for (int bj = 0; bj < 2; ++bj) {
;                     const int row = u.pm * 256 + ai * 128 + wr * 64 + m * 16 + fr, col = col0 + bj * 128;
;                     float g1[8]; unpack8(gw[ai][m][bj], g1);
;                     if (u.z == 0) {
; #pragma unroll
;                         for (int n = 0; n < 2; ++n)
; #pragma unroll
;                             for (int j = 0; j < 4; ++j) acc[ai][bj][m][n][j] *= __builtin_amdgcn_rcpf(__builtin_fmaxf(g1[n * 4 + j], 1.0e-30f));
;                     } else {
;                         float v[8];
; #pragma unroll
;                         for (int n = 0; n < 2; ++n)
; #pragma unroll
;                             for (int j = 0; j < 4; ++j) v[n * 4 + j] = acc[ai][bj][m][n][j] * g1[n * 4 + j];
;                         *(u32x4*)((char*)MIX + (unsigned)((row * DM + col) * 2)) = pack8(v);
;                     }
.LBB0_771:
	v_lshlrev_b32_e32 v152, 16, v144
	v_and_b32_e32 v151, 0xffff0000, v144
	v_lshlrev_b32_e32 v150, 16, v145
	v_and_b32_e32 v149, 0xffff0000, v145
	v_lshlrev_b32_e32 v148, 16, v146
	v_and_b32_e32 v146, 0xffff0000, v146
	v_lshlrev_b32_e32 v144, 16, v147
	s_and_b64 vcc, exec, s[46:47]
	v_and_b32_e32 v145, 0xffff0000, v147
	s_cbranch_vccnz .LBB0_800
	s_lshl_b32 s9, s71, 19
	v_mul_f32_e32 v96, v44, v152
	s_add_i32 s9, s64, s9
	v_mul_f32_e32 v147, v45, v151
	v_mul_f32_e32 v155, v47, v149
	v_mul_f32_e32 v156, v40, v148
	v_mul_f32_e32 v157, v41, v146
	v_mul_f32_e32 v158, v42, v144
	v_mul_f32_e32 v159, v43, v145
	v_cvt_pk_bf16_f32 v154, v96, v147
	v_add3_u32 v96, s9, v99, v98
	v_mul_f32_e32 v153, v46, v150
	v_cvt_pk_bf16_f32 v155, v153, v155
	v_cvt_pk_bf16_f32 v156, v156, v157
	v_cvt_pk_bf16_f32 v157, v158, v159
	v_lshl_add_u64 v[158:159], s[54:55], 0, v[96:97]
	global_store_dwordx4 v[158:159], v[154:157], off
	s_cbranch_execnz .LBB0_774

; __device__ __forceinline__ void unpack8(const u32x4 w, float* f) { f[0] = bf_lo(w.x); f[1] = bf_hi(w.x); f[2] = bf_lo(w.y); f[3] = bf_hi(w.y); f[4] = bf_lo(w.z); f[5] = bf_hi(w.z); f[6] = bf_lo(w.w); f[7] = bf_hi(w.w); }
; __device__ __forceinline__ u32x4 pack8(const float* f) { u32x4 w; w.x = cvt_pk_bf16(f[0], f[1]); w.y = cvt_pk_bf16(f[2], f[3]); w.z = cvt_pk_bf16(f[4], f[5]); w.w = cvt_pk_bf16(f[6], f[7]); return w; }
;     __device__ __forceinline__ void operator()(AccT& acc, const Unit& u, int wr, int wc, int fr, int fq) const {
;     ...
;                 for (int bj = 0; bj < 2; ++bj) {
;                     const int row = u.pm * 256 + ai * 128 + wr * 64 + m * 16 + fr, col = col0 + bj * 128;
;                     float g1[8]; unpack8(gw[ai][m][bj], g1);
;                     if (u.z == 0) {
; #pragma unroll
;                         for (int n = 0; n < 2; ++n)
; #pragma unroll
;                             for (int j = 0; j < 4; ++j) acc[ai][bj][m][n][j] *= __builtin_amdgcn_rcpf(__builtin_fmaxf(g1[n * 4 + j], 1.0e-30f));
;                     } else {
;                         float v[8];
; #pragma unroll
;                         for (int n = 0; n < 2; ++n)
; #pragma unroll
;                             for (int j = 0; j < 4; ++j) v[n * 4 + j] = acc[ai][bj][m][n][j] * g1[n * 4 + j];
;                         *(u32x4*)((char*)MIX + (unsigned)((row * DM + col) * 2)) = pack8(v);
;                     }
.LBB0_774:
	v_lshlrev_b32_e32 v148, 16, v140
	v_and_b32_e32 v147, 0xffff0000, v140
	v_lshlrev_b32_e32 v146, 16, v141
	v_and_b32_e32 v145, 0xffff0000, v141
	v_lshlrev_b32_e32 v144, 16, v142
	v_and_b32_e32 v142, 0xffff0000, v142
	v_lshlrev_b32_e32 v140, 16, v143
	s_and_b64 vcc, exec, s[46:47]
	v_and_b32_e32 v141, 0xffff0000, v143
	s_cbranch_vccnz .LBB0_801
	s_lshl_b32 s9, s71, 19
	v_mul_f32_e32 v96, v12, v148
	s_add_i32 s9, s65, s9
	v_mul_f32_e32 v143, v13, v147
	v_mul_f32_e32 v151, v15, v145
	v_mul_f32_e32 v152, v8, v144
	v_mul_f32_e32 v153, v9, v142
	v_mul_f32_e32 v154, v10, v140
	v_mul_f32_e32 v155, v11, v141
	v_cvt_pk_bf16_f32 v150, v96, v143
	v_add3_u32 v96, s9, v99, v98
	v_mul_f32_e32 v149, v14, v146
	v_cvt_pk_bf16_f32 v151, v149, v151
	v_cvt_pk_bf16_f32 v152, v152, v153
	v_cvt_pk_bf16_f32 v153, v154, v155
	v_lshl_add_u64 v[154:155], s[54:55], 0, v[96:97]
	global_store_dwordx4 v[154:155], v[150:153], off
	s_cbranch_execnz .LBB0_777

; __device__ __forceinline__ void unpack8(const u32x4 w, float* f) { f[0] = bf_lo(w.x); f[1] = bf_hi(w.x); f[2] = bf_lo(w.y); f[3] = bf_hi(w.y); f[4] = bf_lo(w.z); f[5] = bf_hi(w.z); f[6] = bf_lo(w.w); f[7] = bf_hi(w.w); }
; __device__ __forceinline__ u32x4 pack8(const float* f) { u32x4 w; w.x = cvt_pk_bf16(f[0], f[1]); w.y = cvt_pk_bf16(f[2], f[3]); w.z = cvt_pk_bf16(f[4], f[5]); w.w = cvt_pk_bf16(f[6], f[7]); return w; }
;     __device__ __forceinline__ void operator()(AccT& acc, const Unit& u, int wr, int wc, int fr, int fq) const {
;     ...
;                 for (int bj = 0; bj < 2; ++bj) {
;                     const int row = u.pm * 256 + ai * 128 + wr * 64 + m * 16 + fr, col = col0 + bj * 128;
;                     float g1[8]; unpack8(gw[ai][m][bj], g1);
;                     if (u.z == 0) {
; #pragma unroll
;                         for (int n = 0; n < 2; ++n)
; #pragma unroll
;                             for (int j = 0; j < 4; ++j) acc[ai][bj][m][n][j] *= __builtin_amdgcn_rcpf(__builtin_fmaxf(g1[n * 4 + j], 1.0e-30f));
;                     } else {
;                         float v[8];
; #pragma unroll
;                         for (int n = 0; n < 2; ++n)
; #pragma unroll
;                             for (int j = 0; j < 4; ++j) v[n * 4 + j] = acc[ai][bj][m][n][j] * g1[n * 4 + j];
;                         *(u32x4*)((char*)MIX + (unsigned)((row * DM + col) * 2)) = pack8(v);
;                     }
.LBB0_777:
	v_lshlrev_b32_e32 v144, 16, v136
	v_and_b32_e32 v143, 0xffff0000, v136
	v_lshlrev_b32_e32 v142, 16, v137
	v_and_b32_e32 v141, 0xffff0000, v137
	v_lshlrev_b32_e32 v140, 16, v138
	v_and_b32_e32 v138, 0xffff0000, v138
	v_lshlrev_b32_e32 v136, 16, v139
	s_and_b64 vcc, exec, s[46:47]
	v_and_b32_e32 v137, 0xffff0000, v139
	s_cbranch_vccnz .LBB0_802
	s_lshl_b32 s9, s71, 19
	v_mul_f32_e32 v96, v36, v144
	s_add_i32 s9, s66, s9
	v_mul_f32_e32 v139, v37, v143
	v_mul_f32_e32 v147, v39, v141
	v_mul_f32_e32 v148, v32, v140
	v_mul_f32_e32 v149, v33, v138
	v_mul_f32_e32 v150, v34, v136
	v_mul_f32_e32 v151, v35, v137
	v_cvt_pk_bf16_f32 v146, v96, v139
	v_add3_u32 v96, s9, v99, v98
	v_mul_f32_e32 v145, v38, v142
	v_cvt_pk_bf16_f32 v147, v145, v147
	v_cvt_pk_bf16_f32 v148, v148, v149
	v_cvt_pk_bf16_f32 v149, v150, v151
	v_lshl_add_u64 v[150:151], s[54:55], 0, v[96:97]
	global_store_dwordx4 v[150:151], v[146:149], off
	s_cbranch_execnz .LBB0_780

; __device__ __forceinline__ void unpack8(const u32x4 w, float* f) { f[0] = bf_lo(w.x); f[1] = bf_hi(w.x); f[2] = bf_lo(w.y); f[3] = bf_hi(w.y); f[4] = bf_lo(w.z); f[5] = bf_hi(w.z); f[6] = bf_lo(w.w); f[7] = bf_hi(w.w); }
; __device__ __forceinline__ u32x4 pack8(const float* f) { u32x4 w; w.x = cvt_pk_bf16(f[0], f[1]); w.y = cvt_pk_bf16(f[2], f[3]); w.z = cvt_pk_bf16(f[4], f[5]); w.w = cvt_pk_bf16(f[6], f[7]); return w; }
;     __device__ __forceinline__ void operator()(AccT& acc, const Unit& u, int wr, int wc, int fr, int fq) const {
;     ...
;                 for (int bj = 0; bj < 2; ++bj) {
;                     const int row = u.pm * 256 + ai * 128 + wr * 64 + m * 16 + fr, col = col0 + bj * 128;
;                     float g1[8]; unpack8(gw[ai][m][bj], g1);
;                     if (u.z == 0) {
; #pragma unroll
;                         for (int n = 0; n < 2; ++n)
; #pragma unroll
;                             for (int j = 0; j < 4; ++j) acc[ai][bj][m][n][j] *= __builtin_amdgcn_rcpf(__builtin_fmaxf(g1[n * 4 + j], 1.0e-30f));
;                     } else {
;                         float v[8];
; #pragma unroll
;                         for (int n = 0; n < 2; ++n)
; #pragma unroll
;                             for (int j = 0; j < 4; ++j) v[n * 4 + j] = acc[ai][bj][m][n][j] * g1[n * 4 + j];
;                         *(u32x4*)((char*)MIX + (unsigned)((row * DM + col) * 2)) = pack8(v);
;                     }
.LBB0_780:
	v_lshlrev_b32_e32 v140, 16, v132
	v_and_b32_e32 v139, 0xffff0000, v132
	v_lshlrev_b32_e32 v138, 16, v133
	v_and_b32_e32 v137, 0xffff0000, v133
	v_lshlrev_b32_e32 v136, 16, v134
	v_and_b32_e32 v134, 0xffff0000, v134
	v_lshlrev_b32_e32 v132, 16, v135
	s_and_b64 vcc, exec, s[46:47]
	v_and_b32_e32 v133, 0xffff0000, v135
	s_cbranch_vccnz .LBB0_803
	s_lshl_b32 s9, s71, 19
	v_mul_f32_e32 v96, v4, v140
	s_add_i32 s9, s67, s9
	v_mul_f32_e32 v135, v5, v139
	v_cvt_pk_bf16_f32 v142, v96, v135
	v_add3_u32 v96, s9, v99, v98
	v_mul_f32_e32 v143, v7, v137
	v_mul_f32_e32 v144, v0, v136
	v_mul_f32_e32 v145, v1, v134
	v_lshl_add_u64 v[98:99], s[54:55], 0, v[96:97]
	v_mul_f32_e32 v141, v6, v138
	v_mul_f32_e32 v146, v2, v132
	v_mul_f32_e32 v147, v3, v133
	v_cvt_pk_bf16_f32 v143, v141, v143
	v_cvt_pk_bf16_f32 v144, v144, v145
	v_cvt_pk_bf16_f32 v145, v146, v147
	global_store_dwordx4 v[98:99], v[142:145], off
	s_cbranch_execnz .LBB0_783

; #define LAS __attribute__((address_space(3)))
; template <int KSTEPS  >
; __device__ __forceinline__ void small_mma_ksplit(f32x4 (&acc)[2], const bf16_t* A, int lda, const bf16_t* Bt, int ldb, int n0, LAS unsigned char* lds, const SmallId& id) {
;     ...
;     for (int ks = 0; ks < KSTEPS; ++ks) {
;         bf16x8 a[8], b[2];
; #pragma unroll
;         for (int rb = 0; rb < 8; ++rb) a[rb] = *(const bf16x8*)(ap + (size_t)(16 * rb) * lda + 32 * ks);
;         b[0] = *(const bf16x8*)(bp + 32 * ks); b[1] = *(const bf16x8*)(bp + (size_t)16 * ldb + 32 * ks);
; #pragma unroll
;         for (int rb = 0; rb < 8; ++rb) { part[rb][0] = __builtin_amdgcn_mfma_f32_16x16x32_bf16(b[0], a[rb], part[rb][0], 0, 0, 0); part[rb][1] = __builtin_amdgcn_mfma_f32_16x16x32_bf16(b[1], a[rb], part[rb][1], 0, 0, 0); }
;     }
;     LAS f32x4* red = (LAS f32x4*)lds;
; #pragma unroll
;     for (int rb = 0; rb < 8; ++rb) { red[((id.w * 8 + rb) * 2 + 0) * 64 + lane] = part[rb][0]; red[((id.w * 8 + rb) * 2 + 1) * 64 + lane] = part[rb][1]; }
;     asm volatile("s_waitcnt lgkmcnt(0)" ::: "memory"); __syncthreads();
.LBB0_863:
	v_lshl_add_u64 v[106:107], v[72:73], 0, s[8:9]
	v_add_co_u32_e64 v92, s[0:1], s10, v106
	v_lshl_add_u64 v[88:89], v[74:75], 0, s[8:9]
	s_nop 1
	v_addc_co_u32_e64 v93, s[0:1], 0, v107, s[0:1]
	v_add_co_u32_e64 v102, s[0:1], s11, v106
	s_add_u32 s8, s8, 64
	s_nop 1
	v_addc_co_u32_e64 v103, s[0:1], 0, v107, s[0:1]
	v_add_co_u32_e64 v90, s[0:1], s18, v88
	s_addc_u32 s9, s9, 0
	s_nop 1
	v_addc_co_u32_e64 v91, s[0:1], 0, v89, s[0:1]
	v_add_co_u32_e64 v98, s[0:1], s19, v88
	s_cmpk_lg_i32 s8, 0x100
	s_nop 1
	v_addc_co_u32_e64 v99, s[0:1], 0, v89, s[0:1]
	global_load_dwordx4 v[88:91], v[90:91], off
	global_load_dwordx4 v[92:95], v[92:93], off
	global_load_dwordx4 v[98:101], v[98:99], off
	global_load_dwordx4 v[102:105], v[102:103], off
	v_add_co_u32_e64 v108, s[0:1], s12, v106
	s_nop 1
	v_addc_co_u32_e64 v109, s[0:1], 0, v107, s[0:1]
	v_add_co_u32_e64 v110, s[0:1], s13, v106
	s_nop 1
	v_addc_co_u32_e64 v111, s[0:1], 0, v107, s[0:1]
	global_load_dwordx4 v[180:183], v[108:109], off
	global_load_dwordx4 v[184:187], v[110:111], off
	v_add_co_u32_e64 v108, s[0:1], s14, v106
	s_nop 1
	v_addc_co_u32_e64 v109, s[0:1], 0, v107, s[0:1]
	v_add_co_u32_e64 v110, s[0:1], s15, v106
	s_nop 1
	v_addc_co_u32_e64 v111, s[0:1], 0, v107, s[0:1]
	global_load_dwordx4 v[188:191], v[108:109], off
	global_load_dwordx4 v[206:209], v[110:111], off
	v_add_co_u32_e64 v108, s[0:1], s16, v106
	s_nop 1
	v_addc_co_u32_e64 v109, s[0:1], 0, v107, s[0:1]
	v_add_co_u32_e64 v106, s[0:1], s17, v106
	s_nop 1
	v_addc_co_u32_e64 v107, s[0:1], 0, v107, s[0:1]
	global_load_dwordx4 v[210:213], v[108:109], off
	global_load_dwordx4 v[214:217], v[106:107], off
	s_waitcnt vmcnt(0) lgkmcnt(0)
	v_mfma_f32_16x16x32_bf16 v[36:39], v[88:91], v[92:95], v[36:39]
	v_mfma_f32_16x16x32_bf16 v[24:27], v[98:101], v[92:95], v[24:27]
	v_mfma_f32_16x16x32_bf16 v[20:23], v[88:91], v[102:105], v[20:23]
	v_mfma_f32_16x16x32_bf16 v[16:19], v[98:101], v[102:105], v[16:19]
	v_mfma_f32_16x16x32_bf16 v[12:15], v[88:91], v[180:183], v[12:15]
	v_mfma_f32_16x16x32_bf16 v[8:11], v[98:101], v[180:183], v[8:11]
	v_mfma_f32_16x16x32_bf16 v[4:7], v[88:91], v[184:187], v[4:7]
	v_mfma_f32_16x16x32_bf16 v[0:3], v[98:101], v[184:187], v[0:3]
	v_mfma_f32_16x16x32_bf16 v[28:31], v[88:91], v[188:191], v[28:31]
	v_mfma_f32_16x16x32_bf16 v[32:35], v[98:101], v[188:191], v[32:35]
	v_mfma_f32_16x16x32_bf16 v[40:43], v[88:91], v[206:209], v[40:43]
	v_mfma_f32_16x16x32_bf16 v[44:47], v[98:101], v[206:209], v[44:47]
	v_mfma_f32_16x16x32_bf16 v[48:51], v[88:91], v[210:213], v[48:51]
	v_mfma_f32_16x16x32_bf16 v[52:55], v[98:101], v[210:213], v[52:55]
	v_mfma_f32_16x16x32_bf16 v[56:59], v[88:91], v[214:217], v[56:59]
	v_mfma_f32_16x16x32_bf16 v[60:63], v[98:101], v[214:217], v[60:63]
	s_cbranch_scc1 .LBB0_863
	ds_write_b128 v76, v[36:39]
	ds_write_b128 v76, v[24:27] offset:1024
	ds_write_b128 v76, v[20:23] offset:2048
	ds_write_b128 v76, v[16:19] offset:3072
	ds_write_b128 v76, v[12:15] offset:4096
	ds_write_b128 v76, v[8:11] offset:5120
	ds_write_b128 v76, v[4:7] offset:6144
	ds_write_b128 v76, v[0:3] offset:7168
	ds_write_b128 v76, v[28:31] offset:8192
	ds_write_b128 v76, v[32:35] offset:9216
	ds_write_b128 v76, v[40:43] offset:10240
	ds_write_b128 v76, v[44:47] offset:11264
	ds_write_b128 v76, v[48:51] offset:12288
	ds_write_b128 v76, v[52:55] offset:13312
	ds_write_b128 v76, v[56:59] offset:14336
	ds_write_b128 v76, v[60:63] offset:15360
	s_waitcnt lgkmcnt(0)
	s_waitcnt lgkmcnt(0)
	s_barrier
; __device__ __forceinline__ unsigned cvt_pk_bf16(float lo, float hi) { unsigned r; asm volatile("v_cvt_pk_bf16_f32 %0, %1, %2" : "=v"(r) : "v"(lo), "v"(hi)); return r; }
; template <int KSTEPS  >
; __device__ __forceinline__ void small_mma_ksplit(f32x4 (&acc)[2], const bf16_t* A, int lda, const bf16_t* Bt, int ldb, int n0, LAS unsigned char* lds, const SmallId& id) {
;     ...
;     for (int w2 = 0; w2 < 8; ++w2) { acc[0] += red[((w2 * 8 + id.w) * 2 + 0) * 64 + lane]; acc[1] += red[((w2 * 8 + id.w) * 2 + 1) * 64 + lane]; }
;     asm volatile("s_waitcnt lgkmcnt(0)" ::: "memory"); __syncthreads();
; template <bool RES_F32, bool OUT_F32, int KSTEPS>
; __device__ __forceinline__ void small_res(const Params& p, LAS unsigned char* lds, const bf16_t* A, int lda, const bf16_t* Bt, int K, float* ssq_next, int G, int bx) {
;     ...
; #pragma unroll
;         for (int nb = 0; nb < 2; ++nb) { const int col = n0 + 16 * nb + 4 * id.fq;
;             f32x4 r;
;             if (RES_F32) r = *(const f32x4*)(p.xs + (size_t)(id.row - MP) * DM + col);
;             else { const u32x2 w = *(const u32x2*)(XB + (size_t)id.row * DM + col); r = (f32x4){bf_lo(w.x), bf_hi(w.x), bf_lo(w.y), bf_hi(w.y)}; }
;             const f32x4 x = r + acc[nb];
;             if (OUT_F32) *(f32x4*)(p.out + (size_t)id.row * DM + col) = x;
;             else { u32x2 w; w.x = cvt_pk_bf16(x[0], x[1]); w.y = cvt_pk_bf16(x[2], x[3]); *(u32x2*)(XB + (size_t)id.row * DM + col) = w; }
;             s += (x[0] * x[0] + x[1] * x[1]) + (x[2] * x[2] + x[3] * x[3]); }
;         if (!OUT_F32) { s += __shfl_xor(s, 16); s += __shfl_xor(s, 32); if (id.fq == 0) atomicAdd(ssq_next + id.row, s); }
	ds_read_b128 v[0:3], v77
	s_waitcnt lgkmcnt(0)
	v_pk_add_f32 v[4:5], v[2:3], 0 op_sel_hi:[1,0]
	v_pk_add_f32 v[6:7], v[0:1], 0 op_sel_hi:[1,0]
	ds_read_b128 v[0:3], v77 offset:1024
	s_waitcnt lgkmcnt(0)
	v_pk_add_f32 v[8:9], v[2:3], 0 op_sel_hi:[1,0]
	v_pk_add_f32 v[10:11], v[0:1], 0 op_sel_hi:[1,0]
	ds_read_b128 v[0:3], v77 offset:16384
	s_waitcnt lgkmcnt(0)
	v_pk_add_f32 v[4:5], v[4:5], v[2:3]
	v_pk_add_f32 v[6:7], v[6:7], v[0:1]
	ds_read_b128 v[0:3], v77 offset:17408
	s_waitcnt lgkmcnt(0)
	v_pk_add_f32 v[8:9], v[8:9], v[2:3]
	v_pk_add_f32 v[10:11], v[10:11], v[0:1]
	ds_read_b128 v[0:3], v77 offset:32768
	s_waitcnt lgkmcnt(0)
	v_pk_add_f32 v[4:5], v[4:5], v[2:3]
	v_pk_add_f32 v[6:7], v[6:7], v[0:1]
	ds_read_b128 v[0:3], v77 offset:33792
	s_waitcnt lgkmcnt(0)
	v_pk_add_f32 v[8:9], v[8:9], v[2:3]
	v_pk_add_f32 v[10:11], v[10:11], v[0:1]
	ds_read_b128 v[0:3], v77 offset:49152
	s_waitcnt lgkmcnt(0)
	v_pk_add_f32 v[4:5], v[4:5], v[2:3]
	v_pk_add_f32 v[6:7], v[6:7], v[0:1]
	ds_read_b128 v[0:3], v77 offset:50176
	s_waitcnt lgkmcnt(0)
	v_pk_add_f32 v[8:9], v[8:9], v[2:3]
	v_pk_add_f32 v[10:11], v[10:11], v[0:1]
	ds_read_b128 v[0:3], v78
	s_waitcnt lgkmcnt(0)
	v_pk_add_f32 v[4:5], v[4:5], v[2:3]
	v_pk_add_f32 v[6:7], v[6:7], v[0:1]
	ds_read_b128 v[0:3], v79
	s_waitcnt lgkmcnt(0)
	v_pk_add_f32 v[8:9], v[8:9], v[2:3]
	v_pk_add_f32 v[10:11], v[10:11], v[0:1]
	ds_read_b128 v[0:3], v80
	s_waitcnt lgkmcnt(0)
	v_pk_add_f32 v[4:5], v[4:5], v[2:3]
	v_pk_add_f32 v[6:7], v[6:7], v[0:1]
	ds_read_b128 v[0:3], v81
	s_waitcnt lgkmcnt(0)
	v_pk_add_f32 v[8:9], v[8:9], v[2:3]
	v_pk_add_f32 v[10:11], v[10:11], v[0:1]
	ds_read_b128 v[0:3], v82
	s_waitcnt lgkmcnt(0)
	v_pk_add_f32 v[4:5], v[4:5], v[2:3]
	v_pk_add_f32 v[6:7], v[6:7], v[0:1]
	ds_read_b128 v[0:3], v83
	s_waitcnt lgkmcnt(0)
	v_pk_add_f32 v[8:9], v[8:9], v[2:3]
	v_pk_add_f32 v[10:11], v[10:11], v[0:1]
	ds_read_b128 v[0:3], v84
	s_waitcnt lgkmcnt(0)
	v_pk_add_f32 v[4:5], v[4:5], v[2:3]
	v_pk_add_f32 v[6:7], v[6:7], v[0:1]
	ds_read_b128 v[0:3], v85
	s_waitcnt lgkmcnt(0)
	s_waitcnt lgkmcnt(0)
	s_barrier
	v_pk_add_f32 v[2:3], v[8:9], v[2:3]
	v_lshl_or_b32 v8, s7, 5, v86
	v_ashrrev_i32_e32 v9, 31, v8
	v_lshl_add_u64 v[8:9], v[8:9], 1, v[64:65]
	v_pk_add_f32 v[0:1], v[10:11], v[0:1]
	global_load_dwordx2 v[10:11], v[8:9], off
	s_waitcnt vmcnt(0) lgkmcnt(0)
	v_lshlrev_b32_e32 v12, 16, v10
	v_and_b32_e32 v13, 0xffff0000, v10
	v_lshlrev_b32_e32 v10, 16, v11
	v_and_b32_e32 v11, 0xffff0000, v11
	v_pk_add_f32 v[4:5], v[4:5], v[10:11]
	v_pk_add_f32 v[6:7], v[6:7], v[12:13]
	s_nop 0
	v_cvt_pk_bf16_f32 v10, v6, v7
	v_cvt_pk_bf16_f32 v11, v4, v5
	v_mul_f32_e32 v7, v7, v7
	v_mul_f32_e32 v5, v5, v5
	v_fmac_f32_e32 v7, v6, v6
	v_fmac_f32_e32 v5, v4, v4
	global_store_dwordx2 v[8:9], v[10:11], off
	v_add_f32_e32 v10, v7, v5
	global_load_dwordx2 v[4:5], v[8:9], off offset:32
	s_waitcnt vmcnt(0) lgkmcnt(0)
	v_lshlrev_b32_e32 v6, 16, v4
	v_and_b32_e32 v7, 0xffff0000, v4
	v_lshlrev_b32_e32 v4, 16, v5
	v_and_b32_e32 v5, 0xffff0000, v5
	v_pk_add_f32 v[0:1], v[0:1], v[6:7]
	v_pk_add_f32 v[2:3], v[2:3], v[4:5]
	v_cvt_pk_bf16_f32 v4, v0, v1
	v_mul_f32_e32 v1, v1, v1
	v_fmac_f32_e32 v1, v0, v0
	v_mul_f32_e32 v0, v3, v3
	v_cvt_pk_bf16_f32 v5, v2, v3
	v_fmac_f32_e32 v0, v2, v2
	v_and_b32_e32 v2, 64, v225
	v_add_f32_e32 v0, v1, v0
	v_xor_b32_e32 v1, 16, v225
	v_add_u32_e32 v2, 64, v2
	v_cmp_lt_i32_e64 s[0:1], v1, v2
	v_add_f32_e32 v0, v10, v0
	global_store_dwordx2 v[8:9], v[4:5], off offset:32
	v_cndmask_b32_e64 v1, v225, v1, s[0:1]
	v_lshlrev_b32_e32 v1, 2, v1
	ds_bpermute_b32 v1, v1, v0
	s_waitcnt lgkmcnt(0)
	v_add_f32_e32 v0, v0, v1
	v_xor_b32_e32 v1, 32, v225
	v_cmp_lt_i32_e64 s[0:1], v1, v2
	s_nop 1
	v_cndmask_b32_e64 v1, v225, v1, s[0:1]
	v_lshlrev_b32_e32 v1, 2, v1
	ds_bpermute_b32 v1, v1, v0
	s_and_saveexec_b64 s[0:1], vcc
	s_cbranch_execz .LBB0_861
	s_waitcnt lgkmcnt(0)
	v_add_f32_e32 v0, v0, v1
	global_atomic_add_f32 v[66:67], v0, off
	s_branch .LBB0_861

;     __device__ __forceinline__ void operator()(AccT& acc, const Unit& u, int wr, int wc, int fr, int fq) const {
;     ...
;             u32x4 rb[2][4][2];
; #pragma unroll
;             for (int ai = 0; ai < 2; ++ai)
; #pragma unroll
;                 for (int m = 0; m < 4; ++m)
; #pragma unroll
;                     for (int bj = 0; bj < 2; ++bj) rb[ai][m][bj] = __builtin_nontemporal_load((const u32x4*)((const char*)XB + (unsigned)(((u.pm * 256 + ai * 128 + wr * 64 + m * 16 + fr) * DM + col0 + bj * 128) * 2)));
; #pragma unroll
;             for (int ai = 0; ai < 2; ++ai)
; #pragma unroll
;                 for (int m = 0; m < 4; ++m) {
;                     const int row = u.pm * 256 + ai * 128 + wr * 64 + m * 16 + fr; float s = 0.f;
; #pragma unroll
;                     for (int bj = 0; bj < 2; ++bj) { const u32x4 w = rb[ai][m][bj];
;                         finish((f32x4){bf_lo(w.x), bf_hi(w.x), bf_lo(w.y), bf_hi(w.y)} + acc[ai][bj][m][0], (f32x4){bf_lo(w.z), bf_hi(w.z), bf_lo(w.w), bf_hi(w.w)} + acc[ai][bj][m][1], row, col0 + bj * 128, s); }
;                     if (!OUT_F32) { s += __shfl_xor(s, 16); s += __shfl_xor(s, 32); if (fq == 0) atomicAdd(ssq_next + row, s); }
.LBB0_882:
	s_lshl_b32 s0, s48, 8
	v_mov_b32_e32 v96, v230
	v_mov_b32_e32 v219, v229
	s_or_b32 s0, s0, s37
	s_nop 0
	v_lshl_add_u32 v218, v219, 3, s0
	s_lshl_b32 s0, s45, 8
	s_add_i32 s0, s0, s33
	v_add_u32_e32 v220, s0, v96
	v_lshlrev_b32_e32 v96, 11, v220
	v_lshl_add_u32 v96, v218, 1, v96
	v_lshl_add_u64 v[118:119], s[90:91], 0, v[96:97]
	global_load_dwordx4 v[190:193], v[118:119], off nt
	v_add_u32_e32 v118, 0x100, v96
	v_mov_b32_e32 v119, v97
	v_lshl_add_u64 v[118:119], s[90:91], 0, v[118:119]
	global_load_dwordx4 v[186:189], v[118:119], off nt
	v_add_u32_e32 v118, 0x8000, v96
	v_mov_b32_e32 v119, v97
	v_lshl_add_u64 v[118:119], s[90:91], 0, v[118:119]
	global_load_dwordx4 v[182:185], v[118:119], off nt
	v_add_u32_e32 v118, 0x8100, v96
	v_mov_b32_e32 v119, v97
	v_lshl_add_u64 v[118:119], s[90:91], 0, v[118:119]
	global_load_dwordx4 v[178:181], v[118:119], off nt
	v_add_u32_e32 v118, 0x10000, v96
	v_mov_b32_e32 v119, v97
	v_lshl_add_u64 v[118:119], s[90:91], 0, v[118:119]
	global_load_dwordx4 v[174:177], v[118:119], off nt
	v_add_u32_e32 v118, 0x10100, v96
	v_mov_b32_e32 v119, v97
	v_lshl_add_u64 v[118:119], s[90:91], 0, v[118:119]
	global_load_dwordx4 v[170:173], v[118:119], off nt
	v_add_u32_e32 v118, 0x18000, v96
	v_mov_b32_e32 v119, v97
	v_lshl_add_u64 v[118:119], s[90:91], 0, v[118:119]
	global_load_dwordx4 v[166:169], v[118:119], off nt
	v_add_u32_e32 v118, 0x18100, v96
	v_mov_b32_e32 v119, v97
	v_lshl_add_u64 v[118:119], s[90:91], 0, v[118:119]
	global_load_dwordx4 v[162:165], v[118:119], off nt
	v_add_u32_e32 v118, 0x40000, v96
	v_mov_b32_e32 v119, v97
	v_lshl_add_u64 v[118:119], s[90:91], 0, v[118:119]
	global_load_dwordx4 v[158:161], v[118:119], off nt
	v_add_u32_e32 v118, 0x40100, v96
	v_mov_b32_e32 v119, v97
	v_lshl_add_u64 v[118:119], s[90:91], 0, v[118:119]
	global_load_dwordx4 v[154:157], v[118:119], off nt
	v_add_u32_e32 v118, 0x48000, v96
	v_mov_b32_e32 v119, v97
	v_lshl_add_u64 v[118:119], s[90:91], 0, v[118:119]
	global_load_dwordx4 v[150:153], v[118:119], off nt
	v_add_u32_e32 v118, 0x48100, v96
	v_mov_b32_e32 v119, v97
	v_lshl_add_u64 v[118:119], s[90:91], 0, v[118:119]
	global_load_dwordx4 v[146:149], v[118:119], off nt
	v_add_u32_e32 v118, 0x50000, v96
	v_mov_b32_e32 v119, v97
	v_lshl_add_u64 v[118:119], s[90:91], 0, v[118:119]
	global_load_dwordx4 v[134:137], v[118:119], off nt
	v_add_u32_e32 v118, 0x50100, v96
	v_mov_b32_e32 v119, v97
	v_lshl_add_u64 v[118:119], s[90:91], 0, v[118:119]
	global_load_dwordx4 v[126:129], v[118:119], off nt
	v_add_u32_e32 v118, 0x58000, v96
	v_mov_b32_e32 v119, v97
	v_add_u32_e32 v96, 0x58100, v96
	v_lshl_add_u64 v[118:119], s[90:91], 0, v[118:119]
	v_lshl_add_u64 v[138:139], s[90:91], 0, v[96:97]
	global_load_dwordx4 v[118:121], v[118:119], off nt
	v_ashrrev_i32_e32 v221, 31, v220
	global_load_dwordx4 v[138:141], v[138:139], off nt
	v_lshlrev_b64 v[234:235], 11, v[220:221]
	v_cmp_eq_u32_e32 vcc, 0, v219
	v_lshl_add_u64 v[234:235], s[90:91], 0, v[234:235]
	v_ashrrev_i32_e32 v219, 31, v218
	v_lshl_add_u64 v[234:235], v[218:219], 1, v[234:235]
	s_waitcnt vmcnt(0) lgkmcnt(0)
	v_lshlrev_b32_e32 v236, 16, v190
	v_and_b32_e32 v237, 0xffff0000, v190
	v_lshlrev_b32_e32 v190, 16, v191
	v_and_b32_e32 v191, 0xffff0000, v191
	v_pk_add_f32 v[144:145], v[144:145], v[190:191]
	v_lshlrev_b32_e32 v190, 16, v192
	v_and_b32_e32 v191, 0xffff0000, v192
	v_pk_add_f32 v[142:143], v[142:143], v[236:237]
	v_lshlrev_b32_e32 v192, 16, v193
	v_and_b32_e32 v193, 0xffff0000, v193
	v_pk_add_f32 v[190:191], v[130:131], v[190:191]
	v_cvt_pk_bf16_f32 v130, v142, v143
	v_pk_add_f32 v[192:193], v[132:133], v[192:193]
	v_cvt_pk_bf16_f32 v131, v144, v145
	v_cvt_pk_bf16_f32 v132, v190, v191
	v_mul_f32_e32 v96, v143, v143
	v_cvt_pk_bf16_f32 v133, v192, v193
	global_store_dwordx4 v[234:235], v[130:133], off
	v_fmac_f32_e32 v96, v142, v142
	s_nop 0
	v_mul_f32_e32 v130, v145, v145
	v_fmac_f32_e32 v130, v144, v144
	v_add_f32_e32 v96, v96, v130
	v_mul_f32_e32 v130, v191, v191
	v_fmac_f32_e32 v130, v190, v190
	v_add_f32_e32 v96, v130, v96
	v_mul_f32_e32 v130, v193, v193
	v_fmac_f32_e32 v130, v192, v192
	v_add_f32_e32 v96, v130, v96
	v_lshlrev_b32_e32 v130, 16, v186
	v_and_b32_e32 v131, 0xffff0000, v186
	v_lshlrev_b32_e32 v132, 16, v187
	v_and_b32_e32 v133, 0xffff0000, v187
	v_pk_add_f32 v[122:123], v[122:123], v[130:131]
	v_lshlrev_b32_e32 v130, 16, v188
	v_and_b32_e32 v131, 0xffff0000, v188
	v_pk_add_f32 v[124:125], v[124:125], v[132:133]
	v_lshlrev_b32_e32 v132, 16, v189
	v_and_b32_e32 v133, 0xffff0000, v189
	v_pk_add_f32 v[130:131], v[114:115], v[130:131]
	v_cvt_pk_bf16_f32 v114, v122, v123
	v_cvt_pk_bf16_f32 v115, v124, v125
	v_pk_add_f32 v[132:133], v[116:117], v[132:133]
	v_cvt_pk_bf16_f32 v116, v130, v131
	s_nop 0
	v_cvt_pk_bf16_f32 v117, v132, v133
	global_store_dwordx4 v[234:235], v[114:117], off offset:256
	s_nop 1
	v_mul_f32_e32 v114, v123, v123
	v_mul_f32_e32 v115, v125, v125
	v_fmac_f32_e32 v114, v122, v122
	v_fmac_f32_e32 v115, v124, v124
	v_add_f32_e32 v114, v114, v115
	v_mul_f32_e32 v115, v131, v131
	v_fmac_f32_e32 v115, v130, v130
	v_add_f32_e32 v114, v115, v114
	v_mul_f32_e32 v115, v133, v133
	v_fmac_f32_e32 v115, v132, v132
	v_add_f32_e32 v114, v115, v114
	v_and_b32_e32 v115, 64, v225
	v_add_f32_e32 v114, v96, v114
	v_xor_b32_e32 v96, 16, v225
	v_add_u32_e32 v115, 64, v115
	v_cmp_lt_i32_e64 s[0:1], v96, v115
	s_nop 1
	v_cndmask_b32_e64 v96, v225, v96, s[0:1]
	v_lshlrev_b32_e32 v96, 2, v96
	ds_bpermute_b32 v116, v96, v114
	s_waitcnt lgkmcnt(0)
	v_add_f32_e32 v114, v114, v116
	v_xor_b32_e32 v116, 32, v225
	v_cmp_lt_i32_e64 s[0:1], v116, v115
	s_nop 1
	v_cndmask_b32_e64 v115, v225, v116, s[0:1]
	v_lshlrev_b32_e32 v116, 2, v115
	ds_bpermute_b32 v115, v116, v114
	s_and_saveexec_b64 s[0:1], vcc
	s_cbranch_execz .LBB0_884
	v_lshl_add_u64 v[122:123], v[220:221], 2, s[2:3]
	s_waitcnt lgkmcnt(0)
	v_add_f32_e32 v114, v114, v115
	global_atomic_add_f32 v[122:123], v114, off
;     __device__ __forceinline__ void operator()(AccT& acc, const Unit& u, int wr, int wc, int fr, int fq) const {
;     ...
;             u32x4 rb[2][4][2];
; #pragma unroll
;             for (int ai = 0; ai < 2; ++ai)
; #pragma unroll
;                 for (int m = 0; m < 4; ++m)
; #pragma unroll
;                     for (int bj = 0; bj < 2; ++bj) rb[ai][m][bj] = __builtin_nontemporal_load((const u32x4*)((const char*)XB + (unsigned)(((u.pm * 256 + ai * 128 + wr * 64 + m * 16 + fr) * DM + col0 + bj * 128) * 2)));
; #pragma unroll
;             for (int ai = 0; ai < 2; ++ai)
; #pragma unroll
;                 for (int m = 0; m < 4; ++m) {
;                     const int row = u.pm * 256 + ai * 128 + wr * 64 + m * 16 + fr; float s = 0.f;
; #pragma unroll
;                     for (int bj = 0; bj < 2; ++bj) { const u32x4 w = rb[ai][m][bj];
;                         finish((f32x4){bf_lo(w.x), bf_hi(w.x), bf_lo(w.y), bf_hi(w.y)} + acc[ai][bj][m][0], (f32x4){bf_lo(w.z), bf_hi(w.z), bf_lo(w.w), bf_hi(w.w)} + acc[ai][bj][m][1], row, col0 + bj * 128, s); }
;                     if (!OUT_F32) { s += __shfl_xor(s, 16); s += __shfl_xor(s, 32); if (fq == 0) atomicAdd(ssq_next + row, s); }
.LBB0_884:
	s_or_b64 exec, exec, s[0:1]
	v_lshlrev_b32_e32 v124, 16, v182
	v_and_b32_e32 v125, 0xffff0000, v182
	v_lshlrev_b32_e32 v130, 16, v183
	v_and_b32_e32 v131, 0xffff0000, v183
	v_pk_add_f32 v[110:111], v[110:111], v[124:125]
	v_lshlrev_b32_e32 v124, 16, v184
	v_and_b32_e32 v125, 0xffff0000, v184
	v_pk_add_f32 v[112:113], v[112:113], v[130:131]
	v_pk_add_f32 v[124:125], v[106:107], v[124:125]
	v_cvt_pk_bf16_f32 v106, v110, v111
	v_mul_f32_e32 v111, v111, v111
	v_fmac_f32_e32 v111, v110, v110
	v_mul_f32_e32 v110, v113, v113
	v_fmac_f32_e32 v110, v112, v112
	v_lshlrev_b32_e32 v130, 16, v185
	v_and_b32_e32 v131, 0xffff0000, v185
	v_add_f32_e32 v110, v111, v110
	v_mul_f32_e32 v111, v125, v125
	v_pk_add_f32 v[130:131], v[108:109], v[130:131]
	v_fmac_f32_e32 v111, v124, v124
	v_add_f32_e32 v110, v111, v110
	v_mul_f32_e32 v111, v131, v131
	v_fmac_f32_e32 v111, v130, v130
	v_cvt_pk_bf16_f32 v107, v112, v113
	v_add_f32_e32 v117, v111, v110
	v_lshlrev_b32_e32 v110, 16, v178
	v_and_b32_e32 v111, 0xffff0000, v178
	v_lshlrev_b32_e32 v112, 16, v179
	v_and_b32_e32 v113, 0xffff0000, v179
	v_pk_add_f32 v[104:105], v[104:105], v[112:113]
	v_pk_add_f32 v[102:103], v[102:103], v[110:111]
	v_lshlrev_b32_e32 v110, 16, v180
	v_and_b32_e32 v111, 0xffff0000, v180
	v_pk_add_f32 v[110:111], v[98:99], v[110:111]
	v_mul_f32_e32 v98, v103, v103
	v_mul_f32_e32 v99, v105, v105
	v_fmac_f32_e32 v98, v102, v102
	v_fmac_f32_e32 v99, v104, v104
	v_lshlrev_b32_e32 v112, 16, v181
	v_and_b32_e32 v113, 0xffff0000, v181
	v_add_f32_e32 v98, v98, v99
	v_mul_f32_e32 v99, v111, v111
	v_pk_add_f32 v[112:113], v[100:101], v[112:113]
	v_fmac_f32_e32 v99, v110, v110
	v_add_f32_e32 v98, v99, v98
	v_mul_f32_e32 v99, v113, v113
	v_fmac_f32_e32 v99, v112, v112
	v_add_f32_e32 v98, v99, v98
	v_add_f32_e32 v101, v117, v98
	ds_bpermute_b32 v117, v96, v101
	v_add_u32_e32 v114, 16, v220
	s_waitcnt lgkmcnt(0)
	v_ashrrev_i32_e32 v115, 31, v114
	v_lshlrev_b64 v[122:123], 11, v[114:115]
	v_lshl_add_u64 v[98:99], s[90:91], 0, v[122:123]
	v_lshl_add_u64 v[122:123], v[218:219], 1, v[98:99]
	v_add_f32_e32 v98, v101, v117
	ds_bpermute_b32 v99, v116, v98
	v_cvt_pk_bf16_f32 v108, v124, v125
	v_cvt_pk_bf16_f32 v109, v130, v131
	global_store_dwordx4 v[122:123], v[106:109], off
	v_cvt_pk_bf16_f32 v100, v102, v103
	v_cvt_pk_bf16_f32 v101, v104, v105
	v_cvt_pk_bf16_f32 v102, v110, v111
	v_cvt_pk_bf16_f32 v103, v112, v113
	global_store_dwordx4 v[122:123], v[100:103], off offset:256
	s_and_saveexec_b64 s[0:1], vcc
	s_cbranch_execz .LBB0_886
	v_lshl_add_u64 v[100:101], v[114:115], 2, s[2:3]
	s_waitcnt lgkmcnt(0)
	v_add_f32_e32 v98, v98, v99
	global_atomic_add_f32 v[100:101], v98, off
.LBB0_886:
	s_or_b64 exec, exec, s[0:1]
	v_lshlrev_b32_e32 v102, 16, v174
	v_and_b32_e32 v103, 0xffff0000, v174
	v_lshlrev_b32_e32 v104, 16, v175
	v_and_b32_e32 v105, 0xffff0000, v175
	v_pk_add_f32 v[92:93], v[92:93], v[102:103]
	v_lshlrev_b32_e32 v102, 16, v176
	v_and_b32_e32 v103, 0xffff0000, v176
	v_pk_add_f32 v[94:95], v[94:95], v[104:105]
	v_pk_add_f32 v[102:103], v[88:89], v[102:103]
	v_cvt_pk_bf16_f32 v88, v92, v93
	v_mul_f32_e32 v93, v93, v93
	v_fmac_f32_e32 v93, v92, v92
	v_mul_f32_e32 v92, v95, v95
	v_fmac_f32_e32 v92, v94, v94
	v_lshlrev_b32_e32 v104, 16, v177
	v_and_b32_e32 v105, 0xffff0000, v177
	v_add_f32_e32 v92, v93, v92
	v_mul_f32_e32 v93, v103, v103
	v_pk_add_f32 v[104:105], v[90:91], v[104:105]
	v_fmac_f32_e32 v93, v102, v102
	v_add_f32_e32 v92, v93, v92
	v_mul_f32_e32 v93, v105, v105
	v_fmac_f32_e32 v93, v104, v104
	v_cvt_pk_bf16_f32 v89, v94, v95
	v_cvt_pk_bf16_f32 v90, v102, v103
	v_add_f32_e32 v102, v93, v92
	v_lshlrev_b32_e32 v92, 16, v170
	v_and_b32_e32 v93, 0xffff0000, v170
	v_lshlrev_b32_e32 v94, 16, v171
	v_and_b32_e32 v95, 0xffff0000, v171
	v_pk_add_f32 v[86:87], v[86:87], v[94:95]
	v_pk_add_f32 v[84:85], v[84:85], v[92:93]
	v_lshlrev_b32_e32 v92, 16, v172
	v_and_b32_e32 v93, 0xffff0000, v172
	v_pk_add_f32 v[92:93], v[80:81], v[92:93]
	v_mul_f32_e32 v80, v85, v85
	v_mul_f32_e32 v81, v87, v87
	v_fmac_f32_e32 v80, v84, v84
	v_fmac_f32_e32 v81, v86, v86
	v_lshlrev_b32_e32 v94, 16, v173
	v_and_b32_e32 v95, 0xffff0000, v173
	v_add_f32_e32 v80, v80, v81
	v_mul_f32_e32 v81, v93, v93
	v_pk_add_f32 v[94:95], v[82:83], v[94:95]
	v_fmac_f32_e32 v81, v92, v92
	v_add_f32_e32 v80, v81, v80
	v_mul_f32_e32 v81, v95, v95
	v_fmac_f32_e32 v81, v94, v94
	v_add_f32_e32 v80, v81, v80
	v_add_f32_e32 v83, v102, v80
	ds_bpermute_b32 v102, v96, v83
	v_add_u32_e32 v98, 32, v220
	s_waitcnt lgkmcnt(0)
	v_ashrrev_i32_e32 v99, 31, v98
	v_lshlrev_b64 v[100:101], 11, v[98:99]
	v_lshl_add_u64 v[80:81], s[90:91], 0, v[100:101]
	v_lshl_add_u64 v[100:101], v[218:219], 1, v[80:81]
	v_add_f32_e32 v80, v83, v102
	ds_bpermute_b32 v81, v116, v80
	v_cvt_pk_bf16_f32 v91, v104, v105
	global_store_dwordx4 v[100:101], v[88:91], off
	v_cvt_pk_bf16_f32 v82, v84, v85
	v_cvt_pk_bf16_f32 v83, v86, v87
	v_cvt_pk_bf16_f32 v84, v92, v93
	v_cvt_pk_bf16_f32 v85, v94, v95
	global_store_dwordx4 v[100:101], v[82:85], off offset:256
	s_and_saveexec_b64 s[0:1], vcc
	s_cbranch_execz .LBB0_888
	v_lshl_add_u64 v[82:83], v[98:99], 2, s[2:3]
	s_waitcnt lgkmcnt(0)
	v_add_f32_e32 v80, v80, v81
	global_atomic_add_f32 v[82:83], v80, off
;     __device__ __forceinline__ void operator()(AccT& acc, const Unit& u, int wr, int wc, int fr, int fq) const {
;     ...
;             u32x4 rb[2][4][2];
; #pragma unroll
;             for (int ai = 0; ai < 2; ++ai)
; #pragma unroll
;                 for (int m = 0; m < 4; ++m)
; #pragma unroll
;                     for (int bj = 0; bj < 2; ++bj) rb[ai][m][bj] = __builtin_nontemporal_load((const u32x4*)((const char*)XB + (unsigned)(((u.pm * 256 + ai * 128 + wr * 64 + m * 16 + fr) * DM + col0 + bj * 128) * 2)));
; #pragma unroll
;             for (int ai = 0; ai < 2; ++ai)
; #pragma unroll
;                 for (int m = 0; m < 4; ++m) {
;                     const int row = u.pm * 256 + ai * 128 + wr * 64 + m * 16 + fr; float s = 0.f;
; #pragma unroll
;                     for (int bj = 0; bj < 2; ++bj) { const u32x4 w = rb[ai][m][bj];
;                         finish((f32x4){bf_lo(w.x), bf_hi(w.x), bf_lo(w.y), bf_hi(w.y)} + acc[ai][bj][m][0], (f32x4){bf_lo(w.z), bf_hi(w.z), bf_lo(w.w), bf_hi(w.w)} + acc[ai][bj][m][1], row, col0 + bj * 128, s); }
;                     if (!OUT_F32) { s += __shfl_xor(s, 16); s += __shfl_xor(s, 32); if (fq == 0) atomicAdd(ssq_next + row, s); }
.LBB0_888:
	s_or_b64 exec, exec, s[0:1]
	v_lshlrev_b32_e32 v84, 16, v166
	v_and_b32_e32 v85, 0xffff0000, v166
	v_lshlrev_b32_e32 v86, 16, v167
	v_and_b32_e32 v87, 0xffff0000, v167
	v_pk_add_f32 v[76:77], v[76:77], v[84:85]
	v_lshlrev_b32_e32 v84, 16, v168
	v_and_b32_e32 v85, 0xffff0000, v168
	v_pk_add_f32 v[78:79], v[78:79], v[86:87]
	v_pk_add_f32 v[84:85], v[72:73], v[84:85]
	v_cvt_pk_bf16_f32 v72, v76, v77
	v_mul_f32_e32 v77, v77, v77
	v_fmac_f32_e32 v77, v76, v76
	v_mul_f32_e32 v76, v79, v79
	v_fmac_f32_e32 v76, v78, v78
	v_lshlrev_b32_e32 v86, 16, v169
	v_and_b32_e32 v87, 0xffff0000, v169
	v_add_f32_e32 v76, v77, v76
	v_mul_f32_e32 v77, v85, v85
	v_pk_add_f32 v[86:87], v[74:75], v[86:87]
	v_fmac_f32_e32 v77, v84, v84
	v_add_f32_e32 v76, v77, v76
	v_mul_f32_e32 v77, v87, v87
	v_fmac_f32_e32 v77, v86, v86
	v_cvt_pk_bf16_f32 v73, v78, v79
	v_cvt_pk_bf16_f32 v74, v84, v85
	v_add_f32_e32 v84, v77, v76
	v_lshlrev_b32_e32 v76, 16, v162
	v_and_b32_e32 v77, 0xffff0000, v162
	v_lshlrev_b32_e32 v78, 16, v163
	v_and_b32_e32 v79, 0xffff0000, v163
	v_pk_add_f32 v[70:71], v[70:71], v[78:79]
	v_pk_add_f32 v[68:69], v[68:69], v[76:77]
	v_lshlrev_b32_e32 v76, 16, v164
	v_and_b32_e32 v77, 0xffff0000, v164
	v_pk_add_f32 v[76:77], v[64:65], v[76:77]
	v_mul_f32_e32 v64, v69, v69
	v_mul_f32_e32 v65, v71, v71
	v_fmac_f32_e32 v64, v68, v68
	v_fmac_f32_e32 v65, v70, v70
	v_lshlrev_b32_e32 v78, 16, v165
	v_and_b32_e32 v79, 0xffff0000, v165
	v_add_f32_e32 v64, v64, v65
	v_mul_f32_e32 v65, v77, v77
	v_pk_add_f32 v[78:79], v[66:67], v[78:79]
	v_fmac_f32_e32 v65, v76, v76
	v_add_f32_e32 v64, v65, v64
	v_mul_f32_e32 v65, v79, v79
	v_fmac_f32_e32 v65, v78, v78
	v_add_f32_e32 v64, v65, v64
	v_add_f32_e32 v67, v84, v64
	ds_bpermute_b32 v84, v96, v67
	v_add_u32_e32 v80, 48, v220
	s_waitcnt lgkmcnt(0)
	v_ashrrev_i32_e32 v81, 31, v80
	v_lshlrev_b64 v[82:83], 11, v[80:81]
	v_lshl_add_u64 v[64:65], s[90:91], 0, v[82:83]
	v_lshl_add_u64 v[82:83], v[218:219], 1, v[64:65]
	v_add_f32_e32 v64, v67, v84
	ds_bpermute_b32 v65, v116, v64
	v_cvt_pk_bf16_f32 v75, v86, v87
	global_store_dwordx4 v[82:83], v[72:75], off
	v_cvt_pk_bf16_f32 v66, v68, v69
	v_cvt_pk_bf16_f32 v67, v70, v71
	v_cvt_pk_bf16_f32 v68, v76, v77
	v_cvt_pk_bf16_f32 v69, v78, v79
	global_store_dwordx4 v[82:83], v[66:69], off offset:256
	s_and_saveexec_b64 s[0:1], vcc
	s_cbranch_execz .LBB0_890
	v_lshl_add_u64 v[66:67], v[80:81], 2, s[2:3]
	s_waitcnt lgkmcnt(0)
	v_add_f32_e32 v64, v64, v65
	global_atomic_add_f32 v[66:67], v64, off
.LBB0_890:
	s_or_b64 exec, exec, s[0:1]
	v_lshlrev_b32_e32 v68, 16, v158
	v_and_b32_e32 v69, 0xffff0000, v158
	v_lshlrev_b32_e32 v70, 16, v159
	v_and_b32_e32 v71, 0xffff0000, v159
	v_pk_add_f32 v[60:61], v[60:61], v[68:69]
	v_lshlrev_b32_e32 v68, 16, v160
	v_and_b32_e32 v69, 0xffff0000, v160
	v_pk_add_f32 v[62:63], v[62:63], v[70:71]
	v_pk_add_f32 v[68:69], v[56:57], v[68:69]
	v_cvt_pk_bf16_f32 v56, v60, v61
	v_mul_f32_e32 v61, v61, v61
	v_fmac_f32_e32 v61, v60, v60
	v_mul_f32_e32 v60, v63, v63
	v_fmac_f32_e32 v60, v62, v62
	v_lshlrev_b32_e32 v70, 16, v161
	v_and_b32_e32 v71, 0xffff0000, v161
	v_add_f32_e32 v60, v61, v60
	v_mul_f32_e32 v61, v69, v69
	v_pk_add_f32 v[70:71], v[58:59], v[70:71]
	v_fmac_f32_e32 v61, v68, v68
	v_add_f32_e32 v60, v61, v60
	v_mul_f32_e32 v61, v71, v71
	v_fmac_f32_e32 v61, v70, v70
	v_cvt_pk_bf16_f32 v57, v62, v63
	v_cvt_pk_bf16_f32 v58, v68, v69
	v_add_f32_e32 v68, v61, v60
	v_lshlrev_b32_e32 v60, 16, v154
	v_and_b32_e32 v61, 0xffff0000, v154
	v_lshlrev_b32_e32 v62, 16, v155
	v_and_b32_e32 v63, 0xffff0000, v155
	v_pk_add_f32 v[54:55], v[54:55], v[62:63]
	v_pk_add_f32 v[52:53], v[52:53], v[60:61]
	v_lshlrev_b32_e32 v60, 16, v156
	v_and_b32_e32 v61, 0xffff0000, v156
	v_pk_add_f32 v[60:61], v[48:49], v[60:61]
	v_mul_f32_e32 v48, v53, v53
	v_mul_f32_e32 v49, v55, v55
	v_fmac_f32_e32 v48, v52, v52
	v_fmac_f32_e32 v49, v54, v54
	v_lshlrev_b32_e32 v62, 16, v157
	v_and_b32_e32 v63, 0xffff0000, v157
	v_add_f32_e32 v48, v48, v49
	v_mul_f32_e32 v49, v61, v61
	v_pk_add_f32 v[62:63], v[50:51], v[62:63]
	v_fmac_f32_e32 v49, v60, v60
	v_add_f32_e32 v48, v49, v48
	v_mul_f32_e32 v49, v63, v63
	v_fmac_f32_e32 v49, v62, v62
	v_add_f32_e32 v48, v49, v48
	v_add_f32_e32 v51, v68, v48
	ds_bpermute_b32 v68, v96, v51
	v_add_u32_e32 v64, 0x80, v220
	s_waitcnt lgkmcnt(0)
	v_ashrrev_i32_e32 v65, 31, v64
	v_lshlrev_b64 v[66:67], 11, v[64:65]
	v_lshl_add_u64 v[48:49], s[90:91], 0, v[66:67]
	v_lshl_add_u64 v[66:67], v[218:219], 1, v[48:49]
	v_add_f32_e32 v48, v51, v68
	ds_bpermute_b32 v49, v116, v48
	v_cvt_pk_bf16_f32 v59, v70, v71
	global_store_dwordx4 v[66:67], v[56:59], off
	v_cvt_pk_bf16_f32 v50, v52, v53
	v_cvt_pk_bf16_f32 v51, v54, v55
	v_cvt_pk_bf16_f32 v52, v60, v61
	v_cvt_pk_bf16_f32 v53, v62, v63
	global_store_dwordx4 v[66:67], v[50:53], off offset:256
	s_and_saveexec_b64 s[0:1], vcc
	s_cbranch_execz .LBB0_892
	v_lshl_add_u64 v[50:51], v[64:65], 2, s[2:3]
	s_waitcnt lgkmcnt(0)
	v_add_f32_e32 v48, v48, v49
	global_atomic_add_f32 v[50:51], v48, off
;     __device__ __forceinline__ void operator()(AccT& acc, const Unit& u, int wr, int wc, int fr, int fq) const {
;     ...
;             u32x4 rb[2][4][2];
; #pragma unroll
;             for (int ai = 0; ai < 2; ++ai)
; #pragma unroll
;                 for (int m = 0; m < 4; ++m)
; #pragma unroll
;                     for (int bj = 0; bj < 2; ++bj) rb[ai][m][bj] = __builtin_nontemporal_load((const u32x4*)((const char*)XB + (unsigned)(((u.pm * 256 + ai * 128 + wr * 64 + m * 16 + fr) * DM + col0 + bj * 128) * 2)));
; #pragma unroll
;             for (int ai = 0; ai < 2; ++ai)
; #pragma unroll
;                 for (int m = 0; m < 4; ++m) {
;                     const int row = u.pm * 256 + ai * 128 + wr * 64 + m * 16 + fr; float s = 0.f;
; #pragma unroll
;                     for (int bj = 0; bj < 2; ++bj) { const u32x4 w = rb[ai][m][bj];
;                         finish((f32x4){bf_lo(w.x), bf_hi(w.x), bf_lo(w.y), bf_hi(w.y)} + acc[ai][bj][m][0], (f32x4){bf_lo(w.z), bf_hi(w.z), bf_lo(w.w), bf_hi(w.w)} + acc[ai][bj][m][1], row, col0 + bj * 128, s); }
;                     if (!OUT_F32) { s += __shfl_xor(s, 16); s += __shfl_xor(s, 32); if (fq == 0) atomicAdd(ssq_next + row, s); }
.LBB0_892:
	s_or_b64 exec, exec, s[0:1]
	v_lshlrev_b32_e32 v52, 16, v150
	v_and_b32_e32 v53, 0xffff0000, v150
	v_lshlrev_b32_e32 v54, 16, v151
	v_and_b32_e32 v55, 0xffff0000, v151
	v_pk_add_f32 v[44:45], v[44:45], v[52:53]
	v_lshlrev_b32_e32 v52, 16, v152
	v_and_b32_e32 v53, 0xffff0000, v152
	v_pk_add_f32 v[46:47], v[46:47], v[54:55]
	v_pk_add_f32 v[52:53], v[40:41], v[52:53]
	v_cvt_pk_bf16_f32 v40, v44, v45
	v_mul_f32_e32 v45, v45, v45
	v_fmac_f32_e32 v45, v44, v44
	v_mul_f32_e32 v44, v47, v47
	v_fmac_f32_e32 v44, v46, v46
	v_lshlrev_b32_e32 v54, 16, v153
	v_and_b32_e32 v55, 0xffff0000, v153
	v_add_f32_e32 v44, v45, v44
	v_mul_f32_e32 v45, v53, v53
	v_pk_add_f32 v[54:55], v[42:43], v[54:55]
	v_fmac_f32_e32 v45, v52, v52
	v_add_f32_e32 v44, v45, v44
	v_mul_f32_e32 v45, v55, v55
	v_fmac_f32_e32 v45, v54, v54
	v_cvt_pk_bf16_f32 v41, v46, v47
	v_cvt_pk_bf16_f32 v42, v52, v53
	v_add_f32_e32 v52, v45, v44
	v_lshlrev_b32_e32 v44, 16, v146
	v_and_b32_e32 v45, 0xffff0000, v146
	v_lshlrev_b32_e32 v46, 16, v147
	v_and_b32_e32 v47, 0xffff0000, v147
	v_pk_add_f32 v[38:39], v[38:39], v[46:47]
	v_pk_add_f32 v[36:37], v[36:37], v[44:45]
	v_lshlrev_b32_e32 v44, 16, v148
	v_and_b32_e32 v45, 0xffff0000, v148
	v_pk_add_f32 v[44:45], v[32:33], v[44:45]
	v_mul_f32_e32 v32, v37, v37
	v_mul_f32_e32 v33, v39, v39
	v_fmac_f32_e32 v32, v36, v36
	v_fmac_f32_e32 v33, v38, v38
	v_lshlrev_b32_e32 v46, 16, v149
	v_and_b32_e32 v47, 0xffff0000, v149
	v_add_f32_e32 v32, v32, v33
	v_mul_f32_e32 v33, v45, v45
	v_pk_add_f32 v[46:47], v[34:35], v[46:47]
	v_fmac_f32_e32 v33, v44, v44
	v_add_f32_e32 v32, v33, v32
	v_mul_f32_e32 v33, v47, v47
	v_fmac_f32_e32 v33, v46, v46
	v_add_f32_e32 v32, v33, v32
	v_add_f32_e32 v35, v52, v32
	ds_bpermute_b32 v52, v96, v35
	v_add_u32_e32 v48, 0x90, v220
	s_waitcnt lgkmcnt(0)
	v_ashrrev_i32_e32 v49, 31, v48
	v_lshlrev_b64 v[50:51], 11, v[48:49]
	v_lshl_add_u64 v[32:33], s[90:91], 0, v[50:51]
	v_lshl_add_u64 v[50:51], v[218:219], 1, v[32:33]
	v_add_f32_e32 v32, v35, v52
	ds_bpermute_b32 v33, v116, v32
	v_cvt_pk_bf16_f32 v43, v54, v55
	global_store_dwordx4 v[50:51], v[40:43], off
	v_cvt_pk_bf16_f32 v34, v36, v37
	v_cvt_pk_bf16_f32 v35, v38, v39
	v_cvt_pk_bf16_f32 v36, v44, v45
	v_cvt_pk_bf16_f32 v37, v46, v47
	global_store_dwordx4 v[50:51], v[34:37], off offset:256
	s_and_saveexec_b64 s[0:1], vcc
	s_cbranch_execz .LBB0_894
	v_lshl_add_u64 v[34:35], v[48:49], 2, s[2:3]
	s_waitcnt lgkmcnt(0)
	v_add_f32_e32 v32, v32, v33
	global_atomic_add_f32 v[34:35], v32, off
;     __device__ __forceinline__ void operator()(AccT& acc, const Unit& u, int wr, int wc, int fr, int fq) const {
;     ...
;             u32x4 rb[2][4][2];
; #pragma unroll
;             for (int ai = 0; ai < 2; ++ai)
; #pragma unroll
;                 for (int m = 0; m < 4; ++m)
; #pragma unroll
;                     for (int bj = 0; bj < 2; ++bj) rb[ai][m][bj] = __builtin_nontemporal_load((const u32x4*)((const char*)XB + (unsigned)(((u.pm * 256 + ai * 128 + wr * 64 + m * 16 + fr) * DM + col0 + bj * 128) * 2)));
; #pragma unroll
;             for (int ai = 0; ai < 2; ++ai)
; #pragma unroll
;                 for (int m = 0; m < 4; ++m) {
;                     const int row = u.pm * 256 + ai * 128 + wr * 64 + m * 16 + fr; float s = 0.f;
; #pragma unroll
;                     for (int bj = 0; bj < 2; ++bj) { const u32x4 w = rb[ai][m][bj];
;                         finish((f32x4){bf_lo(w.x), bf_hi(w.x), bf_lo(w.y), bf_hi(w.y)} + acc[ai][bj][m][0], (f32x4){bf_lo(w.z), bf_hi(w.z), bf_lo(w.w), bf_hi(w.w)} + acc[ai][bj][m][1], row, col0 + bj * 128, s); }
;                     if (!OUT_F32) { s += __shfl_xor(s, 16); s += __shfl_xor(s, 32); if (fq == 0) atomicAdd(ssq_next + row, s); }
.LBB0_894:
	s_or_b64 exec, exec, s[0:1]
	v_lshlrev_b32_e32 v36, 16, v134
	v_and_b32_e32 v37, 0xffff0000, v134
	v_lshlrev_b32_e32 v38, 16, v135
	v_and_b32_e32 v39, 0xffff0000, v135
	v_pk_add_f32 v[28:29], v[28:29], v[36:37]
	v_lshlrev_b32_e32 v36, 16, v136
	v_and_b32_e32 v37, 0xffff0000, v136
	v_pk_add_f32 v[30:31], v[30:31], v[38:39]
	v_pk_add_f32 v[36:37], v[24:25], v[36:37]
	v_cvt_pk_bf16_f32 v24, v28, v29
	v_mul_f32_e32 v29, v29, v29
	v_fmac_f32_e32 v29, v28, v28
	v_mul_f32_e32 v28, v31, v31
	v_fmac_f32_e32 v28, v30, v30
	v_lshlrev_b32_e32 v38, 16, v137
	v_and_b32_e32 v39, 0xffff0000, v137
	v_add_f32_e32 v28, v29, v28
	v_mul_f32_e32 v29, v37, v37
	v_pk_add_f32 v[38:39], v[26:27], v[38:39]
	v_fmac_f32_e32 v29, v36, v36
	v_add_f32_e32 v28, v29, v28
	v_mul_f32_e32 v29, v39, v39
	v_fmac_f32_e32 v29, v38, v38
	v_cvt_pk_bf16_f32 v25, v30, v31
	v_cvt_pk_bf16_f32 v26, v36, v37
	v_add_f32_e32 v36, v29, v28
	v_lshlrev_b32_e32 v28, 16, v126
	v_and_b32_e32 v29, 0xffff0000, v126
	v_lshlrev_b32_e32 v30, 16, v127
	v_and_b32_e32 v31, 0xffff0000, v127
	v_pk_add_f32 v[22:23], v[22:23], v[30:31]
	v_pk_add_f32 v[20:21], v[20:21], v[28:29]
	v_lshlrev_b32_e32 v28, 16, v128
	v_and_b32_e32 v29, 0xffff0000, v128
	v_pk_add_f32 v[28:29], v[16:17], v[28:29]
	v_mul_f32_e32 v16, v21, v21
	v_mul_f32_e32 v17, v23, v23
	v_fmac_f32_e32 v16, v20, v20
	v_fmac_f32_e32 v17, v22, v22
	v_lshlrev_b32_e32 v30, 16, v129
	v_and_b32_e32 v31, 0xffff0000, v129
	v_add_f32_e32 v16, v16, v17
	v_mul_f32_e32 v17, v29, v29
	v_pk_add_f32 v[30:31], v[18:19], v[30:31]
	v_fmac_f32_e32 v17, v28, v28
	v_add_f32_e32 v16, v17, v16
	v_mul_f32_e32 v17, v31, v31
	v_fmac_f32_e32 v17, v30, v30
	v_add_f32_e32 v16, v17, v16
	v_add_f32_e32 v19, v36, v16
	ds_bpermute_b32 v36, v96, v19
	v_add_u32_e32 v32, 0xa0, v220
	s_waitcnt lgkmcnt(0)
	v_ashrrev_i32_e32 v33, 31, v32
	v_lshlrev_b64 v[34:35], 11, v[32:33]
	v_lshl_add_u64 v[16:17], s[90:91], 0, v[34:35]
	v_lshl_add_u64 v[34:35], v[218:219], 1, v[16:17]
	v_add_f32_e32 v16, v19, v36
	ds_bpermute_b32 v17, v116, v16
	v_cvt_pk_bf16_f32 v27, v38, v39
	global_store_dwordx4 v[34:35], v[24:27], off
	v_cvt_pk_bf16_f32 v18, v20, v21
	v_cvt_pk_bf16_f32 v19, v22, v23
	v_cvt_pk_bf16_f32 v20, v28, v29
	v_cvt_pk_bf16_f32 v21, v30, v31
	global_store_dwordx4 v[34:35], v[18:21], off offset:256
	s_and_saveexec_b64 s[0:1], vcc
	s_cbranch_execz .LBB0_896
	v_lshl_add_u64 v[18:19], v[32:33], 2, s[2:3]
	s_waitcnt lgkmcnt(0)
	v_add_f32_e32 v16, v16, v17
	global_atomic_add_f32 v[18:19], v16, off
.LBB0_896:
	s_or_b64 exec, exec, s[0:1]
	v_lshlrev_b32_e32 v20, 16, v118
	v_and_b32_e32 v21, 0xffff0000, v118
	v_lshlrev_b32_e32 v22, 16, v119
	v_and_b32_e32 v23, 0xffff0000, v119
	v_pk_add_f32 v[12:13], v[12:13], v[20:21]
	v_lshlrev_b32_e32 v20, 16, v120
	v_and_b32_e32 v21, 0xffff0000, v120
	v_pk_add_f32 v[14:15], v[14:15], v[22:23]
	v_pk_add_f32 v[20:21], v[8:9], v[20:21]
	v_cvt_pk_bf16_f32 v8, v12, v13
	v_mul_f32_e32 v13, v13, v13
	v_fmac_f32_e32 v13, v12, v12
	v_mul_f32_e32 v12, v15, v15
	v_fmac_f32_e32 v12, v14, v14
	v_lshlrev_b32_e32 v22, 16, v121
	v_and_b32_e32 v23, 0xffff0000, v121
	v_add_f32_e32 v12, v13, v12
	v_mul_f32_e32 v13, v21, v21
	v_pk_add_f32 v[22:23], v[10:11], v[22:23]
	v_fmac_f32_e32 v13, v20, v20
	v_add_f32_e32 v12, v13, v12
	v_mul_f32_e32 v13, v23, v23
	v_fmac_f32_e32 v13, v22, v22
	v_cvt_pk_bf16_f32 v9, v14, v15
	v_cvt_pk_bf16_f32 v10, v20, v21
	v_add_f32_e32 v20, v13, v12
	v_lshlrev_b32_e32 v12, 16, v138
	v_and_b32_e32 v13, 0xffff0000, v138
	v_lshlrev_b32_e32 v14, 16, v139
	v_and_b32_e32 v15, 0xffff0000, v139
	v_pk_add_f32 v[6:7], v[6:7], v[14:15]
	v_pk_add_f32 v[4:5], v[4:5], v[12:13]
	v_lshlrev_b32_e32 v12, 16, v140
	v_and_b32_e32 v13, 0xffff0000, v140
	v_pk_add_f32 v[12:13], v[0:1], v[12:13]
	v_mul_f32_e32 v0, v5, v5
	v_mul_f32_e32 v1, v7, v7
	v_fmac_f32_e32 v0, v4, v4
	v_fmac_f32_e32 v1, v6, v6
	v_lshlrev_b32_e32 v14, 16, v141
	v_and_b32_e32 v15, 0xffff0000, v141
	v_add_f32_e32 v0, v0, v1
	v_mul_f32_e32 v1, v13, v13
	v_pk_add_f32 v[14:15], v[2:3], v[14:15]
	v_fmac_f32_e32 v1, v12, v12
	v_add_f32_e32 v0, v1, v0
	v_mul_f32_e32 v1, v15, v15
	v_fmac_f32_e32 v1, v14, v14
	v_add_f32_e32 v0, v1, v0
	v_add_f32_e32 v3, v20, v0
	ds_bpermute_b32 v20, v96, v3
	v_add_u32_e32 v16, 0xb0, v220
	s_waitcnt lgkmcnt(0)
	v_ashrrev_i32_e32 v17, 31, v16
	v_lshlrev_b64 v[18:19], 11, v[16:17]
	v_lshl_add_u64 v[0:1], s[90:91], 0, v[18:19]
	v_lshl_add_u64 v[18:19], v[218:219], 1, v[0:1]
	v_add_f32_e32 v0, v3, v20
	ds_bpermute_b32 v1, v116, v0
	v_cvt_pk_bf16_f32 v11, v22, v23
	global_store_dwordx4 v[18:19], v[8:11], off
	v_cvt_pk_bf16_f32 v2, v4, v5
	v_cvt_pk_bf16_f32 v3, v6, v7
	v_cvt_pk_bf16_f32 v4, v12, v13
	v_cvt_pk_bf16_f32 v5, v14, v15
	global_store_dwordx4 v[18:19], v[2:5], off offset:256
	s_and_saveexec_b64 s[0:1], vcc
	s_cbranch_execz .LBB0_898
	v_lshl_add_u64 v[2:3], v[16:17], 2, s[2:3]
	s_waitcnt lgkmcnt(0)
	v_add_f32_e32 v0, v0, v1
	global_atomic_add_f32 v[2:3], v0, off

; #define LAS __attribute__((address_space(3)))
; template <int KSTEPS  >
; __device__ __forceinline__ void small_mma_ksplit(f32x4 (&acc)[2], const bf16_t* A, int lda, const bf16_t* Bt, int ldb, int n0, LAS unsigned char* lds, const SmallId& id) {
;     ...
;     for (int ks = 0; ks < KSTEPS; ++ks) {
;         bf16x8 a[8], b[2];
; #pragma unroll
;         for (int rb = 0; rb < 8; ++rb) a[rb] = *(const bf16x8*)(ap + (size_t)(16 * rb) * lda + 32 * ks);
;         b[0] = *(const bf16x8*)(bp + 32 * ks); b[1] = *(const bf16x8*)(bp + (size_t)16 * ldb + 32 * ks);
; #pragma unroll
;         for (int rb = 0; rb < 8; ++rb) { part[rb][0] = __builtin_amdgcn_mfma_f32_16x16x32_bf16(b[0], a[rb], part[rb][0], 0, 0, 0); part[rb][1] = __builtin_amdgcn_mfma_f32_16x16x32_bf16(b[1], a[rb], part[rb][1], 0, 0, 0); }
;     }
;     LAS f32x4* red = (LAS f32x4*)lds;
; #pragma unroll
;     for (int rb = 0; rb < 8; ++rb) { red[((id.w * 8 + rb) * 2 + 0) * 64 + lane] = part[rb][0]; red[((id.w * 8 + rb) * 2 + 1) * 64 + lane] = part[rb][1]; }
;     asm volatile("s_waitcnt lgkmcnt(0)" ::: "memory"); __syncthreads();
.LBB0_908:
	v_lshl_add_u64 v[94:95], v[74:75], 0, s[8:9]
	v_lshl_add_u64 v[90:91], v[76:77], 0, s[8:9]
	v_add_co_u32_e64 v98, s[0:1], s10, v94
	v_add_co_u32_e64 v92, s[48:49], s18, v90
	v_add_co_u32_e64 v102, s[50:51], s19, v90
	s_nop 1
	v_addc_co_u32_e64 v99, s[0:1], 0, v95, s[0:1]
	s_nop 1
	v_addc_co_u32_e64 v93, s[0:1], 0, v91, s[48:49]
	s_nop 1
	v_addc_co_u32_e64 v103, s[0:1], 0, v91, s[50:51]
	global_load_dwordx4 v[90:93], v[92:93], off
	global_load_dwordx4 v[98:101], v[98:99], off
	v_add_co_u32_e64 v106, s[46:47], s11, v94
	global_load_dwordx4 v[102:105], v[102:103], off
	s_nop 1
	v_addc_co_u32_e64 v107, s[0:1], 0, v95, s[46:47]
	s_add_u32 s8, s8, 64
	s_addc_u32 s9, s9, 0
	s_cmpk_lg_i32 s8, 0x100
	global_load_dwordx4 v[180:183], v[106:107], off
	v_add_co_u32_e64 v106, s[0:1], s12, v94
	s_nop 1
	v_addc_co_u32_e64 v107, s[0:1], 0, v95, s[0:1]
	global_load_dwordx4 v[184:187], v[106:107], off
	v_add_co_u32_e64 v106, s[0:1], s13, v94
	s_nop 1
	v_addc_co_u32_e64 v107, s[0:1], 0, v95, s[0:1]
	global_load_dwordx4 v[188:191], v[106:107], off
	v_add_co_u32_e64 v106, s[0:1], s14, v94
	s_nop 1
	v_addc_co_u32_e64 v107, s[0:1], 0, v95, s[0:1]
	global_load_dwordx4 v[206:209], v[106:107], off
	v_add_co_u32_e64 v106, s[0:1], s15, v94
	s_nop 1
	v_addc_co_u32_e64 v107, s[0:1], 0, v95, s[0:1]
	global_load_dwordx4 v[210:213], v[106:107], off
	v_add_co_u32_e64 v106, s[0:1], s16, v94
	s_nop 1
	v_addc_co_u32_e64 v107, s[0:1], 0, v95, s[0:1]
	v_add_co_u32_e64 v94, s[0:1], s17, v94
	global_load_dwordx4 v[214:217], v[106:107], off
	s_nop 1
	v_addc_co_u32_e64 v95, s[0:1], 0, v95, s[0:1]
	global_load_dwordx4 v[218:221], v[94:95], off
	s_waitcnt vmcnt(0) lgkmcnt(0)
	v_mfma_f32_16x16x32_bf16 v[36:39], v[90:93], v[98:101], v[36:39]
	v_mfma_f32_16x16x32_bf16 v[24:27], v[102:105], v[98:101], v[24:27]
	v_mfma_f32_16x16x32_bf16 v[20:23], v[90:93], v[180:183], v[20:23]
	v_mfma_f32_16x16x32_bf16 v[16:19], v[102:105], v[180:183], v[16:19]
	v_mfma_f32_16x16x32_bf16 v[12:15], v[90:93], v[184:187], v[12:15]
	v_mfma_f32_16x16x32_bf16 v[8:11], v[102:105], v[184:187], v[8:11]
	v_mfma_f32_16x16x32_bf16 v[4:7], v[90:93], v[188:191], v[4:7]
	v_mfma_f32_16x16x32_bf16 v[0:3], v[102:105], v[188:191], v[0:3]
	v_mfma_f32_16x16x32_bf16 v[28:31], v[90:93], v[206:209], v[28:31]
	v_mfma_f32_16x16x32_bf16 v[32:35], v[102:105], v[206:209], v[32:35]
	v_mfma_f32_16x16x32_bf16 v[40:43], v[90:93], v[210:213], v[40:43]
	v_mfma_f32_16x16x32_bf16 v[44:47], v[102:105], v[210:213], v[44:47]
	v_mfma_f32_16x16x32_bf16 v[48:51], v[90:93], v[214:217], v[48:51]
	v_mfma_f32_16x16x32_bf16 v[52:55], v[102:105], v[214:217], v[52:55]
	v_mfma_f32_16x16x32_bf16 v[56:59], v[90:93], v[218:221], v[56:59]
	v_mfma_f32_16x16x32_bf16 v[60:63], v[102:105], v[218:221], v[60:63]
	s_cbranch_scc1 .LBB0_908
	ds_write_b128 v78, v[36:39]
	ds_write_b128 v78, v[24:27] offset:1024
	ds_write_b128 v78, v[20:23] offset:2048
	ds_write_b128 v78, v[16:19] offset:3072
	ds_write_b128 v78, v[12:15] offset:4096
	ds_write_b128 v78, v[8:11] offset:5120
	ds_write_b128 v78, v[4:7] offset:6144
	ds_write_b128 v78, v[0:3] offset:7168
	ds_write_b128 v78, v[28:31] offset:8192
	ds_write_b128 v78, v[32:35] offset:9216
	ds_write_b128 v78, v[40:43] offset:10240
	ds_write_b128 v78, v[44:47] offset:11264
	ds_write_b128 v78, v[48:51] offset:12288
	ds_write_b128 v78, v[52:55] offset:13312
	ds_write_b128 v78, v[56:59] offset:14336
	ds_write_b128 v78, v[60:63] offset:15360
	s_waitcnt lgkmcnt(0)
	s_waitcnt lgkmcnt(0)
	s_barrier
; __device__ __forceinline__ unsigned cvt_pk_bf16(float lo, float hi) { unsigned r; asm volatile("v_cvt_pk_bf16_f32 %0, %1, %2" : "=v"(r) : "v"(lo), "v"(hi)); return r; }
; template <int KSTEPS  >
; __device__ __forceinline__ void small_mma_ksplit(f32x4 (&acc)[2], const bf16_t* A, int lda, const bf16_t* Bt, int ldb, int n0, LAS unsigned char* lds, const SmallId& id) {
;     ...
;     acc[0] = (f32x4){0.f, 0.f, 0.f, 0.f}; acc[1] = acc[0];
; #pragma unroll
;     for (int w2 = 0; w2 < 8; ++w2) { acc[0] += red[((w2 * 8 + id.w) * 2 + 0) * 64 + lane]; acc[1] += red[((w2 * 8 + id.w) * 2 + 1) * 64 + lane]; }
;     asm volatile("s_waitcnt lgkmcnt(0)" ::: "memory"); __syncthreads();
; template <bool RES_F32, bool OUT_F32, int KSTEPS>
; __device__ __forceinline__ void small_res(const Params& p, LAS unsigned char* lds, const bf16_t* A, int lda, const bf16_t* Bt, int K, float* ssq_next, int G, int bx) {
;     ...
;         float s = 0.f;
; #pragma unroll
;         for (int nb = 0; nb < 2; ++nb) { const int col = n0 + 16 * nb + 4 * id.fq;
;             f32x4 r;
;             if (RES_F32) r = *(const f32x4*)(p.xs + (size_t)(id.row - MP) * DM + col);
;             else { const u32x2 w = *(const u32x2*)(XB + (size_t)id.row * DM + col); r = (f32x4){bf_lo(w.x), bf_hi(w.x), bf_lo(w.y), bf_hi(w.y)}; }
;             const f32x4 x = r + acc[nb];
;             if (OUT_F32) *(f32x4*)(p.out + (size_t)id.row * DM + col) = x;
;             else { u32x2 w; w.x = cvt_pk_bf16(x[0], x[1]); w.y = cvt_pk_bf16(x[2], x[3]); *(u32x2*)(XB + (size_t)id.row * DM + col) = w; }
;             s += (x[0] * x[0] + x[1] * x[1]) + (x[2] * x[2] + x[3] * x[3]); }
;         if (!OUT_F32) { s += __shfl_xor(s, 16); s += __shfl_xor(s, 32); if (id.fq == 0) atomicAdd(ssq_next + id.row, s); }
	ds_read_b128 v[0:3], v79
	v_lshl_or_b32 v12, s7, 5, v88
	v_ashrrev_i32_e32 v13, 31, v12
	v_lshl_add_u64 v[14:15], v[12:13], 2, v[68:69]
	s_waitcnt lgkmcnt(0)
	v_pk_add_f32 v[4:5], v[2:3], 0 op_sel_hi:[1,0]
	v_pk_add_f32 v[6:7], v[0:1], 0 op_sel_hi:[1,0]
	ds_read_b128 v[0:3], v79 offset:1024
	s_waitcnt lgkmcnt(0)
	v_pk_add_f32 v[8:9], v[2:3], 0 op_sel_hi:[1,0]
	v_pk_add_f32 v[10:11], v[0:1], 0 op_sel_hi:[1,0]
	ds_read_b128 v[0:3], v79 offset:16384
	s_waitcnt lgkmcnt(0)
	v_pk_add_f32 v[4:5], v[4:5], v[2:3]
	v_pk_add_f32 v[6:7], v[6:7], v[0:1]
	ds_read_b128 v[0:3], v79 offset:17408
	s_waitcnt lgkmcnt(0)
	v_pk_add_f32 v[8:9], v[8:9], v[2:3]
	v_pk_add_f32 v[10:11], v[10:11], v[0:1]
	ds_read_b128 v[0:3], v79 offset:32768
	s_waitcnt lgkmcnt(0)
	v_pk_add_f32 v[4:5], v[4:5], v[2:3]
	v_pk_add_f32 v[6:7], v[6:7], v[0:1]
	ds_read_b128 v[0:3], v79 offset:33792
	s_waitcnt lgkmcnt(0)
	v_pk_add_f32 v[8:9], v[8:9], v[2:3]
	v_pk_add_f32 v[10:11], v[10:11], v[0:1]
	ds_read_b128 v[0:3], v79 offset:49152
	s_waitcnt lgkmcnt(0)
	v_pk_add_f32 v[4:5], v[4:5], v[2:3]
	v_pk_add_f32 v[6:7], v[6:7], v[0:1]
	ds_read_b128 v[0:3], v79 offset:50176
	s_waitcnt lgkmcnt(0)
	v_pk_add_f32 v[8:9], v[8:9], v[2:3]
	v_pk_add_f32 v[10:11], v[10:11], v[0:1]
	ds_read_b128 v[0:3], v80
	s_waitcnt lgkmcnt(0)
	v_pk_add_f32 v[4:5], v[4:5], v[2:3]
	v_pk_add_f32 v[6:7], v[6:7], v[0:1]
	ds_read_b128 v[0:3], v81
	s_waitcnt lgkmcnt(0)
	v_pk_add_f32 v[8:9], v[8:9], v[2:3]
	v_pk_add_f32 v[10:11], v[10:11], v[0:1]
	ds_read_b128 v[0:3], v82
	s_waitcnt lgkmcnt(0)
	v_pk_add_f32 v[4:5], v[4:5], v[2:3]
	v_pk_add_f32 v[6:7], v[6:7], v[0:1]
	ds_read_b128 v[0:3], v83
	s_waitcnt lgkmcnt(0)
	v_pk_add_f32 v[8:9], v[8:9], v[2:3]
	v_pk_add_f32 v[10:11], v[10:11], v[0:1]
	ds_read_b128 v[0:3], v84
	s_waitcnt lgkmcnt(0)
	v_pk_add_f32 v[4:5], v[4:5], v[2:3]
	v_pk_add_f32 v[6:7], v[6:7], v[0:1]
	ds_read_b128 v[0:3], v85
	s_waitcnt lgkmcnt(0)
	v_pk_add_f32 v[8:9], v[8:9], v[2:3]
	v_pk_add_f32 v[10:11], v[10:11], v[0:1]
	ds_read_b128 v[0:3], v86
	s_waitcnt lgkmcnt(0)
	v_pk_add_f32 v[4:5], v[4:5], v[2:3]
	v_pk_add_f32 v[6:7], v[6:7], v[0:1]
	ds_read_b128 v[0:3], v87
	s_waitcnt lgkmcnt(0)
	s_waitcnt lgkmcnt(0)
	s_barrier
	v_pk_add_f32 v[8:9], v[8:9], v[2:3]
	v_pk_add_f32 v[10:11], v[10:11], v[0:1]
	global_load_dwordx4 v[0:3], v[14:15], off
	s_waitcnt vmcnt(0)
	v_pk_add_f32 v[0:1], v[6:7], v[0:1]
	v_pk_add_f32 v[2:3], v[4:5], v[2:3]
	v_cvt_pk_bf16_f32 v4, v0, v1
	v_mul_f32_e32 v1, v1, v1
	v_lshl_add_u64 v[6:7], v[12:13], 1, v[64:65]
	v_fmac_f32_e32 v1, v0, v0
	v_mul_f32_e32 v0, v3, v3
	v_cvt_pk_bf16_f32 v5, v2, v3
	global_store_dwordx2 v[6:7], v[4:5], off
	v_fmac_f32_e32 v0, v2, v2
	v_add_f32_e32 v12, v1, v0
	global_load_dwordx4 v[0:3], v[14:15], off offset:64
	s_waitcnt vmcnt(0)
	v_pk_add_f32 v[0:1], v[10:11], v[0:1]
	v_pk_add_f32 v[2:3], v[8:9], v[2:3]
	v_cvt_pk_bf16_f32 v4, v0, v1
	v_mul_f32_e32 v1, v1, v1
	v_fmac_f32_e32 v1, v0, v0
	v_mul_f32_e32 v0, v3, v3
	v_cvt_pk_bf16_f32 v5, v2, v3
	v_fmac_f32_e32 v0, v2, v2
	v_and_b32_e32 v2, 64, v225
	v_add_f32_e32 v0, v1, v0
	v_xor_b32_e32 v1, 16, v225
	v_add_u32_e32 v2, 64, v2
	v_cmp_lt_i32_e64 s[0:1], v1, v2
	v_add_f32_e32 v0, v12, v0
	global_store_dwordx2 v[6:7], v[4:5], off offset:32
	v_cndmask_b32_e64 v1, v225, v1, s[0:1]
	v_lshlrev_b32_e32 v1, 2, v1
	ds_bpermute_b32 v1, v1, v0
	s_waitcnt lgkmcnt(0)
	v_add_f32_e32 v0, v0, v1
	v_xor_b32_e32 v1, 32, v225
	v_cmp_lt_i32_e64 s[0:1], v1, v2
	s_nop 1
	v_cndmask_b32_e64 v1, v225, v1, s[0:1]
	v_lshlrev_b32_e32 v1, 2, v1
	ds_bpermute_b32 v1, v1, v0
	s_and_saveexec_b64 s[0:1], vcc
	s_cbranch_execz .LBB0_906
	s_waitcnt lgkmcnt(0)
	v_add_f32_e32 v0, v0, v1
	global_atomic_add_f32 v[66:67], v0, off
	s_branch .LBB0_906

; __device__ __forceinline__ unsigned cvt_pk_bf16(float lo, float hi) { unsigned r; asm volatile("v_cvt_pk_bf16_f32 %0, %1, %2" : "=v"(r) : "v"(lo), "v"(hi)); return r; }
;     __device__ __forceinline__ void finish(const f32x4 x0, const f32x4 x1, int row, int col, float& s) const {
;         if (OUT_F32) { *(f32x4*)(out + (size_t)row * DM + col) = x0; *(f32x4*)(out + (size_t)row * DM + col + 4) = x1; }
;         else { u32x4 w; w.x = cvt_pk_bf16(x0[0], x0[1]); w.y = cvt_pk_bf16(x0[2], x0[3]); w.z = cvt_pk_bf16(x1[0], x1[1]); w.w = cvt_pk_bf16(x1[2], x1[3]); *(u32x4*)(XB + (size_t)row * DM + col) = w; }
;         s += (x0[0] * x0[0] + x0[1] * x0[1]) + (x0[2] * x0[2] + x0[3] * x0[3]) + (x1[0] * x1[0] + x1[1] * x1[1]) + (x1[2] * x1[2] + x1[3] * x1[3]);
;     __device__ __forceinline__ void operator()(AccT& acc, const Unit& u, int wr, int wc, int fr, int fq) const {
;     ...
; #pragma unroll
;             for (int ai = 0; ai < 2; ++ai) {
;                 f32x4 rv[4][2][2];
; #pragma unroll
;                 for (int m = 0; m < 4; ++m)
; #pragma unroll
;                     for (int bj = 0; bj < 2; ++bj) { const size_t o = (size_t)(u.pm * 256 + ai * 128 + wr * 64 + m * 16 + fr) * DM + col0 + bj * 128; rv[m][bj][0] = *(const f32x4*)(res + o); rv[m][bj][1] = *(const f32x4*)(res + o + 4); }
; #pragma unroll
;                 for (int m = 0; m < 4; ++m) {
;                     const int row = u.pm * 256 + ai * 128 + wr * 64 + m * 16 + fr; float s = 0.f;
; #pragma unroll
;                     for (int bj = 0; bj < 2; ++bj) finish(rv[m][bj][0] + acc[ai][bj][m][0], rv[m][bj][1] + acc[ai][bj][m][1], row, col0 + bj * 128, s);
;                     if (!OUT_F32) { s += __shfl_xor(s, 16); s += __shfl_xor(s, 32); if (fq == 0) atomicAdd(ssq_next + row, s); }
;                 }
.LBB0_927:
	s_lshl_b32 s0, s48, 8
	v_mov_b32_e32 v130, v212
	v_mov_b32_e32 v131, v213
	s_or_b32 s0, s0, s37
	v_readlane_b32 s56, v249, 4
	v_lshl_add_u32 v188, v131, 3, s0
	s_lshl_b32 s0, s45, 8
	s_add_i32 s0, s0, s33
	v_add_u32_e32 v190, s0, v130
	v_ashrrev_i32_e32 v189, 31, v188
	v_readlane_b32 s57, v249, 5
	v_ashrrev_i32_e32 v191, 31, v190
	v_cmp_eq_u32_e32 vcc, 0, v131
	v_lshl_add_u64 v[192:193], v[188:189], 2, s[56:57]
	v_lshlrev_b64 v[130:131], 12, v[190:191]
	v_lshl_add_u64 v[130:131], v[192:193], 0, v[130:131]
	global_load_dwordx4 v[216:219], v[130:131], off offset:16
	global_load_dwordx4 v[230:233], v[130:131], off
	global_load_dwordx4 v[234:237], v[130:131], off offset:528
	global_load_dwordx4 v[238:241], v[130:131], off offset:512
	v_add_u32_e32 v210, 16, v190
	v_ashrrev_i32_e32 v211, 31, v210
	v_lshlrev_b64 v[130:131], 12, v[210:211]
	v_add_u32_e32 v208, 32, v190
	v_lshl_add_u64 v[130:131], v[192:193], 0, v[130:131]
	v_ashrrev_i32_e32 v209, 31, v208
	global_load_dwordx4 v[170:173], v[130:131], off offset:16
	global_load_dwordx4 v[174:177], v[130:131], off
	global_load_dwordx4 v[162:165], v[130:131], off offset:528
	global_load_dwordx4 v[166:169], v[130:131], off offset:512
	v_lshlrev_b64 v[130:131], 12, v[208:209]
	v_add_u32_e32 v206, 48, v190
	v_lshl_add_u64 v[130:131], v[192:193], 0, v[130:131]
	v_ashrrev_i32_e32 v207, 31, v206
	global_load_dwordx4 v[154:157], v[130:131], off offset:16
	global_load_dwordx4 v[158:161], v[130:131], off
	global_load_dwordx4 v[138:141], v[130:131], off offset:528
	global_load_dwordx4 v[142:145], v[130:131], off offset:512
	v_lshlrev_b64 v[130:131], 12, v[206:207]
	v_lshl_add_u64 v[134:135], v[192:193], 0, v[130:131]
	global_load_dwordx4 v[146:149], v[134:135], off offset:16
	global_load_dwordx4 v[150:153], v[134:135], off
	global_load_dwordx4 v[130:133], v[134:135], off offset:528
	s_nop 0
	global_load_dwordx4 v[134:137], v[134:135], off offset:512
	v_lshlrev_b64 v[220:221], 11, v[190:191]
	v_lshl_add_u64 v[220:221], s[90:91], 0, v[220:221]
	v_lshl_add_u64 v[220:221], v[188:189], 1, v[220:221]
	v_readlane_b32 s58, v249, 6
	v_readlane_b32 s59, v249, 7
	v_readlane_b32 s60, v249, 8
	v_readlane_b32 s61, v249, 9
	v_readlane_b32 s62, v249, 10
	v_readlane_b32 s63, v249, 11
	v_readlane_b32 s64, v249, 12
	v_readlane_b32 s65, v249, 13
	v_readlane_b32 s66, v249, 14
	v_readlane_b32 s67, v249, 15
	v_readlane_b32 s68, v249, 16
	v_readlane_b32 s69, v249, 17
	v_readlane_b32 s70, v249, 18
	v_readlane_b32 s71, v249, 19
	s_waitcnt vmcnt(0)
	v_pk_add_f32 v[216:217], v[122:123], v[216:217]
	v_pk_add_f32 v[128:129], v[128:129], v[232:233]
	v_pk_add_f32 v[126:127], v[126:127], v[230:231]
	v_pk_add_f32 v[218:219], v[124:125], v[218:219]
	v_cvt_pk_bf16_f32 v122, v126, v127
	v_cvt_pk_bf16_f32 v123, v128, v129
	v_cvt_pk_bf16_f32 v124, v216, v217
	v_pk_add_f32 v[120:121], v[120:121], v[240:241]
	v_cvt_pk_bf16_f32 v125, v218, v219
	global_store_dwordx4 v[220:221], v[122:125], off
	v_pk_add_f32 v[118:119], v[118:119], v[238:239]
	s_nop 0
	v_mul_f32_e32 v122, v127, v127
	v_mul_f32_e32 v123, v129, v129
	v_fmac_f32_e32 v122, v126, v126
	v_fmac_f32_e32 v123, v128, v128
	v_add_f32_e32 v122, v122, v123
	v_mul_f32_e32 v123, v217, v217
	v_fmac_f32_e32 v123, v216, v216
	v_add_f32_e32 v122, v122, v123
	v_mul_f32_e32 v123, v219, v219
	v_fmac_f32_e32 v123, v218, v218
	v_pk_add_f32 v[124:125], v[114:115], v[234:235]
	v_cvt_pk_bf16_f32 v114, v118, v119
	v_cvt_pk_bf16_f32 v115, v120, v121
	v_add_f32_e32 v126, v123, v122
	v_pk_add_f32 v[122:123], v[116:117], v[236:237]
	v_cvt_pk_bf16_f32 v116, v124, v125
	s_nop 0
	v_cvt_pk_bf16_f32 v117, v122, v123
	global_store_dwordx4 v[220:221], v[114:117], off offset:256
	s_nop 1
	v_mul_f32_e32 v114, v119, v119
	v_mul_f32_e32 v115, v121, v121
	v_fmac_f32_e32 v114, v118, v118
	v_fmac_f32_e32 v115, v120, v120
	v_add_f32_e32 v114, v114, v115
	v_mul_f32_e32 v115, v125, v125
	v_fmac_f32_e32 v115, v124, v124
	v_add_f32_e32 v114, v114, v115
	v_mul_f32_e32 v115, v123, v123
	v_fmac_f32_e32 v115, v122, v122
	v_and_b32_e32 v116, 64, v225
	v_add_f32_e32 v114, v115, v114
	v_xor_b32_e32 v115, 16, v225
	v_add_u32_e32 v116, 64, v116
	v_cmp_lt_i32_e64 s[0:1], v115, v116
	v_add_f32_e32 v114, v126, v114
	s_nop 0
	v_cndmask_b32_e64 v115, v225, v115, s[0:1]
	v_lshlrev_b32_e32 v122, 2, v115
	ds_bpermute_b32 v115, v122, v114
	s_waitcnt lgkmcnt(0)
	v_add_f32_e32 v114, v114, v115
	v_xor_b32_e32 v115, 32, v225
	v_cmp_lt_i32_e64 s[0:1], v115, v116
	s_nop 1
	v_cndmask_b32_e64 v115, v225, v115, s[0:1]
	v_lshlrev_b32_e32 v123, 2, v115
	ds_bpermute_b32 v115, v123, v114
	s_and_saveexec_b64 s[0:1], vcc
	s_cbranch_execz .LBB0_929
	v_lshl_add_u64 v[116:117], v[190:191], 2, s[2:3]
	s_waitcnt lgkmcnt(0)
	v_add_f32_e32 v114, v114, v115
	global_atomic_add_f32 v[116:117], v114, off
; __device__ __forceinline__ unsigned cvt_pk_bf16(float lo, float hi) { unsigned r; asm volatile("v_cvt_pk_bf16_f32 %0, %1, %2" : "=v"(r) : "v"(lo), "v"(hi)); return r; }
;     __device__ __forceinline__ void finish(const f32x4 x0, const f32x4 x1, int row, int col, float& s) const {
;         if (OUT_F32) { *(f32x4*)(out + (size_t)row * DM + col) = x0; *(f32x4*)(out + (size_t)row * DM + col + 4) = x1; }
;         else { u32x4 w; w.x = cvt_pk_bf16(x0[0], x0[1]); w.y = cvt_pk_bf16(x0[2], x0[3]); w.z = cvt_pk_bf16(x1[0], x1[1]); w.w = cvt_pk_bf16(x1[2], x1[3]); *(u32x4*)(XB + (size_t)row * DM + col) = w; }
;         s += (x0[0] * x0[0] + x0[1] * x0[1]) + (x0[2] * x0[2] + x0[3] * x0[3]) + (x1[0] * x1[0] + x1[1] * x1[1]) + (x1[2] * x1[2] + x1[3] * x1[3]);
;     __device__ __forceinline__ void operator()(AccT& acc, const Unit& u, int wr, int wc, int fr, int fq) const {
;     ...
; #pragma unroll
;             for (int ai = 0; ai < 2; ++ai) {
;                 f32x4 rv[4][2][2];
; #pragma unroll
;                 for (int m = 0; m < 4; ++m)
; #pragma unroll
;                     for (int bj = 0; bj < 2; ++bj) { const size_t o = (size_t)(u.pm * 256 + ai * 128 + wr * 64 + m * 16 + fr) * DM + col0 + bj * 128; rv[m][bj][0] = *(const f32x4*)(res + o); rv[m][bj][1] = *(const f32x4*)(res + o + 4); }
; #pragma unroll
;                 for (int m = 0; m < 4; ++m) {
;                     const int row = u.pm * 256 + ai * 128 + wr * 64 + m * 16 + fr; float s = 0.f;
; #pragma unroll
;                     for (int bj = 0; bj < 2; ++bj) finish(rv[m][bj][0] + acc[ai][bj][m][0], rv[m][bj][1] + acc[ai][bj][m][1], row, col0 + bj * 128, s);
;                     if (!OUT_F32) { s += __shfl_xor(s, 16); s += __shfl_xor(s, 32); if (fq == 0) atomicAdd(ssq_next + row, s); }
;                 }
.LBB0_929:
	s_or_b64 exec, exec, s[0:1]
	v_pk_add_f32 v[110:111], v[110:111], v[174:175]
	v_pk_add_f32 v[112:113], v[112:113], v[176:177]
	v_pk_add_f32 v[118:119], v[106:107], v[170:171]
	v_cvt_pk_bf16_f32 v106, v110, v111
	v_mul_f32_e32 v111, v111, v111
	v_fmac_f32_e32 v111, v110, v110
	v_mul_f32_e32 v110, v113, v113
	v_fmac_f32_e32 v110, v112, v112
	v_add_f32_e32 v110, v111, v110
	v_mul_f32_e32 v111, v119, v119
	v_pk_add_f32 v[104:105], v[104:105], v[168:169]
	v_pk_add_f32 v[102:103], v[102:103], v[166:167]
	v_pk_add_f32 v[116:117], v[108:109], v[172:173]
	v_cvt_pk_bf16_f32 v107, v112, v113
	v_fmac_f32_e32 v111, v118, v118
	v_pk_add_f32 v[112:113], v[98:99], v[162:163]
	v_mul_f32_e32 v98, v103, v103
	v_mul_f32_e32 v99, v105, v105
	v_add_f32_e32 v110, v110, v111
	v_mul_f32_e32 v111, v117, v117
	v_fmac_f32_e32 v98, v102, v102
	v_fmac_f32_e32 v99, v104, v104
	v_fmac_f32_e32 v111, v116, v116
	v_add_f32_e32 v98, v98, v99
	v_mul_f32_e32 v99, v113, v113
	v_cvt_pk_bf16_f32 v108, v118, v119
	v_cvt_pk_bf16_f32 v109, v116, v117
	v_add_f32_e32 v116, v111, v110
	v_pk_add_f32 v[110:111], v[100:101], v[164:165]
	v_fmac_f32_e32 v99, v112, v112
	v_add_f32_e32 v98, v98, v99
	v_mul_f32_e32 v99, v111, v111
	v_fmac_f32_e32 v99, v110, v110
	v_add_f32_e32 v98, v99, v98
	v_add_f32_e32 v101, v116, v98
	ds_bpermute_b32 v116, v122, v101
	s_waitcnt lgkmcnt(0)
	v_lshlrev_b64 v[114:115], 11, v[210:211]
	v_lshl_add_u64 v[98:99], s[90:91], 0, v[114:115]
	v_lshl_add_u64 v[114:115], v[188:189], 1, v[98:99]
	global_store_dwordx4 v[114:115], v[106:109], off
	v_add_f32_e32 v98, v101, v116
	ds_bpermute_b32 v99, v123, v98
	v_cvt_pk_bf16_f32 v100, v102, v103
	v_cvt_pk_bf16_f32 v101, v104, v105
	v_cvt_pk_bf16_f32 v102, v112, v113
	v_cvt_pk_bf16_f32 v103, v110, v111
	global_store_dwordx4 v[114:115], v[100:103], off offset:256
	s_and_saveexec_b64 s[0:1], vcc
	s_cbranch_execz .LBB0_931
	v_lshl_add_u64 v[100:101], v[210:211], 2, s[2:3]
	s_waitcnt lgkmcnt(0)
	v_add_f32_e32 v98, v98, v99
	global_atomic_add_f32 v[100:101], v98, off
.LBB0_931:
	s_or_b64 exec, exec, s[0:1]
	v_pk_add_f32 v[92:93], v[92:93], v[158:159]
	v_pk_add_f32 v[94:95], v[94:95], v[160:161]
	v_pk_add_f32 v[102:103], v[88:89], v[154:155]
	v_cvt_pk_bf16_f32 v88, v92, v93
	v_mul_f32_e32 v93, v93, v93
	v_fmac_f32_e32 v93, v92, v92
	v_mul_f32_e32 v92, v95, v95
	v_fmac_f32_e32 v92, v94, v94
	v_add_f32_e32 v92, v93, v92
	v_mul_f32_e32 v93, v103, v103
	v_pk_add_f32 v[86:87], v[86:87], v[144:145]
	v_pk_add_f32 v[84:85], v[84:85], v[142:143]
	v_pk_add_f32 v[100:101], v[90:91], v[156:157]
	v_cvt_pk_bf16_f32 v89, v94, v95
	v_fmac_f32_e32 v93, v102, v102
	v_pk_add_f32 v[94:95], v[80:81], v[138:139]
	v_mul_f32_e32 v80, v85, v85
	v_mul_f32_e32 v81, v87, v87
	v_add_f32_e32 v92, v92, v93
	v_mul_f32_e32 v93, v101, v101
	v_fmac_f32_e32 v80, v84, v84
	v_fmac_f32_e32 v81, v86, v86
	v_fmac_f32_e32 v93, v100, v100
	v_add_f32_e32 v80, v80, v81
	v_mul_f32_e32 v81, v95, v95
	v_cvt_pk_bf16_f32 v90, v102, v103
	v_cvt_pk_bf16_f32 v91, v100, v101
	v_add_f32_e32 v100, v93, v92
	v_pk_add_f32 v[92:93], v[82:83], v[140:141]
	v_fmac_f32_e32 v81, v94, v94
	v_add_f32_e32 v80, v80, v81
	v_mul_f32_e32 v81, v93, v93
	v_fmac_f32_e32 v81, v92, v92
	v_add_f32_e32 v80, v81, v80
	v_add_f32_e32 v83, v100, v80
	ds_bpermute_b32 v100, v122, v83
	s_waitcnt lgkmcnt(0)
	v_lshlrev_b64 v[98:99], 11, v[208:209]
	v_lshl_add_u64 v[80:81], s[90:91], 0, v[98:99]
	v_lshl_add_u64 v[98:99], v[188:189], 1, v[80:81]
	global_store_dwordx4 v[98:99], v[88:91], off
	v_add_f32_e32 v80, v83, v100
	ds_bpermute_b32 v81, v123, v80
	v_cvt_pk_bf16_f32 v82, v84, v85
	v_cvt_pk_bf16_f32 v83, v86, v87
	v_cvt_pk_bf16_f32 v84, v94, v95
	v_cvt_pk_bf16_f32 v85, v92, v93
	global_store_dwordx4 v[98:99], v[82:85], off offset:256
	s_and_saveexec_b64 s[0:1], vcc
	s_cbranch_execz .LBB0_933
	v_lshl_add_u64 v[82:83], v[208:209], 2, s[2:3]
	s_waitcnt lgkmcnt(0)
	v_add_f32_e32 v80, v80, v81
	global_atomic_add_f32 v[82:83], v80, off
.LBB0_933:
	s_or_b64 exec, exec, s[0:1]
	v_pk_add_f32 v[76:77], v[76:77], v[150:151]
	v_pk_add_f32 v[78:79], v[78:79], v[152:153]
	v_pk_add_f32 v[84:85], v[72:73], v[146:147]
	v_cvt_pk_bf16_f32 v72, v76, v77
	v_mul_f32_e32 v77, v77, v77
	v_fmac_f32_e32 v77, v76, v76
	v_mul_f32_e32 v76, v79, v79
	v_fmac_f32_e32 v76, v78, v78
	v_add_f32_e32 v76, v77, v76
	v_mul_f32_e32 v77, v85, v85
	v_pk_add_f32 v[70:71], v[70:71], v[136:137]
	v_pk_add_f32 v[68:69], v[68:69], v[134:135]
	v_pk_add_f32 v[82:83], v[74:75], v[148:149]
	v_cvt_pk_bf16_f32 v73, v78, v79
	v_fmac_f32_e32 v77, v84, v84
	v_pk_add_f32 v[78:79], v[64:65], v[130:131]
	v_mul_f32_e32 v64, v69, v69
	v_mul_f32_e32 v65, v71, v71
	v_add_f32_e32 v76, v76, v77
	v_mul_f32_e32 v77, v83, v83
	v_fmac_f32_e32 v64, v68, v68
	v_fmac_f32_e32 v65, v70, v70
	v_fmac_f32_e32 v77, v82, v82
	v_add_f32_e32 v64, v64, v65
	v_mul_f32_e32 v65, v79, v79
	v_cvt_pk_bf16_f32 v74, v84, v85
	v_cvt_pk_bf16_f32 v75, v82, v83
	v_add_f32_e32 v82, v77, v76
	v_pk_add_f32 v[76:77], v[66:67], v[132:133]
	v_fmac_f32_e32 v65, v78, v78
	v_add_f32_e32 v64, v64, v65
	v_mul_f32_e32 v65, v77, v77
	v_fmac_f32_e32 v65, v76, v76
	v_add_f32_e32 v64, v65, v64
	v_add_f32_e32 v67, v82, v64
	ds_bpermute_b32 v82, v122, v67
	s_waitcnt lgkmcnt(0)
	v_lshlrev_b64 v[80:81], 11, v[206:207]
	v_lshl_add_u64 v[64:65], s[90:91], 0, v[80:81]
	v_lshl_add_u64 v[80:81], v[188:189], 1, v[64:65]
	global_store_dwordx4 v[80:81], v[72:75], off
	v_add_f32_e32 v64, v67, v82
	ds_bpermute_b32 v65, v123, v64
	v_cvt_pk_bf16_f32 v66, v68, v69
	v_cvt_pk_bf16_f32 v67, v70, v71
	v_cvt_pk_bf16_f32 v68, v78, v79
	v_cvt_pk_bf16_f32 v69, v76, v77
	global_store_dwordx4 v[80:81], v[66:69], off offset:256
	s_and_saveexec_b64 s[0:1], vcc
	s_cbranch_execz .LBB0_935
	v_lshl_add_u64 v[66:67], v[206:207], 2, s[2:3]
	s_waitcnt lgkmcnt(0)
	v_add_f32_e32 v64, v64, v65
	global_atomic_add_f32 v[66:67], v64, off
; __device__ __forceinline__ unsigned cvt_pk_bf16(float lo, float hi) { unsigned r; asm volatile("v_cvt_pk_bf16_f32 %0, %1, %2" : "=v"(r) : "v"(lo), "v"(hi)); return r; }
;     __device__ __forceinline__ void finish(const f32x4 x0, const f32x4 x1, int row, int col, float& s) const {
;         if (OUT_F32) { *(f32x4*)(out + (size_t)row * DM + col) = x0; *(f32x4*)(out + (size_t)row * DM + col + 4) = x1; }
;         else { u32x4 w; w.x = cvt_pk_bf16(x0[0], x0[1]); w.y = cvt_pk_bf16(x0[2], x0[3]); w.z = cvt_pk_bf16(x1[0], x1[1]); w.w = cvt_pk_bf16(x1[2], x1[3]); *(u32x4*)(XB + (size_t)row * DM + col) = w; }
;         s += (x0[0] * x0[0] + x0[1] * x0[1]) + (x0[2] * x0[2] + x0[3] * x0[3]) + (x1[0] * x1[0] + x1[1] * x1[1]) + (x1[2] * x1[2] + x1[3] * x1[3]);
;     __device__ __forceinline__ void operator()(AccT& acc, const Unit& u, int wr, int wc, int fr, int fq) const {
;     ...
; #pragma unroll
;             for (int ai = 0; ai < 2; ++ai) {
;                 f32x4 rv[4][2][2];
; #pragma unroll
;                 for (int m = 0; m < 4; ++m)
; #pragma unroll
;                     for (int bj = 0; bj < 2; ++bj) { const size_t o = (size_t)(u.pm * 256 + ai * 128 + wr * 64 + m * 16 + fr) * DM + col0 + bj * 128; rv[m][bj][0] = *(const f32x4*)(res + o); rv[m][bj][1] = *(const f32x4*)(res + o + 4); }
; #pragma unroll
;                 for (int m = 0; m < 4; ++m) {
;                     const int row = u.pm * 256 + ai * 128 + wr * 64 + m * 16 + fr; float s = 0.f;
; #pragma unroll
;                     for (int bj = 0; bj < 2; ++bj) finish(rv[m][bj][0] + acc[ai][bj][m][0], rv[m][bj][1] + acc[ai][bj][m][1], row, col0 + bj * 128, s);
;                     if (!OUT_F32) { s += __shfl_xor(s, 16); s += __shfl_xor(s, 32); if (fq == 0) atomicAdd(ssq_next + row, s); }
;                 }
.LBB0_935:
	s_or_b64 exec, exec, s[0:1]
	v_add_u32_e32 v120, 0x80, v190
	v_ashrrev_i32_e32 v121, 31, v120
	s_waitcnt lgkmcnt(0)
	v_lshlrev_b64 v[64:65], 12, v[120:121]
	v_lshl_add_u64 v[64:65], v[192:193], 0, v[64:65]
	global_load_dwordx4 v[124:127], v[64:65], off
	global_load_dwordx4 v[128:131], v[64:65], off offset:16
	global_load_dwordx4 v[132:135], v[64:65], off offset:512
	global_load_dwordx4 v[136:139], v[64:65], off offset:528
	v_add_u32_e32 v118, 0x90, v190
	v_add_u32_e32 v116, 0xa0, v190
	v_add_u32_e32 v114, 0xb0, v190
	v_ashrrev_i32_e32 v119, 31, v118
	v_ashrrev_i32_e32 v117, 31, v116
	v_ashrrev_i32_e32 v115, 31, v114
	v_lshlrev_b64 v[64:65], 12, v[118:119]
	v_lshlrev_b64 v[66:67], 12, v[116:117]
	v_lshlrev_b64 v[68:69], 12, v[114:115]
	v_lshl_add_u64 v[64:65], v[192:193], 0, v[64:65]
	v_lshl_add_u64 v[66:67], v[192:193], 0, v[66:67]
	v_lshl_add_u64 v[68:69], v[192:193], 0, v[68:69]
	global_load_dwordx4 v[106:109], v[64:65], off offset:16
	global_load_dwordx4 v[110:113], v[64:65], off
	global_load_dwordx4 v[98:101], v[64:65], off offset:528
	global_load_dwordx4 v[102:105], v[64:65], off offset:512
	global_load_dwordx4 v[88:91], v[66:67], off offset:16
	global_load_dwordx4 v[92:95], v[66:67], off
	global_load_dwordx4 v[80:83], v[66:67], off offset:528
	global_load_dwordx4 v[84:87], v[66:67], off offset:512
	global_load_dwordx4 v[72:75], v[68:69], off offset:16
	global_load_dwordx4 v[76:79], v[68:69], off
	s_nop 0
	global_load_dwordx4 v[64:67], v[68:69], off offset:528
	s_nop 0
	global_load_dwordx4 v[68:71], v[68:69], off offset:512
	v_lshlrev_b64 v[140:141], 11, v[120:121]
	s_waitcnt vmcnt(0)
	v_pk_add_f32 v[62:63], v[62:63], v[126:127]
	v_pk_add_f32 v[60:61], v[60:61], v[124:125]
	v_pk_add_f32 v[54:55], v[54:55], v[134:135]
	v_pk_add_f32 v[52:53], v[52:53], v[132:133]
	v_pk_add_f32 v[58:59], v[58:59], v[130:131]
	v_pk_add_f32 v[56:57], v[56:57], v[128:129]
	v_pk_add_f32 v[126:127], v[48:49], v[136:137]
	v_cvt_pk_bf16_f32 v48, v60, v61
	v_cvt_pk_bf16_f32 v49, v62, v63
	v_mul_f32_e32 v61, v61, v61
	v_mul_f32_e32 v63, v63, v63
	v_mul_f32_e32 v128, v53, v53
	v_mul_f32_e32 v129, v55, v55
	v_pk_add_f32 v[124:125], v[50:51], v[138:139]
	v_cvt_pk_bf16_f32 v50, v56, v57
	v_cvt_pk_bf16_f32 v51, v58, v59
	v_mul_f32_e32 v57, v57, v57
	v_mul_f32_e32 v59, v59, v59
	v_mul_f32_e32 v130, v127, v127
	v_fmac_f32_e32 v61, v60, v60
	v_fmac_f32_e32 v63, v62, v62
	v_fmac_f32_e32 v128, v52, v52
	v_fmac_f32_e32 v129, v54, v54
	v_mul_f32_e32 v131, v125, v125
	v_fmac_f32_e32 v57, v56, v56
	v_fmac_f32_e32 v59, v58, v58
	v_fmac_f32_e32 v130, v126, v126
	v_add_f32_e32 v56, v61, v63
	v_add_f32_e32 v58, v128, v129
	v_fmac_f32_e32 v131, v124, v124
	v_add_f32_e32 v56, v56, v57
	v_add_f32_e32 v57, v58, v130
	v_add_f32_e32 v56, v59, v56
	v_add_f32_e32 v57, v131, v57
	v_add_f32_e32 v58, v56, v57
	ds_bpermute_b32 v59, v122, v58
	v_lshl_add_u64 v[56:57], s[90:91], 0, v[140:141]
	v_lshl_add_u64 v[56:57], v[188:189], 1, v[56:57]
	global_store_dwordx4 v[56:57], v[48:51], off
	s_waitcnt lgkmcnt(0)
	s_nop 0
	v_add_f32_e32 v48, v58, v59
	ds_bpermute_b32 v49, v123, v48
	v_cvt_pk_bf16_f32 v50, v52, v53
	v_cvt_pk_bf16_f32 v51, v54, v55
	v_cvt_pk_bf16_f32 v52, v126, v127
	v_cvt_pk_bf16_f32 v53, v124, v125
	global_store_dwordx4 v[56:57], v[50:53], off offset:256
	s_and_saveexec_b64 s[0:1], vcc
	s_cbranch_execz .LBB0_937
	v_lshl_add_u64 v[50:51], v[120:121], 2, s[2:3]
	s_waitcnt lgkmcnt(0)
	v_add_f32_e32 v48, v48, v49
	global_atomic_add_f32 v[50:51], v48, off
.LBB0_937:
	s_or_b64 exec, exec, s[0:1]
	v_pk_add_f32 v[44:45], v[44:45], v[110:111]
	v_pk_add_f32 v[46:47], v[46:47], v[112:113]
	v_pk_add_f32 v[52:53], v[40:41], v[106:107]
	v_cvt_pk_bf16_f32 v40, v44, v45
	v_mul_f32_e32 v45, v45, v45
	v_fmac_f32_e32 v45, v44, v44
	v_mul_f32_e32 v44, v47, v47
	v_fmac_f32_e32 v44, v46, v46
	v_add_f32_e32 v44, v45, v44
	v_mul_f32_e32 v45, v53, v53
	v_pk_add_f32 v[38:39], v[38:39], v[104:105]
	v_pk_add_f32 v[36:37], v[36:37], v[102:103]
	v_pk_add_f32 v[50:51], v[42:43], v[108:109]
	v_cvt_pk_bf16_f32 v41, v46, v47
	v_fmac_f32_e32 v45, v52, v52
	v_pk_add_f32 v[46:47], v[32:33], v[98:99]
	v_mul_f32_e32 v32, v37, v37
	v_mul_f32_e32 v33, v39, v39
	v_add_f32_e32 v44, v44, v45
	v_mul_f32_e32 v45, v51, v51
	v_fmac_f32_e32 v32, v36, v36
	v_fmac_f32_e32 v33, v38, v38
	v_fmac_f32_e32 v45, v50, v50
	v_add_f32_e32 v32, v32, v33
	v_mul_f32_e32 v33, v47, v47
	v_cvt_pk_bf16_f32 v42, v52, v53
	v_cvt_pk_bf16_f32 v43, v50, v51
	v_add_f32_e32 v50, v45, v44
	v_pk_add_f32 v[44:45], v[34:35], v[100:101]
	v_fmac_f32_e32 v33, v46, v46
	v_add_f32_e32 v32, v32, v33
	v_mul_f32_e32 v33, v45, v45
	v_fmac_f32_e32 v33, v44, v44
	v_add_f32_e32 v32, v33, v32
	v_add_f32_e32 v35, v50, v32
	ds_bpermute_b32 v50, v122, v35
	s_waitcnt lgkmcnt(0)
	v_lshlrev_b64 v[48:49], 11, v[118:119]
	v_lshl_add_u64 v[32:33], s[90:91], 0, v[48:49]
	v_lshl_add_u64 v[48:49], v[188:189], 1, v[32:33]
	global_store_dwordx4 v[48:49], v[40:43], off
	v_add_f32_e32 v32, v35, v50
	ds_bpermute_b32 v33, v123, v32
	v_cvt_pk_bf16_f32 v34, v36, v37
	v_cvt_pk_bf16_f32 v35, v38, v39
	v_cvt_pk_bf16_f32 v36, v46, v47
	v_cvt_pk_bf16_f32 v37, v44, v45
	global_store_dwordx4 v[48:49], v[34:37], off offset:256
	s_and_saveexec_b64 s[0:1], vcc
	s_cbranch_execz .LBB0_939
	v_lshl_add_u64 v[34:35], v[118:119], 2, s[2:3]
	s_waitcnt lgkmcnt(0)
	v_add_f32_e32 v32, v32, v33
	global_atomic_add_f32 v[34:35], v32, off
; __device__ __forceinline__ unsigned cvt_pk_bf16(float lo, float hi) { unsigned r; asm volatile("v_cvt_pk_bf16_f32 %0, %1, %2" : "=v"(r) : "v"(lo), "v"(hi)); return r; }
;     __device__ __forceinline__ void finish(const f32x4 x0, const f32x4 x1, int row, int col, float& s) const {
;         if (OUT_F32) { *(f32x4*)(out + (size_t)row * DM + col) = x0; *(f32x4*)(out + (size_t)row * DM + col + 4) = x1; }
;         else { u32x4 w; w.x = cvt_pk_bf16(x0[0], x0[1]); w.y = cvt_pk_bf16(x0[2], x0[3]); w.z = cvt_pk_bf16(x1[0], x1[1]); w.w = cvt_pk_bf16(x1[2], x1[3]); *(u32x4*)(XB + (size_t)row * DM + col) = w; }
;         s += (x0[0] * x0[0] + x0[1] * x0[1]) + (x0[2] * x0[2] + x0[3] * x0[3]) + (x1[0] * x1[0] + x1[1] * x1[1]) + (x1[2] * x1[2] + x1[3] * x1[3]);
;     __device__ __forceinline__ void operator()(AccT& acc, const Unit& u, int wr, int wc, int fr, int fq) const {
;     ...
; #pragma unroll
;             for (int ai = 0; ai < 2; ++ai) {
;                 f32x4 rv[4][2][2];
; #pragma unroll
;                 for (int m = 0; m < 4; ++m)
; #pragma unroll
;                     for (int bj = 0; bj < 2; ++bj) { const size_t o = (size_t)(u.pm * 256 + ai * 128 + wr * 64 + m * 16 + fr) * DM + col0 + bj * 128; rv[m][bj][0] = *(const f32x4*)(res + o); rv[m][bj][1] = *(const f32x4*)(res + o + 4); }
; #pragma unroll
;                 for (int m = 0; m < 4; ++m) {
;                     const int row = u.pm * 256 + ai * 128 + wr * 64 + m * 16 + fr; float s = 0.f;
; #pragma unroll
;                     for (int bj = 0; bj < 2; ++bj) finish(rv[m][bj][0] + acc[ai][bj][m][0], rv[m][bj][1] + acc[ai][bj][m][1], row, col0 + bj * 128, s);
;                     if (!OUT_F32) { s += __shfl_xor(s, 16); s += __shfl_xor(s, 32); if (fq == 0) atomicAdd(ssq_next + row, s); }
;                 }
.LBB0_939:
	s_or_b64 exec, exec, s[0:1]
	v_pk_add_f32 v[28:29], v[28:29], v[92:93]
	v_pk_add_f32 v[30:31], v[30:31], v[94:95]
	v_pk_add_f32 v[36:37], v[24:25], v[88:89]
	v_cvt_pk_bf16_f32 v24, v28, v29
	v_mul_f32_e32 v29, v29, v29
	v_fmac_f32_e32 v29, v28, v28
	v_mul_f32_e32 v28, v31, v31
	v_fmac_f32_e32 v28, v30, v30
	v_add_f32_e32 v28, v29, v28
	v_mul_f32_e32 v29, v37, v37
	v_pk_add_f32 v[22:23], v[22:23], v[86:87]
	v_pk_add_f32 v[20:21], v[20:21], v[84:85]
	v_pk_add_f32 v[34:35], v[26:27], v[90:91]
	v_cvt_pk_bf16_f32 v25, v30, v31
	v_fmac_f32_e32 v29, v36, v36
	v_pk_add_f32 v[30:31], v[16:17], v[80:81]
	v_mul_f32_e32 v16, v21, v21
	v_mul_f32_e32 v17, v23, v23
	v_add_f32_e32 v28, v28, v29
	v_mul_f32_e32 v29, v35, v35
	v_fmac_f32_e32 v16, v20, v20
	v_fmac_f32_e32 v17, v22, v22
	v_fmac_f32_e32 v29, v34, v34
	v_add_f32_e32 v16, v16, v17
	v_mul_f32_e32 v17, v31, v31
	v_cvt_pk_bf16_f32 v26, v36, v37
	v_cvt_pk_bf16_f32 v27, v34, v35
	v_add_f32_e32 v34, v29, v28
	v_pk_add_f32 v[28:29], v[18:19], v[82:83]
	v_fmac_f32_e32 v17, v30, v30
	v_add_f32_e32 v16, v16, v17
	v_mul_f32_e32 v17, v29, v29
	v_fmac_f32_e32 v17, v28, v28
	v_add_f32_e32 v16, v17, v16
	v_add_f32_e32 v19, v34, v16
	ds_bpermute_b32 v34, v122, v19
	s_waitcnt lgkmcnt(0)
	v_lshlrev_b64 v[32:33], 11, v[116:117]
	v_lshl_add_u64 v[16:17], s[90:91], 0, v[32:33]
	v_lshl_add_u64 v[32:33], v[188:189], 1, v[16:17]
	global_store_dwordx4 v[32:33], v[24:27], off
	v_add_f32_e32 v16, v19, v34
	ds_bpermute_b32 v17, v123, v16
	v_cvt_pk_bf16_f32 v18, v20, v21
	v_cvt_pk_bf16_f32 v19, v22, v23
	v_cvt_pk_bf16_f32 v20, v30, v31
	v_cvt_pk_bf16_f32 v21, v28, v29
	global_store_dwordx4 v[32:33], v[18:21], off offset:256
	s_and_saveexec_b64 s[0:1], vcc
	s_cbranch_execz .LBB0_941
	v_lshl_add_u64 v[18:19], v[116:117], 2, s[2:3]
	s_waitcnt lgkmcnt(0)
	v_add_f32_e32 v16, v16, v17
	global_atomic_add_f32 v[18:19], v16, off
.LBB0_941:
	s_or_b64 exec, exec, s[0:1]
	v_pk_add_f32 v[12:13], v[12:13], v[76:77]
	v_pk_add_f32 v[14:15], v[14:15], v[78:79]
	v_pk_add_f32 v[20:21], v[8:9], v[72:73]
	v_cvt_pk_bf16_f32 v8, v12, v13
	v_mul_f32_e32 v13, v13, v13
	v_fmac_f32_e32 v13, v12, v12
	v_mul_f32_e32 v12, v15, v15
	v_fmac_f32_e32 v12, v14, v14
	v_add_f32_e32 v12, v13, v12
	v_mul_f32_e32 v13, v21, v21
	v_pk_add_f32 v[6:7], v[6:7], v[70:71]
	v_pk_add_f32 v[4:5], v[4:5], v[68:69]
	v_pk_add_f32 v[18:19], v[10:11], v[74:75]
	v_cvt_pk_bf16_f32 v9, v14, v15
	v_fmac_f32_e32 v13, v20, v20
	v_pk_add_f32 v[14:15], v[0:1], v[64:65]
	v_mul_f32_e32 v0, v5, v5
	v_mul_f32_e32 v1, v7, v7
	v_add_f32_e32 v12, v12, v13
	v_mul_f32_e32 v13, v19, v19
	v_fmac_f32_e32 v0, v4, v4
	v_fmac_f32_e32 v1, v6, v6
	v_fmac_f32_e32 v13, v18, v18
	v_add_f32_e32 v0, v0, v1
	v_mul_f32_e32 v1, v15, v15
	v_cvt_pk_bf16_f32 v10, v20, v21
	v_cvt_pk_bf16_f32 v11, v18, v19
	v_add_f32_e32 v18, v13, v12
	v_pk_add_f32 v[12:13], v[2:3], v[66:67]
	v_fmac_f32_e32 v1, v14, v14
	v_add_f32_e32 v0, v0, v1
	v_mul_f32_e32 v1, v13, v13
	v_fmac_f32_e32 v1, v12, v12
	v_add_f32_e32 v0, v1, v0
	v_add_f32_e32 v3, v18, v0
	ds_bpermute_b32 v18, v122, v3
	s_waitcnt lgkmcnt(0)
	v_lshlrev_b64 v[16:17], 11, v[114:115]
	v_lshl_add_u64 v[0:1], s[90:91], 0, v[16:17]
	v_lshl_add_u64 v[16:17], v[188:189], 1, v[0:1]
	global_store_dwordx4 v[16:17], v[8:11], off
	v_add_f32_e32 v0, v3, v18
	ds_bpermute_b32 v1, v123, v0
	v_cvt_pk_bf16_f32 v2, v4, v5
	v_cvt_pk_bf16_f32 v3, v6, v7
	v_cvt_pk_bf16_f32 v4, v14, v15
	v_cvt_pk_bf16_f32 v5, v12, v13
	global_store_dwordx4 v[16:17], v[2:5], off offset:256
	s_and_saveexec_b64 s[0:1], vcc
	s_cbranch_execz .LBB0_943
	v_lshl_add_u64 v[2:3], v[114:115], 2, s[2:3]
	s_waitcnt lgkmcnt(0)
	v_add_f32_e32 v0, v0, v1
	global_atomic_add_f32 v[2:3], v0, off

; #define LAS __attribute__((address_space(3)))
; template <int KSTEPS  >
; __device__ __forceinline__ void small_mma_ksplit(f32x4 (&acc)[2], const bf16_t* A, int lda, const bf16_t* Bt, int ldb, int n0, LAS unsigned char* lds, const SmallId& id) {
;     ...
; #pragma unroll 1
;     for (int ks = 0; ks < KSTEPS; ++ks) {
;         bf16x8 a[8], b[2];
; #pragma unroll
;         for (int rb = 0; rb < 8; ++rb) a[rb] = *(const bf16x8*)(ap + (size_t)(16 * rb) * lda + 32 * ks);
;         b[0] = *(const bf16x8*)(bp + 32 * ks); b[1] = *(const bf16x8*)(bp + (size_t)16 * ldb + 32 * ks);
; #pragma unroll
;         for (int rb = 0; rb < 8; ++rb) { part[rb][0] = __builtin_amdgcn_mfma_f32_16x16x32_bf16(b[0], a[rb], part[rb][0], 0, 0, 0); part[rb][1] = __builtin_amdgcn_mfma_f32_16x16x32_bf16(b[1], a[rb], part[rb][1], 0, 0, 0); }
;     }
;     LAS f32x4* red = (LAS f32x4*)lds;
; #pragma unroll
;     for (int rb = 0; rb < 8; ++rb) { red[((id.w * 8 + rb) * 2 + 0) * 64 + lane] = part[rb][0]; red[((id.w * 8 + rb) * 2 + 1) * 64 + lane] = part[rb][1]; }
;     asm volatile("s_waitcnt lgkmcnt(0)" ::: "memory"); __syncthreads();
;     acc[0] = (f32x4){0.f, 0.f, 0.f, 0.f}; acc[1] = acc[0];
; #pragma unroll
;     for (int w2 = 0; w2 < 8; ++w2) { acc[0] += red[((w2 * 8 + id.w) * 2 + 0) * 64 + lane]; acc[1] += red[((w2 * 8 + id.w) * 2 + 1) * 64 + lane]; }
;     asm volatile("s_waitcnt lgkmcnt(0)" ::: "memory"); __syncthreads();
.LBB0_1003:
	v_lshl_add_u64 v[82:83], v[148:149], 0, s[0:1]
	v_add_co_u32_e32 v70, vcc, s11, v82
	v_lshl_add_u64 v[66:67], v[64:65], 0, s[0:1]
	s_nop 1
	v_addc_co_u32_e32 v71, vcc, 0, v83, vcc
	v_add_co_u32_e32 v78, vcc, s12, v82
	s_add_u32 s0, s0, 64
	s_nop 1
	v_addc_co_u32_e32 v79, vcc, 0, v83, vcc
	v_add_co_u32_e32 v68, vcc, s26, v66
	s_addc_u32 s1, s1, 0
	s_nop 1
	v_addc_co_u32_e32 v69, vcc, 0, v67, vcc
	v_add_co_u32_e32 v74, vcc, s88, v66
	s_cmpk_lg_i32 s0, 0x100
	s_nop 1
	v_addc_co_u32_e32 v75, vcc, 0, v67, vcc
	global_load_dwordx4 v[66:69], v[68:69], off
	global_load_dwordx4 v[70:73], v[70:71], off
	global_load_dwordx4 v[74:77], v[74:75], off
	global_load_dwordx4 v[78:81], v[78:79], off
	v_add_co_u32_e32 v84, vcc, s13, v82
	s_nop 1
	v_addc_co_u32_e32 v85, vcc, 0, v83, vcc
	v_add_co_u32_e32 v86, vcc, s14, v82
	s_nop 1
	v_addc_co_u32_e32 v87, vcc, 0, v83, vcc
	global_load_dwordx4 v[180:183], v[84:85], off
	global_load_dwordx4 v[184:187], v[86:87], off
	v_add_co_u32_e32 v84, vcc, s15, v82
	s_nop 1
	v_addc_co_u32_e32 v85, vcc, 0, v83, vcc
	v_add_co_u32_e32 v86, vcc, s16, v82
	s_nop 1
	v_addc_co_u32_e32 v87, vcc, 0, v83, vcc
	global_load_dwordx4 v[188:191], v[84:85], off
	global_load_dwordx4 v[206:209], v[86:87], off
	v_add_co_u32_e32 v84, vcc, s17, v82
	s_nop 1
	v_addc_co_u32_e32 v85, vcc, 0, v83, vcc
	v_add_co_u32_e32 v82, vcc, s35, v82
	s_nop 1
	v_addc_co_u32_e32 v83, vcc, 0, v83, vcc
	global_load_dwordx4 v[210:213], v[84:85], off
	global_load_dwordx4 v[214:217], v[82:83], off
	s_waitcnt vmcnt(0) lgkmcnt(0)
	v_mfma_f32_16x16x32_bf16 v[36:39], v[66:69], v[70:73], v[36:39]
	v_mfma_f32_16x16x32_bf16 v[24:27], v[74:77], v[70:73], v[24:27]
	v_mfma_f32_16x16x32_bf16 v[20:23], v[66:69], v[78:81], v[20:23]
	v_mfma_f32_16x16x32_bf16 v[16:19], v[74:77], v[78:81], v[16:19]
	v_mfma_f32_16x16x32_bf16 v[12:15], v[66:69], v[180:183], v[12:15]
	v_mfma_f32_16x16x32_bf16 v[8:11], v[74:77], v[180:183], v[8:11]
	v_mfma_f32_16x16x32_bf16 v[4:7], v[66:69], v[184:187], v[4:7]
	v_mfma_f32_16x16x32_bf16 v[0:3], v[74:77], v[184:187], v[0:3]
	v_mfma_f32_16x16x32_bf16 v[28:31], v[66:69], v[188:191], v[28:31]
	v_mfma_f32_16x16x32_bf16 v[32:35], v[74:77], v[188:191], v[32:35]
	v_mfma_f32_16x16x32_bf16 v[40:43], v[66:69], v[206:209], v[40:43]
	v_mfma_f32_16x16x32_bf16 v[44:47], v[74:77], v[206:209], v[44:47]
	v_mfma_f32_16x16x32_bf16 v[48:51], v[66:69], v[210:213], v[48:51]
	v_mfma_f32_16x16x32_bf16 v[52:55], v[74:77], v[210:213], v[52:55]
	v_mfma_f32_16x16x32_bf16 v[56:59], v[66:69], v[214:217], v[56:59]
	v_mfma_f32_16x16x32_bf16 v[60:63], v[74:77], v[214:217], v[60:63]
	s_cbranch_scc1 .LBB0_1003
	s_add_i32 s9, s9, s8
	v_add_u32_e32 v64, s9, v96
	v_ashrrev_i32_e32 v65, 31, v64
	v_lshlrev_b64 v[64:65], 11, v[64:65]
	ds_write_b128 v157, v[36:39]
	ds_write_b128 v157, v[24:27] offset:1024
	ds_write_b128 v157, v[20:23] offset:2048
	ds_write_b128 v157, v[16:19] offset:3072
	ds_write_b128 v157, v[12:15] offset:4096
	ds_write_b128 v157, v[8:11] offset:5120
	ds_write_b128 v157, v[4:7] offset:6144
	ds_write_b128 v157, v[0:3] offset:7168
	ds_write_b128 v157, v[28:31] offset:8192
	ds_write_b128 v157, v[32:35] offset:9216
	ds_write_b128 v157, v[40:43] offset:10240
	ds_write_b128 v157, v[44:47] offset:11264
	ds_write_b128 v157, v[48:51] offset:12288
	ds_write_b128 v157, v[52:55] offset:13312
	ds_write_b128 v157, v[56:59] offset:14336
	ds_write_b128 v157, v[60:63] offset:15360
	v_lshl_add_u64 v[130:131], v[146:147], 0, v[64:65]
	s_waitcnt lgkmcnt(0)
	s_waitcnt lgkmcnt(0)
	s_barrier
	ds_read_b128 v[92:95], v158
	ds_read_b128 v[28:31], v158 offset:1024
	ds_read_b128 v[88:91], v158 offset:16384
	ds_read_b128 v[24:27], v158 offset:17408
	ds_read_b128 v[84:87], v158 offset:32768
	ds_read_b128 v[20:23], v158 offset:33792
	ds_read_b128 v[80:83], v158 offset:49152
	ds_read_b128 v[16:19], v158 offset:50176
	ds_read_b128 v[76:79], v159
	ds_read_b128 v[12:15], v160
	ds_read_b128 v[72:75], v161
	ds_read_b128 v[8:11], v162
	ds_read_b128 v[68:71], v163
	ds_read_b128 v[4:7], v164
	ds_read_b128 v[64:67], v165
	ds_read_b128 v[0:3], v166
	s_waitcnt lgkmcnt(0)
	v_mov_b32_e32 v32, 0
	s_mov_b64 s[0:1], 0
	v_mov_b32_e32 v33, v32
	v_mov_b32_e32 v34, v32
	v_mov_b32_e32 v35, v32
	v_mov_b32_e32 v36, v32
	v_mov_b32_e32 v37, v32
	v_mov_b32_e32 v38, v32
	v_mov_b32_e32 v39, v32
	v_mov_b32_e32 v40, v32
	v_mov_b32_e32 v41, v32
	v_mov_b32_e32 v42, v32
	v_mov_b32_e32 v43, v32
	v_mov_b32_e32 v44, v32
	v_mov_b32_e32 v45, v32
	v_mov_b32_e32 v46, v32
	v_mov_b32_e32 v47, v32
	v_mov_b32_e32 v48, v32
	v_mov_b32_e32 v49, v32
	v_mov_b32_e32 v50, v32
	v_mov_b32_e32 v51, v32
	v_mov_b32_e32 v52, v32
	v_mov_b32_e32 v53, v32
	v_mov_b32_e32 v54, v32
	v_mov_b32_e32 v55, v32
	v_mov_b32_e32 v56, v32
	v_mov_b32_e32 v57, v32
	v_mov_b32_e32 v58, v32
	v_mov_b32_e32 v59, v32
	v_mov_b32_e32 v102, v32
	v_mov_b32_e32 v103, v32
	v_mov_b32_e32 v104, v32
	v_mov_b32_e32 v105, v32
	v_mov_b32_e32 v60, v32
	v_mov_b32_e32 v61, v32
	v_mov_b32_e32 v62, v32
	v_mov_b32_e32 v63, v32
	v_mov_b32_e32 v98, v32
	v_mov_b32_e32 v99, v32
	v_mov_b32_e32 v100, v32
	v_mov_b32_e32 v101, v32
	v_mov_b32_e32 v106, v32
	v_mov_b32_e32 v107, v32
	v_mov_b32_e32 v108, v32
	v_mov_b32_e32 v109, v32
	v_mov_b32_e32 v110, v32
	v_mov_b32_e32 v111, v32
	v_mov_b32_e32 v112, v32
	v_mov_b32_e32 v113, v32
	v_mov_b32_e32 v114, v32
	v_mov_b32_e32 v115, v32
	v_mov_b32_e32 v116, v32
	v_mov_b32_e32 v117, v32
	v_mov_b32_e32 v118, v32
	v_mov_b32_e32 v119, v32
	v_mov_b32_e32 v120, v32
	v_mov_b32_e32 v121, v32
	v_mov_b32_e32 v122, v32
	v_mov_b32_e32 v123, v32
	v_mov_b32_e32 v124, v32
	v_mov_b32_e32 v125, v32
	v_mov_b32_e32 v126, v32
	v_mov_b32_e32 v127, v32
	v_mov_b32_e32 v128, v32
	v_mov_b32_e32 v129, v32
	s_waitcnt lgkmcnt(0)
	s_barrier
; #define LAS __attribute__((address_space(3)))
; template <int KSTEPS  >
; __device__ __forceinline__ void small_mma_ksplit(f32x4 (&acc)[2], const bf16_t* A, int lda, const bf16_t* Bt, int ldb, int n0, LAS unsigned char* lds, const SmallId& id) {
;     ...
; #pragma unroll 1
;     for (int ks = 0; ks < KSTEPS; ++ks) {
;         bf16x8 a[8], b[2];
; #pragma unroll
;         for (int rb = 0; rb < 8; ++rb) a[rb] = *(const bf16x8*)(ap + (size_t)(16 * rb) * lda + 32 * ks);
;         b[0] = *(const bf16x8*)(bp + 32 * ks); b[1] = *(const bf16x8*)(bp + (size_t)16 * ldb + 32 * ks);
; #pragma unroll
;         for (int rb = 0; rb < 8; ++rb) { part[rb][0] = __builtin_amdgcn_mfma_f32_16x16x32_bf16(b[0], a[rb], part[rb][0], 0, 0, 0); part[rb][1] = __builtin_amdgcn_mfma_f32_16x16x32_bf16(b[1], a[rb], part[rb][1], 0, 0, 0); }
;     }
;     LAS f32x4* red = (LAS f32x4*)lds;
; #pragma unroll
;     for (int rb = 0; rb < 8; ++rb) { red[((id.w * 8 + rb) * 2 + 0) * 64 + lane] = part[rb][0]; red[((id.w * 8 + rb) * 2 + 1) * 64 + lane] = part[rb][1]; }
;     asm volatile("s_waitcnt lgkmcnt(0)" ::: "memory"); __syncthreads();
;     acc[0] = (f32x4){0.f, 0.f, 0.f, 0.f}; acc[1] = acc[0];
; #pragma unroll
;     for (int w2 = 0; w2 < 8; ++w2) { acc[0] += red[((w2 * 8 + id.w) * 2 + 0) * 64 + lane]; acc[1] += red[((w2 * 8 + id.w) * 2 + 1) * 64 + lane]; }
;     asm volatile("s_waitcnt lgkmcnt(0)" ::: "memory"); __syncthreads();
; __device__ __forceinline__ void small_up(const Params& p, int l, LAS unsigned char* lds, int G, int bx) {
;     ...
;         const float rs = __builtin_amdgcn_rsqf(ssq[id.row] * (1.0f / 1024.0f) + EPS);
;         const int fr = id.fr;
; #pragma unroll
;         for (int nb = 0; nb < 2; ++nb) {
;             const int colg = c0 + 16 * nb + 4 * id.fq, colv = FF + colg;
;             const f32x4 cg_ = acc[nb] * rs, cv_ = acc[2 + nb] * rs;
;             f32x4 hg = (f32x4){0.f, 0.f, 0.f, 0.f}, hv = hg;
;             if (fr >= 14) { const float* sp = sconv + (size_t)(id.w * 2 + (fr - 14)) * FF2; hg = *(const f32x4*)(sp + colg); hv = *(const f32x4*)(sp + colv); }
.LBB0_1005:
	v_lshl_add_u64 v[136:137], v[148:149], 0, s[0:1]
	v_add_co_u32_e32 v150, vcc, s11, v136
	v_lshl_add_u64 v[132:133], v[130:131], 0, s[0:1]
	s_nop 1
	v_addc_co_u32_e32 v151, vcc, 0, v137, vcc
	v_add_co_u32_e32 v154, vcc, s12, v136
	s_add_u32 s0, s0, 64
	s_nop 1
	v_addc_co_u32_e32 v155, vcc, 0, v137, vcc
	v_add_co_u32_e32 v134, vcc, s26, v132
	s_addc_u32 s1, s1, 0
	s_nop 1
	v_addc_co_u32_e32 v135, vcc, 0, v133, vcc
	v_add_co_u32_e32 v168, vcc, s88, v132
	s_cmpk_lg_i32 s0, 0x100
	s_nop 1
	v_addc_co_u32_e32 v169, vcc, 0, v133, vcc
	global_load_dwordx4 v[132:135], v[134:135], off
	global_load_dwordx4 v[150:153], v[150:151], off
	global_load_dwordx4 v[168:171], v[168:169], off
	global_load_dwordx4 v[172:175], v[154:155], off
	v_add_co_u32_e32 v154, vcc, s13, v136
	s_nop 1
	v_addc_co_u32_e32 v155, vcc, 0, v137, vcc
	v_add_co_u32_e32 v176, vcc, s14, v136
	s_nop 1
	v_addc_co_u32_e32 v177, vcc, 0, v137, vcc
	global_load_dwordx4 v[180:183], v[154:155], off
	global_load_dwordx4 v[184:187], v[176:177], off
	v_add_co_u32_e32 v154, vcc, s15, v136
	s_nop 1
	v_addc_co_u32_e32 v155, vcc, 0, v137, vcc
	v_add_co_u32_e32 v176, vcc, s16, v136
	s_nop 1
	v_addc_co_u32_e32 v177, vcc, 0, v137, vcc
	global_load_dwordx4 v[188:191], v[154:155], off
	global_load_dwordx4 v[206:209], v[176:177], off
	v_add_co_u32_e32 v154, vcc, s17, v136
	s_nop 1
	v_addc_co_u32_e32 v155, vcc, 0, v137, vcc
	v_add_co_u32_e32 v136, vcc, s35, v136
	s_nop 1
	v_addc_co_u32_e32 v137, vcc, 0, v137, vcc
	global_load_dwordx4 v[210:213], v[154:155], off
	global_load_dwordx4 v[214:217], v[136:137], off
	s_waitcnt vmcnt(0) lgkmcnt(0)
	v_mfma_f32_16x16x32_bf16 v[102:105], v[132:135], v[150:153], v[102:105]
	v_mfma_f32_16x16x32_bf16 v[56:59], v[168:171], v[150:153], v[56:59]
	v_mfma_f32_16x16x32_bf16 v[52:55], v[132:135], v[172:175], v[52:55]
	v_mfma_f32_16x16x32_bf16 v[48:51], v[168:171], v[172:175], v[48:51]
	v_mfma_f32_16x16x32_bf16 v[44:47], v[132:135], v[180:183], v[44:47]
	v_mfma_f32_16x16x32_bf16 v[40:43], v[168:171], v[180:183], v[40:43]
	v_mfma_f32_16x16x32_bf16 v[36:39], v[132:135], v[184:187], v[36:39]
	v_mfma_f32_16x16x32_bf16 v[32:35], v[168:171], v[184:187], v[32:35]
	v_mfma_f32_16x16x32_bf16 v[60:63], v[132:135], v[188:191], v[60:63]
	v_mfma_f32_16x16x32_bf16 v[98:101], v[168:171], v[188:191], v[98:101]
	v_mfma_f32_16x16x32_bf16 v[106:109], v[132:135], v[206:209], v[106:109]
	v_mfma_f32_16x16x32_bf16 v[110:113], v[168:171], v[206:209], v[110:113]
	v_mfma_f32_16x16x32_bf16 v[114:117], v[132:135], v[210:213], v[114:117]
	v_mfma_f32_16x16x32_bf16 v[118:121], v[168:171], v[210:213], v[118:121]
	v_mfma_f32_16x16x32_bf16 v[122:125], v[132:135], v[214:217], v[122:125]
	v_mfma_f32_16x16x32_bf16 v[126:129], v[168:171], v[214:217], v[126:129]
	s_cbranch_scc1 .LBB0_1005
	ds_write_b128 v157, v[102:105]
	ds_write_b128 v157, v[56:59] offset:1024
	ds_write_b128 v157, v[52:55] offset:2048
	ds_write_b128 v157, v[48:51] offset:3072
	ds_write_b128 v157, v[44:47] offset:4096
	ds_write_b128 v157, v[40:43] offset:5120
	ds_write_b128 v157, v[36:39] offset:6144
	ds_write_b128 v157, v[32:35] offset:7168
	ds_write_b128 v157, v[60:63] offset:8192
	ds_write_b128 v157, v[98:101] offset:9216
	ds_write_b128 v157, v[106:109] offset:10240
	ds_write_b128 v157, v[110:113] offset:11264
	ds_write_b128 v157, v[114:117] offset:12288
	ds_write_b128 v157, v[118:121] offset:13312
	ds_write_b128 v157, v[122:125] offset:14336
	ds_write_b128 v157, v[126:129] offset:15360
	s_waitcnt lgkmcnt(0)
	s_waitcnt lgkmcnt(0)
	s_barrier
	ds_read_b128 v[106:109], v158
	ds_read_b128 v[52:55], v158 offset:1024
	ds_read_b128 v[110:113], v158 offset:16384
	ds_read_b128 v[56:59], v158 offset:17408
	ds_read_b128 v[114:117], v158 offset:32768
	ds_read_b128 v[60:63], v158 offset:33792
	ds_read_b128 v[118:121], v158 offset:49152
	ds_read_b128 v[32:35], v158 offset:50176
	ds_read_b128 v[122:125], v159
	ds_read_b128 v[36:39], v160
	ds_read_b128 v[126:129], v161
	ds_read_b128 v[40:43], v162
	ds_read_b128 v[130:133], v163
	ds_read_b128 v[44:47], v164
	ds_read_b128 v[134:137], v165
	ds_read_b128 v[48:51], v166
	s_waitcnt lgkmcnt(0)
	s_waitcnt lgkmcnt(0)
	s_barrier
	global_load_dword v168, v[138:139], off
	v_lshl_or_b32 v150, s7, 5, v167
	v_add_u32_e32 v154, 0xb00, v150
	v_ashrrev_i32_e32 v155, 31, v154
	s_and_saveexec_b64 s[0:1], s[48:49]
	s_xor_b64 s[0:1], exec, s[0:1]
	s_or_saveexec_b64 s[0:1], s[0:1]
	v_ashrrev_i32_e32 v151, 31, v150
	v_mov_b32_e32 v98, 0
	v_lshl_add_u64 v[152:153], v[150:151], 2, v[140:141]
	v_mov_b32_e32 v99, 0
	v_mov_b32_e32 v100, 0
	v_mov_b32_e32 v101, 0
	v_mov_b32_e32 v102, 0
	v_mov_b32_e32 v103, 0
	v_mov_b32_e32 v104, 0
	v_mov_b32_e32 v105, 0
	s_xor_b64 exec, exec, s[0:1]
	s_cbranch_execz .LBB0_1008
	v_add_co_u32_e32 v98, vcc, 0x2000, v152
	s_nop 1
	v_addc_co_u32_e32 v99, vcc, 0, v153, vcc
	global_load_dwordx4 v[102:105], v[152:153], off
	s_nop 0
	global_load_dwordx4 v[98:101], v[98:99], off offset:3072
; __device__ __forceinline__ float ror1(float x) { return __builtin_bit_cast(float, __builtin_amdgcn_update_dpp(0, __builtin_bit_cast(int, x), 0x121, 0xf, 0xf, false)); }
; __device__ __forceinline__ float ror2(float x) { return __builtin_bit_cast(float, __builtin_amdgcn_update_dpp(0, __builtin_bit_cast(int, x), 0x122, 0xf, 0xf, false)); }
; __device__ __forceinline__ void small_up(const Params& p, int l, LAS unsigned char* lds, int G, int bx) {
;     ...
;         const float rs = __builtin_amdgcn_rsqf(ssq[id.row] * (1.0f / 1024.0f) + EPS);
;         const int fr = id.fr;
; #pragma unroll
;         for (int nb = 0; nb < 2; ++nb) {
;             const int colg = c0 + 16 * nb + 4 * id.fq, colv = FF + colg;
;             const f32x4 cg_ = acc[nb] * rs, cv_ = acc[2 + nb] * rs;
;             f32x4 hg = (f32x4){0.f, 0.f, 0.f, 0.f}, hv = hg;
;             if (fr >= 14) { const float* sp = sconv + (size_t)(id.w * 2 + (fr - 14)) * FF2; hg = *(const f32x4*)(sp + colg); hv = *(const f32x4*)(sp + colv); }
;             const f32x4 w0g = *(const f32x4*)(cw + colg), w1g = *(const f32x4*)(cw + FF2 + colg), w2g = *(const f32x4*)(cw + 2 * FF2 + colg), bg = *(const f32x4*)(cb + colg);
;             const f32x4 w0v = *(const f32x4*)(cw + colv), w1v = *(const f32x4*)(cw + FF2 + colv), w2v = *(const f32x4*)(cw + 2 * FF2 + colv), bv = *(const f32x4*)(cb + colv);
;             f32x4 p1g, p2g, p1v, p2v;
; #pragma unroll
;             for (int j = 0; j < 4; ++j) {
;                 p1g[j] = ror1(fr == 15 ? hg[j] : cg_[j]); p2g[j] = ror2(fr >= 14 ? hg[j] : cg_[j]);
;                 p1v[j] = ror1(fr == 15 ? hv[j] : cv_[j]); p2v[j] = ror2(fr >= 14 ? hv[j] : cv_[j]);
;             }
;             const f32x4 hcg = bg + w0g * p2g + w1g * p1g + w2g * cg_;
;             const f32x4 hcv = bv + w0v * p2v + w1v * p1v + w2v * cv_;
.LBB0_1008:
	s_or_b64 exec, exec, s[0:1]
	v_pk_add_f32 v[94:95], v[94:95], 0 op_sel_hi:[1,0]
	v_pk_add_f32 v[92:93], v[92:93], 0 op_sel_hi:[1,0]
	v_pk_add_f32 v[90:91], v[94:95], v[90:91]
	v_pk_add_f32 v[88:89], v[92:93], v[88:89]
	v_pk_add_f32 v[86:87], v[90:91], v[86:87]
	v_pk_add_f32 v[84:85], v[88:89], v[84:85]
	v_pk_add_f32 v[82:83], v[86:87], v[82:83]
	v_pk_add_f32 v[80:81], v[84:85], v[80:81]
	v_pk_add_f32 v[78:79], v[82:83], v[78:79]
	v_pk_add_f32 v[76:77], v[80:81], v[76:77]
	v_pk_add_f32 v[74:75], v[78:79], v[74:75]
	v_pk_add_f32 v[72:73], v[76:77], v[72:73]
	v_pk_add_f32 v[70:71], v[74:75], v[70:71]
	v_pk_add_f32 v[68:69], v[72:73], v[68:69]
	v_pk_add_f32 v[66:67], v[70:71], v[66:67]
	v_pk_add_f32 v[70:71], v[106:107], 0 op_sel_hi:[1,0]
	v_pk_add_f32 v[64:65], v[68:69], v[64:65]
	v_pk_add_f32 v[70:71], v[70:71], v[110:111]
	v_pk_add_f32 v[68:69], v[108:109], 0 op_sel_hi:[1,0]
	v_pk_add_f32 v[70:71], v[70:71], v[114:115]
	v_pk_add_f32 v[68:69], v[68:69], v[112:113]
	v_pk_add_f32 v[70:71], v[70:71], v[118:119]
	v_pk_add_f32 v[68:69], v[68:69], v[116:117]
	v_pk_add_f32 v[70:71], v[70:71], v[122:123]
	v_pk_add_f32 v[68:69], v[68:69], v[120:121]
	v_pk_add_f32 v[70:71], v[70:71], v[126:127]
	v_pk_add_f32 v[68:69], v[68:69], v[124:125]
	v_pk_add_f32 v[70:71], v[70:71], v[130:131]
	v_pk_add_f32 v[68:69], v[68:69], v[128:129]
	v_pk_add_f32 v[74:75], v[70:71], v[134:135]
	s_waitcnt vmcnt(0) lgkmcnt(0)
	v_fmamk_f32 v70, v168, 0x3a800000, v223
	v_rsq_f32_e32 v72, v70
	v_pk_add_f32 v[68:69], v[68:69], v[132:133]
	v_lshlrev_b64 v[76:77], 2, v[150:151]
	v_pk_add_f32 v[68:69], v[68:69], v[136:137]
	v_lshl_add_u64 v[82:83], s[42:43], 0, v[76:77]
	v_pk_mul_f32 v[70:71], v[68:69], v[72:73] op_sel_hi:[1,0]
	v_pk_mul_f32 v[68:69], v[74:75], v[72:73] op_sel_hi:[1,0]
	v_lshl_add_u64 v[74:75], s[40:41], 0, v[76:77]
	v_lshl_add_u64 v[86:87], s[94:95], 0, v[76:77]
	v_lshl_add_u64 v[76:77], s[44:45], 0, v[76:77]
	global_load_dwordx4 v[78:81], v[74:75], off
	global_load_dwordx4 v[90:93], v[76:77], off
	v_lshlrev_b64 v[94:95], 2, v[154:155]
	global_load_dwordx4 v[82:85], v[82:83], off
	v_lshl_add_u64 v[106:107], s[40:41], 0, v[94:95]
	global_load_dwordx4 v[86:89], v[86:87], off
	v_lshl_add_u64 v[110:111], s[42:43], 0, v[94:95]
	v_lshl_add_u64 v[114:115], s[94:95], 0, v[94:95]
	v_lshl_add_u64 v[94:95], s[44:45], 0, v[94:95]
	global_load_dwordx4 v[106:109], v[106:107], off
	v_pk_mul_f32 v[64:65], v[64:65], v[72:73] op_sel_hi:[1,0]
	global_load_dwordx4 v[118:121], v[94:95], off
	v_pk_mul_f32 v[66:67], v[66:67], v[72:73] op_sel_hi:[1,0]
	global_load_dwordx4 v[110:113], v[110:111], off
	v_cndmask_b32_e64 v73, v64, v102, s[50:51]
	global_load_dwordx4 v[114:117], v[114:115], off
	v_mov_b32_e32 v94, v97
	v_mov_b32_e32 v122, v97
	v_mov_b32_e32 v95, v97
	v_mov_b32_dpp v94, v73 row_ror:1 row_mask:0xf bank_mask:0xf
	v_cndmask_b32_e64 v73, v64, v102, s[46:47]
	v_mov_b32_e32 v102, v97
	v_mov_b32_e32 v123, v97
	v_mov_b32_e32 v124, v97
	v_mov_b32_dpp v102, v73 row_ror:2 row_mask:0xf bank_mask:0xf
	v_cndmask_b32_e64 v73, v68, v98, s[50:51]
	v_mov_b32_e32 v126, v97
	v_mov_b32_e32 v125, v97
	v_mov_b32_dpp v122, v73 row_ror:1 row_mask:0xf bank_mask:0xf
	v_cndmask_b32_e64 v73, v68, v98, s[46:47]
	v_mov_b32_e32 v98, v97
	s_mov_b32 s0, 0xbf3a00e3
	v_mov_b32_e32 v127, v97
	v_mov_b32_dpp v98, v73 row_ror:2 row_mask:0xf bank_mask:0xf
	v_cndmask_b32_e64 v73, v65, v103, s[50:51]
	s_nop 1
	v_mov_b32_dpp v95, v73 row_ror:1 row_mask:0xf bank_mask:0xf
	v_cndmask_b32_e64 v73, v65, v103, s[46:47]
	v_mov_b32_e32 v103, v97
	s_nop 1
	v_mov_b32_dpp v103, v73 row_ror:2 row_mask:0xf bank_mask:0xf
	v_cndmask_b32_e64 v73, v69, v99, s[50:51]
	s_waitcnt vmcnt(6)
	v_pk_fma_f32 v[78:79], v[78:79], v[102:103], v[90:91]
	v_mov_b32_dpp v123, v73 row_ror:1 row_mask:0xf bank_mask:0xf
	v_cndmask_b32_e64 v73, v69, v99, s[46:47]
	v_mov_b32_e32 v99, v97
	s_waitcnt vmcnt(5)
	v_pk_fma_f32 v[78:79], v[82:83], v[94:95], v[78:79]
	v_mov_b32_dpp v99, v73 row_ror:2 row_mask:0xf bank_mask:0xf
	v_cndmask_b32_e64 v73, v66, v104, s[50:51]
	s_waitcnt vmcnt(4)
; __device__ __forceinline__ unsigned cvt_pk_bf16(float lo, float hi) { unsigned r; asm volatile("v_cvt_pk_bf16_f32 %0, %1, %2" : "=v"(r) : "v"(lo), "v"(hi)); return r; }
; __device__ __forceinline__ f32x2 gelu_pk(f32x2 v) {
;     const f32x2 av = __builtin_elementwise_abs(v), d = av * 0.2316418882f + 1.0f;
;     f32x2 t; t.x = __builtin_amdgcn_rcpf(d.x); t.y = __builtin_amdgcn_rcpf(d.y);
;     f32x2 q = t * 0.5307027145f + (-0.7265760135f); q = q * t + 0.7107068705f; q = q * t + (-0.142248368f); q = q * t + 0.127414796f; q = q * t;
;     const f32x2 s = (v * v) * (-0.72134752044f);
;     f32x2 e; e.x = __builtin_amdgcn_exp2f(s.x); e.y = __builtin_amdgcn_exp2f(s.y);
;     const f32x2 m = v * (q * e), r = v - m;
;     f32x2 o; o.x = v.x < 0.f ? m.x : r.x; o.y = v.y < 0.f ? m.y : r.y; return o;
; }
; __device__ __forceinline__ void small_up(const Params& p, int l, LAS unsigned char* lds, int G, int bx) {
;     ...
;             const f32x4 hcg = bg + w0g * p2g + w1g * p1g + w2g * cg_;
;             const f32x4 hcv = bv + w0v * p2v + w1v * p1v + w2v * cv_;
;             const f32x2 ga = gelu_pk((f32x2){hcg[0], hcg[1]}), gb2 = gelu_pk((f32x2){hcg[2], hcg[3]});
;             u32x2 w; w.x = cvt_pk_bf16(ga.x * hcv[0], ga.y * hcv[1]); w.y = cvt_pk_bf16(gb2.x * hcv[2], gb2.y * hcv[3]);
;             *(u32x2*)(U + (size_t)id.row * FF + colg) = w;
;             if (fr >= 14) { float* cp = conv_s + (size_t)(id.w * 2 + (fr - 14)) * FF2; *(f32x4*)(cp + colg) = cg_; *(f32x4*)(cp + colv) = cv_; }
	v_pk_fma_f32 v[78:79], v[64:65], v[86:87], v[78:79]
	v_mov_b32_dpp v124, v73 row_ror:1 row_mask:0xf bank_mask:0xf
	v_cndmask_b32_e64 v73, v66, v104, s[46:47]
	v_mov_b32_e32 v104, v97
	v_and_b32_e32 v87, 0x7fffffff, v79
	v_and_b32_e32 v86, 0x7fffffff, v78
	v_mov_b32_dpp v104, v73 row_ror:2 row_mask:0xf bank_mask:0xf
	v_cndmask_b32_e64 v73, v70, v100, s[50:51]
	v_pk_fma_f32 v[86:87], v[86:87], s[6:7], 1.0 op_sel_hi:[1,0,0]
	v_cmp_gt_f32_e32 vcc, 0, v78
	v_mov_b32_dpp v126, v73 row_ror:1 row_mask:0xf bank_mask:0xf
	v_cndmask_b32_e64 v73, v70, v100, s[46:47]
	v_mov_b32_e32 v100, v97
	v_rcp_f32_e32 v86, v86
	v_rcp_f32_e32 v87, v87
	v_mov_b32_dpp v100, v73 row_ror:2 row_mask:0xf bank_mask:0xf
	v_cndmask_b32_e64 v73, v67, v105, s[50:51]
	s_nop 1
	v_mov_b32_dpp v125, v73 row_ror:1 row_mask:0xf bank_mask:0xf
	v_cndmask_b32_e64 v73, v67, v105, s[46:47]
	v_mov_b32_e32 v105, v97
	s_nop 1
	v_mov_b32_dpp v105, v73 row_ror:2 row_mask:0xf bank_mask:0xf
	v_pk_fma_f32 v[80:81], v[80:81], v[104:105], v[92:93]
	v_pk_mul_f32 v[92:93], v[78:79], v[78:79]
	v_pk_fma_f32 v[80:81], v[84:85], v[124:125], v[80:81]
	v_pk_mul_f32 v[92:93], v[92:93], s[36:37] op_sel_hi:[1,0]
	v_pk_fma_f32 v[80:81], v[66:67], v[88:89], v[80:81]
	v_mov_b64_e32 v[88:89], s[0:1]
	v_pk_fma_f32 v[90:91], v[86:87], s[24:25], v[88:89] op_sel_hi:[1,0,0]
	v_exp_f32_e32 v92, v92
	v_pk_fma_f32 v[90:91], v[86:87], v[90:91], s[28:29] op_sel_hi:[1,1,0]
	v_exp_f32_e32 v93, v93
	v_pk_fma_f32 v[90:91], v[86:87], v[90:91], s[30:31] op_sel_hi:[1,1,0]
	v_cndmask_b32_e64 v73, v71, v101, s[50:51]
	v_pk_fma_f32 v[90:91], v[86:87], v[90:91], s[34:35] op_sel_hi:[1,1,0]
	s_waitcnt vmcnt(2)
	v_pk_fma_f32 v[84:85], v[106:107], v[98:99], v[118:119]
	v_pk_mul_f32 v[86:87], v[86:87], v[90:91]
	v_mov_b32_dpp v127, v73 row_ror:1 row_mask:0xf bank_mask:0xf
	v_pk_mul_f32 v[86:87], v[92:93], v[86:87]
	v_cndmask_b32_e64 v73, v71, v101, s[46:47]
	v_mov_b32_e32 v101, v97
	v_pk_mul_f32 v[92:93], v[78:79], v[86:87]
	v_pk_fma_f32 v[86:87], v[78:79], v[86:87], v[78:79] neg_lo:[1,0,0] neg_hi:[1,0,0]
	v_mov_b32_dpp v101, v73 row_ror:2 row_mask:0xf bank_mask:0xf
	v_cndmask_b32_e32 v73, v86, v92, vcc
	v_cmp_gt_f32_e32 vcc, 0, v79
	v_and_b32_e32 v79, 0x7fffffff, v81
	v_and_b32_e32 v78, 0x7fffffff, v80
	v_pk_fma_f32 v[78:79], v[78:79], s[6:7], 1.0 op_sel_hi:[1,0,0]
	v_cndmask_b32_e32 v92, v87, v93, vcc
	v_rcp_f32_e32 v78, v78
	v_rcp_f32_e32 v79, v79
	v_pk_mul_f32 v[90:91], v[80:81], v[80:81]
	v_pk_fma_f32 v[82:83], v[108:109], v[100:101], v[120:121]
	v_cmp_gt_f32_e32 vcc, 0, v80
	v_pk_fma_f32 v[86:87], v[78:79], s[24:25], v[88:89] op_sel_hi:[1,0,0]
	s_waitcnt vmcnt(1)
	v_pk_fma_f32 v[82:83], v[112:113], v[126:127], v[82:83]
	v_pk_fma_f32 v[86:87], v[78:79], v[86:87], s[28:29] op_sel_hi:[1,1,0]
	v_pk_fma_f32 v[84:85], v[110:111], v[122:123], v[84:85]
	v_pk_fma_f32 v[86:87], v[78:79], v[86:87], s[30:31] op_sel_hi:[1,1,0]
	s_waitcnt vmcnt(0)
	v_pk_fma_f32 v[82:83], v[70:71], v[116:117], v[82:83]
	v_pk_fma_f32 v[86:87], v[78:79], v[86:87], s[34:35] op_sel_hi:[1,1,0]
	v_pk_fma_f32 v[84:85], v[68:69], v[114:115], v[84:85]
	v_pk_mul_f32 v[78:79], v[78:79], v[86:87]
	v_pk_mul_f32 v[86:87], v[90:91], s[36:37] op_sel_hi:[1,0]
	v_mul_f32_e32 v73, v84, v73
	v_exp_f32_e32 v86, v86
	v_exp_f32_e32 v87, v87
	s_nop 0
	v_pk_mul_f32 v[78:79], v[86:87], v[78:79]
	s_nop 0
	v_pk_mul_f32 v[86:87], v[80:81], v[78:79]
	v_pk_fma_f32 v[78:79], v[80:81], v[78:79], v[80:81] neg_lo:[1,0,0] neg_hi:[1,0,0]
	s_nop 0
	v_cndmask_b32_e32 v80, v78, v86, vcc
	v_cmp_gt_f32_e32 vcc, 0, v81
	v_mul_f32_e32 v78, v85, v92
	v_cvt_pk_bf16_f32 v78, v73, v78
	v_mul_f32_e32 v73, v82, v80
	v_cndmask_b32_e32 v79, v79, v87, vcc
	v_mul_f32_e32 v79, v83, v79
	v_cvt_pk_bf16_f32 v79, v73, v79
	v_lshl_add_u64 v[80:81], v[150:151], 1, v[142:143]
	global_store_dwordx2 v[80:81], v[78:79], off
	v_lshl_add_u64 v[78:79], v[150:151], 2, v[144:145]
	s_and_saveexec_b64 s[0:1], s[46:47]
	s_cbranch_execz .LBB0_1010
	v_lshl_add_u64 v[82:83], v[154:155], 2, v[144:145]
	global_store_dwordx4 v[78:79], v[64:67], off
	global_store_dwordx4 v[82:83], v[68:71], off

; template <int KSTEPS  >
; __device__ __forceinline__ void small_mma_ksplit(f32x4 (&acc)[2], const bf16_t* A, int lda, const bf16_t* Bt, int ldb, int n0, LAS unsigned char* lds, const SmallId& id) {
;     ...
;     acc[0] = (f32x4){0.f, 0.f, 0.f, 0.f}; acc[1] = acc[0];
; #pragma unroll
;     for (int w2 = 0; w2 < 8; ++w2) { acc[0] += red[((w2 * 8 + id.w) * 2 + 0) * 64 + lane]; acc[1] += red[((w2 * 8 + id.w) * 2 + 1) * 64 + lane]; }
; __device__ __forceinline__ void small_up(const Params& p, int l, LAS unsigned char* lds, int G, int bx) {
;     ...
;         for (int nb = 0; nb < 2; ++nb) {
;             const int colg = c0 + 16 * nb + 4 * id.fq, colv = FF + colg;
;             const f32x4 cg_ = acc[nb] * rs, cv_ = acc[2 + nb] * rs;
;             f32x4 hg = (f32x4){0.f, 0.f, 0.f, 0.f}, hv = hg;
;             if (fr >= 14) { const float* sp = sconv + (size_t)(id.w * 2 + (fr - 14)) * FF2; hg = *(const f32x4*)(sp + colg); hv = *(const f32x4*)(sp + colv); }
;             const f32x4 w0g = *(const f32x4*)(cw + colg), w1g = *(const f32x4*)(cw + FF2 + colg), w2g = *(const f32x4*)(cw + 2 * FF2 + colg), bg = *(const f32x4*)(cb + colg);
;             const f32x4 w0v = *(const f32x4*)(cw + colv), w1v = *(const f32x4*)(cw + FF2 + colv), w2v = *(const f32x4*)(cw + 2 * FF2 + colv), bv = *(const f32x4*)(cb + colv);
.LBB0_1014:
	s_or_b64 exec, exec, s[0:1]
	v_pk_add_f32 v[30:31], v[30:31], 0 op_sel_hi:[1,0]
	v_pk_add_f32 v[28:29], v[28:29], 0 op_sel_hi:[1,0]
	v_pk_add_f32 v[26:27], v[30:31], v[26:27]
	v_pk_add_f32 v[24:25], v[28:29], v[24:25]
	v_pk_add_f32 v[22:23], v[26:27], v[22:23]
	v_pk_add_f32 v[20:21], v[24:25], v[20:21]
	v_pk_add_f32 v[18:19], v[22:23], v[18:19]
	v_pk_add_f32 v[16:17], v[20:21], v[16:17]
	v_pk_add_f32 v[14:15], v[18:19], v[14:15]
	v_pk_add_f32 v[12:13], v[16:17], v[12:13]
	v_pk_add_f32 v[10:11], v[14:15], v[10:11]
	v_pk_add_f32 v[8:9], v[12:13], v[8:9]
	v_pk_add_f32 v[6:7], v[10:11], v[6:7]
	v_pk_add_f32 v[4:5], v[8:9], v[4:5]
	v_pk_add_f32 v[2:3], v[6:7], v[2:3]
	v_or_b32_e32 v6, 16, v150
	v_ashrrev_i32_e32 v7, 31, v6
	global_load_dwordx4 v[8:11], v[74:75], off offset:64
	v_lshlrev_b64 v[6:7], 2, v[6:7]
	v_lshl_add_u64 v[16:17], s[42:43], 0, v[6:7]
	v_lshl_add_u64 v[6:7], s[94:95], 0, v[6:7]
	global_load_dwordx4 v[12:15], v[76:77], off offset:64
	s_nop 0
	global_load_dwordx4 v[16:19], v[16:17], off
	s_nop 0
	global_load_dwordx4 v[20:23], v[6:7], off
	v_lshlrev_b64 v[6:7], 2, v[82:83]
	v_lshl_add_u64 v[24:25], s[40:41], 0, v[6:7]
	v_lshl_add_u64 v[28:29], s[44:45], 0, v[6:7]
	global_load_dwordx4 v[24:27], v[24:25], off
	v_pk_add_f32 v[0:1], v[4:5], v[0:1]
	global_load_dwordx4 v[28:31], v[28:29], off
	v_pk_add_f32 v[4:5], v[54:55], 0 op_sel_hi:[1,0]
	v_lshl_add_u64 v[54:55], s[42:43], 0, v[6:7]
	v_pk_add_f32 v[52:53], v[52:53], 0 op_sel_hi:[1,0]
	global_load_dwordx4 v[74:77], v[54:55], off
	v_pk_add_f32 v[52:53], v[52:53], v[56:57]
	v_lshl_add_u64 v[6:7], s[94:95], 0, v[6:7]
	v_pk_add_f32 v[56:57], v[52:53], v[60:61]
	global_load_dwordx4 v[52:55], v[6:7], off
	v_pk_add_f32 v[4:5], v[4:5], v[58:59]
	v_pk_add_f32 v[6:7], v[56:57], v[32:33]
	v_pk_add_f32 v[4:5], v[4:5], v[62:63]
	v_pk_add_f32 v[6:7], v[6:7], v[36:37]
	v_pk_add_f32 v[4:5], v[4:5], v[34:35]
	v_pk_add_f32 v[6:7], v[6:7], v[40:41]
	v_pk_add_f32 v[4:5], v[4:5], v[38:39]
	v_mov_b32_e32 v73, v72
	v_pk_add_f32 v[4:5], v[4:5], v[42:43]
	v_pk_add_f32 v[6:7], v[6:7], v[44:45]
	v_pk_add_f32 v[4:5], v[4:5], v[46:47]
	v_pk_add_f32 v[32:33], v[6:7], v[48:49]
	v_pk_add_f32 v[4:5], v[4:5], v[50:51]
	v_mov_b32_e32 v6, v72
	v_mov_b32_e32 v7, v72
	v_pk_mul_f32 v[0:1], v[0:1], v[72:73]
	v_pk_mul_f32 v[2:3], v[2:3], v[6:7]
	v_pk_mul_f32 v[6:7], v[4:5], v[6:7]
	v_pk_mul_f32 v[4:5], v[32:33], v[72:73]
	s_waitcnt vmcnt(0)
; __device__ __forceinline__ unsigned cvt_pk_bf16(float lo, float hi) { unsigned r; asm volatile("v_cvt_pk_bf16_f32 %0, %1, %2" : "=v"(r) : "v"(lo), "v"(hi)); return r; }
; __device__ __forceinline__ float ror1(float x) { return __builtin_bit_cast(float, __builtin_amdgcn_update_dpp(0, __builtin_bit_cast(int, x), 0x121, 0xf, 0xf, false)); }
; __device__ __forceinline__ float ror2(float x) { return __builtin_bit_cast(float, __builtin_amdgcn_update_dpp(0, __builtin_bit_cast(int, x), 0x122, 0xf, 0xf, false)); }
; __device__ __forceinline__ f32x2 gelu_pk(f32x2 v) {
;     const f32x2 av = __builtin_elementwise_abs(v), d = av * 0.2316418882f + 1.0f;
;     f32x2 t; t.x = __builtin_amdgcn_rcpf(d.x); t.y = __builtin_amdgcn_rcpf(d.y);
;     f32x2 q = t * 0.5307027145f + (-0.7265760135f); q = q * t + 0.7107068705f; q = q * t + (-0.142248368f); q = q * t + 0.127414796f; q = q * t;
;     const f32x2 s = (v * v) * (-0.72134752044f);
;     f32x2 e; e.x = __builtin_amdgcn_exp2f(s.x); e.y = __builtin_amdgcn_exp2f(s.y);
;     const f32x2 m = v * (q * e), r = v - m;
;     f32x2 o; o.x = v.x < 0.f ? m.x : r.x; o.y = v.y < 0.f ? m.y : r.y; return o;
; }
; __device__ __forceinline__ void small_up(const Params& p, int l, LAS unsigned char* lds, int G, int bx) {
;     ...
;             f32x4 p1g, p2g, p1v, p2v;
; #pragma unroll
;             for (int j = 0; j < 4; ++j) {
;                 p1g[j] = ror1(fr == 15 ? hg[j] : cg_[j]); p2g[j] = ror2(fr >= 14 ? hg[j] : cg_[j]);
;                 p1v[j] = ror1(fr == 15 ? hv[j] : cv_[j]); p2v[j] = ror2(fr >= 14 ? hv[j] : cv_[j]);
;             }
;             const f32x4 hcg = bg + w0g * p2g + w1g * p1g + w2g * cg_;
;             const f32x4 hcv = bv + w0v * p2v + w1v * p1v + w2v * cv_;
;             const f32x2 ga = gelu_pk((f32x2){hcg[0], hcg[1]}), gb2 = gelu_pk((f32x2){hcg[2], hcg[3]});
;             u32x2 w; w.x = cvt_pk_bf16(ga.x * hcv[0], ga.y * hcv[1]); w.y = cvt_pk_bf16(gb2.x * hcv[2], gb2.y * hcv[3]);
;             *(u32x2*)(U + (size_t)id.row * FF + colg) = w;
;             if (fr >= 14) { float* cp = conv_s + (size_t)(id.w * 2 + (fr - 14)) * FF2; *(f32x4*)(cp + colg) = cg_; *(f32x4*)(cp + colv) = cv_; }
;         }
	v_cndmask_b32_e64 v33, v0, v68, s[50:51]
	v_mov_b32_e32 v32, v97
	v_mov_b32_e32 v34, v97
	v_mov_b32_e32 v36, v97
	v_mov_b32_dpp v32, v33 row_ror:1 row_mask:0xf bank_mask:0xf
	v_cndmask_b32_e64 v33, v0, v68, s[46:47]
	v_mov_b32_e32 v38, v97
	v_cndmask_b32_e64 v35, v1, v69, s[50:51]
	v_mov_b32_dpp v34, v33 row_ror:2 row_mask:0xf bank_mask:0xf
	v_cndmask_b32_e64 v33, v4, v64, s[50:51]
	v_cndmask_b32_e64 v37, v1, v69, s[46:47]
	v_cndmask_b32_e64 v39, v5, v65, s[50:51]
	v_mov_b32_dpp v36, v33 row_ror:1 row_mask:0xf bank_mask:0xf
	v_cndmask_b32_e64 v33, v4, v64, s[46:47]
	v_cndmask_b32_e64 v40, v5, v65, s[46:47]
	v_cndmask_b32_e64 v41, v2, v70, s[50:51]
	v_mov_b32_dpp v38, v33 row_ror:2 row_mask:0xf bank_mask:0xf
	v_mov_b32_e32 v33, v97
	v_mov_b32_e32 v42, v97
	v_mov_b32_e32 v44, v97
	v_mov_b32_dpp v33, v35 row_ror:1 row_mask:0xf bank_mask:0xf
	v_mov_b32_e32 v35, v97
	v_mov_b32_e32 v46, v97
	v_cndmask_b32_e64 v43, v3, v71, s[50:51]
	v_mov_b32_dpp v35, v37 row_ror:2 row_mask:0xf bank_mask:0xf
	v_mov_b32_e32 v37, v97
	v_cndmask_b32_e64 v45, v3, v71, s[46:47]
	s_mov_b32 s0, 0xbf3a00e3
	v_mov_b32_dpp v37, v39 row_ror:1 row_mask:0xf bank_mask:0xf
	v_mov_b32_e32 v39, v97
	v_cndmask_b32_e64 v47, v7, v67, s[50:51]
	v_cndmask_b32_e64 v48, v7, v67, s[46:47]
	v_mov_b32_dpp v39, v40 row_ror:2 row_mask:0xf bank_mask:0xf
	v_mov_b32_e32 v40, v97
	v_pk_fma_f32 v[8:9], v[8:9], v[34:35], v[12:13]
	s_nop 0
	v_mov_b32_dpp v40, v41 row_ror:1 row_mask:0xf bank_mask:0xf
	v_cndmask_b32_e64 v41, v2, v70, s[46:47]
	v_pk_fma_f32 v[8:9], v[16:17], v[32:33], v[8:9]
	s_nop 0
	v_mov_b32_dpp v42, v41 row_ror:2 row_mask:0xf bank_mask:0xf
	v_cndmask_b32_e64 v41, v6, v66, s[50:51]
	v_pk_fma_f32 v[8:9], v[0:1], v[20:21], v[8:9]
	s_nop 0
	v_mov_b32_dpp v44, v41 row_ror:1 row_mask:0xf bank_mask:0xf
	v_cndmask_b32_e64 v41, v6, v66, s[46:47]
	v_and_b32_e32 v17, 0x7fffffff, v9
	v_and_b32_e32 v16, 0x7fffffff, v8
	v_mov_b32_dpp v46, v41 row_ror:2 row_mask:0xf bank_mask:0xf
	v_mov_b32_e32 v41, v97
	v_pk_fma_f32 v[16:17], v[16:17], s[6:7], 1.0 op_sel_hi:[1,0,0]
	v_cmp_gt_f32_e32 vcc, 0, v8
	v_mov_b32_dpp v41, v43 row_ror:1 row_mask:0xf bank_mask:0xf
	v_mov_b32_e32 v43, v97
	v_rcp_f32_e32 v16, v16
	v_rcp_f32_e32 v17, v17
	v_mov_b32_dpp v43, v45 row_ror:2 row_mask:0xf bank_mask:0xf
	v_pk_fma_f32 v[10:11], v[10:11], v[42:43], v[14:15]
	v_pk_fma_f32 v[14:15], v[24:25], v[38:39], v[28:29]
	v_pk_fma_f32 v[10:11], v[18:19], v[40:41], v[10:11]
	v_mov_b64_e32 v[18:19], s[0:1]
	v_pk_fma_f32 v[10:11], v[2:3], v[22:23], v[10:11]
	v_pk_mul_f32 v[22:23], v[8:9], v[8:9]
	v_pk_fma_f32 v[20:21], v[16:17], s[24:25], v[18:19] op_sel_hi:[1,0,0]
	v_pk_mul_f32 v[22:23], v[22:23], s[36:37] op_sel_hi:[1,0]
	v_pk_fma_f32 v[20:21], v[16:17], v[20:21], s[28:29] op_sel_hi:[1,1,0]
	v_exp_f32_e32 v22, v22
	v_exp_f32_e32 v23, v23
	v_pk_fma_f32 v[20:21], v[16:17], v[20:21], s[30:31] op_sel_hi:[1,1,0]
	v_and_b32_e32 v25, 0x7fffffff, v11
	v_and_b32_e32 v24, 0x7fffffff, v10
	v_pk_fma_f32 v[20:21], v[16:17], v[20:21], s[34:35] op_sel_hi:[1,1,0]
	v_pk_fma_f32 v[24:25], v[24:25], s[6:7], 1.0 op_sel_hi:[1,0,0]
	v_pk_mul_f32 v[16:17], v[16:17], v[20:21]
	v_rcp_f32_e32 v24, v24
	v_rcp_f32_e32 v25, v25
	v_pk_mul_f32 v[16:17], v[22:23], v[16:17]
	v_pk_mul_f32 v[20:21], v[10:11], v[10:11]
	v_pk_mul_f32 v[22:23], v[8:9], v[16:17]
	v_pk_fma_f32 v[16:17], v[8:9], v[16:17], v[8:9] neg_lo:[1,0,0] neg_hi:[1,0,0]
	v_mov_b32_e32 v45, v97
	v_cndmask_b32_e32 v22, v16, v22, vcc
	v_cmp_gt_f32_e32 vcc, 0, v9
	v_pk_fma_f32 v[8:9], v[24:25], s[24:25], v[18:19] op_sel_hi:[1,0,0]
	v_mov_b32_dpp v45, v47 row_ror:1 row_mask:0xf bank_mask:0xf
	v_cndmask_b32_e32 v23, v17, v23, vcc
	v_pk_mul_f32 v[16:17], v[20:21], s[36:37] op_sel_hi:[1,0]
	v_pk_fma_f32 v[8:9], v[24:25], v[8:9], s[28:29] op_sel_hi:[1,1,0]
	v_exp_f32_e32 v16, v16
	v_exp_f32_e32 v17, v17
	v_pk_fma_f32 v[8:9], v[24:25], v[8:9], s[30:31] op_sel_hi:[1,1,0]
	v_mov_b32_e32 v47, v97
	v_pk_fma_f32 v[8:9], v[24:25], v[8:9], s[34:35] op_sel_hi:[1,1,0]
	v_cmp_gt_f32_e32 vcc, 0, v10
	v_pk_mul_f32 v[8:9], v[24:25], v[8:9]
	v_mov_b32_dpp v47, v48 row_ror:2 row_mask:0xf bank_mask:0xf
	v_pk_mul_f32 v[8:9], v[16:17], v[8:9]
	v_pk_fma_f32 v[12:13], v[26:27], v[46:47], v[30:31]
	v_pk_mul_f32 v[16:17], v[10:11], v[8:9]
	v_pk_fma_f32 v[8:9], v[10:11], v[8:9], v[10:11] neg_lo:[1,0,0] neg_hi:[1,0,0]
	v_pk_fma_f32 v[12:13], v[76:77], v[44:45], v[12:13]
	v_pk_fma_f32 v[14:15], v[74:75], v[36:37], v[14:15]
	v_cndmask_b32_e32 v10, v8, v16, vcc
	v_cmp_gt_f32_e32 vcc, 0, v11
	v_pk_fma_f32 v[12:13], v[6:7], v[54:55], v[12:13]
	v_pk_fma_f32 v[14:15], v[4:5], v[52:53], v[14:15]
	v_cndmask_b32_e32 v9, v9, v17, vcc
	v_mul_f32_e32 v8, v14, v22
	v_mul_f32_e32 v9, v13, v9
	v_mul_f32_e32 v11, v15, v23
	v_cvt_pk_bf16_f32 v8, v8, v11
	v_mul_f32_e32 v10, v12, v10
	v_cvt_pk_bf16_f32 v9, v10, v9
	global_store_dwordx2 v[80:81], v[8:9], off offset:32
	s_and_saveexec_b64 s[0:1], s[46:47]
	s_cbranch_execz .LBB0_1001
	v_lshl_add_u64 v[8:9], v[82:83], 2, v[144:145]
	global_store_dwordx4 v[78:79], v[0:3], off offset:64
	global_store_dwordx4 v[8:9], v[4:7], off
	s_branch .LBB0_1001

; #define LAS __attribute__((address_space(3)))
;     __device__ __forceinline__ void operator()(AccT& acc, const Unit& u, int wr, int wc, int fr, int fq) const {
;     ...
;         const long arow0 = (long)u.pm * 256;
;         const int colg0 = u.pn * 128 + wc * 32 + fq * 8;
;         f32x4 cwg[2][3], cwv[2][3], cbg[2], cbv[2];
; #pragma unroll
;         for (int n = 0; n < 1; ++n) { const int colg = colg0 + n * 4, colv = FF + colg;
; #pragma unroll
;             for (int j = 0; j < 3; ++j) { cwg[n][j] = *(const f32x4*)(cw + j * FF2 + colg); cwv[n][j] = *(const f32x4*)(cw + j * FF2 + colv); }
;             cbg[n] = *(const f32x4*)(cb + colg); cbv[n] = *(const f32x4*)(cb + colv); }
;         float sq[2][4];
; #pragma unroll
;         for (int ai = 0; ai < 2; ++ai)
; #pragma unroll
;             for (int m = 0; m < 4; ++m) { const int rl = ai * 128 + wr * 64 + m * 16 + fr, t = tstart + rl; sq[ai][m] = ssq[arow0 + rl]; }
; #pragma unroll
;         for (int ai = 0; ai < 2; ++ai)
; #pragma unroll
;             for (int m = 0; m < 4; ++m) {
;                 const int rl = ai * 128 + wr * 64 + m * 16 + fr;
;                 const int t = tstart + rl;
;                 const float rs = __builtin_amdgcn_rsqf(sq[ai][m] * (1.0f / 1024.0f) + EPS);
; #pragma unroll
;                 for (int bj = 0; bj < 2; ++bj)
; #pragma unroll
;                     for (int n = 0; n < 2; ++n) acc[ai][bj][m][n] = acc[ai][bj][m][n] * rs;
;             }
;         if (fr >= 14) {
; #pragma unroll
;             for (int ai = 0; ai < 2; ++ai)
; #pragma unroll
;                 for (int bj = 0; bj < 2; ++bj)
; #pragma unroll
;                     for (int n = 0; n < 2; ++n)
;                         *(LAS f32x4*)(xch + (((ai * 2 + wr) * 2 + (fr - 14)) * 256 + bj * 128 + wc * 32 + fq * 8 + n * 4)) = acc[ai][bj][3][n];
.LBB0_1028:
	v_mov_b32_e32 v80, v230
	v_mov_b32_e32 v220, v229
	s_lshl_b32 s3, s22, 7
	v_readlane_b32 s9, v246, 38
	s_ashr_i32 s17, s16, 31
	s_or_b32 s3, s3, s9
	v_lshlrev_b32_e32 v165, 3, v80
	v_add_u32_e32 v182, s3, v165
	v_readlane_b32 s3, v246, 30
	s_lshl_b64 s[14:15], s[16:17], 10
	v_readlane_b32 s18, v246, 20
	v_add_u32_e32 v210, s3, v220
	v_readlane_b32 s19, v246, 21
	s_add_u32 s14, s18, s14
	s_addc_u32 s15, s19, s15
	v_ashrrev_i32_e32 v211, 31, v210
	v_add_u32_e32 v208, 16, v210
	v_lshl_add_u64 v[126:127], v[210:211], 2, s[14:15]
	v_ashrrev_i32_e32 v209, 31, v208
	v_add_u32_e32 v206, 32, v210
	global_load_dword v211, v[126:127], off
	v_lshl_add_u64 v[126:127], v[208:209], 2, s[14:15]
	v_ashrrev_i32_e32 v207, 31, v206
	v_add_u32_e32 v192, 48, v210
	global_load_dword v209, v[126:127], off
	v_lshl_add_u64 v[126:127], v[206:207], 2, s[14:15]
	v_ashrrev_i32_e32 v193, 31, v192
	global_load_dword v207, v[126:127], off
	v_lshl_add_u64 v[126:127], v[192:193], 2, s[14:15]
	v_add_u32_e32 v190, 0x80, v210
	v_ashrrev_i32_e32 v183, 31, v182
	global_load_dword v164, v[126:127], off
	v_ashrrev_i32_e32 v191, 31, v190
	v_add_u32_e32 v188, 0x90, v210
	v_lshlrev_b64 v[80:81], 2, v[182:183]
	v_lshl_add_u64 v[126:127], v[190:191], 2, s[14:15]
	v_ashrrev_i32_e32 v189, 31, v188
	v_add_u32_e32 v186, 0xa0, v210
	v_lshl_add_u64 v[212:213], s[44:45], 0, v[80:81]
	global_load_dword v191, v[126:127], off
	v_lshl_add_u64 v[126:127], v[188:189], 2, s[14:15]
	v_ashrrev_i32_e32 v187, 31, v186
	v_add_u32_e32 v184, 0xb0, v210
	v_add_co_u32_e32 v82, vcc, 0x2000, v212
	global_load_dword v189, v[126:127], off
	v_lshl_add_u64 v[126:127], v[186:187], 2, s[14:15]
	v_ashrrev_i32_e32 v185, 31, v184
	v_addc_co_u32_e32 v83, vcc, 0, v213, vcc
	v_lshl_add_u64 v[214:215], s[40:41], 0, v[80:81]
	global_load_dword v187, v[126:127], off
	v_lshl_add_u64 v[126:127], v[184:185], 2, s[14:15]
	global_load_dwordx4 v[84:87], v[82:83], off offset:3072
	v_add_co_u32_e32 v82, vcc, 0x2000, v214
	global_load_dword v127, v[126:127], off
	s_nop 0
	v_addc_co_u32_e32 v83, vcc, 0, v215, vcc
	v_lshl_add_u64 v[218:219], s[42:43], 0, v[80:81]
	global_load_dwordx4 v[92:95], v[82:83], off offset:3072
	v_add_co_u32_e32 v82, vcc, 0x2000, v218
	v_lshl_add_u64 v[216:217], s[94:95], 0, v[80:81]
	s_nop 0
	v_addc_co_u32_e32 v83, vcc, 0, v219, vcc
	v_add_co_u32_e32 v80, vcc, 0x2000, v216
	global_load_dwordx4 v[98:101], v[212:213], off
	s_nop 0
	v_addc_co_u32_e32 v81, vcc, 0, v217, vcc
	global_load_dwordx4 v[102:105], v[214:215], off
	global_load_dwordx4 v[110:113], v[216:217], off
	global_load_dwordx4 v[106:109], v[218:219], off
	global_load_dwordx4 v[88:91], v[82:83], off offset:3072
	v_cmp_lt_i32_e64 s[48:49], 13, v220
	global_load_dwordx4 v[80:83], v[80:81], off offset:3072
	s_waitcnt vmcnt(0) lgkmcnt(0)
	v_fmamk_f32 v126, v164, 0x3a800000, v223
	v_rsq_f32_e32 v126, v126
	s_nop 0
	v_pk_mul_f32 v[154:155], v[154:155], v[126:127] op_sel_hi:[1,0]
	v_pk_mul_f32 v[152:153], v[152:153], v[126:127] op_sel_hi:[1,0]
	v_pk_mul_f32 v[50:51], v[50:51], v[126:127] op_sel_hi:[1,0]
	v_pk_mul_f32 v[48:49], v[48:49], v[126:127] op_sel_hi:[1,0]
	v_pk_mul_f32 v[150:151], v[150:151], v[126:127] op_sel_hi:[1,0]
	v_pk_mul_f32 v[148:149], v[148:149], v[126:127] op_sel_hi:[1,0]
	v_pk_mul_f32 v[46:47], v[46:47], v[126:127] op_sel_hi:[1,0]
	v_pk_mul_f32 v[44:45], v[44:45], v[126:127] op_sel_hi:[1,0]
	v_fmamk_f32 v126, v127, 0x3a800000, v223
	v_rsq_f32_e32 v164, v126
	s_nop 0
	v_pk_mul_f32 v[126:127], v[124:125], v[164:165] op_sel_hi:[1,0]
	v_pk_mul_f32 v[124:125], v[122:123], v[164:165] op_sel_hi:[1,0]
	v_pk_mul_f32 v[18:19], v[18:19], v[164:165] op_sel_hi:[1,0]
	v_pk_mul_f32 v[16:17], v[16:17], v[164:165] op_sel_hi:[1,0]
	v_pk_mul_f32 v[130:131], v[130:131], v[164:165] op_sel_hi:[1,0]
	v_pk_mul_f32 v[128:129], v[128:129], v[164:165] op_sel_hi:[1,0]
	v_pk_mul_f32 v[22:23], v[22:23], v[164:165] op_sel_hi:[1,0]
	v_pk_mul_f32 v[20:21], v[20:21], v[164:165] op_sel_hi:[1,0]
	v_lshlrev_b32_e32 v122, 2, v165
	s_and_saveexec_b64 s[14:15], s[48:49]
	s_movk_i32 s54, 0xff04
	s_cbranch_execz .LBB0_1030
	v_readlane_b32 s3, v246, 33
	s_nop 1
	v_add_lshl_u32 v123, s3, v220, 10
	v_readlane_b32 s3, v246, 41
	s_nop 1
	v_add3_u32 v164, s3, v123, v122
	v_readlane_b32 s3, v246, 39
	ds_write_b128 v164, v[152:155]
	ds_write_b128 v164, v[48:51] offset:16
	ds_write_b128 v164, v[148:151] offset:512
	ds_write_b128 v164, v[44:47] offset:528
	v_add3_u32 v123, s3, v123, v122
	ds_write_b128 v123, v[124:127]
	ds_write_b128 v164, v[16:19] offset:4112
	ds_write_b128 v164, v[128:131] offset:4608
	ds_write_b128 v164, v[20:23] offset:4624

; #define LAS __attribute__((address_space(3)))
; __device__ __forceinline__ unsigned cvt_pk_bf16(float lo, float hi) { unsigned r; asm volatile("v_cvt_pk_bf16_f32 %0, %1, %2" : "=v"(r) : "v"(lo), "v"(hi)); return r; }
; __device__ __forceinline__ float ror1(float x) { return __builtin_bit_cast(float, __builtin_amdgcn_update_dpp(0, __builtin_bit_cast(int, x), 0x121, 0xf, 0xf, false)); }
;     __device__ __forceinline__ void operator()(AccT& acc, const Unit& u, int wr, int wc, int fr, int fq) const {
;     ...
;                 if (s > 0 && fr >= 14) {
;                     hg = *(const LAS f32x4*)(xch + (((s - 1) * 2 + (fr - 14)) * 256 + wc * 32 + fq * 8 + n * 4));
;                     hv = *(const LAS f32x4*)(xch + (((s - 1) * 2 + (fr - 14)) * 256 + 128 + wc * 32 + fq * 8 + n * 4));
;                 }
; #pragma unroll
;                 for (int m = 0; m < 4; ++m) {
;                     const int rl = ai * 128 + wr * 64 + m * 16 + fr;
;                     const f32x4 cg_ = acc[ai][0][m][n], cv_ = acc[ai][1][m][n];
;                     f32x4 p1g, p2g, p1v, p2v;
; #pragma unroll
;                     for (int j = 0; j < 4; ++j) {
;                         p1g[j] = ror1(fr == 15 ? hg[j] : cg_[j]); p2g[j] = ror2(fr >= 14 ? hg[j] : cg_[j]);
;                         p1v[j] = ror1(fr == 15 ? hv[j] : cv_[j]); p2v[j] = ror2(fr >= 14 ? hv[j] : cv_[j]);
;                     }
;                     const f32x4 hcg = bg + w0g * p2g + w1g * p1g + w2g * cg_;
;                     const f32x4 hcv = bv + w0v * p2v + w1v * p1v + w2v * cv_;
;                     const f32x2 ga = gelu_pk((f32x2){hcg[0], hcg[1]}), gb2 = gelu_pk((f32x2){hcg[2], hcg[3]});
;                     u32x2 w; w.x = cvt_pk_bf16(ga.x * hcv[0], ga.y * hcv[1]); w.y = cvt_pk_bf16(gb2.x * hcv[2], gb2.y * hcv[3]);
;                     const int t = tstart + rl;
;                     if (n == 0) stash[ai][m] = w;
;                     else if (rl >= 2) *(u32x4*)(U + (size_t)(arow0 + rl) * FF + colg0) = (u32x4){stash[ai][m].x, stash[ai][m].y, w.x, w.y};
;                     if (rl < 2 || rl >= 254) { float* hp = halo + ((size_t)u.pm * 4 + (rl < 2 ? rl : rl - 252)) * FF2; *(f32x4*)(hp + colg) = cg_; *(f32x4*)(hp + colv) = cv_; }
;                     if (t >= SEQ - 2) { float* cp = conv_p + (size_t)(b * 2 + (t - (SEQ - 2))) * FF2; *(f32x4*)(cp + colg) = cg_; *(f32x4*)(cp + colv) = cv_; }
.LBB0_1032:
	s_or_b64 exec, exec, s[14:15]
	v_fmamk_f32 v122, v211, 0x3a800000, v223
	v_cmp_eq_u32_e64 s[50:51], 15, v220
	v_rsq_f32_e32 v220, v122
	s_nop 0
	v_pk_mul_f32 v[160:161], v[160:161], v[220:221] op_sel_hi:[1,0]
	v_pk_mul_f32 v[156:157], v[156:157], v[220:221] op_sel_hi:[1,0]
	s_waitcnt lgkmcnt(1)
	v_cndmask_b32_e64 v123, v160, v164, s[50:51]
	v_cndmask_b32_e64 v193, v161, v165, s[50:51]
	v_pk_mul_f32 v[162:163], v[162:163], v[220:221] op_sel_hi:[1,0]
	v_mov_b32_dpp v122, v123 row_ror:1 row_mask:0xf bank_mask:0xf
	v_cndmask_b32_e64 v123, v160, v164, s[48:49]
	v_pk_mul_f32 v[158:159], v[158:159], v[220:221] op_sel_hi:[1,0]
	s_nop 0
	v_mov_b32_dpp v164, v123 row_ror:2 row_mask:0xf bank_mask:0xf
	s_waitcnt lgkmcnt(0)
	v_cndmask_b32_e64 v123, v156, v168, s[50:51]
	s_nop 1
	v_mov_b32_dpp v234, v123 row_ror:1 row_mask:0xf bank_mask:0xf
	v_cndmask_b32_e64 v123, v156, v168, s[48:49]
	s_mov_b32 s18, 0xbf3a00e3
	s_nop 0
	v_mov_b32_dpp v168, v123 row_ror:2 row_mask:0xf bank_mask:0xf
	s_lshl_b64 s[14:15], s[16:17], 2
	s_nop 0
	v_mov_b32_dpp v123, v193 row_ror:1 row_mask:0xf bank_mask:0xf
	v_cndmask_b32_e64 v193, v161, v165, s[48:49]
	s_nop 1
	v_mov_b32_dpp v165, v193 row_ror:2 row_mask:0xf bank_mask:0xf
	v_cndmask_b32_e64 v193, v157, v169, s[50:51]
	v_pk_fma_f32 v[164:165], v[102:103], v[164:165], v[98:99]
	s_nop 0
	v_mov_b32_dpp v235, v193 row_ror:1 row_mask:0xf bank_mask:0xf
	v_cndmask_b32_e64 v193, v157, v169, s[48:49]
	v_pk_fma_f32 v[122:123], v[106:107], v[122:123], v[164:165]
	s_nop 0
	v_mov_b32_dpp v169, v193 row_ror:2 row_mask:0xf bank_mask:0xf
	v_cndmask_b32_e64 v193, v162, v166, s[50:51]
	v_pk_fma_f32 v[122:123], v[110:111], v[160:161], v[122:123]
	v_pk_fma_f32 v[168:169], v[92:93], v[168:169], v[84:85]
	v_mov_b32_dpp v236, v193 row_ror:1 row_mask:0xf bank_mask:0xf
	v_cndmask_b32_e64 v193, v162, v166, s[48:49]
	v_pk_fma_f32 v[168:169], v[88:89], v[234:235], v[168:169]
	v_mov_b64_e32 v[234:235], s[18:19]
	v_mov_b32_dpp v166, v193 row_ror:2 row_mask:0xf bank_mask:0xf
	v_cndmask_b32_e64 v193, v158, v170, s[50:51]
	v_cmp_gt_f32_e32 vcc, 0, v122
	v_pk_fma_f32 v[168:169], v[80:81], v[156:157], v[168:169]
	v_mov_b32_dpp v238, v193 row_ror:1 row_mask:0xf bank_mask:0xf
	v_cndmask_b32_e64 v193, v158, v170, s[48:49]
	s_nop 1
	v_mov_b32_dpp v170, v193 row_ror:2 row_mask:0xf bank_mask:0xf
	v_cndmask_b32_e64 v193, v163, v167, s[50:51]
	s_nop 1
	v_mov_b32_dpp v237, v193 row_ror:1 row_mask:0xf bank_mask:0xf
	v_cndmask_b32_e64 v193, v163, v167, s[48:49]
	s_nop 1
	v_mov_b32_dpp v167, v193 row_ror:2 row_mask:0xf bank_mask:0xf
	v_cndmask_b32_e64 v193, v159, v171, s[50:51]
	v_pk_fma_f32 v[166:167], v[104:105], v[166:167], v[100:101]
	s_nop 0
	v_mov_b32_dpp v239, v193 row_ror:1 row_mask:0xf bank_mask:0xf
	v_cndmask_b32_e64 v193, v159, v171, s[48:49]
	v_pk_fma_f32 v[164:165], v[108:109], v[236:237], v[166:167]
	s_nop 0
	v_mov_b32_dpp v171, v193 row_ror:2 row_mask:0xf bank_mask:0xf
	v_pk_fma_f32 v[166:167], v[94:95], v[170:171], v[86:87]
	v_and_b32_e32 v171, 0x7fffffff, v123
	v_and_b32_e32 v170, 0x7fffffff, v122
	v_pk_fma_f32 v[170:171], v[170:171], s[6:7], 1.0 op_sel_hi:[1,0,0]
	v_pk_fma_f32 v[166:167], v[90:91], v[238:239], v[166:167]
	v_rcp_f32_e32 v170, v170
	v_rcp_f32_e32 v171, v171
	v_pk_mul_f32 v[238:239], v[122:123], v[122:123]
	v_pk_fma_f32 v[164:165], v[112:113], v[162:163], v[164:165]
	v_pk_mul_f32 v[238:239], v[238:239], s[36:37] op_sel_hi:[1,0]
	v_pk_fma_f32 v[236:237], v[170:171], s[24:25], v[234:235] op_sel_hi:[1,0,0]
	v_exp_f32_e32 v238, v238
	v_pk_fma_f32 v[236:237], v[170:171], v[236:237], s[28:29] op_sel_hi:[1,1,0]
	v_exp_f32_e32 v239, v239
	v_pk_fma_f32 v[236:237], v[170:171], v[236:237], s[30:31] op_sel_hi:[1,1,0]
	v_pk_fma_f32 v[166:167], v[82:83], v[158:159], v[166:167]
	v_pk_fma_f32 v[236:237], v[170:171], v[236:237], s[34:35] op_sel_hi:[1,1,0]
	s_nop 0
	v_pk_mul_f32 v[170:171], v[170:171], v[236:237]
	v_pk_mul_f32 v[236:237], v[164:165], v[164:165]
	v_pk_mul_f32 v[170:171], v[238:239], v[170:171]
	s_nop 0
	v_pk_mul_f32 v[238:239], v[122:123], v[170:171]
	v_pk_fma_f32 v[170:171], v[122:123], v[170:171], v[122:123] neg_lo:[1,0,0] neg_hi:[1,0,0]
	v_and_b32_e32 v122, 0x7fffffff, v164
	v_cndmask_b32_e32 v193, v170, v238, vcc
	v_cmp_gt_f32_e32 vcc, 0, v123
	v_and_b32_e32 v123, 0x7fffffff, v165
	v_pk_fma_f32 v[122:123], v[122:123], s[6:7], 1.0 op_sel_hi:[1,0,0]
	v_cndmask_b32_e32 v211, v171, v239, vcc
	v_rcp_f32_e32 v122, v122
	v_rcp_f32_e32 v123, v123
	v_cmp_gt_f32_e32 vcc, 0, v164
	v_pk_fma_f32 v[170:171], v[122:123], s[24:25], v[234:235] op_sel_hi:[1,0,0]
	s_nop 0
	v_pk_fma_f32 v[170:171], v[122:123], v[170:171], s[28:29] op_sel_hi:[1,1,0]
	s_nop 0
	v_pk_fma_f32 v[170:171], v[122:123], v[170:171], s[30:31] op_sel_hi:[1,1,0]
	s_nop 0
	v_pk_fma_f32 v[170:171], v[122:123], v[170:171], s[34:35] op_sel_hi:[1,1,0]
	s_nop 0
	v_pk_mul_f32 v[122:123], v[122:123], v[170:171]
	v_pk_mul_f32 v[170:171], v[236:237], s[36:37] op_sel_hi:[1,0]
	s_nop 0
	v_exp_f32_e32 v170, v170
	v_exp_f32_e32 v171, v171
	s_nop 0
	v_pk_mul_f32 v[122:123], v[170:171], v[122:123]
	s_nop 0
	v_pk_mul_f32 v[170:171], v[164:165], v[122:123]
	v_pk_fma_f32 v[122:123], v[164:165], v[122:123], v[164:165] neg_lo:[1,0,0] neg_hi:[1,0,0]
	s_nop 0
	v_cndmask_b32_e32 v164, v122, v170, vcc
	v_cmp_gt_f32_e32 vcc, 0, v165
	v_mul_f32_e32 v122, v168, v193
	v_mul_f32_e32 v164, v166, v164
	v_cndmask_b32_e32 v123, v123, v171, vcc
	v_mul_f32_e32 v123, v167, v123
	v_mul_f32_e32 v165, v169, v211
	v_cvt_pk_bf16_f32 v122, v122, v165
	v_cvt_pk_bf16_f32 v123, v164, v123
	v_add_u32_e32 v164, 0xffffff02, v210
	v_cmp_gt_u32_e64 s[80:81], s54, v164
	v_add_u32_e32 v169, 0xffffff04, v210
	s_and_saveexec_b64 s[18:19], s[80:81]
	s_cbranch_execz .LBB0_1034
	v_cmp_gt_i32_e32 vcc, 2, v210
	v_mov_b64_e32 v[166:167], s[92:93]
	s_movk_i32 s3, 0x5800
	v_cndmask_b32_e32 v164, v169, v210, vcc
	v_ashrrev_i32_e32 v165, 31, v164
	v_lshl_add_u64 v[164:165], s[14:15], 0, v[164:165]
	v_mad_u64_u32 v[166:167], s[22:23], v164, s3, v[166:167]
	v_mad_i32_i24 v167, v165, s3, v167
	v_lshl_add_u64 v[164:165], v[182:183], 2, v[166:167]
	global_store_dwordx4 v[164:165], v[160:163], off
	v_add_co_u32_e32 v164, vcc, 0x2000, v164
	s_nop 1
	v_addc_co_u32_e32 v165, vcc, 0, v165, vcc
	global_store_dwordx4 v[164:165], v[156:159], off offset:3072
; __device__ __forceinline__ unsigned cvt_pk_bf16(float lo, float hi) { unsigned r; asm volatile("v_cvt_pk_bf16_f32 %0, %1, %2" : "=v"(r) : "v"(lo), "v"(hi)); return r; }
; __device__ __forceinline__ float ror1(float x) { return __builtin_bit_cast(float, __builtin_amdgcn_update_dpp(0, __builtin_bit_cast(int, x), 0x121, 0xf, 0xf, false)); }
; __device__ __forceinline__ float ror2(float x) { return __builtin_bit_cast(float, __builtin_amdgcn_update_dpp(0, __builtin_bit_cast(int, x), 0x122, 0xf, 0xf, false)); }
;     __device__ __forceinline__ void operator()(AccT& acc, const Unit& u, int wr, int wc, int fr, int fq) const {
;     ...
;                 for (int m = 0; m < 4; ++m) {
;                     const int rl = ai * 128 + wr * 64 + m * 16 + fr;
;                     const f32x4 cg_ = acc[ai][0][m][n], cv_ = acc[ai][1][m][n];
;                     f32x4 p1g, p2g, p1v, p2v;
; #pragma unroll
;                     for (int j = 0; j < 4; ++j) {
;                         p1g[j] = ror1(fr == 15 ? hg[j] : cg_[j]); p2g[j] = ror2(fr >= 14 ? hg[j] : cg_[j]);
;                         p1v[j] = ror1(fr == 15 ? hv[j] : cv_[j]); p2v[j] = ror2(fr >= 14 ? hv[j] : cv_[j]);
;                     }
;                     const f32x4 hcg = bg + w0g * p2g + w1g * p1g + w2g * cg_;
;                     const f32x4 hcv = bv + w0v * p2v + w1v * p1v + w2v * cv_;
;                     const f32x2 ga = gelu_pk((f32x2){hcg[0], hcg[1]}), gb2 = gelu_pk((f32x2){hcg[2], hcg[3]});
;                     u32x2 w; w.x = cvt_pk_bf16(ga.x * hcv[0], ga.y * hcv[1]); w.y = cvt_pk_bf16(gb2.x * hcv[2], gb2.y * hcv[3]);
;                     const int t = tstart + rl;
;                     if (n == 0) stash[ai][m] = w;
;                     else if (rl >= 2) *(u32x4*)(U + (size_t)(arow0 + rl) * FF + colg0) = (u32x4){stash[ai][m].x, stash[ai][m].y, w.x, w.y};
;                     if (rl < 2 || rl >= 254) { float* hp = halo + ((size_t)u.pm * 4 + (rl < 2 ? rl : rl - 252)) * FF2; *(f32x4*)(hp + colg) = cg_; *(f32x4*)(hp + colv) = cv_; }
;                     if (t >= SEQ - 2) { float* cp = conv_p + (size_t)(b * 2 + (t - (SEQ - 2))) * FF2; *(f32x4*)(cp + colg) = cg_; *(f32x4*)(cp + colv) = cv_; }
.LBB0_1034:
	s_or_b64 exec, exec, s[18:19]
	s_lshl_b32 s3, s16, 8
	s_ashr_i32 s9, s16, 5
	s_and_b32 s3, s3, 0x3f00
	s_and_b32 s9, s9, -2
	s_addk_i32 s9, 0xc002
	s_movk_i32 s18, 0x3ffd
	s_mov_b64 s[82:83], 0
	v_fmamk_f32 v164, v209, 0x3a800000, v223
	v_rsq_f32_e32 v168, v164
	s_nop 0
	v_pk_mul_f32 v[146:147], v[146:147], v[168:169] op_sel_hi:[1,0]
	v_pk_mul_f32 v[144:145], v[144:145], v[168:169] op_sel_hi:[1,0]
	v_pk_mul_f32 v[166:167], v[120:121], v[168:169] op_sel_hi:[1,0]
	v_pk_mul_f32 v[164:165], v[118:119], v[168:169] op_sel_hi:[1,0]
	v_cndmask_b32_e64 v119, v144, v160, s[50:51]
	v_cndmask_b32_e64 v121, v145, v161, s[50:51]
	s_nop 0
	v_mov_b32_dpp v118, v119 row_ror:1 row_mask:0xf bank_mask:0xf
	v_cndmask_b32_e64 v119, v144, v160, s[48:49]
	v_cndmask_b32_e64 v161, v145, v161, s[48:49]
	s_nop 0
	v_mov_b32_dpp v120, v119 row_ror:2 row_mask:0xf bank_mask:0xf
	v_cndmask_b32_e64 v119, v164, v156, s[50:51]
	v_cndmask_b32_e64 v171, v165, v157, s[50:51]
	s_nop 0
	v_mov_b32_dpp v160, v119 row_ror:1 row_mask:0xf bank_mask:0xf
	v_cndmask_b32_e64 v119, v164, v156, s[48:49]
	s_nop 1
	v_mov_b32_dpp v156, v119 row_ror:2 row_mask:0xf bank_mask:0xf
	s_mov_b32 s18, 0xbf3a00e3
	v_mov_b32_dpp v119, v121 row_ror:1 row_mask:0xf bank_mask:0xf
	s_nop 1
	v_mov_b32_dpp v121, v161 row_ror:2 row_mask:0xf bank_mask:0xf
	v_pk_fma_f32 v[120:121], v[102:103], v[120:121], v[98:99]
	s_nop 0
	v_mov_b32_dpp v161, v171 row_ror:1 row_mask:0xf bank_mask:0xf
	v_cndmask_b32_e64 v171, v165, v157, s[48:49]
	v_pk_fma_f32 v[118:119], v[106:107], v[118:119], v[120:121]
	s_nop 0
	v_mov_b32_dpp v157, v171 row_ror:2 row_mask:0xf bank_mask:0xf
	v_cndmask_b32_e64 v171, v146, v162, s[50:51]
	v_pk_fma_f32 v[118:119], v[110:111], v[144:145], v[118:119]
	v_pk_fma_f32 v[156:157], v[92:93], v[156:157], v[84:85]
	v_mov_b32_dpp v234, v171 row_ror:1 row_mask:0xf bank_mask:0xf
	v_cndmask_b32_e64 v171, v146, v162, s[48:49]
	v_pk_fma_f32 v[156:157], v[88:89], v[160:161], v[156:157]
	v_and_b32_e32 v161, 0x7fffffff, v119
	v_mov_b32_dpp v162, v171 row_ror:2 row_mask:0xf bank_mask:0xf
	v_cndmask_b32_e64 v171, v166, v158, s[50:51]
	v_and_b32_e32 v160, 0x7fffffff, v118
	v_pk_fma_f32 v[160:161], v[160:161], s[6:7], 1.0 op_sel_hi:[1,0,0]
	v_mov_b32_dpp v236, v171 row_ror:1 row_mask:0xf bank_mask:0xf
	v_cndmask_b32_e64 v171, v166, v158, s[48:49]
	v_rcp_f32_e32 v160, v160
	v_rcp_f32_e32 v161, v161
	v_mov_b32_dpp v158, v171 row_ror:2 row_mask:0xf bank_mask:0xf
	v_cndmask_b32_e64 v171, v147, v163, s[50:51]
	v_cmp_gt_f32_e32 vcc, 0, v118
	v_pk_fma_f32 v[156:157], v[80:81], v[164:165], v[156:157]
	v_mov_b32_dpp v235, v171 row_ror:1 row_mask:0xf bank_mask:0xf
	v_cndmask_b32_e64 v171, v147, v163, s[48:49]
	s_nop 1
	v_mov_b32_dpp v163, v171 row_ror:2 row_mask:0xf bank_mask:0xf
	v_cndmask_b32_e64 v171, v167, v159, s[50:51]
	v_pk_fma_f32 v[162:163], v[104:105], v[162:163], v[100:101]
	s_nop 0
	v_mov_b32_dpp v237, v171 row_ror:1 row_mask:0xf bank_mask:0xf
	v_cndmask_b32_e64 v171, v167, v159, s[48:49]
	v_pk_fma_f32 v[120:121], v[108:109], v[234:235], v[162:163]
	v_mov_b64_e32 v[162:163], s[18:19]
	v_mov_b32_dpp v159, v171 row_ror:2 row_mask:0xf bank_mask:0xf
	v_pk_fma_f32 v[158:159], v[94:95], v[158:159], v[86:87]
	v_pk_fma_f32 v[234:235], v[160:161], s[24:25], v[162:163] op_sel_hi:[1,0,0]
	v_pk_fma_f32 v[158:159], v[90:91], v[236:237], v[158:159]
	v_pk_mul_f32 v[236:237], v[118:119], v[118:119]
	v_pk_fma_f32 v[234:235], v[160:161], v[234:235], s[28:29] op_sel_hi:[1,1,0]
	v_pk_mul_f32 v[236:237], v[236:237], s[36:37] op_sel_hi:[1,0]
	v_pk_fma_f32 v[234:235], v[160:161], v[234:235], s[30:31] op_sel_hi:[1,1,0]
	v_exp_f32_e32 v236, v236
	v_exp_f32_e32 v237, v237
	v_pk_fma_f32 v[234:235], v[160:161], v[234:235], s[34:35] op_sel_hi:[1,1,0]
	v_pk_fma_f32 v[120:121], v[112:113], v[146:147], v[120:121]
	v_pk_mul_f32 v[160:161], v[160:161], v[234:235]
	v_pk_mul_f32 v[234:235], v[120:121], v[120:121]
	v_pk_mul_f32 v[160:161], v[236:237], v[160:161]
	v_pk_fma_f32 v[158:159], v[82:83], v[166:167], v[158:159]
	v_pk_mul_f32 v[236:237], v[118:119], v[160:161]
	v_pk_fma_f32 v[160:161], v[118:119], v[160:161], v[118:119] neg_lo:[1,0,0] neg_hi:[1,0,0]
	v_and_b32_e32 v118, 0x7fffffff, v120
	v_cndmask_b32_e32 v171, v160, v236, vcc
	v_cmp_gt_f32_e32 vcc, 0, v119
	v_and_b32_e32 v119, 0x7fffffff, v121
	v_pk_fma_f32 v[118:119], v[118:119], s[6:7], 1.0 op_sel_hi:[1,0,0]
	v_cndmask_b32_e32 v193, v161, v237, vcc
	v_rcp_f32_e32 v118, v118
	v_rcp_f32_e32 v119, v119
	v_cmp_gt_f32_e32 vcc, 0, v120
	v_pk_fma_f32 v[160:161], v[118:119], s[24:25], v[162:163] op_sel_hi:[1,0,0]
	s_nop 0
	v_pk_fma_f32 v[160:161], v[118:119], v[160:161], s[28:29] op_sel_hi:[1,1,0]
	s_nop 0
	v_pk_fma_f32 v[160:161], v[118:119], v[160:161], s[30:31] op_sel_hi:[1,1,0]
	s_nop 0
	v_pk_fma_f32 v[160:161], v[118:119], v[160:161], s[34:35] op_sel_hi:[1,1,0]
	s_nop 0
	v_pk_mul_f32 v[118:119], v[118:119], v[160:161]
	v_pk_mul_f32 v[160:161], v[234:235], s[36:37] op_sel_hi:[1,0]
	s_nop 0
	v_exp_f32_e32 v160, v160
	v_exp_f32_e32 v161, v161
	s_nop 0
	v_pk_mul_f32 v[118:119], v[160:161], v[118:119]
	s_nop 0
	v_pk_mul_f32 v[160:161], v[120:121], v[118:119]
	v_pk_fma_f32 v[118:119], v[120:121], v[118:119], v[120:121] neg_lo:[1,0,0] neg_hi:[1,0,0]
	v_mul_f32_e32 v120, v156, v171
	v_cndmask_b32_e32 v118, v118, v160, vcc
	v_cmp_gt_f32_e32 vcc, 0, v121
	v_mul_f32_e32 v121, v157, v193
	v_mul_f32_e32 v118, v158, v118
	v_cndmask_b32_e32 v119, v119, v161, vcc
	v_cvt_pk_bf16_f32 v120, v120, v121
	v_mul_f32_e32 v119, v159, v119
	v_cvt_pk_bf16_f32 v121, v118, v119
	s_mov_b64 s[76:77], 0
	s_movk_i32 s18, 0x3ffd
	s_mov_b64 s[78:79], 0
	v_fmamk_f32 v118, v207, 0x3a800000, v223
	v_rsq_f32_e32 v156, v118
; __device__ __forceinline__ unsigned cvt_pk_bf16(float lo, float hi) { unsigned r; asm volatile("v_cvt_pk_bf16_f32 %0, %1, %2" : "=v"(r) : "v"(lo), "v"(hi)); return r; }
; __device__ __forceinline__ float ror1(float x) { return __builtin_bit_cast(float, __builtin_amdgcn_update_dpp(0, __builtin_bit_cast(int, x), 0x121, 0xf, 0xf, false)); }
; __device__ __forceinline__ float ror2(float x) { return __builtin_bit_cast(float, __builtin_amdgcn_update_dpp(0, __builtin_bit_cast(int, x), 0x122, 0xf, 0xf, false)); }
;     __device__ __forceinline__ void operator()(AccT& acc, const Unit& u, int wr, int wc, int fr, int fq) const {
;     ...
;                 for (int m = 0; m < 4; ++m) {
;                     const int rl = ai * 128 + wr * 64 + m * 16 + fr;
;                     const f32x4 cg_ = acc[ai][0][m][n], cv_ = acc[ai][1][m][n];
;                     f32x4 p1g, p2g, p1v, p2v;
; #pragma unroll
;                     for (int j = 0; j < 4; ++j) {
;                         p1g[j] = ror1(fr == 15 ? hg[j] : cg_[j]); p2g[j] = ror2(fr >= 14 ? hg[j] : cg_[j]);
;                         p1v[j] = ror1(fr == 15 ? hv[j] : cv_[j]); p2v[j] = ror2(fr >= 14 ? hv[j] : cv_[j]);
;                     }
;                     const f32x4 hcg = bg + w0g * p2g + w1g * p1g + w2g * cg_;
;                     const f32x4 hcv = bv + w0v * p2v + w1v * p1v + w2v * cv_;
;                     const f32x2 ga = gelu_pk((f32x2){hcg[0], hcg[1]}), gb2 = gelu_pk((f32x2){hcg[2], hcg[3]});
;                     u32x2 w; w.x = cvt_pk_bf16(ga.x * hcv[0], ga.y * hcv[1]); w.y = cvt_pk_bf16(gb2.x * hcv[2], gb2.y * hcv[3]);
;                     const int t = tstart + rl;
;                     if (n == 0) stash[ai][m] = w;
;                     else if (rl >= 2) *(u32x4*)(U + (size_t)(arow0 + rl) * FF + colg0) = (u32x4){stash[ai][m].x, stash[ai][m].y, w.x, w.y};
;                     if (rl < 2 || rl >= 254) { float* hp = halo + ((size_t)u.pm * 4 + (rl < 2 ? rl : rl - 252)) * FF2; *(f32x4*)(hp + colg) = cg_; *(f32x4*)(hp + colv) = cv_; }
;                     if (t >= SEQ - 2) { float* cp = conv_p + (size_t)(b * 2 + (t - (SEQ - 2))) * FF2; *(f32x4*)(cp + colg) = cg_; *(f32x4*)(cp + colv) = cv_; }
	s_nop 0
	v_pk_mul_f32 v[142:143], v[142:143], v[156:157] op_sel_hi:[1,0]
	v_pk_mul_f32 v[140:141], v[140:141], v[156:157] op_sel_hi:[1,0]
	v_pk_mul_f32 v[116:117], v[116:117], v[156:157] op_sel_hi:[1,0]
	v_pk_mul_f32 v[114:115], v[114:115], v[156:157] op_sel_hi:[1,0]
	v_cndmask_b32_e64 v119, v140, v144, s[50:51]
	s_nop 1
	v_mov_b32_dpp v118, v119 row_ror:1 row_mask:0xf bank_mask:0xf
	v_cndmask_b32_e64 v119, v140, v144, s[48:49]
	v_cndmask_b32_e64 v159, v141, v145, s[50:51]
	v_cndmask_b32_e64 v161, v115, v165, s[50:51]
	v_mov_b32_dpp v144, v119 row_ror:2 row_mask:0xf bank_mask:0xf
	v_cndmask_b32_e64 v119, v114, v164, s[50:51]
	v_cndmask_b32_e64 v163, v115, v165, s[48:49]
	s_nop 0
	v_mov_b32_dpp v158, v119 row_ror:1 row_mask:0xf bank_mask:0xf
	v_cndmask_b32_e64 v119, v114, v164, s[48:49]
	s_nop 1
	v_mov_b32_dpp v160, v119 row_ror:2 row_mask:0xf bank_mask:0xf
	s_mov_b32 s18, 0xbf3a00e3
	v_mov_b32_dpp v119, v159 row_ror:1 row_mask:0xf bank_mask:0xf
	v_cndmask_b32_e64 v159, v141, v145, s[48:49]
	s_nop 1
	v_mov_b32_dpp v145, v159 row_ror:2 row_mask:0xf bank_mask:0xf
	v_pk_fma_f32 v[144:145], v[102:103], v[144:145], v[98:99]
	s_nop 0
	v_mov_b32_dpp v159, v161 row_ror:1 row_mask:0xf bank_mask:0xf
	v_pk_fma_f32 v[118:119], v[106:107], v[118:119], v[144:145]
	s_nop 0
	v_mov_b32_dpp v161, v163 row_ror:2 row_mask:0xf bank_mask:0xf
	v_cndmask_b32_e64 v163, v142, v146, s[50:51]
	v_pk_fma_f32 v[118:119], v[110:111], v[140:141], v[118:119]
	v_pk_fma_f32 v[160:161], v[92:93], v[160:161], v[84:85]
	v_mov_b32_dpp v164, v163 row_ror:1 row_mask:0xf bank_mask:0xf
	v_cndmask_b32_e64 v163, v142, v146, s[48:49]
	v_pk_fma_f32 v[158:159], v[88:89], v[158:159], v[160:161]
	v_and_b32_e32 v161, 0x7fffffff, v119
	v_mov_b32_dpp v146, v163 row_ror:2 row_mask:0xf bank_mask:0xf
	v_cndmask_b32_e64 v163, v116, v166, s[50:51]
	v_and_b32_e32 v160, 0x7fffffff, v118
	v_pk_fma_f32 v[160:161], v[160:161], s[6:7], 1.0 op_sel_hi:[1,0,0]
	v_mov_b32_dpp v234, v163 row_ror:1 row_mask:0xf bank_mask:0xf
	v_cndmask_b32_e64 v163, v116, v166, s[48:49]
	v_rcp_f32_e32 v160, v160
	v_rcp_f32_e32 v161, v161
	v_mov_b32_dpp v166, v163 row_ror:2 row_mask:0xf bank_mask:0xf
	v_cndmask_b32_e64 v163, v143, v147, s[50:51]
	v_cmp_gt_f32_e32 vcc, 0, v118
	v_pk_fma_f32 v[158:159], v[80:81], v[114:115], v[158:159]
	v_mov_b32_dpp v165, v163 row_ror:1 row_mask:0xf bank_mask:0xf
	v_cndmask_b32_e64 v163, v143, v147, s[48:49]
	s_nop 1
	v_mov_b32_dpp v147, v163 row_ror:2 row_mask:0xf bank_mask:0xf
	v_cndmask_b32_e64 v163, v117, v167, s[50:51]
	v_pk_fma_f32 v[146:147], v[104:105], v[146:147], v[100:101]
	s_nop 0
	v_mov_b32_dpp v235, v163 row_ror:1 row_mask:0xf bank_mask:0xf
	v_cndmask_b32_e64 v163, v117, v167, s[48:49]
	v_pk_fma_f32 v[144:145], v[108:109], v[164:165], v[146:147]
	v_mov_b64_e32 v[164:165], s[18:19]
	v_mov_b32_dpp v167, v163 row_ror:2 row_mask:0xf bank_mask:0xf
	v_pk_fma_f32 v[146:147], v[94:95], v[166:167], v[86:87]
	v_pk_fma_f32 v[166:167], v[160:161], s[24:25], v[164:165] op_sel_hi:[1,0,0]
	v_pk_fma_f32 v[146:147], v[90:91], v[234:235], v[146:147]
	v_pk_mul_f32 v[234:235], v[118:119], v[118:119]
	v_pk_fma_f32 v[166:167], v[160:161], v[166:167], s[28:29] op_sel_hi:[1,1,0]
	v_pk_mul_f32 v[234:235], v[234:235], s[36:37] op_sel_hi:[1,0]
	v_pk_fma_f32 v[166:167], v[160:161], v[166:167], s[30:31] op_sel_hi:[1,1,0]
	v_exp_f32_e32 v234, v234
	v_exp_f32_e32 v235, v235
	v_pk_fma_f32 v[166:167], v[160:161], v[166:167], s[34:35] op_sel_hi:[1,1,0]
	v_pk_fma_f32 v[144:145], v[112:113], v[142:143], v[144:145]
	v_pk_mul_f32 v[160:161], v[160:161], v[166:167]
	v_pk_mul_f32 v[166:167], v[144:145], v[144:145]
	v_pk_mul_f32 v[160:161], v[234:235], v[160:161]
	v_pk_fma_f32 v[146:147], v[82:83], v[116:117], v[146:147]
	v_pk_mul_f32 v[234:235], v[118:119], v[160:161]
	v_pk_fma_f32 v[160:161], v[118:119], v[160:161], v[118:119] neg_lo:[1,0,0] neg_hi:[1,0,0]
	v_and_b32_e32 v118, 0x7fffffff, v144
	v_cndmask_b32_e32 v163, v160, v234, vcc
	v_cmp_gt_f32_e32 vcc, 0, v119
	v_and_b32_e32 v119, 0x7fffffff, v145
	v_pk_fma_f32 v[118:119], v[118:119], s[6:7], 1.0 op_sel_hi:[1,0,0]
	v_cndmask_b32_e32 v171, v161, v235, vcc
	v_rcp_f32_e32 v118, v118
	v_rcp_f32_e32 v119, v119
	v_cmp_gt_f32_e32 vcc, 0, v144
	v_pk_fma_f32 v[160:161], v[118:119], s[24:25], v[164:165] op_sel_hi:[1,0,0]
	s_nop 0
	v_pk_fma_f32 v[160:161], v[118:119], v[160:161], s[28:29] op_sel_hi:[1,1,0]
	s_nop 0
	v_pk_fma_f32 v[160:161], v[118:119], v[160:161], s[30:31] op_sel_hi:[1,1,0]
	s_nop 0
	v_pk_fma_f32 v[160:161], v[118:119], v[160:161], s[34:35] op_sel_hi:[1,1,0]
	s_nop 0
	v_pk_mul_f32 v[118:119], v[118:119], v[160:161]
	v_pk_mul_f32 v[160:161], v[166:167], s[36:37] op_sel_hi:[1,0]
	s_nop 0
	v_exp_f32_e32 v160, v160
	v_exp_f32_e32 v161, v161
	s_nop 0
	v_pk_mul_f32 v[118:119], v[160:161], v[118:119]
	s_nop 0
	v_pk_mul_f32 v[160:161], v[144:145], v[118:119]
	v_pk_fma_f32 v[118:119], v[144:145], v[118:119], v[144:145] neg_lo:[1,0,0] neg_hi:[1,0,0]
	s_nop 0
	v_cndmask_b32_e32 v144, v118, v160, vcc
	v_cmp_gt_f32_e32 vcc, 0, v145
	v_mul_f32_e32 v118, v158, v163
	v_mul_f32_e32 v144, v146, v144
	v_cndmask_b32_e32 v119, v119, v161, vcc
	v_mul_f32_e32 v119, v147, v119
	v_mul_f32_e32 v145, v159, v171
	v_cvt_pk_bf16_f32 v118, v118, v145
	v_cvt_pk_bf16_f32 v119, v144, v119
	s_mov_b64 s[72:73], 0
	s_movk_i32 s18, 0x3ffd
	s_mov_b64 s[74:75], 0
	v_cndmask_b32_e64 v145, v152, v140, s[50:51]
	v_cndmask_b32_e64 v147, v153, v141, s[50:51]
	s_nop 0
	v_mov_b32_dpp v144, v145 row_ror:1 row_mask:0xf bank_mask:0xf
	v_cndmask_b32_e64 v145, v152, v140, s[48:49]
	v_cndmask_b32_e64 v158, v149, v115, s[50:51]
	v_cndmask_b32_e64 v159, v154, v142, s[50:51]
	v_mov_b32_dpp v140, v145 row_ror:2 row_mask:0xf bank_mask:0xf
; #define LAS __attribute__((address_space(3)))
; __device__ __forceinline__ unsigned cvt_pk_bf16(float lo, float hi) { unsigned r; asm volatile("v_cvt_pk_bf16_f32 %0, %1, %2" : "=v"(r) : "v"(lo), "v"(hi)); return r; }
;     __device__ __forceinline__ void operator()(AccT& acc, const Unit& u, int wr, int wc, int fr, int fq) const {
;     ...
;             for (int ai = 0; ai < 2; ++ai) {
;                 f32x4 hg = (f32x4){0.f, 0.f, 0.f, 0.f}, hv = hg;
;                 const int s = ai * 2 + wr;
;                 if (s > 0 && fr >= 14) {
;                     hg = *(const LAS f32x4*)(xch + (((s - 1) * 2 + (fr - 14)) * 256 + wc * 32 + fq * 8 + n * 4));
;                     hv = *(const LAS f32x4*)(xch + (((s - 1) * 2 + (fr - 14)) * 256 + 128 + wc * 32 + fq * 8 + n * 4));
;                 }
; #pragma unroll
;                 for (int m = 0; m < 4; ++m) {
;                     const int rl = ai * 128 + wr * 64 + m * 16 + fr;
;                     const f32x4 cg_ = acc[ai][0][m][n], cv_ = acc[ai][1][m][n];
;                     f32x4 p1g, p2g, p1v, p2v;
; #pragma unroll
;                     for (int j = 0; j < 4; ++j) {
;                         p1g[j] = ror1(fr == 15 ? hg[j] : cg_[j]); p2g[j] = ror2(fr >= 14 ? hg[j] : cg_[j]);
;                         p1v[j] = ror1(fr == 15 ? hv[j] : cv_[j]); p2v[j] = ror2(fr >= 14 ? hv[j] : cv_[j]);
;                     }
;                     const f32x4 hcg = bg + w0g * p2g + w1g * p1g + w2g * cg_;
;                     const f32x4 hcv = bv + w0v * p2v + w1v * p1v + w2v * cv_;
;                     const f32x2 ga = gelu_pk((f32x2){hcg[0], hcg[1]}), gb2 = gelu_pk((f32x2){hcg[2], hcg[3]});
;                     u32x2 w; w.x = cvt_pk_bf16(ga.x * hcv[0], ga.y * hcv[1]); w.y = cvt_pk_bf16(gb2.x * hcv[2], gb2.y * hcv[3]);
;                     const int t = tstart + rl;
;                     if (n == 0) stash[ai][m] = w;
;                     else if (rl >= 2) *(u32x4*)(U + (size_t)(arow0 + rl) * FF + colg0) = (u32x4){stash[ai][m].x, stash[ai][m].y, w.x, w.y};
;                     if (rl < 2 || rl >= 254) { float* hp = halo + ((size_t)u.pm * 4 + (rl < 2 ? rl : rl - 252)) * FF2; *(f32x4*)(hp + colg) = cg_; *(f32x4*)(hp + colv) = cv_; }
;                     if (t >= SEQ - 2) { float* cp = conv_p + (size_t)(b * 2 + (t - (SEQ - 2))) * FF2; *(f32x4*)(cp + colg) = cg_; *(f32x4*)(cp + colv) = cv_; }
	v_cndmask_b32_e64 v145, v148, v114, s[50:51]
	v_cndmask_b32_e64 v163, v155, v143, s[50:51]
	s_nop 0
	v_mov_b32_dpp v146, v145 row_ror:1 row_mask:0xf bank_mask:0xf
	v_cndmask_b32_e64 v145, v148, v114, s[48:49]
	s_mov_b32 s18, 0xbf3a00e3
	s_nop 0
	v_mov_b32_dpp v114, v145 row_ror:2 row_mask:0xf bank_mask:0xf
	s_nop 1
	v_mov_b32_dpp v145, v147 row_ror:1 row_mask:0xf bank_mask:0xf
	v_cndmask_b32_e64 v147, v153, v141, s[48:49]
	s_nop 1
	v_mov_b32_dpp v141, v147 row_ror:2 row_mask:0xf bank_mask:0xf
	v_pk_fma_f32 v[140:141], v[102:103], v[140:141], v[98:99]
	s_nop 0
	v_mov_b32_dpp v147, v158 row_ror:1 row_mask:0xf bank_mask:0xf
	v_cndmask_b32_e64 v158, v149, v115, s[48:49]
	v_pk_fma_f32 v[140:141], v[106:107], v[144:145], v[140:141]
	s_nop 0
	v_mov_b32_dpp v115, v158 row_ror:2 row_mask:0xf bank_mask:0xf
	v_pk_fma_f32 v[140:141], v[110:111], v[152:153], v[140:141]
	v_pk_fma_f32 v[114:115], v[92:93], v[114:115], v[84:85]
	v_mov_b32_dpp v158, v159 row_ror:1 row_mask:0xf bank_mask:0xf
	v_cndmask_b32_e64 v159, v154, v142, s[48:49]
	v_pk_fma_f32 v[114:115], v[88:89], v[146:147], v[114:115]
	v_mov_b64_e32 v[146:147], s[18:19]
	v_mov_b32_dpp v142, v159 row_ror:2 row_mask:0xf bank_mask:0xf
	v_cndmask_b32_e64 v159, v150, v116, s[50:51]
	v_cmp_gt_f32_e32 vcc, 0, v140
	v_pk_fma_f32 v[114:115], v[80:81], v[148:149], v[114:115]
	v_mov_b32_dpp v164, v159 row_ror:1 row_mask:0xf bank_mask:0xf
	v_cndmask_b32_e64 v159, v150, v116, s[48:49]
	s_nop 1
	v_mov_b32_dpp v116, v159 row_ror:2 row_mask:0xf bank_mask:0xf
	s_nop 1
	v_mov_b32_dpp v159, v163 row_ror:1 row_mask:0xf bank_mask:0xf
	v_cndmask_b32_e64 v163, v155, v143, s[48:49]
	s_nop 1
	v_mov_b32_dpp v143, v163 row_ror:2 row_mask:0xf bank_mask:0xf
	v_cndmask_b32_e64 v163, v151, v117, s[50:51]
	v_pk_fma_f32 v[142:143], v[104:105], v[142:143], v[100:101]
	s_nop 0
	v_mov_b32_dpp v165, v163 row_ror:1 row_mask:0xf bank_mask:0xf
	v_cndmask_b32_e64 v163, v151, v117, s[48:49]
	v_pk_fma_f32 v[142:143], v[108:109], v[158:159], v[142:143]
	s_nop 0
	v_mov_b32_dpp v117, v163 row_ror:2 row_mask:0xf bank_mask:0xf
	v_pk_fma_f32 v[116:117], v[94:95], v[116:117], v[86:87]
	v_pk_fma_f32 v[142:143], v[112:113], v[154:155], v[142:143]
	v_pk_fma_f32 v[116:117], v[90:91], v[164:165], v[116:117]
	v_pk_mul_f32 v[164:165], v[140:141], v[140:141]
	v_pk_fma_f32 v[144:145], v[82:83], v[150:151], v[116:117]
	v_and_b32_e32 v117, 0x7fffffff, v141
	v_and_b32_e32 v116, 0x7fffffff, v140
	v_pk_fma_f32 v[116:117], v[116:117], s[6:7], 1.0 op_sel_hi:[1,0,0]
	v_pk_mul_f32 v[164:165], v[164:165], s[36:37] op_sel_hi:[1,0]
	v_rcp_f32_e32 v116, v116
	v_rcp_f32_e32 v117, v117
	v_exp_f32_e32 v164, v164
	v_exp_f32_e32 v165, v165
	v_pk_fma_f32 v[158:159], v[116:117], s[24:25], v[146:147] op_sel_hi:[1,0,0]
	s_nop 0
	v_pk_fma_f32 v[158:159], v[116:117], v[158:159], s[28:29] op_sel_hi:[1,1,0]
	s_nop 0
	v_pk_fma_f32 v[158:159], v[116:117], v[158:159], s[30:31] op_sel_hi:[1,1,0]
	s_nop 0
	v_pk_fma_f32 v[158:159], v[116:117], v[158:159], s[34:35] op_sel_hi:[1,1,0]
	s_nop 0
	v_pk_mul_f32 v[116:117], v[116:117], v[158:159]
	v_pk_mul_f32 v[158:159], v[142:143], v[142:143]
	v_pk_mul_f32 v[116:117], v[164:165], v[116:117]
	s_nop 0
	v_pk_mul_f32 v[164:165], v[140:141], v[116:117]
	v_pk_fma_f32 v[116:117], v[140:141], v[116:117], v[140:141] neg_lo:[1,0,0] neg_hi:[1,0,0]
	s_nop 0
	v_cndmask_b32_e32 v163, v116, v164, vcc
	v_cmp_gt_f32_e32 vcc, 0, v141
	v_and_b32_e32 v116, 0x7fffffff, v142
	v_mul_f32_e32 v114, v114, v163
	v_cndmask_b32_e32 v164, v117, v165, vcc
	v_and_b32_e32 v117, 0x7fffffff, v143
	v_pk_fma_f32 v[116:117], v[116:117], s[6:7], 1.0 op_sel_hi:[1,0,0]
	v_cmp_gt_f32_e32 vcc, 0, v142
	v_rcp_f32_e32 v116, v116
	v_rcp_f32_e32 v117, v117
	v_mul_f32_e32 v115, v115, v164
	v_pk_fma_f32 v[140:141], v[116:117], s[24:25], v[146:147] op_sel_hi:[1,0,0]
	s_nop 0
	v_pk_fma_f32 v[140:141], v[116:117], v[140:141], s[28:29] op_sel_hi:[1,1,0]
	s_nop 0
	v_pk_fma_f32 v[140:141], v[116:117], v[140:141], s[30:31] op_sel_hi:[1,1,0]
	s_nop 0
	v_pk_fma_f32 v[140:141], v[116:117], v[140:141], s[34:35] op_sel_hi:[1,1,0]
	s_nop 0
	v_pk_mul_f32 v[116:117], v[116:117], v[140:141]
	v_pk_mul_f32 v[140:141], v[158:159], s[36:37] op_sel_hi:[1,0]
	v_add_u32_e32 v158, 0xffffff34, v210
	v_exp_f32_e32 v140, v140
	v_exp_f32_e32 v141, v141
	s_nop 0
	v_pk_mul_f32 v[116:117], v[140:141], v[116:117]
	s_nop 0
	v_pk_mul_f32 v[140:141], v[142:143], v[116:117]
	v_pk_fma_f32 v[116:117], v[142:143], v[116:117], v[142:143] neg_lo:[1,0,0] neg_hi:[1,0,0]
	s_nop 0
	v_cndmask_b32_e32 v140, v116, v140, vcc
	v_cmp_gt_f32_e32 vcc, 0, v143
	v_cvt_pk_bf16_f32 v116, v114, v115
	v_mul_f32_e32 v114, v144, v140
	s_nop 0
	v_cndmask_b32_e32 v117, v117, v141, vcc
	v_mul_f32_e32 v115, v145, v117
	v_cvt_pk_bf16_f32 v117, v114, v115
	s_mov_b64 s[68:69], 0
	s_movk_i32 s18, 0x3ffd
	s_mov_b64 s[70:71], 0
	v_readlane_b32 s18, v246, 36
	v_readlane_b32 s19, v246, 37
	s_and_b64 s[18:19], s[18:19], s[48:49]
	v_mov_b32_e32 v144, 0
	v_mov_b32_e32 v145, 0
	v_mov_b32_e32 v146, 0
	v_mov_b32_e32 v147, 0
	v_mov_b32_e32 v148, 0
	v_mov_b32_e32 v149, 0
	v_mov_b32_e32 v150, 0
	v_mov_b32_e32 v151, 0
	s_and_saveexec_b64 s[22:23], s[18:19]
	s_cbranch_execz .LBB0_1050
	v_add_u32_e32 v115, 0xffffd000, v185
	v_add_u32_e32 v114, 0xffffd200, v185
	ds_read_b128 v[144:147], v115
	ds_read_b128 v[148:151], v114
; #define LAS __attribute__((address_space(3)))
; __device__ __forceinline__ unsigned cvt_pk_bf16(float lo, float hi) { unsigned r; asm volatile("v_cvt_pk_bf16_f32 %0, %1, %2" : "=v"(r) : "v"(lo), "v"(hi)); return r; }
;     __device__ __forceinline__ void operator()(AccT& acc, const Unit& u, int wr, int wc, int fr, int fq) const {
;     ...
;             for (int ai = 0; ai < 2; ++ai) {
;                 f32x4 hg = (f32x4){0.f, 0.f, 0.f, 0.f}, hv = hg;
;                 const int s = ai * 2 + wr;
;                 if (s > 0 && fr >= 14) {
;                     hg = *(const LAS f32x4*)(xch + (((s - 1) * 2 + (fr - 14)) * 256 + wc * 32 + fq * 8 + n * 4));
;                     hv = *(const LAS f32x4*)(xch + (((s - 1) * 2 + (fr - 14)) * 256 + 128 + wc * 32 + fq * 8 + n * 4));
;                 }
; #pragma unroll
;                 for (int m = 0; m < 4; ++m) {
;                     const int rl = ai * 128 + wr * 64 + m * 16 + fr;
;                     const f32x4 cg_ = acc[ai][0][m][n], cv_ = acc[ai][1][m][n];
;                     f32x4 p1g, p2g, p1v, p2v;
; #pragma unroll
;                     for (int j = 0; j < 4; ++j) {
;                         p1g[j] = ror1(fr == 15 ? hg[j] : cg_[j]); p2g[j] = ror2(fr >= 14 ? hg[j] : cg_[j]);
;                         p1v[j] = ror1(fr == 15 ? hv[j] : cv_[j]); p2v[j] = ror2(fr >= 14 ? hv[j] : cv_[j]);
;                     }
;                     const f32x4 hcg = bg + w0g * p2g + w1g * p1g + w2g * cg_;
;                     const f32x4 hcv = bv + w0v * p2v + w1v * p1v + w2v * cv_;
;                     const f32x2 ga = gelu_pk((f32x2){hcg[0], hcg[1]}), gb2 = gelu_pk((f32x2){hcg[2], hcg[3]});
;                     u32x2 w; w.x = cvt_pk_bf16(ga.x * hcv[0], ga.y * hcv[1]); w.y = cvt_pk_bf16(gb2.x * hcv[2], gb2.y * hcv[3]);
;                     const int t = tstart + rl;
;                     if (n == 0) stash[ai][m] = w;
;                     else if (rl >= 2) *(u32x4*)(U + (size_t)(arow0 + rl) * FF + colg0) = (u32x4){stash[ai][m].x, stash[ai][m].y, w.x, w.y};
;                     if (rl < 2 || rl >= 254) { float* hp = halo + ((size_t)u.pm * 4 + (rl < 2 ? rl : rl - 252)) * FF2; *(f32x4*)(hp + colg) = cg_; *(f32x4*)(hp + colv) = cv_; }
;                     if (t >= SEQ - 2) { float* cp = conv_p + (size_t)(b * 2 + (t - (SEQ - 2))) * FF2; *(f32x4*)(cp + colg) = cg_; *(f32x4*)(cp + colv) = cv_; }
.LBB0_1050:
	s_or_b64 exec, exec, s[22:23]
	v_fmamk_f32 v114, v191, 0x3a800000, v223
	v_rsq_f32_e32 v152, v114
	s_nop 0
	v_pk_mul_f32 v[136:137], v[136:137], v[152:153] op_sel_hi:[1,0]
	v_pk_mul_f32 v[140:141], v[132:133], v[152:153] op_sel_hi:[1,0]
	s_waitcnt lgkmcnt(0)
	v_cndmask_b32_e64 v115, v136, v144, s[50:51]
	v_pk_mul_f32 v[142:143], v[134:135], v[152:153] op_sel_hi:[1,0]
	s_nop 0
	v_mov_b32_dpp v114, v115 row_ror:1 row_mask:0xf bank_mask:0xf
	v_cndmask_b32_e64 v115, v136, v144, s[48:49]
	s_nop 1
	v_mov_b32_dpp v132, v115 row_ror:2 row_mask:0xf bank_mask:0xf
	v_cndmask_b32_e64 v115, v140, v148, s[50:51]
	v_cndmask_b32_e64 v133, v137, v145, s[50:51]
	v_cndmask_b32_e64 v135, v137, v145, s[48:49]
	v_mov_b32_dpp v134, v115 row_ror:1 row_mask:0xf bank_mask:0xf
	v_cndmask_b32_e64 v115, v140, v148, s[48:49]
	v_cndmask_b32_e64 v145, v141, v149, s[50:51]
	v_pk_mul_f32 v[138:139], v[138:139], v[152:153] op_sel_hi:[1,0]
	v_mov_b32_dpp v144, v115 row_ror:2 row_mask:0xf bank_mask:0xf
	v_cndmask_b32_e64 v148, v141, v149, s[48:49]
	v_cndmask_b32_e64 v149, v138, v146, s[50:51]
	v_mov_b32_dpp v115, v133 row_ror:1 row_mask:0xf bank_mask:0xf
	v_cndmask_b32_e64 v153, v139, v147, s[50:51]
	s_mov_b32 s22, 0xbf3a00e3
	v_mov_b32_dpp v133, v135 row_ror:2 row_mask:0xf bank_mask:0xf
	v_pk_fma_f32 v[132:133], v[102:103], v[132:133], v[98:99]
	s_nop 0
	v_mov_b32_dpp v135, v145 row_ror:1 row_mask:0xf bank_mask:0xf
	v_pk_fma_f32 v[114:115], v[106:107], v[114:115], v[132:133]
	s_nop 0
	v_mov_b32_dpp v145, v148 row_ror:2 row_mask:0xf bank_mask:0xf
	v_pk_fma_f32 v[114:115], v[110:111], v[136:137], v[114:115]
	v_pk_fma_f32 v[144:145], v[92:93], v[144:145], v[84:85]
	v_mov_b32_dpp v148, v149 row_ror:1 row_mask:0xf bank_mask:0xf
	v_cndmask_b32_e64 v149, v138, v146, s[48:49]
	v_pk_fma_f32 v[134:135], v[88:89], v[134:135], v[144:145]
	v_cmp_gt_f32_e32 vcc, 0, v114
	v_mov_b32_dpp v146, v149 row_ror:2 row_mask:0xf bank_mask:0xf
	v_cndmask_b32_e64 v149, v142, v150, s[50:51]
	v_pk_fma_f32 v[134:135], v[80:81], v[140:141], v[134:135]
	s_nop 0
	v_mov_b32_dpp v154, v149 row_ror:1 row_mask:0xf bank_mask:0xf
	v_cndmask_b32_e64 v149, v142, v150, s[48:49]
	s_nop 1
	v_mov_b32_dpp v150, v149 row_ror:2 row_mask:0xf bank_mask:0xf
	s_nop 1
	v_mov_b32_dpp v149, v153 row_ror:1 row_mask:0xf bank_mask:0xf
	v_cndmask_b32_e64 v153, v139, v147, s[48:49]
	s_nop 1
	v_mov_b32_dpp v147, v153 row_ror:2 row_mask:0xf bank_mask:0xf
	v_cndmask_b32_e64 v153, v143, v151, s[50:51]
	v_pk_fma_f32 v[146:147], v[104:105], v[146:147], v[100:101]
	s_nop 0
	v_mov_b32_dpp v155, v153 row_ror:1 row_mask:0xf bank_mask:0xf
	v_cndmask_b32_e64 v153, v143, v151, s[48:49]
	v_pk_fma_f32 v[132:133], v[108:109], v[148:149], v[146:147]
	v_mov_b64_e32 v[148:149], s[22:23]
	v_mov_b32_dpp v151, v153 row_ror:2 row_mask:0xf bank_mask:0xf
	v_pk_fma_f32 v[146:147], v[94:95], v[150:151], v[86:87]
	v_pk_fma_f32 v[132:133], v[112:113], v[138:139], v[132:133]
	v_pk_fma_f32 v[144:145], v[90:91], v[154:155], v[146:147]
	v_and_b32_e32 v147, 0x7fffffff, v115
	v_and_b32_e32 v146, 0x7fffffff, v114
	v_pk_fma_f32 v[146:147], v[146:147], s[6:7], 1.0 op_sel_hi:[1,0,0]
	v_pk_mul_f32 v[154:155], v[114:115], v[114:115]
	v_rcp_f32_e32 v146, v146
	v_rcp_f32_e32 v147, v147
	v_pk_mul_f32 v[154:155], v[154:155], s[36:37] op_sel_hi:[1,0]
	v_pk_fma_f32 v[144:145], v[82:83], v[142:143], v[144:145]
	v_exp_f32_e32 v154, v154
	v_pk_fma_f32 v[150:151], v[146:147], s[24:25], v[148:149] op_sel_hi:[1,0,0]
	v_exp_f32_e32 v155, v155
	v_pk_fma_f32 v[150:151], v[146:147], v[150:151], s[28:29] op_sel_hi:[1,1,0]
	s_nop 0
	v_pk_fma_f32 v[150:151], v[146:147], v[150:151], s[30:31] op_sel_hi:[1,1,0]
	s_nop 0
	v_pk_fma_f32 v[150:151], v[146:147], v[150:151], s[34:35] op_sel_hi:[1,1,0]
	s_nop 0
	v_pk_mul_f32 v[146:147], v[146:147], v[150:151]
	v_pk_mul_f32 v[150:151], v[132:133], v[132:133]
	v_pk_mul_f32 v[146:147], v[154:155], v[146:147]
	s_nop 0
	v_pk_mul_f32 v[154:155], v[114:115], v[146:147]
	v_pk_fma_f32 v[146:147], v[114:115], v[146:147], v[114:115] neg_lo:[1,0,0] neg_hi:[1,0,0]
	v_and_b32_e32 v114, 0x7fffffff, v132
	v_cndmask_b32_e32 v153, v146, v154, vcc
	v_cmp_gt_f32_e32 vcc, 0, v115
	v_and_b32_e32 v115, 0x7fffffff, v133
	v_pk_fma_f32 v[114:115], v[114:115], s[6:7], 1.0 op_sel_hi:[1,0,0]
	v_cndmask_b32_e32 v154, v147, v155, vcc
	v_rcp_f32_e32 v114, v114
	v_rcp_f32_e32 v115, v115
	v_cmp_gt_f32_e32 vcc, 0, v132
	v_pk_fma_f32 v[146:147], v[114:115], s[24:25], v[148:149] op_sel_hi:[1,0,0]
	s_nop 0
	v_pk_fma_f32 v[146:147], v[114:115], v[146:147], s[28:29] op_sel_hi:[1,1,0]
	s_nop 0
	v_pk_fma_f32 v[146:147], v[114:115], v[146:147], s[30:31] op_sel_hi:[1,1,0]
	s_nop 0
	v_pk_fma_f32 v[146:147], v[114:115], v[146:147], s[34:35] op_sel_hi:[1,1,0]
	s_nop 0
	v_pk_mul_f32 v[114:115], v[114:115], v[146:147]
	v_pk_mul_f32 v[146:147], v[150:151], s[36:37] op_sel_hi:[1,0]
	s_nop 0
	v_exp_f32_e32 v146, v146
	v_exp_f32_e32 v147, v147
	s_nop 0
	v_pk_mul_f32 v[114:115], v[146:147], v[114:115]
	s_nop 0
	v_pk_mul_f32 v[146:147], v[132:133], v[114:115]
	v_pk_fma_f32 v[114:115], v[132:133], v[114:115], v[132:133] neg_lo:[1,0,0] neg_hi:[1,0,0]
	s_nop 0
	v_cndmask_b32_e32 v132, v114, v146, vcc
	v_cmp_gt_f32_e32 vcc, 0, v133
	v_mul_f32_e32 v114, v134, v153
	v_mul_f32_e32 v132, v144, v132
	v_cndmask_b32_e32 v115, v115, v147, vcc
	v_mul_f32_e32 v115, v145, v115
	v_mul_f32_e32 v133, v135, v154
	v_cvt_pk_bf16_f32 v114, v114, v133
	v_cvt_pk_bf16_f32 v115, v132, v115
	s_mov_b64 s[64:65], 0
	s_movk_i32 s22, 0x3ffd
	s_mov_b64 s[66:67], 0
	v_fmamk_f32 v132, v189, 0x3a800000, v223
	v_rsq_f32_e32 v144, v132
	s_nop 0
	v_pk_mul_f32 v[78:79], v[78:79], v[144:145] op_sel_hi:[1,0]
; __device__ __forceinline__ unsigned cvt_pk_bf16(float lo, float hi) { unsigned r; asm volatile("v_cvt_pk_bf16_f32 %0, %1, %2" : "=v"(r) : "v"(lo), "v"(hi)); return r; }
; __device__ __forceinline__ float ror1(float x) { return __builtin_bit_cast(float, __builtin_amdgcn_update_dpp(0, __builtin_bit_cast(int, x), 0x121, 0xf, 0xf, false)); }
; __device__ __forceinline__ float ror2(float x) { return __builtin_bit_cast(float, __builtin_amdgcn_update_dpp(0, __builtin_bit_cast(int, x), 0x122, 0xf, 0xf, false)); }
;     __device__ __forceinline__ void operator()(AccT& acc, const Unit& u, int wr, int wc, int fr, int fq) const {
;     ...
;                 for (int m = 0; m < 4; ++m) {
;                     const int rl = ai * 128 + wr * 64 + m * 16 + fr;
;                     const f32x4 cg_ = acc[ai][0][m][n], cv_ = acc[ai][1][m][n];
;                     f32x4 p1g, p2g, p1v, p2v;
; #pragma unroll
;                     for (int j = 0; j < 4; ++j) {
;                         p1g[j] = ror1(fr == 15 ? hg[j] : cg_[j]); p2g[j] = ror2(fr >= 14 ? hg[j] : cg_[j]);
;                         p1v[j] = ror1(fr == 15 ? hv[j] : cv_[j]); p2v[j] = ror2(fr >= 14 ? hv[j] : cv_[j]);
;                     }
;                     const f32x4 hcg = bg + w0g * p2g + w1g * p1g + w2g * cg_;
;                     const f32x4 hcv = bv + w0v * p2v + w1v * p1v + w2v * cv_;
;                     const f32x2 ga = gelu_pk((f32x2){hcg[0], hcg[1]}), gb2 = gelu_pk((f32x2){hcg[2], hcg[3]});
;                     u32x2 w; w.x = cvt_pk_bf16(ga.x * hcv[0], ga.y * hcv[1]); w.y = cvt_pk_bf16(gb2.x * hcv[2], gb2.y * hcv[3]);
;                     const int t = tstart + rl;
;                     if (n == 0) stash[ai][m] = w;
;                     else if (rl >= 2) *(u32x4*)(U + (size_t)(arow0 + rl) * FF + colg0) = (u32x4){stash[ai][m].x, stash[ai][m].y, w.x, w.y};
;                     if (rl < 2 || rl >= 254) { float* hp = halo + ((size_t)u.pm * 4 + (rl < 2 ? rl : rl - 252)) * FF2; *(f32x4*)(hp + colg) = cg_; *(f32x4*)(hp + colv) = cv_; }
;                     if (t >= SEQ - 2) { float* cp = conv_p + (size_t)(b * 2 + (t - (SEQ - 2))) * FF2; *(f32x4*)(cp + colg) = cg_; *(f32x4*)(cp + colv) = cv_; }
	v_pk_mul_f32 v[76:77], v[76:77], v[144:145] op_sel_hi:[1,0]
	v_pk_mul_f32 v[134:135], v[74:75], v[144:145] op_sel_hi:[1,0]
	v_pk_mul_f32 v[132:133], v[72:73], v[144:145] op_sel_hi:[1,0]
	v_cndmask_b32_e64 v73, v76, v136, s[50:51]
	v_cndmask_b32_e64 v75, v77, v137, s[50:51]
	s_nop 0
	v_mov_b32_dpp v72, v73 row_ror:1 row_mask:0xf bank_mask:0xf
	v_cndmask_b32_e64 v73, v76, v136, s[48:49]
	v_cndmask_b32_e64 v137, v77, v137, s[48:49]
	s_nop 0
	v_mov_b32_dpp v74, v73 row_ror:2 row_mask:0xf bank_mask:0xf
	v_cndmask_b32_e64 v73, v132, v140, s[50:51]
	v_cndmask_b32_e64 v147, v133, v141, s[50:51]
	s_nop 0
	v_mov_b32_dpp v136, v73 row_ror:1 row_mask:0xf bank_mask:0xf
	v_cndmask_b32_e64 v73, v132, v140, s[48:49]
	s_nop 1
	v_mov_b32_dpp v140, v73 row_ror:2 row_mask:0xf bank_mask:0xf
	s_mov_b32 s22, 0xbf3a00e3
	v_mov_b32_dpp v73, v75 row_ror:1 row_mask:0xf bank_mask:0xf
	s_nop 1
	v_mov_b32_dpp v75, v137 row_ror:2 row_mask:0xf bank_mask:0xf
	v_pk_fma_f32 v[74:75], v[102:103], v[74:75], v[98:99]
	s_nop 0
	v_mov_b32_dpp v137, v147 row_ror:1 row_mask:0xf bank_mask:0xf
	v_cndmask_b32_e64 v147, v133, v141, s[48:49]
	v_pk_fma_f32 v[72:73], v[106:107], v[72:73], v[74:75]
	s_nop 0
	v_mov_b32_dpp v141, v147 row_ror:2 row_mask:0xf bank_mask:0xf
	v_cndmask_b32_e64 v147, v78, v138, s[50:51]
	v_pk_fma_f32 v[72:73], v[110:111], v[76:77], v[72:73]
	v_pk_fma_f32 v[140:141], v[92:93], v[140:141], v[84:85]
	v_mov_b32_dpp v148, v147 row_ror:1 row_mask:0xf bank_mask:0xf
	v_cndmask_b32_e64 v147, v78, v138, s[48:49]
	v_pk_fma_f32 v[136:137], v[88:89], v[136:137], v[140:141]
	v_and_b32_e32 v141, 0x7fffffff, v73
	v_mov_b32_dpp v138, v147 row_ror:2 row_mask:0xf bank_mask:0xf
	v_cndmask_b32_e64 v147, v134, v142, s[50:51]
	v_and_b32_e32 v140, 0x7fffffff, v72
	v_pk_fma_f32 v[140:141], v[140:141], s[6:7], 1.0 op_sel_hi:[1,0,0]
	v_mov_b32_dpp v150, v147 row_ror:1 row_mask:0xf bank_mask:0xf
	v_cndmask_b32_e64 v147, v134, v142, s[48:49]
	v_rcp_f32_e32 v140, v140
	v_rcp_f32_e32 v141, v141
	v_mov_b32_dpp v142, v147 row_ror:2 row_mask:0xf bank_mask:0xf
	v_cndmask_b32_e64 v147, v79, v139, s[50:51]
	v_cmp_gt_f32_e32 vcc, 0, v72
	v_pk_fma_f32 v[136:137], v[80:81], v[132:133], v[136:137]
	v_mov_b32_dpp v149, v147 row_ror:1 row_mask:0xf bank_mask:0xf
	v_cndmask_b32_e64 v147, v79, v139, s[48:49]
	s_nop 1
	v_mov_b32_dpp v139, v147 row_ror:2 row_mask:0xf bank_mask:0xf
	v_cndmask_b32_e64 v147, v135, v143, s[50:51]
	v_pk_fma_f32 v[138:139], v[104:105], v[138:139], v[100:101]
	s_nop 0
	v_mov_b32_dpp v151, v147 row_ror:1 row_mask:0xf bank_mask:0xf
	v_cndmask_b32_e64 v147, v135, v143, s[48:49]
	v_pk_fma_f32 v[74:75], v[108:109], v[148:149], v[138:139]
	s_nop 0
	v_mov_b32_dpp v143, v147 row_ror:2 row_mask:0xf bank_mask:0xf
	v_pk_fma_f32 v[138:139], v[94:95], v[142:143], v[86:87]
	v_mov_b64_e32 v[142:143], s[22:23]
	v_pk_fma_f32 v[138:139], v[90:91], v[150:151], v[138:139]
	v_pk_mul_f32 v[150:151], v[72:73], v[72:73]
	v_pk_fma_f32 v[148:149], v[140:141], s[24:25], v[142:143] op_sel_hi:[1,0,0]
	v_pk_mul_f32 v[150:151], v[150:151], s[36:37] op_sel_hi:[1,0]
	v_pk_fma_f32 v[148:149], v[140:141], v[148:149], s[28:29] op_sel_hi:[1,1,0]
	v_exp_f32_e32 v150, v150
	v_exp_f32_e32 v151, v151
	v_pk_fma_f32 v[148:149], v[140:141], v[148:149], s[30:31] op_sel_hi:[1,1,0]
	v_pk_fma_f32 v[74:75], v[112:113], v[78:79], v[74:75]
	v_pk_fma_f32 v[148:149], v[140:141], v[148:149], s[34:35] op_sel_hi:[1,1,0]
	v_pk_fma_f32 v[138:139], v[82:83], v[134:135], v[138:139]
	v_pk_mul_f32 v[140:141], v[140:141], v[148:149]
	v_pk_mul_f32 v[148:149], v[74:75], v[74:75]
	v_pk_mul_f32 v[140:141], v[150:151], v[140:141]
	s_nop 0
	v_pk_mul_f32 v[150:151], v[72:73], v[140:141]
	v_pk_fma_f32 v[140:141], v[72:73], v[140:141], v[72:73] neg_lo:[1,0,0] neg_hi:[1,0,0]
	v_and_b32_e32 v72, 0x7fffffff, v74
	v_cndmask_b32_e32 v147, v140, v150, vcc
	v_cmp_gt_f32_e32 vcc, 0, v73
	v_and_b32_e32 v73, 0x7fffffff, v75
	v_pk_fma_f32 v[72:73], v[72:73], s[6:7], 1.0 op_sel_hi:[1,0,0]
	v_cndmask_b32_e32 v150, v141, v151, vcc
	v_rcp_f32_e32 v72, v72
	v_rcp_f32_e32 v73, v73
	v_cmp_gt_f32_e32 vcc, 0, v74
	v_pk_fma_f32 v[140:141], v[72:73], s[24:25], v[142:143] op_sel_hi:[1,0,0]
	s_nop 0
	v_pk_fma_f32 v[140:141], v[72:73], v[140:141], s[28:29] op_sel_hi:[1,1,0]
	s_nop 0
	v_pk_fma_f32 v[140:141], v[72:73], v[140:141], s[30:31] op_sel_hi:[1,1,0]
	s_nop 0
	v_pk_fma_f32 v[140:141], v[72:73], v[140:141], s[34:35] op_sel_hi:[1,1,0]
	s_nop 0
	v_pk_mul_f32 v[72:73], v[72:73], v[140:141]
	v_pk_mul_f32 v[140:141], v[148:149], s[36:37] op_sel_hi:[1,0]
	s_nop 0
	v_exp_f32_e32 v140, v140
	v_exp_f32_e32 v141, v141
	s_nop 0
	v_pk_mul_f32 v[72:73], v[140:141], v[72:73]
	s_nop 0
	v_pk_mul_f32 v[140:141], v[74:75], v[72:73]
	v_pk_fma_f32 v[72:73], v[74:75], v[72:73], v[74:75] neg_lo:[1,0,0] neg_hi:[1,0,0]
	s_nop 0
	v_cndmask_b32_e32 v74, v72, v140, vcc
	v_cmp_gt_f32_e32 vcc, 0, v75
	v_mul_f32_e32 v72, v136, v147
	v_mul_f32_e32 v74, v138, v74
	v_cndmask_b32_e32 v73, v73, v141, vcc
	v_mul_f32_e32 v73, v139, v73
	v_mul_f32_e32 v75, v137, v150
	v_cvt_pk_bf16_f32 v72, v72, v75
	v_cvt_pk_bf16_f32 v73, v74, v73
	s_mov_b64 s[60:61], 0
	s_movk_i32 s22, 0x3ffd
	s_mov_b64 s[62:63], 0
	v_fmamk_f32 v74, v187, 0x3a800000, v223
	v_rsq_f32_e32 v140, v74
	s_nop 0
	v_pk_mul_f32 v[70:71], v[70:71], v[140:141] op_sel_hi:[1,0]
	v_pk_mul_f32 v[68:69], v[68:69], v[140:141] op_sel_hi:[1,0]
	v_pk_mul_f32 v[138:139], v[66:67], v[140:141] op_sel_hi:[1,0]
	v_pk_mul_f32 v[136:137], v[64:65], v[140:141] op_sel_hi:[1,0]
	v_cndmask_b32_e64 v65, v68, v76, s[50:51]
	s_nop 1
	v_mov_b32_dpp v64, v65 row_ror:1 row_mask:0xf bank_mask:0xf
	v_cndmask_b32_e64 v65, v68, v76, s[48:49]
	v_cndmask_b32_e64 v67, v69, v77, s[50:51]
; __device__ __forceinline__ unsigned cvt_pk_bf16(float lo, float hi) { unsigned r; asm volatile("v_cvt_pk_bf16_f32 %0, %1, %2" : "=v"(r) : "v"(lo), "v"(hi)); return r; }
; __device__ __forceinline__ float ror1(float x) { return __builtin_bit_cast(float, __builtin_amdgcn_update_dpp(0, __builtin_bit_cast(int, x), 0x121, 0xf, 0xf, false)); }
; __device__ __forceinline__ float ror2(float x) { return __builtin_bit_cast(float, __builtin_amdgcn_update_dpp(0, __builtin_bit_cast(int, x), 0x122, 0xf, 0xf, false)); }
;     __device__ __forceinline__ void operator()(AccT& acc, const Unit& u, int wr, int wc, int fr, int fq) const {
;     ...
;                 for (int m = 0; m < 4; ++m) {
;                     const int rl = ai * 128 + wr * 64 + m * 16 + fr;
;                     const f32x4 cg_ = acc[ai][0][m][n], cv_ = acc[ai][1][m][n];
;                     f32x4 p1g, p2g, p1v, p2v;
; #pragma unroll
;                     for (int j = 0; j < 4; ++j) {
;                         p1g[j] = ror1(fr == 15 ? hg[j] : cg_[j]); p2g[j] = ror2(fr >= 14 ? hg[j] : cg_[j]);
;                         p1v[j] = ror1(fr == 15 ? hv[j] : cv_[j]); p2v[j] = ror2(fr >= 14 ? hv[j] : cv_[j]);
;                     }
;                     const f32x4 hcg = bg + w0g * p2g + w1g * p1g + w2g * cg_;
;                     const f32x4 hcv = bv + w0v * p2v + w1v * p1v + w2v * cv_;
;                     const f32x2 ga = gelu_pk((f32x2){hcg[0], hcg[1]}), gb2 = gelu_pk((f32x2){hcg[2], hcg[3]});
;                     u32x2 w; w.x = cvt_pk_bf16(ga.x * hcv[0], ga.y * hcv[1]); w.y = cvt_pk_bf16(gb2.x * hcv[2], gb2.y * hcv[3]);
;                     const int t = tstart + rl;
;                     if (n == 0) stash[ai][m] = w;
;                     else if (rl >= 2) *(u32x4*)(U + (size_t)(arow0 + rl) * FF + colg0) = (u32x4){stash[ai][m].x, stash[ai][m].y, w.x, w.y};
;                     if (rl < 2 || rl >= 254) { float* hp = halo + ((size_t)u.pm * 4 + (rl < 2 ? rl : rl - 252)) * FF2; *(f32x4*)(hp + colg) = cg_; *(f32x4*)(hp + colv) = cv_; }
;                     if (t >= SEQ - 2) { float* cp = conv_p + (size_t)(b * 2 + (t - (SEQ - 2))) * FF2; *(f32x4*)(cp + colg) = cg_; *(f32x4*)(cp + colv) = cv_; }
	s_nop 0
	v_mov_b32_dpp v66, v65 row_ror:2 row_mask:0xf bank_mask:0xf
	v_cndmask_b32_e64 v65, v136, v132, s[50:51]
	v_cndmask_b32_e64 v75, v69, v77, s[48:49]
	v_cndmask_b32_e64 v77, v137, v133, s[50:51]
	v_mov_b32_dpp v74, v65 row_ror:1 row_mask:0xf bank_mask:0xf
	v_cndmask_b32_e64 v65, v136, v132, s[48:49]
	v_cndmask_b32_e64 v132, v137, v133, s[48:49]
	v_cndmask_b32_e64 v133, v70, v78, s[50:51]
	v_mov_b32_dpp v76, v65 row_ror:2 row_mask:0xf bank_mask:0xf
	v_cndmask_b32_e64 v143, v71, v79, s[50:51]
	v_mov_b32_dpp v65, v67 row_ror:1 row_mask:0xf bank_mask:0xf
	s_mov_b32 s22, 0xbf3a00e3
	v_mov_b32_dpp v67, v75 row_ror:2 row_mask:0xf bank_mask:0xf
	v_pk_fma_f32 v[66:67], v[102:103], v[66:67], v[98:99]
	s_nop 0
	v_mov_b32_dpp v75, v77 row_ror:1 row_mask:0xf bank_mask:0xf
	v_pk_fma_f32 v[64:65], v[106:107], v[64:65], v[66:67]
	s_nop 0
	v_mov_b32_dpp v77, v132 row_ror:2 row_mask:0xf bank_mask:0xf
	v_pk_fma_f32 v[64:65], v[110:111], v[68:69], v[64:65]
	v_pk_fma_f32 v[76:77], v[92:93], v[76:77], v[84:85]
	v_mov_b32_dpp v132, v133 row_ror:1 row_mask:0xf bank_mask:0xf
	v_cndmask_b32_e64 v133, v70, v78, s[48:49]
	v_pk_fma_f32 v[74:75], v[88:89], v[74:75], v[76:77]
	v_cmp_gt_f32_e32 vcc, 0, v64
	v_mov_b32_dpp v78, v133 row_ror:2 row_mask:0xf bank_mask:0xf
	v_cndmask_b32_e64 v133, v138, v134, s[50:51]
	v_pk_fma_f32 v[74:75], v[80:81], v[136:137], v[74:75]
	s_nop 0
	v_mov_b32_dpp v148, v133 row_ror:1 row_mask:0xf bank_mask:0xf
	v_cndmask_b32_e64 v133, v138, v134, s[48:49]
	s_nop 1
	v_mov_b32_dpp v134, v133 row_ror:2 row_mask:0xf bank_mask:0xf
	s_nop 1
	v_mov_b32_dpp v133, v143 row_ror:1 row_mask:0xf bank_mask:0xf
	v_cndmask_b32_e64 v143, v71, v79, s[48:49]
	s_nop 1
	v_mov_b32_dpp v79, v143 row_ror:2 row_mask:0xf bank_mask:0xf
	v_cndmask_b32_e64 v143, v139, v135, s[50:51]
	v_pk_fma_f32 v[78:79], v[104:105], v[78:79], v[100:101]
	s_nop 0
	v_mov_b32_dpp v149, v143 row_ror:1 row_mask:0xf bank_mask:0xf
	v_cndmask_b32_e64 v143, v139, v135, s[48:49]
	v_pk_fma_f32 v[66:67], v[108:109], v[132:133], v[78:79]
	v_mov_b64_e32 v[132:133], s[22:23]
	v_mov_b32_dpp v135, v143 row_ror:2 row_mask:0xf bank_mask:0xf
	v_pk_fma_f32 v[78:79], v[94:95], v[134:135], v[86:87]
	v_pk_fma_f32 v[66:67], v[112:113], v[70:71], v[66:67]
	v_pk_fma_f32 v[76:77], v[90:91], v[148:149], v[78:79]
	v_and_b32_e32 v79, 0x7fffffff, v65
	v_and_b32_e32 v78, 0x7fffffff, v64
	v_pk_fma_f32 v[78:79], v[78:79], s[6:7], 1.0 op_sel_hi:[1,0,0]
	v_pk_mul_f32 v[148:149], v[64:65], v[64:65]
	v_rcp_f32_e32 v78, v78
	v_rcp_f32_e32 v79, v79
	v_pk_mul_f32 v[148:149], v[148:149], s[36:37] op_sel_hi:[1,0]
	v_pk_fma_f32 v[76:77], v[82:83], v[138:139], v[76:77]
	v_exp_f32_e32 v148, v148
	v_pk_fma_f32 v[134:135], v[78:79], s[24:25], v[132:133] op_sel_hi:[1,0,0]
	v_exp_f32_e32 v149, v149
	v_pk_fma_f32 v[134:135], v[78:79], v[134:135], s[28:29] op_sel_hi:[1,1,0]
	s_nop 0
	v_pk_fma_f32 v[134:135], v[78:79], v[134:135], s[30:31] op_sel_hi:[1,1,0]
	s_nop 0
	v_pk_fma_f32 v[134:135], v[78:79], v[134:135], s[34:35] op_sel_hi:[1,1,0]
	s_nop 0
	v_pk_mul_f32 v[78:79], v[78:79], v[134:135]
	v_pk_mul_f32 v[134:135], v[66:67], v[66:67]
	v_pk_mul_f32 v[78:79], v[148:149], v[78:79]
	s_nop 0
	v_pk_mul_f32 v[148:149], v[64:65], v[78:79]
	v_pk_fma_f32 v[78:79], v[64:65], v[78:79], v[64:65] neg_lo:[1,0,0] neg_hi:[1,0,0]
	v_and_b32_e32 v64, 0x7fffffff, v66
	v_cndmask_b32_e32 v143, v78, v148, vcc
	v_cmp_gt_f32_e32 vcc, 0, v65
	v_and_b32_e32 v65, 0x7fffffff, v67
	v_pk_fma_f32 v[64:65], v[64:65], s[6:7], 1.0 op_sel_hi:[1,0,0]
	v_cndmask_b32_e32 v147, v79, v149, vcc
	v_rcp_f32_e32 v64, v64
	v_rcp_f32_e32 v65, v65
	v_cmp_gt_f32_e32 vcc, 0, v66
	v_pk_fma_f32 v[78:79], v[64:65], s[24:25], v[132:133] op_sel_hi:[1,0,0]
	s_nop 0
	v_pk_fma_f32 v[78:79], v[64:65], v[78:79], s[28:29] op_sel_hi:[1,1,0]
	s_nop 0
	v_pk_fma_f32 v[78:79], v[64:65], v[78:79], s[30:31] op_sel_hi:[1,1,0]
	s_nop 0
	v_pk_fma_f32 v[78:79], v[64:65], v[78:79], s[34:35] op_sel_hi:[1,1,0]
	s_nop 0
	v_pk_mul_f32 v[64:65], v[64:65], v[78:79]
	v_pk_mul_f32 v[78:79], v[134:135], s[36:37] op_sel_hi:[1,0]
	v_add_u32_e32 v134, 0xffffffa4, v210
	v_exp_f32_e32 v78, v78
	v_exp_f32_e32 v79, v79
	s_nop 0
	v_pk_mul_f32 v[64:65], v[78:79], v[64:65]
	s_nop 0
	v_pk_mul_f32 v[78:79], v[66:67], v[64:65]
	v_pk_fma_f32 v[64:65], v[66:67], v[64:65], v[66:67] neg_lo:[1,0,0] neg_hi:[1,0,0]
	v_mul_f32_e32 v66, v74, v143
	v_cndmask_b32_e32 v64, v64, v78, vcc
	v_cmp_gt_f32_e32 vcc, 0, v67
	v_mul_f32_e32 v67, v75, v147
	v_mul_f32_e32 v64, v76, v64
	v_cndmask_b32_e32 v65, v65, v79, vcc
	v_cvt_pk_bf16_f32 v66, v66, v67
	v_mul_f32_e32 v65, v77, v65
	v_cvt_pk_bf16_f32 v67, v64, v65
	s_mov_b64 s[56:57], 0
	s_movk_i32 s22, 0x3ffd
	s_mov_b64 s[58:59], 0
	v_cndmask_b32_e64 v65, v124, v68, s[50:51]
	s_nop 1
	v_mov_b32_dpp v64, v65 row_ror:1 row_mask:0xf bank_mask:0xf
	v_cndmask_b32_e64 v65, v124, v68, s[48:49]
	v_cndmask_b32_e64 v75, v125, v69, s[50:51]
	v_cndmask_b32_e64 v77, v129, v137, s[50:51]
	v_mov_b32_dpp v68, v65 row_ror:2 row_mask:0xf bank_mask:0xf
	v_cndmask_b32_e64 v65, v128, v136, s[50:51]
	v_cndmask_b32_e64 v78, v129, v137, s[48:49]
	v_cndmask_b32_e64 v79, v126, v70, s[50:51]
	v_mov_b32_dpp v74, v65 row_ror:1 row_mask:0xf bank_mask:0xf
	v_cndmask_b32_e64 v65, v128, v136, s[48:49]
	s_nop 1
	v_mov_b32_dpp v76, v65 row_ror:2 row_mask:0xf bank_mask:0xf
	v_cndmask_b32_e64 v133, v127, v71, s[50:51]
; __device__ __forceinline__ unsigned cvt_pk_bf16(float lo, float hi) { unsigned r; asm volatile("v_cvt_pk_bf16_f32 %0, %1, %2" : "=v"(r) : "v"(lo), "v"(hi)); return r; }
; __device__ __forceinline__ float ror1(float x) { return __builtin_bit_cast(float, __builtin_amdgcn_update_dpp(0, __builtin_bit_cast(int, x), 0x121, 0xf, 0xf, false)); }
; __device__ __forceinline__ float ror2(float x) { return __builtin_bit_cast(float, __builtin_amdgcn_update_dpp(0, __builtin_bit_cast(int, x), 0x122, 0xf, 0xf, false)); }
;     __device__ __forceinline__ void operator()(AccT& acc, const Unit& u, int wr, int wc, int fr, int fq) const {
;     ...
;                 for (int m = 0; m < 4; ++m) {
;                     const int rl = ai * 128 + wr * 64 + m * 16 + fr;
;                     const f32x4 cg_ = acc[ai][0][m][n], cv_ = acc[ai][1][m][n];
;                     f32x4 p1g, p2g, p1v, p2v;
; #pragma unroll
;                     for (int j = 0; j < 4; ++j) {
;                         p1g[j] = ror1(fr == 15 ? hg[j] : cg_[j]); p2g[j] = ror2(fr >= 14 ? hg[j] : cg_[j]);
;                         p1v[j] = ror1(fr == 15 ? hv[j] : cv_[j]); p2v[j] = ror2(fr >= 14 ? hv[j] : cv_[j]);
;                     }
;                     const f32x4 hcg = bg + w0g * p2g + w1g * p1g + w2g * cg_;
;                     const f32x4 hcv = bv + w0v * p2v + w1v * p1v + w2v * cv_;
;                     const f32x2 ga = gelu_pk((f32x2){hcg[0], hcg[1]}), gb2 = gelu_pk((f32x2){hcg[2], hcg[3]});
;                     u32x2 w; w.x = cvt_pk_bf16(ga.x * hcv[0], ga.y * hcv[1]); w.y = cvt_pk_bf16(gb2.x * hcv[2], gb2.y * hcv[3]);
;                     const int t = tstart + rl;
;                     if (n == 0) stash[ai][m] = w;
;                     else if (rl >= 2) *(u32x4*)(U + (size_t)(arow0 + rl) * FF + colg0) = (u32x4){stash[ai][m].x, stash[ai][m].y, w.x, w.y};
;                     if (rl < 2 || rl >= 254) { float* hp = halo + ((size_t)u.pm * 4 + (rl < 2 ? rl : rl - 252)) * FF2; *(f32x4*)(hp + colg) = cg_; *(f32x4*)(hp + colv) = cv_; }
;                     if (t >= SEQ - 2) { float* cp = conv_p + (size_t)(b * 2 + (t - (SEQ - 2))) * FF2; *(f32x4*)(cp + colg) = cg_; *(f32x4*)(cp + colv) = cv_; }
	v_cndmask_b32_e64 v137, v131, v139, s[50:51]
	v_mov_b32_dpp v65, v75 row_ror:1 row_mask:0xf bank_mask:0xf
	v_cndmask_b32_e64 v75, v125, v69, s[48:49]
	s_mov_b32 s22, 0xbf3a00e3
	s_nop 0
	v_mov_b32_dpp v69, v75 row_ror:2 row_mask:0xf bank_mask:0xf
	v_pk_fma_f32 v[68:69], v[102:103], v[68:69], v[98:99]
	s_nop 0
	v_mov_b32_dpp v75, v77 row_ror:1 row_mask:0xf bank_mask:0xf
	v_pk_fma_f32 v[64:65], v[106:107], v[64:65], v[68:69]
	s_nop 0
	v_mov_b32_dpp v77, v78 row_ror:2 row_mask:0xf bank_mask:0xf
	v_pk_fma_f32 v[64:65], v[110:111], v[124:125], v[64:65]
	v_pk_fma_f32 v[76:77], v[92:93], v[76:77], v[84:85]
	v_mov_b32_dpp v78, v79 row_ror:1 row_mask:0xf bank_mask:0xf
	v_cndmask_b32_e64 v79, v126, v70, s[48:49]
	v_pk_fma_f32 v[74:75], v[88:89], v[74:75], v[76:77]
	v_and_b32_e32 v77, 0x7fffffff, v65
	v_mov_b32_dpp v70, v79 row_ror:2 row_mask:0xf bank_mask:0xf
	v_cndmask_b32_e64 v79, v130, v138, s[50:51]
	v_and_b32_e32 v76, 0x7fffffff, v64
	v_pk_fma_f32 v[76:77], v[76:77], s[6:7], 1.0 op_sel_hi:[1,0,0]
	v_mov_b32_dpp v132, v79 row_ror:1 row_mask:0xf bank_mask:0xf
	v_cndmask_b32_e64 v79, v130, v138, s[48:49]
	v_cndmask_b32_e64 v138, v131, v139, s[48:49]
	v_rcp_f32_e32 v76, v76
	v_mov_b32_dpp v136, v79 row_ror:2 row_mask:0xf bank_mask:0xf
	v_rcp_f32_e32 v77, v77
	v_pk_fma_f32 v[74:75], v[80:81], v[128:129], v[74:75]
	v_mov_b32_dpp v79, v133 row_ror:1 row_mask:0xf bank_mask:0xf
	v_cndmask_b32_e64 v133, v127, v71, s[48:49]
	v_cmp_gt_f32_e32 vcc, 0, v64
	s_nop 0
	v_mov_b32_dpp v71, v133 row_ror:2 row_mask:0xf bank_mask:0xf
	v_pk_fma_f32 v[70:71], v[104:105], v[70:71], v[100:101]
	s_nop 0
	v_mov_b32_dpp v133, v137 row_ror:1 row_mask:0xf bank_mask:0xf
	v_pk_fma_f32 v[68:69], v[108:109], v[78:79], v[70:71]
	v_mov_b64_e32 v[78:79], s[22:23]
	v_mov_b32_dpp v137, v138 row_ror:2 row_mask:0xf bank_mask:0xf
	v_pk_fma_f32 v[70:71], v[94:95], v[136:137], v[86:87]
	v_pk_fma_f32 v[80:81], v[76:77], s[24:25], v[78:79] op_sel_hi:[1,0,0]
	v_pk_fma_f32 v[70:71], v[90:91], v[132:133], v[70:71]
	v_pk_fma_f32 v[68:69], v[112:113], v[126:127], v[68:69]
	v_pk_fma_f32 v[70:71], v[82:83], v[130:131], v[70:71]
	v_pk_mul_f32 v[82:83], v[64:65], v[64:65]
	v_pk_fma_f32 v[80:81], v[76:77], v[80:81], s[28:29] op_sel_hi:[1,1,0]
	v_pk_mul_f32 v[82:83], v[82:83], s[36:37] op_sel_hi:[1,0]
	v_pk_fma_f32 v[80:81], v[76:77], v[80:81], s[30:31] op_sel_hi:[1,1,0]
	v_exp_f32_e32 v82, v82
	v_exp_f32_e32 v83, v83
	v_and_b32_e32 v85, 0x7fffffff, v69
	v_and_b32_e32 v84, 0x7fffffff, v68
	v_pk_fma_f32 v[80:81], v[76:77], v[80:81], s[34:35] op_sel_hi:[1,1,0]
	v_pk_fma_f32 v[84:85], v[84:85], s[6:7], 1.0 op_sel_hi:[1,0,0]
	v_pk_mul_f32 v[76:77], v[76:77], v[80:81]
	v_rcp_f32_e32 v84, v84
	v_rcp_f32_e32 v85, v85
	v_pk_mul_f32 v[76:77], v[82:83], v[76:77]
	v_pk_mul_f32 v[80:81], v[68:69], v[68:69]
	v_pk_mul_f32 v[82:83], v[64:65], v[76:77]
	v_pk_fma_f32 v[76:77], v[64:65], v[76:77], v[64:65] neg_lo:[1,0,0] neg_hi:[1,0,0]
	v_add_u32_e32 v132, 0xffffffb4, v210
	v_cndmask_b32_e32 v82, v76, v82, vcc
	v_cmp_gt_f32_e32 vcc, 0, v65
	v_pk_fma_f32 v[64:65], v[84:85], s[24:25], v[78:79] op_sel_hi:[1,0,0]
	s_nop 0
	v_cndmask_b32_e32 v83, v77, v83, vcc
	v_pk_mul_f32 v[76:77], v[80:81], s[36:37] op_sel_hi:[1,0]
	v_pk_fma_f32 v[64:65], v[84:85], v[64:65], s[28:29] op_sel_hi:[1,1,0]
	v_exp_f32_e32 v76, v76
	v_exp_f32_e32 v77, v77
	v_pk_fma_f32 v[64:65], v[84:85], v[64:65], s[30:31] op_sel_hi:[1,1,0]
	v_cmp_gt_f32_e32 vcc, 0, v68
	v_pk_fma_f32 v[64:65], v[84:85], v[64:65], s[34:35] op_sel_hi:[1,1,0]
	s_nop 0
	v_pk_mul_f32 v[64:65], v[84:85], v[64:65]
	s_nop 0
	v_pk_mul_f32 v[64:65], v[76:77], v[64:65]
	s_nop 0
	v_pk_mul_f32 v[76:77], v[68:69], v[64:65]
	v_pk_fma_f32 v[64:65], v[68:69], v[64:65], v[68:69] neg_lo:[1,0,0] neg_hi:[1,0,0]
	s_nop 0
	v_cndmask_b32_e32 v68, v64, v76, vcc
	v_cmp_gt_f32_e32 vcc, 0, v69
	v_mul_f32_e32 v64, v74, v82
	v_mul_f32_e32 v68, v70, v68
	v_cndmask_b32_e32 v65, v65, v77, vcc
	v_mul_f32_e32 v65, v71, v65
	v_mul_f32_e32 v69, v75, v83
	v_cvt_pk_bf16_f32 v64, v64, v69
	v_cvt_pk_bf16_f32 v65, v68, v65
	v_add_u32_e32 v68, 0xffffffb2, v210
	v_cmp_gt_u32_e64 s[52:53], s54, v68
	s_and_saveexec_b64 s[22:23], s[52:53]
	s_cbranch_execz .LBB0_1064
	v_cmp_gt_i32_e32 vcc, 2, v184
	v_mov_b64_e32 v[70:71], s[92:93]
	s_nop 0
	v_cndmask_b32_e32 v68, v132, v184, vcc
	v_ashrrev_i32_e32 v69, 31, v68
	v_lshl_add_u64 v[68:69], s[14:15], 0, v[68:69]
	s_movk_i32 vcc_lo, 0x5800
	v_mad_u64_u32 v[70:71], s[54:55], v68, vcc_lo, v[70:71]
	v_mad_i32_i24 v71, v69, vcc_lo, v71
	v_lshl_add_u64 v[68:69], v[182:183], 2, v[70:71]
	global_store_dwordx4 v[68:69], v[124:127], off
	v_add_co_u32_e32 v68, vcc, 0x2000, v68
	s_nop 1
	v_addc_co_u32_e32 v69, vcc, 0, v69, vcc
	global_store_dwordx4 v[68:69], v[128:131], off offset:3072
.LBB0_1064:
	s_or_b64 exec, exec, s[22:23]
	v_add_u32_e32 v68, s3, v184
	s_movk_i32 s3, 0x3ffd
	v_cmp_lt_i32_e64 s[54:55], s3, v68
	v_add_u32_e32 v133, s9, v68
	s_and_saveexec_b64 s[22:23], s[54:55]
	s_cbranch_execz .LBB0_1066
	v_mov_b64_e32 v[68:69], s[0:1]
	s_movk_i32 s3, 0x5800
	v_mad_i64_i32 v[68:69], vcc, v133, s3, v[68:69]
	v_lshl_add_u64 v[68:69], v[182:183], 2, v[68:69]
	global_store_dwordx4 v[68:69], v[124:127], off
	v_add_co_u32_e32 v68, vcc, 0x2000, v68
	s_nop 1
	v_addc_co_u32_e32 v69, vcc, 0, v69, vcc
	global_store_dwordx4 v[68:69], v[128:131], off offset:3072

;     __device__ __forceinline__ void operator()(AccT& acc, const Unit& u, int wr, int wc, int fr, int fq) const {
;     ...
;         for (int n = 0; n < 2; ++n) {
;             const int colg = colg0 + n * 4, colv = FF + colg;
;             if (n == 1) {
; #pragma unroll
;                 for (int j = 0; j < 3; ++j) { cwg[1][j] = *(const f32x4*)(cw + j * FF2 + colg); cwv[1][j] = *(const f32x4*)(cw + j * FF2 + colv); }
;                 cbg[1] = *(const f32x4*)(cb + colg); cbv[1] = *(const f32x4*)(cb + colv); }
;             const f32x4 w0g = cwg[n][0], w1g = cwg[n][1], w2g = cwg[n][2], bg = cbg[n];
;             const f32x4 w0v = cwv[n][0], w1v = cwv[n][1], w2v = cwv[n][2], bv = cbv[n];
; #pragma unroll
;             for (int ai = 0; ai < 2; ++ai) {
;                 f32x4 hg = (f32x4){0.f, 0.f, 0.f, 0.f}, hv = hg;
;                 const int s = ai * 2 + wr;
;                 if (s > 0 && fr >= 14) {
;                     hg = *(const LAS f32x4*)(xch + (((s - 1) * 2 + (fr - 14)) * 256 + wc * 32 + fq * 8 + n * 4));
;                     hv = *(const LAS f32x4*)(xch + (((s - 1) * 2 + (fr - 14)) * 256 + 128 + wc * 32 + fq * 8 + n * 4));
;                 }
; #pragma unroll
;                 for (int m = 0; m < 4; ++m) {
;                     const int rl = ai * 128 + wr * 64 + m * 16 + fr;
;                     const f32x4 cg_ = acc[ai][0][m][n], cv_ = acc[ai][1][m][n];
;                     f32x4 p1g, p2g, p1v, p2v;
; #pragma unroll
;                     for (int j = 0; j < 4; ++j) {
;                         p1g[j] = ror1(fr == 15 ? hg[j] : cg_[j]); p2g[j] = ror2(fr >= 14 ? hg[j] : cg_[j]);
;                         p1v[j] = ror1(fr == 15 ? hv[j] : cv_[j]); p2v[j] = ror2(fr >= 14 ? hv[j] : cv_[j]);
;                     }
;                     const f32x4 hcg = bg + w0g * p2g + w1g * p1g + w2g * cg_;
;                     const f32x4 hcv = bv + w0v * p2v + w1v * p1v + w2v * cv_;
;                     const f32x2 ga = gelu_pk((f32x2){hcg[0], hcg[1]}), gb2 = gelu_pk((f32x2){hcg[2], hcg[3]});
;                     u32x2 w; w.x = cvt_pk_bf16(ga.x * hcv[0], ga.y * hcv[1]); w.y = cvt_pk_bf16(gb2.x * hcv[2], gb2.y * hcv[3]);
;                     const int t = tstart + rl;
;                     if (n == 0) stash[ai][m] = w;
;                     else if (rl >= 2) *(u32x4*)(U + (size_t)(arow0 + rl) * FF + colg0) = (u32x4){stash[ai][m].x, stash[ai][m].y, w.x, w.y};
.LBB0_1068:
	s_or_b64 exec, exec, s[22:23]
	v_mov_b32_e32 v221, v220
	v_mov_b32_e32 v74, v220
	v_mov_b32_e32 v75, v220
	v_pk_mul_f32 v[60:61], v[60:61], v[220:221]
	v_pk_mul_f32 v[62:63], v[62:63], v[74:75]
	v_pk_mul_f32 v[58:59], v[58:59], v[74:75]
	s_waitcnt lgkmcnt(0)
	v_cndmask_b32_e64 v75, v60, v68, s[50:51]
	v_pk_mul_f32 v[56:57], v[56:57], v[220:221]
	s_nop 0
	v_mov_b32_dpp v74, v75 row_ror:1 row_mask:0xf bank_mask:0xf
	v_cndmask_b32_e64 v75, v60, v68, s[48:49]
	v_cndmask_b32_e64 v125, v61, v69, s[50:51]
	v_cndmask_b32_e64 v126, v57, v111, s[50:51]
	v_mov_b32_dpp v68, v75 row_ror:2 row_mask:0xf bank_mask:0xf
	v_cndmask_b32_e64 v75, v56, v110, s[50:51]
	v_cndmask_b32_e64 v127, v62, v70, s[50:51]
	s_nop 0
	v_mov_b32_dpp v124, v75 row_ror:1 row_mask:0xf bank_mask:0xf
	v_cndmask_b32_e64 v75, v56, v110, s[48:49]
	v_cndmask_b32_e64 v129, v63, v71, s[50:51]
	v_cndmask_b32_e64 v130, v59, v113, s[50:51]
	v_mov_b32_dpp v110, v75 row_ror:2 row_mask:0xf bank_mask:0xf
	s_mov_b32 s20, 0xbf3a00e3
	s_lshl_b64 s[16:17], s[16:17], 8
	v_mov_b32_dpp v75, v125 row_ror:1 row_mask:0xf bank_mask:0xf
	v_cndmask_b32_e64 v125, v61, v69, s[48:49]
	s_nop 1
	v_mov_b32_dpp v69, v125 row_ror:2 row_mask:0xf bank_mask:0xf
	s_waitcnt vmcnt(0)
	v_pk_fma_f32 v[68:69], v[106:107], v[68:69], v[92:93]
	v_mov_b32_dpp v125, v126 row_ror:1 row_mask:0xf bank_mask:0xf
	v_cndmask_b32_e64 v126, v57, v111, s[48:49]
	v_pk_fma_f32 v[68:69], v[102:103], v[74:75], v[68:69]
	s_nop 0
	v_mov_b32_dpp v111, v126 row_ror:2 row_mask:0xf bank_mask:0xf
	v_pk_fma_f32 v[68:69], v[60:61], v[98:99], v[68:69]
	v_pk_fma_f32 v[110:111], v[88:89], v[110:111], v[84:85]
	v_mov_b32_dpp v126, v127 row_ror:1 row_mask:0xf bank_mask:0xf
	v_cndmask_b32_e64 v127, v62, v70, s[48:49]
	v_pk_fma_f32 v[110:111], v[80:81], v[124:125], v[110:111]
	v_mov_b64_e32 v[124:125], s[20:21]
	v_mov_b32_dpp v70, v127 row_ror:2 row_mask:0xf bank_mask:0xf
	v_cndmask_b32_e64 v127, v58, v112, s[50:51]
	v_cmp_gt_f32_e32 vcc, 0, v68
	v_pk_fma_f32 v[110:111], v[56:57], v[76:77], v[110:111]
	v_mov_b32_dpp v128, v127 row_ror:1 row_mask:0xf bank_mask:0xf
	v_cndmask_b32_e64 v127, v58, v112, s[48:49]
	s_nop 1
	v_mov_b32_dpp v112, v127 row_ror:2 row_mask:0xf bank_mask:0xf
	s_nop 1
	v_mov_b32_dpp v127, v129 row_ror:1 row_mask:0xf bank_mask:0xf
	v_cndmask_b32_e64 v129, v63, v71, s[48:49]
	s_nop 1
	v_mov_b32_dpp v71, v129 row_ror:2 row_mask:0xf bank_mask:0xf
	v_pk_fma_f32 v[70:71], v[108:109], v[70:71], v[94:95]
	s_nop 0
	v_mov_b32_dpp v129, v130 row_ror:1 row_mask:0xf bank_mask:0xf
	v_cndmask_b32_e64 v130, v59, v113, s[48:49]
	v_pk_fma_f32 v[70:71], v[104:105], v[126:127], v[70:71]
	s_nop 0
	v_mov_b32_dpp v113, v130 row_ror:2 row_mask:0xf bank_mask:0xf
	v_pk_fma_f32 v[74:75], v[90:91], v[112:113], v[86:87]
	v_and_b32_e32 v113, 0x7fffffff, v69
	v_and_b32_e32 v112, 0x7fffffff, v68
	v_pk_fma_f32 v[112:113], v[112:113], s[6:7], 1.0 op_sel_hi:[1,0,0]
	v_pk_fma_f32 v[74:75], v[82:83], v[128:129], v[74:75]
	v_rcp_f32_e32 v112, v112
	v_rcp_f32_e32 v113, v113
	v_pk_mul_f32 v[128:129], v[68:69], v[68:69]
	v_pk_fma_f32 v[70:71], v[62:63], v[100:101], v[70:71]
	v_pk_mul_f32 v[128:129], v[128:129], s[36:37] op_sel_hi:[1,0]
	v_pk_fma_f32 v[126:127], v[112:113], s[24:25], v[124:125] op_sel_hi:[1,0,0]
	v_exp_f32_e32 v128, v128
	v_pk_fma_f32 v[126:127], v[112:113], v[126:127], s[28:29] op_sel_hi:[1,1,0]
	v_exp_f32_e32 v129, v129
	v_pk_fma_f32 v[126:127], v[112:113], v[126:127], s[30:31] op_sel_hi:[1,1,0]
	v_pk_fma_f32 v[74:75], v[58:59], v[78:79], v[74:75]
	v_pk_fma_f32 v[126:127], v[112:113], v[126:127], s[34:35] op_sel_hi:[1,1,0]
	s_nop 0
	v_pk_mul_f32 v[112:113], v[112:113], v[126:127]
	v_pk_mul_f32 v[126:127], v[70:71], v[70:71]
	v_pk_mul_f32 v[112:113], v[128:129], v[112:113]
	s_nop 0
	v_pk_mul_f32 v[128:129], v[68:69], v[112:113]
	v_pk_fma_f32 v[112:113], v[68:69], v[112:113], v[68:69] neg_lo:[1,0,0] neg_hi:[1,0,0]
	v_and_b32_e32 v68, 0x7fffffff, v70
	v_cndmask_b32_e32 v128, v112, v128, vcc
	v_cmp_gt_f32_e32 vcc, 0, v69
	v_and_b32_e32 v69, 0x7fffffff, v71
	v_pk_fma_f32 v[68:69], v[68:69], s[6:7], 1.0 op_sel_hi:[1,0,0]
	v_cndmask_b32_e32 v129, v113, v129, vcc
	v_rcp_f32_e32 v68, v68
	v_rcp_f32_e32 v69, v69
	v_cmp_gt_f32_e32 vcc, 0, v70
	v_pk_fma_f32 v[112:113], v[68:69], s[24:25], v[124:125] op_sel_hi:[1,0,0]
	s_nop 0
	v_pk_fma_f32 v[112:113], v[68:69], v[112:113], s[28:29] op_sel_hi:[1,1,0]
	s_nop 0
	v_pk_fma_f32 v[112:113], v[68:69], v[112:113], s[30:31] op_sel_hi:[1,1,0]
	s_nop 0
	v_pk_fma_f32 v[112:113], v[68:69], v[112:113], s[34:35] op_sel_hi:[1,1,0]
	s_nop 0
	v_pk_mul_f32 v[68:69], v[68:69], v[112:113]
	v_pk_mul_f32 v[112:113], v[126:127], s[36:37] op_sel_hi:[1,0]
	s_nop 0
	v_exp_f32_e32 v112, v112
	v_exp_f32_e32 v113, v113
	s_nop 0
	v_pk_mul_f32 v[68:69], v[112:113], v[68:69]
	s_nop 0
	v_pk_mul_f32 v[112:113], v[70:71], v[68:69]
	v_pk_fma_f32 v[68:69], v[70:71], v[68:69], v[70:71] neg_lo:[1,0,0] neg_hi:[1,0,0]
	v_mul_f32_e32 v70, v110, v128
	v_cndmask_b32_e32 v68, v68, v112, vcc
	v_cmp_gt_f32_e32 vcc, 0, v71
	v_mul_f32_e32 v71, v111, v129
	v_cvt_pk_bf16_f32 v124, v70, v71
	v_mul_f32_e32 v68, v74, v68
	v_cndmask_b32_e32 v69, v69, v113, vcc
	v_cmp_lt_i32_e32 vcc, 1, v210
	v_mul_f32_e32 v69, v75, v69
	v_cvt_pk_bf16_f32 v125, v68, v69
	s_and_saveexec_b64 s[20:21], vcc
	s_cbranch_execz .LBB0_1105
	v_mov_b32_e32 v211, v97
	v_lshl_add_u64 v[68:69], s[16:17], 0, v[210:211]
	v_mov_b64_e32 v[70:71], s[84:85]
	s_movk_i32 s3, 0x1600
	v_mad_u64_u32 v[70:71], s[22:23], v68, s3, v[70:71]
	v_mad_i32_i24 v71, v69, s3, v71
	v_lshl_add_u64 v[68:69], v[182:183], 1, v[70:71]
	global_store_dwordx4 v[68:69], v[122:125], off
	s_or_b64 exec, exec, s[20:21]
	s_and_saveexec_b64 s[20:21], s[80:81]
	s_cbranch_execnz .LBB0_1106

; __device__ __forceinline__ unsigned cvt_pk_bf16(float lo, float hi) { unsigned r; asm volatile("v_cvt_pk_bf16_f32 %0, %1, %2" : "=v"(r) : "v"(lo), "v"(hi)); return r; }
; __device__ __forceinline__ float ror1(float x) { return __builtin_bit_cast(float, __builtin_amdgcn_update_dpp(0, __builtin_bit_cast(int, x), 0x121, 0xf, 0xf, false)); }
; __device__ __forceinline__ float ror2(float x) { return __builtin_bit_cast(float, __builtin_amdgcn_update_dpp(0, __builtin_bit_cast(int, x), 0x122, 0xf, 0xf, false)); }
;     __device__ __forceinline__ void operator()(AccT& acc, const Unit& u, int wr, int wc, int fr, int fq) const {
;     ...
;                     const f32x4 cg_ = acc[ai][0][m][n], cv_ = acc[ai][1][m][n];
;                     f32x4 p1g, p2g, p1v, p2v;
; #pragma unroll
;                     for (int j = 0; j < 4; ++j) {
;                         p1g[j] = ror1(fr == 15 ? hg[j] : cg_[j]); p2g[j] = ror2(fr >= 14 ? hg[j] : cg_[j]);
;                         p1v[j] = ror1(fr == 15 ? hv[j] : cv_[j]); p2v[j] = ror2(fr >= 14 ? hv[j] : cv_[j]);
;                     }
;                     const f32x4 hcg = bg + w0g * p2g + w1g * p1g + w2g * cg_;
;                     const f32x4 hcv = bv + w0v * p2v + w1v * p1v + w2v * cv_;
;                     const f32x2 ga = gelu_pk((f32x2){hcg[0], hcg[1]}), gb2 = gelu_pk((f32x2){hcg[2], hcg[3]});
;                     u32x2 w; w.x = cvt_pk_bf16(ga.x * hcv[0], ga.y * hcv[1]); w.y = cvt_pk_bf16(gb2.x * hcv[2], gb2.y * hcv[3]);
;                     const int t = tstart + rl;
;                     if (n == 0) stash[ai][m] = w;
;                     else if (rl >= 2) *(u32x4*)(U + (size_t)(arow0 + rl) * FF + colg0) = (u32x4){stash[ai][m].x, stash[ai][m].y, w.x, w.y};
;                     if (rl < 2 || rl >= 254) { float* hp = halo + ((size_t)u.pm * 4 + (rl < 2 ? rl : rl - 252)) * FF2; *(f32x4*)(hp + colg) = cg_; *(f32x4*)(hp + colv) = cv_; }
;                     if (t >= SEQ - 2) { float* cp = conv_p + (size_t)(b * 2 + (t - (SEQ - 2))) * FF2; *(f32x4*)(cp + colg) = cg_; *(f32x4*)(cp + colv) = cv_; }
.LBB0_1071:
	v_mov_b64_e32 v[68:69], s[0:1]
	s_movk_i32 s3, 0x5800
	v_mad_i64_i32 v[68:69], s[22:23], v170, s3, v[68:69]
	v_lshl_add_u64 v[68:69], v[182:183], 2, v[68:69]
	global_store_dwordx4 v[68:69], v[60:63], off offset:16
	v_add_co_u32_e32 v68, vcc, 0x2000, v68
	s_nop 1
	v_addc_co_u32_e32 v69, vcc, 0, v69, vcc
	global_store_dwordx4 v[68:69], v[56:59], off offset:3088
.LBB0_1072:
	s_or_b64 exec, exec, s[20:21]
	v_mov_b32_e32 v169, v168
	v_mov_b32_e32 v68, v168
	v_mov_b32_e32 v69, v168
	v_pk_mul_f32 v[54:55], v[54:55], v[68:69]
	v_pk_mul_f32 v[52:53], v[52:53], v[168:169]
	v_pk_mul_f32 v[42:43], v[42:43], v[68:69]
	v_pk_mul_f32 v[40:41], v[40:41], v[168:169]
	v_cndmask_b32_e64 v69, v52, v60, s[50:51]
	v_cndmask_b32_e64 v71, v53, v61, s[50:51]
	s_nop 0
	v_mov_b32_dpp v68, v69 row_ror:1 row_mask:0xf bank_mask:0xf
	v_cndmask_b32_e64 v69, v52, v60, s[48:49]
	v_cndmask_b32_e64 v74, v41, v57, s[50:51]
	v_cndmask_b32_e64 v75, v54, v62, s[50:51]
	v_mov_b32_dpp v60, v69 row_ror:2 row_mask:0xf bank_mask:0xf
	v_cndmask_b32_e64 v69, v40, v56, s[50:51]
	v_cndmask_b32_e64 v111, v55, v63, s[50:51]
	s_nop 0
	v_mov_b32_dpp v70, v69 row_ror:1 row_mask:0xf bank_mask:0xf
	v_cndmask_b32_e64 v69, v40, v56, s[48:49]
	v_cndmask_b32_e64 v112, v43, v59, s[50:51]
	s_mov_b32 s20, 0xbf3a00e3
	v_mov_b32_dpp v56, v69 row_ror:2 row_mask:0xf bank_mask:0xf
	s_nop 1
	v_mov_b32_dpp v69, v71 row_ror:1 row_mask:0xf bank_mask:0xf
	v_cndmask_b32_e64 v71, v53, v61, s[48:49]
	s_nop 1
	v_mov_b32_dpp v61, v71 row_ror:2 row_mask:0xf bank_mask:0xf
	v_pk_fma_f32 v[60:61], v[106:107], v[60:61], v[92:93]
	s_nop 0
	v_mov_b32_dpp v71, v74 row_ror:1 row_mask:0xf bank_mask:0xf
	v_cndmask_b32_e64 v74, v41, v57, s[48:49]
	v_pk_fma_f32 v[60:61], v[102:103], v[68:69], v[60:61]
	s_nop 0
	v_mov_b32_dpp v57, v74 row_ror:2 row_mask:0xf bank_mask:0xf
	v_pk_fma_f32 v[60:61], v[52:53], v[98:99], v[60:61]
	v_pk_fma_f32 v[56:57], v[88:89], v[56:57], v[84:85]
	v_mov_b32_dpp v74, v75 row_ror:1 row_mask:0xf bank_mask:0xf
	v_cndmask_b32_e64 v75, v54, v62, s[48:49]
	v_and_b32_e32 v69, 0x7fffffff, v61
	v_and_b32_e32 v68, 0x7fffffff, v60
	v_mov_b32_dpp v62, v75 row_ror:2 row_mask:0xf bank_mask:0xf
	v_cndmask_b32_e64 v75, v42, v58, s[50:51]
	v_pk_fma_f32 v[68:69], v[68:69], s[6:7], 1.0 op_sel_hi:[1,0,0]
	v_pk_fma_f32 v[56:57], v[80:81], v[70:71], v[56:57]
	v_mov_b32_dpp v110, v75 row_ror:1 row_mask:0xf bank_mask:0xf
	v_cndmask_b32_e64 v75, v42, v58, s[48:49]
	v_rcp_f32_e32 v68, v68
	v_rcp_f32_e32 v69, v69
	v_mov_b32_dpp v58, v75 row_ror:2 row_mask:0xf bank_mask:0xf
	v_mov_b64_e32 v[70:71], s[20:21]
	v_cmp_gt_f32_e32 vcc, 0, v60
	v_mov_b32_dpp v75, v111 row_ror:1 row_mask:0xf bank_mask:0xf
	v_cndmask_b32_e64 v111, v55, v63, s[48:49]
	v_pk_fma_f32 v[56:57], v[40:41], v[76:77], v[56:57]
	s_nop 0
	v_mov_b32_dpp v63, v111 row_ror:2 row_mask:0xf bank_mask:0xf
	v_pk_fma_f32 v[62:63], v[108:109], v[62:63], v[94:95]
	s_nop 0
	v_mov_b32_dpp v111, v112 row_ror:1 row_mask:0xf bank_mask:0xf
	v_cndmask_b32_e64 v112, v43, v59, s[48:49]
	v_pk_fma_f32 v[62:63], v[104:105], v[74:75], v[62:63]
	v_pk_fma_f32 v[74:75], v[68:69], s[24:25], v[70:71] op_sel_hi:[1,0,0]
	v_mov_b32_dpp v59, v112 row_ror:2 row_mask:0xf bank_mask:0xf
	v_pk_fma_f32 v[58:59], v[90:91], v[58:59], v[86:87]
	v_pk_fma_f32 v[74:75], v[68:69], v[74:75], s[28:29] op_sel_hi:[1,1,0]
	v_pk_fma_f32 v[58:59], v[82:83], v[110:111], v[58:59]
	v_pk_mul_f32 v[110:111], v[60:61], v[60:61]
	v_pk_fma_f32 v[74:75], v[68:69], v[74:75], s[30:31] op_sel_hi:[1,1,0]
	v_pk_mul_f32 v[110:111], v[110:111], s[36:37] op_sel_hi:[1,0]
	v_pk_fma_f32 v[74:75], v[68:69], v[74:75], s[34:35] op_sel_hi:[1,1,0]
	v_exp_f32_e32 v110, v110
	v_exp_f32_e32 v111, v111
	v_pk_mul_f32 v[68:69], v[68:69], v[74:75]
	v_pk_fma_f32 v[62:63], v[54:55], v[100:101], v[62:63]
	v_pk_fma_f32 v[58:59], v[42:43], v[78:79], v[58:59]
	v_pk_mul_f32 v[68:69], v[110:111], v[68:69]
	v_pk_mul_f32 v[74:75], v[62:63], v[62:63]
	v_pk_mul_f32 v[110:111], v[60:61], v[68:69]
	v_pk_fma_f32 v[68:69], v[60:61], v[68:69], v[60:61] neg_lo:[1,0,0] neg_hi:[1,0,0]
	v_and_b32_e32 v60, 0x7fffffff, v62
	v_cndmask_b32_e32 v110, v68, v110, vcc
	v_cmp_gt_f32_e32 vcc, 0, v61
	v_and_b32_e32 v61, 0x7fffffff, v63
	v_pk_fma_f32 v[60:61], v[60:61], s[6:7], 1.0 op_sel_hi:[1,0,0]
	v_cndmask_b32_e32 v111, v69, v111, vcc
	v_rcp_f32_e32 v60, v60
	v_rcp_f32_e32 v61, v61
	v_cmp_gt_f32_e32 vcc, 0, v62
	v_mul_f32_e32 v56, v56, v110
	v_mul_f32_e32 v57, v57, v111
	v_pk_fma_f32 v[68:69], v[60:61], s[24:25], v[70:71] op_sel_hi:[1,0,0]
	v_cvt_pk_bf16_f32 v122, v56, v57
	s_nop 0
	v_pk_fma_f32 v[68:69], v[60:61], v[68:69], s[28:29] op_sel_hi:[1,1,0]
	s_nop 0
	v_pk_fma_f32 v[68:69], v[60:61], v[68:69], s[30:31] op_sel_hi:[1,1,0]
	s_nop 0
	v_pk_fma_f32 v[68:69], v[60:61], v[68:69], s[34:35] op_sel_hi:[1,1,0]
	s_nop 0
	v_pk_mul_f32 v[60:61], v[60:61], v[68:69]
	v_pk_mul_f32 v[68:69], v[74:75], s[36:37] op_sel_hi:[1,0]
	s_nop 0
	v_exp_f32_e32 v68, v68
	v_exp_f32_e32 v69, v69
	s_nop 0
	v_pk_mul_f32 v[60:61], v[68:69], v[60:61]
	s_nop 0
	v_pk_mul_f32 v[68:69], v[62:63], v[60:61]
	v_pk_fma_f32 v[60:61], v[62:63], v[60:61], v[62:63] neg_lo:[1,0,0] neg_hi:[1,0,0]
	s_nop 0
	v_cndmask_b32_e32 v60, v60, v68, vcc
	v_cmp_gt_f32_e32 vcc, 0, v63
	v_mul_f32_e32 v56, v58, v60
	s_nop 0
	v_cndmask_b32_e32 v61, v61, v69, vcc
	v_cmp_lt_i32_e32 vcc, 1, v208
	v_mul_f32_e32 v57, v59, v61
	v_cvt_pk_bf16_f32 v123, v56, v57
	s_and_saveexec_b64 s[20:21], vcc
	s_cbranch_execz .LBB0_1107
	v_mov_b32_e32 v209, v97
	v_lshl_add_u64 v[56:57], s[16:17], 0, v[208:209]
	v_mov_b64_e32 v[58:59], s[84:85]
	s_movk_i32 s3, 0x1600
	v_mad_u64_u32 v[58:59], s[22:23], v56, s3, v[58:59]
	v_mad_i32_i24 v59, v57, s3, v59
	v_lshl_add_u64 v[56:57], v[182:183], 1, v[58:59]
	global_store_dwordx4 v[56:57], v[120:123], off
	s_or_b64 exec, exec, s[20:21]
	s_and_saveexec_b64 s[20:21], s[76:77]
	s_cbranch_execnz .LBB0_1108

; __device__ __forceinline__ unsigned cvt_pk_bf16(float lo, float hi) { unsigned r; asm volatile("v_cvt_pk_bf16_f32 %0, %1, %2" : "=v"(r) : "v"(lo), "v"(hi)); return r; }
; __device__ __forceinline__ float ror1(float x) { return __builtin_bit_cast(float, __builtin_amdgcn_update_dpp(0, __builtin_bit_cast(int, x), 0x121, 0xf, 0xf, false)); }
; __device__ __forceinline__ float ror2(float x) { return __builtin_bit_cast(float, __builtin_amdgcn_update_dpp(0, __builtin_bit_cast(int, x), 0x122, 0xf, 0xf, false)); }
;     __device__ __forceinline__ void operator()(AccT& acc, const Unit& u, int wr, int wc, int fr, int fq) const {
;     ...
;                     const f32x4 cg_ = acc[ai][0][m][n], cv_ = acc[ai][1][m][n];
;                     f32x4 p1g, p2g, p1v, p2v;
; #pragma unroll
;                     for (int j = 0; j < 4; ++j) {
;                         p1g[j] = ror1(fr == 15 ? hg[j] : cg_[j]); p2g[j] = ror2(fr >= 14 ? hg[j] : cg_[j]);
;                         p1v[j] = ror1(fr == 15 ? hv[j] : cv_[j]); p2v[j] = ror2(fr >= 14 ? hv[j] : cv_[j]);
;                     }
;                     const f32x4 hcg = bg + w0g * p2g + w1g * p1g + w2g * cg_;
;                     const f32x4 hcv = bv + w0v * p2v + w1v * p1v + w2v * cv_;
;                     const f32x2 ga = gelu_pk((f32x2){hcg[0], hcg[1]}), gb2 = gelu_pk((f32x2){hcg[2], hcg[3]});
;                     u32x2 w; w.x = cvt_pk_bf16(ga.x * hcv[0], ga.y * hcv[1]); w.y = cvt_pk_bf16(gb2.x * hcv[2], gb2.y * hcv[3]);
;                     const int t = tstart + rl;
;                     if (n == 0) stash[ai][m] = w;
;                     else if (rl >= 2) *(u32x4*)(U + (size_t)(arow0 + rl) * FF + colg0) = (u32x4){stash[ai][m].x, stash[ai][m].y, w.x, w.y};
;                     if (rl < 2 || rl >= 254) { float* hp = halo + ((size_t)u.pm * 4 + (rl < 2 ? rl : rl - 252)) * FF2; *(f32x4*)(hp + colg) = cg_; *(f32x4*)(hp + colv) = cv_; }
;                     if (t >= SEQ - 2) { float* cp = conv_p + (size_t)(b * 2 + (t - (SEQ - 2))) * FF2; *(f32x4*)(cp + colg) = cg_; *(f32x4*)(cp + colv) = cv_; }
.LBB0_1075:
	v_mov_b64_e32 v[56:57], s[0:1]
	s_movk_i32 s3, 0x5800
	v_mad_i64_i32 v[56:57], s[22:23], v162, s3, v[56:57]
	v_lshl_add_u64 v[56:57], v[182:183], 2, v[56:57]
	global_store_dwordx4 v[56:57], v[52:55], off offset:16
	v_add_co_u32_e32 v56, vcc, 0x2000, v56
	s_nop 1
	v_addc_co_u32_e32 v57, vcc, 0, v57, vcc
	global_store_dwordx4 v[56:57], v[40:43], off offset:3088
.LBB0_1076:
	s_or_b64 exec, exec, s[20:21]
	v_mov_b32_e32 v157, v156
	v_mov_b32_e32 v56, v156
	v_mov_b32_e32 v57, v156
	v_pk_mul_f32 v[38:39], v[38:39], v[56:57]
	v_pk_mul_f32 v[36:37], v[36:37], v[156:157]
	v_pk_mul_f32 v[34:35], v[34:35], v[56:57]
	v_pk_mul_f32 v[32:33], v[32:33], v[156:157]
	v_cndmask_b32_e64 v57, v36, v52, s[50:51]
	v_cndmask_b32_e64 v59, v37, v53, s[50:51]
	s_nop 0
	v_mov_b32_dpp v56, v57 row_ror:1 row_mask:0xf bank_mask:0xf
	v_cndmask_b32_e64 v57, v36, v52, s[48:49]
	v_cndmask_b32_e64 v60, v33, v41, s[50:51]
	v_cndmask_b32_e64 v61, v38, v54, s[50:51]
	v_mov_b32_dpp v52, v57 row_ror:2 row_mask:0xf bank_mask:0xf
	v_cndmask_b32_e64 v57, v32, v40, s[50:51]
	v_cndmask_b32_e64 v63, v39, v55, s[50:51]
	s_nop 0
	v_mov_b32_dpp v58, v57 row_ror:1 row_mask:0xf bank_mask:0xf
	v_cndmask_b32_e64 v57, v32, v40, s[48:49]
	v_cndmask_b32_e64 v68, v35, v43, s[50:51]
	s_mov_b32 s20, 0xbf3a00e3
	v_mov_b32_dpp v40, v57 row_ror:2 row_mask:0xf bank_mask:0xf
	s_nop 1
	v_mov_b32_dpp v57, v59 row_ror:1 row_mask:0xf bank_mask:0xf
	v_cndmask_b32_e64 v59, v37, v53, s[48:49]
	s_nop 1
	v_mov_b32_dpp v53, v59 row_ror:2 row_mask:0xf bank_mask:0xf
	v_pk_fma_f32 v[52:53], v[106:107], v[52:53], v[92:93]
	s_nop 0
	v_mov_b32_dpp v59, v60 row_ror:1 row_mask:0xf bank_mask:0xf
	v_cndmask_b32_e64 v60, v33, v41, s[48:49]
	v_pk_fma_f32 v[52:53], v[102:103], v[56:57], v[52:53]
	s_nop 0
	v_mov_b32_dpp v41, v60 row_ror:2 row_mask:0xf bank_mask:0xf
	v_pk_fma_f32 v[52:53], v[36:37], v[98:99], v[52:53]
	v_pk_fma_f32 v[40:41], v[88:89], v[40:41], v[84:85]
	v_mov_b32_dpp v60, v61 row_ror:1 row_mask:0xf bank_mask:0xf
	v_cndmask_b32_e64 v61, v38, v54, s[48:49]
	v_and_b32_e32 v57, 0x7fffffff, v53
	v_and_b32_e32 v56, 0x7fffffff, v52
	v_mov_b32_dpp v54, v61 row_ror:2 row_mask:0xf bank_mask:0xf
	v_cndmask_b32_e64 v61, v34, v42, s[50:51]
	v_pk_fma_f32 v[56:57], v[56:57], s[6:7], 1.0 op_sel_hi:[1,0,0]
	v_pk_fma_f32 v[40:41], v[80:81], v[58:59], v[40:41]
	v_mov_b32_dpp v62, v61 row_ror:1 row_mask:0xf bank_mask:0xf
	v_cndmask_b32_e64 v61, v34, v42, s[48:49]
	v_rcp_f32_e32 v56, v56
	v_rcp_f32_e32 v57, v57
	v_mov_b32_dpp v42, v61 row_ror:2 row_mask:0xf bank_mask:0xf
	v_mov_b64_e32 v[58:59], s[20:21]
	v_cmp_gt_f32_e32 vcc, 0, v52
	v_mov_b32_dpp v61, v63 row_ror:1 row_mask:0xf bank_mask:0xf
	v_cndmask_b32_e64 v63, v39, v55, s[48:49]
	v_pk_fma_f32 v[40:41], v[32:33], v[76:77], v[40:41]
	s_nop 0
	v_mov_b32_dpp v55, v63 row_ror:2 row_mask:0xf bank_mask:0xf
	v_pk_fma_f32 v[54:55], v[108:109], v[54:55], v[94:95]
	s_nop 0
	v_mov_b32_dpp v63, v68 row_ror:1 row_mask:0xf bank_mask:0xf
	v_cndmask_b32_e64 v68, v35, v43, s[48:49]
	v_pk_fma_f32 v[54:55], v[104:105], v[60:61], v[54:55]
	v_pk_fma_f32 v[60:61], v[56:57], s[24:25], v[58:59] op_sel_hi:[1,0,0]
	v_mov_b32_dpp v43, v68 row_ror:2 row_mask:0xf bank_mask:0xf
	v_pk_fma_f32 v[42:43], v[90:91], v[42:43], v[86:87]
	v_pk_fma_f32 v[60:61], v[56:57], v[60:61], s[28:29] op_sel_hi:[1,1,0]
	v_pk_fma_f32 v[42:43], v[82:83], v[62:63], v[42:43]
	v_pk_mul_f32 v[62:63], v[52:53], v[52:53]
	v_pk_fma_f32 v[60:61], v[56:57], v[60:61], s[30:31] op_sel_hi:[1,1,0]
	v_pk_mul_f32 v[62:63], v[62:63], s[36:37] op_sel_hi:[1,0]
	v_pk_fma_f32 v[60:61], v[56:57], v[60:61], s[34:35] op_sel_hi:[1,1,0]
	v_exp_f32_e32 v62, v62
	v_exp_f32_e32 v63, v63
	v_pk_mul_f32 v[56:57], v[56:57], v[60:61]
	v_pk_fma_f32 v[54:55], v[38:39], v[100:101], v[54:55]
	v_pk_fma_f32 v[42:43], v[34:35], v[78:79], v[42:43]
	v_pk_mul_f32 v[56:57], v[62:63], v[56:57]
	v_pk_mul_f32 v[60:61], v[54:55], v[54:55]
	v_pk_mul_f32 v[62:63], v[52:53], v[56:57]
	v_pk_fma_f32 v[56:57], v[52:53], v[56:57], v[52:53] neg_lo:[1,0,0] neg_hi:[1,0,0]
	v_and_b32_e32 v52, 0x7fffffff, v54
	v_cndmask_b32_e32 v62, v56, v62, vcc
	v_cmp_gt_f32_e32 vcc, 0, v53
	v_and_b32_e32 v53, 0x7fffffff, v55
	v_pk_fma_f32 v[52:53], v[52:53], s[6:7], 1.0 op_sel_hi:[1,0,0]
	v_cndmask_b32_e32 v63, v57, v63, vcc
	v_rcp_f32_e32 v52, v52
	v_rcp_f32_e32 v53, v53
	v_cmp_gt_f32_e32 vcc, 0, v54
	v_mul_f32_e32 v40, v40, v62
	v_mul_f32_e32 v41, v41, v63
	v_pk_fma_f32 v[56:57], v[52:53], s[24:25], v[58:59] op_sel_hi:[1,0,0]
	v_cvt_pk_bf16_f32 v120, v40, v41
	s_nop 0
	v_pk_fma_f32 v[56:57], v[52:53], v[56:57], s[28:29] op_sel_hi:[1,1,0]
	s_nop 0
	v_pk_fma_f32 v[56:57], v[52:53], v[56:57], s[30:31] op_sel_hi:[1,1,0]
	s_nop 0
	v_pk_fma_f32 v[56:57], v[52:53], v[56:57], s[34:35] op_sel_hi:[1,1,0]
	s_nop 0
	v_pk_mul_f32 v[52:53], v[52:53], v[56:57]
	v_pk_mul_f32 v[56:57], v[60:61], s[36:37] op_sel_hi:[1,0]
	s_nop 0
	v_exp_f32_e32 v56, v56
	v_exp_f32_e32 v57, v57
	s_nop 0
	v_pk_mul_f32 v[52:53], v[56:57], v[52:53]
	s_nop 0
	v_pk_mul_f32 v[56:57], v[54:55], v[52:53]
	v_pk_fma_f32 v[52:53], v[54:55], v[52:53], v[54:55] neg_lo:[1,0,0] neg_hi:[1,0,0]
	s_nop 0
	v_cndmask_b32_e32 v52, v52, v56, vcc
	v_cmp_gt_f32_e32 vcc, 0, v55
	v_mul_f32_e32 v40, v42, v52
	s_nop 0
	v_cndmask_b32_e32 v53, v53, v57, vcc
	v_cmp_lt_i32_e32 vcc, 1, v206
	v_mul_f32_e32 v41, v43, v53
	v_cvt_pk_bf16_f32 v121, v40, v41
	s_and_saveexec_b64 s[20:21], vcc
	s_cbranch_execz .LBB0_1109
	v_mov_b32_e32 v207, v97
	v_lshl_add_u64 v[40:41], s[16:17], 0, v[206:207]
	v_mov_b64_e32 v[42:43], s[84:85]
	s_movk_i32 s3, 0x1600
	v_mad_u64_u32 v[42:43], s[22:23], v40, s3, v[42:43]
	v_mad_i32_i24 v43, v41, s3, v43
	v_lshl_add_u64 v[40:41], v[182:183], 1, v[42:43]
	global_store_dwordx4 v[40:41], v[118:121], off
	s_or_b64 exec, exec, s[20:21]
	s_and_saveexec_b64 s[20:21], s[72:73]
	s_cbranch_execnz .LBB0_1110

; __device__ __forceinline__ unsigned cvt_pk_bf16(float lo, float hi) { unsigned r; asm volatile("v_cvt_pk_bf16_f32 %0, %1, %2" : "=v"(r) : "v"(lo), "v"(hi)); return r; }
; __device__ __forceinline__ float ror1(float x) { return __builtin_bit_cast(float, __builtin_amdgcn_update_dpp(0, __builtin_bit_cast(int, x), 0x121, 0xf, 0xf, false)); }
; __device__ __forceinline__ float ror2(float x) { return __builtin_bit_cast(float, __builtin_amdgcn_update_dpp(0, __builtin_bit_cast(int, x), 0x122, 0xf, 0xf, false)); }
;     __device__ __forceinline__ void operator()(AccT& acc, const Unit& u, int wr, int wc, int fr, int fq) const {
;     ...
;                     const f32x4 cg_ = acc[ai][0][m][n], cv_ = acc[ai][1][m][n];
;                     f32x4 p1g, p2g, p1v, p2v;
; #pragma unroll
;                     for (int j = 0; j < 4; ++j) {
;                         p1g[j] = ror1(fr == 15 ? hg[j] : cg_[j]); p2g[j] = ror2(fr >= 14 ? hg[j] : cg_[j]);
;                         p1v[j] = ror1(fr == 15 ? hv[j] : cv_[j]); p2v[j] = ror2(fr >= 14 ? hv[j] : cv_[j]);
;                     }
;                     const f32x4 hcg = bg + w0g * p2g + w1g * p1g + w2g * cg_;
;                     const f32x4 hcv = bv + w0v * p2v + w1v * p1v + w2v * cv_;
;                     const f32x2 ga = gelu_pk((f32x2){hcg[0], hcg[1]}), gb2 = gelu_pk((f32x2){hcg[2], hcg[3]});
;                     u32x2 w; w.x = cvt_pk_bf16(ga.x * hcv[0], ga.y * hcv[1]); w.y = cvt_pk_bf16(gb2.x * hcv[2], gb2.y * hcv[3]);
;                     const int t = tstart + rl;
;                     if (n == 0) stash[ai][m] = w;
;                     else if (rl >= 2) *(u32x4*)(U + (size_t)(arow0 + rl) * FF + colg0) = (u32x4){stash[ai][m].x, stash[ai][m].y, w.x, w.y};
;                     if (rl < 2 || rl >= 254) { float* hp = halo + ((size_t)u.pm * 4 + (rl < 2 ? rl : rl - 252)) * FF2; *(f32x4*)(hp + colg) = cg_; *(f32x4*)(hp + colv) = cv_; }
;                     if (t >= SEQ - 2) { float* cp = conv_p + (size_t)(b * 2 + (t - (SEQ - 2))) * FF2; *(f32x4*)(cp + colg) = cg_; *(f32x4*)(cp + colv) = cv_; }
.LBB0_1079:
	v_mov_b64_e32 v[40:41], s[0:1]
	s_movk_i32 s3, 0x5800
	v_mad_i64_i32 v[40:41], s[22:23], v161, s3, v[40:41]
	v_lshl_add_u64 v[40:41], v[182:183], 2, v[40:41]
	global_store_dwordx4 v[40:41], v[36:39], off offset:16
	v_add_co_u32_e32 v40, vcc, 0x2000, v40
	s_nop 1
	v_addc_co_u32_e32 v41, vcc, 0, v41, vcc
	global_store_dwordx4 v[40:41], v[32:35], off offset:3088
.LBB0_1080:
	s_or_b64 exec, exec, s[20:21]
	v_cndmask_b32_e64 v41, v48, v36, s[50:51]
	v_cndmask_b32_e64 v43, v49, v37, s[50:51]
	s_nop 0
	v_mov_b32_dpp v40, v41 row_ror:1 row_mask:0xf bank_mask:0xf
	v_cndmask_b32_e64 v41, v48, v36, s[48:49]
	v_cndmask_b32_e64 v52, v45, v33, s[50:51]
	v_cndmask_b32_e64 v53, v50, v38, s[50:51]
	v_mov_b32_dpp v36, v41 row_ror:2 row_mask:0xf bank_mask:0xf
	v_cndmask_b32_e64 v41, v44, v32, s[50:51]
	v_cndmask_b32_e64 v55, v51, v39, s[50:51]
	s_nop 0
	v_mov_b32_dpp v42, v41 row_ror:1 row_mask:0xf bank_mask:0xf
	v_cndmask_b32_e64 v41, v44, v32, s[48:49]
	v_cndmask_b32_e64 v56, v47, v35, s[50:51]
	s_mov_b32 s20, 0xbf3a00e3
	v_mov_b32_dpp v32, v41 row_ror:2 row_mask:0xf bank_mask:0xf
	s_nop 1
	v_mov_b32_dpp v41, v43 row_ror:1 row_mask:0xf bank_mask:0xf
	v_cndmask_b32_e64 v43, v49, v37, s[48:49]
	s_nop 1
	v_mov_b32_dpp v37, v43 row_ror:2 row_mask:0xf bank_mask:0xf
	v_pk_fma_f32 v[36:37], v[106:107], v[36:37], v[92:93]
	s_nop 0
	v_mov_b32_dpp v43, v52 row_ror:1 row_mask:0xf bank_mask:0xf
	v_cndmask_b32_e64 v52, v45, v33, s[48:49]
	v_pk_fma_f32 v[36:37], v[102:103], v[40:41], v[36:37]
	s_nop 0
	v_mov_b32_dpp v33, v52 row_ror:2 row_mask:0xf bank_mask:0xf
	v_pk_fma_f32 v[36:37], v[48:49], v[98:99], v[36:37]
	v_pk_fma_f32 v[32:33], v[88:89], v[32:33], v[84:85]
	v_mov_b32_dpp v52, v53 row_ror:1 row_mask:0xf bank_mask:0xf
	v_cndmask_b32_e64 v53, v50, v38, s[48:49]
	v_and_b32_e32 v41, 0x7fffffff, v37
	v_and_b32_e32 v40, 0x7fffffff, v36
	v_mov_b32_dpp v38, v53 row_ror:2 row_mask:0xf bank_mask:0xf
	v_cndmask_b32_e64 v53, v46, v34, s[50:51]
	v_pk_fma_f32 v[40:41], v[40:41], s[6:7], 1.0 op_sel_hi:[1,0,0]
	v_pk_fma_f32 v[32:33], v[80:81], v[42:43], v[32:33]
	v_mov_b32_dpp v54, v53 row_ror:1 row_mask:0xf bank_mask:0xf
	v_cndmask_b32_e64 v53, v46, v34, s[48:49]
	v_rcp_f32_e32 v40, v40
	v_rcp_f32_e32 v41, v41
	v_mov_b32_dpp v34, v53 row_ror:2 row_mask:0xf bank_mask:0xf
	v_mov_b64_e32 v[42:43], s[20:21]
	v_cmp_gt_f32_e32 vcc, 0, v36
	v_mov_b32_dpp v53, v55 row_ror:1 row_mask:0xf bank_mask:0xf
	v_cndmask_b32_e64 v55, v51, v39, s[48:49]
	v_pk_fma_f32 v[32:33], v[44:45], v[76:77], v[32:33]
	s_nop 0
	v_mov_b32_dpp v39, v55 row_ror:2 row_mask:0xf bank_mask:0xf
	v_pk_fma_f32 v[38:39], v[108:109], v[38:39], v[94:95]
	s_nop 0
	v_mov_b32_dpp v55, v56 row_ror:1 row_mask:0xf bank_mask:0xf
	v_cndmask_b32_e64 v56, v47, v35, s[48:49]
	v_pk_fma_f32 v[38:39], v[104:105], v[52:53], v[38:39]
	v_pk_fma_f32 v[52:53], v[40:41], s[24:25], v[42:43] op_sel_hi:[1,0,0]
	v_mov_b32_dpp v35, v56 row_ror:2 row_mask:0xf bank_mask:0xf
	v_pk_fma_f32 v[34:35], v[90:91], v[34:35], v[86:87]
	v_pk_fma_f32 v[52:53], v[40:41], v[52:53], s[28:29] op_sel_hi:[1,1,0]
	v_pk_fma_f32 v[34:35], v[82:83], v[54:55], v[34:35]
	v_pk_mul_f32 v[54:55], v[36:37], v[36:37]
	v_pk_fma_f32 v[52:53], v[40:41], v[52:53], s[30:31] op_sel_hi:[1,1,0]
	v_pk_mul_f32 v[54:55], v[54:55], s[36:37] op_sel_hi:[1,0]
	v_pk_fma_f32 v[52:53], v[40:41], v[52:53], s[34:35] op_sel_hi:[1,1,0]
	v_exp_f32_e32 v54, v54
	v_exp_f32_e32 v55, v55
	v_pk_mul_f32 v[40:41], v[40:41], v[52:53]
	v_pk_fma_f32 v[38:39], v[50:51], v[100:101], v[38:39]
	v_pk_fma_f32 v[34:35], v[46:47], v[78:79], v[34:35]
	v_pk_mul_f32 v[40:41], v[54:55], v[40:41]
	v_pk_mul_f32 v[52:53], v[38:39], v[38:39]
	v_pk_mul_f32 v[54:55], v[36:37], v[40:41]
	v_pk_fma_f32 v[40:41], v[36:37], v[40:41], v[36:37] neg_lo:[1,0,0] neg_hi:[1,0,0]
	v_and_b32_e32 v36, 0x7fffffff, v38
	v_cndmask_b32_e32 v54, v40, v54, vcc
	v_cmp_gt_f32_e32 vcc, 0, v37
	v_and_b32_e32 v37, 0x7fffffff, v39
	v_pk_fma_f32 v[36:37], v[36:37], s[6:7], 1.0 op_sel_hi:[1,0,0]
	v_cndmask_b32_e32 v55, v41, v55, vcc
	v_rcp_f32_e32 v36, v36
	v_rcp_f32_e32 v37, v37
	v_cmp_gt_f32_e32 vcc, 0, v38
	v_mul_f32_e32 v32, v32, v54
	v_mul_f32_e32 v33, v33, v55
	v_pk_fma_f32 v[40:41], v[36:37], s[24:25], v[42:43] op_sel_hi:[1,0,0]
	v_cvt_pk_bf16_f32 v118, v32, v33
	s_nop 0
	v_pk_fma_f32 v[40:41], v[36:37], v[40:41], s[28:29] op_sel_hi:[1,1,0]
	s_nop 0
	v_pk_fma_f32 v[40:41], v[36:37], v[40:41], s[30:31] op_sel_hi:[1,1,0]
	s_nop 0
	v_pk_fma_f32 v[40:41], v[36:37], v[40:41], s[34:35] op_sel_hi:[1,1,0]
	s_nop 0
	v_pk_mul_f32 v[36:37], v[36:37], v[40:41]
	v_pk_mul_f32 v[40:41], v[52:53], s[36:37] op_sel_hi:[1,0]
	s_nop 0
	v_exp_f32_e32 v40, v40
	v_exp_f32_e32 v41, v41
	s_nop 0
	v_pk_mul_f32 v[36:37], v[40:41], v[36:37]
	s_nop 0
	v_pk_mul_f32 v[40:41], v[38:39], v[36:37]
	v_pk_fma_f32 v[36:37], v[38:39], v[36:37], v[38:39] neg_lo:[1,0,0] neg_hi:[1,0,0]
	s_nop 0
	v_cndmask_b32_e32 v36, v36, v40, vcc
	v_cmp_gt_f32_e32 vcc, 0, v39
	v_mul_f32_e32 v32, v34, v36
	s_nop 0
	v_cndmask_b32_e32 v37, v37, v41, vcc
	v_cmp_lt_i32_e32 vcc, 1, v192
	v_mul_f32_e32 v33, v35, v37
	v_cvt_pk_bf16_f32 v119, v32, v33
	s_and_saveexec_b64 s[20:21], vcc
	s_cbranch_execz .LBB0_1111
	v_mov_b32_e32 v193, v97
	v_lshl_add_u64 v[32:33], s[16:17], 0, v[192:193]
	v_mov_b64_e32 v[34:35], s[84:85]
	s_movk_i32 s3, 0x1600
	v_mad_u64_u32 v[34:35], s[22:23], v32, s3, v[34:35]
	v_mad_i32_i24 v35, v33, s3, v35
	v_lshl_add_u64 v[32:33], v[182:183], 1, v[34:35]
	global_store_dwordx4 v[32:33], v[116:119], off
	s_or_b64 exec, exec, s[20:21]
	s_and_saveexec_b64 s[20:21], s[68:69]
	s_cbranch_execnz .LBB0_1112

;     __device__ __forceinline__ void operator()(AccT& acc, const Unit& u, int wr, int wc, int fr, int fq) const {
;     ...
;                     if (t >= SEQ - 2) { float* cp = conv_p + (size_t)(b * 2 + (t - (SEQ - 2))) * FF2; *(f32x4*)(cp + colg) = cg_; *(f32x4*)(cp + colv) = cv_; }
.LBB0_1083:
	v_mov_b64_e32 v[32:33], s[0:1]
	s_movk_i32 s3, 0x5800
	v_mad_i64_i32 v[32:33], s[22:23], v159, s3, v[32:33]
	v_lshl_add_u64 v[32:33], v[182:183], 2, v[32:33]
	global_store_dwordx4 v[32:33], v[48:51], off offset:16
	v_add_co_u32_e32 v32, vcc, 0x2000, v32
	s_nop 1
	v_addc_co_u32_e32 v33, vcc, 0, v33, vcc
	global_store_dwordx4 v[32:33], v[44:47], off offset:3088

; #define LAS __attribute__((address_space(3)))
; __device__ __forceinline__ unsigned cvt_pk_bf16(float lo, float hi) { unsigned r; asm volatile("v_cvt_pk_bf16_f32 %0, %1, %2" : "=v"(r) : "v"(lo), "v"(hi)); return r; }
;     __device__ __forceinline__ void operator()(AccT& acc, const Unit& u, int wr, int wc, int fr, int fq) const {
;     ...
;                 f32x4 hg = (f32x4){0.f, 0.f, 0.f, 0.f}, hv = hg;
;                 const int s = ai * 2 + wr;
;                 if (s > 0 && fr >= 14) {
;                     hg = *(const LAS f32x4*)(xch + (((s - 1) * 2 + (fr - 14)) * 256 + wc * 32 + fq * 8 + n * 4));
;                     hv = *(const LAS f32x4*)(xch + (((s - 1) * 2 + (fr - 14)) * 256 + 128 + wc * 32 + fq * 8 + n * 4));
;                 }
; #pragma unroll
;                 for (int m = 0; m < 4; ++m) {
;                     const int rl = ai * 128 + wr * 64 + m * 16 + fr;
;                     const f32x4 cg_ = acc[ai][0][m][n], cv_ = acc[ai][1][m][n];
;                     f32x4 p1g, p2g, p1v, p2v;
; #pragma unroll
;                     for (int j = 0; j < 4; ++j) {
;                         p1g[j] = ror1(fr == 15 ? hg[j] : cg_[j]); p2g[j] = ror2(fr >= 14 ? hg[j] : cg_[j]);
;                         p1v[j] = ror1(fr == 15 ? hv[j] : cv_[j]); p2v[j] = ror2(fr >= 14 ? hv[j] : cv_[j]);
;                     }
;                     const f32x4 hcg = bg + w0g * p2g + w1g * p1g + w2g * cg_;
;                     const f32x4 hcv = bv + w0v * p2v + w1v * p1v + w2v * cv_;
;                     const f32x2 ga = gelu_pk((f32x2){hcg[0], hcg[1]}), gb2 = gelu_pk((f32x2){hcg[2], hcg[3]});
;                     u32x2 w; w.x = cvt_pk_bf16(ga.x * hcv[0], ga.y * hcv[1]); w.y = cvt_pk_bf16(gb2.x * hcv[2], gb2.y * hcv[3]);
;                     const int t = tstart + rl;
;                     if (n == 0) stash[ai][m] = w;
;                     else if (rl >= 2) *(u32x4*)(U + (size_t)(arow0 + rl) * FF + colg0) = (u32x4){stash[ai][m].x, stash[ai][m].y, w.x, w.y};
;                     if (rl < 2 || rl >= 254) { float* hp = halo + ((size_t)u.pm * 4 + (rl < 2 ? rl : rl - 252)) * FF2; *(f32x4*)(hp + colg) = cg_; *(f32x4*)(hp + colv) = cv_; }
;                     if (t >= SEQ - 2) { float* cp = conv_p + (size_t)(b * 2 + (t - (SEQ - 2))) * FF2; *(f32x4*)(cp + colg) = cg_; *(f32x4*)(cp + colv) = cv_; }
.LBB0_1086:
	s_or_b64 exec, exec, s[20:21]
	v_mov_b32_e32 v153, v152
	v_mov_b32_e32 v40, v152
	v_mov_b32_e32 v41, v152
	v_pk_mul_f32 v[28:29], v[28:29], v[152:153]
	v_pk_mul_f32 v[30:31], v[30:31], v[40:41]
	v_pk_mul_f32 v[26:27], v[26:27], v[40:41]
	s_waitcnt lgkmcnt(0)
	v_cndmask_b32_e64 v41, v28, v32, s[50:51]
	v_pk_mul_f32 v[24:25], v[24:25], v[152:153]
	s_nop 0
	v_mov_b32_dpp v40, v41 row_ror:1 row_mask:0xf bank_mask:0xf
	v_cndmask_b32_e64 v41, v28, v32, s[48:49]
	v_cndmask_b32_e64 v43, v29, v33, s[50:51]
	v_cndmask_b32_e64 v44, v25, v37, s[50:51]
	v_mov_b32_dpp v32, v41 row_ror:2 row_mask:0xf bank_mask:0xf
	v_cndmask_b32_e64 v41, v24, v36, s[50:51]
	v_cndmask_b32_e64 v45, v30, v34, s[50:51]
	s_nop 0
	v_mov_b32_dpp v42, v41 row_ror:1 row_mask:0xf bank_mask:0xf
	v_cndmask_b32_e64 v41, v24, v36, s[48:49]
	v_cndmask_b32_e64 v47, v31, v35, s[50:51]
	v_cndmask_b32_e64 v48, v27, v39, s[50:51]
	v_mov_b32_dpp v36, v41 row_ror:2 row_mask:0xf bank_mask:0xf
	s_mov_b32 s18, 0xbf3a00e3
	s_nop 0
	v_mov_b32_dpp v41, v43 row_ror:1 row_mask:0xf bank_mask:0xf
	v_cndmask_b32_e64 v43, v29, v33, s[48:49]
	s_nop 1
	v_mov_b32_dpp v33, v43 row_ror:2 row_mask:0xf bank_mask:0xf
	v_pk_fma_f32 v[32:33], v[106:107], v[32:33], v[92:93]
	s_nop 0
	v_mov_b32_dpp v43, v44 row_ror:1 row_mask:0xf bank_mask:0xf
	v_cndmask_b32_e64 v44, v25, v37, s[48:49]
	v_pk_fma_f32 v[32:33], v[102:103], v[40:41], v[32:33]
	s_nop 0
	v_mov_b32_dpp v37, v44 row_ror:2 row_mask:0xf bank_mask:0xf
	v_pk_fma_f32 v[32:33], v[28:29], v[98:99], v[32:33]
	v_pk_fma_f32 v[36:37], v[88:89], v[36:37], v[84:85]
	v_mov_b32_dpp v44, v45 row_ror:1 row_mask:0xf bank_mask:0xf
	v_cndmask_b32_e64 v45, v30, v34, s[48:49]
	v_and_b32_e32 v41, 0x7fffffff, v33
	v_and_b32_e32 v40, 0x7fffffff, v32
	v_mov_b32_dpp v34, v45 row_ror:2 row_mask:0xf bank_mask:0xf
	v_cndmask_b32_e64 v45, v26, v38, s[50:51]
	v_pk_fma_f32 v[40:41], v[40:41], s[6:7], 1.0 op_sel_hi:[1,0,0]
	v_pk_fma_f32 v[36:37], v[80:81], v[42:43], v[36:37]
	v_mov_b32_dpp v46, v45 row_ror:1 row_mask:0xf bank_mask:0xf
	v_cndmask_b32_e64 v45, v26, v38, s[48:49]
	v_rcp_f32_e32 v40, v40
	v_rcp_f32_e32 v41, v41
	v_mov_b32_dpp v38, v45 row_ror:2 row_mask:0xf bank_mask:0xf
	v_mov_b64_e32 v[42:43], s[18:19]
	v_cmp_gt_f32_e32 vcc, 0, v32
	v_mov_b32_dpp v45, v47 row_ror:1 row_mask:0xf bank_mask:0xf
	v_cndmask_b32_e64 v47, v31, v35, s[48:49]
	v_pk_fma_f32 v[36:37], v[24:25], v[76:77], v[36:37]
	s_nop 0
	v_mov_b32_dpp v35, v47 row_ror:2 row_mask:0xf bank_mask:0xf
	v_pk_fma_f32 v[34:35], v[108:109], v[34:35], v[94:95]
	s_nop 0
	v_mov_b32_dpp v47, v48 row_ror:1 row_mask:0xf bank_mask:0xf
	v_cndmask_b32_e64 v48, v27, v39, s[48:49]
	v_pk_fma_f32 v[34:35], v[104:105], v[44:45], v[34:35]
	v_pk_fma_f32 v[44:45], v[40:41], s[24:25], v[42:43] op_sel_hi:[1,0,0]
	v_mov_b32_dpp v39, v48 row_ror:2 row_mask:0xf bank_mask:0xf
	v_pk_fma_f32 v[38:39], v[90:91], v[38:39], v[86:87]
	v_pk_fma_f32 v[44:45], v[40:41], v[44:45], s[28:29] op_sel_hi:[1,1,0]
	v_pk_fma_f32 v[38:39], v[82:83], v[46:47], v[38:39]
	v_pk_mul_f32 v[46:47], v[32:33], v[32:33]
	v_pk_fma_f32 v[44:45], v[40:41], v[44:45], s[30:31] op_sel_hi:[1,1,0]
	v_pk_mul_f32 v[46:47], v[46:47], s[36:37] op_sel_hi:[1,0]
	v_pk_fma_f32 v[44:45], v[40:41], v[44:45], s[34:35] op_sel_hi:[1,1,0]
	v_exp_f32_e32 v46, v46
	v_exp_f32_e32 v47, v47
	v_pk_mul_f32 v[40:41], v[40:41], v[44:45]
	v_pk_fma_f32 v[34:35], v[30:31], v[100:101], v[34:35]
	v_pk_fma_f32 v[38:39], v[26:27], v[78:79], v[38:39]
	v_pk_mul_f32 v[40:41], v[46:47], v[40:41]
	v_pk_mul_f32 v[44:45], v[34:35], v[34:35]
	v_pk_mul_f32 v[46:47], v[32:33], v[40:41]
	v_pk_fma_f32 v[40:41], v[32:33], v[40:41], v[32:33] neg_lo:[1,0,0] neg_hi:[1,0,0]
	v_and_b32_e32 v32, 0x7fffffff, v34
	v_cndmask_b32_e32 v46, v40, v46, vcc
	v_cmp_gt_f32_e32 vcc, 0, v33
	v_and_b32_e32 v33, 0x7fffffff, v35
	v_pk_fma_f32 v[32:33], v[32:33], s[6:7], 1.0 op_sel_hi:[1,0,0]
	v_cndmask_b32_e32 v47, v41, v47, vcc
	v_rcp_f32_e32 v32, v32
	v_rcp_f32_e32 v33, v33
	v_cmp_gt_f32_e32 vcc, 0, v34
	v_pk_fma_f32 v[40:41], v[32:33], s[24:25], v[42:43] op_sel_hi:[1,0,0]
	s_nop 0
	v_pk_fma_f32 v[40:41], v[32:33], v[40:41], s[28:29] op_sel_hi:[1,1,0]
	s_nop 0
	v_pk_fma_f32 v[40:41], v[32:33], v[40:41], s[30:31] op_sel_hi:[1,1,0]
	s_nop 0
	v_pk_fma_f32 v[40:41], v[32:33], v[40:41], s[34:35] op_sel_hi:[1,1,0]
	s_nop 0
	v_pk_mul_f32 v[32:33], v[32:33], v[40:41]
	v_pk_mul_f32 v[40:41], v[44:45], s[36:37] op_sel_hi:[1,0]
	s_nop 0
	v_exp_f32_e32 v40, v40
	v_exp_f32_e32 v41, v41
	s_nop 0
	v_pk_mul_f32 v[32:33], v[40:41], v[32:33]
	s_nop 0
	v_pk_mul_f32 v[40:41], v[34:35], v[32:33]
	v_pk_fma_f32 v[32:33], v[34:35], v[32:33], v[34:35] neg_lo:[1,0,0] neg_hi:[1,0,0]
	v_mul_f32_e32 v34, v36, v46
	v_cndmask_b32_e32 v32, v32, v40, vcc
	v_cmp_gt_f32_e32 vcc, 0, v35
	v_mul_f32_e32 v35, v37, v47
	v_cvt_pk_bf16_f32 v116, v34, v35
	v_mul_f32_e32 v32, v38, v32
	v_cndmask_b32_e32 v33, v33, v41, vcc
	v_cmp_lt_i32_e32 vcc, 1, v190
	v_mul_f32_e32 v33, v39, v33
	v_cvt_pk_bf16_f32 v117, v32, v33
	s_and_saveexec_b64 s[18:19], vcc
	s_cbranch_execz .LBB0_1113
	v_mov_b32_e32 v191, v97
	v_lshl_add_u64 v[32:33], s[16:17], 0, v[190:191]
	v_mov_b64_e32 v[34:35], s[84:85]
	s_movk_i32 s3, 0x1600
	v_mad_u64_u32 v[34:35], s[20:21], v32, s3, v[34:35]
	v_mad_i32_i24 v35, v33, s3, v35
	v_lshl_add_u64 v[32:33], v[182:183], 1, v[34:35]
	global_store_dwordx4 v[32:33], v[114:117], off
	s_or_b64 exec, exec, s[18:19]
	s_and_saveexec_b64 s[18:19], s[64:65]
	s_cbranch_execnz .LBB0_1114

; __device__ __forceinline__ unsigned cvt_pk_bf16(float lo, float hi) { unsigned r; asm volatile("v_cvt_pk_bf16_f32 %0, %1, %2" : "=v"(r) : "v"(lo), "v"(hi)); return r; }
; __device__ __forceinline__ float ror1(float x) { return __builtin_bit_cast(float, __builtin_amdgcn_update_dpp(0, __builtin_bit_cast(int, x), 0x121, 0xf, 0xf, false)); }
; __device__ __forceinline__ float ror2(float x) { return __builtin_bit_cast(float, __builtin_amdgcn_update_dpp(0, __builtin_bit_cast(int, x), 0x122, 0xf, 0xf, false)); }
;     __device__ __forceinline__ void operator()(AccT& acc, const Unit& u, int wr, int wc, int fr, int fq) const {
;     ...
;                     const f32x4 cg_ = acc[ai][0][m][n], cv_ = acc[ai][1][m][n];
;                     f32x4 p1g, p2g, p1v, p2v;
; #pragma unroll
;                     for (int j = 0; j < 4; ++j) {
;                         p1g[j] = ror1(fr == 15 ? hg[j] : cg_[j]); p2g[j] = ror2(fr >= 14 ? hg[j] : cg_[j]);
;                         p1v[j] = ror1(fr == 15 ? hv[j] : cv_[j]); p2v[j] = ror2(fr >= 14 ? hv[j] : cv_[j]);
;                     }
;                     const f32x4 hcg = bg + w0g * p2g + w1g * p1g + w2g * cg_;
;                     const f32x4 hcv = bv + w0v * p2v + w1v * p1v + w2v * cv_;
;                     const f32x2 ga = gelu_pk((f32x2){hcg[0], hcg[1]}), gb2 = gelu_pk((f32x2){hcg[2], hcg[3]});
;                     u32x2 w; w.x = cvt_pk_bf16(ga.x * hcv[0], ga.y * hcv[1]); w.y = cvt_pk_bf16(gb2.x * hcv[2], gb2.y * hcv[3]);
;                     const int t = tstart + rl;
;                     if (n == 0) stash[ai][m] = w;
;                     else if (rl >= 2) *(u32x4*)(U + (size_t)(arow0 + rl) * FF + colg0) = (u32x4){stash[ai][m].x, stash[ai][m].y, w.x, w.y};
;                     if (rl < 2 || rl >= 254) { float* hp = halo + ((size_t)u.pm * 4 + (rl < 2 ? rl : rl - 252)) * FF2; *(f32x4*)(hp + colg) = cg_; *(f32x4*)(hp + colv) = cv_; }
;                     if (t >= SEQ - 2) { float* cp = conv_p + (size_t)(b * 2 + (t - (SEQ - 2))) * FF2; *(f32x4*)(cp + colg) = cg_; *(f32x4*)(cp + colv) = cv_; }
.LBB0_1089:
	v_mov_b64_e32 v[32:33], s[0:1]
	s_movk_i32 s3, 0x5800
	v_mad_i64_i32 v[32:33], s[20:21], v146, s3, v[32:33]
	v_lshl_add_u64 v[32:33], v[182:183], 2, v[32:33]
	global_store_dwordx4 v[32:33], v[28:31], off offset:16
	v_add_co_u32_e32 v32, vcc, 0x2000, v32
	s_nop 1
	v_addc_co_u32_e32 v33, vcc, 0, v33, vcc
	global_store_dwordx4 v[32:33], v[24:27], off offset:3088
.LBB0_1090:
	s_or_b64 exec, exec, s[18:19]
	v_mov_b32_e32 v145, v144
	v_mov_b32_e32 v32, v144
	v_mov_b32_e32 v33, v144
	v_pk_mul_f32 v[14:15], v[14:15], v[32:33]
	v_pk_mul_f32 v[12:13], v[12:13], v[144:145]
	v_pk_mul_f32 v[10:11], v[10:11], v[32:33]
	v_pk_mul_f32 v[8:9], v[8:9], v[144:145]
	v_cndmask_b32_e64 v33, v12, v28, s[50:51]
	v_cndmask_b32_e64 v35, v13, v29, s[50:51]
	s_nop 0
	v_mov_b32_dpp v32, v33 row_ror:1 row_mask:0xf bank_mask:0xf
	v_cndmask_b32_e64 v33, v12, v28, s[48:49]
	v_cndmask_b32_e64 v36, v9, v25, s[50:51]
	v_cndmask_b32_e64 v37, v14, v30, s[50:51]
	v_mov_b32_dpp v28, v33 row_ror:2 row_mask:0xf bank_mask:0xf
	v_cndmask_b32_e64 v33, v8, v24, s[50:51]
	v_cndmask_b32_e64 v39, v15, v31, s[50:51]
	s_nop 0
	v_mov_b32_dpp v34, v33 row_ror:1 row_mask:0xf bank_mask:0xf
	v_cndmask_b32_e64 v33, v8, v24, s[48:49]
	v_cndmask_b32_e64 v40, v11, v27, s[50:51]
	s_mov_b32 s18, 0xbf3a00e3
	v_mov_b32_dpp v24, v33 row_ror:2 row_mask:0xf bank_mask:0xf
	s_nop 1
	v_mov_b32_dpp v33, v35 row_ror:1 row_mask:0xf bank_mask:0xf
	v_cndmask_b32_e64 v35, v13, v29, s[48:49]
	s_nop 1
	v_mov_b32_dpp v29, v35 row_ror:2 row_mask:0xf bank_mask:0xf
	v_pk_fma_f32 v[28:29], v[106:107], v[28:29], v[92:93]
	s_nop 0
	v_mov_b32_dpp v35, v36 row_ror:1 row_mask:0xf bank_mask:0xf
	v_cndmask_b32_e64 v36, v9, v25, s[48:49]
	v_pk_fma_f32 v[28:29], v[102:103], v[32:33], v[28:29]
	s_nop 0
	v_mov_b32_dpp v25, v36 row_ror:2 row_mask:0xf bank_mask:0xf
	v_pk_fma_f32 v[28:29], v[12:13], v[98:99], v[28:29]
	v_pk_fma_f32 v[24:25], v[88:89], v[24:25], v[84:85]
	v_mov_b32_dpp v36, v37 row_ror:1 row_mask:0xf bank_mask:0xf
	v_cndmask_b32_e64 v37, v14, v30, s[48:49]
	v_and_b32_e32 v33, 0x7fffffff, v29
	v_and_b32_e32 v32, 0x7fffffff, v28
	v_mov_b32_dpp v30, v37 row_ror:2 row_mask:0xf bank_mask:0xf
	v_cndmask_b32_e64 v37, v10, v26, s[50:51]
	v_pk_fma_f32 v[32:33], v[32:33], s[6:7], 1.0 op_sel_hi:[1,0,0]
	v_pk_fma_f32 v[24:25], v[80:81], v[34:35], v[24:25]
	v_mov_b32_dpp v38, v37 row_ror:1 row_mask:0xf bank_mask:0xf
	v_cndmask_b32_e64 v37, v10, v26, s[48:49]
	v_rcp_f32_e32 v32, v32
	v_rcp_f32_e32 v33, v33
	v_mov_b32_dpp v26, v37 row_ror:2 row_mask:0xf bank_mask:0xf
	v_mov_b64_e32 v[34:35], s[18:19]
	v_cmp_gt_f32_e32 vcc, 0, v28
	v_mov_b32_dpp v37, v39 row_ror:1 row_mask:0xf bank_mask:0xf
	v_cndmask_b32_e64 v39, v15, v31, s[48:49]
	v_pk_fma_f32 v[24:25], v[8:9], v[76:77], v[24:25]
	s_nop 0
	v_mov_b32_dpp v31, v39 row_ror:2 row_mask:0xf bank_mask:0xf
	v_pk_fma_f32 v[30:31], v[108:109], v[30:31], v[94:95]
	s_nop 0
	v_mov_b32_dpp v39, v40 row_ror:1 row_mask:0xf bank_mask:0xf
	v_cndmask_b32_e64 v40, v11, v27, s[48:49]
	v_pk_fma_f32 v[30:31], v[104:105], v[36:37], v[30:31]
	v_pk_fma_f32 v[36:37], v[32:33], s[24:25], v[34:35] op_sel_hi:[1,0,0]
	v_mov_b32_dpp v27, v40 row_ror:2 row_mask:0xf bank_mask:0xf
	v_pk_fma_f32 v[26:27], v[90:91], v[26:27], v[86:87]
	v_pk_fma_f32 v[36:37], v[32:33], v[36:37], s[28:29] op_sel_hi:[1,1,0]
	v_pk_fma_f32 v[26:27], v[82:83], v[38:39], v[26:27]
	v_pk_mul_f32 v[38:39], v[28:29], v[28:29]
	v_pk_fma_f32 v[36:37], v[32:33], v[36:37], s[30:31] op_sel_hi:[1,1,0]
	v_pk_mul_f32 v[38:39], v[38:39], s[36:37] op_sel_hi:[1,0]
	v_pk_fma_f32 v[36:37], v[32:33], v[36:37], s[34:35] op_sel_hi:[1,1,0]
	v_exp_f32_e32 v38, v38
	v_exp_f32_e32 v39, v39
	v_pk_mul_f32 v[32:33], v[32:33], v[36:37]
	v_pk_fma_f32 v[30:31], v[14:15], v[100:101], v[30:31]
	v_pk_fma_f32 v[26:27], v[10:11], v[78:79], v[26:27]
	v_pk_mul_f32 v[32:33], v[38:39], v[32:33]
	v_pk_mul_f32 v[36:37], v[30:31], v[30:31]
	v_pk_mul_f32 v[38:39], v[28:29], v[32:33]
	v_pk_fma_f32 v[32:33], v[28:29], v[32:33], v[28:29] neg_lo:[1,0,0] neg_hi:[1,0,0]
	v_and_b32_e32 v28, 0x7fffffff, v30
	v_cndmask_b32_e32 v38, v32, v38, vcc
	v_cmp_gt_f32_e32 vcc, 0, v29
	v_and_b32_e32 v29, 0x7fffffff, v31
	v_pk_fma_f32 v[28:29], v[28:29], s[6:7], 1.0 op_sel_hi:[1,0,0]
	v_cndmask_b32_e32 v39, v33, v39, vcc
	v_rcp_f32_e32 v28, v28
	v_rcp_f32_e32 v29, v29
	v_cmp_gt_f32_e32 vcc, 0, v30
	v_mul_f32_e32 v24, v24, v38
	v_mul_f32_e32 v25, v25, v39
	v_pk_fma_f32 v[32:33], v[28:29], s[24:25], v[34:35] op_sel_hi:[1,0,0]
	v_cvt_pk_bf16_f32 v74, v24, v25
	s_nop 0
	v_pk_fma_f32 v[32:33], v[28:29], v[32:33], s[28:29] op_sel_hi:[1,1,0]
	s_nop 0
	v_pk_fma_f32 v[32:33], v[28:29], v[32:33], s[30:31] op_sel_hi:[1,1,0]
	s_nop 0
	v_pk_fma_f32 v[32:33], v[28:29], v[32:33], s[34:35] op_sel_hi:[1,1,0]
	s_nop 0
	v_pk_mul_f32 v[28:29], v[28:29], v[32:33]
	v_pk_mul_f32 v[32:33], v[36:37], s[36:37] op_sel_hi:[1,0]
	s_nop 0
	v_exp_f32_e32 v32, v32
	v_exp_f32_e32 v33, v33
	s_nop 0
	v_pk_mul_f32 v[28:29], v[32:33], v[28:29]
	s_nop 0
	v_pk_mul_f32 v[32:33], v[30:31], v[28:29]
	v_pk_fma_f32 v[28:29], v[30:31], v[28:29], v[30:31] neg_lo:[1,0,0] neg_hi:[1,0,0]
	s_nop 0
	v_cndmask_b32_e32 v28, v28, v32, vcc
	v_cmp_gt_f32_e32 vcc, 0, v31
	v_mul_f32_e32 v24, v26, v28
	s_nop 0
	v_cndmask_b32_e32 v29, v29, v33, vcc
	v_cmp_lt_i32_e32 vcc, 1, v188
	v_mul_f32_e32 v25, v27, v29
	v_cvt_pk_bf16_f32 v75, v24, v25
	s_and_saveexec_b64 s[18:19], vcc
	s_cbranch_execz .LBB0_1115
	v_mov_b32_e32 v189, v97
	v_lshl_add_u64 v[24:25], s[16:17], 0, v[188:189]
	v_mov_b64_e32 v[26:27], s[84:85]
	s_movk_i32 s3, 0x1600
	v_mad_u64_u32 v[26:27], s[20:21], v24, s3, v[26:27]
	v_mad_i32_i24 v27, v25, s3, v27
	v_lshl_add_u64 v[24:25], v[182:183], 1, v[26:27]
	global_store_dwordx4 v[24:25], v[72:75], off
	s_or_b64 exec, exec, s[18:19]
	s_and_saveexec_b64 s[18:19], s[60:61]
	s_cbranch_execnz .LBB0_1116

; __device__ __forceinline__ unsigned cvt_pk_bf16(float lo, float hi) { unsigned r; asm volatile("v_cvt_pk_bf16_f32 %0, %1, %2" : "=v"(r) : "v"(lo), "v"(hi)); return r; }
; __device__ __forceinline__ float ror1(float x) { return __builtin_bit_cast(float, __builtin_amdgcn_update_dpp(0, __builtin_bit_cast(int, x), 0x121, 0xf, 0xf, false)); }
; __device__ __forceinline__ float ror2(float x) { return __builtin_bit_cast(float, __builtin_amdgcn_update_dpp(0, __builtin_bit_cast(int, x), 0x122, 0xf, 0xf, false)); }
;     __device__ __forceinline__ void operator()(AccT& acc, const Unit& u, int wr, int wc, int fr, int fq) const {
;     ...
;                     const f32x4 cg_ = acc[ai][0][m][n], cv_ = acc[ai][1][m][n];
;                     f32x4 p1g, p2g, p1v, p2v;
; #pragma unroll
;                     for (int j = 0; j < 4; ++j) {
;                         p1g[j] = ror1(fr == 15 ? hg[j] : cg_[j]); p2g[j] = ror2(fr >= 14 ? hg[j] : cg_[j]);
;                         p1v[j] = ror1(fr == 15 ? hv[j] : cv_[j]); p2v[j] = ror2(fr >= 14 ? hv[j] : cv_[j]);
;                     }
;                     const f32x4 hcg = bg + w0g * p2g + w1g * p1g + w2g * cg_;
;                     const f32x4 hcv = bv + w0v * p2v + w1v * p1v + w2v * cv_;
;                     const f32x2 ga = gelu_pk((f32x2){hcg[0], hcg[1]}), gb2 = gelu_pk((f32x2){hcg[2], hcg[3]});
;                     u32x2 w; w.x = cvt_pk_bf16(ga.x * hcv[0], ga.y * hcv[1]); w.y = cvt_pk_bf16(gb2.x * hcv[2], gb2.y * hcv[3]);
;                     const int t = tstart + rl;
;                     if (n == 0) stash[ai][m] = w;
;                     else if (rl >= 2) *(u32x4*)(U + (size_t)(arow0 + rl) * FF + colg0) = (u32x4){stash[ai][m].x, stash[ai][m].y, w.x, w.y};
;                     if (rl < 2 || rl >= 254) { float* hp = halo + ((size_t)u.pm * 4 + (rl < 2 ? rl : rl - 252)) * FF2; *(f32x4*)(hp + colg) = cg_; *(f32x4*)(hp + colv) = cv_; }
;                     if (t >= SEQ - 2) { float* cp = conv_p + (size_t)(b * 2 + (t - (SEQ - 2))) * FF2; *(f32x4*)(cp + colg) = cg_; *(f32x4*)(cp + colv) = cv_; }
.LBB0_1093:
	v_mov_b64_e32 v[24:25], s[0:1]
	s_movk_i32 s3, 0x5800
	v_mad_i64_i32 v[24:25], s[20:21], v142, s3, v[24:25]
	v_lshl_add_u64 v[24:25], v[182:183], 2, v[24:25]
	global_store_dwordx4 v[24:25], v[12:15], off offset:16
	v_add_co_u32_e32 v24, vcc, 0x2000, v24
	s_nop 1
	v_addc_co_u32_e32 v25, vcc, 0, v25, vcc
	global_store_dwordx4 v[24:25], v[8:11], off offset:3088
.LBB0_1094:
	s_or_b64 exec, exec, s[18:19]
	v_mov_b32_e32 v141, v140
	v_mov_b32_e32 v24, v140
	v_mov_b32_e32 v25, v140
	v_pk_mul_f32 v[6:7], v[6:7], v[24:25]
	v_pk_mul_f32 v[4:5], v[4:5], v[140:141]
	v_pk_mul_f32 v[2:3], v[2:3], v[24:25]
	v_pk_mul_f32 v[0:1], v[0:1], v[140:141]
	v_cndmask_b32_e64 v25, v4, v12, s[50:51]
	v_cndmask_b32_e64 v27, v5, v13, s[50:51]
	s_nop 0
	v_mov_b32_dpp v24, v25 row_ror:1 row_mask:0xf bank_mask:0xf
	v_cndmask_b32_e64 v25, v4, v12, s[48:49]
	v_cndmask_b32_e64 v28, v1, v9, s[50:51]
	v_cndmask_b32_e64 v29, v6, v14, s[50:51]
	v_mov_b32_dpp v12, v25 row_ror:2 row_mask:0xf bank_mask:0xf
	v_cndmask_b32_e64 v25, v0, v8, s[50:51]
	v_cndmask_b32_e64 v31, v7, v15, s[50:51]
	s_nop 0
	v_mov_b32_dpp v26, v25 row_ror:1 row_mask:0xf bank_mask:0xf
	v_cndmask_b32_e64 v25, v0, v8, s[48:49]
	v_cndmask_b32_e64 v32, v3, v11, s[50:51]
	s_mov_b32 s18, 0xbf3a00e3
	v_mov_b32_dpp v8, v25 row_ror:2 row_mask:0xf bank_mask:0xf
	s_nop 1
	v_mov_b32_dpp v25, v27 row_ror:1 row_mask:0xf bank_mask:0xf
	v_cndmask_b32_e64 v27, v5, v13, s[48:49]
	s_nop 1
	v_mov_b32_dpp v13, v27 row_ror:2 row_mask:0xf bank_mask:0xf
	v_pk_fma_f32 v[12:13], v[106:107], v[12:13], v[92:93]
	s_nop 0
	v_mov_b32_dpp v27, v28 row_ror:1 row_mask:0xf bank_mask:0xf
	v_cndmask_b32_e64 v28, v1, v9, s[48:49]
	v_pk_fma_f32 v[12:13], v[102:103], v[24:25], v[12:13]
	s_nop 0
	v_mov_b32_dpp v9, v28 row_ror:2 row_mask:0xf bank_mask:0xf
	v_pk_fma_f32 v[12:13], v[4:5], v[98:99], v[12:13]
	v_pk_fma_f32 v[8:9], v[88:89], v[8:9], v[84:85]
	v_mov_b32_dpp v28, v29 row_ror:1 row_mask:0xf bank_mask:0xf
	v_cndmask_b32_e64 v29, v6, v14, s[48:49]
	v_and_b32_e32 v25, 0x7fffffff, v13
	v_and_b32_e32 v24, 0x7fffffff, v12
	v_mov_b32_dpp v14, v29 row_ror:2 row_mask:0xf bank_mask:0xf
	v_cndmask_b32_e64 v29, v2, v10, s[50:51]
	v_pk_fma_f32 v[24:25], v[24:25], s[6:7], 1.0 op_sel_hi:[1,0,0]
	v_pk_fma_f32 v[8:9], v[80:81], v[26:27], v[8:9]
	v_mov_b32_dpp v30, v29 row_ror:1 row_mask:0xf bank_mask:0xf
	v_cndmask_b32_e64 v29, v2, v10, s[48:49]
	v_rcp_f32_e32 v24, v24
	v_rcp_f32_e32 v25, v25
	v_mov_b32_dpp v10, v29 row_ror:2 row_mask:0xf bank_mask:0xf
	v_mov_b64_e32 v[26:27], s[18:19]
	v_cmp_gt_f32_e32 vcc, 0, v12
	v_mov_b32_dpp v29, v31 row_ror:1 row_mask:0xf bank_mask:0xf
	v_cndmask_b32_e64 v31, v7, v15, s[48:49]
	v_pk_fma_f32 v[8:9], v[0:1], v[76:77], v[8:9]
	s_nop 0
	v_mov_b32_dpp v15, v31 row_ror:2 row_mask:0xf bank_mask:0xf
	v_pk_fma_f32 v[14:15], v[108:109], v[14:15], v[94:95]
	s_nop 0
	v_mov_b32_dpp v31, v32 row_ror:1 row_mask:0xf bank_mask:0xf
	v_cndmask_b32_e64 v32, v3, v11, s[48:49]
	v_pk_fma_f32 v[14:15], v[104:105], v[28:29], v[14:15]
	v_pk_fma_f32 v[28:29], v[24:25], s[24:25], v[26:27] op_sel_hi:[1,0,0]
	v_mov_b32_dpp v11, v32 row_ror:2 row_mask:0xf bank_mask:0xf
	v_pk_fma_f32 v[10:11], v[90:91], v[10:11], v[86:87]
	v_pk_fma_f32 v[28:29], v[24:25], v[28:29], s[28:29] op_sel_hi:[1,1,0]
	v_pk_fma_f32 v[10:11], v[82:83], v[30:31], v[10:11]
	v_pk_mul_f32 v[30:31], v[12:13], v[12:13]
	v_pk_fma_f32 v[28:29], v[24:25], v[28:29], s[30:31] op_sel_hi:[1,1,0]
	v_pk_mul_f32 v[30:31], v[30:31], s[36:37] op_sel_hi:[1,0]
	v_pk_fma_f32 v[28:29], v[24:25], v[28:29], s[34:35] op_sel_hi:[1,1,0]
	v_exp_f32_e32 v30, v30
	v_exp_f32_e32 v31, v31
	v_pk_mul_f32 v[24:25], v[24:25], v[28:29]
	v_pk_fma_f32 v[14:15], v[6:7], v[100:101], v[14:15]
	v_pk_fma_f32 v[10:11], v[2:3], v[78:79], v[10:11]
	v_pk_mul_f32 v[24:25], v[30:31], v[24:25]
	v_pk_mul_f32 v[28:29], v[14:15], v[14:15]
	v_pk_mul_f32 v[30:31], v[12:13], v[24:25]
	v_pk_fma_f32 v[24:25], v[12:13], v[24:25], v[12:13] neg_lo:[1,0,0] neg_hi:[1,0,0]
	v_and_b32_e32 v12, 0x7fffffff, v14
	v_cndmask_b32_e32 v30, v24, v30, vcc
	v_cmp_gt_f32_e32 vcc, 0, v13
	v_and_b32_e32 v13, 0x7fffffff, v15
	v_pk_fma_f32 v[12:13], v[12:13], s[6:7], 1.0 op_sel_hi:[1,0,0]
	v_cndmask_b32_e32 v31, v25, v31, vcc
	v_rcp_f32_e32 v12, v12
	v_rcp_f32_e32 v13, v13
	v_cmp_gt_f32_e32 vcc, 0, v14
	v_mul_f32_e32 v8, v8, v30
	v_mul_f32_e32 v9, v9, v31
	v_pk_fma_f32 v[24:25], v[12:13], s[24:25], v[26:27] op_sel_hi:[1,0,0]
	v_cvt_pk_bf16_f32 v68, v8, v9
	s_nop 0
	v_pk_fma_f32 v[24:25], v[12:13], v[24:25], s[28:29] op_sel_hi:[1,1,0]
	s_nop 0
	v_pk_fma_f32 v[24:25], v[12:13], v[24:25], s[30:31] op_sel_hi:[1,1,0]
	s_nop 0
	v_pk_fma_f32 v[24:25], v[12:13], v[24:25], s[34:35] op_sel_hi:[1,1,0]
	s_nop 0
	v_pk_mul_f32 v[12:13], v[12:13], v[24:25]
	v_pk_mul_f32 v[24:25], v[28:29], s[36:37] op_sel_hi:[1,0]
	s_nop 0
	v_exp_f32_e32 v24, v24
	v_exp_f32_e32 v25, v25
	s_nop 0
	v_pk_mul_f32 v[12:13], v[24:25], v[12:13]
	s_nop 0
	v_pk_mul_f32 v[24:25], v[14:15], v[12:13]
	v_pk_fma_f32 v[12:13], v[14:15], v[12:13], v[14:15] neg_lo:[1,0,0] neg_hi:[1,0,0]
	s_nop 0
	v_cndmask_b32_e32 v12, v12, v24, vcc
	v_cmp_gt_f32_e32 vcc, 0, v15
	v_mul_f32_e32 v8, v10, v12
	s_nop 0
	v_cndmask_b32_e32 v13, v13, v25, vcc
	v_cmp_lt_i32_e32 vcc, 1, v186
	v_mul_f32_e32 v9, v11, v13
	v_cvt_pk_bf16_f32 v69, v8, v9
	s_and_saveexec_b64 s[18:19], vcc
	s_cbranch_execz .LBB0_1117
	v_mov_b32_e32 v187, v97
	v_lshl_add_u64 v[8:9], s[16:17], 0, v[186:187]
	v_mov_b64_e32 v[10:11], s[84:85]
	s_movk_i32 s3, 0x1600
	v_mad_u64_u32 v[10:11], s[20:21], v8, s3, v[10:11]
	v_mad_i32_i24 v11, v9, s3, v11
	v_lshl_add_u64 v[8:9], v[182:183], 1, v[10:11]
	global_store_dwordx4 v[8:9], v[66:69], off
	s_or_b64 exec, exec, s[18:19]
	s_and_saveexec_b64 s[18:19], s[56:57]
	s_cbranch_execnz .LBB0_1118

; __device__ __forceinline__ unsigned cvt_pk_bf16(float lo, float hi) { unsigned r; asm volatile("v_cvt_pk_bf16_f32 %0, %1, %2" : "=v"(r) : "v"(lo), "v"(hi)); return r; }
; __device__ __forceinline__ float ror1(float x) { return __builtin_bit_cast(float, __builtin_amdgcn_update_dpp(0, __builtin_bit_cast(int, x), 0x121, 0xf, 0xf, false)); }
; __device__ __forceinline__ float ror2(float x) { return __builtin_bit_cast(float, __builtin_amdgcn_update_dpp(0, __builtin_bit_cast(int, x), 0x122, 0xf, 0xf, false)); }
;     __device__ __forceinline__ void operator()(AccT& acc, const Unit& u, int wr, int wc, int fr, int fq) const {
;     ...
;                     const f32x4 cg_ = acc[ai][0][m][n], cv_ = acc[ai][1][m][n];
;                     f32x4 p1g, p2g, p1v, p2v;
; #pragma unroll
;                     for (int j = 0; j < 4; ++j) {
;                         p1g[j] = ror1(fr == 15 ? hg[j] : cg_[j]); p2g[j] = ror2(fr >= 14 ? hg[j] : cg_[j]);
;                         p1v[j] = ror1(fr == 15 ? hv[j] : cv_[j]); p2v[j] = ror2(fr >= 14 ? hv[j] : cv_[j]);
;                     }
;                     const f32x4 hcg = bg + w0g * p2g + w1g * p1g + w2g * cg_;
;                     const f32x4 hcv = bv + w0v * p2v + w1v * p1v + w2v * cv_;
;                     const f32x2 ga = gelu_pk((f32x2){hcg[0], hcg[1]}), gb2 = gelu_pk((f32x2){hcg[2], hcg[3]});
;                     u32x2 w; w.x = cvt_pk_bf16(ga.x * hcv[0], ga.y * hcv[1]); w.y = cvt_pk_bf16(gb2.x * hcv[2], gb2.y * hcv[3]);
;                     const int t = tstart + rl;
;                     if (n == 0) stash[ai][m] = w;
;                     else if (rl >= 2) *(u32x4*)(U + (size_t)(arow0 + rl) * FF + colg0) = (u32x4){stash[ai][m].x, stash[ai][m].y, w.x, w.y};
;                     if (rl < 2 || rl >= 254) { float* hp = halo + ((size_t)u.pm * 4 + (rl < 2 ? rl : rl - 252)) * FF2; *(f32x4*)(hp + colg) = cg_; *(f32x4*)(hp + colv) = cv_; }
;                     if (t >= SEQ - 2) { float* cp = conv_p + (size_t)(b * 2 + (t - (SEQ - 2))) * FF2; *(f32x4*)(cp + colg) = cg_; *(f32x4*)(cp + colv) = cv_; }
.LBB0_1097:
	v_mov_b64_e32 v[8:9], s[0:1]
	s_movk_i32 s3, 0x5800
	v_mad_i64_i32 v[8:9], s[20:21], v135, s3, v[8:9]
	v_lshl_add_u64 v[8:9], v[182:183], 2, v[8:9]
	global_store_dwordx4 v[8:9], v[4:7], off offset:16
	v_add_co_u32_e32 v8, vcc, 0x2000, v8
	s_nop 1
	v_addc_co_u32_e32 v9, vcc, 0, v9, vcc
	global_store_dwordx4 v[8:9], v[0:3], off offset:3088
.LBB0_1098:
	s_or_b64 exec, exec, s[18:19]
	v_cndmask_b32_e64 v9, v16, v4, s[50:51]
	v_cndmask_b32_e64 v11, v17, v5, s[50:51]
	s_nop 0
	v_mov_b32_dpp v8, v9 row_ror:1 row_mask:0xf bank_mask:0xf
	v_cndmask_b32_e64 v9, v16, v4, s[48:49]
	v_cndmask_b32_e64 v12, v21, v1, s[50:51]
	v_cndmask_b32_e64 v13, v18, v6, s[50:51]
	v_mov_b32_dpp v4, v9 row_ror:2 row_mask:0xf bank_mask:0xf
	v_cndmask_b32_e64 v9, v20, v0, s[50:51]
	v_cndmask_b32_e64 v15, v19, v7, s[50:51]
	s_nop 0
	v_mov_b32_dpp v10, v9 row_ror:1 row_mask:0xf bank_mask:0xf
	v_cndmask_b32_e64 v9, v20, v0, s[48:49]
	v_cndmask_b32_e64 v24, v23, v3, s[50:51]
	s_mov_b32 s18, 0xbf3a00e3
	v_mov_b32_dpp v0, v9 row_ror:2 row_mask:0xf bank_mask:0xf
	s_nop 1
	v_mov_b32_dpp v9, v11 row_ror:1 row_mask:0xf bank_mask:0xf
	v_cndmask_b32_e64 v11, v17, v5, s[48:49]
	s_nop 1
	v_mov_b32_dpp v5, v11 row_ror:2 row_mask:0xf bank_mask:0xf
	v_pk_fma_f32 v[4:5], v[106:107], v[4:5], v[92:93]
	s_nop 0
	v_mov_b32_dpp v11, v12 row_ror:1 row_mask:0xf bank_mask:0xf
	v_cndmask_b32_e64 v12, v21, v1, s[48:49]
	v_pk_fma_f32 v[4:5], v[102:103], v[8:9], v[4:5]
	s_nop 0
	v_mov_b32_dpp v1, v12 row_ror:2 row_mask:0xf bank_mask:0xf
	v_pk_fma_f32 v[4:5], v[16:17], v[98:99], v[4:5]
	v_pk_fma_f32 v[0:1], v[88:89], v[0:1], v[84:85]
	v_mov_b32_dpp v12, v13 row_ror:1 row_mask:0xf bank_mask:0xf
	v_cndmask_b32_e64 v13, v18, v6, s[48:49]
	v_and_b32_e32 v9, 0x7fffffff, v5
	v_and_b32_e32 v8, 0x7fffffff, v4
	v_mov_b32_dpp v6, v13 row_ror:2 row_mask:0xf bank_mask:0xf
	v_cndmask_b32_e64 v13, v22, v2, s[50:51]
	v_pk_fma_f32 v[8:9], v[8:9], s[6:7], 1.0 op_sel_hi:[1,0,0]
	v_pk_fma_f32 v[0:1], v[80:81], v[10:11], v[0:1]
	v_mov_b32_dpp v14, v13 row_ror:1 row_mask:0xf bank_mask:0xf
	v_cndmask_b32_e64 v13, v22, v2, s[48:49]
	v_rcp_f32_e32 v8, v8
	v_rcp_f32_e32 v9, v9
	v_mov_b32_dpp v2, v13 row_ror:2 row_mask:0xf bank_mask:0xf
	v_mov_b64_e32 v[10:11], s[18:19]
	v_cmp_gt_f32_e32 vcc, 0, v4
	v_mov_b32_dpp v13, v15 row_ror:1 row_mask:0xf bank_mask:0xf
	v_cndmask_b32_e64 v15, v19, v7, s[48:49]
	v_pk_fma_f32 v[0:1], v[20:21], v[76:77], v[0:1]
	s_nop 0
	v_mov_b32_dpp v7, v15 row_ror:2 row_mask:0xf bank_mask:0xf
	v_pk_fma_f32 v[6:7], v[108:109], v[6:7], v[94:95]
	s_nop 0
	v_mov_b32_dpp v15, v24 row_ror:1 row_mask:0xf bank_mask:0xf
	v_cndmask_b32_e64 v24, v23, v3, s[48:49]
	v_pk_fma_f32 v[6:7], v[104:105], v[12:13], v[6:7]
	v_pk_fma_f32 v[12:13], v[8:9], s[24:25], v[10:11] op_sel_hi:[1,0,0]
	v_mov_b32_dpp v3, v24 row_ror:2 row_mask:0xf bank_mask:0xf
	v_pk_fma_f32 v[2:3], v[90:91], v[2:3], v[86:87]
	v_pk_fma_f32 v[6:7], v[18:19], v[100:101], v[6:7]
	v_pk_fma_f32 v[2:3], v[82:83], v[14:15], v[2:3]
	v_pk_mul_f32 v[14:15], v[4:5], v[4:5]
	v_pk_fma_f32 v[12:13], v[8:9], v[12:13], s[28:29] op_sel_hi:[1,1,0]
	v_pk_mul_f32 v[14:15], v[14:15], s[36:37] op_sel_hi:[1,0]
	v_pk_fma_f32 v[12:13], v[8:9], v[12:13], s[30:31] op_sel_hi:[1,1,0]
	v_exp_f32_e32 v14, v14
	v_exp_f32_e32 v15, v15
	v_and_b32_e32 v25, 0x7fffffff, v7
	v_and_b32_e32 v24, 0x7fffffff, v6
	v_pk_fma_f32 v[12:13], v[8:9], v[12:13], s[34:35] op_sel_hi:[1,1,0]
	v_pk_fma_f32 v[24:25], v[24:25], s[6:7], 1.0 op_sel_hi:[1,0,0]
	v_pk_mul_f32 v[8:9], v[8:9], v[12:13]
	v_rcp_f32_e32 v24, v24
	v_rcp_f32_e32 v25, v25
	v_pk_mul_f32 v[8:9], v[14:15], v[8:9]
	v_pk_mul_f32 v[12:13], v[6:7], v[6:7]
	v_pk_mul_f32 v[14:15], v[4:5], v[8:9]
	v_pk_fma_f32 v[8:9], v[4:5], v[8:9], v[4:5] neg_lo:[1,0,0] neg_hi:[1,0,0]
	v_pk_fma_f32 v[2:3], v[22:23], v[78:79], v[2:3]
	v_cndmask_b32_e32 v14, v8, v14, vcc
	v_cmp_gt_f32_e32 vcc, 0, v5
	v_pk_fma_f32 v[4:5], v[24:25], s[24:25], v[10:11] op_sel_hi:[1,0,0]
	v_mul_f32_e32 v0, v0, v14
	v_cndmask_b32_e32 v15, v9, v15, vcc
	v_pk_mul_f32 v[8:9], v[12:13], s[36:37] op_sel_hi:[1,0]
	v_pk_fma_f32 v[4:5], v[24:25], v[4:5], s[28:29] op_sel_hi:[1,1,0]
	v_exp_f32_e32 v8, v8
	v_exp_f32_e32 v9, v9
	v_pk_fma_f32 v[4:5], v[24:25], v[4:5], s[30:31] op_sel_hi:[1,1,0]
	v_cmp_gt_f32_e32 vcc, 0, v6
	v_pk_fma_f32 v[4:5], v[24:25], v[4:5], s[34:35] op_sel_hi:[1,1,0]
	v_mul_f32_e32 v1, v1, v15
	v_pk_mul_f32 v[4:5], v[24:25], v[4:5]
	v_cvt_pk_bf16_f32 v66, v0, v1
	s_nop 0
	v_pk_mul_f32 v[4:5], v[8:9], v[4:5]
	s_nop 0
	v_pk_mul_f32 v[8:9], v[6:7], v[4:5]
	v_pk_fma_f32 v[4:5], v[6:7], v[4:5], v[6:7] neg_lo:[1,0,0] neg_hi:[1,0,0]
	s_nop 0
	v_cndmask_b32_e32 v4, v4, v8, vcc
	v_cmp_gt_f32_e32 vcc, 0, v7
	v_mul_f32_e32 v0, v2, v4
	s_nop 0
	v_cndmask_b32_e32 v5, v5, v9, vcc
	v_cmp_lt_i32_e32 vcc, 1, v184
	v_mul_f32_e32 v1, v3, v5
	v_cvt_pk_bf16_f32 v67, v0, v1
	s_and_saveexec_b64 s[18:19], vcc
	s_cbranch_execz .LBB0_1119
	v_mov_b32_e32 v185, v97
	v_lshl_add_u64 v[0:1], s[16:17], 0, v[184:185]
	v_mov_b64_e32 v[2:3], s[84:85]
	s_movk_i32 s3, 0x1600
	v_mad_u64_u32 v[2:3], s[16:17], v0, s3, v[2:3]
	v_mad_i32_i24 v3, v1, s3, v3
	v_lshl_add_u64 v[0:1], v[182:183], 1, v[2:3]
	global_store_dwordx4 v[0:1], v[64:67], off
	s_or_b64 exec, exec, s[18:19]
	s_and_saveexec_b64 s[16:17], s[52:53]
	s_cbranch_execnz .LBB0_1120

;     __device__ __forceinline__ void operator()(AccT& acc, const Unit& u, int wr, int wc, int fr, int fq) const {
;     ...
;                     if (t >= SEQ - 2) { float* cp = conv_p + (size_t)(b * 2 + (t - (SEQ - 2))) * FF2; *(f32x4*)(cp + colg) = cg_; *(f32x4*)(cp + colv) = cv_; }
.LBB0_1101:
	v_mov_b64_e32 v[0:1], s[0:1]
	s_movk_i32 s3, 0x5800
	v_mad_i64_i32 v[0:1], s[16:17], v133, s3, v[0:1]
	v_lshl_add_u64 v[0:1], v[182:183], 2, v[0:1]
	global_store_dwordx4 v[0:1], v[16:19], off offset:16
	v_add_co_u32_e32 v0, vcc, 0x2000, v0
	s_nop 1
	v_addc_co_u32_e32 v1, vcc, 0, v1, vcc
	global_store_dwordx4 v[0:1], v[20:23], off offset:3088

;     __device__ __forceinline__ void operator()(AccT& acc, const Unit& u, int wr, int wc, int fr, int fq) const {
;     ...
;                     if (rl < 2 || rl >= 254) { float* hp = halo + ((size_t)u.pm * 4 + (rl < 2 ? rl : rl - 252)) * FF2; *(f32x4*)(hp + colg) = cg_; *(f32x4*)(hp + colv) = cv_; }
.LBB0_1106:
	v_cmp_gt_i32_e32 vcc, 2, v210
	v_mov_b64_e32 v[70:71], s[92:93]
	s_movk_i32 s3, 0x5800
	v_cndmask_b32_e32 v68, v169, v210, vcc
	v_ashrrev_i32_e32 v69, 31, v68
	v_lshl_add_u64 v[68:69], s[14:15], 0, v[68:69]
	v_mad_u64_u32 v[70:71], s[22:23], v68, s3, v[70:71]
	v_mad_i32_i24 v71, v69, s3, v71
	v_lshl_add_u64 v[68:69], v[182:183], 2, v[70:71]
	global_store_dwordx4 v[68:69], v[60:63], off offset:16
	v_add_co_u32_e32 v68, vcc, 0x2000, v68
	s_nop 1
	v_addc_co_u32_e32 v69, vcc, 0, v69, vcc
	global_store_dwordx4 v[68:69], v[56:59], off offset:3088
	s_or_b64 exec, exec, s[20:21]
	s_and_saveexec_b64 s[20:21], s[82:83]
	s_cbranch_execnz .LBB0_1071
	s_branch .LBB0_1072

;     __device__ __forceinline__ void operator()(AccT& acc, const Unit& u, int wr, int wc, int fr, int fq) const {
;     ...
;                     if (rl < 2 || rl >= 254) { float* hp = halo + ((size_t)u.pm * 4 + (rl < 2 ? rl : rl - 252)) * FF2; *(f32x4*)(hp + colg) = cg_; *(f32x4*)(hp + colv) = cv_; }
.LBB0_1108:
	v_cmp_gt_i32_e32 vcc, 2, v208
	v_mov_b64_e32 v[58:59], s[92:93]
	s_movk_i32 s3, 0x5800
	v_cndmask_b32_e32 v56, v157, v208, vcc
	v_ashrrev_i32_e32 v57, 31, v56
	v_lshl_add_u64 v[56:57], s[14:15], 0, v[56:57]
	v_mad_u64_u32 v[58:59], s[22:23], v56, s3, v[58:59]
	v_mad_i32_i24 v59, v57, s3, v59
	v_lshl_add_u64 v[56:57], v[182:183], 2, v[58:59]
	global_store_dwordx4 v[56:57], v[52:55], off offset:16
	v_add_co_u32_e32 v56, vcc, 0x2000, v56
	s_nop 1
	v_addc_co_u32_e32 v57, vcc, 0, v57, vcc
	global_store_dwordx4 v[56:57], v[40:43], off offset:3088
	s_or_b64 exec, exec, s[20:21]
	s_and_saveexec_b64 s[20:21], s[78:79]
	s_cbranch_execnz .LBB0_1075
	s_branch .LBB0_1076

;     __device__ __forceinline__ void operator()(AccT& acc, const Unit& u, int wr, int wc, int fr, int fq) const {
;     ...
;                     if (rl < 2 || rl >= 254) { float* hp = halo + ((size_t)u.pm * 4 + (rl < 2 ? rl : rl - 252)) * FF2; *(f32x4*)(hp + colg) = cg_; *(f32x4*)(hp + colv) = cv_; }
.LBB0_1110:
	v_cmp_gt_i32_e32 vcc, 2, v206
	v_mov_b64_e32 v[42:43], s[92:93]
	s_movk_i32 s3, 0x5800
	v_cndmask_b32_e32 v40, v160, v206, vcc
	v_ashrrev_i32_e32 v41, 31, v40
	v_lshl_add_u64 v[40:41], s[14:15], 0, v[40:41]
	v_mad_u64_u32 v[42:43], s[22:23], v40, s3, v[42:43]
	v_mad_i32_i24 v43, v41, s3, v43
	v_lshl_add_u64 v[40:41], v[182:183], 2, v[42:43]
	global_store_dwordx4 v[40:41], v[36:39], off offset:16
	v_add_co_u32_e32 v40, vcc, 0x2000, v40
	s_nop 1
	v_addc_co_u32_e32 v41, vcc, 0, v41, vcc
	global_store_dwordx4 v[40:41], v[32:35], off offset:3088
	s_or_b64 exec, exec, s[20:21]
	s_and_saveexec_b64 s[20:21], s[74:75]
	s_cbranch_execnz .LBB0_1079
	s_branch .LBB0_1080

;     __device__ __forceinline__ void operator()(AccT& acc, const Unit& u, int wr, int wc, int fr, int fq) const {
;     ...
;                     if (rl < 2 || rl >= 254) { float* hp = halo + ((size_t)u.pm * 4 + (rl < 2 ? rl : rl - 252)) * FF2; *(f32x4*)(hp + colg) = cg_; *(f32x4*)(hp + colv) = cv_; }
.LBB0_1112:
	v_cmp_gt_i32_e32 vcc, 2, v192
	v_mov_b64_e32 v[34:35], s[92:93]
	s_movk_i32 s3, 0x5800
	v_cndmask_b32_e32 v32, v158, v192, vcc
	v_ashrrev_i32_e32 v33, 31, v32
	v_lshl_add_u64 v[32:33], s[14:15], 0, v[32:33]
	v_mad_u64_u32 v[34:35], s[22:23], v32, s3, v[34:35]
	v_mad_i32_i24 v35, v33, s3, v35
	v_lshl_add_u64 v[32:33], v[182:183], 2, v[34:35]
	global_store_dwordx4 v[32:33], v[48:51], off offset:16
	v_add_co_u32_e32 v32, vcc, 0x2000, v32
	s_nop 1
	v_addc_co_u32_e32 v33, vcc, 0, v33, vcc
	global_store_dwordx4 v[32:33], v[44:47], off offset:3088
	s_or_b64 exec, exec, s[20:21]
	s_and_saveexec_b64 s[20:21], s[70:71]
	s_cbranch_execnz .LBB0_1083
	s_branch .LBB0_1084

;     __device__ __forceinline__ void operator()(AccT& acc, const Unit& u, int wr, int wc, int fr, int fq) const {
;     ...
;                     if (rl < 2 || rl >= 254) { float* hp = halo + ((size_t)u.pm * 4 + (rl < 2 ? rl : rl - 252)) * FF2; *(f32x4*)(hp + colg) = cg_; *(f32x4*)(hp + colv) = cv_; }
.LBB0_1114:
	v_cmp_gt_i32_e32 vcc, 2, v190
	v_mov_b64_e32 v[34:35], s[92:93]
	s_movk_i32 s3, 0x5800
	v_cndmask_b32_e32 v32, v145, v190, vcc
	v_ashrrev_i32_e32 v33, 31, v32
	v_lshl_add_u64 v[32:33], s[14:15], 0, v[32:33]
	v_mad_u64_u32 v[34:35], s[20:21], v32, s3, v[34:35]
	v_mad_i32_i24 v35, v33, s3, v35
	v_lshl_add_u64 v[32:33], v[182:183], 2, v[34:35]
	global_store_dwordx4 v[32:33], v[28:31], off offset:16
	v_add_co_u32_e32 v32, vcc, 0x2000, v32
	s_nop 1
	v_addc_co_u32_e32 v33, vcc, 0, v33, vcc
	global_store_dwordx4 v[32:33], v[24:27], off offset:3088
	s_or_b64 exec, exec, s[18:19]
	s_and_saveexec_b64 s[18:19], s[66:67]
	s_cbranch_execnz .LBB0_1089
	s_branch .LBB0_1090

;     __device__ __forceinline__ void operator()(AccT& acc, const Unit& u, int wr, int wc, int fr, int fq) const {
;     ...
;                     if (rl < 2 || rl >= 254) { float* hp = halo + ((size_t)u.pm * 4 + (rl < 2 ? rl : rl - 252)) * FF2; *(f32x4*)(hp + colg) = cg_; *(f32x4*)(hp + colv) = cv_; }
.LBB0_1116:
	v_cmp_gt_i32_e32 vcc, 2, v188
	v_mov_b64_e32 v[26:27], s[92:93]
	s_movk_i32 s3, 0x5800
	v_cndmask_b32_e32 v24, v141, v188, vcc
	v_ashrrev_i32_e32 v25, 31, v24
	v_lshl_add_u64 v[24:25], s[14:15], 0, v[24:25]
	v_mad_u64_u32 v[26:27], s[20:21], v24, s3, v[26:27]
	v_mad_i32_i24 v27, v25, s3, v27
	v_lshl_add_u64 v[24:25], v[182:183], 2, v[26:27]
	global_store_dwordx4 v[24:25], v[12:15], off offset:16
	v_add_co_u32_e32 v24, vcc, 0x2000, v24
	s_nop 1
	v_addc_co_u32_e32 v25, vcc, 0, v25, vcc
	global_store_dwordx4 v[24:25], v[8:11], off offset:3088
	s_or_b64 exec, exec, s[18:19]
	s_and_saveexec_b64 s[18:19], s[62:63]
	s_cbranch_execnz .LBB0_1093
	s_branch .LBB0_1094

;     __device__ __forceinline__ void operator()(AccT& acc, const Unit& u, int wr, int wc, int fr, int fq) const {
;     ...
;                     if (rl < 2 || rl >= 254) { float* hp = halo + ((size_t)u.pm * 4 + (rl < 2 ? rl : rl - 252)) * FF2; *(f32x4*)(hp + colg) = cg_; *(f32x4*)(hp + colv) = cv_; }
.LBB0_1118:
	v_cmp_gt_i32_e32 vcc, 2, v186
	v_mov_b64_e32 v[10:11], s[92:93]
	s_movk_i32 s3, 0x5800
	v_cndmask_b32_e32 v8, v134, v186, vcc
	v_ashrrev_i32_e32 v9, 31, v8
	v_lshl_add_u64 v[8:9], s[14:15], 0, v[8:9]
	v_mad_u64_u32 v[10:11], s[20:21], v8, s3, v[10:11]
	v_mad_i32_i24 v11, v9, s3, v11
	v_lshl_add_u64 v[8:9], v[182:183], 2, v[10:11]
	global_store_dwordx4 v[8:9], v[4:7], off offset:16
	v_add_co_u32_e32 v8, vcc, 0x2000, v8
	s_nop 1
	v_addc_co_u32_e32 v9, vcc, 0, v9, vcc
	global_store_dwordx4 v[8:9], v[0:3], off offset:3088
	s_or_b64 exec, exec, s[18:19]
	s_and_saveexec_b64 s[18:19], s[58:59]
	s_cbranch_execnz .LBB0_1097
	s_branch .LBB0_1098

;     __device__ __forceinline__ void operator()(AccT& acc, const Unit& u, int wr, int wc, int fr, int fq) const {
;     ...
;                     if (rl < 2 || rl >= 254) { float* hp = halo + ((size_t)u.pm * 4 + (rl < 2 ? rl : rl - 252)) * FF2; *(f32x4*)(hp + colg) = cg_; *(f32x4*)(hp + colv) = cv_; }
.LBB0_1120:
	v_cmp_gt_i32_e32 vcc, 2, v184
	v_mov_b64_e32 v[2:3], s[92:93]
	s_movk_i32 s3, 0x5800
	v_cndmask_b32_e32 v0, v132, v184, vcc
	v_ashrrev_i32_e32 v1, 31, v0
	v_lshl_add_u64 v[0:1], s[14:15], 0, v[0:1]
	v_mad_u64_u32 v[2:3], s[14:15], v0, s3, v[2:3]
	v_mad_i32_i24 v3, v1, s3, v3
	v_lshl_add_u64 v[0:1], v[182:183], 2, v[2:3]
	global_store_dwordx4 v[0:1], v[16:19], off offset:16
	v_add_co_u32_e32 v0, vcc, 0x2000, v0
	s_nop 1
	v_addc_co_u32_e32 v1, vcc, 0, v1, vcc
	global_store_dwordx4 v[0:1], v[20:23], off offset:3088
	s_or_b64 exec, exec, s[16:17]
	s_and_saveexec_b64 s[14:15], s[54:55]
	s_cbranch_execnz .LBB0_1101
	s_branch .LBB0_1102

; __device__ __forceinline__ unsigned cvt_pk_bf16(float lo, float hi) { unsigned r; asm volatile("v_cvt_pk_bf16_f32 %0, %1, %2" : "=v"(r) : "v"(lo), "v"(hi)); return r; }
; __device__ __forceinline__ void conv_fixup2(const Params& p, int l, int pmA, int pmB) {
;     ...
;         for (int w2 = 0; w2 < 2; ++w2) { const int pm = w2 ? pmB : pmA; const bool first = (pm & 63) == 0;
;         const f32x4 z = (f32x4){0.f, 0.f, 0.f, 0.f};
;         const float* hp = halo + (size_t)(pm - 1) * 4 * FF2; const float* hc_ = halo + (size_t)pm * 4 * FF2;
;         const f32x4 a2g = first ? z : *(const f32x4*)(hp + 2 * FF2 + cg), a2v = first ? z : *(const f32x4*)(hp + 2 * FF2 + cv);
;         const f32x4 a1g = first ? z : *(const f32x4*)(hp + 3 * FF2 + cg), a1v = first ? z : *(const f32x4*)(hp + 3 * FF2 + cv);
;         const f32x4 r0g = *(const f32x4*)(hc_ + cg), r0v = *(const f32x4*)(hc_ + cv), r1g = *(const f32x4*)(hc_ + FF2 + cg), r1v = *(const f32x4*)(hc_ + FF2 + cv);
;         const f32x4 w0g = *(const f32x4*)(cw + cg), w1g = *(const f32x4*)(cw + FF2 + cg), w2g = *(const f32x4*)(cw + 2 * FF2 + cg), bg = *(const f32x4*)(cb + cg);
;         const f32x4 w0v = *(const f32x4*)(cw + cv), w1v = *(const f32x4*)(cw + FF2 + cv), w2v = *(const f32x4*)(cw + 2 * FF2 + cv), bv = *(const f32x4*)(cb + cv);
; #pragma unroll
;         for (int r = 0; r < 2; ++r) {
;             const f32x4 hcg = bg + w0g * (r == 0 ? a2g : a1g) + w1g * (r == 0 ? a1g : r0g) + w2g * (r == 0 ? r0g : r1g);
;             const f32x4 hcv = bv + w0v * (r == 0 ? a2v : a1v) + w1v * (r == 0 ? a1v : r0v) + w2v * (r == 0 ? r0v : r1v);
;             const f32x2 ga = gelu_pk((f32x2){hcg[0], hcg[1]}), gb2 = gelu_pk((f32x2){hcg[2], hcg[3]});
;             u32x2 w; w.x = cvt_pk_bf16(ga.x * hcv[0], ga.y * hcv[1]); w.y = cvt_pk_bf16(gb2.x * hcv[2], gb2.y * hcv[3]);
;             *(u32x2*)(U + (size_t)(pm * 256 + r) * FF + cg) = w;
;         }
.LBB0_1180:
	global_load_dwordx4 v[34:37], v[80:81], off
	global_load_dwordx4 v[38:41], v[78:79], off
	s_mov_b64 s[0:1], 0x2c00
	v_lshl_add_u64 v[12:13], s[46:47], 0, v[72:73]
	v_lshl_add_u64 v[4:5], v[80:81], 0, s[0:1]
	v_lshl_add_u64 v[6:7], v[76:77], 0, s[0:1]
	v_lshl_add_u64 v[10:11], v[78:79], 0, s[0:1]
	global_load_dwordx4 v[42:45], v[76:77], off
	global_load_dwordx4 v[46:49], v[4:5], off
	global_load_dwordx4 v[50:53], v[10:11], off
	global_load_dwordx4 v[54:57], v[12:13], off
	v_add_co_u32_e32 v12, vcc, 0x2000, v12
	global_load_dwordx4 v[58:61], v[74:75], off
	v_lshl_add_u64 v[8:9], v[74:75], 0, s[0:1]
	v_addc_co_u32_e32 v13, vcc, 0, v13, vcc
	global_load_dwordx4 v[4:7], v[6:7], off
	v_lshl_add_u64 v[16:17], s[52:53], 0, v[72:73]
	global_load_dwordx4 v[62:65], v[16:17], off
	s_nop 0
	global_load_dwordx4 v[8:11], v[8:9], off
	s_nop 0
	global_load_dwordx4 v[12:15], v[12:13], off offset:3072
	v_add_co_u32_e32 v16, vcc, 0x2000, v16
	s_mov_b32 s0, 0xbf3a00e3
	s_nop 0
	v_addc_co_u32_e32 v17, vcc, 0, v17, vcc
	global_load_dwordx4 v[16:19], v[16:17], off offset:3072
	v_mov_b64_e32 v[32:33], s[0:1]
	v_lshl_add_u64 v[70:71], v[68:69], 0, s[54:55]
	v_add_u32_e32 v82, 0x200, v82
	s_movk_i32 s0, 0xbf
	v_add_u32_e32 v66, 0x800, v66
	s_waitcnt vmcnt(0) lgkmcnt(0)
	v_pk_fma_f32 v[20:21], v[20:21], v[34:35], v[38:39]
	v_pk_fma_f32 v[22:23], v[22:23], v[36:37], v[40:41]
	v_pk_fma_f32 v[36:37], v[30:31], v[36:37], v[40:41]
	v_pk_fma_f32 v[20:21], v[28:29], v[42:43], v[20:21]
	v_pk_fma_f32 v[34:35], v[28:29], v[34:35], v[38:39]
	v_pk_fma_f32 v[22:23], v[30:31], v[44:45], v[22:23]
	v_pk_fma_f32 v[2:3], v[2:3], v[48:49], v[52:53]
	v_pk_fma_f32 v[0:1], v[0:1], v[46:47], v[50:51]
	v_pk_fma_f32 v[28:29], v[56:57], v[44:45], v[36:37]
	v_pk_fma_f32 v[20:21], v[54:55], v[58:59], v[20:21]
	v_pk_fma_f32 v[30:31], v[54:55], v[42:43], v[34:35]
	v_pk_fma_f32 v[34:35], v[26:27], v[48:49], v[52:53]
	v_pk_fma_f32 v[36:37], v[24:25], v[46:47], v[50:51]
	v_pk_fma_f32 v[22:23], v[56:57], v[60:61], v[22:23]
	v_pk_fma_f32 v[2:3], v[26:27], v[6:7], v[2:3]
	v_pk_fma_f32 v[0:1], v[24:25], v[4:5], v[0:1]
	v_pk_fma_f32 v[24:25], v[64:65], v[60:61], v[28:29]
	v_and_b32_e32 v29, 0x7fffffff, v21
	v_and_b32_e32 v28, 0x7fffffff, v20
	v_pk_fma_f32 v[2:3], v[14:15], v[10:11], v[2:3]
	v_and_b32_e32 v41, 0x7fffffff, v23
	v_and_b32_e32 v40, 0x7fffffff, v22
	v_pk_fma_f32 v[6:7], v[14:15], v[6:7], v[34:35]
	v_pk_fma_f32 v[14:15], v[28:29], s[6:7], 1.0 op_sel_hi:[1,0,0]
	v_pk_fma_f32 v[34:35], v[40:41], s[6:7], 1.0 op_sel_hi:[1,0,0]
	v_rcp_f32_e32 v14, v14
	v_rcp_f32_e32 v15, v15
	v_rcp_f32_e32 v34, v34
	v_rcp_f32_e32 v35, v35
	v_pk_mul_f32 v[38:39], v[20:21], v[20:21]
	v_pk_fma_f32 v[26:27], v[62:63], v[58:59], v[30:31]
	v_pk_mul_f32 v[30:31], v[22:23], v[22:23]
	v_pk_mul_f32 v[28:29], v[38:39], s[36:37] op_sel_hi:[1,0]
	v_pk_fma_f32 v[38:39], v[14:15], s[24:25], v[32:33] op_sel_hi:[1,0,0]
	v_pk_mul_f32 v[30:31], v[30:31], s[36:37] op_sel_hi:[1,0]
	v_exp_f32_e32 v28, v28
	v_exp_f32_e32 v29, v29
	v_pk_fma_f32 v[40:41], v[34:35], s[24:25], v[32:33] op_sel_hi:[1,0,0]
	v_pk_fma_f32 v[38:39], v[14:15], v[38:39], s[28:29] op_sel_hi:[1,1,0]
	v_exp_f32_e32 v30, v30
	v_exp_f32_e32 v31, v31
	v_pk_fma_f32 v[40:41], v[34:35], v[40:41], s[28:29] op_sel_hi:[1,1,0]
	v_pk_fma_f32 v[38:39], v[14:15], v[38:39], s[30:31] op_sel_hi:[1,1,0]
	v_pk_fma_f32 v[40:41], v[34:35], v[40:41], s[30:31] op_sel_hi:[1,1,0]
	v_pk_fma_f32 v[38:39], v[14:15], v[38:39], s[34:35] op_sel_hi:[1,1,0]
	v_pk_fma_f32 v[40:41], v[34:35], v[40:41], s[34:35] op_sel_hi:[1,1,0]
	v_pk_mul_f32 v[14:15], v[14:15], v[38:39]
	v_pk_mul_f32 v[34:35], v[34:35], v[40:41]
	v_pk_mul_f32 v[14:15], v[28:29], v[14:15]
	v_pk_mul_f32 v[28:29], v[30:31], v[34:35]
	v_pk_mul_f32 v[30:31], v[20:21], v[14:15]
	v_pk_fma_f32 v[14:15], v[20:21], v[14:15], v[20:21] neg_lo:[1,0,0] neg_hi:[1,0,0]
	v_cmp_gt_f32_e32 vcc, 0, v20
	v_pk_mul_f32 v[34:35], v[22:23], v[28:29]
	v_pk_fma_f32 v[28:29], v[22:23], v[28:29], v[22:23] neg_lo:[1,0,0] neg_hi:[1,0,0]
	v_cndmask_b32_e32 v14, v14, v30, vcc
	v_cmp_gt_f32_e32 vcc, 0, v21
	v_pk_fma_f32 v[0:1], v[12:13], v[8:9], v[0:1]
	s_nop 0
	v_cndmask_b32_e32 v15, v15, v31, vcc
	v_cmp_gt_f32_e32 vcc, 0, v22
	v_mul_f32_e32 v0, v0, v14
	v_mul_f32_e32 v1, v1, v15
	v_cndmask_b32_e32 v20, v28, v34, vcc
	v_cmp_gt_f32_e32 vcc, 0, v23
	v_mul_f32_e32 v2, v2, v20
	v_cvt_pk_bf16_f32 v0, v0, v1
	s_nop 0
	v_cndmask_b32_e32 v21, v29, v35, vcc
	v_mul_f32_e32 v3, v3, v21
	v_cvt_pk_bf16_f32 v1, v2, v3
	global_store_dwordx2 v[70:71], v[0:1], off
	v_and_b32_e32 v1, 0x7fffffff, v27
	v_and_b32_e32 v0, 0x7fffffff, v26
	v_pk_fma_f32 v[0:1], v[0:1], s[6:7], 1.0 op_sel_hi:[1,0,0]
	v_pk_fma_f32 v[2:3], v[12:13], v[4:5], v[36:37]
	v_rcp_f32_e32 v0, v0
	v_rcp_f32_e32 v1, v1
	v_pk_fma_f32 v[2:3], v[16:17], v[8:9], v[2:3]
	v_pk_mul_f32 v[8:9], v[26:27], v[26:27]
	v_pk_fma_f32 v[4:5], v[18:19], v[10:11], v[6:7]
	v_pk_fma_f32 v[6:7], v[0:1], s[24:25], v[32:33] op_sel_hi:[1,0,0]
	v_pk_mul_f32 v[8:9], v[8:9], s[36:37] op_sel_hi:[1,0]
	v_pk_fma_f32 v[6:7], v[0:1], v[6:7], s[28:29] op_sel_hi:[1,1,0]
	v_exp_f32_e32 v8, v8
	v_exp_f32_e32 v9, v9
	v_pk_fma_f32 v[6:7], v[0:1], v[6:7], s[30:31] op_sel_hi:[1,1,0]
	v_and_b32_e32 v11, 0x7fffffff, v25
	v_and_b32_e32 v10, 0x7fffffff, v24
	v_pk_fma_f32 v[6:7], v[0:1], v[6:7], s[34:35] op_sel_hi:[1,1,0]
	v_pk_fma_f32 v[10:11], v[10:11], s[6:7], 1.0 op_sel_hi:[1,0,0]
	v_pk_mul_f32 v[0:1], v[0:1], v[6:7]
	v_rcp_f32_e32 v10, v10
	v_rcp_f32_e32 v11, v11
	v_pk_mul_f32 v[0:1], v[8:9], v[0:1]
	v_cmp_gt_f32_e32 vcc, 0, v26
	v_pk_mul_f32 v[8:9], v[26:27], v[0:1]
	v_pk_fma_f32 v[0:1], v[26:27], v[0:1], v[26:27] neg_lo:[1,0,0] neg_hi:[1,0,0]
	v_pk_mul_f32 v[6:7], v[24:25], v[24:25]
	v_cndmask_b32_e32 v8, v0, v8, vcc
	v_cmp_gt_f32_e32 vcc, 0, v27
	v_pk_mul_f32 v[6:7], v[6:7], s[36:37] op_sel_hi:[1,0]
	s_nop 0
	v_cndmask_b32_e32 v9, v1, v9, vcc
	v_pk_fma_f32 v[0:1], v[10:11], s[24:25], v[32:33] op_sel_hi:[1,0,0]
	v_exp_f32_e32 v6, v6
	v_pk_fma_f32 v[0:1], v[10:11], v[0:1], s[28:29] op_sel_hi:[1,1,0]
	v_exp_f32_e32 v7, v7
	v_pk_fma_f32 v[0:1], v[10:11], v[0:1], s[30:31] op_sel_hi:[1,1,0]
	v_cmp_gt_f32_e32 vcc, 0, v24
	v_pk_fma_f32 v[0:1], v[10:11], v[0:1], s[34:35] op_sel_hi:[1,1,0]
	s_nop 0
	v_pk_mul_f32 v[0:1], v[10:11], v[0:1]
	s_nop 0
	v_pk_mul_f32 v[0:1], v[6:7], v[0:1]
	s_nop 0
	v_pk_mul_f32 v[6:7], v[24:25], v[0:1]
	v_pk_fma_f32 v[0:1], v[24:25], v[0:1], v[24:25] neg_lo:[1,0,0] neg_hi:[1,0,0]
	s_nop 0
	v_cndmask_b32_e32 v6, v0, v6, vcc
	v_cmp_gt_f32_e32 vcc, 0, v25
	v_mul_f32_e32 v0, v2, v8
	v_mul_f32_e32 v2, v3, v9
	v_cndmask_b32_e32 v1, v1, v7, vcc
	v_cvt_pk_bf16_f32 v0, v0, v2
	v_mul_f32_e32 v2, v4, v6
	v_mul_f32_e32 v1, v5, v1
	v_cmp_lt_i32_e32 vcc, s0, v82
	v_cvt_pk_bf16_f32 v1, v2, v1
	v_lshl_add_u64 v[2:3], v[68:69], 0, s[56:57]
	s_or_b64 s[58:59], vcc, s[58:59]
	global_store_dwordx2 v[2:3], v[0:1], off
	s_andn2_b64 exec, exec, s[58:59]
	s_cbranch_execz .LBB0_1197
; __device__ __forceinline__ void conv_fixup2(const Params& p, int l, int pmA, int pmB) {
;     ...
;         for (int w2 = 0; w2 < 2; ++w2) { const int pm = w2 ? pmB : pmA; const bool first = (pm & 63) == 0;
;         const f32x4 z = (f32x4){0.f, 0.f, 0.f, 0.f};
;         const float* hp = halo + (size_t)(pm - 1) * 4 * FF2; const float* hc_ = halo + (size_t)pm * 4 * FF2;
;         const f32x4 a2g = first ? z : *(const f32x4*)(hp + 2 * FF2 + cg), a2v = first ? z : *(const f32x4*)(hp + 2 * FF2 + cv);
;         const f32x4 a1g = first ? z : *(const f32x4*)(hp + 3 * FF2 + cg), a1v = first ? z : *(const f32x4*)(hp + 3 * FF2 + cv);
;         const f32x4 r0g = *(const f32x4*)(hc_ + cg), r0v = *(const f32x4*)(hc_ + cv), r1g = *(const f32x4*)(hc_ + FF2 + cg), r1v = *(const f32x4*)(hc_ + FF2 + cv);
;         const f32x4 w0g = *(const f32x4*)(cw + cg), w1g = *(const f32x4*)(cw + FF2 + cg), w2g = *(const f32x4*)(cw + 2 * FF2 + cg), bg = *(const f32x4*)(cb + cg);
;         const f32x4 w0v = *(const f32x4*)(cw + cv), w1v = *(const f32x4*)(cw + FF2 + cv), w2v = *(const f32x4*)(cw + 2 * FF2 + cv), bv = *(const f32x4*)(cb + cv);
.LBB0_1181:
	v_cndmask_b32_e64 v0, 0, 1, s[8:9]
	v_ashrrev_i32_e32 v67, 31, v66
	v_mov_b32_e32 v58, 0
	v_cmp_ne_u32_e64 s[0:1], 1, v0
	s_andn2_b64 vcc, exec, s[8:9]
	v_mov_b32_e32 v62, 0
	v_mov_b32_e32 v63, 0
	v_mov_b32_e32 v64, 0
	v_mov_b32_e32 v65, 0
	s_cbranch_vccnz .LBB0_1183
	v_lshl_add_u64 v[0:1], v[66:67], 2, s[12:13]
	global_load_dwordx4 v[62:65], v[0:1], off
.LBB0_1183:
	v_add_u32_e32 v70, 0xb00, v66
	v_ashrrev_i32_e32 v71, 31, v70
	s_and_b64 vcc, exec, s[0:1]
	v_mov_b32_e32 v59, 0
	v_mov_b32_e32 v60, 0
	v_mov_b32_e32 v61, 0
	s_cbranch_vccnz .LBB0_1185
	v_lshl_add_u64 v[0:1], v[70:71], 2, s[12:13]
	global_load_dwordx4 v[58:61], v[0:1], off
.LBB0_1185:
	v_mov_b32_e32 v2, 0
	s_and_b64 vcc, exec, s[0:1]
	v_mov_b32_e32 v6, 0
	v_mov_b32_e32 v7, 0
	v_mov_b32_e32 v8, 0
	v_mov_b32_e32 v9, 0
	s_cbranch_vccnz .LBB0_1187
	v_lshl_add_u64 v[0:1], v[66:67], 2, s[14:15]
	global_load_dwordx4 v[6:9], v[0:1], off
.LBB0_1187:
	s_and_b64 vcc, exec, s[0:1]
	v_mov_b32_e32 v3, 0
	v_mov_b32_e32 v4, 0
	v_mov_b32_e32 v5, 0
	s_cbranch_vccnz .LBB0_1189
	v_lshl_add_u64 v[0:1], v[70:71], 2, s[14:15]
	global_load_dwordx4 v[2:5], v[0:1], off
.LBB0_1189:
	v_lshlrev_b64 v[72:73], 2, v[66:67]
	v_lshl_add_u64 v[0:1], s[10:11], 0, v[72:73]
	global_load_dwordx4 v[10:13], v[0:1], off
	v_add_co_u32_e32 v0, vcc, 0x2000, v0
	v_lshl_add_u64 v[80:81], s[40:41], 0, v[72:73]
	s_nop 0
	v_addc_co_u32_e32 v1, vcc, 0, v1, vcc
	global_load_dwordx4 v[14:17], v[0:1], off offset:3072
	v_lshl_add_u64 v[0:1], s[16:17], 0, v[72:73]
	global_load_dwordx4 v[22:25], v[0:1], off
	v_add_co_u32_e32 v0, vcc, 0x2000, v0
	v_lshl_add_u64 v[76:77], s[42:43], 0, v[72:73]
	s_nop 0
	v_addc_co_u32_e32 v1, vcc, 0, v1, vcc
	v_lshl_add_u64 v[74:75], s[94:95], 0, v[72:73]
	v_lshl_add_u64 v[78:79], s[44:45], 0, v[72:73]
	global_load_dwordx4 v[18:21], v[0:1], off offset:3072
	global_load_dwordx4 v[34:37], v[80:81], off
	global_load_dwordx4 v[30:33], v[76:77], off
	global_load_dwordx4 v[26:29], v[74:75], off
	global_load_dwordx4 v[38:41], v[78:79], off
	v_add_co_u32_e32 v0, vcc, 0x2000, v80
	s_mov_b32 s0, 0xbf3a00e3
	s_nop 0
	v_addc_co_u32_e32 v1, vcc, 0, v81, vcc
	global_load_dwordx4 v[42:45], v[0:1], off offset:3072
	v_add_co_u32_e32 v0, vcc, 0x2000, v76
	v_lshl_add_u64 v[68:69], v[66:67], 1, s[84:85]
	s_nop 0
	v_addc_co_u32_e32 v1, vcc, 0, v77, vcc
	global_load_dwordx4 v[46:49], v[0:1], off offset:3072
	v_add_co_u32_e32 v0, vcc, 0x2000, v74
	s_waitcnt vmcnt(0) lgkmcnt(0)
	v_pk_fma_f32 v[62:63], v[62:63], v[34:35], v[38:39]
	v_addc_co_u32_e32 v1, vcc, 0, v75, vcc
	global_load_dwordx4 v[50:53], v[0:1], off offset:3072
	v_add_co_u32_e32 v0, vcc, 0x2000, v78
	s_nop 1
	v_addc_co_u32_e32 v1, vcc, 0, v79, vcc
	global_load_dwordx4 v[54:57], v[0:1], off offset:3072
	v_pk_fma_f32 v[0:1], v[64:65], v[36:37], v[40:41]
	v_pk_fma_f32 v[64:65], v[6:7], v[30:31], v[62:63]
	v_pk_fma_f32 v[0:1], v[8:9], v[32:33], v[0:1]
	v_pk_fma_f32 v[84:85], v[10:11], v[26:27], v[64:65]
	v_pk_fma_f32 v[62:63], v[12:13], v[28:29], v[0:1]
	v_mov_b64_e32 v[64:65], s[0:1]
	v_pk_mul_f32 v[88:89], v[84:85], v[84:85]
	v_cmp_gt_f32_e32 vcc, 0, v84
	v_pk_mul_f32 v[88:89], v[88:89], s[36:37] op_sel_hi:[1,0]
	v_pk_fma_f32 v[6:7], v[6:7], v[34:35], v[38:39]
	v_exp_f32_e32 v88, v88
	v_exp_f32_e32 v89, v89
	v_pk_fma_f32 v[6:7], v[10:11], v[30:31], v[6:7]
	v_pk_fma_f32 v[8:9], v[8:9], v[36:37], v[40:41]
	v_pk_fma_f32 v[6:7], v[22:23], v[26:27], v[6:7]
	v_pk_fma_f32 v[8:9], v[12:13], v[32:33], v[8:9]
	v_and_b32_e32 v11, 0x7fffffff, v7
	v_and_b32_e32 v10, 0x7fffffff, v6
	v_pk_fma_f32 v[10:11], v[10:11], s[6:7], 1.0 op_sel_hi:[1,0,0]
	v_pk_fma_f32 v[8:9], v[24:25], v[28:29], v[8:9]
	v_rcp_f32_e32 v10, v10
	v_rcp_f32_e32 v11, v11
	v_mov_b32_e32 v22, 0
	v_mov_b32_e32 v23, 0
	v_pk_fma_f32 v[12:13], v[10:11], s[24:25], v[64:65] op_sel_hi:[1,0,0]
	s_nop 0
	v_pk_fma_f32 v[12:13], v[10:11], v[12:13], s[28:29] op_sel_hi:[1,1,0]
	s_waitcnt vmcnt(0)
; __device__ __forceinline__ unsigned cvt_pk_bf16(float lo, float hi) { unsigned r; asm volatile("v_cvt_pk_bf16_f32 %0, %1, %2" : "=v"(r) : "v"(lo), "v"(hi)); return r; }
; __device__ __forceinline__ void conv_fixup2(const Params& p, int l, int pmA, int pmB) {
;     ...
;         const f32x4 a2g = first ? z : *(const f32x4*)(hp + 2 * FF2 + cg), a2v = first ? z : *(const f32x4*)(hp + 2 * FF2 + cv);
;         const f32x4 a1g = first ? z : *(const f32x4*)(hp + 3 * FF2 + cg), a1v = first ? z : *(const f32x4*)(hp + 3 * FF2 + cv);
;     ...
; #pragma unroll
;         for (int r = 0; r < 2; ++r) {
;             const f32x4 hcg = bg + w0g * (r == 0 ? a2g : a1g) + w1g * (r == 0 ? a1g : r0g) + w2g * (r == 0 ? r0g : r1g);
;             const f32x4 hcv = bv + w0v * (r == 0 ? a2v : a1v) + w1v * (r == 0 ? a1v : r0v) + w2v * (r == 0 ? r0v : r1v);
;             const f32x2 ga = gelu_pk((f32x2){hcg[0], hcg[1]}), gb2 = gelu_pk((f32x2){hcg[2], hcg[3]});
;             u32x2 w; w.x = cvt_pk_bf16(ga.x * hcv[0], ga.y * hcv[1]); w.y = cvt_pk_bf16(gb2.x * hcv[2], gb2.y * hcv[3]);
;             *(u32x2*)(U + (size_t)(pm * 256 + r) * FF + cg) = w;
;         }
	v_pk_fma_f32 v[0:1], v[60:61], v[44:45], v[56:57]
	v_pk_fma_f32 v[58:59], v[58:59], v[42:43], v[54:55]
	v_pk_fma_f32 v[0:1], v[4:5], v[48:49], v[0:1]
	v_pk_fma_f32 v[60:61], v[2:3], v[46:47], v[58:59]
	v_pk_fma_f32 v[58:59], v[16:17], v[52:53], v[0:1]
	v_and_b32_e32 v1, 0x7fffffff, v85
	v_and_b32_e32 v0, 0x7fffffff, v84
	v_pk_fma_f32 v[0:1], v[0:1], s[6:7], 1.0 op_sel_hi:[1,0,0]
	v_pk_fma_f32 v[2:3], v[2:3], v[42:43], v[54:55]
	v_rcp_f32_e32 v0, v0
	v_rcp_f32_e32 v1, v1
	v_pk_fma_f32 v[60:61], v[14:15], v[50:51], v[60:61]
	v_pk_fma_f32 v[2:3], v[14:15], v[46:47], v[2:3]
	v_pk_mul_f32 v[14:15], v[6:7], v[6:7]
	v_pk_fma_f32 v[86:87], v[0:1], s[24:25], v[64:65] op_sel_hi:[1,0,0]
	v_pk_mul_f32 v[14:15], v[14:15], s[36:37] op_sel_hi:[1,0]
	v_pk_fma_f32 v[86:87], v[0:1], v[86:87], s[28:29] op_sel_hi:[1,1,0]
	v_exp_f32_e32 v14, v14
	v_pk_fma_f32 v[86:87], v[0:1], v[86:87], s[30:31] op_sel_hi:[1,1,0]
	v_exp_f32_e32 v15, v15
	v_pk_fma_f32 v[86:87], v[0:1], v[86:87], s[34:35] op_sel_hi:[1,1,0]
	v_pk_fma_f32 v[12:13], v[10:11], v[12:13], s[30:31] op_sel_hi:[1,1,0]
	v_pk_mul_f32 v[0:1], v[0:1], v[86:87]
	v_pk_mul_f32 v[86:87], v[62:63], v[62:63]
	v_pk_mul_f32 v[0:1], v[88:89], v[0:1]
	v_pk_mul_f32 v[86:87], v[86:87], s[36:37] op_sel_hi:[1,0]
	v_pk_mul_f32 v[88:89], v[84:85], v[0:1]
	v_pk_fma_f32 v[90:91], v[84:85], v[0:1], v[84:85] neg_lo:[1,0,0] neg_hi:[1,0,0]
	v_and_b32_e32 v84, 0x7fffffff, v62
	v_cndmask_b32_e32 v1, v90, v88, vcc
	v_cmp_gt_f32_e32 vcc, 0, v85
	v_and_b32_e32 v85, 0x7fffffff, v63
	v_pk_fma_f32 v[84:85], v[84:85], s[6:7], 1.0 op_sel_hi:[1,0,0]
	v_cndmask_b32_e32 v83, v91, v89, vcc
	v_rcp_f32_e32 v84, v84
	v_rcp_f32_e32 v85, v85
	v_exp_f32_e32 v86, v86
	v_exp_f32_e32 v87, v87
	v_pk_fma_f32 v[12:13], v[10:11], v[12:13], s[34:35] op_sel_hi:[1,1,0]
	v_pk_fma_f32 v[88:89], v[84:85], s[24:25], v[64:65] op_sel_hi:[1,0,0]
	v_cmp_gt_f32_e32 vcc, 0, v62
	v_pk_fma_f32 v[88:89], v[84:85], v[88:89], s[28:29] op_sel_hi:[1,1,0]
	v_pk_mul_f32 v[10:11], v[10:11], v[12:13]
	v_pk_fma_f32 v[88:89], v[84:85], v[88:89], s[30:31] op_sel_hi:[1,1,0]
	v_mul_f32_e32 v1, v60, v1
	v_pk_fma_f32 v[88:89], v[84:85], v[88:89], s[34:35] op_sel_hi:[1,1,0]
	v_mul_f32_e32 v60, v61, v83
	v_pk_mul_f32 v[84:85], v[84:85], v[88:89]
	v_pk_mul_f32 v[10:11], v[14:15], v[10:11]
	v_pk_mul_f32 v[84:85], v[86:87], v[84:85]
	v_cvt_pk_bf16_f32 v60, v1, v60
	v_pk_mul_f32 v[14:15], v[6:7], v[10:11]
	v_pk_mul_f32 v[86:87], v[62:63], v[84:85]
	v_pk_fma_f32 v[84:85], v[62:63], v[84:85], v[62:63] neg_lo:[1,0,0] neg_hi:[1,0,0]
	v_pk_fma_f32 v[10:11], v[6:7], v[10:11], v[6:7] neg_lo:[1,0,0] neg_hi:[1,0,0]
	v_cndmask_b32_e32 v62, v84, v86, vcc
	v_cmp_gt_f32_e32 vcc, 0, v63
	v_mul_f32_e32 v1, v58, v62
	v_pk_mul_f32 v[12:13], v[8:9], v[8:9]
	v_cndmask_b32_e32 v63, v85, v87, vcc
	v_cmp_gt_f32_e32 vcc, 0, v6
	v_mul_f32_e32 v58, v59, v63
	v_cvt_pk_bf16_f32 v61, v1, v58
	v_and_b32_e32 v6, 0x7fffffff, v8
	v_cndmask_b32_e32 v1, v10, v14, vcc
	v_cmp_gt_f32_e32 vcc, 0, v7
	v_and_b32_e32 v7, 0x7fffffff, v9
	v_pk_fma_f32 v[6:7], v[6:7], s[6:7], 1.0 op_sel_hi:[1,0,0]
	v_cndmask_b32_e32 v14, v11, v15, vcc
	v_rcp_f32_e32 v6, v6
	v_rcp_f32_e32 v7, v7
	v_pk_fma_f32 v[4:5], v[4:5], v[44:45], v[56:57]
	v_cmp_gt_f32_e32 vcc, 0, v8
	v_pk_fma_f32 v[4:5], v[16:17], v[48:49], v[4:5]
	v_pk_fma_f32 v[10:11], v[6:7], s[24:25], v[64:65] op_sel_hi:[1,0,0]
	v_pk_fma_f32 v[2:3], v[18:19], v[50:51], v[2:3]
	v_pk_fma_f32 v[10:11], v[6:7], v[10:11], s[28:29] op_sel_hi:[1,1,0]
	v_lshl_add_u64 v[58:59], v[68:69], 0, s[18:19]
	v_pk_fma_f32 v[10:11], v[6:7], v[10:11], s[30:31] op_sel_hi:[1,1,0]
	v_pk_fma_f32 v[4:5], v[20:21], v[52:53], v[4:5]
	v_pk_fma_f32 v[10:11], v[6:7], v[10:11], s[34:35] op_sel_hi:[1,1,0]
	v_mul_f32_e32 v1, v2, v1
	v_pk_mul_f32 v[6:7], v[6:7], v[10:11]
	v_pk_mul_f32 v[10:11], v[12:13], s[36:37] op_sel_hi:[1,0]
	v_mul_f32_e32 v2, v3, v14
	v_exp_f32_e32 v10, v10
	v_exp_f32_e32 v11, v11
	global_store_dwordx2 v[58:59], v[60:61], off
	v_cvt_pk_bf16_f32 v2, v1, v2
	v_mov_b32_e32 v0, 0
	v_pk_mul_f32 v[6:7], v[10:11], v[6:7]
	v_mov_b32_e32 v20, 0
	v_pk_mul_f32 v[10:11], v[8:9], v[6:7]
	v_pk_fma_f32 v[6:7], v[8:9], v[6:7], v[8:9] neg_lo:[1,0,0] neg_hi:[1,0,0]
	v_mov_b32_e32 v21, 0
	v_cndmask_b32_e32 v6, v6, v10, vcc
	v_cmp_gt_f32_e32 vcc, 0, v9
	v_mul_f32_e32 v1, v4, v6
	s_nop 0
	v_cndmask_b32_e32 v7, v7, v11, vcc
	v_mul_f32_e32 v3, v5, v7
	v_cvt_pk_bf16_f32 v3, v1, v3
	v_cndmask_b32_e64 v1, 0, 1, s[22:23]
	v_lshl_add_u64 v[4:5], v[68:69], 0, s[20:21]
	v_cmp_ne_u32_e64 s[0:1], 1, v1
	s_andn2_b64 vcc, exec, s[22:23]
	global_store_dwordx2 v[4:5], v[2:3], off
	s_cbranch_vccnz .LBB0_1191
	v_lshl_add_u64 v[2:3], v[66:67], 2, s[48:49]
	global_load_dwordx4 v[20:23], v[2:3], off
.LBB0_1191:
	s_and_b64 vcc, exec, s[0:1]
	v_mov_b32_e32 v1, 0
	v_mov_b32_e32 v2, 0
	v_mov_b32_e32 v3, 0
	s_cbranch_vccnz .LBB0_1193
	v_lshl_add_u64 v[0:1], v[70:71], 2, s[48:49]
	global_load_dwordx4 v[0:3], v[0:1], off
.LBB0_1193:
	v_mov_b32_e32 v24, 0
	s_and_b64 vcc, exec, s[0:1]
	v_mov_b32_e32 v28, 0
	v_mov_b32_e32 v29, 0
	v_mov_b32_e32 v30, 0
	v_mov_b32_e32 v31, 0
	s_cbranch_vccnz .LBB0_1195
	v_lshl_add_u64 v[4:5], v[66:67], 2, s[50:51]
	global_load_dwordx4 v[28:31], v[4:5], off
.LBB0_1195:
	s_and_b64 vcc, exec, s[0:1]
	v_mov_b32_e32 v25, 0
	v_mov_b32_e32 v26, 0
	v_mov_b32_e32 v27, 0
	s_cbranch_vccnz .LBB0_1180
	v_lshl_add_u64 v[4:5], v[70:71], 2, s[50:51]
	global_load_dwordx4 v[24:27], v[4:5], off
	s_branch .LBB0_1180

; __device__ __forceinline__ void conv_fixup(const Params& p, int l, int pm) {
;     ...
;         const f32x4 r0g = *(const f32x4*)(hc_ + cg), r0v = *(const f32x4*)(hc_ + cv), r1g = *(const f32x4*)(hc_ + FF2 + cg), r1v = *(const f32x4*)(hc_ + FF2 + cv);
;         const f32x4 w0g = *(const f32x4*)(cw + cg), w1g = *(const f32x4*)(cw + FF2 + cg), w2g = *(const f32x4*)(cw + 2 * FF2 + cg), bg = *(const f32x4*)(cb + cg);
;         const f32x4 w0v = *(const f32x4*)(cw + cv), w1v = *(const f32x4*)(cw + FF2 + cv), w2v = *(const f32x4*)(cw + 2 * FF2 + cv), bv = *(const f32x4*)(cb + cv);
.LBB0_1210:
	v_lshlrev_b64 v[36:37], 2, v[64:65]
	v_lshl_add_u64 v[12:13], s[10:11], 0, v[36:37]
	v_lshl_add_u64 v[20:21], s[16:17], 0, v[36:37]
	global_load_dwordx4 v[8:11], v[12:13], off
	global_load_dwordx4 v[16:19], v[20:21], off
	v_add_co_u32_e32 v12, vcc, 0x2000, v12
	v_lshl_add_u64 v[40:41], s[40:41], 0, v[36:37]
	s_nop 0
	v_addc_co_u32_e32 v13, vcc, 0, v13, vcc
	v_add_co_u32_e32 v20, vcc, 0x2000, v20
	v_lshl_add_u64 v[44:45], s[42:43], 0, v[36:37]
	s_nop 0
	v_addc_co_u32_e32 v21, vcc, 0, v21, vcc
	global_load_dwordx4 v[24:27], v[40:41], off
	global_load_dwordx4 v[32:35], v[44:45], off
	v_add_co_u32_e32 v40, vcc, 0x2000, v40
	v_lshl_add_u64 v[48:49], s[94:95], 0, v[36:37]
	s_nop 0
	v_addc_co_u32_e32 v41, vcc, 0, v41, vcc
	v_add_co_u32_e32 v44, vcc, 0x2000, v44
	global_load_dwordx4 v[28:31], v[48:49], off
	s_nop 0
	v_addc_co_u32_e32 v45, vcc, 0, v45, vcc
	v_add_co_u32_e32 v48, vcc, 0x2000, v48
	v_lshl_add_u64 v[52:53], s[44:45], 0, v[36:37]
	s_nop 0
	v_addc_co_u32_e32 v49, vcc, 0, v49, vcc
	global_load_dwordx4 v[36:39], v[52:53], off
	v_add_co_u32_e32 v52, vcc, 0x2000, v52
	global_load_dwordx4 v[40:43], v[40:41], off offset:3072
	s_nop 0
	v_addc_co_u32_e32 v53, vcc, 0, v53, vcc
	global_load_dwordx4 v[52:55], v[52:53], off offset:3072
	s_mov_b32 s0, 0xbf3a00e3
	global_load_dwordx4 v[44:47], v[44:45], off offset:3072
	v_lshl_add_u64 v[66:67], v[64:65], 1, s[84:85]
	global_load_dwordx4 v[12:15], v[12:13], off offset:3072
	v_add_u32_e32 v68, 0x200, v68
	global_load_dwordx4 v[48:51], v[48:49], off offset:3072
	v_add_u32_e32 v64, 0x800, v64
	global_load_dwordx4 v[20:23], v[20:21], off offset:3072
	s_waitcnt vmcnt(0) lgkmcnt(0)
; __device__ __forceinline__ unsigned cvt_pk_bf16(float lo, float hi) { unsigned r; asm volatile("v_cvt_pk_bf16_f32 %0, %1, %2" : "=v"(r) : "v"(lo), "v"(hi)); return r; }
; __device__ __forceinline__ void conv_fixup(const Params& p, int l, int pm) {
;     ...
;         const float* hp = halo + (size_t)(pm - 1) * 4 * FF2; const float* hc_ = halo + (size_t)pm * 4 * FF2;
;         const f32x4 a2g = first ? z : *(const f32x4*)(hp + 2 * FF2 + cg), a2v = first ? z : *(const f32x4*)(hp + 2 * FF2 + cv);
;         const f32x4 a1g = first ? z : *(const f32x4*)(hp + 3 * FF2 + cg), a1v = first ? z : *(const f32x4*)(hp + 3 * FF2 + cv);
;     ...
;         for (int r = 0; r < 2; ++r) {
;             const f32x4 hcg = bg + w0g * (r == 0 ? a2g : a1g) + w1g * (r == 0 ? a1g : r0g) + w2g * (r == 0 ? r0g : r1g);
;             const f32x4 hcv = bv + w0v * (r == 0 ? a2v : a1v) + w1v * (r == 0 ? a1v : r0v) + w2v * (r == 0 ? r0v : r1v);
;             const f32x2 ga = gelu_pk((f32x2){hcg[0], hcg[1]}), gb2 = gelu_pk((f32x2){hcg[2], hcg[3]});
;             u32x2 w; w.x = cvt_pk_bf16(ga.x * hcv[0], ga.y * hcv[1]); w.y = cvt_pk_bf16(gb2.x * hcv[2], gb2.y * hcv[3]);
;             *(u32x2*)(U + (size_t)(pm * 256 + r) * FF + cg) = w;
;         }
	v_pk_fma_f32 v[60:61], v[60:61], v[24:25], v[36:37]
	s_nop 0
	v_pk_fma_f32 v[70:71], v[4:5], v[32:33], v[60:61]
	v_pk_fma_f32 v[62:63], v[62:63], v[26:27], v[38:39]
	v_pk_fma_f32 v[70:71], v[8:9], v[28:29], v[70:71]
	v_pk_fma_f32 v[60:61], v[6:7], v[34:35], v[62:63]
	v_pk_mul_f32 v[76:77], v[70:71], v[70:71]
	v_pk_fma_f32 v[56:57], v[56:57], v[40:41], v[52:53]
	v_pk_mul_f32 v[76:77], v[76:77], s[36:37] op_sel_hi:[1,0]
	v_pk_fma_f32 v[56:57], v[0:1], v[44:45], v[56:57]
	v_exp_f32_e32 v76, v76
	v_exp_f32_e32 v77, v77
	v_pk_fma_f32 v[60:61], v[10:11], v[30:31], v[60:61]
	v_pk_fma_f32 v[62:63], v[12:13], v[48:49], v[56:57]
	v_and_b32_e32 v57, 0x7fffffff, v71
	v_and_b32_e32 v56, 0x7fffffff, v70
	v_pk_fma_f32 v[56:57], v[56:57], s[6:7], 1.0 op_sel_hi:[1,0,0]
	v_cmp_gt_f32_e32 vcc, 0, v70
	v_rcp_f32_e32 v72, v56
	v_rcp_f32_e32 v73, v57
	v_mov_b64_e32 v[56:57], s[0:1]
	v_pk_fma_f32 v[4:5], v[4:5], v[24:25], v[36:37]
	v_pk_fma_f32 v[0:1], v[0:1], v[40:41], v[52:53]
	v_pk_fma_f32 v[74:75], v[72:73], s[24:25], v[56:57] op_sel_hi:[1,0,0]
	v_pk_fma_f32 v[4:5], v[8:9], v[32:33], v[4:5]
	v_pk_fma_f32 v[74:75], v[72:73], v[74:75], s[28:29] op_sel_hi:[1,1,0]
	v_pk_fma_f32 v[4:5], v[16:17], v[28:29], v[4:5]
	v_pk_fma_f32 v[74:75], v[72:73], v[74:75], s[30:31] op_sel_hi:[1,1,0]
	v_and_b32_e32 v9, 0x7fffffff, v5
	v_pk_fma_f32 v[74:75], v[72:73], v[74:75], s[34:35] op_sel_hi:[1,1,0]
	v_and_b32_e32 v8, 0x7fffffff, v4
	v_pk_mul_f32 v[72:73], v[72:73], v[74:75]
	v_pk_fma_f32 v[8:9], v[8:9], s[6:7], 1.0 op_sel_hi:[1,0,0]
	v_pk_mul_f32 v[72:73], v[76:77], v[72:73]
	v_rcp_f32_e32 v8, v8
	v_pk_mul_f32 v[76:77], v[70:71], v[72:73]
	v_pk_fma_f32 v[72:73], v[70:71], v[72:73], v[70:71] neg_lo:[1,0,0] neg_hi:[1,0,0]
	v_and_b32_e32 v70, 0x7fffffff, v60
	v_cndmask_b32_e32 v65, v72, v76, vcc
	v_cmp_gt_f32_e32 vcc, 0, v71
	v_and_b32_e32 v71, 0x7fffffff, v61
	v_pk_fma_f32 v[70:71], v[70:71], s[6:7], 1.0 op_sel_hi:[1,0,0]
	v_cndmask_b32_e32 v69, v73, v77, vcc
	v_rcp_f32_e32 v70, v70
	v_rcp_f32_e32 v71, v71
	v_rcp_f32_e32 v9, v9
	v_pk_mul_f32 v[74:75], v[60:61], v[60:61]
	v_pk_fma_f32 v[6:7], v[6:7], v[26:27], v[38:39]
	v_pk_fma_f32 v[72:73], v[70:71], s[24:25], v[56:57] op_sel_hi:[1,0,0]
	v_pk_fma_f32 v[0:1], v[12:13], v[44:45], v[0:1]
	v_pk_fma_f32 v[72:73], v[70:71], v[72:73], s[28:29] op_sel_hi:[1,1,0]
	v_pk_mul_f32 v[12:13], v[4:5], v[4:5]
	v_pk_fma_f32 v[72:73], v[70:71], v[72:73], s[30:31] op_sel_hi:[1,1,0]
	v_pk_fma_f32 v[6:7], v[10:11], v[34:35], v[6:7]
	v_pk_fma_f32 v[72:73], v[70:71], v[72:73], s[34:35] op_sel_hi:[1,1,0]
	v_pk_fma_f32 v[10:11], v[8:9], s[24:25], v[56:57] op_sel_hi:[1,0,0]
	v_pk_mul_f32 v[70:71], v[70:71], v[72:73]
	v_pk_mul_f32 v[72:73], v[74:75], s[36:37] op_sel_hi:[1,0]
	v_pk_mul_f32 v[12:13], v[12:13], s[36:37] op_sel_hi:[1,0]
	v_exp_f32_e32 v72, v72
	v_exp_f32_e32 v73, v73
	v_pk_fma_f32 v[10:11], v[8:9], v[10:11], s[28:29] op_sel_hi:[1,1,0]
	v_exp_f32_e32 v12, v12
	v_exp_f32_e32 v13, v13
	v_pk_fma_f32 v[10:11], v[8:9], v[10:11], s[30:31] op_sel_hi:[1,1,0]
	v_pk_mul_f32 v[70:71], v[72:73], v[70:71]
	v_pk_fma_f32 v[10:11], v[8:9], v[10:11], s[34:35] op_sel_hi:[1,1,0]
	v_pk_mul_f32 v[72:73], v[60:61], v[70:71]
	v_pk_fma_f32 v[70:71], v[60:61], v[70:71], v[60:61] neg_lo:[1,0,0] neg_hi:[1,0,0]
	v_cmp_gt_f32_e32 vcc, 0, v60
	v_pk_mul_f32 v[8:9], v[8:9], v[10:11]
	v_pk_fma_f32 v[6:7], v[18:19], v[30:31], v[6:7]
	v_cndmask_b32_e32 v70, v70, v72, vcc
	v_cmp_gt_f32_e32 vcc, 0, v61
	v_pk_mul_f32 v[8:9], v[12:13], v[8:9]
	v_pk_mul_f32 v[10:11], v[6:7], v[6:7]
	v_cndmask_b32_e32 v61, v71, v73, vcc
	v_pk_mul_f32 v[12:13], v[4:5], v[8:9]
	v_pk_fma_f32 v[8:9], v[4:5], v[8:9], v[4:5] neg_lo:[1,0,0] neg_hi:[1,0,0]
	v_cmp_gt_f32_e32 vcc, 0, v4
	v_and_b32_e32 v4, 0x7fffffff, v6
	v_pk_fma_f32 v[58:59], v[58:59], v[42:43], v[54:55]
	v_cndmask_b32_e32 v12, v8, v12, vcc
	v_cmp_gt_f32_e32 vcc, 0, v5
	v_and_b32_e32 v5, 0x7fffffff, v7
	v_pk_fma_f32 v[4:5], v[4:5], s[6:7], 1.0 op_sel_hi:[1,0,0]
	v_cndmask_b32_e32 v13, v9, v13, vcc
	v_rcp_f32_e32 v4, v4
	v_rcp_f32_e32 v5, v5
	v_pk_fma_f32 v[58:59], v[2:3], v[46:47], v[58:59]
	v_pk_fma_f32 v[2:3], v[2:3], v[42:43], v[54:55]
	v_pk_fma_f32 v[58:59], v[14:15], v[50:51], v[58:59]
	v_pk_fma_f32 v[8:9], v[4:5], s[24:25], v[56:57] op_sel_hi:[1,0,0]
	v_cmp_gt_f32_e32 vcc, 0, v6
	v_pk_fma_f32 v[8:9], v[4:5], v[8:9], s[28:29] op_sel_hi:[1,1,0]
	v_mul_f32_e32 v60, v62, v65
	v_pk_fma_f32 v[8:9], v[4:5], v[8:9], s[30:31] op_sel_hi:[1,1,0]
	v_mul_f32_e32 v58, v58, v70
	v_pk_fma_f32 v[8:9], v[4:5], v[8:9], s[34:35] op_sel_hi:[1,1,0]
	v_mul_f32_e32 v59, v59, v61
	v_pk_mul_f32 v[4:5], v[4:5], v[8:9]
	v_pk_mul_f32 v[8:9], v[10:11], s[36:37] op_sel_hi:[1,0]
	v_pk_fma_f32 v[2:3], v[14:15], v[46:47], v[2:3]
	v_exp_f32_e32 v8, v8
	v_exp_f32_e32 v9, v9
	v_pk_fma_f32 v[0:1], v[20:21], v[48:49], v[0:1]
	v_mul_f32_e32 v62, v63, v69
	v_cvt_pk_bf16_f32 v60, v60, v62
	v_pk_mul_f32 v[4:5], v[8:9], v[4:5]
	v_cvt_pk_bf16_f32 v61, v58, v59
	v_lshl_add_u64 v[58:59], v[66:67], 0, s[18:19]
	v_pk_mul_f32 v[8:9], v[6:7], v[4:5]
	v_pk_fma_f32 v[4:5], v[6:7], v[4:5], v[6:7] neg_lo:[1,0,0] neg_hi:[1,0,0]
	v_pk_fma_f32 v[2:3], v[22:23], v[50:51], v[2:3]
	v_cndmask_b32_e32 v4, v4, v8, vcc
	v_cmp_gt_f32_e32 vcc, 0, v7
	v_mul_f32_e32 v0, v0, v12
	v_mul_f32_e32 v1, v1, v13
	v_cndmask_b32_e32 v5, v5, v9, vcc
	global_store_dwordx2 v[58:59], v[60:61], off
	v_cvt_pk_bf16_f32 v0, v0, v1
	v_mul_f32_e32 v1, v2, v4
	v_mul_f32_e32 v2, v3, v5
	v_cmp_lt_i32_e32 vcc, s25, v68
	v_cvt_pk_bf16_f32 v1, v1, v2
	v_lshl_add_u64 v[2:3], v[66:67], 0, s[20:21]
	s_or_b64 s[22:23], vcc, s[22:23]
	global_store_dwordx2 v[2:3], v[0:1], off
	s_andn2_b64 exec, exec, s[22:23]
	s_cbranch_execz .LBB0_1199
.LBB0_1211:
	v_cndmask_b32_e64 v0, 0, 1, s[8:9]
	v_mov_b32_e32 v56, 0
	v_cmp_ne_u32_e64 s[0:1], 1, v0
	s_andn2_b64 vcc, exec, s[8:9]
	v_ashrrev_i32_e32 v65, 31, v64
	v_mov_b32_e32 v60, 0
	v_mov_b32_e32 v61, 0
	v_mov_b32_e32 v62, 0
	v_mov_b32_e32 v63, 0
	s_cbranch_vccnz .LBB0_1213
	v_lshl_add_u64 v[0:1], v[64:65], 2, s[12:13]
	global_load_dwordx4 v[60:63], v[0:1], off
.LBB0_1213:
	v_add_u32_e32 v8, 0xb00, v64
	s_and_b64 vcc, exec, s[0:1]
	v_ashrrev_i32_e32 v9, 31, v8
	v_mov_b32_e32 v57, 0
	v_mov_b32_e32 v58, 0
	v_mov_b32_e32 v59, 0
	s_cbranch_vccnz .LBB0_1215
	v_lshl_add_u64 v[0:1], v[8:9], 2, s[12:13]
	global_load_dwordx4 v[56:59], v[0:1], off
.LBB0_1215:
	v_mov_b32_e32 v0, 0
	s_and_b64 vcc, exec, s[0:1]
	v_mov_b32_e32 v4, 0
	v_mov_b32_e32 v5, 0
	v_mov_b32_e32 v6, 0
	v_mov_b32_e32 v7, 0
	s_cbranch_vccnz .LBB0_1217
	v_lshl_add_u64 v[2:3], v[64:65], 2, s[14:15]
	global_load_dwordx4 v[4:7], v[2:3], off
.LBB0_1217:
	s_and_b64 vcc, exec, s[0:1]
	v_mov_b32_e32 v1, 0
	v_mov_b32_e32 v2, 0
	v_mov_b32_e32 v3, 0
	s_cbranch_vccnz .LBB0_1210
	v_lshl_add_u64 v[0:1], v[8:9], 2, s[14:15]
	global_load_dwordx4 v[0:3], v[0:1], off
	s_branch .LBB0_1210

; #define LAS __attribute__((address_space(3)))
; template <int KSTEPS  >
; __device__ __forceinline__ void small_mma_ksplit(f32x4 (&acc)[2], const bf16_t* A, int lda, const bf16_t* Bt, int ldb, int n0, LAS unsigned char* lds, const SmallId& id) {
;     ...
;     for (int ks = 0; ks < KSTEPS; ++ks) {
;         bf16x8 a[8], b[2];
; #pragma unroll
;         for (int rb = 0; rb < 8; ++rb) a[rb] = *(const bf16x8*)(ap + (size_t)(16 * rb) * lda + 32 * ks);
;         b[0] = *(const bf16x8*)(bp + 32 * ks); b[1] = *(const bf16x8*)(bp + (size_t)16 * ldb + 32 * ks);
; #pragma unroll
;         for (int rb = 0; rb < 8; ++rb) { part[rb][0] = __builtin_amdgcn_mfma_f32_16x16x32_bf16(b[0], a[rb], part[rb][0], 0, 0, 0); part[rb][1] = __builtin_amdgcn_mfma_f32_16x16x32_bf16(b[1], a[rb], part[rb][1], 0, 0, 0); }
;     }
;     LAS f32x4* red = (LAS f32x4*)lds;
; #pragma unroll
;     for (int rb = 0; rb < 8; ++rb) { red[((id.w * 8 + rb) * 2 + 0) * 64 + lane] = part[rb][0]; red[((id.w * 8 + rb) * 2 + 1) * 64 + lane] = part[rb][1]; }
;     asm volatile("s_waitcnt lgkmcnt(0)" ::: "memory"); __syncthreads();
;     acc[0] = (f32x4){0.f, 0.f, 0.f, 0.f}; acc[1] = acc[0];
; #pragma unroll
;     for (int w2 = 0; w2 < 8; ++w2) { acc[0] += red[((w2 * 8 + id.w) * 2 + 0) * 64 + lane]; acc[1] += red[((w2 * 8 + id.w) * 2 + 1) * 64 + lane]; }
;     asm volatile("s_waitcnt lgkmcnt(0)" ::: "memory"); __syncthreads();
; }
; template <bool RES_F32, bool OUT_F32, int KSTEPS>
; __device__ __forceinline__ void small_res(const Params& p, LAS unsigned char* lds, const bf16_t* A, int lda, const bf16_t* Bt, int K, float* ssq_next, int G, int bx) {
;     ...
;         for (int nb = 0; nb < 2; ++nb) { const int col = n0 + 16 * nb + 4 * id.fq;
;             f32x4 r;
;             if (RES_F32) r = *(const f32x4*)(p.xs + (size_t)(id.row - MP) * DM + col);
;             else { const u32x2 w = *(const u32x2*)(XB + (size_t)id.row * DM + col); r = (f32x4){bf_lo(w.x), bf_hi(w.x), bf_lo(w.y), bf_hi(w.y)}; }
;             const f32x4 x = r + acc[nb];
;             if (OUT_F32) *(f32x4*)(p.out + (size_t)id.row * DM + col) = x;
;             else { u32x2 w; w.x = cvt_pk_bf16(x[0], x[1]); w.y = cvt_pk_bf16(x[2], x[3]); *(u32x2*)(XB + (size_t)id.row * DM + col) = w; }
;             s += (x[0] * x[0] + x[1] * x[1]) + (x[2] * x[2] + x[3] * x[3]); }
.LBB0_1223:
	v_lshl_add_u64 v[94:95], v[70:71], 0, s[0:1]
	v_add_co_u32_e32 v90, vcc, s52, v94
	v_lshl_add_u64 v[86:87], v[72:73], 0, s[0:1]
	s_nop 1
	v_addc_co_u32_e32 v91, vcc, 0, v95, vcc
	v_add_co_u32_e32 v102, vcc, s53, v94
	s_add_u32 s0, s0, 64
	s_nop 1
	v_addc_co_u32_e32 v103, vcc, 0, v95, vcc
	v_add_co_u32_e32 v88, vcc, s62, v86
	s_addc_u32 s1, s1, 0
	s_nop 1
	v_addc_co_u32_e32 v89, vcc, 0, v87, vcc
	v_add_co_u32_e32 v98, vcc, s63, v86
	s_cmpk_lg_i32 s0, 0x2c0
	s_nop 1
	v_addc_co_u32_e32 v99, vcc, 0, v87, vcc
	global_load_dwordx4 v[86:89], v[88:89], off
	global_load_dwordx4 v[90:93], v[90:91], off
	global_load_dwordx4 v[98:101], v[98:99], off
	global_load_dwordx4 v[102:105], v[102:103], off
	v_add_co_u32_e32 v106, vcc, s56, v94
	s_nop 1
	v_addc_co_u32_e32 v107, vcc, 0, v95, vcc
	v_add_co_u32_e32 v108, vcc, s57, v94
	s_nop 1
	v_addc_co_u32_e32 v109, vcc, 0, v95, vcc
	global_load_dwordx4 v[180:183], v[106:107], off
	global_load_dwordx4 v[184:187], v[108:109], off
	v_add_co_u32_e32 v106, vcc, s58, v94
	s_nop 1
	v_addc_co_u32_e32 v107, vcc, 0, v95, vcc
	v_add_co_u32_e32 v108, vcc, s59, v94
	s_nop 1
	v_addc_co_u32_e32 v109, vcc, 0, v95, vcc
	global_load_dwordx4 v[188:191], v[106:107], off
	global_load_dwordx4 v[206:209], v[108:109], off
	v_add_co_u32_e32 v106, vcc, s60, v94
	s_nop 1
	v_addc_co_u32_e32 v107, vcc, 0, v95, vcc
	v_add_co_u32_e32 v94, vcc, s61, v94
	s_nop 1
	v_addc_co_u32_e32 v95, vcc, 0, v95, vcc
	global_load_dwordx4 v[210:213], v[106:107], off
	global_load_dwordx4 v[214:217], v[94:95], off
	s_waitcnt vmcnt(0) lgkmcnt(0)
	v_mfma_f32_16x16x32_bf16 v[36:39], v[86:89], v[90:93], v[36:39]
	v_mfma_f32_16x16x32_bf16 v[24:27], v[98:101], v[90:93], v[24:27]
	v_mfma_f32_16x16x32_bf16 v[20:23], v[86:89], v[102:105], v[20:23]
	v_mfma_f32_16x16x32_bf16 v[16:19], v[98:101], v[102:105], v[16:19]
	v_mfma_f32_16x16x32_bf16 v[12:15], v[86:89], v[180:183], v[12:15]
	v_mfma_f32_16x16x32_bf16 v[8:11], v[98:101], v[180:183], v[8:11]
	v_mfma_f32_16x16x32_bf16 v[4:7], v[86:89], v[184:187], v[4:7]
	v_mfma_f32_16x16x32_bf16 v[0:3], v[98:101], v[184:187], v[0:3]
	v_mfma_f32_16x16x32_bf16 v[28:31], v[86:89], v[188:191], v[28:31]
	v_mfma_f32_16x16x32_bf16 v[32:35], v[98:101], v[188:191], v[32:35]
	v_mfma_f32_16x16x32_bf16 v[40:43], v[86:89], v[206:209], v[40:43]
	v_mfma_f32_16x16x32_bf16 v[44:47], v[98:101], v[206:209], v[44:47]
	v_mfma_f32_16x16x32_bf16 v[48:51], v[86:89], v[210:213], v[48:51]
	v_mfma_f32_16x16x32_bf16 v[52:55], v[98:101], v[210:213], v[52:55]
	v_mfma_f32_16x16x32_bf16 v[56:59], v[86:89], v[214:217], v[56:59]
	v_mfma_f32_16x16x32_bf16 v[60:63], v[98:101], v[214:217], v[60:63]
	s_cbranch_scc1 .LBB0_1223
	ds_write_b128 v74, v[36:39]
	ds_write_b128 v74, v[24:27] offset:1024
	ds_write_b128 v74, v[20:23] offset:2048
	ds_write_b128 v74, v[16:19] offset:3072
	ds_write_b128 v74, v[12:15] offset:4096
	ds_write_b128 v74, v[8:11] offset:5120
	ds_write_b128 v74, v[4:7] offset:6144
	ds_write_b128 v74, v[0:3] offset:7168
	ds_write_b128 v74, v[28:31] offset:8192
	ds_write_b128 v74, v[32:35] offset:9216
	ds_write_b128 v74, v[40:43] offset:10240
	ds_write_b128 v74, v[44:47] offset:11264
	ds_write_b128 v74, v[48:51] offset:12288
	ds_write_b128 v74, v[52:55] offset:13312
	ds_write_b128 v74, v[56:59] offset:14336
	ds_write_b128 v74, v[60:63] offset:15360
	s_waitcnt lgkmcnt(0)
	s_waitcnt lgkmcnt(0)
	s_barrier
	ds_read_b128 v[0:3], v75
	v_lshl_or_b32 v12, s2, 5, v84
	v_ashrrev_i32_e32 v13, 31, v12
	v_lshl_add_u64 v[14:15], v[12:13], 1, v[64:65]
	s_add_i32 s2, s2, s92
	s_waitcnt lgkmcnt(0)
	v_pk_add_f32 v[4:5], v[2:3], 0 op_sel_hi:[1,0]
	v_pk_add_f32 v[6:7], v[0:1], 0 op_sel_hi:[1,0]
	ds_read_b128 v[0:3], v75 offset:1024
	v_add_u32_e32 v85, s37, v85
	s_cmp_lt_i32 s2, 32
	s_waitcnt lgkmcnt(0)
	v_pk_add_f32 v[8:9], v[2:3], 0 op_sel_hi:[1,0]
	v_pk_add_f32 v[10:11], v[0:1], 0 op_sel_hi:[1,0]
	ds_read_b128 v[0:3], v75 offset:16384
	s_waitcnt lgkmcnt(0)
	v_pk_add_f32 v[4:5], v[4:5], v[2:3]
	v_pk_add_f32 v[6:7], v[6:7], v[0:1]
	ds_read_b128 v[0:3], v75 offset:17408
	s_waitcnt lgkmcnt(0)
	v_pk_add_f32 v[8:9], v[8:9], v[2:3]
	v_pk_add_f32 v[10:11], v[10:11], v[0:1]
	ds_read_b128 v[0:3], v75 offset:32768
	s_waitcnt lgkmcnt(0)
	v_pk_add_f32 v[4:5], v[4:5], v[2:3]
	v_pk_add_f32 v[6:7], v[6:7], v[0:1]
	ds_read_b128 v[0:3], v75 offset:33792
	s_waitcnt lgkmcnt(0)
	v_pk_add_f32 v[8:9], v[8:9], v[2:3]
	v_pk_add_f32 v[10:11], v[10:11], v[0:1]
	ds_read_b128 v[0:3], v75 offset:49152
	s_waitcnt lgkmcnt(0)
	v_pk_add_f32 v[4:5], v[4:5], v[2:3]
	v_pk_add_f32 v[6:7], v[6:7], v[0:1]
	ds_read_b128 v[0:3], v75 offset:50176
	s_waitcnt lgkmcnt(0)
	v_pk_add_f32 v[8:9], v[8:9], v[2:3]
	v_pk_add_f32 v[10:11], v[10:11], v[0:1]
	ds_read_b128 v[0:3], v76
	s_waitcnt lgkmcnt(0)
	v_pk_add_f32 v[4:5], v[4:5], v[2:3]
	v_pk_add_f32 v[6:7], v[6:7], v[0:1]
	ds_read_b128 v[0:3], v77
	s_waitcnt lgkmcnt(0)
	v_pk_add_f32 v[8:9], v[8:9], v[2:3]
	v_pk_add_f32 v[10:11], v[10:11], v[0:1]
	ds_read_b128 v[0:3], v78
	s_waitcnt lgkmcnt(0)
	v_pk_add_f32 v[4:5], v[4:5], v[2:3]
	v_pk_add_f32 v[6:7], v[6:7], v[0:1]
	ds_read_b128 v[0:3], v79
	s_waitcnt lgkmcnt(0)
	v_pk_add_f32 v[8:9], v[8:9], v[2:3]
	v_pk_add_f32 v[10:11], v[10:11], v[0:1]
	ds_read_b128 v[0:3], v80
	s_waitcnt lgkmcnt(0)
	v_pk_add_f32 v[4:5], v[4:5], v[2:3]
	v_pk_add_f32 v[6:7], v[6:7], v[0:1]
	ds_read_b128 v[0:3], v81
	s_waitcnt lgkmcnt(0)
	v_pk_add_f32 v[8:9], v[8:9], v[2:3]
	v_pk_add_f32 v[10:11], v[10:11], v[0:1]
	ds_read_b128 v[0:3], v82
	s_waitcnt lgkmcnt(0)
	v_pk_add_f32 v[4:5], v[4:5], v[2:3]
	v_pk_add_f32 v[6:7], v[6:7], v[0:1]
	ds_read_b128 v[0:3], v83
	s_waitcnt lgkmcnt(0)
	s_waitcnt lgkmcnt(0)
	s_barrier
	v_pk_add_f32 v[10:11], v[10:11], v[0:1]
	global_load_dwordx2 v[0:1], v[14:15], off
	v_pk_add_f32 v[8:9], v[8:9], v[2:3]
	s_waitcnt vmcnt(0) lgkmcnt(0)
	v_lshlrev_b32_e32 v2, 16, v0
	v_and_b32_e32 v3, 0xffff0000, v0
	v_lshlrev_b32_e32 v16, 16, v1
	v_and_b32_e32 v17, 0xffff0000, v1
	v_pk_add_f32 v[0:1], v[6:7], v[2:3]
	v_pk_add_f32 v[2:3], v[4:5], v[16:17]
	v_lshl_add_u64 v[4:5], v[12:13], 2, v[66:67]
	global_store_dwordx4 v[4:5], v[0:3], off
	global_load_dwordx2 v[0:1], v[14:15], off offset:32
	s_waitcnt vmcnt(0) lgkmcnt(0)
	v_lshlrev_b32_e32 v6, 16, v0
	v_and_b32_e32 v7, 0xffff0000, v0
	v_lshlrev_b32_e32 v0, 16, v1
	v_and_b32_e32 v1, 0xffff0000, v1
	v_pk_add_f32 v[2:3], v[8:9], v[0:1]
	v_pk_add_f32 v[0:1], v[10:11], v[6:7]
	global_store_dwordx4 v[4:5], v[0:3], off offset:64
	s_cbranch_scc1 .LBB0_1222

;     __device__ __forceinline__ void finish(const f32x4 x0, const f32x4 x1, int row, int col, float& s) const {
;         if (OUT_F32) { *(f32x4*)(out + (size_t)row * DM + col) = x0; *(f32x4*)(out + (size_t)row * DM + col + 4) = x1; }
;     __device__ __forceinline__ void operator()(AccT& acc, const Unit& u, int wr, int wc, int fr, int fq) const {
;     ...
;             u32x4 rb[2][4][2];
; #pragma unroll
;             for (int ai = 0; ai < 2; ++ai)
; #pragma unroll
;                 for (int m = 0; m < 4; ++m)
; #pragma unroll
;                     for (int bj = 0; bj < 2; ++bj) rb[ai][m][bj] = __builtin_nontemporal_load((const u32x4*)((const char*)XB + (unsigned)(((u.pm * 256 + ai * 128 + wr * 64 + m * 16 + fr) * DM + col0 + bj * 128) * 2)));
; #pragma unroll
;             for (int ai = 0; ai < 2; ++ai)
; #pragma unroll
;                 for (int m = 0; m < 4; ++m) {
;                     const int row = u.pm * 256 + ai * 128 + wr * 64 + m * 16 + fr; float s = 0.f;
; #pragma unroll
;                     for (int bj = 0; bj < 2; ++bj) { const u32x4 w = rb[ai][m][bj];
;                         finish((f32x4){bf_lo(w.x), bf_hi(w.x), bf_lo(w.y), bf_hi(w.y)} + acc[ai][bj][m][0], (f32x4){bf_lo(w.z), bf_hi(w.z), bf_lo(w.w), bf_hi(w.w)} + acc[ai][bj][m][1], row, col0 + bj * 128, s); }
.LBB0_1245:
	s_lshl_b32 s12, s44, 8
	v_mov_b32_e32 v96, v229
	v_mov_b32_e32 v130, v230
	s_or_b32 s12, s12, s31
	s_and_b64 vcc, exec, s[46:47]
	v_lshl_add_u32 v220, v130, 3, s12
	s_lshl_b32 s12, s43, 8
	s_add_i32 s12, s12, s29
	v_add_u32_e32 v218, s12, v96
	v_lshlrev_b32_e32 v96, 11, v218
	v_lshl_add_u32 v96, v220, 1, v96
	v_lshl_add_u64 v[130:131], s[90:91], 0, v[96:97]
	global_load_dwordx4 v[190:193], v[130:131], off nt
	v_add_u32_e32 v130, 0x100, v96
	v_mov_b32_e32 v131, v97
	v_lshl_add_u64 v[130:131], s[90:91], 0, v[130:131]
	global_load_dwordx4 v[186:189], v[130:131], off nt
	v_add_u32_e32 v130, 0x8000, v96
	v_mov_b32_e32 v131, v97
	v_lshl_add_u64 v[130:131], s[90:91], 0, v[130:131]
	global_load_dwordx4 v[182:185], v[130:131], off nt
	v_add_u32_e32 v130, 0x8100, v96
	v_mov_b32_e32 v131, v97
	v_lshl_add_u64 v[130:131], s[90:91], 0, v[130:131]
	global_load_dwordx4 v[178:181], v[130:131], off nt
	v_add_u32_e32 v130, 0x10000, v96
	v_mov_b32_e32 v131, v97
	v_lshl_add_u64 v[130:131], s[90:91], 0, v[130:131]
	global_load_dwordx4 v[174:177], v[130:131], off nt
	v_add_u32_e32 v130, 0x10100, v96
	v_mov_b32_e32 v131, v97
	v_lshl_add_u64 v[130:131], s[90:91], 0, v[130:131]
	global_load_dwordx4 v[170:173], v[130:131], off nt
	v_add_u32_e32 v130, 0x18000, v96
	v_mov_b32_e32 v131, v97
	v_lshl_add_u64 v[130:131], s[90:91], 0, v[130:131]
	global_load_dwordx4 v[166:169], v[130:131], off nt
	v_add_u32_e32 v130, 0x18100, v96
	v_mov_b32_e32 v131, v97
	v_lshl_add_u64 v[130:131], s[90:91], 0, v[130:131]
	global_load_dwordx4 v[162:165], v[130:131], off nt
	v_add_u32_e32 v130, 0x40000, v96
	v_mov_b32_e32 v131, v97
	v_lshl_add_u64 v[130:131], s[90:91], 0, v[130:131]
	global_load_dwordx4 v[158:161], v[130:131], off nt
	v_add_u32_e32 v130, 0x40100, v96
	v_mov_b32_e32 v131, v97
	v_lshl_add_u64 v[130:131], s[90:91], 0, v[130:131]
	global_load_dwordx4 v[154:157], v[130:131], off nt
	v_add_u32_e32 v130, 0x48000, v96
	v_mov_b32_e32 v131, v97
	v_lshl_add_u64 v[130:131], s[90:91], 0, v[130:131]
	global_load_dwordx4 v[150:153], v[130:131], off nt
	v_add_u32_e32 v130, 0x48100, v96
	v_mov_b32_e32 v131, v97
	v_lshl_add_u64 v[130:131], s[90:91], 0, v[130:131]
	global_load_dwordx4 v[146:149], v[130:131], off nt
	v_add_u32_e32 v130, 0x50000, v96
	v_mov_b32_e32 v131, v97
	v_lshl_add_u64 v[130:131], s[90:91], 0, v[130:131]
	global_load_dwordx4 v[142:145], v[130:131], off nt
	v_add_u32_e32 v130, 0x50100, v96
	v_mov_b32_e32 v131, v97
	v_lshl_add_u64 v[130:131], s[90:91], 0, v[130:131]
	global_load_dwordx4 v[138:141], v[130:131], off nt
	v_add_u32_e32 v130, 0x58000, v96
	v_mov_b32_e32 v131, v97
	v_lshl_add_u64 v[130:131], s[90:91], 0, v[130:131]
	global_load_dwordx4 v[134:137], v[130:131], off nt
	v_add_u32_e32 v96, 0x58100, v96
	v_lshl_add_u64 v[130:131], s[90:91], 0, v[96:97]
	global_load_dwordx4 v[130:133], v[130:131], off nt
	v_ashrrev_i32_e32 v219, 31, v218
	v_ashrrev_i32_e32 v221, 31, v220
	s_mov_b64 s[12:13], -1
	s_waitcnt vmcnt(0) lgkmcnt(0)
	v_lshlrev_b32_e32 v234, 16, v190
	v_and_b32_e32 v235, 0xffff0000, v190
	v_lshlrev_b32_e32 v190, 16, v191
	v_and_b32_e32 v191, 0xffff0000, v191
	v_pk_add_f32 v[128:129], v[128:129], v[190:191]
	v_lshlrev_b32_e32 v190, 16, v192
	v_and_b32_e32 v191, 0xffff0000, v192
	v_lshlrev_b32_e32 v192, 16, v193
	v_and_b32_e32 v193, 0xffff0000, v193
	v_pk_add_f32 v[122:123], v[122:123], v[190:191]
	v_lshlrev_b64 v[190:191], 12, v[218:219]
	v_pk_add_f32 v[124:125], v[124:125], v[192:193]
	v_lshl_add_u64 v[192:193], s[64:65], 0, v[190:191]
	v_lshlrev_b64 v[190:191], 2, v[220:221]
	v_pk_add_f32 v[126:127], v[126:127], v[234:235]
	v_lshl_add_u64 v[192:193], v[192:193], 0, v[190:191]
	global_store_dwordx4 v[192:193], v[126:129], off
	global_store_dwordx4 v[192:193], v[122:125], off offset:16
	s_nop 1
	v_lshlrev_b32_e32 v122, 16, v186
	v_and_b32_e32 v123, 0xffff0000, v186
	v_lshlrev_b32_e32 v124, 16, v187
	v_and_b32_e32 v125, 0xffff0000, v187
	v_pk_add_f32 v[118:119], v[118:119], v[122:123]
	v_lshlrev_b32_e32 v122, 16, v188
	v_and_b32_e32 v123, 0xffff0000, v188
	v_pk_add_f32 v[120:121], v[120:121], v[124:125]
	v_lshlrev_b32_e32 v124, 16, v189
	v_and_b32_e32 v125, 0xffff0000, v189
	v_pk_add_f32 v[110:111], v[110:111], v[122:123]
	v_pk_add_f32 v[112:113], v[112:113], v[124:125]
	global_store_dwordx4 v[192:193], v[118:121], off offset:512
	global_store_dwordx4 v[192:193], v[110:113], off offset:528
	s_nop 0
	v_add_u32_e32 v118, 16, v218
	v_lshlrev_b32_e32 v110, 16, v182
	v_and_b32_e32 v111, 0xffff0000, v182
	v_ashrrev_i32_e32 v119, 31, v118
	v_pk_add_f32 v[110:111], v[114:115], v[110:111]
	v_lshlrev_b32_e32 v114, 16, v184
	v_and_b32_e32 v115, 0xffff0000, v184
	v_pk_add_f32 v[106:107], v[106:107], v[114:115]
	v_lshlrev_b64 v[114:115], 12, v[118:119]
	v_lshlrev_b32_e32 v112, 16, v183
	v_and_b32_e32 v113, 0xffff0000, v183
	v_lshl_add_u64 v[114:115], s[64:65], 0, v[114:115]
	v_pk_add_f32 v[112:113], v[116:117], v[112:113]
	v_lshlrev_b32_e32 v116, 16, v185
	v_and_b32_e32 v117, 0xffff0000, v185
	v_lshl_add_u64 v[114:115], v[114:115], 0, v[190:191]
	v_pk_add_f32 v[108:109], v[108:109], v[116:117]
	global_store_dwordx4 v[114:115], v[110:113], off
	global_store_dwordx4 v[114:115], v[106:109], off offset:16
	s_nop 1
	v_lshlrev_b32_e32 v106, 16, v178
	v_and_b32_e32 v107, 0xffff0000, v178
	v_lshlrev_b32_e32 v108, 16, v179
	v_and_b32_e32 v109, 0xffff0000, v179
	v_pk_add_f32 v[102:103], v[102:103], v[106:107]
	v_lshlrev_b32_e32 v106, 16, v180
	v_and_b32_e32 v107, 0xffff0000, v180
	v_pk_add_f32 v[104:105], v[104:105], v[108:109]
	v_lshlrev_b32_e32 v108, 16, v181
	v_and_b32_e32 v109, 0xffff0000, v181
	v_pk_add_f32 v[92:93], v[92:93], v[106:107]
	v_pk_add_f32 v[94:95], v[94:95], v[108:109]
;     __device__ __forceinline__ void finish(const f32x4 x0, const f32x4 x1, int row, int col, float& s) const {
;         if (OUT_F32) { *(f32x4*)(out + (size_t)row * DM + col) = x0; *(f32x4*)(out + (size_t)row * DM + col + 4) = x1; }
;     __device__ __forceinline__ void operator()(AccT& acc, const Unit& u, int wr, int wc, int fr, int fq) const {
;     ...
;             for (int ai = 0; ai < 2; ++ai)
; #pragma unroll
;                 for (int m = 0; m < 4; ++m) {
;                     const int row = u.pm * 256 + ai * 128 + wr * 64 + m * 16 + fr; float s = 0.f;
; #pragma unroll
;                     for (int bj = 0; bj < 2; ++bj) { const u32x4 w = rb[ai][m][bj];
;                         finish((f32x4){bf_lo(w.x), bf_hi(w.x), bf_lo(w.y), bf_hi(w.y)} + acc[ai][bj][m][0], (f32x4){bf_lo(w.z), bf_hi(w.z), bf_lo(w.w), bf_hi(w.w)} + acc[ai][bj][m][1], row, col0 + bj * 128, s); }
	global_store_dwordx4 v[114:115], v[102:105], off offset:512
	global_store_dwordx4 v[114:115], v[92:95], off offset:528
	s_nop 0
	v_add_u32_e32 v102, 32, v218
	v_lshlrev_b32_e32 v92, 16, v174
	v_and_b32_e32 v93, 0xffff0000, v174
	v_ashrrev_i32_e32 v103, 31, v102
	v_pk_add_f32 v[92:93], v[98:99], v[92:93]
	v_lshlrev_b32_e32 v98, 16, v176
	v_and_b32_e32 v99, 0xffff0000, v176
	v_pk_add_f32 v[88:89], v[88:89], v[98:99]
	v_lshlrev_b64 v[98:99], 12, v[102:103]
	v_lshlrev_b32_e32 v94, 16, v175
	v_and_b32_e32 v95, 0xffff0000, v175
	v_lshl_add_u64 v[98:99], s[64:65], 0, v[98:99]
	v_pk_add_f32 v[94:95], v[100:101], v[94:95]
	v_lshlrev_b32_e32 v100, 16, v177
	v_and_b32_e32 v101, 0xffff0000, v177
	v_lshl_add_u64 v[98:99], v[98:99], 0, v[190:191]
	v_pk_add_f32 v[90:91], v[90:91], v[100:101]
	global_store_dwordx4 v[98:99], v[92:95], off
	global_store_dwordx4 v[98:99], v[88:91], off offset:16
	s_nop 1
	v_lshlrev_b32_e32 v88, 16, v170
	v_and_b32_e32 v89, 0xffff0000, v170
	v_lshlrev_b32_e32 v90, 16, v171
	v_and_b32_e32 v91, 0xffff0000, v171
	v_pk_add_f32 v[84:85], v[84:85], v[88:89]
	v_lshlrev_b32_e32 v88, 16, v172
	v_and_b32_e32 v89, 0xffff0000, v172
	v_pk_add_f32 v[86:87], v[86:87], v[90:91]
	v_lshlrev_b32_e32 v90, 16, v173
	v_and_b32_e32 v91, 0xffff0000, v173
	v_pk_add_f32 v[76:77], v[76:77], v[88:89]
	v_pk_add_f32 v[78:79], v[78:79], v[90:91]
	global_store_dwordx4 v[98:99], v[84:87], off offset:512
	global_store_dwordx4 v[98:99], v[76:79], off offset:528
	s_nop 0
	v_add_u32_e32 v84, 48, v218
	v_lshlrev_b32_e32 v76, 16, v166
	v_and_b32_e32 v77, 0xffff0000, v166
	v_ashrrev_i32_e32 v85, 31, v84
	v_pk_add_f32 v[76:77], v[80:81], v[76:77]
	v_lshlrev_b32_e32 v80, 16, v168
	v_and_b32_e32 v81, 0xffff0000, v168
	v_pk_add_f32 v[72:73], v[72:73], v[80:81]
	v_lshlrev_b64 v[80:81], 12, v[84:85]
	v_lshlrev_b32_e32 v78, 16, v167
	v_and_b32_e32 v79, 0xffff0000, v167
	v_lshl_add_u64 v[80:81], s[64:65], 0, v[80:81]
	v_pk_add_f32 v[78:79], v[82:83], v[78:79]
	v_lshlrev_b32_e32 v82, 16, v169
	v_and_b32_e32 v83, 0xffff0000, v169
	v_lshl_add_u64 v[80:81], v[80:81], 0, v[190:191]
	v_pk_add_f32 v[74:75], v[74:75], v[82:83]
	global_store_dwordx4 v[80:81], v[76:79], off
	global_store_dwordx4 v[80:81], v[72:75], off offset:16
	s_nop 1
	v_lshlrev_b32_e32 v72, 16, v162
	v_and_b32_e32 v73, 0xffff0000, v162
	v_lshlrev_b32_e32 v74, 16, v163
	v_and_b32_e32 v75, 0xffff0000, v163
	v_pk_add_f32 v[68:69], v[68:69], v[72:73]
	v_lshlrev_b32_e32 v72, 16, v164
	v_and_b32_e32 v73, 0xffff0000, v164
	v_pk_add_f32 v[70:71], v[70:71], v[74:75]
	v_lshlrev_b32_e32 v74, 16, v165
	v_and_b32_e32 v75, 0xffff0000, v165
	v_pk_add_f32 v[64:65], v[64:65], v[72:73]
	v_pk_add_f32 v[66:67], v[66:67], v[74:75]
	global_store_dwordx4 v[80:81], v[68:71], off offset:512
	global_store_dwordx4 v[80:81], v[64:67], off offset:528
	s_nop 0
	v_lshlrev_b32_e32 v68, 16, v159
	v_add_u32_e32 v64, 0x80, v218
	v_ashrrev_i32_e32 v65, 31, v64
	v_lshlrev_b32_e32 v66, 16, v158
	v_and_b32_e32 v67, 0xffff0000, v158
	v_lshlrev_b64 v[64:65], 12, v[64:65]
	v_and_b32_e32 v69, 0xffff0000, v159
	v_pk_add_f32 v[60:61], v[60:61], v[66:67]
	v_lshlrev_b32_e32 v66, 16, v160
	v_and_b32_e32 v67, 0xffff0000, v160
	v_lshl_add_u64 v[64:65], s[64:65], 0, v[64:65]
	v_pk_add_f32 v[62:63], v[62:63], v[68:69]
	v_lshlrev_b32_e32 v68, 16, v161
	v_and_b32_e32 v69, 0xffff0000, v161
	v_pk_add_f32 v[56:57], v[56:57], v[66:67]
	v_lshl_add_u64 v[64:65], v[64:65], 0, v[190:191]
	v_pk_add_f32 v[58:59], v[58:59], v[68:69]
	global_store_dwordx4 v[64:65], v[60:63], off
	global_store_dwordx4 v[64:65], v[56:59], off offset:16
	s_nop 1
	v_lshlrev_b32_e32 v56, 16, v154
	v_and_b32_e32 v57, 0xffff0000, v154
	v_lshlrev_b32_e32 v58, 16, v155
	v_and_b32_e32 v59, 0xffff0000, v155
	v_pk_add_f32 v[52:53], v[52:53], v[56:57]
	v_lshlrev_b32_e32 v56, 16, v156
	v_and_b32_e32 v57, 0xffff0000, v156
	v_pk_add_f32 v[54:55], v[54:55], v[58:59]
	v_lshlrev_b32_e32 v58, 16, v157
	v_and_b32_e32 v59, 0xffff0000, v157
	v_pk_add_f32 v[44:45], v[44:45], v[56:57]
	v_pk_add_f32 v[46:47], v[46:47], v[58:59]
	global_store_dwordx4 v[64:65], v[52:55], off offset:512
	global_store_dwordx4 v[64:65], v[44:47], off offset:528
;     __device__ __forceinline__ void finish(const f32x4 x0, const f32x4 x1, int row, int col, float& s) const {
;         if (OUT_F32) { *(f32x4*)(out + (size_t)row * DM + col) = x0; *(f32x4*)(out + (size_t)row * DM + col + 4) = x1; }
;     __device__ __forceinline__ void operator()(AccT& acc, const Unit& u, int wr, int wc, int fr, int fq) const {
;     ...
;             for (int ai = 0; ai < 2; ++ai)
; #pragma unroll
;                 for (int m = 0; m < 4; ++m) {
;                     const int row = u.pm * 256 + ai * 128 + wr * 64 + m * 16 + fr; float s = 0.f;
; #pragma unroll
;                     for (int bj = 0; bj < 2; ++bj) { const u32x4 w = rb[ai][m][bj];
;                         finish((f32x4){bf_lo(w.x), bf_hi(w.x), bf_lo(w.y), bf_hi(w.y)} + acc[ai][bj][m][0], (f32x4){bf_lo(w.z), bf_hi(w.z), bf_lo(w.w), bf_hi(w.w)} + acc[ai][bj][m][1], row, col0 + bj * 128, s); }
	s_nop 0
	v_add_u32_e32 v52, 0x90, v218
	v_lshlrev_b32_e32 v44, 16, v150
	v_and_b32_e32 v45, 0xffff0000, v150
	v_ashrrev_i32_e32 v53, 31, v52
	v_pk_add_f32 v[44:45], v[48:49], v[44:45]
	v_lshlrev_b32_e32 v48, 16, v152
	v_and_b32_e32 v49, 0xffff0000, v152
	v_pk_add_f32 v[40:41], v[40:41], v[48:49]
	v_lshlrev_b64 v[48:49], 12, v[52:53]
	v_lshlrev_b32_e32 v46, 16, v151
	v_and_b32_e32 v47, 0xffff0000, v151
	v_lshl_add_u64 v[48:49], s[64:65], 0, v[48:49]
	v_pk_add_f32 v[46:47], v[50:51], v[46:47]
	v_lshlrev_b32_e32 v50, 16, v153
	v_and_b32_e32 v51, 0xffff0000, v153
	v_lshl_add_u64 v[48:49], v[48:49], 0, v[190:191]
	v_pk_add_f32 v[42:43], v[42:43], v[50:51]
	global_store_dwordx4 v[48:49], v[44:47], off
	global_store_dwordx4 v[48:49], v[40:43], off offset:16
	s_nop 1
	v_lshlrev_b32_e32 v40, 16, v146
	v_and_b32_e32 v41, 0xffff0000, v146
	v_lshlrev_b32_e32 v42, 16, v147
	v_and_b32_e32 v43, 0xffff0000, v147
	v_pk_add_f32 v[36:37], v[36:37], v[40:41]
	v_lshlrev_b32_e32 v40, 16, v148
	v_and_b32_e32 v41, 0xffff0000, v148
	v_pk_add_f32 v[38:39], v[38:39], v[42:43]
	v_lshlrev_b32_e32 v42, 16, v149
	v_and_b32_e32 v43, 0xffff0000, v149
	v_pk_add_f32 v[28:29], v[28:29], v[40:41]
	v_pk_add_f32 v[30:31], v[30:31], v[42:43]
	global_store_dwordx4 v[48:49], v[36:39], off offset:512
	global_store_dwordx4 v[48:49], v[28:31], off offset:528
	s_nop 0
	v_add_u32_e32 v36, 0xa0, v218
	v_lshlrev_b32_e32 v28, 16, v142
	v_and_b32_e32 v29, 0xffff0000, v142
	v_ashrrev_i32_e32 v37, 31, v36
	v_pk_add_f32 v[28:29], v[32:33], v[28:29]
	v_lshlrev_b32_e32 v32, 16, v144
	v_and_b32_e32 v33, 0xffff0000, v144
	v_pk_add_f32 v[24:25], v[24:25], v[32:33]
	v_lshlrev_b64 v[32:33], 12, v[36:37]
	v_lshlrev_b32_e32 v30, 16, v143
	v_and_b32_e32 v31, 0xffff0000, v143
	v_lshl_add_u64 v[32:33], s[64:65], 0, v[32:33]
	v_pk_add_f32 v[30:31], v[34:35], v[30:31]
	v_lshlrev_b32_e32 v34, 16, v145
	v_and_b32_e32 v35, 0xffff0000, v145
	v_lshl_add_u64 v[32:33], v[32:33], 0, v[190:191]
	v_pk_add_f32 v[26:27], v[26:27], v[34:35]
	global_store_dwordx4 v[32:33], v[28:31], off
	global_store_dwordx4 v[32:33], v[24:27], off offset:16
	s_nop 1
	v_lshlrev_b32_e32 v24, 16, v138
	v_and_b32_e32 v25, 0xffff0000, v138
	v_lshlrev_b32_e32 v26, 16, v139
	v_and_b32_e32 v27, 0xffff0000, v139
	v_pk_add_f32 v[20:21], v[20:21], v[24:25]
	v_lshlrev_b32_e32 v24, 16, v140
	v_and_b32_e32 v25, 0xffff0000, v140
	v_pk_add_f32 v[22:23], v[22:23], v[26:27]
	v_lshlrev_b32_e32 v26, 16, v141
	v_and_b32_e32 v27, 0xffff0000, v141
	v_pk_add_f32 v[12:13], v[12:13], v[24:25]
	v_pk_add_f32 v[14:15], v[14:15], v[26:27]
	global_store_dwordx4 v[32:33], v[20:23], off offset:512
	global_store_dwordx4 v[32:33], v[12:15], off offset:528
	s_nop 0
	v_add_u32_e32 v20, 0xb0, v218
	v_lshlrev_b32_e32 v12, 16, v134
	v_and_b32_e32 v13, 0xffff0000, v134
	v_ashrrev_i32_e32 v21, 31, v20
	v_pk_add_f32 v[12:13], v[16:17], v[12:13]
	v_lshlrev_b32_e32 v16, 16, v136
	v_and_b32_e32 v17, 0xffff0000, v136
	v_lshlrev_b32_e32 v14, 16, v135
	v_and_b32_e32 v15, 0xffff0000, v135
	v_pk_add_f32 v[8:9], v[8:9], v[16:17]
	v_lshlrev_b64 v[16:17], 12, v[20:21]
	v_pk_add_f32 v[14:15], v[18:19], v[14:15]
	v_lshlrev_b32_e32 v18, 16, v137
	v_and_b32_e32 v19, 0xffff0000, v137
	v_lshl_add_u64 v[16:17], s[64:65], 0, v[16:17]
	v_pk_add_f32 v[10:11], v[10:11], v[18:19]
	v_lshl_add_u64 v[16:17], v[16:17], 0, v[190:191]
	global_store_dwordx4 v[16:17], v[12:15], off
	global_store_dwordx4 v[16:17], v[8:11], off offset:16
	s_nop 1
	v_lshlrev_b32_e32 v8, 16, v130
	v_and_b32_e32 v9, 0xffff0000, v130
	v_lshlrev_b32_e32 v10, 16, v131
	v_and_b32_e32 v11, 0xffff0000, v131
	v_pk_add_f32 v[6:7], v[6:7], v[10:11]
	v_pk_add_f32 v[4:5], v[4:5], v[8:9]
	v_lshlrev_b32_e32 v8, 16, v132
	v_and_b32_e32 v9, 0xffff0000, v132
	v_lshlrev_b32_e32 v10, 16, v133
	v_and_b32_e32 v11, 0xffff0000, v133
	v_pk_add_f32 v[2:3], v[2:3], v[10:11]
	v_pk_add_f32 v[0:1], v[0:1], v[8:9]
	global_store_dwordx4 v[16:17], v[4:7], off offset:512
	global_store_dwordx4 v[16:17], v[0:3], off offset:528
	s_cbranch_vccnz .LBB0_1230
	s_andn2_b64 vcc, exec, s[2:3]
	s_cbranch_vccnz .LBB0_1229
	s_barrier
	s_branch .LBB0_1229

; #define LAS __attribute__((address_space(3)))
; template <int KSTEPS  >
; __device__ __forceinline__ void small_mma_ksplit(f32x4 (&acc)[2], const bf16_t* A, int lda, const bf16_t* Bt, int ldb, int n0, LAS unsigned char* lds, const SmallId& id) {
;     ...
;     for (int ks = 0; ks < KSTEPS; ++ks) {
;         bf16x8 a[8], b[2];
; #pragma unroll
;         for (int rb = 0; rb < 8; ++rb) a[rb] = *(const bf16x8*)(ap + (size_t)(16 * rb) * lda + 32 * ks);
;         b[0] = *(const bf16x8*)(bp + 32 * ks); b[1] = *(const bf16x8*)(bp + (size_t)16 * ldb + 32 * ks);
; #pragma unroll
;         for (int rb = 0; rb < 8; ++rb) { part[rb][0] = __builtin_amdgcn_mfma_f32_16x16x32_bf16(b[0], a[rb], part[rb][0], 0, 0, 0); part[rb][1] = __builtin_amdgcn_mfma_f32_16x16x32_bf16(b[1], a[rb], part[rb][1], 0, 0, 0); }
;     }
;     LAS f32x4* red = (LAS f32x4*)lds;
; #pragma unroll
;     for (int rb = 0; rb < 8; ++rb) { red[((id.w * 8 + rb) * 2 + 0) * 64 + lane] = part[rb][0]; red[((id.w * 8 + rb) * 2 + 1) * 64 + lane] = part[rb][1]; }
;     asm volatile("s_waitcnt lgkmcnt(0)" ::: "memory"); __syncthreads();
;     acc[0] = (f32x4){0.f, 0.f, 0.f, 0.f}; acc[1] = acc[0];
; #pragma unroll
;     for (int w2 = 0; w2 < 8; ++w2) { acc[0] += red[((w2 * 8 + id.w) * 2 + 0) * 64 + lane]; acc[1] += red[((w2 * 8 + id.w) * 2 + 1) * 64 + lane]; }
.LBB0_1255:
	v_lshl_add_u64 v[94:95], v[70:71], 0, s[8:9]
	v_add_co_u32_e64 v90, s[0:1], s52, v94
	v_lshl_add_u64 v[86:87], v[72:73], 0, s[8:9]
	s_nop 1
	v_addc_co_u32_e64 v91, s[0:1], 0, v95, s[0:1]
	v_add_co_u32_e64 v102, s[0:1], s53, v94
	s_add_u32 s8, s8, 64
	s_nop 1
	v_addc_co_u32_e64 v103, s[0:1], 0, v95, s[0:1]
	v_add_co_u32_e64 v88, s[0:1], s62, v86
	s_addc_u32 s9, s9, 0
	s_nop 1
	v_addc_co_u32_e64 v89, s[0:1], 0, v87, s[0:1]
	v_add_co_u32_e64 v98, s[0:1], s63, v86
	s_cmpk_lg_i32 s8, 0x2c0
	s_nop 1
	v_addc_co_u32_e64 v99, s[0:1], 0, v87, s[0:1]
	global_load_dwordx4 v[86:89], v[88:89], off
	global_load_dwordx4 v[90:93], v[90:91], off
	global_load_dwordx4 v[98:101], v[98:99], off
	global_load_dwordx4 v[102:105], v[102:103], off
	v_add_co_u32_e64 v106, s[0:1], s56, v94
	s_nop 1
	v_addc_co_u32_e64 v107, s[0:1], 0, v95, s[0:1]
	v_add_co_u32_e64 v108, s[0:1], s57, v94
	s_nop 1
	v_addc_co_u32_e64 v109, s[0:1], 0, v95, s[0:1]
	global_load_dwordx4 v[180:183], v[106:107], off
	global_load_dwordx4 v[184:187], v[108:109], off
	v_add_co_u32_e64 v106, s[0:1], s58, v94
	s_nop 1
	v_addc_co_u32_e64 v107, s[0:1], 0, v95, s[0:1]
	v_add_co_u32_e64 v108, s[0:1], s59, v94
	s_nop 1
	v_addc_co_u32_e64 v109, s[0:1], 0, v95, s[0:1]
	global_load_dwordx4 v[188:191], v[106:107], off
	global_load_dwordx4 v[206:209], v[108:109], off
	v_add_co_u32_e64 v106, s[0:1], s60, v94
	s_nop 1
	v_addc_co_u32_e64 v107, s[0:1], 0, v95, s[0:1]
	v_add_co_u32_e64 v94, s[0:1], s61, v94
	s_nop 1
	v_addc_co_u32_e64 v95, s[0:1], 0, v95, s[0:1]
	global_load_dwordx4 v[210:213], v[106:107], off
	global_load_dwordx4 v[214:217], v[94:95], off
	s_waitcnt vmcnt(0) lgkmcnt(0)
	v_mfma_f32_16x16x32_bf16 v[36:39], v[86:89], v[90:93], v[36:39]
	v_mfma_f32_16x16x32_bf16 v[24:27], v[98:101], v[90:93], v[24:27]
	v_mfma_f32_16x16x32_bf16 v[20:23], v[86:89], v[102:105], v[20:23]
	v_mfma_f32_16x16x32_bf16 v[16:19], v[98:101], v[102:105], v[16:19]
	v_mfma_f32_16x16x32_bf16 v[12:15], v[86:89], v[180:183], v[12:15]
	v_mfma_f32_16x16x32_bf16 v[8:11], v[98:101], v[180:183], v[8:11]
	v_mfma_f32_16x16x32_bf16 v[4:7], v[86:89], v[184:187], v[4:7]
	v_mfma_f32_16x16x32_bf16 v[0:3], v[98:101], v[184:187], v[0:3]
	v_mfma_f32_16x16x32_bf16 v[28:31], v[86:89], v[188:191], v[28:31]
	v_mfma_f32_16x16x32_bf16 v[32:35], v[98:101], v[188:191], v[32:35]
	v_mfma_f32_16x16x32_bf16 v[40:43], v[86:89], v[206:209], v[40:43]
	v_mfma_f32_16x16x32_bf16 v[44:47], v[98:101], v[206:209], v[44:47]
	v_mfma_f32_16x16x32_bf16 v[48:51], v[86:89], v[210:213], v[48:51]
	v_mfma_f32_16x16x32_bf16 v[52:55], v[98:101], v[210:213], v[52:55]
	v_mfma_f32_16x16x32_bf16 v[56:59], v[86:89], v[214:217], v[56:59]
	v_mfma_f32_16x16x32_bf16 v[60:63], v[98:101], v[214:217], v[60:63]
	s_cbranch_scc1 .LBB0_1255
	ds_write_b128 v74, v[36:39]
	ds_write_b128 v74, v[24:27] offset:1024
	ds_write_b128 v74, v[20:23] offset:2048
	ds_write_b128 v74, v[16:19] offset:3072
	ds_write_b128 v74, v[12:15] offset:4096
	ds_write_b128 v74, v[8:11] offset:5120
	ds_write_b128 v74, v[4:7] offset:6144
	ds_write_b128 v74, v[0:3] offset:7168
	ds_write_b128 v74, v[28:31] offset:8192
	ds_write_b128 v74, v[32:35] offset:9216
	ds_write_b128 v74, v[40:43] offset:10240
	ds_write_b128 v74, v[44:47] offset:11264
	ds_write_b128 v74, v[48:51] offset:12288
	ds_write_b128 v74, v[52:55] offset:13312
	ds_write_b128 v74, v[56:59] offset:14336
	ds_write_b128 v74, v[60:63] offset:15360
	s_waitcnt lgkmcnt(0)
	s_waitcnt lgkmcnt(0)
	s_barrier
; __device__ __forceinline__ unsigned cvt_pk_bf16(float lo, float hi) { unsigned r; asm volatile("v_cvt_pk_bf16_f32 %0, %1, %2" : "=v"(r) : "v"(lo), "v"(hi)); return r; }
; template <int KSTEPS  >
; __device__ __forceinline__ void small_mma_ksplit(f32x4 (&acc)[2], const bf16_t* A, int lda, const bf16_t* Bt, int ldb, int n0, LAS unsigned char* lds, const SmallId& id) {
;     ...
;     for (int w2 = 0; w2 < 8; ++w2) { acc[0] += red[((w2 * 8 + id.w) * 2 + 0) * 64 + lane]; acc[1] += red[((w2 * 8 + id.w) * 2 + 1) * 64 + lane]; }
;     asm volatile("s_waitcnt lgkmcnt(0)" ::: "memory"); __syncthreads();
; template <bool RES_F32, bool OUT_F32, int KSTEPS>
; __device__ __forceinline__ void small_res(const Params& p, LAS unsigned char* lds, const bf16_t* A, int lda, const bf16_t* Bt, int K, float* ssq_next, int G, int bx) {
;     ...
;         for (int nb = 0; nb < 2; ++nb) { const int col = n0 + 16 * nb + 4 * id.fq;
;             f32x4 r;
;             if (RES_F32) r = *(const f32x4*)(p.xs + (size_t)(id.row - MP) * DM + col);
;             else { const u32x2 w = *(const u32x2*)(XB + (size_t)id.row * DM + col); r = (f32x4){bf_lo(w.x), bf_hi(w.x), bf_lo(w.y), bf_hi(w.y)}; }
;             const f32x4 x = r + acc[nb];
;             if (OUT_F32) *(f32x4*)(p.out + (size_t)id.row * DM + col) = x;
;             else { u32x2 w; w.x = cvt_pk_bf16(x[0], x[1]); w.y = cvt_pk_bf16(x[2], x[3]); *(u32x2*)(XB + (size_t)id.row * DM + col) = w; }
;             s += (x[0] * x[0] + x[1] * x[1]) + (x[2] * x[2] + x[3] * x[3]); }
;         if (!OUT_F32) { s += __shfl_xor(s, 16); s += __shfl_xor(s, 32); if (id.fq == 0) atomicAdd(ssq_next + id.row, s); }
	ds_read_b128 v[0:3], v75
	s_waitcnt lgkmcnt(0)
	v_pk_add_f32 v[4:5], v[2:3], 0 op_sel_hi:[1,0]
	v_pk_add_f32 v[6:7], v[0:1], 0 op_sel_hi:[1,0]
	ds_read_b128 v[0:3], v75 offset:1024
	s_waitcnt lgkmcnt(0)
	v_pk_add_f32 v[8:9], v[2:3], 0 op_sel_hi:[1,0]
	v_pk_add_f32 v[10:11], v[0:1], 0 op_sel_hi:[1,0]
	ds_read_b128 v[0:3], v75 offset:16384
	s_waitcnt lgkmcnt(0)
	v_pk_add_f32 v[4:5], v[4:5], v[2:3]
	v_pk_add_f32 v[6:7], v[6:7], v[0:1]
	ds_read_b128 v[0:3], v75 offset:17408
	s_waitcnt lgkmcnt(0)
	v_pk_add_f32 v[8:9], v[8:9], v[2:3]
	v_pk_add_f32 v[10:11], v[10:11], v[0:1]
	ds_read_b128 v[0:3], v75 offset:32768
	s_waitcnt lgkmcnt(0)
	v_pk_add_f32 v[4:5], v[4:5], v[2:3]
	v_pk_add_f32 v[6:7], v[6:7], v[0:1]
	ds_read_b128 v[0:3], v75 offset:33792
	s_waitcnt lgkmcnt(0)
	v_pk_add_f32 v[8:9], v[8:9], v[2:3]
	v_pk_add_f32 v[10:11], v[10:11], v[0:1]
	ds_read_b128 v[0:3], v75 offset:49152
	s_waitcnt lgkmcnt(0)
	v_pk_add_f32 v[4:5], v[4:5], v[2:3]
	v_pk_add_f32 v[6:7], v[6:7], v[0:1]
	ds_read_b128 v[0:3], v75 offset:50176
	s_waitcnt lgkmcnt(0)
	v_pk_add_f32 v[8:9], v[8:9], v[2:3]
	v_pk_add_f32 v[10:11], v[10:11], v[0:1]
	ds_read_b128 v[0:3], v76
	s_waitcnt lgkmcnt(0)
	v_pk_add_f32 v[4:5], v[4:5], v[2:3]
	v_pk_add_f32 v[6:7], v[6:7], v[0:1]
	ds_read_b128 v[0:3], v77
	s_waitcnt lgkmcnt(0)
	v_pk_add_f32 v[8:9], v[8:9], v[2:3]
	v_pk_add_f32 v[10:11], v[10:11], v[0:1]
	ds_read_b128 v[0:3], v78
	s_waitcnt lgkmcnt(0)
	v_pk_add_f32 v[4:5], v[4:5], v[2:3]
	v_pk_add_f32 v[6:7], v[6:7], v[0:1]
	ds_read_b128 v[0:3], v79
	s_waitcnt lgkmcnt(0)
	v_pk_add_f32 v[8:9], v[8:9], v[2:3]
	v_pk_add_f32 v[10:11], v[10:11], v[0:1]
	ds_read_b128 v[0:3], v80
	s_waitcnt lgkmcnt(0)
	v_pk_add_f32 v[4:5], v[4:5], v[2:3]
	v_pk_add_f32 v[6:7], v[6:7], v[0:1]
	ds_read_b128 v[0:3], v81
	s_waitcnt lgkmcnt(0)
	v_pk_add_f32 v[8:9], v[8:9], v[2:3]
	v_pk_add_f32 v[10:11], v[10:11], v[0:1]
	ds_read_b128 v[0:3], v82
	s_waitcnt lgkmcnt(0)
	v_pk_add_f32 v[4:5], v[4:5], v[2:3]
	v_pk_add_f32 v[6:7], v[6:7], v[0:1]
	ds_read_b128 v[0:3], v83
	s_waitcnt lgkmcnt(0)
	s_waitcnt lgkmcnt(0)
	s_barrier
	v_pk_add_f32 v[2:3], v[8:9], v[2:3]
	v_lshl_or_b32 v8, s7, 5, v84
	v_ashrrev_i32_e32 v9, 31, v8
	v_lshl_add_u64 v[8:9], v[8:9], 1, v[64:65]
	v_pk_add_f32 v[0:1], v[10:11], v[0:1]
	global_load_dwordx2 v[10:11], v[8:9], off
	s_waitcnt vmcnt(0) lgkmcnt(0)
	v_lshlrev_b32_e32 v12, 16, v10
	v_and_b32_e32 v13, 0xffff0000, v10
	v_lshlrev_b32_e32 v10, 16, v11
	v_and_b32_e32 v11, 0xffff0000, v11
	v_pk_add_f32 v[4:5], v[4:5], v[10:11]
	v_pk_add_f32 v[6:7], v[6:7], v[12:13]
	s_nop 0
	v_cvt_pk_bf16_f32 v10, v6, v7
	v_cvt_pk_bf16_f32 v11, v4, v5
	v_mul_f32_e32 v7, v7, v7
	v_mul_f32_e32 v5, v5, v5
	v_fmac_f32_e32 v7, v6, v6
	v_fmac_f32_e32 v5, v4, v4
	global_store_dwordx2 v[8:9], v[10:11], off
	v_add_f32_e32 v10, v7, v5
	global_load_dwordx2 v[4:5], v[8:9], off offset:32
	s_waitcnt vmcnt(0) lgkmcnt(0)
	v_lshlrev_b32_e32 v6, 16, v4
	v_and_b32_e32 v7, 0xffff0000, v4
	v_lshlrev_b32_e32 v4, 16, v5
	v_and_b32_e32 v5, 0xffff0000, v5
	v_pk_add_f32 v[0:1], v[0:1], v[6:7]
	v_pk_add_f32 v[2:3], v[2:3], v[4:5]
	v_cvt_pk_bf16_f32 v4, v0, v1
	v_mul_f32_e32 v1, v1, v1
	v_fmac_f32_e32 v1, v0, v0
	v_mul_f32_e32 v0, v3, v3
	v_cvt_pk_bf16_f32 v5, v2, v3
	v_fmac_f32_e32 v0, v2, v2
	v_and_b32_e32 v2, 64, v225
	v_add_f32_e32 v0, v1, v0
	v_xor_b32_e32 v1, 16, v225
	v_add_u32_e32 v2, 64, v2
	v_cmp_lt_i32_e64 s[0:1], v1, v2
	v_add_f32_e32 v0, v10, v0
	global_store_dwordx2 v[8:9], v[4:5], off offset:32
	v_cndmask_b32_e64 v1, v225, v1, s[0:1]
	v_lshlrev_b32_e32 v1, 2, v1
	ds_bpermute_b32 v1, v1, v0
	s_waitcnt lgkmcnt(0)
	v_add_f32_e32 v0, v0, v1
	v_xor_b32_e32 v1, 32, v225
	v_cmp_lt_i32_e64 s[0:1], v1, v2
	s_nop 1
	v_cndmask_b32_e64 v1, v225, v1, s[0:1]
	v_lshlrev_b32_e32 v1, 2, v1
	ds_bpermute_b32 v1, v1, v0
	s_and_saveexec_b64 s[0:1], vcc
	s_cbranch_execz .LBB0_1253
	s_waitcnt lgkmcnt(0)
	v_add_f32_e32 v0, v0, v1
	global_atomic_add_f32 v[66:67], v0, off
	s_branch .LBB0_1253

; __device__ __forceinline__ unsigned cvt_pk_bf16(float lo, float hi) { unsigned r; asm volatile("v_cvt_pk_bf16_f32 %0, %1, %2" : "=v"(r) : "v"(lo), "v"(hi)); return r; }
;     __device__ __forceinline__ void finish(const f32x4 x0, const f32x4 x1, int row, int col, float& s) const {
;     ...
;         else { u32x4 w; w.x = cvt_pk_bf16(x0[0], x0[1]); w.y = cvt_pk_bf16(x0[2], x0[3]); w.z = cvt_pk_bf16(x1[0], x1[1]); w.w = cvt_pk_bf16(x1[2], x1[3]); *(u32x4*)(XB + (size_t)row * DM + col) = w; }
;         s += (x0[0] * x0[0] + x0[1] * x0[1]) + (x0[2] * x0[2] + x0[3] * x0[3]) + (x1[0] * x1[0] + x1[1] * x1[1]) + (x1[2] * x1[2] + x1[3] * x1[3]);
;     __device__ __forceinline__ void operator()(AccT& acc, const Unit& u, int wr, int wc, int fr, int fq) const {
;     ...
;             u32x4 rb[2][4][2];
; #pragma unroll
;             for (int ai = 0; ai < 2; ++ai)
; #pragma unroll
;                 for (int m = 0; m < 4; ++m)
; #pragma unroll
;                     for (int bj = 0; bj < 2; ++bj) rb[ai][m][bj] = __builtin_nontemporal_load((const u32x4*)((const char*)XB + (unsigned)(((u.pm * 256 + ai * 128 + wr * 64 + m * 16 + fr) * DM + col0 + bj * 128) * 2)));
; #pragma unroll
;             for (int ai = 0; ai < 2; ++ai)
; #pragma unroll
;                 for (int m = 0; m < 4; ++m) {
;                     const int row = u.pm * 256 + ai * 128 + wr * 64 + m * 16 + fr; float s = 0.f;
; #pragma unroll
;                     for (int bj = 0; bj < 2; ++bj) { const u32x4 w = rb[ai][m][bj];
;                         finish((f32x4){bf_lo(w.x), bf_hi(w.x), bf_lo(w.y), bf_hi(w.y)} + acc[ai][bj][m][0], (f32x4){bf_lo(w.z), bf_hi(w.z), bf_lo(w.w), bf_hi(w.w)} + acc[ai][bj][m][1], row, col0 + bj * 128, s); }
;                     if (!OUT_F32) { s += __shfl_xor(s, 16); s += __shfl_xor(s, 32); if (fq == 0) atomicAdd(ssq_next + row, s); }
.LBB0_1278:
	s_lshl_b32 s0, s48, 8
	v_mov_b32_e32 v96, v230
	v_mov_b32_e32 v219, v229
	s_or_b32 s0, s0, s37
	s_nop 0
	v_lshl_add_u32 v218, v219, 3, s0
	s_lshl_b32 s0, s47, 8
	s_add_i32 s0, s0, s33
	v_add_u32_e32 v220, s0, v96
	v_lshlrev_b32_e32 v96, 11, v220
	v_lshl_add_u32 v96, v218, 1, v96
	v_lshl_add_u64 v[118:119], s[90:91], 0, v[96:97]
	global_load_dwordx4 v[190:193], v[118:119], off nt
	v_add_u32_e32 v118, 0x100, v96
	v_mov_b32_e32 v119, v97
	v_lshl_add_u64 v[118:119], s[90:91], 0, v[118:119]
	global_load_dwordx4 v[186:189], v[118:119], off nt
	v_add_u32_e32 v118, 0x8000, v96
	v_mov_b32_e32 v119, v97
	v_lshl_add_u64 v[118:119], s[90:91], 0, v[118:119]
	global_load_dwordx4 v[182:185], v[118:119], off nt
	v_add_u32_e32 v118, 0x8100, v96
	v_mov_b32_e32 v119, v97
	v_lshl_add_u64 v[118:119], s[90:91], 0, v[118:119]
	global_load_dwordx4 v[178:181], v[118:119], off nt
	v_add_u32_e32 v118, 0x10000, v96
	v_mov_b32_e32 v119, v97
	v_lshl_add_u64 v[118:119], s[90:91], 0, v[118:119]
	global_load_dwordx4 v[174:177], v[118:119], off nt
	v_add_u32_e32 v118, 0x10100, v96
	v_mov_b32_e32 v119, v97
	v_lshl_add_u64 v[118:119], s[90:91], 0, v[118:119]
	global_load_dwordx4 v[170:173], v[118:119], off nt
	v_add_u32_e32 v118, 0x18000, v96
	v_mov_b32_e32 v119, v97
	v_lshl_add_u64 v[118:119], s[90:91], 0, v[118:119]
	global_load_dwordx4 v[166:169], v[118:119], off nt
	v_add_u32_e32 v118, 0x18100, v96
	v_mov_b32_e32 v119, v97
	v_lshl_add_u64 v[118:119], s[90:91], 0, v[118:119]
	global_load_dwordx4 v[162:165], v[118:119], off nt
	v_add_u32_e32 v118, 0x40000, v96
	v_mov_b32_e32 v119, v97
	v_lshl_add_u64 v[118:119], s[90:91], 0, v[118:119]
	global_load_dwordx4 v[158:161], v[118:119], off nt
	v_add_u32_e32 v118, 0x40100, v96
	v_mov_b32_e32 v119, v97
	v_lshl_add_u64 v[118:119], s[90:91], 0, v[118:119]
	global_load_dwordx4 v[154:157], v[118:119], off nt
	v_add_u32_e32 v118, 0x48000, v96
	v_mov_b32_e32 v119, v97
	v_lshl_add_u64 v[118:119], s[90:91], 0, v[118:119]
	global_load_dwordx4 v[150:153], v[118:119], off nt
	v_add_u32_e32 v118, 0x48100, v96
	v_mov_b32_e32 v119, v97
	v_lshl_add_u64 v[118:119], s[90:91], 0, v[118:119]
	global_load_dwordx4 v[146:149], v[118:119], off nt
	v_add_u32_e32 v118, 0x50000, v96
	v_mov_b32_e32 v119, v97
	v_lshl_add_u64 v[118:119], s[90:91], 0, v[118:119]
	global_load_dwordx4 v[134:137], v[118:119], off nt
	v_add_u32_e32 v118, 0x50100, v96
	v_mov_b32_e32 v119, v97
	v_lshl_add_u64 v[118:119], s[90:91], 0, v[118:119]
	global_load_dwordx4 v[126:129], v[118:119], off nt
	v_add_u32_e32 v118, 0x58000, v96
	v_mov_b32_e32 v119, v97
	v_add_u32_e32 v96, 0x58100, v96
	v_lshl_add_u64 v[118:119], s[90:91], 0, v[118:119]
	v_lshl_add_u64 v[138:139], s[90:91], 0, v[96:97]
	global_load_dwordx4 v[118:121], v[118:119], off nt
	v_ashrrev_i32_e32 v221, 31, v220
	global_load_dwordx4 v[138:141], v[138:139], off nt
	v_lshlrev_b64 v[234:235], 11, v[220:221]
	v_cmp_eq_u32_e32 vcc, 0, v219
	v_lshl_add_u64 v[234:235], s[90:91], 0, v[234:235]
	v_ashrrev_i32_e32 v219, 31, v218
	v_lshl_add_u64 v[234:235], v[218:219], 1, v[234:235]
	s_waitcnt vmcnt(0) lgkmcnt(0)
	v_lshlrev_b32_e32 v236, 16, v190
	v_and_b32_e32 v237, 0xffff0000, v190
	v_lshlrev_b32_e32 v190, 16, v191
	v_and_b32_e32 v191, 0xffff0000, v191
	v_pk_add_f32 v[144:145], v[144:145], v[190:191]
	v_lshlrev_b32_e32 v190, 16, v192
	v_and_b32_e32 v191, 0xffff0000, v192
	v_pk_add_f32 v[142:143], v[142:143], v[236:237]
	v_lshlrev_b32_e32 v192, 16, v193
	v_and_b32_e32 v193, 0xffff0000, v193
	v_pk_add_f32 v[190:191], v[130:131], v[190:191]
	v_cvt_pk_bf16_f32 v130, v142, v143
	v_pk_add_f32 v[192:193], v[132:133], v[192:193]
	v_cvt_pk_bf16_f32 v131, v144, v145
	v_cvt_pk_bf16_f32 v132, v190, v191
	v_mul_f32_e32 v96, v143, v143
	v_cvt_pk_bf16_f32 v133, v192, v193
	global_store_dwordx4 v[234:235], v[130:133], off
	v_fmac_f32_e32 v96, v142, v142
	s_nop 0
	v_mul_f32_e32 v130, v145, v145
	v_fmac_f32_e32 v130, v144, v144
	v_add_f32_e32 v96, v96, v130
	v_mul_f32_e32 v130, v191, v191
	v_fmac_f32_e32 v130, v190, v190
	v_add_f32_e32 v96, v130, v96
	v_mul_f32_e32 v130, v193, v193
	v_fmac_f32_e32 v130, v192, v192
	v_add_f32_e32 v96, v130, v96
	v_lshlrev_b32_e32 v130, 16, v186
	v_and_b32_e32 v131, 0xffff0000, v186
	v_lshlrev_b32_e32 v132, 16, v187
	v_and_b32_e32 v133, 0xffff0000, v187
	v_pk_add_f32 v[122:123], v[122:123], v[130:131]
	v_lshlrev_b32_e32 v130, 16, v188
	v_and_b32_e32 v131, 0xffff0000, v188
	v_pk_add_f32 v[124:125], v[124:125], v[132:133]
	v_lshlrev_b32_e32 v132, 16, v189
	v_and_b32_e32 v133, 0xffff0000, v189
	v_pk_add_f32 v[130:131], v[114:115], v[130:131]
	v_cvt_pk_bf16_f32 v114, v122, v123
	v_cvt_pk_bf16_f32 v115, v124, v125
	v_pk_add_f32 v[132:133], v[116:117], v[132:133]
	v_cvt_pk_bf16_f32 v116, v130, v131
	s_nop 0
	v_cvt_pk_bf16_f32 v117, v132, v133
	global_store_dwordx4 v[234:235], v[114:117], off offset:256
	s_nop 1
	v_mul_f32_e32 v114, v123, v123
	v_mul_f32_e32 v115, v125, v125
	v_fmac_f32_e32 v114, v122, v122
	v_fmac_f32_e32 v115, v124, v124
	v_add_f32_e32 v114, v114, v115
	v_mul_f32_e32 v115, v131, v131
	v_fmac_f32_e32 v115, v130, v130
	v_add_f32_e32 v114, v115, v114
	v_mul_f32_e32 v115, v133, v133
	v_fmac_f32_e32 v115, v132, v132
	v_add_f32_e32 v114, v115, v114
	v_and_b32_e32 v115, 64, v225
	v_add_f32_e32 v114, v96, v114
	v_xor_b32_e32 v96, 16, v225
	v_add_u32_e32 v115, 64, v115
	v_cmp_lt_i32_e64 s[0:1], v96, v115
	s_nop 1
	v_cndmask_b32_e64 v96, v225, v96, s[0:1]
	v_lshlrev_b32_e32 v96, 2, v96
	ds_bpermute_b32 v116, v96, v114
	s_waitcnt lgkmcnt(0)
	v_add_f32_e32 v114, v114, v116
	v_xor_b32_e32 v116, 32, v225
	v_cmp_lt_i32_e64 s[0:1], v116, v115
	s_nop 1
	v_cndmask_b32_e64 v115, v225, v116, s[0:1]
	v_lshlrev_b32_e32 v116, 2, v115
	ds_bpermute_b32 v115, v116, v114
	s_and_saveexec_b64 s[0:1], vcc
	s_cbranch_execz .LBB0_1280
	v_lshl_add_u64 v[122:123], v[220:221], 2, s[2:3]
	s_waitcnt lgkmcnt(0)
	v_add_f32_e32 v114, v114, v115
	global_atomic_add_f32 v[122:123], v114, off
